# speedup vs baseline: 1.0229x; 1.0059x over previous
; __device__ __forceinline__ float sigmf(float x) { return 1.f / (1.f + __expf(-x)); }
; __device__ __forceinline__ void inproj_epilogue(const Params& p, int layer, int mt, int ntile, int tid,
;                                                 f32x16 (&acc)[2][2], unsigned char* smem) {
;     ...
;     acc_foreach(tid, acc, [&](int row, int col, float v) {
;       int t = m0 + row;
;       float o = v;
;       if (mode == 1) o = (t >= NPADR) ? v : 0.f;
;       if (mode == 2) o = sigmf(v);
;       sT[row * 136 + col] = f2bf(o);
;     });
.LBB0_209:
	v_bfe_u32 v110, v107, 16, 1
	v_and_b32_e32 v106, 0x5f, v106
	v_add3_u32 v111, v107, v110, s77
	v_mul_lo_u32 v110, v96, s78
	v_lshl_add_u32 v107, v106, 1, v110
	ds_write_b16_d16_hi v107, v111
	v_add3_u32 v111, s60, v96, 1
	v_cmp_lt_i32_e64 s[10:11], s43, v111
	v_cndmask_b32_e64 v111, 0, 1, s[12:13]
	v_cmp_ne_u32_e64 s[6:7], 1, v111
	s_nop 1

; __device__ __forceinline__ float sigmf(float x) { return 1.f / (1.f + __expf(-x)); }
; __device__ __forceinline__ void inproj_epilogue(const Params& p, int layer, int mt, int ntile, int tid,
;                                                 f32x16 (&acc)[2][2], unsigned char* smem) {
;     ...
;     acc_foreach(tid, acc, [&](int row, int col, float v) {
;       int t = m0 + row;
;       float o = v;
;       if (mode == 1) o = (t >= NPADR) ? v : 0.f;
;       if (mode == 2) o = sigmf(v);
;       sT[row * 136 + col] = f2bf(o);
;     });
.LBB0_212:
	v_bfe_u32 v112, v111, 16, 1
	v_add3_u32 v112, v111, v112, s77
	v_add_u32_e32 v111, 0x110, v110
	v_lshl_add_u32 v110, v106, 1, v111
	ds_write_b16_d16_hi v110, v112
	v_add3_u32 v112, s60, v96, 2
	v_cmp_lt_i32_e64 s[12:13], s43, v112
	s_nop 1

; __device__ __forceinline__ float sigmf(float x) { return 1.f / (1.f + __expf(-x)); }
; __device__ __forceinline__ void inproj_epilogue(const Params& p, int layer, int mt, int ntile, int tid,
;                                                 f32x16 (&acc)[2][2], unsigned char* smem) {
;     ...
;     acc_foreach(tid, acc, [&](int row, int col, float v) {
;       int t = m0 + row;
;       float o = v;
;       if (mode == 1) o = (t >= NPADR) ? v : 0.f;
;       if (mode == 2) o = sigmf(v);
;       sT[row * 136 + col] = f2bf(o);
;     });
.LBB0_215:
	v_bfe_u32 v113, v112, 16, 1
	v_add3_u32 v113, v112, v113, s77
	v_add_u32_e32 v112, 0x110, v111
	v_lshl_add_u32 v111, v106, 1, v112
	ds_write_b16_d16_hi v111, v113
	v_add3_u32 v113, s60, v96, 3
	v_cmp_lt_i32_e64 s[14:15], s43, v113
	s_nop 1

; __device__ __forceinline__ float sigmf(float x) { return 1.f / (1.f + __expf(-x)); }
; __device__ __forceinline__ void inproj_epilogue(const Params& p, int layer, int mt, int ntile, int tid,
;                                                 f32x16 (&acc)[2][2], unsigned char* smem) {
;     ...
;     acc_foreach(tid, acc, [&](int row, int col, float v) {
;       int t = m0 + row;
;       float o = v;
;       if (mode == 1) o = (t >= NPADR) ? v : 0.f;
;       if (mode == 2) o = sigmf(v);
;       sT[row * 136 + col] = f2bf(o);
;     });
.LBB0_218:
	v_bfe_u32 v114, v113, 16, 1
	v_add3_u32 v114, v113, v114, s77
	v_add_u32_e32 v113, 0x110, v112
	v_lshl_add_u32 v112, v106, 1, v113
	ds_write_b16_d16_hi v112, v114
	v_add3_u32 v114, s60, v96, 8
	v_cmp_lt_i32_e64 s[16:17], s43, v114
	s_nop 1

; __device__ __forceinline__ float sigmf(float x) { return 1.f / (1.f + __expf(-x)); }
; __device__ __forceinline__ void inproj_epilogue(const Params& p, int layer, int mt, int ntile, int tid,
;                                                 f32x16 (&acc)[2][2], unsigned char* smem) {
;     ...
;     acc_foreach(tid, acc, [&](int row, int col, float v) {
;       int t = m0 + row;
;       float o = v;
;       if (mode == 1) o = (t >= NPADR) ? v : 0.f;
;       if (mode == 2) o = sigmf(v);
;       sT[row * 136 + col] = f2bf(o);
;     });
.LBB0_221:
	v_bfe_u32 v115, v114, 16, 1
	v_add3_u32 v115, v114, v115, s77
	v_add_u32_e32 v114, 0x550, v113
	v_lshl_add_u32 v113, v106, 1, v114
	ds_write_b16_d16_hi v113, v115
	v_add3_u32 v115, s60, v96, 9
	v_cmp_lt_i32_e64 s[18:19], s43, v115
	s_nop 1

; __device__ __forceinline__ float sigmf(float x) { return 1.f / (1.f + __expf(-x)); }
; __device__ __forceinline__ void inproj_epilogue(const Params& p, int layer, int mt, int ntile, int tid,
;                                                 f32x16 (&acc)[2][2], unsigned char* smem) {
;     ...
;     acc_foreach(tid, acc, [&](int row, int col, float v) {
;       int t = m0 + row;
;       float o = v;
;       if (mode == 1) o = (t >= NPADR) ? v : 0.f;
;       if (mode == 2) o = sigmf(v);
;       sT[row * 136 + col] = f2bf(o);
;     });
.LBB0_224:
	v_bfe_u32 v116, v115, 16, 1
	v_add3_u32 v116, v115, v116, s77
	v_add_u32_e32 v115, 0x110, v114
	v_lshl_add_u32 v114, v106, 1, v115
	ds_write_b16_d16_hi v114, v116
	v_add3_u32 v116, s60, v96, 10
	v_cmp_lt_i32_e64 s[20:21], s43, v116
	s_nop 1

; __device__ __forceinline__ float sigmf(float x) { return 1.f / (1.f + __expf(-x)); }
; __device__ __forceinline__ void inproj_epilogue(const Params& p, int layer, int mt, int ntile, int tid,
;                                                 f32x16 (&acc)[2][2], unsigned char* smem) {
;     ...
;     acc_foreach(tid, acc, [&](int row, int col, float v) {
;       int t = m0 + row;
;       float o = v;
;       if (mode == 1) o = (t >= NPADR) ? v : 0.f;
;       if (mode == 2) o = sigmf(v);
;       sT[row * 136 + col] = f2bf(o);
;     });
.LBB0_227:
	v_bfe_u32 v117, v116, 16, 1
	v_add3_u32 v117, v116, v117, s77
	v_add_u32_e32 v116, 0x110, v115
	v_lshl_add_u32 v115, v106, 1, v116
	ds_write_b16_d16_hi v115, v117
	v_add3_u32 v117, s60, v96, 11
	v_cmp_lt_i32_e64 s[22:23], s43, v117
	s_nop 1

; __device__ __forceinline__ float sigmf(float x) { return 1.f / (1.f + __expf(-x)); }
; __device__ __forceinline__ void inproj_epilogue(const Params& p, int layer, int mt, int ntile, int tid,
;                                                 f32x16 (&acc)[2][2], unsigned char* smem) {
;     ...
;     acc_foreach(tid, acc, [&](int row, int col, float v) {
;       int t = m0 + row;
;       float o = v;
;       if (mode == 1) o = (t >= NPADR) ? v : 0.f;
;       if (mode == 2) o = sigmf(v);
;       sT[row * 136 + col] = f2bf(o);
;     });
.LBB0_230:
	v_bfe_u32 v118, v117, 16, 1
	v_add_u32_e32 v116, 0x110, v116
	v_add3_u32 v118, v117, v118, s77
	v_lshl_add_u32 v117, v106, 1, v116
	ds_write_b16_d16_hi v117, v118
	v_add3_u32 v118, s60, v96, 16
	v_cmp_lt_i32_e64 s[24:25], s43, v118
	s_nop 1

; __device__ __forceinline__ float sigmf(float x) { return 1.f / (1.f + __expf(-x)); }
; __device__ __forceinline__ void inproj_epilogue(const Params& p, int layer, int mt, int ntile, int tid,
;                                                 f32x16 (&acc)[2][2], unsigned char* smem) {
;     ...
;     acc_foreach(tid, acc, [&](int row, int col, float v) {
;       int t = m0 + row;
;       float o = v;
;       if (mode == 1) o = (t >= NPADR) ? v : 0.f;
;       if (mode == 2) o = sigmf(v);
;       sT[row * 136 + col] = f2bf(o);
;     });
.LBB0_233:
	v_bfe_u32 v119, v118, 16, 1
	v_add_u32_e32 v116, 0x550, v116
	v_add3_u32 v119, v118, v119, s77
	v_lshl_add_u32 v118, v106, 1, v116
	ds_write_b16_d16_hi v118, v119
	v_add3_u32 v119, s60, v96, 17
	v_cmp_lt_i32_e64 s[26:27], s43, v119
	s_nop 1

; __device__ __forceinline__ float sigmf(float x) { return 1.f / (1.f + __expf(-x)); }
; __device__ __forceinline__ void inproj_epilogue(const Params& p, int layer, int mt, int ntile, int tid,
;                                                 f32x16 (&acc)[2][2], unsigned char* smem) {
;     ...
;     acc_foreach(tid, acc, [&](int row, int col, float v) {
;       int t = m0 + row;
;       float o = v;
;       if (mode == 1) o = (t >= NPADR) ? v : 0.f;
;       if (mode == 2) o = sigmf(v);
;       sT[row * 136 + col] = f2bf(o);
;     });
.LBB0_236:
	v_bfe_u32 v120, v119, 16, 1
	v_add_u32_e32 v116, 0x110, v116
	v_add3_u32 v120, v119, v120, s77
	v_lshl_add_u32 v119, v106, 1, v116
	ds_write_b16_d16_hi v119, v120
	v_add3_u32 v120, s60, v96, 18
	v_cmp_lt_i32_e64 s[28:29], s43, v120
	s_nop 1

; __device__ __forceinline__ float sigmf(float x) { return 1.f / (1.f + __expf(-x)); }
; __device__ __forceinline__ void inproj_epilogue(const Params& p, int layer, int mt, int ntile, int tid,
;                                                 f32x16 (&acc)[2][2], unsigned char* smem) {
;     ...
;     acc_foreach(tid, acc, [&](int row, int col, float v) {
;       int t = m0 + row;
;       float o = v;
;       if (mode == 1) o = (t >= NPADR) ? v : 0.f;
;       if (mode == 2) o = sigmf(v);
;       sT[row * 136 + col] = f2bf(o);
;     });
.LBB0_239:
	v_bfe_u32 v121, v120, 16, 1
	v_add_u32_e32 v116, 0x110, v116
	v_add3_u32 v121, v120, v121, s77
	v_lshl_add_u32 v120, v106, 1, v116
	ds_write_b16_d16_hi v120, v121
	v_add3_u32 v121, s60, v96, 19
	v_cmp_lt_i32_e64 s[30:31], s43, v121
	s_nop 1

; __device__ __forceinline__ float sigmf(float x) { return 1.f / (1.f + __expf(-x)); }
; __device__ __forceinline__ void inproj_epilogue(const Params& p, int layer, int mt, int ntile, int tid,
;                                                 f32x16 (&acc)[2][2], unsigned char* smem) {
;     ...
;     acc_foreach(tid, acc, [&](int row, int col, float v) {
;       int t = m0 + row;
;       float o = v;
;       if (mode == 1) o = (t >= NPADR) ? v : 0.f;
;       if (mode == 2) o = sigmf(v);
;       sT[row * 136 + col] = f2bf(o);
;     });
.LBB0_242:
	v_bfe_u32 v122, v121, 16, 1
	v_add_u32_e32 v116, 0x110, v116
	v_add3_u32 v122, v121, v122, s77
	v_lshl_add_u32 v121, v106, 1, v116
	ds_write_b16_d16_hi v121, v122
	v_add3_u32 v122, s60, v96, 24
	v_cmp_lt_i32_e64 s[34:35], s43, v122
	s_nop 1

; __device__ __forceinline__ float sigmf(float x) { return 1.f / (1.f + __expf(-x)); }
; __device__ __forceinline__ void inproj_epilogue(const Params& p, int layer, int mt, int ntile, int tid,
;                                                 f32x16 (&acc)[2][2], unsigned char* smem) {
;     ...
;     acc_foreach(tid, acc, [&](int row, int col, float v) {
;       int t = m0 + row;
;       float o = v;
;       if (mode == 1) o = (t >= NPADR) ? v : 0.f;
;       if (mode == 2) o = sigmf(v);
;       sT[row * 136 + col] = f2bf(o);
;     });
.LBB0_245:
	v_bfe_u32 v123, v122, 16, 1
	v_add_u32_e32 v116, 0x550, v116
	v_add3_u32 v123, v122, v123, s77
	v_lshl_add_u32 v122, v106, 1, v116
	ds_write_b16_d16_hi v122, v123
	v_add3_u32 v123, s60, v96, 25
	v_cmp_lt_i32_e64 s[36:37], s43, v123
	s_nop 1

; __device__ __forceinline__ float sigmf(float x) { return 1.f / (1.f + __expf(-x)); }
; __device__ __forceinline__ void inproj_epilogue(const Params& p, int layer, int mt, int ntile, int tid,
;                                                 f32x16 (&acc)[2][2], unsigned char* smem) {
;     ...
;     acc_foreach(tid, acc, [&](int row, int col, float v) {
;       int t = m0 + row;
;       float o = v;
;       if (mode == 1) o = (t >= NPADR) ? v : 0.f;
;       if (mode == 2) o = sigmf(v);
;       sT[row * 136 + col] = f2bf(o);
;     });
.LBB0_248:
	v_bfe_u32 v124, v123, 16, 1
	v_add_u32_e32 v116, 0x110, v116
	v_add3_u32 v124, v123, v124, s77
	v_lshl_add_u32 v123, v106, 1, v116
	ds_write_b16_d16_hi v123, v124
	v_add3_u32 v124, s60, v96, 26
	v_cmp_lt_i32_e64 s[38:39], s43, v124
	s_nop 1

; __device__ __forceinline__ float sigmf(float x) { return 1.f / (1.f + __expf(-x)); }
; __device__ __forceinline__ void inproj_epilogue(const Params& p, int layer, int mt, int ntile, int tid,
;                                                 f32x16 (&acc)[2][2], unsigned char* smem) {
;     ...
;     acc_foreach(tid, acc, [&](int row, int col, float v) {
;       int t = m0 + row;
;       float o = v;
;       if (mode == 1) o = (t >= NPADR) ? v : 0.f;
;       if (mode == 2) o = sigmf(v);
;       sT[row * 136 + col] = f2bf(o);
;     });
.LBB0_251:
	v_bfe_u32 v125, v124, 16, 1
	v_add_u32_e32 v116, 0x110, v116
	v_add3_u32 v124, v124, v125, s77
	v_lshl_add_u32 v116, v106, 1, v116
	ds_write_b16_d16_hi v116, v124
	v_add3_u32 v124, s60, v96, 27
	v_cmp_lt_i32_e64 s[40:41], s43, v124
	s_nop 1

; __device__ __forceinline__ float sigmf(float x) { return 1.f / (1.f + __expf(-x)); }
; __device__ __forceinline__ void inproj_epilogue(const Params& p, int layer, int mt, int ntile, int tid,
;                                                 f32x16 (&acc)[2][2], unsigned char* smem) {
;     ...
;     acc_foreach(tid, acc, [&](int row, int col, float v) {
;       int t = m0 + row;
;       float o = v;
;       if (mode == 1) o = (t >= NPADR) ? v : 0.f;
;       if (mode == 2) o = sigmf(v);
;       sT[row * 136 + col] = f2bf(o);
;     });
.LBB0_254:
	v_bfe_u32 v125, v124, 16, 1
	v_add3_u32 v124, v124, v125, s77
	ds_write_b16_d16_hi v116, v124 offset:272
	s_nop 1

; __device__ __forceinline__ float sigmf(float x) { return 1.f / (1.f + __expf(-x)); }
; __device__ __forceinline__ void inproj_epilogue(const Params& p, int layer, int mt, int ntile, int tid,
;                                                 f32x16 (&acc)[2][2], unsigned char* smem) {
;     ...
;     acc_foreach(tid, acc, [&](int row, int col, float v) {
;       int t = m0 + row;
;       float o = v;
;       if (mode == 1) o = (t >= NPADR) ? v : 0.f;
;       if (mode == 2) o = sigmf(v);
;       sT[row * 136 + col] = f2bf(o);
;     });
.LBB0_257:
	v_bfe_u32 v124, v48, 16, 1
	v_add3_u32 v48, v48, v124, s77
	ds_write_b16_d16_hi v107, v48 offset:64
	s_nop 1

; __device__ __forceinline__ float sigmf(float x) { return 1.f / (1.f + __expf(-x)); }
; __device__ __forceinline__ void inproj_epilogue(const Params& p, int layer, int mt, int ntile, int tid,
;                                                 f32x16 (&acc)[2][2], unsigned char* smem) {
;     ...
;     acc_foreach(tid, acc, [&](int row, int col, float v) {
;       int t = m0 + row;
;       float o = v;
;       if (mode == 1) o = (t >= NPADR) ? v : 0.f;
;       if (mode == 2) o = sigmf(v);
;       sT[row * 136 + col] = f2bf(o);
;     });
.LBB0_260:
	v_bfe_u32 v49, v48, 16, 1
	v_add3_u32 v48, v48, v49, s77
	ds_write_b16_d16_hi v110, v48 offset:64
	s_nop 1

; __device__ __forceinline__ float sigmf(float x) { return 1.f / (1.f + __expf(-x)); }
; __device__ __forceinline__ void inproj_epilogue(const Params& p, int layer, int mt, int ntile, int tid,
;                                                 f32x16 (&acc)[2][2], unsigned char* smem) {
;     ...
;     acc_foreach(tid, acc, [&](int row, int col, float v) {
;       int t = m0 + row;
;       float o = v;
;       if (mode == 1) o = (t >= NPADR) ? v : 0.f;
;       if (mode == 2) o = sigmf(v);
;       sT[row * 136 + col] = f2bf(o);
;     });
.LBB0_263:
	v_bfe_u32 v49, v48, 16, 1
	v_add3_u32 v48, v48, v49, s77
	ds_write_b16_d16_hi v111, v48 offset:64
	s_nop 1

; __device__ __forceinline__ float sigmf(float x) { return 1.f / (1.f + __expf(-x)); }
; __device__ __forceinline__ void inproj_epilogue(const Params& p, int layer, int mt, int ntile, int tid,
;                                                 f32x16 (&acc)[2][2], unsigned char* smem) {
;     ...
;     acc_foreach(tid, acc, [&](int row, int col, float v) {
;       int t = m0 + row;
;       float o = v;
;       if (mode == 1) o = (t >= NPADR) ? v : 0.f;
;       if (mode == 2) o = sigmf(v);
;       sT[row * 136 + col] = f2bf(o);
;     });
.LBB0_266:
	v_bfe_u32 v49, v48, 16, 1
	v_add3_u32 v48, v48, v49, s77
	ds_write_b16_d16_hi v112, v48 offset:64
	s_nop 1

; __device__ __forceinline__ float sigmf(float x) { return 1.f / (1.f + __expf(-x)); }
; __device__ __forceinline__ void inproj_epilogue(const Params& p, int layer, int mt, int ntile, int tid,
;                                                 f32x16 (&acc)[2][2], unsigned char* smem) {
;     ...
;     acc_foreach(tid, acc, [&](int row, int col, float v) {
;       int t = m0 + row;
;       float o = v;
;       if (mode == 1) o = (t >= NPADR) ? v : 0.f;
;       if (mode == 2) o = sigmf(v);
;       sT[row * 136 + col] = f2bf(o);
;     });
.LBB0_269:
	v_bfe_u32 v49, v48, 16, 1
	v_add3_u32 v48, v48, v49, s77
	ds_write_b16_d16_hi v113, v48 offset:64
	s_nop 1

; __device__ __forceinline__ float sigmf(float x) { return 1.f / (1.f + __expf(-x)); }
; __device__ __forceinline__ void inproj_epilogue(const Params& p, int layer, int mt, int ntile, int tid,
;                                                 f32x16 (&acc)[2][2], unsigned char* smem) {
;     ...
;     acc_foreach(tid, acc, [&](int row, int col, float v) {
;       int t = m0 + row;
;       float o = v;
;       if (mode == 1) o = (t >= NPADR) ? v : 0.f;
;       if (mode == 2) o = sigmf(v);
;       sT[row * 136 + col] = f2bf(o);
;     });
.LBB0_272:
	v_bfe_u32 v49, v48, 16, 1
	v_add3_u32 v48, v48, v49, s77
	ds_write_b16_d16_hi v114, v48 offset:64
	s_nop 1

; __device__ __forceinline__ float sigmf(float x) { return 1.f / (1.f + __expf(-x)); }
; __device__ __forceinline__ void inproj_epilogue(const Params& p, int layer, int mt, int ntile, int tid,
;                                                 f32x16 (&acc)[2][2], unsigned char* smem) {
;     ...
;     acc_foreach(tid, acc, [&](int row, int col, float v) {
;       int t = m0 + row;
;       float o = v;
;       if (mode == 1) o = (t >= NPADR) ? v : 0.f;
;       if (mode == 2) o = sigmf(v);
;       sT[row * 136 + col] = f2bf(o);
;     });
.LBB0_275:
	v_bfe_u32 v49, v48, 16, 1
	v_add3_u32 v48, v48, v49, s77
	ds_write_b16_d16_hi v115, v48 offset:64
	s_nop 1

; __device__ __forceinline__ float sigmf(float x) { return 1.f / (1.f + __expf(-x)); }
; __device__ __forceinline__ void inproj_epilogue(const Params& p, int layer, int mt, int ntile, int tid,
;                                                 f32x16 (&acc)[2][2], unsigned char* smem) {
;     ...
;     acc_foreach(tid, acc, [&](int row, int col, float v) {
;       int t = m0 + row;
;       float o = v;
;       if (mode == 1) o = (t >= NPADR) ? v : 0.f;
;       if (mode == 2) o = sigmf(v);
;       sT[row * 136 + col] = f2bf(o);
;     });
.LBB0_278:
	v_bfe_u32 v49, v48, 16, 1
	v_add3_u32 v48, v48, v49, s77
	ds_write_b16_d16_hi v117, v48 offset:64
	s_nop 1

; __device__ __forceinline__ float sigmf(float x) { return 1.f / (1.f + __expf(-x)); }
; __device__ __forceinline__ void inproj_epilogue(const Params& p, int layer, int mt, int ntile, int tid,
;                                                 f32x16 (&acc)[2][2], unsigned char* smem) {
;     ...
;     acc_foreach(tid, acc, [&](int row, int col, float v) {
;       int t = m0 + row;
;       float o = v;
;       if (mode == 1) o = (t >= NPADR) ? v : 0.f;
;       if (mode == 2) o = sigmf(v);
;       sT[row * 136 + col] = f2bf(o);
;     });
.LBB0_281:
	v_bfe_u32 v49, v48, 16, 1
	v_add3_u32 v48, v48, v49, s77
	ds_write_b16_d16_hi v118, v48 offset:64
	s_nop 1

; __device__ __forceinline__ float sigmf(float x) { return 1.f / (1.f + __expf(-x)); }
; __device__ __forceinline__ void inproj_epilogue(const Params& p, int layer, int mt, int ntile, int tid,
;                                                 f32x16 (&acc)[2][2], unsigned char* smem) {
;     ...
;     acc_foreach(tid, acc, [&](int row, int col, float v) {
;       int t = m0 + row;
;       float o = v;
;       if (mode == 1) o = (t >= NPADR) ? v : 0.f;
;       if (mode == 2) o = sigmf(v);
;       sT[row * 136 + col] = f2bf(o);
;     });
.LBB0_284:
	v_bfe_u32 v49, v48, 16, 1
	v_add3_u32 v48, v48, v49, s77
	ds_write_b16_d16_hi v119, v48 offset:64
	s_nop 1

; __device__ __forceinline__ float sigmf(float x) { return 1.f / (1.f + __expf(-x)); }
; __device__ __forceinline__ void inproj_epilogue(const Params& p, int layer, int mt, int ntile, int tid,
;                                                 f32x16 (&acc)[2][2], unsigned char* smem) {
;     ...
;     acc_foreach(tid, acc, [&](int row, int col, float v) {
;       int t = m0 + row;
;       float o = v;
;       if (mode == 1) o = (t >= NPADR) ? v : 0.f;
;       if (mode == 2) o = sigmf(v);
;       sT[row * 136 + col] = f2bf(o);
;     });
.LBB0_287:
	v_bfe_u32 v49, v48, 16, 1
	v_add3_u32 v48, v48, v49, s77
	ds_write_b16_d16_hi v120, v48 offset:64
	s_nop 1

; __device__ __forceinline__ float sigmf(float x) { return 1.f / (1.f + __expf(-x)); }
; __device__ __forceinline__ void inproj_epilogue(const Params& p, int layer, int mt, int ntile, int tid,
;                                                 f32x16 (&acc)[2][2], unsigned char* smem) {
;     ...
;     acc_foreach(tid, acc, [&](int row, int col, float v) {
;       int t = m0 + row;
;       float o = v;
;       if (mode == 1) o = (t >= NPADR) ? v : 0.f;
;       if (mode == 2) o = sigmf(v);
;       sT[row * 136 + col] = f2bf(o);
;     });
.LBB0_290:
	v_bfe_u32 v49, v48, 16, 1
	v_add3_u32 v48, v48, v49, s77
	ds_write_b16_d16_hi v121, v48 offset:64
	s_nop 1

; __device__ __forceinline__ float sigmf(float x) { return 1.f / (1.f + __expf(-x)); }
; __device__ __forceinline__ void inproj_epilogue(const Params& p, int layer, int mt, int ntile, int tid,
;                                                 f32x16 (&acc)[2][2], unsigned char* smem) {
;     ...
;     acc_foreach(tid, acc, [&](int row, int col, float v) {
;       int t = m0 + row;
;       float o = v;
;       if (mode == 1) o = (t >= NPADR) ? v : 0.f;
;       if (mode == 2) o = sigmf(v);
;       sT[row * 136 + col] = f2bf(o);
;     });
.LBB0_293:
	v_bfe_u32 v49, v48, 16, 1
	v_add3_u32 v48, v48, v49, s77
	ds_write_b16_d16_hi v122, v48 offset:64
	s_nop 1

; __device__ __forceinline__ float sigmf(float x) { return 1.f / (1.f + __expf(-x)); }
; __device__ __forceinline__ void inproj_epilogue(const Params& p, int layer, int mt, int ntile, int tid,
;                                                 f32x16 (&acc)[2][2], unsigned char* smem) {
;     ...
;     acc_foreach(tid, acc, [&](int row, int col, float v) {
;       int t = m0 + row;
;       float o = v;
;       if (mode == 1) o = (t >= NPADR) ? v : 0.f;
;       if (mode == 2) o = sigmf(v);
;       sT[row * 136 + col] = f2bf(o);
;     });
.LBB0_296:
	v_bfe_u32 v49, v48, 16, 1
	v_add3_u32 v48, v48, v49, s77
	ds_write_b16_d16_hi v123, v48 offset:64
	s_nop 1

; __device__ __forceinline__ float sigmf(float x) { return 1.f / (1.f + __expf(-x)); }
; __device__ __forceinline__ void inproj_epilogue(const Params& p, int layer, int mt, int ntile, int tid,
;                                                 f32x16 (&acc)[2][2], unsigned char* smem) {
;     ...
;     acc_foreach(tid, acc, [&](int row, int col, float v) {
;       int t = m0 + row;
;       float o = v;
;       if (mode == 1) o = (t >= NPADR) ? v : 0.f;
;       if (mode == 2) o = sigmf(v);
;       sT[row * 136 + col] = f2bf(o);
;     });
.LBB0_299:
	v_bfe_u32 v49, v48, 16, 1
	v_add3_u32 v48, v48, v49, s77
	ds_write_b16_d16_hi v116, v48 offset:64
	s_nop 1

; __device__ __forceinline__ float sigmf(float x) { return 1.f / (1.f + __expf(-x)); }
; template <int MT, int NT, class F>
; __device__ __forceinline__ void acc_foreach(int tid, f32x16 (&acc)[MT][NT], F f) {
;     ...
;         int row = wm * (MT * 32) + mt * 32 + (i & 3) + 8 * (i >> 2) + 4 * hi;
;         int col = wn * (NT * 32) + nt * 32 + c;
; __device__ __forceinline__ void inproj_epilogue(const Params& p, int layer, int mt, int ntile, int tid,
;                                                 f32x16 (&acc)[2][2], unsigned char* smem) {
;     ...
;     acc_foreach(tid, acc, [&](int row, int col, float v) {
;       int t = m0 + row;
;       float o = v;
;       if (mode == 1) o = (t >= NPADR) ? v : 0.f;
;       if (mode == 2) o = sigmf(v);
;       sT[row * 136 + col] = f2bf(o);
;     });
;     lds_tile_flush<128>(tid, sT, dstb, ld);
;   }
.LBB0_302:
	v_bfe_u32 v50, v48, 16, 1
	v_add_u32_e32 v49, 0x110, v116
	v_add3_u32 v48, v48, v50, s77
	ds_write_b16_d16_hi v49, v48 offset:64
	v_or_b32_e32 v48, 32, v96
	v_add_u32_e32 v49, s60, v48
	v_cmp_lt_i32_e64 s[8:9], s43, v49
	s_nop 1

; __device__ __forceinline__ float sigmf(float x) { return 1.f / (1.f + __expf(-x)); }
; template <int MT, int NT, class F>
; __device__ __forceinline__ void acc_foreach(int tid, f32x16 (&acc)[MT][NT], F f) {
;     ...
;         int row = wm * (MT * 32) + mt * 32 + (i & 3) + 8 * (i >> 2) + 4 * hi;
;         int col = wn * (NT * 32) + nt * 32 + c;
; __device__ __forceinline__ void inproj_epilogue(const Params& p, int layer, int mt, int ntile, int tid,
;                                                 f32x16 (&acc)[2][2], unsigned char* smem) {
;     ...
;     acc_foreach(tid, acc, [&](int row, int col, float v) {
;       int t = m0 + row;
;       float o = v;
;       if (mode == 1) o = (t >= NPADR) ? v : 0.f;
;       if (mode == 2) o = sigmf(v);
;       sT[row * 136 + col] = f2bf(o);
;     });
.LBB0_305:
	v_bfe_u32 v50, v49, 16, 1
	v_add3_u32 v50, v49, v50, s77
	v_mul_lo_u32 v49, v48, s78
	v_lshl_add_u32 v48, v106, 1, v49
	ds_write_b16_d16_hi v48, v50
	v_add3_u32 v50, s60, v96, 33
	v_cmp_lt_i32_e64 s[10:11], s43, v50
	s_nop 1

; __device__ __forceinline__ float sigmf(float x) { return 1.f / (1.f + __expf(-x)); }
; template <int MT, int NT, class F>
; __device__ __forceinline__ void acc_foreach(int tid, f32x16 (&acc)[MT][NT], F f) {
;     ...
;         int row = wm * (MT * 32) + mt * 32 + (i & 3) + 8 * (i >> 2) + 4 * hi;
;         int col = wn * (NT * 32) + nt * 32 + c;
; __device__ __forceinline__ void inproj_epilogue(const Params& p, int layer, int mt, int ntile, int tid,
;                                                 f32x16 (&acc)[2][2], unsigned char* smem) {
;     ...
;     acc_foreach(tid, acc, [&](int row, int col, float v) {
;       int t = m0 + row;
;       float o = v;
;       if (mode == 1) o = (t >= NPADR) ? v : 0.f;
;       if (mode == 2) o = sigmf(v);
;       sT[row * 136 + col] = f2bf(o);
;     });
.LBB0_308:
	v_bfe_u32 v51, v50, 16, 1
	v_add3_u32 v51, v50, v51, s77
	v_add_u32_e32 v50, 0x110, v49
	v_lshl_add_u32 v49, v106, 1, v50
	ds_write_b16_d16_hi v49, v51
	v_add3_u32 v51, s60, v96, 34
	v_cmp_lt_i32_e64 s[12:13], s43, v51
	s_nop 1

; __device__ __forceinline__ float sigmf(float x) { return 1.f / (1.f + __expf(-x)); }
; template <int MT, int NT, class F>
; __device__ __forceinline__ void acc_foreach(int tid, f32x16 (&acc)[MT][NT], F f) {
;     ...
;         int row = wm * (MT * 32) + mt * 32 + (i & 3) + 8 * (i >> 2) + 4 * hi;
;         int col = wn * (NT * 32) + nt * 32 + c;
; __device__ __forceinline__ void inproj_epilogue(const Params& p, int layer, int mt, int ntile, int tid,
;                                                 f32x16 (&acc)[2][2], unsigned char* smem) {
;     ...
;     acc_foreach(tid, acc, [&](int row, int col, float v) {
;       int t = m0 + row;
;       float o = v;
;       if (mode == 1) o = (t >= NPADR) ? v : 0.f;
;       if (mode == 2) o = sigmf(v);
;       sT[row * 136 + col] = f2bf(o);
;     });
.LBB0_311:
	v_bfe_u32 v52, v51, 16, 1
	v_add3_u32 v52, v51, v52, s77
	v_add_u32_e32 v51, 0x110, v50
	v_lshl_add_u32 v50, v106, 1, v51
	ds_write_b16_d16_hi v50, v52
	v_add3_u32 v52, s60, v96, 35
	v_cmp_lt_i32_e64 s[14:15], s43, v52
	s_nop 1

; __device__ __forceinline__ float sigmf(float x) { return 1.f / (1.f + __expf(-x)); }
; template <int MT, int NT, class F>
; __device__ __forceinline__ void acc_foreach(int tid, f32x16 (&acc)[MT][NT], F f) {
;     ...
;         int row = wm * (MT * 32) + mt * 32 + (i & 3) + 8 * (i >> 2) + 4 * hi;
;         int col = wn * (NT * 32) + nt * 32 + c;
; __device__ __forceinline__ void inproj_epilogue(const Params& p, int layer, int mt, int ntile, int tid,
;                                                 f32x16 (&acc)[2][2], unsigned char* smem) {
;     ...
;     acc_foreach(tid, acc, [&](int row, int col, float v) {
;       int t = m0 + row;
;       float o = v;
;       if (mode == 1) o = (t >= NPADR) ? v : 0.f;
;       if (mode == 2) o = sigmf(v);
;       sT[row * 136 + col] = f2bf(o);
;     });
.LBB0_314:
	v_bfe_u32 v53, v52, 16, 1
	v_add3_u32 v53, v52, v53, s77
	v_add_u32_e32 v52, 0x110, v51
	v_lshl_add_u32 v51, v106, 1, v52
	ds_write_b16_d16_hi v51, v53
	v_add3_u32 v53, s60, v96, 40
	v_cmp_lt_i32_e64 s[16:17], s43, v53
	s_nop 1

; __device__ __forceinline__ float sigmf(float x) { return 1.f / (1.f + __expf(-x)); }
; template <int MT, int NT, class F>
; __device__ __forceinline__ void acc_foreach(int tid, f32x16 (&acc)[MT][NT], F f) {
;     ...
;         int row = wm * (MT * 32) + mt * 32 + (i & 3) + 8 * (i >> 2) + 4 * hi;
;         int col = wn * (NT * 32) + nt * 32 + c;
; __device__ __forceinline__ void inproj_epilogue(const Params& p, int layer, int mt, int ntile, int tid,
;                                                 f32x16 (&acc)[2][2], unsigned char* smem) {
;     ...
;     acc_foreach(tid, acc, [&](int row, int col, float v) {
;       int t = m0 + row;
;       float o = v;
;       if (mode == 1) o = (t >= NPADR) ? v : 0.f;
;       if (mode == 2) o = sigmf(v);
;       sT[row * 136 + col] = f2bf(o);
;     });
.LBB0_317:
	v_bfe_u32 v54, v53, 16, 1
	v_add3_u32 v54, v53, v54, s77
	v_add_u32_e32 v53, 0x550, v52
	v_lshl_add_u32 v52, v106, 1, v53
	ds_write_b16_d16_hi v52, v54
	v_add3_u32 v54, s60, v96, 41
	v_cmp_lt_i32_e64 s[18:19], s43, v54
	s_nop 1

; __device__ __forceinline__ float sigmf(float x) { return 1.f / (1.f + __expf(-x)); }
; template <int MT, int NT, class F>
; __device__ __forceinline__ void acc_foreach(int tid, f32x16 (&acc)[MT][NT], F f) {
;     ...
;         int row = wm * (MT * 32) + mt * 32 + (i & 3) + 8 * (i >> 2) + 4 * hi;
;         int col = wn * (NT * 32) + nt * 32 + c;
; __device__ __forceinline__ void inproj_epilogue(const Params& p, int layer, int mt, int ntile, int tid,
;                                                 f32x16 (&acc)[2][2], unsigned char* smem) {
;     ...
;     acc_foreach(tid, acc, [&](int row, int col, float v) {
;       int t = m0 + row;
;       float o = v;
;       if (mode == 1) o = (t >= NPADR) ? v : 0.f;
;       if (mode == 2) o = sigmf(v);
;       sT[row * 136 + col] = f2bf(o);
;     });
.LBB0_320:
	v_bfe_u32 v55, v54, 16, 1
	v_add3_u32 v55, v54, v55, s77
	v_add_u32_e32 v54, 0x110, v53
	v_lshl_add_u32 v53, v106, 1, v54
	ds_write_b16_d16_hi v53, v55
	v_add3_u32 v55, s60, v96, 42
	v_cmp_lt_i32_e64 s[20:21], s43, v55
	s_nop 1

; __device__ __forceinline__ float sigmf(float x) { return 1.f / (1.f + __expf(-x)); }
; template <int MT, int NT, class F>
; __device__ __forceinline__ void acc_foreach(int tid, f32x16 (&acc)[MT][NT], F f) {
;     ...
;         int row = wm * (MT * 32) + mt * 32 + (i & 3) + 8 * (i >> 2) + 4 * hi;
;         int col = wn * (NT * 32) + nt * 32 + c;
; __device__ __forceinline__ void inproj_epilogue(const Params& p, int layer, int mt, int ntile, int tid,
;                                                 f32x16 (&acc)[2][2], unsigned char* smem) {
;     ...
;     acc_foreach(tid, acc, [&](int row, int col, float v) {
;       int t = m0 + row;
;       float o = v;
;       if (mode == 1) o = (t >= NPADR) ? v : 0.f;
;       if (mode == 2) o = sigmf(v);
;       sT[row * 136 + col] = f2bf(o);
;     });
.LBB0_323:
	v_bfe_u32 v56, v55, 16, 1
	v_add3_u32 v56, v55, v56, s77
	v_add_u32_e32 v55, 0x110, v54
	v_lshl_add_u32 v54, v106, 1, v55
	ds_write_b16_d16_hi v54, v56
	v_add3_u32 v56, s60, v96, 43
	v_cmp_lt_i32_e64 s[22:23], s43, v56
	s_nop 1

; __device__ __forceinline__ float sigmf(float x) { return 1.f / (1.f + __expf(-x)); }
; template <int MT, int NT, class F>
; __device__ __forceinline__ void acc_foreach(int tid, f32x16 (&acc)[MT][NT], F f) {
;     ...
;         int row = wm * (MT * 32) + mt * 32 + (i & 3) + 8 * (i >> 2) + 4 * hi;
;         int col = wn * (NT * 32) + nt * 32 + c;
; __device__ __forceinline__ void inproj_epilogue(const Params& p, int layer, int mt, int ntile, int tid,
;                                                 f32x16 (&acc)[2][2], unsigned char* smem) {
;     ...
;     acc_foreach(tid, acc, [&](int row, int col, float v) {
;       int t = m0 + row;
;       float o = v;
;       if (mode == 1) o = (t >= NPADR) ? v : 0.f;
;       if (mode == 2) o = sigmf(v);
;       sT[row * 136 + col] = f2bf(o);
;     });
.LBB0_326:
	v_bfe_u32 v57, v56, 16, 1
	v_add_u32_e32 v55, 0x110, v55
	v_add3_u32 v57, v56, v57, s77
	v_lshl_add_u32 v56, v106, 1, v55
	ds_write_b16_d16_hi v56, v57
	v_add3_u32 v57, s60, v96, 48
	v_cmp_lt_i32_e64 s[24:25], s43, v57
	s_nop 1

; __device__ __forceinline__ float sigmf(float x) { return 1.f / (1.f + __expf(-x)); }
; template <int MT, int NT, class F>
; __device__ __forceinline__ void acc_foreach(int tid, f32x16 (&acc)[MT][NT], F f) {
;     ...
;         int row = wm * (MT * 32) + mt * 32 + (i & 3) + 8 * (i >> 2) + 4 * hi;
;         int col = wn * (NT * 32) + nt * 32 + c;
; __device__ __forceinline__ void inproj_epilogue(const Params& p, int layer, int mt, int ntile, int tid,
;                                                 f32x16 (&acc)[2][2], unsigned char* smem) {
;     ...
;     acc_foreach(tid, acc, [&](int row, int col, float v) {
;       int t = m0 + row;
;       float o = v;
;       if (mode == 1) o = (t >= NPADR) ? v : 0.f;
;       if (mode == 2) o = sigmf(v);
;       sT[row * 136 + col] = f2bf(o);
;     });
.LBB0_329:
	v_bfe_u32 v58, v57, 16, 1
	v_add_u32_e32 v55, 0x550, v55
	v_add3_u32 v58, v57, v58, s77
	v_lshl_add_u32 v57, v106, 1, v55
	ds_write_b16_d16_hi v57, v58
	v_add3_u32 v58, s60, v96, 49
	v_cmp_lt_i32_e64 s[26:27], s43, v58
	s_nop 1

; __device__ __forceinline__ float sigmf(float x) { return 1.f / (1.f + __expf(-x)); }
; template <int MT, int NT, class F>
; __device__ __forceinline__ void acc_foreach(int tid, f32x16 (&acc)[MT][NT], F f) {
;     ...
;         int row = wm * (MT * 32) + mt * 32 + (i & 3) + 8 * (i >> 2) + 4 * hi;
;         int col = wn * (NT * 32) + nt * 32 + c;
; __device__ __forceinline__ void inproj_epilogue(const Params& p, int layer, int mt, int ntile, int tid,
;                                                 f32x16 (&acc)[2][2], unsigned char* smem) {
;     ...
;     acc_foreach(tid, acc, [&](int row, int col, float v) {
;       int t = m0 + row;
;       float o = v;
;       if (mode == 1) o = (t >= NPADR) ? v : 0.f;
;       if (mode == 2) o = sigmf(v);
;       sT[row * 136 + col] = f2bf(o);
;     });
.LBB0_332:
	v_bfe_u32 v59, v58, 16, 1
	v_add_u32_e32 v55, 0x110, v55
	v_add3_u32 v59, v58, v59, s77
	v_lshl_add_u32 v58, v106, 1, v55
	ds_write_b16_d16_hi v58, v59
	v_add3_u32 v59, s60, v96, 50
	v_cmp_lt_i32_e64 s[28:29], s43, v59
	s_nop 1

; __device__ __forceinline__ float sigmf(float x) { return 1.f / (1.f + __expf(-x)); }
; template <int MT, int NT, class F>
; __device__ __forceinline__ void acc_foreach(int tid, f32x16 (&acc)[MT][NT], F f) {
;     ...
;         int row = wm * (MT * 32) + mt * 32 + (i & 3) + 8 * (i >> 2) + 4 * hi;
;         int col = wn * (NT * 32) + nt * 32 + c;
; __device__ __forceinline__ void inproj_epilogue(const Params& p, int layer, int mt, int ntile, int tid,
;                                                 f32x16 (&acc)[2][2], unsigned char* smem) {
;     ...
;     acc_foreach(tid, acc, [&](int row, int col, float v) {
;       int t = m0 + row;
;       float o = v;
;       if (mode == 1) o = (t >= NPADR) ? v : 0.f;
;       if (mode == 2) o = sigmf(v);
;       sT[row * 136 + col] = f2bf(o);
;     });
.LBB0_335:
	v_bfe_u32 v60, v59, 16, 1
	v_add_u32_e32 v55, 0x110, v55
	v_add3_u32 v60, v59, v60, s77
	v_lshl_add_u32 v59, v106, 1, v55
	ds_write_b16_d16_hi v59, v60
	v_add3_u32 v60, s60, v96, 51
	v_cmp_lt_i32_e64 s[30:31], s43, v60
	s_nop 1

; __device__ __forceinline__ float sigmf(float x) { return 1.f / (1.f + __expf(-x)); }
; template <int MT, int NT, class F>
; __device__ __forceinline__ void acc_foreach(int tid, f32x16 (&acc)[MT][NT], F f) {
;     ...
;         int row = wm * (MT * 32) + mt * 32 + (i & 3) + 8 * (i >> 2) + 4 * hi;
;         int col = wn * (NT * 32) + nt * 32 + c;
; __device__ __forceinline__ void inproj_epilogue(const Params& p, int layer, int mt, int ntile, int tid,
;                                                 f32x16 (&acc)[2][2], unsigned char* smem) {
;     ...
;     acc_foreach(tid, acc, [&](int row, int col, float v) {
;       int t = m0 + row;
;       float o = v;
;       if (mode == 1) o = (t >= NPADR) ? v : 0.f;
;       if (mode == 2) o = sigmf(v);
;       sT[row * 136 + col] = f2bf(o);
;     });
.LBB0_338:
	v_bfe_u32 v61, v60, 16, 1
	v_add_u32_e32 v55, 0x110, v55
	v_add3_u32 v61, v60, v61, s77
	v_lshl_add_u32 v60, v106, 1, v55
	ds_write_b16_d16_hi v60, v61
	v_add3_u32 v61, s60, v96, 56
	v_cmp_lt_i32_e64 s[34:35], s43, v61
	s_nop 1

; __device__ __forceinline__ float sigmf(float x) { return 1.f / (1.f + __expf(-x)); }
; template <int MT, int NT, class F>
; __device__ __forceinline__ void acc_foreach(int tid, f32x16 (&acc)[MT][NT], F f) {
;     ...
;         int row = wm * (MT * 32) + mt * 32 + (i & 3) + 8 * (i >> 2) + 4 * hi;
;         int col = wn * (NT * 32) + nt * 32 + c;
; __device__ __forceinline__ void inproj_epilogue(const Params& p, int layer, int mt, int ntile, int tid,
;                                                 f32x16 (&acc)[2][2], unsigned char* smem) {
;     ...
;     acc_foreach(tid, acc, [&](int row, int col, float v) {
;       int t = m0 + row;
;       float o = v;
;       if (mode == 1) o = (t >= NPADR) ? v : 0.f;
;       if (mode == 2) o = sigmf(v);
;       sT[row * 136 + col] = f2bf(o);
;     });
.LBB0_341:
	v_bfe_u32 v62, v61, 16, 1
	v_add_u32_e32 v55, 0x550, v55
	v_add3_u32 v62, v61, v62, s77
	v_lshl_add_u32 v61, v106, 1, v55
	ds_write_b16_d16_hi v61, v62
	v_add3_u32 v62, s60, v96, 57
	v_cmp_lt_i32_e64 s[36:37], s43, v62
	s_nop 1

; __device__ __forceinline__ float sigmf(float x) { return 1.f / (1.f + __expf(-x)); }
; template <int MT, int NT, class F>
; __device__ __forceinline__ void acc_foreach(int tid, f32x16 (&acc)[MT][NT], F f) {
;     ...
;         int row = wm * (MT * 32) + mt * 32 + (i & 3) + 8 * (i >> 2) + 4 * hi;
;         int col = wn * (NT * 32) + nt * 32 + c;
; __device__ __forceinline__ void inproj_epilogue(const Params& p, int layer, int mt, int ntile, int tid,
;                                                 f32x16 (&acc)[2][2], unsigned char* smem) {
;     ...
;     acc_foreach(tid, acc, [&](int row, int col, float v) {
;       int t = m0 + row;
;       float o = v;
;       if (mode == 1) o = (t >= NPADR) ? v : 0.f;
;       if (mode == 2) o = sigmf(v);
;       sT[row * 136 + col] = f2bf(o);
;     });
.LBB0_344:
	v_bfe_u32 v63, v62, 16, 1
	v_add_u32_e32 v55, 0x110, v55
	v_add3_u32 v63, v62, v63, s77
	v_lshl_add_u32 v62, v106, 1, v55
	ds_write_b16_d16_hi v62, v63
	v_add3_u32 v63, s60, v96, 58
	v_cmp_lt_i32_e64 s[38:39], s43, v63
	s_nop 1

; __device__ __forceinline__ float sigmf(float x) { return 1.f / (1.f + __expf(-x)); }
; template <int MT, int NT, class F>
; __device__ __forceinline__ void acc_foreach(int tid, f32x16 (&acc)[MT][NT], F f) {
;     ...
;         int row = wm * (MT * 32) + mt * 32 + (i & 3) + 8 * (i >> 2) + 4 * hi;
;         int col = wn * (NT * 32) + nt * 32 + c;
; __device__ __forceinline__ void inproj_epilogue(const Params& p, int layer, int mt, int ntile, int tid,
;                                                 f32x16 (&acc)[2][2], unsigned char* smem) {
;     ...
;     acc_foreach(tid, acc, [&](int row, int col, float v) {
;       int t = m0 + row;
;       float o = v;
;       if (mode == 1) o = (t >= NPADR) ? v : 0.f;
;       if (mode == 2) o = sigmf(v);
;       sT[row * 136 + col] = f2bf(o);
;     });
.LBB0_347:
	v_bfe_u32 v107, v63, 16, 1
	v_add_u32_e32 v55, 0x110, v55
	v_add3_u32 v63, v63, v107, s77
	v_lshl_add_u32 v55, v106, 1, v55
	ds_write_b16_d16_hi v55, v63
	v_add3_u32 v63, s60, v96, 59
	v_cmp_lt_i32_e64 s[40:41], s43, v63
	s_nop 1

; __device__ __forceinline__ float sigmf(float x) { return 1.f / (1.f + __expf(-x)); }
; __device__ __forceinline__ void inproj_epilogue(const Params& p, int layer, int mt, int ntile, int tid,
;                                                 f32x16 (&acc)[2][2], unsigned char* smem) {
;     ...
;     acc_foreach(tid, acc, [&](int row, int col, float v) {
;       int t = m0 + row;
;       float o = v;
;       if (mode == 1) o = (t >= NPADR) ? v : 0.f;
;       if (mode == 2) o = sigmf(v);
;       sT[row * 136 + col] = f2bf(o);
;     });
.LBB0_350:
	v_bfe_u32 v96, v63, 16, 1
	v_add3_u32 v63, v63, v96, s77
	ds_write_b16_d16_hi v55, v63 offset:272
	s_nop 1

; __device__ __forceinline__ float sigmf(float x) { return 1.f / (1.f + __expf(-x)); }
; __device__ __forceinline__ void inproj_epilogue(const Params& p, int layer, int mt, int ntile, int tid,
;                                                 f32x16 (&acc)[2][2], unsigned char* smem) {
;     ...
;     acc_foreach(tid, acc, [&](int row, int col, float v) {
;       int t = m0 + row;
;       float o = v;
;       if (mode == 1) o = (t >= NPADR) ? v : 0.f;
;       if (mode == 2) o = sigmf(v);
;       sT[row * 136 + col] = f2bf(o);
;     });
.LBB0_353:
	v_bfe_u32 v63, v32, 16, 1
	v_add3_u32 v32, v32, v63, s77
	ds_write_b16_d16_hi v48, v32 offset:64
	s_nop 1

; __device__ __forceinline__ float sigmf(float x) { return 1.f / (1.f + __expf(-x)); }
; __device__ __forceinline__ void inproj_epilogue(const Params& p, int layer, int mt, int ntile, int tid,
;                                                 f32x16 (&acc)[2][2], unsigned char* smem) {
;     ...
;     acc_foreach(tid, acc, [&](int row, int col, float v) {
;       int t = m0 + row;
;       float o = v;
;       if (mode == 1) o = (t >= NPADR) ? v : 0.f;
;       if (mode == 2) o = sigmf(v);
;       sT[row * 136 + col] = f2bf(o);
;     });
.LBB0_356:
	v_bfe_u32 v33, v32, 16, 1
	v_add3_u32 v32, v32, v33, s77
	ds_write_b16_d16_hi v49, v32 offset:64
	s_nop 1

; __device__ __forceinline__ float sigmf(float x) { return 1.f / (1.f + __expf(-x)); }
; __device__ __forceinline__ void inproj_epilogue(const Params& p, int layer, int mt, int ntile, int tid,
;                                                 f32x16 (&acc)[2][2], unsigned char* smem) {
;     ...
;     acc_foreach(tid, acc, [&](int row, int col, float v) {
;       int t = m0 + row;
;       float o = v;
;       if (mode == 1) o = (t >= NPADR) ? v : 0.f;
;       if (mode == 2) o = sigmf(v);
;       sT[row * 136 + col] = f2bf(o);
;     });
.LBB0_359:
	v_bfe_u32 v33, v32, 16, 1
	v_add3_u32 v32, v32, v33, s77
	ds_write_b16_d16_hi v50, v32 offset:64
	s_nop 1

; __device__ __forceinline__ float sigmf(float x) { return 1.f / (1.f + __expf(-x)); }
; __device__ __forceinline__ void inproj_epilogue(const Params& p, int layer, int mt, int ntile, int tid,
;                                                 f32x16 (&acc)[2][2], unsigned char* smem) {
;     ...
;     acc_foreach(tid, acc, [&](int row, int col, float v) {
;       int t = m0 + row;
;       float o = v;
;       if (mode == 1) o = (t >= NPADR) ? v : 0.f;
;       if (mode == 2) o = sigmf(v);
;       sT[row * 136 + col] = f2bf(o);
;     });
.LBB0_362:
	v_bfe_u32 v33, v32, 16, 1
	v_add3_u32 v32, v32, v33, s77
	ds_write_b16_d16_hi v51, v32 offset:64
	s_nop 1

; __device__ __forceinline__ float sigmf(float x) { return 1.f / (1.f + __expf(-x)); }
; __device__ __forceinline__ void inproj_epilogue(const Params& p, int layer, int mt, int ntile, int tid,
;                                                 f32x16 (&acc)[2][2], unsigned char* smem) {
;     ...
;     acc_foreach(tid, acc, [&](int row, int col, float v) {
;       int t = m0 + row;
;       float o = v;
;       if (mode == 1) o = (t >= NPADR) ? v : 0.f;
;       if (mode == 2) o = sigmf(v);
;       sT[row * 136 + col] = f2bf(o);
;     });
.LBB0_365:
	v_bfe_u32 v33, v32, 16, 1
	v_add3_u32 v32, v32, v33, s77
	ds_write_b16_d16_hi v52, v32 offset:64
	s_nop 1

; __device__ __forceinline__ float sigmf(float x) { return 1.f / (1.f + __expf(-x)); }
; __device__ __forceinline__ void inproj_epilogue(const Params& p, int layer, int mt, int ntile, int tid,
;                                                 f32x16 (&acc)[2][2], unsigned char* smem) {
;     ...
;     acc_foreach(tid, acc, [&](int row, int col, float v) {
;       int t = m0 + row;
;       float o = v;
;       if (mode == 1) o = (t >= NPADR) ? v : 0.f;
;       if (mode == 2) o = sigmf(v);
;       sT[row * 136 + col] = f2bf(o);
;     });
.LBB0_368:
	v_bfe_u32 v33, v32, 16, 1
	v_add3_u32 v32, v32, v33, s77
	ds_write_b16_d16_hi v53, v32 offset:64
	s_nop 1

; __device__ __forceinline__ float sigmf(float x) { return 1.f / (1.f + __expf(-x)); }
; __device__ __forceinline__ void inproj_epilogue(const Params& p, int layer, int mt, int ntile, int tid,
;                                                 f32x16 (&acc)[2][2], unsigned char* smem) {
;     ...
;     acc_foreach(tid, acc, [&](int row, int col, float v) {
;       int t = m0 + row;
;       float o = v;
;       if (mode == 1) o = (t >= NPADR) ? v : 0.f;
;       if (mode == 2) o = sigmf(v);
;       sT[row * 136 + col] = f2bf(o);
;     });
.LBB0_371:
	v_bfe_u32 v33, v32, 16, 1
	v_add3_u32 v32, v32, v33, s77
	ds_write_b16_d16_hi v54, v32 offset:64
	s_nop 1

; __device__ __forceinline__ float sigmf(float x) { return 1.f / (1.f + __expf(-x)); }
; __device__ __forceinline__ void inproj_epilogue(const Params& p, int layer, int mt, int ntile, int tid,
;                                                 f32x16 (&acc)[2][2], unsigned char* smem) {
;     ...
;     acc_foreach(tid, acc, [&](int row, int col, float v) {
;       int t = m0 + row;
;       float o = v;
;       if (mode == 1) o = (t >= NPADR) ? v : 0.f;
;       if (mode == 2) o = sigmf(v);
;       sT[row * 136 + col] = f2bf(o);
;     });
.LBB0_374:
	v_bfe_u32 v33, v32, 16, 1
	v_add3_u32 v32, v32, v33, s77
	ds_write_b16_d16_hi v56, v32 offset:64
	s_nop 1

; __device__ __forceinline__ float sigmf(float x) { return 1.f / (1.f + __expf(-x)); }
; __device__ __forceinline__ void inproj_epilogue(const Params& p, int layer, int mt, int ntile, int tid,
;                                                 f32x16 (&acc)[2][2], unsigned char* smem) {
;     ...
;     acc_foreach(tid, acc, [&](int row, int col, float v) {
;       int t = m0 + row;
;       float o = v;
;       if (mode == 1) o = (t >= NPADR) ? v : 0.f;
;       if (mode == 2) o = sigmf(v);
;       sT[row * 136 + col] = f2bf(o);
;     });
.LBB0_377:
	v_bfe_u32 v33, v32, 16, 1
	v_add3_u32 v32, v32, v33, s77
	ds_write_b16_d16_hi v57, v32 offset:64
	s_nop 1

; __device__ __forceinline__ float sigmf(float x) { return 1.f / (1.f + __expf(-x)); }
; __device__ __forceinline__ void inproj_epilogue(const Params& p, int layer, int mt, int ntile, int tid,
;                                                 f32x16 (&acc)[2][2], unsigned char* smem) {
;     ...
;     acc_foreach(tid, acc, [&](int row, int col, float v) {
;       int t = m0 + row;
;       float o = v;
;       if (mode == 1) o = (t >= NPADR) ? v : 0.f;
;       if (mode == 2) o = sigmf(v);
;       sT[row * 136 + col] = f2bf(o);
;     });
.LBB0_380:
	v_bfe_u32 v33, v32, 16, 1
	v_add3_u32 v32, v32, v33, s77
	ds_write_b16_d16_hi v58, v32 offset:64
	s_nop 1

; __device__ __forceinline__ float sigmf(float x) { return 1.f / (1.f + __expf(-x)); }
; __device__ __forceinline__ void inproj_epilogue(const Params& p, int layer, int mt, int ntile, int tid,
;                                                 f32x16 (&acc)[2][2], unsigned char* smem) {
;     ...
;     acc_foreach(tid, acc, [&](int row, int col, float v) {
;       int t = m0 + row;
;       float o = v;
;       if (mode == 1) o = (t >= NPADR) ? v : 0.f;
;       if (mode == 2) o = sigmf(v);
;       sT[row * 136 + col] = f2bf(o);
;     });
.LBB0_383:
	v_bfe_u32 v33, v32, 16, 1
	v_add3_u32 v32, v32, v33, s77
	ds_write_b16_d16_hi v59, v32 offset:64
	s_nop 1

; __device__ __forceinline__ float sigmf(float x) { return 1.f / (1.f + __expf(-x)); }
; __device__ __forceinline__ void inproj_epilogue(const Params& p, int layer, int mt, int ntile, int tid,
;                                                 f32x16 (&acc)[2][2], unsigned char* smem) {
;     ...
;     acc_foreach(tid, acc, [&](int row, int col, float v) {
;       int t = m0 + row;
;       float o = v;
;       if (mode == 1) o = (t >= NPADR) ? v : 0.f;
;       if (mode == 2) o = sigmf(v);
;       sT[row * 136 + col] = f2bf(o);
;     });
.LBB0_386:
	v_bfe_u32 v33, v32, 16, 1
	v_add3_u32 v32, v32, v33, s77
	ds_write_b16_d16_hi v60, v32 offset:64
	s_nop 1

; __device__ __forceinline__ float sigmf(float x) { return 1.f / (1.f + __expf(-x)); }
; __device__ __forceinline__ void inproj_epilogue(const Params& p, int layer, int mt, int ntile, int tid,
;                                                 f32x16 (&acc)[2][2], unsigned char* smem) {
;     ...
;     acc_foreach(tid, acc, [&](int row, int col, float v) {
;       int t = m0 + row;
;       float o = v;
;       if (mode == 1) o = (t >= NPADR) ? v : 0.f;
;       if (mode == 2) o = sigmf(v);
;       sT[row * 136 + col] = f2bf(o);
;     });
.LBB0_389:
	v_bfe_u32 v33, v32, 16, 1
	v_add3_u32 v32, v32, v33, s77
	ds_write_b16_d16_hi v61, v32 offset:64
	s_nop 1

; __device__ __forceinline__ float sigmf(float x) { return 1.f / (1.f + __expf(-x)); }
; __device__ __forceinline__ void inproj_epilogue(const Params& p, int layer, int mt, int ntile, int tid,
;                                                 f32x16 (&acc)[2][2], unsigned char* smem) {
;     ...
;     acc_foreach(tid, acc, [&](int row, int col, float v) {
;       int t = m0 + row;
;       float o = v;
;       if (mode == 1) o = (t >= NPADR) ? v : 0.f;
;       if (mode == 2) o = sigmf(v);
;       sT[row * 136 + col] = f2bf(o);
;     });
.LBB0_392:
	v_bfe_u32 v33, v32, 16, 1
	v_add3_u32 v32, v32, v33, s77
	ds_write_b16_d16_hi v62, v32 offset:64
	s_nop 1

; __device__ __forceinline__ float sigmf(float x) { return 1.f / (1.f + __expf(-x)); }
; __device__ __forceinline__ void inproj_epilogue(const Params& p, int layer, int mt, int ntile, int tid,
;                                                 f32x16 (&acc)[2][2], unsigned char* smem) {
;     ...
;     acc_foreach(tid, acc, [&](int row, int col, float v) {
;       int t = m0 + row;
;       float o = v;
;       if (mode == 1) o = (t >= NPADR) ? v : 0.f;
;       if (mode == 2) o = sigmf(v);
;       sT[row * 136 + col] = f2bf(o);
;     });
.LBB0_395:
	v_bfe_u32 v33, v32, 16, 1
	v_add3_u32 v32, v32, v33, s77
	ds_write_b16_d16_hi v55, v32 offset:64
	s_nop 1

; __device__ __forceinline__ float sigmf(float x) { return 1.f / (1.f + __expf(-x)); }
; template <int MT, int NT, class F>
; __device__ __forceinline__ void acc_foreach(int tid, f32x16 (&acc)[MT][NT], F f) {
;     ...
;         int row = wm * (MT * 32) + mt * 32 + (i & 3) + 8 * (i >> 2) + 4 * hi;
;         int col = wn * (NT * 32) + nt * 32 + c;
; __device__ __forceinline__ void inproj_epilogue(const Params& p, int layer, int mt, int ntile, int tid,
;                                                 f32x16 (&acc)[2][2], unsigned char* smem) {
;     ...
;       if (mode == 2) o = sigmf(v);
;       sT[row * 136 + col] = f2bf(o);
.Lgv_0:
	v_mul_f32_e32 v107, 0xbfb8aa3b, v16
	v_exp_f32_e32 v107, v107
	s_nop 0
	v_add_f32_e32 v107, 1.0, v107
	v_div_scale_f32 v110, s[6:7], v107, v107, 1.0
	v_rcp_f32_e32 v111, v110
	v_div_scale_f32 v112, vcc, 1.0, v107, 1.0
	v_fma_f32 v113, -v110, v111, 1.0
	v_fmac_f32_e32 v111, v113, v111
	v_mul_f32_e32 v113, v112, v111
	v_fma_f32 v114, -v110, v113, v112
	v_fmac_f32_e32 v113, v114, v111
	v_fma_f32 v110, -v110, v113, v112
	v_div_fmas_f32 v110, v110, v111, v113
	v_div_fixup_f32 v107, v110, v107, 1.0
	v_bfe_u32 v110, v107, 16, 1
	v_and_b32_e32 v106, 0x5f, v106
	v_add3_u32 v111, v107, v110, s77
	v_mul_lo_u32 v110, v96, s78
	v_lshl_add_u32 v107, v106, 1, v110
	ds_write_b16_d16_hi v107, v111
	v_add3_u32 v111, s60, v96, 1
	v_cmp_lt_i32_e64 s[10:11], s43, v111
	v_cndmask_b32_e64 v111, 0, 1, s[12:13]
	v_cmp_ne_u32_e64 s[6:7], 1, v111
	s_andn2_b64 vcc, exec, s[12:13]
	v_mul_f32_e32 v111, 0xbfb8aa3b, v17
	v_exp_f32_e32 v111, v111
	s_nop 0
	v_add_f32_e32 v111, 1.0, v111
	v_div_scale_f32 v112, s[12:13], v111, v111, 1.0
	v_rcp_f32_e32 v113, v112
	v_div_scale_f32 v114, vcc, 1.0, v111, 1.0
	v_fma_f32 v115, -v112, v113, 1.0
	v_fmac_f32_e32 v113, v115, v113
	v_mul_f32_e32 v115, v114, v113
	v_fma_f32 v116, -v112, v115, v114
	v_fmac_f32_e32 v115, v116, v113
	v_fma_f32 v112, -v112, v115, v114
	v_div_fmas_f32 v112, v112, v113, v115
	v_div_fixup_f32 v111, v112, v111, 1.0
	v_bfe_u32 v112, v111, 16, 1
	v_add3_u32 v112, v111, v112, s77
	v_add_u32_e32 v111, 0x110, v110
	v_lshl_add_u32 v110, v106, 1, v111
	ds_write_b16_d16_hi v110, v112
	v_add3_u32 v112, s60, v96, 2
	s_and_b64 vcc, exec, s[6:7]
	v_cmp_lt_i32_e64 s[12:13], s43, v112
	v_mul_f32_e32 v112, 0xbfb8aa3b, v18
	v_exp_f32_e32 v112, v112
	s_nop 0
	v_add_f32_e32 v112, 1.0, v112
	v_div_scale_f32 v113, s[14:15], v112, v112, 1.0
	v_rcp_f32_e32 v114, v113
	v_div_scale_f32 v115, vcc, 1.0, v112, 1.0
	v_fma_f32 v116, -v113, v114, 1.0
	v_fmac_f32_e32 v114, v116, v114
	v_mul_f32_e32 v116, v115, v114
	v_fma_f32 v117, -v113, v116, v115
	v_fmac_f32_e32 v116, v117, v114
	v_fma_f32 v113, -v113, v116, v115
	v_div_fmas_f32 v113, v113, v114, v116
	v_div_fixup_f32 v112, v113, v112, 1.0
	v_bfe_u32 v113, v112, 16, 1
	v_add3_u32 v113, v112, v113, s77
	v_add_u32_e32 v112, 0x110, v111
	v_lshl_add_u32 v111, v106, 1, v112
	ds_write_b16_d16_hi v111, v113
	v_add3_u32 v113, s60, v96, 3
	s_and_b64 vcc, exec, s[6:7]
	v_cmp_lt_i32_e64 s[14:15], s43, v113
	v_mul_f32_e32 v113, 0xbfb8aa3b, v19
	v_exp_f32_e32 v113, v113
	s_nop 0
	v_add_f32_e32 v113, 1.0, v113
	v_div_scale_f32 v114, s[16:17], v113, v113, 1.0
	v_rcp_f32_e32 v115, v114
	v_div_scale_f32 v116, vcc, 1.0, v113, 1.0
	v_fma_f32 v117, -v114, v115, 1.0
	v_fmac_f32_e32 v115, v117, v115
	v_mul_f32_e32 v117, v116, v115
	v_fma_f32 v118, -v114, v117, v116
	v_fmac_f32_e32 v117, v118, v115
	v_fma_f32 v114, -v114, v117, v116
	v_div_fmas_f32 v114, v114, v115, v117
	v_div_fixup_f32 v113, v114, v113, 1.0
	v_bfe_u32 v114, v113, 16, 1
	v_add3_u32 v114, v113, v114, s77
	v_add_u32_e32 v113, 0x110, v112
	v_lshl_add_u32 v112, v106, 1, v113
	ds_write_b16_d16_hi v112, v114
	v_add3_u32 v114, s60, v96, 8
	s_and_b64 vcc, exec, s[6:7]
	v_cmp_lt_i32_e64 s[16:17], s43, v114
	v_mul_f32_e32 v114, 0xbfb8aa3b, v20
	v_exp_f32_e32 v114, v114
	s_nop 0
	v_add_f32_e32 v114, 1.0, v114
	v_div_scale_f32 v115, s[18:19], v114, v114, 1.0
	v_rcp_f32_e32 v116, v115
	v_div_scale_f32 v117, vcc, 1.0, v114, 1.0
	v_fma_f32 v118, -v115, v116, 1.0
	v_fmac_f32_e32 v116, v118, v116
	v_mul_f32_e32 v118, v117, v116
	v_fma_f32 v119, -v115, v118, v117
	v_fmac_f32_e32 v118, v119, v116
	v_fma_f32 v115, -v115, v118, v117
	v_div_fmas_f32 v115, v115, v116, v118
	v_div_fixup_f32 v114, v115, v114, 1.0
	v_bfe_u32 v115, v114, 16, 1
	v_add3_u32 v115, v114, v115, s77
	v_add_u32_e32 v114, 0x550, v113
	v_lshl_add_u32 v113, v106, 1, v114
	ds_write_b16_d16_hi v113, v115
	v_add3_u32 v115, s60, v96, 9
	s_and_b64 vcc, exec, s[6:7]
	v_cmp_lt_i32_e64 s[18:19], s43, v115
	v_mul_f32_e32 v115, 0xbfb8aa3b, v21
	v_exp_f32_e32 v115, v115
	s_nop 0
	v_add_f32_e32 v115, 1.0, v115
	v_div_scale_f32 v116, s[20:21], v115, v115, 1.0
	v_rcp_f32_e32 v117, v116
	v_div_scale_f32 v118, vcc, 1.0, v115, 1.0
	v_fma_f32 v119, -v116, v117, 1.0
	v_fmac_f32_e32 v117, v119, v117
	v_mul_f32_e32 v119, v118, v117
	v_fma_f32 v120, -v116, v119, v118
	v_fmac_f32_e32 v119, v120, v117
	v_fma_f32 v116, -v116, v119, v118
	v_div_fmas_f32 v116, v116, v117, v119
	v_div_fixup_f32 v115, v116, v115, 1.0
	v_bfe_u32 v116, v115, 16, 1
	v_add3_u32 v116, v115, v116, s77
	v_add_u32_e32 v115, 0x110, v114
	v_lshl_add_u32 v114, v106, 1, v115
	ds_write_b16_d16_hi v114, v116
	v_add3_u32 v116, s60, v96, 10
	s_and_b64 vcc, exec, s[6:7]
	v_cmp_lt_i32_e64 s[20:21], s43, v116
	v_mul_f32_e32 v116, 0xbfb8aa3b, v22
	v_exp_f32_e32 v116, v116
	s_nop 0
	v_add_f32_e32 v116, 1.0, v116
	v_div_scale_f32 v117, s[22:23], v116, v116, 1.0
	v_rcp_f32_e32 v118, v117
	v_div_scale_f32 v119, vcc, 1.0, v116, 1.0
	v_fma_f32 v120, -v117, v118, 1.0
	v_fmac_f32_e32 v118, v120, v118
	v_mul_f32_e32 v120, v119, v118
	v_fma_f32 v121, -v117, v120, v119
	v_fmac_f32_e32 v120, v121, v118
	v_fma_f32 v117, -v117, v120, v119
	v_div_fmas_f32 v117, v117, v118, v120
	v_div_fixup_f32 v116, v117, v116, 1.0
	v_bfe_u32 v117, v116, 16, 1
	v_add3_u32 v117, v116, v117, s77
	v_add_u32_e32 v116, 0x110, v115
	v_lshl_add_u32 v115, v106, 1, v116
	ds_write_b16_d16_hi v115, v117
	v_add3_u32 v117, s60, v96, 11
	s_and_b64 vcc, exec, s[6:7]
	v_cmp_lt_i32_e64 s[22:23], s43, v117
	v_mul_f32_e32 v117, 0xbfb8aa3b, v23
	v_exp_f32_e32 v117, v117
	s_nop 0
	v_add_f32_e32 v117, 1.0, v117
	v_div_scale_f32 v118, s[24:25], v117, v117, 1.0
	v_rcp_f32_e32 v119, v118
; __device__ __forceinline__ float sigmf(float x) { return 1.f / (1.f + __expf(-x)); }
; template <int MT, int NT, class F>
; __device__ __forceinline__ void acc_foreach(int tid, f32x16 (&acc)[MT][NT], F f) {
;     ...
;         int row = wm * (MT * 32) + mt * 32 + (i & 3) + 8 * (i >> 2) + 4 * hi;
;         int col = wn * (NT * 32) + nt * 32 + c;
; __device__ __forceinline__ void inproj_epilogue(const Params& p, int layer, int mt, int ntile, int tid,
;                                                 f32x16 (&acc)[2][2], unsigned char* smem) {
;     ...
;       if (mode == 2) o = sigmf(v);
;       sT[row * 136 + col] = f2bf(o);
	v_div_scale_f32 v120, vcc, 1.0, v117, 1.0
	v_fma_f32 v121, -v118, v119, 1.0
	v_fmac_f32_e32 v119, v121, v119
	v_mul_f32_e32 v121, v120, v119
	v_fma_f32 v122, -v118, v121, v120
	v_fmac_f32_e32 v121, v122, v119
	v_fma_f32 v118, -v118, v121, v120
	v_div_fmas_f32 v118, v118, v119, v121
	v_div_fixup_f32 v117, v118, v117, 1.0
	v_bfe_u32 v118, v117, 16, 1
	v_add_u32_e32 v116, 0x110, v116
	v_add3_u32 v118, v117, v118, s77
	v_lshl_add_u32 v117, v106, 1, v116
	ds_write_b16_d16_hi v117, v118
	v_add3_u32 v118, s60, v96, 16
	s_and_b64 vcc, exec, s[6:7]
	v_cmp_lt_i32_e64 s[24:25], s43, v118
	v_mul_f32_e32 v118, 0xbfb8aa3b, v24
	v_exp_f32_e32 v118, v118
	s_nop 0
	v_add_f32_e32 v118, 1.0, v118
	v_div_scale_f32 v119, s[26:27], v118, v118, 1.0
	v_rcp_f32_e32 v120, v119
	v_div_scale_f32 v121, vcc, 1.0, v118, 1.0
	v_fma_f32 v122, -v119, v120, 1.0
	v_fmac_f32_e32 v120, v122, v120
	v_mul_f32_e32 v122, v121, v120
	v_fma_f32 v123, -v119, v122, v121
	v_fmac_f32_e32 v122, v123, v120
	v_fma_f32 v119, -v119, v122, v121
	v_div_fmas_f32 v119, v119, v120, v122
	v_div_fixup_f32 v118, v119, v118, 1.0
	v_bfe_u32 v119, v118, 16, 1
	v_add_u32_e32 v116, 0x550, v116
	v_add3_u32 v119, v118, v119, s77
	v_lshl_add_u32 v118, v106, 1, v116
	ds_write_b16_d16_hi v118, v119
	v_add3_u32 v119, s60, v96, 17
	s_and_b64 vcc, exec, s[6:7]
	v_cmp_lt_i32_e64 s[26:27], s43, v119
	v_mul_f32_e32 v119, 0xbfb8aa3b, v25
	v_exp_f32_e32 v119, v119
	s_nop 0
	v_add_f32_e32 v119, 1.0, v119
	v_div_scale_f32 v120, s[28:29], v119, v119, 1.0
	v_rcp_f32_e32 v121, v120
	v_div_scale_f32 v122, vcc, 1.0, v119, 1.0
	v_fma_f32 v123, -v120, v121, 1.0
	v_fmac_f32_e32 v121, v123, v121
	v_mul_f32_e32 v123, v122, v121
	v_fma_f32 v124, -v120, v123, v122
	v_fmac_f32_e32 v123, v124, v121
	v_fma_f32 v120, -v120, v123, v122
	v_div_fmas_f32 v120, v120, v121, v123
	v_div_fixup_f32 v119, v120, v119, 1.0
	v_bfe_u32 v120, v119, 16, 1
	v_add_u32_e32 v116, 0x110, v116
	v_add3_u32 v120, v119, v120, s77
	v_lshl_add_u32 v119, v106, 1, v116
	ds_write_b16_d16_hi v119, v120
	v_add3_u32 v120, s60, v96, 18
	s_and_b64 vcc, exec, s[6:7]
	v_cmp_lt_i32_e64 s[28:29], s43, v120
	v_mul_f32_e32 v120, 0xbfb8aa3b, v26
	v_exp_f32_e32 v120, v120
	s_nop 0
	v_add_f32_e32 v120, 1.0, v120
	v_div_scale_f32 v121, s[30:31], v120, v120, 1.0
	v_rcp_f32_e32 v122, v121
	v_div_scale_f32 v123, vcc, 1.0, v120, 1.0
	v_fma_f32 v124, -v121, v122, 1.0
	v_fmac_f32_e32 v122, v124, v122
	v_mul_f32_e32 v124, v123, v122
	v_fma_f32 v125, -v121, v124, v123
	v_fmac_f32_e32 v124, v125, v122
	v_fma_f32 v121, -v121, v124, v123
	v_div_fmas_f32 v121, v121, v122, v124
	v_div_fixup_f32 v120, v121, v120, 1.0
	v_bfe_u32 v121, v120, 16, 1
	v_add_u32_e32 v116, 0x110, v116
	v_add3_u32 v121, v120, v121, s77
	v_lshl_add_u32 v120, v106, 1, v116
	ds_write_b16_d16_hi v120, v121
	v_add3_u32 v121, s60, v96, 19
	s_and_b64 vcc, exec, s[6:7]
	v_cmp_lt_i32_e64 s[30:31], s43, v121
	v_mul_f32_e32 v121, 0xbfb8aa3b, v27
	v_exp_f32_e32 v121, v121
	s_nop 0
	v_add_f32_e32 v121, 1.0, v121
	v_div_scale_f32 v122, s[34:35], v121, v121, 1.0
	v_rcp_f32_e32 v123, v122
	v_div_scale_f32 v124, vcc, 1.0, v121, 1.0
	v_fma_f32 v125, -v122, v123, 1.0
	v_fmac_f32_e32 v123, v125, v123
	v_mul_f32_e32 v125, v124, v123
	v_fma_f32 v126, -v122, v125, v124
	v_fmac_f32_e32 v125, v126, v123
	v_fma_f32 v122, -v122, v125, v124
	v_div_fmas_f32 v122, v122, v123, v125
	v_div_fixup_f32 v121, v122, v121, 1.0
	v_bfe_u32 v122, v121, 16, 1
	v_add_u32_e32 v116, 0x110, v116
	v_add3_u32 v122, v121, v122, s77
	v_lshl_add_u32 v121, v106, 1, v116
	ds_write_b16_d16_hi v121, v122
	v_add3_u32 v122, s60, v96, 24
	s_and_b64 vcc, exec, s[6:7]
	v_cmp_lt_i32_e64 s[34:35], s43, v122
	v_mul_f32_e32 v122, 0xbfb8aa3b, v28
	v_exp_f32_e32 v122, v122
	s_nop 0
	v_add_f32_e32 v122, 1.0, v122
	v_div_scale_f32 v123, s[36:37], v122, v122, 1.0
	v_rcp_f32_e32 v124, v123
	v_div_scale_f32 v125, vcc, 1.0, v122, 1.0
	v_fma_f32 v126, -v123, v124, 1.0
	v_fmac_f32_e32 v124, v126, v124
	v_mul_f32_e32 v126, v125, v124
	v_fma_f32 v127, -v123, v126, v125
	v_fmac_f32_e32 v126, v127, v124
	v_fma_f32 v123, -v123, v126, v125
	v_div_fmas_f32 v123, v123, v124, v126
	v_div_fixup_f32 v122, v123, v122, 1.0
	v_bfe_u32 v123, v122, 16, 1
	v_add_u32_e32 v116, 0x550, v116
	v_add3_u32 v123, v122, v123, s77
	v_lshl_add_u32 v122, v106, 1, v116
	ds_write_b16_d16_hi v122, v123
	v_add3_u32 v123, s60, v96, 25
	s_and_b64 vcc, exec, s[6:7]
	v_cmp_lt_i32_e64 s[36:37], s43, v123
	v_mul_f32_e32 v123, 0xbfb8aa3b, v29
	v_exp_f32_e32 v123, v123
	s_nop 0
	v_add_f32_e32 v123, 1.0, v123
	v_div_scale_f32 v124, s[38:39], v123, v123, 1.0
	v_rcp_f32_e32 v125, v124
	v_div_scale_f32 v126, vcc, 1.0, v123, 1.0
	v_fma_f32 v127, -v124, v125, 1.0
	v_fmac_f32_e32 v125, v127, v125
	v_mul_f32_e32 v127, v126, v125
	v_fma_f32 v128, -v124, v127, v126
	v_fmac_f32_e32 v127, v128, v125
	v_fma_f32 v124, -v124, v127, v126
	v_div_fmas_f32 v124, v124, v125, v127
	v_div_fixup_f32 v123, v124, v123, 1.0
	v_bfe_u32 v124, v123, 16, 1
	v_add_u32_e32 v116, 0x110, v116
	v_add3_u32 v124, v123, v124, s77
	v_lshl_add_u32 v123, v106, 1, v116
	ds_write_b16_d16_hi v123, v124
	v_add3_u32 v124, s60, v96, 26
	s_and_b64 vcc, exec, s[6:7]
	v_cmp_lt_i32_e64 s[38:39], s43, v124
	v_mul_f32_e32 v124, 0xbfb8aa3b, v30
	v_exp_f32_e32 v124, v124
	s_nop 0
	v_add_f32_e32 v124, 1.0, v124
	v_div_scale_f32 v125, s[40:41], v124, v124, 1.0
	v_rcp_f32_e32 v126, v125
	v_div_scale_f32 v127, vcc, 1.0, v124, 1.0
	v_fma_f32 v128, -v125, v126, 1.0
	v_fmac_f32_e32 v126, v128, v126
	v_mul_f32_e32 v128, v127, v126
	v_fma_f32 v129, -v125, v128, v127
	v_fmac_f32_e32 v128, v129, v126
	v_fma_f32 v125, -v125, v128, v127
	v_div_fmas_f32 v125, v125, v126, v128
; __device__ __forceinline__ float sigmf(float x) { return 1.f / (1.f + __expf(-x)); }
; __device__ __forceinline__ void inproj_epilogue(const Params& p, int layer, int mt, int ntile, int tid,
;                                                 f32x16 (&acc)[2][2], unsigned char* smem) {
;     ...
;       if (mode == 2) o = sigmf(v);
;       sT[row * 136 + col] = f2bf(o);
	v_div_fixup_f32 v124, v125, v124, 1.0
	v_bfe_u32 v125, v124, 16, 1
	v_add_u32_e32 v116, 0x110, v116
	v_add3_u32 v124, v124, v125, s77
	v_lshl_add_u32 v116, v106, 1, v116
	ds_write_b16_d16_hi v116, v124
	v_add3_u32 v124, s60, v96, 27
	s_and_b64 vcc, exec, s[6:7]
	v_cmp_lt_i32_e64 s[40:41], s43, v124
	v_mul_f32_e32 v124, 0xbfb8aa3b, v31
	v_exp_f32_e32 v124, v124
	s_nop 0
	v_add_f32_e32 v124, 1.0, v124
	v_div_scale_f32 v125, vcc, v124, v124, 1.0
	v_rcp_f32_e32 v126, v125
	v_div_scale_f32 v127, vcc, 1.0, v124, 1.0
	v_fma_f32 v128, -v125, v126, 1.0
	v_fmac_f32_e32 v126, v128, v126
	v_mul_f32_e32 v128, v127, v126
	v_fma_f32 v129, -v125, v128, v127
	v_fmac_f32_e32 v128, v129, v126
	v_fma_f32 v125, -v125, v128, v127
	v_div_fmas_f32 v125, v125, v126, v128
	v_div_fixup_f32 v124, v125, v124, 1.0
	v_bfe_u32 v125, v124, 16, 1
	v_add3_u32 v124, v124, v125, s77
	ds_write_b16_d16_hi v116, v124 offset:272
	s_and_b64 vcc, exec, s[6:7]
	v_mul_f32_e32 v48, 0xbfb8aa3b, v48
	v_exp_f32_e32 v48, v48
	s_nop 0
	v_add_f32_e32 v48, 1.0, v48
	v_div_scale_f32 v124, s[8:9], v48, v48, 1.0
	v_rcp_f32_e32 v125, v124
	v_div_scale_f32 v126, vcc, 1.0, v48, 1.0
	v_fma_f32 v127, -v124, v125, 1.0
	v_fmac_f32_e32 v125, v127, v125
	v_mul_f32_e32 v127, v126, v125
	v_fma_f32 v128, -v124, v127, v126
	v_fmac_f32_e32 v127, v128, v125
	v_fma_f32 v124, -v124, v127, v126
	v_div_fmas_f32 v124, v124, v125, v127
	v_div_fixup_f32 v48, v124, v48, 1.0
	v_bfe_u32 v124, v48, 16, 1
	v_add3_u32 v48, v48, v124, s77
	s_and_b64 vcc, exec, s[6:7]
	ds_write_b16_d16_hi v107, v48 offset:64
	v_mul_f32_e32 v48, 0xbfb8aa3b, v49
	v_exp_f32_e32 v48, v48
	s_nop 0
	v_add_f32_e32 v48, 1.0, v48
	v_div_scale_f32 v49, s[8:9], v48, v48, 1.0
	v_rcp_f32_e32 v107, v49
	v_div_scale_f32 v124, vcc, 1.0, v48, 1.0
	v_fma_f32 v125, -v49, v107, 1.0
	v_fmac_f32_e32 v107, v125, v107
	v_mul_f32_e32 v125, v124, v107
	v_fma_f32 v126, -v49, v125, v124
	v_fmac_f32_e32 v125, v126, v107
	v_fma_f32 v49, -v49, v125, v124
	v_div_fmas_f32 v49, v49, v107, v125
	v_div_fixup_f32 v48, v49, v48, 1.0
	v_bfe_u32 v49, v48, 16, 1
	v_add3_u32 v48, v48, v49, s77
	s_and_b64 vcc, exec, s[6:7]
	ds_write_b16_d16_hi v110, v48 offset:64
	v_mul_f32_e32 v48, 0xbfb8aa3b, v50
	v_exp_f32_e32 v48, v48
	s_nop 0
	v_add_f32_e32 v48, 1.0, v48
	v_div_scale_f32 v49, s[8:9], v48, v48, 1.0
	v_rcp_f32_e32 v50, v49
	v_div_scale_f32 v107, vcc, 1.0, v48, 1.0
	v_fma_f32 v110, -v49, v50, 1.0
	v_fmac_f32_e32 v50, v110, v50
	v_mul_f32_e32 v110, v107, v50
	v_fma_f32 v124, -v49, v110, v107
	v_fmac_f32_e32 v110, v124, v50
	v_fma_f32 v49, -v49, v110, v107
	v_div_fmas_f32 v49, v49, v50, v110
	v_div_fixup_f32 v48, v49, v48, 1.0
	v_bfe_u32 v49, v48, 16, 1
	v_add3_u32 v48, v48, v49, s77
	s_and_b64 vcc, exec, s[6:7]
	ds_write_b16_d16_hi v111, v48 offset:64
	v_mul_f32_e32 v48, 0xbfb8aa3b, v51
	v_exp_f32_e32 v48, v48
	s_nop 0
	v_add_f32_e32 v48, 1.0, v48
	v_div_scale_f32 v49, s[8:9], v48, v48, 1.0
	v_rcp_f32_e32 v50, v49
	v_div_scale_f32 v51, vcc, 1.0, v48, 1.0
	v_fma_f32 v107, -v49, v50, 1.0
	v_fmac_f32_e32 v50, v107, v50
	v_mul_f32_e32 v107, v51, v50
	v_fma_f32 v110, -v49, v107, v51
	v_fmac_f32_e32 v107, v110, v50
	v_fma_f32 v49, -v49, v107, v51
	v_div_fmas_f32 v49, v49, v50, v107
	v_div_fixup_f32 v48, v49, v48, 1.0
	v_bfe_u32 v49, v48, 16, 1
	v_add3_u32 v48, v48, v49, s77
	s_and_b64 vcc, exec, s[6:7]
	ds_write_b16_d16_hi v112, v48 offset:64
	v_mul_f32_e32 v48, 0xbfb8aa3b, v52
	v_exp_f32_e32 v48, v48
	s_nop 0
	v_add_f32_e32 v48, 1.0, v48
	v_div_scale_f32 v49, s[8:9], v48, v48, 1.0
	v_rcp_f32_e32 v50, v49
	v_div_scale_f32 v51, vcc, 1.0, v48, 1.0
	v_fma_f32 v52, -v49, v50, 1.0
	v_fmac_f32_e32 v50, v52, v50
	v_mul_f32_e32 v52, v51, v50
	v_fma_f32 v107, -v49, v52, v51
	v_fmac_f32_e32 v52, v107, v50
	v_fma_f32 v49, -v49, v52, v51
	v_div_fmas_f32 v49, v49, v50, v52
	v_div_fixup_f32 v48, v49, v48, 1.0
	v_bfe_u32 v49, v48, 16, 1
	v_add3_u32 v48, v48, v49, s77
	s_and_b64 vcc, exec, s[6:7]
	ds_write_b16_d16_hi v113, v48 offset:64
	v_mul_f32_e32 v48, 0xbfb8aa3b, v53
	v_exp_f32_e32 v48, v48
	s_nop 0
	v_add_f32_e32 v48, 1.0, v48
	v_div_scale_f32 v49, s[8:9], v48, v48, 1.0
	v_rcp_f32_e32 v50, v49
	v_div_scale_f32 v51, vcc, 1.0, v48, 1.0
	v_fma_f32 v52, -v49, v50, 1.0
	v_fmac_f32_e32 v50, v52, v50
	v_mul_f32_e32 v52, v51, v50
	v_fma_f32 v53, -v49, v52, v51
	v_fmac_f32_e32 v52, v53, v50
	v_fma_f32 v49, -v49, v52, v51
	v_div_fmas_f32 v49, v49, v50, v52
	v_div_fixup_f32 v48, v49, v48, 1.0
	v_bfe_u32 v49, v48, 16, 1
	v_add3_u32 v48, v48, v49, s77
	s_and_b64 vcc, exec, s[6:7]
	ds_write_b16_d16_hi v114, v48 offset:64
	v_mul_f32_e32 v48, 0xbfb8aa3b, v54
	v_exp_f32_e32 v48, v48
	s_nop 0
	v_add_f32_e32 v48, 1.0, v48
	v_div_scale_f32 v49, s[8:9], v48, v48, 1.0
	v_rcp_f32_e32 v50, v49
	v_div_scale_f32 v51, vcc, 1.0, v48, 1.0
	v_fma_f32 v52, -v49, v50, 1.0
	v_fmac_f32_e32 v50, v52, v50
	v_mul_f32_e32 v52, v51, v50
	v_fma_f32 v53, -v49, v52, v51
	v_fmac_f32_e32 v52, v53, v50
	v_fma_f32 v49, -v49, v52, v51
	v_div_fmas_f32 v49, v49, v50, v52
	v_div_fixup_f32 v48, v49, v48, 1.0
	v_bfe_u32 v49, v48, 16, 1
	v_add3_u32 v48, v48, v49, s77
	s_and_b64 vcc, exec, s[6:7]
	ds_write_b16_d16_hi v115, v48 offset:64
	v_mul_f32_e32 v48, 0xbfb8aa3b, v55
	v_exp_f32_e32 v48, v48
	s_nop 0
	v_add_f32_e32 v48, 1.0, v48
	v_div_scale_f32 v49, s[8:9], v48, v48, 1.0
	v_rcp_f32_e32 v50, v49
	v_div_scale_f32 v51, vcc, 1.0, v48, 1.0
	v_fma_f32 v52, -v49, v50, 1.0
	v_fmac_f32_e32 v50, v52, v50
	v_mul_f32_e32 v52, v51, v50
	v_fma_f32 v53, -v49, v52, v51
	v_fmac_f32_e32 v52, v53, v50
	v_fma_f32 v49, -v49, v52, v51
	v_div_fmas_f32 v49, v49, v50, v52
	v_div_fixup_f32 v48, v49, v48, 1.0
	v_bfe_u32 v49, v48, 16, 1
	v_add3_u32 v48, v48, v49, s77
; __device__ __forceinline__ float sigmf(float x) { return 1.f / (1.f + __expf(-x)); }
; template <int MT, int NT, class F>
; __device__ __forceinline__ void acc_foreach(int tid, f32x16 (&acc)[MT][NT], F f) {
;     ...
;         int row = wm * (MT * 32) + mt * 32 + (i & 3) + 8 * (i >> 2) + 4 * hi;
;         int col = wn * (NT * 32) + nt * 32 + c;
; __device__ __forceinline__ void inproj_epilogue(const Params& p, int layer, int mt, int ntile, int tid,
;                                                 f32x16 (&acc)[2][2], unsigned char* smem) {
;     ...
;       if (mode == 2) o = sigmf(v);
;       sT[row * 136 + col] = f2bf(o);
	s_and_b64 vcc, exec, s[6:7]
	ds_write_b16_d16_hi v117, v48 offset:64
	v_mul_f32_e32 v48, 0xbfb8aa3b, v56
	v_exp_f32_e32 v48, v48
	s_nop 0
	v_add_f32_e32 v48, 1.0, v48
	v_div_scale_f32 v49, s[8:9], v48, v48, 1.0
	v_rcp_f32_e32 v50, v49
	v_div_scale_f32 v51, vcc, 1.0, v48, 1.0
	v_fma_f32 v52, -v49, v50, 1.0
	v_fmac_f32_e32 v50, v52, v50
	v_mul_f32_e32 v52, v51, v50
	v_fma_f32 v53, -v49, v52, v51
	v_fmac_f32_e32 v52, v53, v50
	v_fma_f32 v49, -v49, v52, v51
	v_div_fmas_f32 v49, v49, v50, v52
	v_div_fixup_f32 v48, v49, v48, 1.0
	v_bfe_u32 v49, v48, 16, 1
	v_add3_u32 v48, v48, v49, s77
	s_and_b64 vcc, exec, s[6:7]
	ds_write_b16_d16_hi v118, v48 offset:64
	v_mul_f32_e32 v48, 0xbfb8aa3b, v57
	v_exp_f32_e32 v48, v48
	s_nop 0
	v_add_f32_e32 v48, 1.0, v48
	v_div_scale_f32 v49, s[8:9], v48, v48, 1.0
	v_rcp_f32_e32 v50, v49
	v_div_scale_f32 v51, vcc, 1.0, v48, 1.0
	v_fma_f32 v52, -v49, v50, 1.0
	v_fmac_f32_e32 v50, v52, v50
	v_mul_f32_e32 v52, v51, v50
	v_fma_f32 v53, -v49, v52, v51
	v_fmac_f32_e32 v52, v53, v50
	v_fma_f32 v49, -v49, v52, v51
	v_div_fmas_f32 v49, v49, v50, v52
	v_div_fixup_f32 v48, v49, v48, 1.0
	v_bfe_u32 v49, v48, 16, 1
	v_add3_u32 v48, v48, v49, s77
	s_and_b64 vcc, exec, s[6:7]
	ds_write_b16_d16_hi v119, v48 offset:64
	v_mul_f32_e32 v48, 0xbfb8aa3b, v58
	v_exp_f32_e32 v48, v48
	s_nop 0
	v_add_f32_e32 v48, 1.0, v48
	v_div_scale_f32 v49, s[8:9], v48, v48, 1.0
	v_rcp_f32_e32 v50, v49
	v_div_scale_f32 v51, vcc, 1.0, v48, 1.0
	v_fma_f32 v52, -v49, v50, 1.0
	v_fmac_f32_e32 v50, v52, v50
	v_mul_f32_e32 v52, v51, v50
	v_fma_f32 v53, -v49, v52, v51
	v_fmac_f32_e32 v52, v53, v50
	v_fma_f32 v49, -v49, v52, v51
	v_div_fmas_f32 v49, v49, v50, v52
	v_div_fixup_f32 v48, v49, v48, 1.0
	v_bfe_u32 v49, v48, 16, 1
	v_add3_u32 v48, v48, v49, s77
	s_and_b64 vcc, exec, s[6:7]
	ds_write_b16_d16_hi v120, v48 offset:64
	v_mul_f32_e32 v48, 0xbfb8aa3b, v59
	v_exp_f32_e32 v48, v48
	s_nop 0
	v_add_f32_e32 v48, 1.0, v48
	v_div_scale_f32 v49, s[8:9], v48, v48, 1.0
	v_rcp_f32_e32 v50, v49
	v_div_scale_f32 v51, vcc, 1.0, v48, 1.0
	v_fma_f32 v52, -v49, v50, 1.0
	v_fmac_f32_e32 v50, v52, v50
	v_mul_f32_e32 v52, v51, v50
	v_fma_f32 v53, -v49, v52, v51
	v_fmac_f32_e32 v52, v53, v50
	v_fma_f32 v49, -v49, v52, v51
	v_div_fmas_f32 v49, v49, v50, v52
	v_div_fixup_f32 v48, v49, v48, 1.0
	v_bfe_u32 v49, v48, 16, 1
	v_add3_u32 v48, v48, v49, s77
	s_and_b64 vcc, exec, s[6:7]
	ds_write_b16_d16_hi v121, v48 offset:64
	v_mul_f32_e32 v48, 0xbfb8aa3b, v60
	v_exp_f32_e32 v48, v48
	s_nop 0
	v_add_f32_e32 v48, 1.0, v48
	v_div_scale_f32 v49, s[8:9], v48, v48, 1.0
	v_rcp_f32_e32 v50, v49
	v_div_scale_f32 v51, vcc, 1.0, v48, 1.0
	v_fma_f32 v52, -v49, v50, 1.0
	v_fmac_f32_e32 v50, v52, v50
	v_mul_f32_e32 v52, v51, v50
	v_fma_f32 v53, -v49, v52, v51
	v_fmac_f32_e32 v52, v53, v50
	v_fma_f32 v49, -v49, v52, v51
	v_div_fmas_f32 v49, v49, v50, v52
	v_div_fixup_f32 v48, v49, v48, 1.0
	v_bfe_u32 v49, v48, 16, 1
	v_add3_u32 v48, v48, v49, s77
	s_and_b64 vcc, exec, s[6:7]
	ds_write_b16_d16_hi v122, v48 offset:64
	v_mul_f32_e32 v48, 0xbfb8aa3b, v61
	v_exp_f32_e32 v48, v48
	s_nop 0
	v_add_f32_e32 v48, 1.0, v48
	v_div_scale_f32 v49, s[8:9], v48, v48, 1.0
	v_rcp_f32_e32 v50, v49
	v_div_scale_f32 v51, vcc, 1.0, v48, 1.0
	v_fma_f32 v52, -v49, v50, 1.0
	v_fmac_f32_e32 v50, v52, v50
	v_mul_f32_e32 v52, v51, v50
	v_fma_f32 v53, -v49, v52, v51
	v_fmac_f32_e32 v52, v53, v50
	v_fma_f32 v49, -v49, v52, v51
	v_div_fmas_f32 v49, v49, v50, v52
	v_div_fixup_f32 v48, v49, v48, 1.0
	v_bfe_u32 v49, v48, 16, 1
	v_add3_u32 v48, v48, v49, s77
	s_and_b64 vcc, exec, s[6:7]
	ds_write_b16_d16_hi v123, v48 offset:64
	v_mul_f32_e32 v48, 0xbfb8aa3b, v62
	v_exp_f32_e32 v48, v48
	s_nop 0
	v_add_f32_e32 v48, 1.0, v48
	v_div_scale_f32 v49, s[8:9], v48, v48, 1.0
	v_rcp_f32_e32 v50, v49
	v_div_scale_f32 v51, vcc, 1.0, v48, 1.0
	v_fma_f32 v52, -v49, v50, 1.0
	v_fmac_f32_e32 v50, v52, v50
	v_mul_f32_e32 v52, v51, v50
	v_fma_f32 v53, -v49, v52, v51
	v_fmac_f32_e32 v52, v53, v50
	v_fma_f32 v49, -v49, v52, v51
	v_div_fmas_f32 v49, v49, v50, v52
	v_div_fixup_f32 v48, v49, v48, 1.0
	v_bfe_u32 v49, v48, 16, 1
	v_add3_u32 v48, v48, v49, s77
	s_and_b64 vcc, exec, s[6:7]
	ds_write_b16_d16_hi v116, v48 offset:64
	v_mul_f32_e32 v48, 0xbfb8aa3b, v63
	v_exp_f32_e32 v48, v48
	s_nop 0
	v_add_f32_e32 v48, 1.0, v48
	v_div_scale_f32 v49, s[8:9], v48, v48, 1.0
	v_rcp_f32_e32 v50, v49
	v_div_scale_f32 v51, vcc, 1.0, v48, 1.0
	v_fma_f32 v52, -v49, v50, 1.0
	v_fmac_f32_e32 v50, v52, v50
	v_mul_f32_e32 v52, v51, v50
	v_fma_f32 v53, -v49, v52, v51
	v_fmac_f32_e32 v52, v53, v50
	v_fma_f32 v49, -v49, v52, v51
	v_div_fmas_f32 v49, v49, v50, v52
	v_div_fixup_f32 v48, v49, v48, 1.0
	v_bfe_u32 v50, v48, 16, 1
	v_add_u32_e32 v49, 0x110, v116
	v_add3_u32 v48, v48, v50, s77
	ds_write_b16_d16_hi v49, v48 offset:64
	v_or_b32_e32 v48, 32, v96
	v_add_u32_e32 v49, s60, v48
	s_and_b64 vcc, exec, s[6:7]
	v_cmp_lt_i32_e64 s[8:9], s43, v49
	v_mul_f32_e32 v49, 0xbfb8aa3b, v0
	v_exp_f32_e32 v49, v49
	s_nop 0
	v_add_f32_e32 v49, 1.0, v49
	v_div_scale_f32 v50, s[10:11], v49, v49, 1.0
	v_rcp_f32_e32 v51, v50
	v_div_scale_f32 v52, vcc, 1.0, v49, 1.0
	v_fma_f32 v53, -v50, v51, 1.0
	v_fmac_f32_e32 v51, v53, v51
	v_mul_f32_e32 v53, v52, v51
	v_fma_f32 v54, -v50, v53, v52
	v_fmac_f32_e32 v53, v54, v51
	v_fma_f32 v50, -v50, v53, v52
	v_div_fmas_f32 v50, v50, v51, v53
	v_div_fixup_f32 v49, v50, v49, 1.0
	v_bfe_u32 v50, v49, 16, 1
	v_add3_u32 v50, v49, v50, s77
	v_mul_lo_u32 v49, v48, s78
	v_lshl_add_u32 v48, v106, 1, v49
	ds_write_b16_d16_hi v48, v50
	v_add3_u32 v50, s60, v96, 33
	s_and_b64 vcc, exec, s[6:7]
	v_cmp_lt_i32_e64 s[10:11], s43, v50
	v_mul_f32_e32 v50, 0xbfb8aa3b, v1
; __device__ __forceinline__ float sigmf(float x) { return 1.f / (1.f + __expf(-x)); }
; template <int MT, int NT, class F>
; __device__ __forceinline__ void acc_foreach(int tid, f32x16 (&acc)[MT][NT], F f) {
;     ...
;         int row = wm * (MT * 32) + mt * 32 + (i & 3) + 8 * (i >> 2) + 4 * hi;
;         int col = wn * (NT * 32) + nt * 32 + c;
; __device__ __forceinline__ void inproj_epilogue(const Params& p, int layer, int mt, int ntile, int tid,
;                                                 f32x16 (&acc)[2][2], unsigned char* smem) {
;     ...
;       if (mode == 2) o = sigmf(v);
;       sT[row * 136 + col] = f2bf(o);
	v_exp_f32_e32 v50, v50
	s_nop 0
	v_add_f32_e32 v50, 1.0, v50
	v_div_scale_f32 v51, s[12:13], v50, v50, 1.0
	v_rcp_f32_e32 v52, v51
	v_div_scale_f32 v53, vcc, 1.0, v50, 1.0
	v_fma_f32 v54, -v51, v52, 1.0
	v_fmac_f32_e32 v52, v54, v52
	v_mul_f32_e32 v54, v53, v52
	v_fma_f32 v55, -v51, v54, v53
	v_fmac_f32_e32 v54, v55, v52
	v_fma_f32 v51, -v51, v54, v53
	v_div_fmas_f32 v51, v51, v52, v54
	v_div_fixup_f32 v50, v51, v50, 1.0
	v_bfe_u32 v51, v50, 16, 1
	v_add3_u32 v51, v50, v51, s77
	v_add_u32_e32 v50, 0x110, v49
	v_lshl_add_u32 v49, v106, 1, v50
	ds_write_b16_d16_hi v49, v51
	v_add3_u32 v51, s60, v96, 34
	s_and_b64 vcc, exec, s[6:7]
	v_cmp_lt_i32_e64 s[12:13], s43, v51
	v_mul_f32_e32 v51, 0xbfb8aa3b, v2
	v_exp_f32_e32 v51, v51
	s_nop 0
	v_add_f32_e32 v51, 1.0, v51
	v_div_scale_f32 v52, s[14:15], v51, v51, 1.0
	v_rcp_f32_e32 v53, v52
	v_div_scale_f32 v54, vcc, 1.0, v51, 1.0
	v_fma_f32 v55, -v52, v53, 1.0
	v_fmac_f32_e32 v53, v55, v53
	v_mul_f32_e32 v55, v54, v53
	v_fma_f32 v56, -v52, v55, v54
	v_fmac_f32_e32 v55, v56, v53
	v_fma_f32 v52, -v52, v55, v54
	v_div_fmas_f32 v52, v52, v53, v55
	v_div_fixup_f32 v51, v52, v51, 1.0
	v_bfe_u32 v52, v51, 16, 1
	v_add3_u32 v52, v51, v52, s77
	v_add_u32_e32 v51, 0x110, v50
	v_lshl_add_u32 v50, v106, 1, v51
	ds_write_b16_d16_hi v50, v52
	v_add3_u32 v52, s60, v96, 35
	s_and_b64 vcc, exec, s[6:7]
	v_cmp_lt_i32_e64 s[14:15], s43, v52
	v_mul_f32_e32 v52, 0xbfb8aa3b, v3
	v_exp_f32_e32 v52, v52
	s_nop 0
	v_add_f32_e32 v52, 1.0, v52
	v_div_scale_f32 v53, s[16:17], v52, v52, 1.0
	v_rcp_f32_e32 v54, v53
	v_div_scale_f32 v55, vcc, 1.0, v52, 1.0
	v_fma_f32 v56, -v53, v54, 1.0
	v_fmac_f32_e32 v54, v56, v54
	v_mul_f32_e32 v56, v55, v54
	v_fma_f32 v57, -v53, v56, v55
	v_fmac_f32_e32 v56, v57, v54
	v_fma_f32 v53, -v53, v56, v55
	v_div_fmas_f32 v53, v53, v54, v56
	v_div_fixup_f32 v52, v53, v52, 1.0
	v_bfe_u32 v53, v52, 16, 1
	v_add3_u32 v53, v52, v53, s77
	v_add_u32_e32 v52, 0x110, v51
	v_lshl_add_u32 v51, v106, 1, v52
	ds_write_b16_d16_hi v51, v53
	v_add3_u32 v53, s60, v96, 40
	s_and_b64 vcc, exec, s[6:7]
	v_cmp_lt_i32_e64 s[16:17], s43, v53
	v_mul_f32_e32 v53, 0xbfb8aa3b, v4
	v_exp_f32_e32 v53, v53
	s_nop 0
	v_add_f32_e32 v53, 1.0, v53
	v_div_scale_f32 v54, s[18:19], v53, v53, 1.0
	v_rcp_f32_e32 v55, v54
	v_div_scale_f32 v56, vcc, 1.0, v53, 1.0
	v_fma_f32 v57, -v54, v55, 1.0
	v_fmac_f32_e32 v55, v57, v55
	v_mul_f32_e32 v57, v56, v55
	v_fma_f32 v58, -v54, v57, v56
	v_fmac_f32_e32 v57, v58, v55
	v_fma_f32 v54, -v54, v57, v56
	v_div_fmas_f32 v54, v54, v55, v57
	v_div_fixup_f32 v53, v54, v53, 1.0
	v_bfe_u32 v54, v53, 16, 1
	v_add3_u32 v54, v53, v54, s77
	v_add_u32_e32 v53, 0x550, v52
	v_lshl_add_u32 v52, v106, 1, v53
	ds_write_b16_d16_hi v52, v54
	v_add3_u32 v54, s60, v96, 41
	s_and_b64 vcc, exec, s[6:7]
	v_cmp_lt_i32_e64 s[18:19], s43, v54
	v_mul_f32_e32 v54, 0xbfb8aa3b, v5
	v_exp_f32_e32 v54, v54
	s_nop 0
	v_add_f32_e32 v54, 1.0, v54
	v_div_scale_f32 v55, s[20:21], v54, v54, 1.0
	v_rcp_f32_e32 v56, v55
	v_div_scale_f32 v57, vcc, 1.0, v54, 1.0
	v_fma_f32 v58, -v55, v56, 1.0
	v_fmac_f32_e32 v56, v58, v56
	v_mul_f32_e32 v58, v57, v56
	v_fma_f32 v59, -v55, v58, v57
	v_fmac_f32_e32 v58, v59, v56
	v_fma_f32 v55, -v55, v58, v57
	v_div_fmas_f32 v55, v55, v56, v58
	v_div_fixup_f32 v54, v55, v54, 1.0
	v_bfe_u32 v55, v54, 16, 1
	v_add3_u32 v55, v54, v55, s77
	v_add_u32_e32 v54, 0x110, v53
	v_lshl_add_u32 v53, v106, 1, v54
	ds_write_b16_d16_hi v53, v55
	v_add3_u32 v55, s60, v96, 42
	s_and_b64 vcc, exec, s[6:7]
	v_cmp_lt_i32_e64 s[20:21], s43, v55
	v_mul_f32_e32 v55, 0xbfb8aa3b, v6
	v_exp_f32_e32 v55, v55
	s_nop 0
	v_add_f32_e32 v55, 1.0, v55
	v_div_scale_f32 v56, s[22:23], v55, v55, 1.0
	v_rcp_f32_e32 v57, v56
	v_div_scale_f32 v58, vcc, 1.0, v55, 1.0
	v_fma_f32 v59, -v56, v57, 1.0
	v_fmac_f32_e32 v57, v59, v57
	v_mul_f32_e32 v59, v58, v57
	v_fma_f32 v60, -v56, v59, v58
	v_fmac_f32_e32 v59, v60, v57
	v_fma_f32 v56, -v56, v59, v58
	v_div_fmas_f32 v56, v56, v57, v59
	v_div_fixup_f32 v55, v56, v55, 1.0
	v_bfe_u32 v56, v55, 16, 1
	v_add3_u32 v56, v55, v56, s77
	v_add_u32_e32 v55, 0x110, v54
	v_lshl_add_u32 v54, v106, 1, v55
	ds_write_b16_d16_hi v54, v56
	v_add3_u32 v56, s60, v96, 43
	s_and_b64 vcc, exec, s[6:7]
	v_cmp_lt_i32_e64 s[22:23], s43, v56
	v_mul_f32_e32 v56, 0xbfb8aa3b, v7
	v_exp_f32_e32 v56, v56
	s_nop 0
	v_add_f32_e32 v56, 1.0, v56
	v_div_scale_f32 v57, s[24:25], v56, v56, 1.0
	v_rcp_f32_e32 v58, v57
	v_div_scale_f32 v59, vcc, 1.0, v56, 1.0
	v_fma_f32 v60, -v57, v58, 1.0
	v_fmac_f32_e32 v58, v60, v58
	v_mul_f32_e32 v60, v59, v58
	v_fma_f32 v61, -v57, v60, v59
	v_fmac_f32_e32 v60, v61, v58
	v_fma_f32 v57, -v57, v60, v59
	v_div_fmas_f32 v57, v57, v58, v60
	v_div_fixup_f32 v56, v57, v56, 1.0
	v_bfe_u32 v57, v56, 16, 1
	v_add_u32_e32 v55, 0x110, v55
	v_add3_u32 v57, v56, v57, s77
	v_lshl_add_u32 v56, v106, 1, v55
	ds_write_b16_d16_hi v56, v57
	v_add3_u32 v57, s60, v96, 48
	s_and_b64 vcc, exec, s[6:7]
	v_cmp_lt_i32_e64 s[24:25], s43, v57
	v_mul_f32_e32 v57, 0xbfb8aa3b, v8
	v_exp_f32_e32 v57, v57
	s_nop 0
	v_add_f32_e32 v57, 1.0, v57
	v_div_scale_f32 v58, s[26:27], v57, v57, 1.0
	v_rcp_f32_e32 v59, v58
	v_div_scale_f32 v60, vcc, 1.0, v57, 1.0
	v_fma_f32 v61, -v58, v59, 1.0
	v_fmac_f32_e32 v59, v61, v59
	v_mul_f32_e32 v61, v60, v59
	v_fma_f32 v62, -v58, v61, v60
	v_fmac_f32_e32 v61, v62, v59
	v_fma_f32 v58, -v58, v61, v60
	v_div_fmas_f32 v58, v58, v59, v61
	v_div_fixup_f32 v57, v58, v57, 1.0
	v_bfe_u32 v58, v57, 16, 1
	v_add_u32_e32 v55, 0x550, v55
	v_add3_u32 v58, v57, v58, s77
	v_lshl_add_u32 v57, v106, 1, v55
	ds_write_b16_d16_hi v57, v58
	v_add3_u32 v58, s60, v96, 49
	s_and_b64 vcc, exec, s[6:7]
	v_cmp_lt_i32_e64 s[26:27], s43, v58
; __device__ __forceinline__ float sigmf(float x) { return 1.f / (1.f + __expf(-x)); }
; template <int MT, int NT, class F>
; __device__ __forceinline__ void acc_foreach(int tid, f32x16 (&acc)[MT][NT], F f) {
;     ...
;         int row = wm * (MT * 32) + mt * 32 + (i & 3) + 8 * (i >> 2) + 4 * hi;
;         int col = wn * (NT * 32) + nt * 32 + c;
; __device__ __forceinline__ void inproj_epilogue(const Params& p, int layer, int mt, int ntile, int tid,
;                                                 f32x16 (&acc)[2][2], unsigned char* smem) {
;     ...
;       if (mode == 2) o = sigmf(v);
;       sT[row * 136 + col] = f2bf(o);
	v_mul_f32_e32 v58, 0xbfb8aa3b, v9
	v_exp_f32_e32 v58, v58
	s_nop 0
	v_add_f32_e32 v58, 1.0, v58
	v_div_scale_f32 v59, s[28:29], v58, v58, 1.0
	v_rcp_f32_e32 v60, v59
	v_div_scale_f32 v61, vcc, 1.0, v58, 1.0
	v_fma_f32 v62, -v59, v60, 1.0
	v_fmac_f32_e32 v60, v62, v60
	v_mul_f32_e32 v62, v61, v60
	v_fma_f32 v63, -v59, v62, v61
	v_fmac_f32_e32 v62, v63, v60
	v_fma_f32 v59, -v59, v62, v61
	v_div_fmas_f32 v59, v59, v60, v62
	v_div_fixup_f32 v58, v59, v58, 1.0
	v_bfe_u32 v59, v58, 16, 1
	v_add_u32_e32 v55, 0x110, v55
	v_add3_u32 v59, v58, v59, s77
	v_lshl_add_u32 v58, v106, 1, v55
	ds_write_b16_d16_hi v58, v59
	v_add3_u32 v59, s60, v96, 50
	s_and_b64 vcc, exec, s[6:7]
	v_cmp_lt_i32_e64 s[28:29], s43, v59
	v_mul_f32_e32 v59, 0xbfb8aa3b, v10
	v_exp_f32_e32 v59, v59
	s_nop 0
	v_add_f32_e32 v59, 1.0, v59
	v_div_scale_f32 v60, s[30:31], v59, v59, 1.0
	v_rcp_f32_e32 v61, v60
	v_div_scale_f32 v62, vcc, 1.0, v59, 1.0
	v_fma_f32 v63, -v60, v61, 1.0
	v_fmac_f32_e32 v61, v63, v61
	v_mul_f32_e32 v63, v62, v61
	v_fma_f32 v107, -v60, v63, v62
	v_fmac_f32_e32 v63, v107, v61
	v_fma_f32 v60, -v60, v63, v62
	v_div_fmas_f32 v60, v60, v61, v63
	v_div_fixup_f32 v59, v60, v59, 1.0
	v_bfe_u32 v60, v59, 16, 1
	v_add_u32_e32 v55, 0x110, v55
	v_add3_u32 v60, v59, v60, s77
	v_lshl_add_u32 v59, v106, 1, v55
	ds_write_b16_d16_hi v59, v60
	v_add3_u32 v60, s60, v96, 51
	s_and_b64 vcc, exec, s[6:7]
	v_cmp_lt_i32_e64 s[30:31], s43, v60
	v_mul_f32_e32 v60, 0xbfb8aa3b, v11
	v_exp_f32_e32 v60, v60
	s_nop 0
	v_add_f32_e32 v60, 1.0, v60
	v_div_scale_f32 v61, s[34:35], v60, v60, 1.0
	v_rcp_f32_e32 v62, v61
	v_div_scale_f32 v63, vcc, 1.0, v60, 1.0
	v_fma_f32 v107, -v61, v62, 1.0
	v_fmac_f32_e32 v62, v107, v62
	v_mul_f32_e32 v107, v63, v62
	v_fma_f32 v110, -v61, v107, v63
	v_fmac_f32_e32 v107, v110, v62
	v_fma_f32 v61, -v61, v107, v63
	v_div_fmas_f32 v61, v61, v62, v107
	v_div_fixup_f32 v60, v61, v60, 1.0
	v_bfe_u32 v61, v60, 16, 1
	v_add_u32_e32 v55, 0x110, v55
	v_add3_u32 v61, v60, v61, s77
	v_lshl_add_u32 v60, v106, 1, v55
	ds_write_b16_d16_hi v60, v61
	v_add3_u32 v61, s60, v96, 56
	s_and_b64 vcc, exec, s[6:7]
	v_cmp_lt_i32_e64 s[34:35], s43, v61
	v_mul_f32_e32 v61, 0xbfb8aa3b, v12
	v_exp_f32_e32 v61, v61
	s_nop 0
	v_add_f32_e32 v61, 1.0, v61
	v_div_scale_f32 v62, s[36:37], v61, v61, 1.0
	v_rcp_f32_e32 v63, v62
	v_div_scale_f32 v107, vcc, 1.0, v61, 1.0
	v_fma_f32 v110, -v62, v63, 1.0
	v_fmac_f32_e32 v63, v110, v63
	v_mul_f32_e32 v110, v107, v63
	v_fma_f32 v111, -v62, v110, v107
	v_fmac_f32_e32 v110, v111, v63
	v_fma_f32 v62, -v62, v110, v107
	v_div_fmas_f32 v62, v62, v63, v110
	v_div_fixup_f32 v61, v62, v61, 1.0
	v_bfe_u32 v62, v61, 16, 1
	v_add_u32_e32 v55, 0x550, v55
	v_add3_u32 v62, v61, v62, s77
	v_lshl_add_u32 v61, v106, 1, v55
	ds_write_b16_d16_hi v61, v62
	v_add3_u32 v62, s60, v96, 57
	s_and_b64 vcc, exec, s[6:7]
	v_cmp_lt_i32_e64 s[36:37], s43, v62
	v_mul_f32_e32 v62, 0xbfb8aa3b, v13
	v_exp_f32_e32 v62, v62
	s_nop 0
	v_add_f32_e32 v62, 1.0, v62
	v_div_scale_f32 v63, s[38:39], v62, v62, 1.0
	v_rcp_f32_e32 v107, v63
	v_div_scale_f32 v110, vcc, 1.0, v62, 1.0
	v_fma_f32 v111, -v63, v107, 1.0
	v_fmac_f32_e32 v107, v111, v107
	v_mul_f32_e32 v111, v110, v107
	v_fma_f32 v112, -v63, v111, v110
	v_fmac_f32_e32 v111, v112, v107
	v_fma_f32 v63, -v63, v111, v110
	v_div_fmas_f32 v63, v63, v107, v111
	v_div_fixup_f32 v62, v63, v62, 1.0
	v_bfe_u32 v63, v62, 16, 1
	v_add_u32_e32 v55, 0x110, v55
	v_add3_u32 v63, v62, v63, s77
	v_lshl_add_u32 v62, v106, 1, v55
	ds_write_b16_d16_hi v62, v63
	v_add3_u32 v63, s60, v96, 58
	s_and_b64 vcc, exec, s[6:7]
	v_cmp_lt_i32_e64 s[38:39], s43, v63
	v_mul_f32_e32 v63, 0xbfb8aa3b, v14
	v_exp_f32_e32 v63, v63
	s_nop 0
	v_add_f32_e32 v63, 1.0, v63
	v_div_scale_f32 v107, s[40:41], v63, v63, 1.0
	v_rcp_f32_e32 v110, v107
	v_div_scale_f32 v111, vcc, 1.0, v63, 1.0
	v_fma_f32 v112, -v107, v110, 1.0
	v_fmac_f32_e32 v110, v112, v110
	v_mul_f32_e32 v112, v111, v110
	v_fma_f32 v113, -v107, v112, v111
	v_fmac_f32_e32 v112, v113, v110
	v_fma_f32 v107, -v107, v112, v111
	v_div_fmas_f32 v107, v107, v110, v112
	v_div_fixup_f32 v63, v107, v63, 1.0
	v_bfe_u32 v107, v63, 16, 1
	v_add_u32_e32 v55, 0x110, v55
	v_add3_u32 v63, v63, v107, s77
	v_lshl_add_u32 v55, v106, 1, v55
	ds_write_b16_d16_hi v55, v63
	v_add3_u32 v63, s60, v96, 59
	s_and_b64 vcc, exec, s[6:7]
	v_cmp_lt_i32_e64 s[40:41], s43, v63
	v_mul_f32_e32 v63, 0xbfb8aa3b, v15
	v_exp_f32_e32 v63, v63
	s_nop 0
	v_add_f32_e32 v63, 1.0, v63
	v_div_scale_f32 v96, vcc, v63, v63, 1.0
	v_rcp_f32_e32 v106, v96
	v_div_scale_f32 v107, vcc, 1.0, v63, 1.0
	v_fma_f32 v110, -v96, v106, 1.0
	v_fmac_f32_e32 v106, v110, v106
	v_mul_f32_e32 v110, v107, v106
	v_fma_f32 v111, -v96, v110, v107
	v_fmac_f32_e32 v110, v111, v106
	v_fma_f32 v96, -v96, v110, v107
	v_div_fmas_f32 v96, v96, v106, v110
	v_div_fixup_f32 v63, v96, v63, 1.0
	v_bfe_u32 v96, v63, 16, 1
	v_add3_u32 v63, v63, v96, s77
	ds_write_b16_d16_hi v55, v63 offset:272
	s_and_b64 vcc, exec, s[6:7]
	v_mul_f32_e32 v32, 0xbfb8aa3b, v32
	v_exp_f32_e32 v32, v32
	s_nop 0
	v_add_f32_e32 v32, 1.0, v32
	v_div_scale_f32 v63, s[8:9], v32, v32, 1.0
	v_rcp_f32_e32 v96, v63
	v_div_scale_f32 v106, vcc, 1.0, v32, 1.0
	v_fma_f32 v107, -v63, v96, 1.0
	v_fmac_f32_e32 v96, v107, v96
	v_mul_f32_e32 v107, v106, v96
	v_fma_f32 v110, -v63, v107, v106
	v_fmac_f32_e32 v107, v110, v96
	v_fma_f32 v63, -v63, v107, v106
	v_div_fmas_f32 v63, v63, v96, v107
	v_div_fixup_f32 v32, v63, v32, 1.0
	v_bfe_u32 v63, v32, 16, 1
	v_add3_u32 v32, v32, v63, s77
	s_and_b64 vcc, exec, s[6:7]
	ds_write_b16_d16_hi v48, v32 offset:64
	v_mul_f32_e32 v32, 0xbfb8aa3b, v33
	v_exp_f32_e32 v32, v32
	s_nop 0
	v_add_f32_e32 v32, 1.0, v32
; __device__ __forceinline__ float sigmf(float x) { return 1.f / (1.f + __expf(-x)); }
; __device__ __forceinline__ void inproj_epilogue(const Params& p, int layer, int mt, int ntile, int tid,
;                                                 f32x16 (&acc)[2][2], unsigned char* smem) {
;     ...
;       if (mode == 2) o = sigmf(v);
;       sT[row * 136 + col] = f2bf(o);
	v_div_scale_f32 v33, s[8:9], v32, v32, 1.0
	v_rcp_f32_e32 v48, v33
	v_div_scale_f32 v63, vcc, 1.0, v32, 1.0
	v_fma_f32 v96, -v33, v48, 1.0
	v_fmac_f32_e32 v48, v96, v48
	v_mul_f32_e32 v96, v63, v48
	v_fma_f32 v106, -v33, v96, v63
	v_fmac_f32_e32 v96, v106, v48
	v_fma_f32 v33, -v33, v96, v63
	v_div_fmas_f32 v33, v33, v48, v96
	v_div_fixup_f32 v32, v33, v32, 1.0
	v_bfe_u32 v33, v32, 16, 1
	v_add3_u32 v32, v32, v33, s77
	s_and_b64 vcc, exec, s[6:7]
	ds_write_b16_d16_hi v49, v32 offset:64
	v_mul_f32_e32 v32, 0xbfb8aa3b, v34
	v_exp_f32_e32 v32, v32
	s_nop 0
	v_add_f32_e32 v32, 1.0, v32
	v_div_scale_f32 v33, s[8:9], v32, v32, 1.0
	v_rcp_f32_e32 v34, v33
	v_div_scale_f32 v48, vcc, 1.0, v32, 1.0
	v_fma_f32 v49, -v33, v34, 1.0
	v_fmac_f32_e32 v34, v49, v34
	v_mul_f32_e32 v49, v48, v34
	v_fma_f32 v63, -v33, v49, v48
	v_fmac_f32_e32 v49, v63, v34
	v_fma_f32 v33, -v33, v49, v48
	v_div_fmas_f32 v33, v33, v34, v49
	v_div_fixup_f32 v32, v33, v32, 1.0
	v_bfe_u32 v33, v32, 16, 1
	v_add3_u32 v32, v32, v33, s77
	s_and_b64 vcc, exec, s[6:7]
	ds_write_b16_d16_hi v50, v32 offset:64
	v_mul_f32_e32 v32, 0xbfb8aa3b, v35
	v_exp_f32_e32 v32, v32
	s_nop 0
	v_add_f32_e32 v32, 1.0, v32
	v_div_scale_f32 v33, s[8:9], v32, v32, 1.0
	v_rcp_f32_e32 v34, v33
	v_div_scale_f32 v35, vcc, 1.0, v32, 1.0
	v_fma_f32 v48, -v33, v34, 1.0
	v_fmac_f32_e32 v34, v48, v34
	v_mul_f32_e32 v48, v35, v34
	v_fma_f32 v49, -v33, v48, v35
	v_fmac_f32_e32 v48, v49, v34
	v_fma_f32 v33, -v33, v48, v35
	v_div_fmas_f32 v33, v33, v34, v48
	v_div_fixup_f32 v32, v33, v32, 1.0
	v_bfe_u32 v33, v32, 16, 1
	v_add3_u32 v32, v32, v33, s77
	s_and_b64 vcc, exec, s[6:7]
	ds_write_b16_d16_hi v51, v32 offset:64
	v_mul_f32_e32 v32, 0xbfb8aa3b, v36
	v_exp_f32_e32 v32, v32
	s_nop 0
	v_add_f32_e32 v32, 1.0, v32
	v_div_scale_f32 v33, s[8:9], v32, v32, 1.0
	v_rcp_f32_e32 v34, v33
	v_div_scale_f32 v35, vcc, 1.0, v32, 1.0
	v_fma_f32 v36, -v33, v34, 1.0
	v_fmac_f32_e32 v34, v36, v34
	v_mul_f32_e32 v36, v35, v34
	v_fma_f32 v48, -v33, v36, v35
	v_fmac_f32_e32 v36, v48, v34
	v_fma_f32 v33, -v33, v36, v35
	v_div_fmas_f32 v33, v33, v34, v36
	v_div_fixup_f32 v32, v33, v32, 1.0
	v_bfe_u32 v33, v32, 16, 1
	v_add3_u32 v32, v32, v33, s77
	s_and_b64 vcc, exec, s[6:7]
	ds_write_b16_d16_hi v52, v32 offset:64
	v_mul_f32_e32 v32, 0xbfb8aa3b, v37
	v_exp_f32_e32 v32, v32
	s_nop 0
	v_add_f32_e32 v32, 1.0, v32
	v_div_scale_f32 v33, s[8:9], v32, v32, 1.0
	v_rcp_f32_e32 v34, v33
	v_div_scale_f32 v35, vcc, 1.0, v32, 1.0
	v_fma_f32 v36, -v33, v34, 1.0
	v_fmac_f32_e32 v34, v36, v34
	v_mul_f32_e32 v36, v35, v34
	v_fma_f32 v37, -v33, v36, v35
	v_fmac_f32_e32 v36, v37, v34
	v_fma_f32 v33, -v33, v36, v35
	v_div_fmas_f32 v33, v33, v34, v36
	v_div_fixup_f32 v32, v33, v32, 1.0
	v_bfe_u32 v33, v32, 16, 1
	v_add3_u32 v32, v32, v33, s77
	s_and_b64 vcc, exec, s[6:7]
	ds_write_b16_d16_hi v53, v32 offset:64
	v_mul_f32_e32 v32, 0xbfb8aa3b, v38
	v_exp_f32_e32 v32, v32
	s_nop 0
	v_add_f32_e32 v32, 1.0, v32
	v_div_scale_f32 v33, s[8:9], v32, v32, 1.0
	v_rcp_f32_e32 v34, v33
	v_div_scale_f32 v35, vcc, 1.0, v32, 1.0
	v_fma_f32 v36, -v33, v34, 1.0
	v_fmac_f32_e32 v34, v36, v34
	v_mul_f32_e32 v36, v35, v34
	v_fma_f32 v37, -v33, v36, v35
	v_fmac_f32_e32 v36, v37, v34
	v_fma_f32 v33, -v33, v36, v35
	v_div_fmas_f32 v33, v33, v34, v36
	v_div_fixup_f32 v32, v33, v32, 1.0
	v_bfe_u32 v33, v32, 16, 1
	v_add3_u32 v32, v32, v33, s77
	s_and_b64 vcc, exec, s[6:7]
	ds_write_b16_d16_hi v54, v32 offset:64
	v_mul_f32_e32 v32, 0xbfb8aa3b, v39
	v_exp_f32_e32 v32, v32
	s_nop 0
	v_add_f32_e32 v32, 1.0, v32
	v_div_scale_f32 v33, s[8:9], v32, v32, 1.0
	v_rcp_f32_e32 v34, v33
	v_div_scale_f32 v35, vcc, 1.0, v32, 1.0
	v_fma_f32 v36, -v33, v34, 1.0
	v_fmac_f32_e32 v34, v36, v34
	v_mul_f32_e32 v36, v35, v34
	v_fma_f32 v37, -v33, v36, v35
	v_fmac_f32_e32 v36, v37, v34
	v_fma_f32 v33, -v33, v36, v35
	v_div_fmas_f32 v33, v33, v34, v36
	v_div_fixup_f32 v32, v33, v32, 1.0
	v_bfe_u32 v33, v32, 16, 1
	v_add3_u32 v32, v32, v33, s77
	s_and_b64 vcc, exec, s[6:7]
	ds_write_b16_d16_hi v56, v32 offset:64
	v_mul_f32_e32 v32, 0xbfb8aa3b, v40
	v_exp_f32_e32 v32, v32
	s_nop 0
	v_add_f32_e32 v32, 1.0, v32
	v_div_scale_f32 v33, s[8:9], v32, v32, 1.0
	v_rcp_f32_e32 v34, v33
	v_div_scale_f32 v35, vcc, 1.0, v32, 1.0
	v_fma_f32 v36, -v33, v34, 1.0
	v_fmac_f32_e32 v34, v36, v34
	v_mul_f32_e32 v36, v35, v34
; __device__ __forceinline__ float sigmf(float x) { return 1.f / (1.f + __expf(-x)); }
; __device__ __forceinline__ void inproj_epilogue(const Params& p, int layer, int mt, int ntile, int tid,
;                                                 f32x16 (&acc)[2][2], unsigned char* smem) {
;     ...
;       if (mode == 2) o = sigmf(v);
;       sT[row * 136 + col] = f2bf(o);
	v_fma_f32 v37, -v33, v36, v35
	v_fmac_f32_e32 v36, v37, v34
	v_fma_f32 v33, -v33, v36, v35
	v_div_fmas_f32 v33, v33, v34, v36
	v_div_fixup_f32 v32, v33, v32, 1.0
	v_bfe_u32 v33, v32, 16, 1
	v_add3_u32 v32, v32, v33, s77
	s_and_b64 vcc, exec, s[6:7]
	ds_write_b16_d16_hi v57, v32 offset:64
	v_mul_f32_e32 v32, 0xbfb8aa3b, v41
	v_exp_f32_e32 v32, v32
	s_nop 0
	v_add_f32_e32 v32, 1.0, v32
	v_div_scale_f32 v33, s[8:9], v32, v32, 1.0
	v_rcp_f32_e32 v34, v33
	v_div_scale_f32 v35, vcc, 1.0, v32, 1.0
	v_fma_f32 v36, -v33, v34, 1.0
	v_fmac_f32_e32 v34, v36, v34
	v_mul_f32_e32 v36, v35, v34
	v_fma_f32 v37, -v33, v36, v35
	v_fmac_f32_e32 v36, v37, v34
	v_fma_f32 v33, -v33, v36, v35
	v_div_fmas_f32 v33, v33, v34, v36
	v_div_fixup_f32 v32, v33, v32, 1.0
	v_bfe_u32 v33, v32, 16, 1
	v_add3_u32 v32, v32, v33, s77
	s_and_b64 vcc, exec, s[6:7]
	ds_write_b16_d16_hi v58, v32 offset:64
	v_mul_f32_e32 v32, 0xbfb8aa3b, v42
	v_exp_f32_e32 v32, v32
	s_nop 0
	v_add_f32_e32 v32, 1.0, v32
	v_div_scale_f32 v33, s[8:9], v32, v32, 1.0
	v_rcp_f32_e32 v34, v33
	v_div_scale_f32 v35, vcc, 1.0, v32, 1.0
	v_fma_f32 v36, -v33, v34, 1.0
	v_fmac_f32_e32 v34, v36, v34
	v_mul_f32_e32 v36, v35, v34
	v_fma_f32 v37, -v33, v36, v35
	v_fmac_f32_e32 v36, v37, v34
	v_fma_f32 v33, -v33, v36, v35
	v_div_fmas_f32 v33, v33, v34, v36
	v_div_fixup_f32 v32, v33, v32, 1.0
	v_bfe_u32 v33, v32, 16, 1
	v_add3_u32 v32, v32, v33, s77
	s_and_b64 vcc, exec, s[6:7]
	ds_write_b16_d16_hi v59, v32 offset:64
	v_mul_f32_e32 v32, 0xbfb8aa3b, v43
	v_exp_f32_e32 v32, v32
	s_nop 0
	v_add_f32_e32 v32, 1.0, v32
	v_div_scale_f32 v33, s[8:9], v32, v32, 1.0
	v_rcp_f32_e32 v34, v33
	v_div_scale_f32 v35, vcc, 1.0, v32, 1.0
	v_fma_f32 v36, -v33, v34, 1.0
	v_fmac_f32_e32 v34, v36, v34
	v_mul_f32_e32 v36, v35, v34
	v_fma_f32 v37, -v33, v36, v35
	v_fmac_f32_e32 v36, v37, v34
	v_fma_f32 v33, -v33, v36, v35
	v_div_fmas_f32 v33, v33, v34, v36
	v_div_fixup_f32 v32, v33, v32, 1.0
	v_bfe_u32 v33, v32, 16, 1
	v_add3_u32 v32, v32, v33, s77
	s_and_b64 vcc, exec, s[6:7]
	ds_write_b16_d16_hi v60, v32 offset:64
	v_mul_f32_e32 v32, 0xbfb8aa3b, v44
	v_exp_f32_e32 v32, v32
	s_nop 0
	v_add_f32_e32 v32, 1.0, v32
	v_div_scale_f32 v33, s[8:9], v32, v32, 1.0
	v_rcp_f32_e32 v34, v33
	v_div_scale_f32 v35, vcc, 1.0, v32, 1.0
	v_fma_f32 v36, -v33, v34, 1.0
	v_fmac_f32_e32 v34, v36, v34
	v_mul_f32_e32 v36, v35, v34
	v_fma_f32 v37, -v33, v36, v35
	v_fmac_f32_e32 v36, v37, v34
	v_fma_f32 v33, -v33, v36, v35
	v_div_fmas_f32 v33, v33, v34, v36
	v_div_fixup_f32 v32, v33, v32, 1.0
	v_bfe_u32 v33, v32, 16, 1
	v_add3_u32 v32, v32, v33, s77
	s_and_b64 vcc, exec, s[6:7]
	ds_write_b16_d16_hi v61, v32 offset:64
	v_mul_f32_e32 v32, 0xbfb8aa3b, v45
	v_exp_f32_e32 v32, v32
	s_nop 0
	v_add_f32_e32 v32, 1.0, v32
	v_div_scale_f32 v33, s[8:9], v32, v32, 1.0
	v_rcp_f32_e32 v34, v33
	v_div_scale_f32 v35, vcc, 1.0, v32, 1.0
	v_fma_f32 v36, -v33, v34, 1.0
	v_fmac_f32_e32 v34, v36, v34
	v_mul_f32_e32 v36, v35, v34
	v_fma_f32 v37, -v33, v36, v35
	v_fmac_f32_e32 v36, v37, v34
	v_fma_f32 v33, -v33, v36, v35
	v_div_fmas_f32 v33, v33, v34, v36
	v_div_fixup_f32 v32, v33, v32, 1.0
	v_bfe_u32 v33, v32, 16, 1
	v_add3_u32 v32, v32, v33, s77
	s_and_b64 vcc, exec, s[6:7]
	ds_write_b16_d16_hi v62, v32 offset:64
	v_mul_f32_e32 v32, 0xbfb8aa3b, v46
	v_exp_f32_e32 v32, v32
	s_nop 0
	v_add_f32_e32 v32, 1.0, v32
	v_div_scale_f32 v33, s[8:9], v32, v32, 1.0
	v_rcp_f32_e32 v34, v33
	v_div_scale_f32 v35, vcc, 1.0, v32, 1.0
	v_fma_f32 v36, -v33, v34, 1.0
	v_fmac_f32_e32 v34, v36, v34
	v_mul_f32_e32 v36, v35, v34
	v_fma_f32 v37, -v33, v36, v35
	v_fmac_f32_e32 v36, v37, v34
	v_fma_f32 v33, -v33, v36, v35
	v_div_fmas_f32 v33, v33, v34, v36
	v_div_fixup_f32 v32, v33, v32, 1.0
	v_bfe_u32 v33, v32, 16, 1
	v_add3_u32 v32, v32, v33, s77
	s_and_b64 vcc, exec, s[6:7]
	ds_write_b16_d16_hi v55, v32 offset:64
	v_mul_f32_e32 v32, 0xbfb8aa3b, v47
	v_exp_f32_e32 v32, v32
	s_nop 0
	v_add_f32_e32 v32, 1.0, v32
	v_div_scale_f32 v33, s[4:5], v32, v32, 1.0
	v_rcp_f32_e32 v34, v33
	v_div_scale_f32 v35, vcc, 1.0, v32, 1.0
	v_fma_f32 v36, -v33, v34, 1.0
	v_fmac_f32_e32 v34, v36, v34
	v_mul_f32_e32 v36, v35, v34
	v_fma_f32 v37, -v33, v36, v35
	v_fmac_f32_e32 v36, v37, v34
	v_fma_f32 v33, -v33, v36, v35
	v_div_fmas_f32 v33, v33, v34, v36
	v_div_fixup_f32 v32, v33, v32, 1.0
	s_branch .LBB0_398

; __device__ __forceinline__ float sigmf(float x) { return 1.f / (1.f + __expf(-x)); }
; template <int MT, int NT, class F>
; __device__ __forceinline__ void acc_foreach(int tid, f32x16 (&acc)[MT][NT], F f) {
;     ...
;         int row = wm * (MT * 32) + mt * 32 + (i & 3) + 8 * (i >> 2) + 4 * hi;
;         int col = wn * (NT * 32) + nt * 32 + c;
; __device__ __forceinline__ void inproj_epilogue(const Params& p, int layer, int mt, int ntile, int tid,
;                                                 f32x16 (&acc)[2][2], unsigned char* smem) {
;     ...
;     acc_foreach(tid, acc, [&](int row, int col, float v) {
;       int t = m0 + row;
;       float o = v;
;       if (mode == 1) o = (t >= NPADR) ? v : 0.f;
;       if (mode == 2) o = sigmf(v);
;       sT[row * 136 + col] = f2bf(o);
;     });
.LBB0_528:
	v_bfe_u32 v110, v107, 16, 1
	v_and_b32_e32 v106, 0x5f, v106
	v_add3_u32 v111, v107, v110, s78
	v_mul_lo_u32 v110, v96, s79
	v_lshl_add_u32 v107, v106, 1, v110
	ds_write_b16_d16_hi v107, v111
	v_add3_u32 v111, s90, v96, 1
	v_cmp_lt_i32_e64 s[10:11], s76, v111
	v_cndmask_b32_e64 v111, 0, 1, s[12:13]
	v_cmp_ne_u32_e64 s[6:7], 1, v111
	s_nop 1

; __device__ __forceinline__ float sigmf(float x) { return 1.f / (1.f + __expf(-x)); }
; template <int MT, int NT, class F>
; __device__ __forceinline__ void acc_foreach(int tid, f32x16 (&acc)[MT][NT], F f) {
;     ...
;         int row = wm * (MT * 32) + mt * 32 + (i & 3) + 8 * (i >> 2) + 4 * hi;
;         int col = wn * (NT * 32) + nt * 32 + c;
; __device__ __forceinline__ void inproj_epilogue(const Params& p, int layer, int mt, int ntile, int tid,
;                                                 f32x16 (&acc)[2][2], unsigned char* smem) {
;     ...
;     acc_foreach(tid, acc, [&](int row, int col, float v) {
;       int t = m0 + row;
;       float o = v;
;       if (mode == 1) o = (t >= NPADR) ? v : 0.f;
;       if (mode == 2) o = sigmf(v);
;       sT[row * 136 + col] = f2bf(o);
;     });
.LBB0_531:
	v_bfe_u32 v112, v111, 16, 1
	v_add3_u32 v112, v111, v112, s78
	v_add_u32_e32 v111, 0x110, v110
	v_lshl_add_u32 v110, v106, 1, v111
	ds_write_b16_d16_hi v110, v112
	v_add3_u32 v112, s90, v96, 2
	v_cmp_lt_i32_e64 s[12:13], s76, v112
	s_nop 1

; __device__ __forceinline__ float sigmf(float x) { return 1.f / (1.f + __expf(-x)); }
; template <int MT, int NT, class F>
; __device__ __forceinline__ void acc_foreach(int tid, f32x16 (&acc)[MT][NT], F f) {
;     ...
;         int row = wm * (MT * 32) + mt * 32 + (i & 3) + 8 * (i >> 2) + 4 * hi;
;         int col = wn * (NT * 32) + nt * 32 + c;
; __device__ __forceinline__ void inproj_epilogue(const Params& p, int layer, int mt, int ntile, int tid,
;                                                 f32x16 (&acc)[2][2], unsigned char* smem) {
;     ...
;     acc_foreach(tid, acc, [&](int row, int col, float v) {
;       int t = m0 + row;
;       float o = v;
;       if (mode == 1) o = (t >= NPADR) ? v : 0.f;
;       if (mode == 2) o = sigmf(v);
;       sT[row * 136 + col] = f2bf(o);
;     });
.LBB0_534:
	v_bfe_u32 v113, v112, 16, 1
	v_add3_u32 v113, v112, v113, s78
	v_add_u32_e32 v112, 0x110, v111
	v_lshl_add_u32 v111, v106, 1, v112
	ds_write_b16_d16_hi v111, v113
	v_add3_u32 v113, s90, v96, 3
	v_cmp_lt_i32_e64 s[14:15], s76, v113
	s_nop 1

; __device__ __forceinline__ float sigmf(float x) { return 1.f / (1.f + __expf(-x)); }
; template <int MT, int NT, class F>
; __device__ __forceinline__ void acc_foreach(int tid, f32x16 (&acc)[MT][NT], F f) {
;     ...
;         int row = wm * (MT * 32) + mt * 32 + (i & 3) + 8 * (i >> 2) + 4 * hi;
;         int col = wn * (NT * 32) + nt * 32 + c;
; __device__ __forceinline__ void inproj_epilogue(const Params& p, int layer, int mt, int ntile, int tid,
;                                                 f32x16 (&acc)[2][2], unsigned char* smem) {
;     ...
;     acc_foreach(tid, acc, [&](int row, int col, float v) {
;       int t = m0 + row;
;       float o = v;
;       if (mode == 1) o = (t >= NPADR) ? v : 0.f;
;       if (mode == 2) o = sigmf(v);
;       sT[row * 136 + col] = f2bf(o);
;     });
.LBB0_537:
	v_bfe_u32 v114, v113, 16, 1
	v_add3_u32 v114, v113, v114, s78
	v_add_u32_e32 v113, 0x110, v112
	v_lshl_add_u32 v112, v106, 1, v113
	ds_write_b16_d16_hi v112, v114
	v_add3_u32 v114, s90, v96, 8
	v_cmp_lt_i32_e64 s[16:17], s76, v114
	s_nop 1

; __device__ __forceinline__ float sigmf(float x) { return 1.f / (1.f + __expf(-x)); }
; template <int MT, int NT, class F>
; __device__ __forceinline__ void acc_foreach(int tid, f32x16 (&acc)[MT][NT], F f) {
;     ...
;         int row = wm * (MT * 32) + mt * 32 + (i & 3) + 8 * (i >> 2) + 4 * hi;
;         int col = wn * (NT * 32) + nt * 32 + c;
; __device__ __forceinline__ void inproj_epilogue(const Params& p, int layer, int mt, int ntile, int tid,
;                                                 f32x16 (&acc)[2][2], unsigned char* smem) {
;     ...
;     acc_foreach(tid, acc, [&](int row, int col, float v) {
;       int t = m0 + row;
;       float o = v;
;       if (mode == 1) o = (t >= NPADR) ? v : 0.f;
;       if (mode == 2) o = sigmf(v);
;       sT[row * 136 + col] = f2bf(o);
;     });
.LBB0_540:
	v_bfe_u32 v115, v114, 16, 1
	v_add3_u32 v115, v114, v115, s78
	v_add_u32_e32 v114, 0x550, v113
	v_lshl_add_u32 v113, v106, 1, v114
	ds_write_b16_d16_hi v113, v115
	v_add3_u32 v115, s90, v96, 9
	v_cmp_lt_i32_e64 s[18:19], s76, v115
	s_nop 1

; __device__ __forceinline__ float sigmf(float x) { return 1.f / (1.f + __expf(-x)); }
; template <int MT, int NT, class F>
; __device__ __forceinline__ void acc_foreach(int tid, f32x16 (&acc)[MT][NT], F f) {
;     ...
;         int row = wm * (MT * 32) + mt * 32 + (i & 3) + 8 * (i >> 2) + 4 * hi;
;         int col = wn * (NT * 32) + nt * 32 + c;
; __device__ __forceinline__ void inproj_epilogue(const Params& p, int layer, int mt, int ntile, int tid,
;                                                 f32x16 (&acc)[2][2], unsigned char* smem) {
;     ...
;     acc_foreach(tid, acc, [&](int row, int col, float v) {
;       int t = m0 + row;
;       float o = v;
;       if (mode == 1) o = (t >= NPADR) ? v : 0.f;
;       if (mode == 2) o = sigmf(v);
;       sT[row * 136 + col] = f2bf(o);
;     });
.LBB0_543:
	v_bfe_u32 v116, v115, 16, 1
	v_add3_u32 v116, v115, v116, s78
	v_add_u32_e32 v115, 0x110, v114
	v_lshl_add_u32 v114, v106, 1, v115
	ds_write_b16_d16_hi v114, v116
	v_add3_u32 v116, s90, v96, 10
	v_cmp_lt_i32_e64 s[20:21], s76, v116
	s_nop 1

; __device__ __forceinline__ float sigmf(float x) { return 1.f / (1.f + __expf(-x)); }
; template <int MT, int NT, class F>
; __device__ __forceinline__ void acc_foreach(int tid, f32x16 (&acc)[MT][NT], F f) {
;     ...
;   for (int mt = 0; mt < MT; mt++)
; #pragma unroll
;     for (int nt = 0; nt < NT; nt++)
; #pragma unroll
;       for (int i = 0; i < 16; i++) {
;         int row = wm * (MT * 32) + mt * 32 + (i & 3) + 8 * (i >> 2) + 4 * hi;
;         int col = wn * (NT * 32) + nt * 32 + c;
;         f(row, col, acc[mt][nt][i]);
; __device__ __forceinline__ void inproj_epilogue(const Params& p, int layer, int mt, int ntile, int tid,
;                                                 f32x16 (&acc)[2][2], unsigned char* smem) {
;     ...
;     acc_foreach(tid, acc, [&](int row, int col, float v) {
;       int t = m0 + row;
;       float o = v;
;       if (mode == 1) o = (t >= NPADR) ? v : 0.f;
;       if (mode == 2) o = sigmf(v);
;       sT[row * 136 + col] = f2bf(o);
;     });
.LBB0_546:
	v_bfe_u32 v117, v116, 16, 1
	v_add3_u32 v117, v116, v117, s78
	v_add_u32_e32 v116, 0x110, v115
	v_lshl_add_u32 v115, v106, 1, v116
	ds_write_b16_d16_hi v115, v117
	v_add3_u32 v117, s90, v96, 11
	v_cmp_lt_i32_e64 s[22:23], s76, v117
	s_nop 1

; __device__ __forceinline__ float sigmf(float x) { return 1.f / (1.f + __expf(-x)); }
; template <int MT, int NT, class F>
; __device__ __forceinline__ void acc_foreach(int tid, f32x16 (&acc)[MT][NT], F f) {
;     ...
;   for (int mt = 0; mt < MT; mt++)
; #pragma unroll
;     for (int nt = 0; nt < NT; nt++)
; #pragma unroll
;       for (int i = 0; i < 16; i++) {
;         int row = wm * (MT * 32) + mt * 32 + (i & 3) + 8 * (i >> 2) + 4 * hi;
;         int col = wn * (NT * 32) + nt * 32 + c;
;         f(row, col, acc[mt][nt][i]);
; __device__ __forceinline__ void inproj_epilogue(const Params& p, int layer, int mt, int ntile, int tid,
;                                                 f32x16 (&acc)[2][2], unsigned char* smem) {
;     ...
;     acc_foreach(tid, acc, [&](int row, int col, float v) {
;       int t = m0 + row;
;       float o = v;
;       if (mode == 1) o = (t >= NPADR) ? v : 0.f;
;       if (mode == 2) o = sigmf(v);
;       sT[row * 136 + col] = f2bf(o);
;     });
.LBB0_549:
	v_bfe_u32 v118, v117, 16, 1
	v_add_u32_e32 v116, 0x110, v116
	v_add3_u32 v118, v117, v118, s78
	v_lshl_add_u32 v117, v106, 1, v116
	ds_write_b16_d16_hi v117, v118
	v_add3_u32 v118, s90, v96, 16
	v_cmp_lt_i32_e64 s[24:25], s76, v118
	s_nop 1

; __device__ __forceinline__ float sigmf(float x) { return 1.f / (1.f + __expf(-x)); }
; template <int MT, int NT, class F>
; __device__ __forceinline__ void acc_foreach(int tid, f32x16 (&acc)[MT][NT], F f) {
;     ...
;   for (int mt = 0; mt < MT; mt++)
; #pragma unroll
;     for (int nt = 0; nt < NT; nt++)
; #pragma unroll
;       for (int i = 0; i < 16; i++) {
;         int row = wm * (MT * 32) + mt * 32 + (i & 3) + 8 * (i >> 2) + 4 * hi;
;         int col = wn * (NT * 32) + nt * 32 + c;
;         f(row, col, acc[mt][nt][i]);
; __device__ __forceinline__ void inproj_epilogue(const Params& p, int layer, int mt, int ntile, int tid,
;                                                 f32x16 (&acc)[2][2], unsigned char* smem) {
;     ...
;     acc_foreach(tid, acc, [&](int row, int col, float v) {
;       int t = m0 + row;
;       float o = v;
;       if (mode == 1) o = (t >= NPADR) ? v : 0.f;
;       if (mode == 2) o = sigmf(v);
;       sT[row * 136 + col] = f2bf(o);
;     });
.LBB0_552:
	v_bfe_u32 v119, v118, 16, 1
	v_add_u32_e32 v116, 0x550, v116
	v_add3_u32 v119, v118, v119, s78
	v_lshl_add_u32 v118, v106, 1, v116
	ds_write_b16_d16_hi v118, v119
	v_add3_u32 v119, s90, v96, 17
	v_cmp_lt_i32_e64 s[26:27], s76, v119
	s_nop 1

; __device__ __forceinline__ float sigmf(float x) { return 1.f / (1.f + __expf(-x)); }
; template <int MT, int NT, class F>
; __device__ __forceinline__ void acc_foreach(int tid, f32x16 (&acc)[MT][NT], F f) {
;     ...
;   for (int mt = 0; mt < MT; mt++)
; #pragma unroll
;     for (int nt = 0; nt < NT; nt++)
; #pragma unroll
;       for (int i = 0; i < 16; i++) {
;         int row = wm * (MT * 32) + mt * 32 + (i & 3) + 8 * (i >> 2) + 4 * hi;
;         int col = wn * (NT * 32) + nt * 32 + c;
;         f(row, col, acc[mt][nt][i]);
; __device__ __forceinline__ void inproj_epilogue(const Params& p, int layer, int mt, int ntile, int tid,
;                                                 f32x16 (&acc)[2][2], unsigned char* smem) {
;     ...
;     acc_foreach(tid, acc, [&](int row, int col, float v) {
;       int t = m0 + row;
;       float o = v;
;       if (mode == 1) o = (t >= NPADR) ? v : 0.f;
;       if (mode == 2) o = sigmf(v);
;       sT[row * 136 + col] = f2bf(o);
;     });
.LBB0_555:
	v_bfe_u32 v120, v119, 16, 1
	v_add_u32_e32 v116, 0x110, v116
	v_add3_u32 v120, v119, v120, s78
	v_lshl_add_u32 v119, v106, 1, v116
	ds_write_b16_d16_hi v119, v120
	v_add3_u32 v120, s90, v96, 18
	v_cmp_lt_i32_e64 s[28:29], s76, v120
	s_nop 1

; __device__ __forceinline__ float sigmf(float x) { return 1.f / (1.f + __expf(-x)); }
; template <int MT, int NT, class F>
; __device__ __forceinline__ void acc_foreach(int tid, f32x16 (&acc)[MT][NT], F f) {
;     ...
;   for (int mt = 0; mt < MT; mt++)
; #pragma unroll
;     for (int nt = 0; nt < NT; nt++)
; #pragma unroll
;       for (int i = 0; i < 16; i++) {
;         int row = wm * (MT * 32) + mt * 32 + (i & 3) + 8 * (i >> 2) + 4 * hi;
;         int col = wn * (NT * 32) + nt * 32 + c;
;         f(row, col, acc[mt][nt][i]);
; __device__ __forceinline__ void inproj_epilogue(const Params& p, int layer, int mt, int ntile, int tid,
;                                                 f32x16 (&acc)[2][2], unsigned char* smem) {
;     ...
;     acc_foreach(tid, acc, [&](int row, int col, float v) {
;       int t = m0 + row;
;       float o = v;
;       if (mode == 1) o = (t >= NPADR) ? v : 0.f;
;       if (mode == 2) o = sigmf(v);
;       sT[row * 136 + col] = f2bf(o);
;     });
.LBB0_558:
	v_bfe_u32 v121, v120, 16, 1
	v_add_u32_e32 v116, 0x110, v116
	v_add3_u32 v121, v120, v121, s78
	v_lshl_add_u32 v120, v106, 1, v116
	ds_write_b16_d16_hi v120, v121
	v_add3_u32 v121, s90, v96, 19
	v_cmp_lt_i32_e64 s[30:31], s76, v121
	s_nop 1

; __device__ __forceinline__ float sigmf(float x) { return 1.f / (1.f + __expf(-x)); }
; template <int MT, int NT, class F>
; __device__ __forceinline__ void acc_foreach(int tid, f32x16 (&acc)[MT][NT], F f) {
;     ...
;   for (int mt = 0; mt < MT; mt++)
; #pragma unroll
;     for (int nt = 0; nt < NT; nt++)
; #pragma unroll
;       for (int i = 0; i < 16; i++) {
;         int row = wm * (MT * 32) + mt * 32 + (i & 3) + 8 * (i >> 2) + 4 * hi;
;         int col = wn * (NT * 32) + nt * 32 + c;
;         f(row, col, acc[mt][nt][i]);
; __device__ __forceinline__ void inproj_epilogue(const Params& p, int layer, int mt, int ntile, int tid,
;                                                 f32x16 (&acc)[2][2], unsigned char* smem) {
;     ...
;     acc_foreach(tid, acc, [&](int row, int col, float v) {
;       int t = m0 + row;
;       float o = v;
;       if (mode == 1) o = (t >= NPADR) ? v : 0.f;
;       if (mode == 2) o = sigmf(v);
;       sT[row * 136 + col] = f2bf(o);
;     });
.LBB0_561:
	v_bfe_u32 v122, v121, 16, 1
	v_add_u32_e32 v116, 0x110, v116
	v_add3_u32 v122, v121, v122, s78
	v_lshl_add_u32 v121, v106, 1, v116
	ds_write_b16_d16_hi v121, v122
	v_add3_u32 v122, s90, v96, 24
	v_cmp_lt_i32_e64 s[34:35], s76, v122
	s_nop 1

; __device__ __forceinline__ float sigmf(float x) { return 1.f / (1.f + __expf(-x)); }
; template <int MT, int NT, class F>
; __device__ __forceinline__ void acc_foreach(int tid, f32x16 (&acc)[MT][NT], F f) {
;     ...
;   for (int mt = 0; mt < MT; mt++)
; #pragma unroll
;     for (int nt = 0; nt < NT; nt++)
; #pragma unroll
;       for (int i = 0; i < 16; i++) {
;         int row = wm * (MT * 32) + mt * 32 + (i & 3) + 8 * (i >> 2) + 4 * hi;
;         int col = wn * (NT * 32) + nt * 32 + c;
;         f(row, col, acc[mt][nt][i]);
; __device__ __forceinline__ void inproj_epilogue(const Params& p, int layer, int mt, int ntile, int tid,
;                                                 f32x16 (&acc)[2][2], unsigned char* smem) {
;     ...
;     acc_foreach(tid, acc, [&](int row, int col, float v) {
;       int t = m0 + row;
;       float o = v;
;       if (mode == 1) o = (t >= NPADR) ? v : 0.f;
;       if (mode == 2) o = sigmf(v);
;       sT[row * 136 + col] = f2bf(o);
;     });
.LBB0_564:
	v_bfe_u32 v123, v122, 16, 1
	v_add_u32_e32 v116, 0x550, v116
	v_add3_u32 v123, v122, v123, s78
	v_lshl_add_u32 v122, v106, 1, v116
	ds_write_b16_d16_hi v122, v123
	v_add3_u32 v123, s90, v96, 25
	v_cmp_lt_i32_e64 s[36:37], s76, v123
	s_nop 1

; __device__ __forceinline__ float sigmf(float x) { return 1.f / (1.f + __expf(-x)); }
; template <int MT, int NT, class F>
; __device__ __forceinline__ void acc_foreach(int tid, f32x16 (&acc)[MT][NT], F f) {
;     ...
;   for (int mt = 0; mt < MT; mt++)
; #pragma unroll
;     for (int nt = 0; nt < NT; nt++)
; #pragma unroll
;       for (int i = 0; i < 16; i++) {
;         int row = wm * (MT * 32) + mt * 32 + (i & 3) + 8 * (i >> 2) + 4 * hi;
;         int col = wn * (NT * 32) + nt * 32 + c;
;         f(row, col, acc[mt][nt][i]);
; __device__ __forceinline__ void inproj_epilogue(const Params& p, int layer, int mt, int ntile, int tid,
;                                                 f32x16 (&acc)[2][2], unsigned char* smem) {
;     ...
;     acc_foreach(tid, acc, [&](int row, int col, float v) {
;       int t = m0 + row;
;       float o = v;
;       if (mode == 1) o = (t >= NPADR) ? v : 0.f;
;       if (mode == 2) o = sigmf(v);
;       sT[row * 136 + col] = f2bf(o);
;     });
.LBB0_567:
	v_bfe_u32 v124, v123, 16, 1
	v_add_u32_e32 v116, 0x110, v116
	v_add3_u32 v124, v123, v124, s78
	v_lshl_add_u32 v123, v106, 1, v116
	ds_write_b16_d16_hi v123, v124
	v_add3_u32 v124, s90, v96, 26
	v_cmp_lt_i32_e64 s[38:39], s76, v124
	s_nop 1

; __device__ __forceinline__ float sigmf(float x) { return 1.f / (1.f + __expf(-x)); }
; template <int MT, int NT, class F>
; __device__ __forceinline__ void acc_foreach(int tid, f32x16 (&acc)[MT][NT], F f) {
;     ...
;   for (int mt = 0; mt < MT; mt++)
; #pragma unroll
;     for (int nt = 0; nt < NT; nt++)
; #pragma unroll
;       for (int i = 0; i < 16; i++) {
;         int row = wm * (MT * 32) + mt * 32 + (i & 3) + 8 * (i >> 2) + 4 * hi;
;         int col = wn * (NT * 32) + nt * 32 + c;
;         f(row, col, acc[mt][nt][i]);
; __device__ __forceinline__ void inproj_epilogue(const Params& p, int layer, int mt, int ntile, int tid,
;                                                 f32x16 (&acc)[2][2], unsigned char* smem) {
;     ...
;     acc_foreach(tid, acc, [&](int row, int col, float v) {
;       int t = m0 + row;
;       float o = v;
;       if (mode == 1) o = (t >= NPADR) ? v : 0.f;
;       if (mode == 2) o = sigmf(v);
;       sT[row * 136 + col] = f2bf(o);
;     });
.LBB0_570:
	v_bfe_u32 v125, v124, 16, 1
	v_add_u32_e32 v116, 0x110, v116
	v_add3_u32 v124, v124, v125, s78
	v_lshl_add_u32 v116, v106, 1, v116
	ds_write_b16_d16_hi v116, v124
	v_add3_u32 v124, s90, v96, 27
	v_cmp_lt_i32_e64 s[40:41], s76, v124
	s_nop 1

; __device__ __forceinline__ float sigmf(float x) { return 1.f / (1.f + __expf(-x)); }
; template <int MT, int NT, class F>
; __device__ __forceinline__ void acc_foreach(int tid, f32x16 (&acc)[MT][NT], F f) {
;     ...
;   for (int mt = 0; mt < MT; mt++)
; #pragma unroll
;     for (int nt = 0; nt < NT; nt++)
; #pragma unroll
;       for (int i = 0; i < 16; i++) {
;         int row = wm * (MT * 32) + mt * 32 + (i & 3) + 8 * (i >> 2) + 4 * hi;
;         int col = wn * (NT * 32) + nt * 32 + c;
;         f(row, col, acc[mt][nt][i]);
; __device__ __forceinline__ void inproj_epilogue(const Params& p, int layer, int mt, int ntile, int tid,
;                                                 f32x16 (&acc)[2][2], unsigned char* smem) {
;     ...
;     acc_foreach(tid, acc, [&](int row, int col, float v) {
;       int t = m0 + row;
;       float o = v;
;       if (mode == 1) o = (t >= NPADR) ? v : 0.f;
;       if (mode == 2) o = sigmf(v);
;       sT[row * 136 + col] = f2bf(o);
;     });
.LBB0_573:
	v_bfe_u32 v125, v124, 16, 1
	v_add3_u32 v124, v124, v125, s78
	ds_write_b16_d16_hi v116, v124 offset:272
	s_nop 1

; __device__ __forceinline__ float sigmf(float x) { return 1.f / (1.f + __expf(-x)); }
; template <int MT, int NT, class F>
; __device__ __forceinline__ void acc_foreach(int tid, f32x16 (&acc)[MT][NT], F f) {
;     ...
;   for (int mt = 0; mt < MT; mt++)
; #pragma unroll
;     for (int nt = 0; nt < NT; nt++)
; #pragma unroll
;       for (int i = 0; i < 16; i++) {
;         int row = wm * (MT * 32) + mt * 32 + (i & 3) + 8 * (i >> 2) + 4 * hi;
;         int col = wn * (NT * 32) + nt * 32 + c;
;         f(row, col, acc[mt][nt][i]);
; __device__ __forceinline__ void inproj_epilogue(const Params& p, int layer, int mt, int ntile, int tid,
;                                                 f32x16 (&acc)[2][2], unsigned char* smem) {
;     ...
;     acc_foreach(tid, acc, [&](int row, int col, float v) {
;       int t = m0 + row;
;       float o = v;
;       if (mode == 1) o = (t >= NPADR) ? v : 0.f;
;       if (mode == 2) o = sigmf(v);
;       sT[row * 136 + col] = f2bf(o);
;     });
.LBB0_576:
	v_bfe_u32 v124, v48, 16, 1
	v_add3_u32 v48, v48, v124, s78
	ds_write_b16_d16_hi v107, v48 offset:64
	s_nop 1

; __device__ __forceinline__ float sigmf(float x) { return 1.f / (1.f + __expf(-x)); }
; template <int MT, int NT, class F>
; __device__ __forceinline__ void acc_foreach(int tid, f32x16 (&acc)[MT][NT], F f) {
;     ...
;   for (int mt = 0; mt < MT; mt++)
; #pragma unroll
;     for (int nt = 0; nt < NT; nt++)
; #pragma unroll
;       for (int i = 0; i < 16; i++) {
;         int row = wm * (MT * 32) + mt * 32 + (i & 3) + 8 * (i >> 2) + 4 * hi;
;         int col = wn * (NT * 32) + nt * 32 + c;
;         f(row, col, acc[mt][nt][i]);
; __device__ __forceinline__ void inproj_epilogue(const Params& p, int layer, int mt, int ntile, int tid,
;                                                 f32x16 (&acc)[2][2], unsigned char* smem) {
;     ...
;     acc_foreach(tid, acc, [&](int row, int col, float v) {
;       int t = m0 + row;
;       float o = v;
;       if (mode == 1) o = (t >= NPADR) ? v : 0.f;
;       if (mode == 2) o = sigmf(v);
;       sT[row * 136 + col] = f2bf(o);
;     });
.LBB0_579:
	v_bfe_u32 v49, v48, 16, 1
	v_add3_u32 v48, v48, v49, s78
	ds_write_b16_d16_hi v110, v48 offset:64
	s_nop 1

; __device__ __forceinline__ float sigmf(float x) { return 1.f / (1.f + __expf(-x)); }
; template <int MT, int NT, class F>
; __device__ __forceinline__ void acc_foreach(int tid, f32x16 (&acc)[MT][NT], F f) {
;     ...
;   for (int mt = 0; mt < MT; mt++)
; #pragma unroll
;     for (int nt = 0; nt < NT; nt++)
; #pragma unroll
;       for (int i = 0; i < 16; i++) {
;         int row = wm * (MT * 32) + mt * 32 + (i & 3) + 8 * (i >> 2) + 4 * hi;
;         int col = wn * (NT * 32) + nt * 32 + c;
;         f(row, col, acc[mt][nt][i]);
; __device__ __forceinline__ void inproj_epilogue(const Params& p, int layer, int mt, int ntile, int tid,
;                                                 f32x16 (&acc)[2][2], unsigned char* smem) {
;     ...
;     acc_foreach(tid, acc, [&](int row, int col, float v) {
;       int t = m0 + row;
;       float o = v;
;       if (mode == 1) o = (t >= NPADR) ? v : 0.f;
;       if (mode == 2) o = sigmf(v);
;       sT[row * 136 + col] = f2bf(o);
;     });
.LBB0_582:
	v_bfe_u32 v49, v48, 16, 1
	v_add3_u32 v48, v48, v49, s78
	ds_write_b16_d16_hi v111, v48 offset:64
	s_nop 1

; __device__ __forceinline__ float sigmf(float x) { return 1.f / (1.f + __expf(-x)); }
; template <int MT, int NT, class F>
; __device__ __forceinline__ void acc_foreach(int tid, f32x16 (&acc)[MT][NT], F f) {
;     ...
;   for (int mt = 0; mt < MT; mt++)
; #pragma unroll
;     for (int nt = 0; nt < NT; nt++)
; #pragma unroll
;       for (int i = 0; i < 16; i++) {
;         int row = wm * (MT * 32) + mt * 32 + (i & 3) + 8 * (i >> 2) + 4 * hi;
;         int col = wn * (NT * 32) + nt * 32 + c;
;         f(row, col, acc[mt][nt][i]);
; __device__ __forceinline__ void inproj_epilogue(const Params& p, int layer, int mt, int ntile, int tid,
;                                                 f32x16 (&acc)[2][2], unsigned char* smem) {
;     ...
;     acc_foreach(tid, acc, [&](int row, int col, float v) {
;       int t = m0 + row;
;       float o = v;
;       if (mode == 1) o = (t >= NPADR) ? v : 0.f;
;       if (mode == 2) o = sigmf(v);
;       sT[row * 136 + col] = f2bf(o);
;     });
.LBB0_585:
	v_bfe_u32 v49, v48, 16, 1
	v_add3_u32 v48, v48, v49, s78
	ds_write_b16_d16_hi v112, v48 offset:64
	s_nop 1

; __device__ __forceinline__ float sigmf(float x) { return 1.f / (1.f + __expf(-x)); }
; template <int MT, int NT, class F>
; __device__ __forceinline__ void acc_foreach(int tid, f32x16 (&acc)[MT][NT], F f) {
;     ...
;   for (int mt = 0; mt < MT; mt++)
; #pragma unroll
;     for (int nt = 0; nt < NT; nt++)
; #pragma unroll
;       for (int i = 0; i < 16; i++) {
;         int row = wm * (MT * 32) + mt * 32 + (i & 3) + 8 * (i >> 2) + 4 * hi;
;         int col = wn * (NT * 32) + nt * 32 + c;
;         f(row, col, acc[mt][nt][i]);
; __device__ __forceinline__ void inproj_epilogue(const Params& p, int layer, int mt, int ntile, int tid,
;                                                 f32x16 (&acc)[2][2], unsigned char* smem) {
;     ...
;     acc_foreach(tid, acc, [&](int row, int col, float v) {
;       int t = m0 + row;
;       float o = v;
;       if (mode == 1) o = (t >= NPADR) ? v : 0.f;
;       if (mode == 2) o = sigmf(v);
;       sT[row * 136 + col] = f2bf(o);
;     });
.LBB0_588:
	v_bfe_u32 v49, v48, 16, 1
	v_add3_u32 v48, v48, v49, s78
	ds_write_b16_d16_hi v113, v48 offset:64
	s_nop 1

; __device__ __forceinline__ float sigmf(float x) { return 1.f / (1.f + __expf(-x)); }
; template <int MT, int NT, class F>
; __device__ __forceinline__ void acc_foreach(int tid, f32x16 (&acc)[MT][NT], F f) {
;     ...
;   for (int mt = 0; mt < MT; mt++)
; #pragma unroll
;     for (int nt = 0; nt < NT; nt++)
; #pragma unroll
;       for (int i = 0; i < 16; i++) {
;         int row = wm * (MT * 32) + mt * 32 + (i & 3) + 8 * (i >> 2) + 4 * hi;
;         int col = wn * (NT * 32) + nt * 32 + c;
;         f(row, col, acc[mt][nt][i]);
; __device__ __forceinline__ void inproj_epilogue(const Params& p, int layer, int mt, int ntile, int tid,
;                                                 f32x16 (&acc)[2][2], unsigned char* smem) {
;     ...
;     acc_foreach(tid, acc, [&](int row, int col, float v) {
;       int t = m0 + row;
;       float o = v;
;       if (mode == 1) o = (t >= NPADR) ? v : 0.f;
;       if (mode == 2) o = sigmf(v);
;       sT[row * 136 + col] = f2bf(o);
;     });
.LBB0_591:
	v_bfe_u32 v49, v48, 16, 1
	v_add3_u32 v48, v48, v49, s78
	ds_write_b16_d16_hi v114, v48 offset:64
	s_nop 1

; __device__ __forceinline__ float sigmf(float x) { return 1.f / (1.f + __expf(-x)); }
; template <int MT, int NT, class F>
; __device__ __forceinline__ void acc_foreach(int tid, f32x16 (&acc)[MT][NT], F f) {
;     ...
;   for (int mt = 0; mt < MT; mt++)
; #pragma unroll
;     for (int nt = 0; nt < NT; nt++)
; #pragma unroll
;       for (int i = 0; i < 16; i++) {
;         int row = wm * (MT * 32) + mt * 32 + (i & 3) + 8 * (i >> 2) + 4 * hi;
;         int col = wn * (NT * 32) + nt * 32 + c;
;         f(row, col, acc[mt][nt][i]);
; __device__ __forceinline__ void inproj_epilogue(const Params& p, int layer, int mt, int ntile, int tid,
;                                                 f32x16 (&acc)[2][2], unsigned char* smem) {
;     ...
;     acc_foreach(tid, acc, [&](int row, int col, float v) {
;       int t = m0 + row;
;       float o = v;
;       if (mode == 1) o = (t >= NPADR) ? v : 0.f;
;       if (mode == 2) o = sigmf(v);
;       sT[row * 136 + col] = f2bf(o);
;     });
.LBB0_594:
	v_bfe_u32 v49, v48, 16, 1
	v_add3_u32 v48, v48, v49, s78
	ds_write_b16_d16_hi v115, v48 offset:64
	s_nop 1

; __device__ __forceinline__ float sigmf(float x) { return 1.f / (1.f + __expf(-x)); }
; template <int MT, int NT, class F>
; __device__ __forceinline__ void acc_foreach(int tid, f32x16 (&acc)[MT][NT], F f) {
;     ...
;   for (int mt = 0; mt < MT; mt++)
; #pragma unroll
;     for (int nt = 0; nt < NT; nt++)
; #pragma unroll
;       for (int i = 0; i < 16; i++) {
;         int row = wm * (MT * 32) + mt * 32 + (i & 3) + 8 * (i >> 2) + 4 * hi;
;         int col = wn * (NT * 32) + nt * 32 + c;
;         f(row, col, acc[mt][nt][i]);
; __device__ __forceinline__ void inproj_epilogue(const Params& p, int layer, int mt, int ntile, int tid,
;                                                 f32x16 (&acc)[2][2], unsigned char* smem) {
;     ...
;     acc_foreach(tid, acc, [&](int row, int col, float v) {
;       int t = m0 + row;
;       float o = v;
;       if (mode == 1) o = (t >= NPADR) ? v : 0.f;
;       if (mode == 2) o = sigmf(v);
;       sT[row * 136 + col] = f2bf(o);
;     });
.LBB0_597:
	v_bfe_u32 v49, v48, 16, 1
	v_add3_u32 v48, v48, v49, s78
	ds_write_b16_d16_hi v117, v48 offset:64
	s_nop 1

; __device__ __forceinline__ float sigmf(float x) { return 1.f / (1.f + __expf(-x)); }
; template <int MT, int NT, class F>
; __device__ __forceinline__ void acc_foreach(int tid, f32x16 (&acc)[MT][NT], F f) {
;     ...
;   for (int mt = 0; mt < MT; mt++)
; #pragma unroll
;     for (int nt = 0; nt < NT; nt++)
; #pragma unroll
;       for (int i = 0; i < 16; i++) {
;         int row = wm * (MT * 32) + mt * 32 + (i & 3) + 8 * (i >> 2) + 4 * hi;
;         int col = wn * (NT * 32) + nt * 32 + c;
;         f(row, col, acc[mt][nt][i]);
; __device__ __forceinline__ void inproj_epilogue(const Params& p, int layer, int mt, int ntile, int tid,
;                                                 f32x16 (&acc)[2][2], unsigned char* smem) {
;     ...
;     acc_foreach(tid, acc, [&](int row, int col, float v) {
;       int t = m0 + row;
;       float o = v;
;       if (mode == 1) o = (t >= NPADR) ? v : 0.f;
;       if (mode == 2) o = sigmf(v);
;       sT[row * 136 + col] = f2bf(o);
;     });
.LBB0_600:
	v_bfe_u32 v49, v48, 16, 1
	v_add3_u32 v48, v48, v49, s78
	ds_write_b16_d16_hi v118, v48 offset:64
	s_nop 1

; __device__ __forceinline__ float sigmf(float x) { return 1.f / (1.f + __expf(-x)); }
; template <int MT, int NT, class F>
; __device__ __forceinline__ void acc_foreach(int tid, f32x16 (&acc)[MT][NT], F f) {
;     ...
;   for (int mt = 0; mt < MT; mt++)
; #pragma unroll
;     for (int nt = 0; nt < NT; nt++)
; #pragma unroll
;       for (int i = 0; i < 16; i++) {
;         int row = wm * (MT * 32) + mt * 32 + (i & 3) + 8 * (i >> 2) + 4 * hi;
;         int col = wn * (NT * 32) + nt * 32 + c;
;         f(row, col, acc[mt][nt][i]);
; __device__ __forceinline__ void inproj_epilogue(const Params& p, int layer, int mt, int ntile, int tid,
;                                                 f32x16 (&acc)[2][2], unsigned char* smem) {
;     ...
;     acc_foreach(tid, acc, [&](int row, int col, float v) {
;       int t = m0 + row;
;       float o = v;
;       if (mode == 1) o = (t >= NPADR) ? v : 0.f;
;       if (mode == 2) o = sigmf(v);
;       sT[row * 136 + col] = f2bf(o);
;     });
.LBB0_603:
	v_bfe_u32 v49, v48, 16, 1
	v_add3_u32 v48, v48, v49, s78
	ds_write_b16_d16_hi v119, v48 offset:64
	s_nop 1

; __device__ __forceinline__ float sigmf(float x) { return 1.f / (1.f + __expf(-x)); }
; template <int MT, int NT, class F>
; __device__ __forceinline__ void acc_foreach(int tid, f32x16 (&acc)[MT][NT], F f) {
;     ...
;   for (int mt = 0; mt < MT; mt++)
; #pragma unroll
;     for (int nt = 0; nt < NT; nt++)
; #pragma unroll
;       for (int i = 0; i < 16; i++) {
;         int row = wm * (MT * 32) + mt * 32 + (i & 3) + 8 * (i >> 2) + 4 * hi;
;         int col = wn * (NT * 32) + nt * 32 + c;
;         f(row, col, acc[mt][nt][i]);
; __device__ __forceinline__ void inproj_epilogue(const Params& p, int layer, int mt, int ntile, int tid,
;                                                 f32x16 (&acc)[2][2], unsigned char* smem) {
;     ...
;     acc_foreach(tid, acc, [&](int row, int col, float v) {
;       int t = m0 + row;
;       float o = v;
;       if (mode == 1) o = (t >= NPADR) ? v : 0.f;
;       if (mode == 2) o = sigmf(v);
;       sT[row * 136 + col] = f2bf(o);
;     });
.LBB0_606:
	v_bfe_u32 v49, v48, 16, 1
	v_add3_u32 v48, v48, v49, s78
	ds_write_b16_d16_hi v120, v48 offset:64
	s_nop 1

; __device__ __forceinline__ float sigmf(float x) { return 1.f / (1.f + __expf(-x)); }
; template <int MT, int NT, class F>
; __device__ __forceinline__ void acc_foreach(int tid, f32x16 (&acc)[MT][NT], F f) {
;     ...
;   for (int mt = 0; mt < MT; mt++)
; #pragma unroll
;     for (int nt = 0; nt < NT; nt++)
; #pragma unroll
;       for (int i = 0; i < 16; i++) {
;         int row = wm * (MT * 32) + mt * 32 + (i & 3) + 8 * (i >> 2) + 4 * hi;
;         int col = wn * (NT * 32) + nt * 32 + c;
;         f(row, col, acc[mt][nt][i]);
; __device__ __forceinline__ void inproj_epilogue(const Params& p, int layer, int mt, int ntile, int tid,
;                                                 f32x16 (&acc)[2][2], unsigned char* smem) {
;     ...
;     acc_foreach(tid, acc, [&](int row, int col, float v) {
;       int t = m0 + row;
;       float o = v;
;       if (mode == 1) o = (t >= NPADR) ? v : 0.f;
;       if (mode == 2) o = sigmf(v);
;       sT[row * 136 + col] = f2bf(o);
;     });
.LBB0_609:
	v_bfe_u32 v49, v48, 16, 1
	v_add3_u32 v48, v48, v49, s78
	ds_write_b16_d16_hi v121, v48 offset:64
	s_nop 1

; __device__ __forceinline__ float sigmf(float x) { return 1.f / (1.f + __expf(-x)); }
; template <int MT, int NT, class F>
; __device__ __forceinline__ void acc_foreach(int tid, f32x16 (&acc)[MT][NT], F f) {
;     ...
;   for (int mt = 0; mt < MT; mt++)
; #pragma unroll
;     for (int nt = 0; nt < NT; nt++)
; #pragma unroll
;       for (int i = 0; i < 16; i++) {
;         int row = wm * (MT * 32) + mt * 32 + (i & 3) + 8 * (i >> 2) + 4 * hi;
;         int col = wn * (NT * 32) + nt * 32 + c;
;         f(row, col, acc[mt][nt][i]);
; __device__ __forceinline__ void inproj_epilogue(const Params& p, int layer, int mt, int ntile, int tid,
;                                                 f32x16 (&acc)[2][2], unsigned char* smem) {
;     ...
;     acc_foreach(tid, acc, [&](int row, int col, float v) {
;       int t = m0 + row;
;       float o = v;
;       if (mode == 1) o = (t >= NPADR) ? v : 0.f;
;       if (mode == 2) o = sigmf(v);
;       sT[row * 136 + col] = f2bf(o);
;     });
.LBB0_612:
	v_bfe_u32 v49, v48, 16, 1
	v_add3_u32 v48, v48, v49, s78
	ds_write_b16_d16_hi v122, v48 offset:64
	s_nop 1

; __device__ __forceinline__ float sigmf(float x) { return 1.f / (1.f + __expf(-x)); }
; template <int MT, int NT, class F>
; __device__ __forceinline__ void acc_foreach(int tid, f32x16 (&acc)[MT][NT], F f) {
;     ...
;   for (int mt = 0; mt < MT; mt++)
; #pragma unroll
;     for (int nt = 0; nt < NT; nt++)
; #pragma unroll
;       for (int i = 0; i < 16; i++) {
;         int row = wm * (MT * 32) + mt * 32 + (i & 3) + 8 * (i >> 2) + 4 * hi;
;         int col = wn * (NT * 32) + nt * 32 + c;
;         f(row, col, acc[mt][nt][i]);
; __device__ __forceinline__ void inproj_epilogue(const Params& p, int layer, int mt, int ntile, int tid,
;                                                 f32x16 (&acc)[2][2], unsigned char* smem) {
;     ...
;     acc_foreach(tid, acc, [&](int row, int col, float v) {
;       int t = m0 + row;
;       float o = v;
;       if (mode == 1) o = (t >= NPADR) ? v : 0.f;
;       if (mode == 2) o = sigmf(v);
;       sT[row * 136 + col] = f2bf(o);
;     });
.LBB0_615:
	v_bfe_u32 v49, v48, 16, 1
	v_add3_u32 v48, v48, v49, s78
	ds_write_b16_d16_hi v123, v48 offset:64
	s_nop 1

; __device__ __forceinline__ float sigmf(float x) { return 1.f / (1.f + __expf(-x)); }
; template <int MT, int NT, class F>
; __device__ __forceinline__ void acc_foreach(int tid, f32x16 (&acc)[MT][NT], F f) {
;     ...
;   for (int mt = 0; mt < MT; mt++)
; #pragma unroll
;     for (int nt = 0; nt < NT; nt++)
; #pragma unroll
;       for (int i = 0; i < 16; i++) {
;         int row = wm * (MT * 32) + mt * 32 + (i & 3) + 8 * (i >> 2) + 4 * hi;
;         int col = wn * (NT * 32) + nt * 32 + c;
;         f(row, col, acc[mt][nt][i]);
; __device__ __forceinline__ void inproj_epilogue(const Params& p, int layer, int mt, int ntile, int tid,
;                                                 f32x16 (&acc)[2][2], unsigned char* smem) {
;     ...
;     acc_foreach(tid, acc, [&](int row, int col, float v) {
;       int t = m0 + row;
;       float o = v;
;       if (mode == 1) o = (t >= NPADR) ? v : 0.f;
;       if (mode == 2) o = sigmf(v);
;       sT[row * 136 + col] = f2bf(o);
;     });
.LBB0_618:
	v_bfe_u32 v49, v48, 16, 1
	v_add3_u32 v48, v48, v49, s78
	ds_write_b16_d16_hi v116, v48 offset:64
	s_nop 1

; __device__ __forceinline__ float sigmf(float x) { return 1.f / (1.f + __expf(-x)); }
; template <int MT, int NT, class F>
; __device__ __forceinline__ void acc_foreach(int tid, f32x16 (&acc)[MT][NT], F f) {
;     ...
;   for (int mt = 0; mt < MT; mt++)
; #pragma unroll
;     for (int nt = 0; nt < NT; nt++)
; #pragma unroll
;       for (int i = 0; i < 16; i++) {
;         int row = wm * (MT * 32) + mt * 32 + (i & 3) + 8 * (i >> 2) + 4 * hi;
;         int col = wn * (NT * 32) + nt * 32 + c;
;         f(row, col, acc[mt][nt][i]);
; __device__ __forceinline__ void inproj_epilogue(const Params& p, int layer, int mt, int ntile, int tid,
;                                                 f32x16 (&acc)[2][2], unsigned char* smem) {
;     ...
;     acc_foreach(tid, acc, [&](int row, int col, float v) {
;       int t = m0 + row;
;       float o = v;
;       if (mode == 1) o = (t >= NPADR) ? v : 0.f;
;       if (mode == 2) o = sigmf(v);
;       sT[row * 136 + col] = f2bf(o);
;     });
.LBB0_621:
	v_bfe_u32 v50, v48, 16, 1
	v_add_u32_e32 v49, 0x110, v116
	v_add3_u32 v48, v48, v50, s78
	ds_write_b16_d16_hi v49, v48 offset:64
	v_or_b32_e32 v48, 32, v96
	v_add_u32_e32 v49, s90, v48
	v_cmp_lt_i32_e64 s[8:9], s76, v49
	s_nop 1

; __device__ __forceinline__ float sigmf(float x) { return 1.f / (1.f + __expf(-x)); }
; template <int MT, int NT, class F>
; __device__ __forceinline__ void acc_foreach(int tid, f32x16 (&acc)[MT][NT], F f) {
;     ...
;   for (int mt = 0; mt < MT; mt++)
; #pragma unroll
;     for (int nt = 0; nt < NT; nt++)
; #pragma unroll
;       for (int i = 0; i < 16; i++) {
;         int row = wm * (MT * 32) + mt * 32 + (i & 3) + 8 * (i >> 2) + 4 * hi;
;         int col = wn * (NT * 32) + nt * 32 + c;
;         f(row, col, acc[mt][nt][i]);
; __device__ __forceinline__ void inproj_epilogue(const Params& p, int layer, int mt, int ntile, int tid,
;                                                 f32x16 (&acc)[2][2], unsigned char* smem) {
;     ...
;     acc_foreach(tid, acc, [&](int row, int col, float v) {
;       int t = m0 + row;
;       float o = v;
;       if (mode == 1) o = (t >= NPADR) ? v : 0.f;
;       if (mode == 2) o = sigmf(v);
;       sT[row * 136 + col] = f2bf(o);
;     });
.LBB0_624:
	v_bfe_u32 v50, v49, 16, 1
	v_add3_u32 v50, v49, v50, s78
	v_mul_lo_u32 v49, v48, s79
	v_lshl_add_u32 v48, v106, 1, v49
	ds_write_b16_d16_hi v48, v50
	v_add3_u32 v50, s90, v96, 33
	v_cmp_lt_i32_e64 s[10:11], s76, v50
	s_nop 1

; __device__ __forceinline__ float sigmf(float x) { return 1.f / (1.f + __expf(-x)); }
; template <int MT, int NT, class F>
; __device__ __forceinline__ void acc_foreach(int tid, f32x16 (&acc)[MT][NT], F f) {
;     ...
;   for (int mt = 0; mt < MT; mt++)
; #pragma unroll
;     for (int nt = 0; nt < NT; nt++)
; #pragma unroll
;       for (int i = 0; i < 16; i++) {
;         int row = wm * (MT * 32) + mt * 32 + (i & 3) + 8 * (i >> 2) + 4 * hi;
;         int col = wn * (NT * 32) + nt * 32 + c;
;         f(row, col, acc[mt][nt][i]);
; __device__ __forceinline__ void inproj_epilogue(const Params& p, int layer, int mt, int ntile, int tid,
;                                                 f32x16 (&acc)[2][2], unsigned char* smem) {
;     ...
;     acc_foreach(tid, acc, [&](int row, int col, float v) {
;       int t = m0 + row;
;       float o = v;
;       if (mode == 1) o = (t >= NPADR) ? v : 0.f;
;       if (mode == 2) o = sigmf(v);
;       sT[row * 136 + col] = f2bf(o);
;     });
.LBB0_627:
	v_bfe_u32 v51, v50, 16, 1
	v_add3_u32 v51, v50, v51, s78
	v_add_u32_e32 v50, 0x110, v49
	v_lshl_add_u32 v49, v106, 1, v50
	ds_write_b16_d16_hi v49, v51
	v_add3_u32 v51, s90, v96, 34
	v_cmp_lt_i32_e64 s[12:13], s76, v51
	s_nop 1

; __device__ __forceinline__ float sigmf(float x) { return 1.f / (1.f + __expf(-x)); }
; template <int MT, int NT, class F>
; __device__ __forceinline__ void acc_foreach(int tid, f32x16 (&acc)[MT][NT], F f) {
;     ...
;   for (int mt = 0; mt < MT; mt++)
; #pragma unroll
;     for (int nt = 0; nt < NT; nt++)
; #pragma unroll
;       for (int i = 0; i < 16; i++) {
;         int row = wm * (MT * 32) + mt * 32 + (i & 3) + 8 * (i >> 2) + 4 * hi;
;         int col = wn * (NT * 32) + nt * 32 + c;
;         f(row, col, acc[mt][nt][i]);
; __device__ __forceinline__ void inproj_epilogue(const Params& p, int layer, int mt, int ntile, int tid,
;                                                 f32x16 (&acc)[2][2], unsigned char* smem) {
;     ...
;     acc_foreach(tid, acc, [&](int row, int col, float v) {
;       int t = m0 + row;
;       float o = v;
;       if (mode == 1) o = (t >= NPADR) ? v : 0.f;
;       if (mode == 2) o = sigmf(v);
;       sT[row * 136 + col] = f2bf(o);
;     });
.LBB0_630:
	v_bfe_u32 v52, v51, 16, 1
	v_add3_u32 v52, v51, v52, s78
	v_add_u32_e32 v51, 0x110, v50
	v_lshl_add_u32 v50, v106, 1, v51
	ds_write_b16_d16_hi v50, v52
	v_add3_u32 v52, s90, v96, 35
	v_cmp_lt_i32_e64 s[14:15], s76, v52
	s_nop 1

; __device__ __forceinline__ float sigmf(float x) { return 1.f / (1.f + __expf(-x)); }
; template <int MT, int NT, class F>
; __device__ __forceinline__ void acc_foreach(int tid, f32x16 (&acc)[MT][NT], F f) {
;     ...
;   for (int mt = 0; mt < MT; mt++)
; #pragma unroll
;     for (int nt = 0; nt < NT; nt++)
; #pragma unroll
;       for (int i = 0; i < 16; i++) {
;         int row = wm * (MT * 32) + mt * 32 + (i & 3) + 8 * (i >> 2) + 4 * hi;
;         int col = wn * (NT * 32) + nt * 32 + c;
;         f(row, col, acc[mt][nt][i]);
; __device__ __forceinline__ void inproj_epilogue(const Params& p, int layer, int mt, int ntile, int tid,
;                                                 f32x16 (&acc)[2][2], unsigned char* smem) {
;     ...
;     acc_foreach(tid, acc, [&](int row, int col, float v) {
;       int t = m0 + row;
;       float o = v;
;       if (mode == 1) o = (t >= NPADR) ? v : 0.f;
;       if (mode == 2) o = sigmf(v);
;       sT[row * 136 + col] = f2bf(o);
;     });
.LBB0_633:
	v_bfe_u32 v53, v52, 16, 1
	v_add3_u32 v53, v52, v53, s78
	v_add_u32_e32 v52, 0x110, v51
	v_lshl_add_u32 v51, v106, 1, v52
	ds_write_b16_d16_hi v51, v53
	v_add3_u32 v53, s90, v96, 40
	v_cmp_lt_i32_e64 s[16:17], s76, v53
	s_nop 1

; __device__ __forceinline__ float sigmf(float x) { return 1.f / (1.f + __expf(-x)); }
; template <int MT, int NT, class F>
; __device__ __forceinline__ void acc_foreach(int tid, f32x16 (&acc)[MT][NT], F f) {
;     ...
;   for (int mt = 0; mt < MT; mt++)
; #pragma unroll
;     for (int nt = 0; nt < NT; nt++)
; #pragma unroll
;       for (int i = 0; i < 16; i++) {
;         int row = wm * (MT * 32) + mt * 32 + (i & 3) + 8 * (i >> 2) + 4 * hi;
;         int col = wn * (NT * 32) + nt * 32 + c;
;         f(row, col, acc[mt][nt][i]);
; __device__ __forceinline__ void inproj_epilogue(const Params& p, int layer, int mt, int ntile, int tid,
;                                                 f32x16 (&acc)[2][2], unsigned char* smem) {
;     ...
;     acc_foreach(tid, acc, [&](int row, int col, float v) {
;       int t = m0 + row;
;       float o = v;
;       if (mode == 1) o = (t >= NPADR) ? v : 0.f;
;       if (mode == 2) o = sigmf(v);
;       sT[row * 136 + col] = f2bf(o);
;     });
.LBB0_636:
	v_bfe_u32 v54, v53, 16, 1
	v_add3_u32 v54, v53, v54, s78
	v_add_u32_e32 v53, 0x550, v52
	v_lshl_add_u32 v52, v106, 1, v53
	ds_write_b16_d16_hi v52, v54
	v_add3_u32 v54, s90, v96, 41
	v_cmp_lt_i32_e64 s[18:19], s76, v54
	s_nop 1

; __device__ __forceinline__ float sigmf(float x) { return 1.f / (1.f + __expf(-x)); }
; template <int MT, int NT, class F>
; __device__ __forceinline__ void acc_foreach(int tid, f32x16 (&acc)[MT][NT], F f) {
;     ...
;   for (int mt = 0; mt < MT; mt++)
; #pragma unroll
;     for (int nt = 0; nt < NT; nt++)
; #pragma unroll
;       for (int i = 0; i < 16; i++) {
;         int row = wm * (MT * 32) + mt * 32 + (i & 3) + 8 * (i >> 2) + 4 * hi;
;         int col = wn * (NT * 32) + nt * 32 + c;
;         f(row, col, acc[mt][nt][i]);
; __device__ __forceinline__ void inproj_epilogue(const Params& p, int layer, int mt, int ntile, int tid,
;                                                 f32x16 (&acc)[2][2], unsigned char* smem) {
;     ...
;     acc_foreach(tid, acc, [&](int row, int col, float v) {
;       int t = m0 + row;
;       float o = v;
;       if (mode == 1) o = (t >= NPADR) ? v : 0.f;
;       if (mode == 2) o = sigmf(v);
;       sT[row * 136 + col] = f2bf(o);
;     });
.LBB0_639:
	v_bfe_u32 v55, v54, 16, 1
	v_add3_u32 v55, v54, v55, s78
	v_add_u32_e32 v54, 0x110, v53
	v_lshl_add_u32 v53, v106, 1, v54
	ds_write_b16_d16_hi v53, v55
	v_add3_u32 v55, s90, v96, 42
	v_cmp_lt_i32_e64 s[20:21], s76, v55
	s_nop 1

; __device__ __forceinline__ float sigmf(float x) { return 1.f / (1.f + __expf(-x)); }
; template <int MT, int NT, class F>
; __device__ __forceinline__ void acc_foreach(int tid, f32x16 (&acc)[MT][NT], F f) {
;     ...
;   for (int mt = 0; mt < MT; mt++)
; #pragma unroll
;     for (int nt = 0; nt < NT; nt++)
; #pragma unroll
;       for (int i = 0; i < 16; i++) {
;         int row = wm * (MT * 32) + mt * 32 + (i & 3) + 8 * (i >> 2) + 4 * hi;
;         int col = wn * (NT * 32) + nt * 32 + c;
;         f(row, col, acc[mt][nt][i]);
; __device__ __forceinline__ void inproj_epilogue(const Params& p, int layer, int mt, int ntile, int tid,
;                                                 f32x16 (&acc)[2][2], unsigned char* smem) {
;     ...
;     acc_foreach(tid, acc, [&](int row, int col, float v) {
;       int t = m0 + row;
;       float o = v;
;       if (mode == 1) o = (t >= NPADR) ? v : 0.f;
;       if (mode == 2) o = sigmf(v);
;       sT[row * 136 + col] = f2bf(o);
;     });
.LBB0_642:
	v_bfe_u32 v56, v55, 16, 1
	v_add3_u32 v56, v55, v56, s78
	v_add_u32_e32 v55, 0x110, v54
	v_lshl_add_u32 v54, v106, 1, v55
	ds_write_b16_d16_hi v54, v56
	v_add3_u32 v56, s90, v96, 43
	v_cmp_lt_i32_e64 s[22:23], s76, v56
	s_nop 1

; __device__ __forceinline__ float sigmf(float x) { return 1.f / (1.f + __expf(-x)); }
; template <int MT, int NT, class F>
; __device__ __forceinline__ void acc_foreach(int tid, f32x16 (&acc)[MT][NT], F f) {
;     ...
;   for (int mt = 0; mt < MT; mt++)
; #pragma unroll
;     for (int nt = 0; nt < NT; nt++)
; #pragma unroll
;       for (int i = 0; i < 16; i++) {
;         int row = wm * (MT * 32) + mt * 32 + (i & 3) + 8 * (i >> 2) + 4 * hi;
;         int col = wn * (NT * 32) + nt * 32 + c;
;         f(row, col, acc[mt][nt][i]);
; __device__ __forceinline__ void inproj_epilogue(const Params& p, int layer, int mt, int ntile, int tid,
;                                                 f32x16 (&acc)[2][2], unsigned char* smem) {
;     ...
;     acc_foreach(tid, acc, [&](int row, int col, float v) {
;       int t = m0 + row;
;       float o = v;
;       if (mode == 1) o = (t >= NPADR) ? v : 0.f;
;       if (mode == 2) o = sigmf(v);
;       sT[row * 136 + col] = f2bf(o);
;     });
.LBB0_645:
	v_bfe_u32 v57, v56, 16, 1
	v_add_u32_e32 v55, 0x110, v55
	v_add3_u32 v57, v56, v57, s78
	v_lshl_add_u32 v56, v106, 1, v55
	ds_write_b16_d16_hi v56, v57
	v_add3_u32 v57, s90, v96, 48
	v_cmp_lt_i32_e64 s[24:25], s76, v57
	s_nop 1

; __device__ __forceinline__ float sigmf(float x) { return 1.f / (1.f + __expf(-x)); }
; template <int MT, int NT, class F>
; __device__ __forceinline__ void acc_foreach(int tid, f32x16 (&acc)[MT][NT], F f) {
;     ...
;   for (int mt = 0; mt < MT; mt++)
; #pragma unroll
;     for (int nt = 0; nt < NT; nt++)
; #pragma unroll
;       for (int i = 0; i < 16; i++) {
;         int row = wm * (MT * 32) + mt * 32 + (i & 3) + 8 * (i >> 2) + 4 * hi;
;         int col = wn * (NT * 32) + nt * 32 + c;
;         f(row, col, acc[mt][nt][i]);
; __device__ __forceinline__ void inproj_epilogue(const Params& p, int layer, int mt, int ntile, int tid,
;                                                 f32x16 (&acc)[2][2], unsigned char* smem) {
;     ...
;     acc_foreach(tid, acc, [&](int row, int col, float v) {
;       int t = m0 + row;
;       float o = v;
;       if (mode == 1) o = (t >= NPADR) ? v : 0.f;
;       if (mode == 2) o = sigmf(v);
;       sT[row * 136 + col] = f2bf(o);
;     });
.LBB0_648:
	v_bfe_u32 v58, v57, 16, 1
	v_add_u32_e32 v55, 0x550, v55
	v_add3_u32 v58, v57, v58, s78
	v_lshl_add_u32 v57, v106, 1, v55
	ds_write_b16_d16_hi v57, v58
	v_add3_u32 v58, s90, v96, 49
	v_cmp_lt_i32_e64 s[26:27], s76, v58
	s_nop 1

; __device__ __forceinline__ float sigmf(float x) { return 1.f / (1.f + __expf(-x)); }
; template <int MT, int NT, class F>
; __device__ __forceinline__ void acc_foreach(int tid, f32x16 (&acc)[MT][NT], F f) {
;     ...
;   for (int mt = 0; mt < MT; mt++)
; #pragma unroll
;     for (int nt = 0; nt < NT; nt++)
; #pragma unroll
;       for (int i = 0; i < 16; i++) {
;         int row = wm * (MT * 32) + mt * 32 + (i & 3) + 8 * (i >> 2) + 4 * hi;
;         int col = wn * (NT * 32) + nt * 32 + c;
;         f(row, col, acc[mt][nt][i]);
; __device__ __forceinline__ void inproj_epilogue(const Params& p, int layer, int mt, int ntile, int tid,
;                                                 f32x16 (&acc)[2][2], unsigned char* smem) {
;     ...
;     acc_foreach(tid, acc, [&](int row, int col, float v) {
;       int t = m0 + row;
;       float o = v;
;       if (mode == 1) o = (t >= NPADR) ? v : 0.f;
;       if (mode == 2) o = sigmf(v);
;       sT[row * 136 + col] = f2bf(o);
;     });
.LBB0_651:
	v_bfe_u32 v59, v58, 16, 1
	v_add_u32_e32 v55, 0x110, v55
	v_add3_u32 v59, v58, v59, s78
	v_lshl_add_u32 v58, v106, 1, v55
	ds_write_b16_d16_hi v58, v59
	v_add3_u32 v59, s90, v96, 50
	v_cmp_lt_i32_e64 s[28:29], s76, v59
	s_nop 1

; __device__ __forceinline__ float sigmf(float x) { return 1.f / (1.f + __expf(-x)); }
; template <int MT, int NT, class F>
; __device__ __forceinline__ void acc_foreach(int tid, f32x16 (&acc)[MT][NT], F f) {
;     ...
;   for (int mt = 0; mt < MT; mt++)
; #pragma unroll
;     for (int nt = 0; nt < NT; nt++)
; #pragma unroll
;       for (int i = 0; i < 16; i++) {
;         int row = wm * (MT * 32) + mt * 32 + (i & 3) + 8 * (i >> 2) + 4 * hi;
;         int col = wn * (NT * 32) + nt * 32 + c;
;         f(row, col, acc[mt][nt][i]);
; __device__ __forceinline__ void inproj_epilogue(const Params& p, int layer, int mt, int ntile, int tid,
;                                                 f32x16 (&acc)[2][2], unsigned char* smem) {
;     ...
;     acc_foreach(tid, acc, [&](int row, int col, float v) {
;       int t = m0 + row;
;       float o = v;
;       if (mode == 1) o = (t >= NPADR) ? v : 0.f;
;       if (mode == 2) o = sigmf(v);
;       sT[row * 136 + col] = f2bf(o);
;     });
.LBB0_654:
	v_bfe_u32 v60, v59, 16, 1
	v_add_u32_e32 v55, 0x110, v55
	v_add3_u32 v60, v59, v60, s78
	v_lshl_add_u32 v59, v106, 1, v55
	ds_write_b16_d16_hi v59, v60
	v_add3_u32 v60, s90, v96, 51
	v_cmp_lt_i32_e64 s[30:31], s76, v60
	s_nop 1

; __device__ __forceinline__ float sigmf(float x) { return 1.f / (1.f + __expf(-x)); }
; template <int MT, int NT, class F>
; __device__ __forceinline__ void acc_foreach(int tid, f32x16 (&acc)[MT][NT], F f) {
;     ...
;   for (int mt = 0; mt < MT; mt++)
; #pragma unroll
;     for (int nt = 0; nt < NT; nt++)
; #pragma unroll
;       for (int i = 0; i < 16; i++) {
;         int row = wm * (MT * 32) + mt * 32 + (i & 3) + 8 * (i >> 2) + 4 * hi;
;         int col = wn * (NT * 32) + nt * 32 + c;
;         f(row, col, acc[mt][nt][i]);
; __device__ __forceinline__ void inproj_epilogue(const Params& p, int layer, int mt, int ntile, int tid,
;                                                 f32x16 (&acc)[2][2], unsigned char* smem) {
;     ...
;     acc_foreach(tid, acc, [&](int row, int col, float v) {
;       int t = m0 + row;
;       float o = v;
;       if (mode == 1) o = (t >= NPADR) ? v : 0.f;
;       if (mode == 2) o = sigmf(v);
;       sT[row * 136 + col] = f2bf(o);
;     });
.LBB0_657:
	v_bfe_u32 v61, v60, 16, 1
	v_add_u32_e32 v55, 0x110, v55
	v_add3_u32 v61, v60, v61, s78
	v_lshl_add_u32 v60, v106, 1, v55
	ds_write_b16_d16_hi v60, v61
	v_add3_u32 v61, s90, v96, 56
	v_cmp_lt_i32_e64 s[34:35], s76, v61
	s_nop 1

; __device__ __forceinline__ float sigmf(float x) { return 1.f / (1.f + __expf(-x)); }
; template <int MT, int NT, class F>
; __device__ __forceinline__ void acc_foreach(int tid, f32x16 (&acc)[MT][NT], F f) {
;     ...
;   for (int mt = 0; mt < MT; mt++)
; #pragma unroll
;     for (int nt = 0; nt < NT; nt++)
; #pragma unroll
;       for (int i = 0; i < 16; i++) {
;         int row = wm * (MT * 32) + mt * 32 + (i & 3) + 8 * (i >> 2) + 4 * hi;
;         int col = wn * (NT * 32) + nt * 32 + c;
;         f(row, col, acc[mt][nt][i]);
; __device__ __forceinline__ void inproj_epilogue(const Params& p, int layer, int mt, int ntile, int tid,
;                                                 f32x16 (&acc)[2][2], unsigned char* smem) {
;     ...
;     acc_foreach(tid, acc, [&](int row, int col, float v) {
;       int t = m0 + row;
;       float o = v;
;       if (mode == 1) o = (t >= NPADR) ? v : 0.f;
;       if (mode == 2) o = sigmf(v);
;       sT[row * 136 + col] = f2bf(o);
;     });
.LBB0_660:
	v_bfe_u32 v62, v61, 16, 1
	v_add_u32_e32 v55, 0x550, v55
	v_add3_u32 v62, v61, v62, s78
	v_lshl_add_u32 v61, v106, 1, v55
	ds_write_b16_d16_hi v61, v62
	v_add3_u32 v62, s90, v96, 57
	v_cmp_lt_i32_e64 s[36:37], s76, v62
	s_nop 1

; __device__ __forceinline__ float sigmf(float x) { return 1.f / (1.f + __expf(-x)); }
; template <int MT, int NT, class F>
; __device__ __forceinline__ void acc_foreach(int tid, f32x16 (&acc)[MT][NT], F f) {
;     ...
;   for (int mt = 0; mt < MT; mt++)
; #pragma unroll
;     for (int nt = 0; nt < NT; nt++)
; #pragma unroll
;       for (int i = 0; i < 16; i++) {
;         int row = wm * (MT * 32) + mt * 32 + (i & 3) + 8 * (i >> 2) + 4 * hi;
;         int col = wn * (NT * 32) + nt * 32 + c;
;         f(row, col, acc[mt][nt][i]);
; __device__ __forceinline__ void inproj_epilogue(const Params& p, int layer, int mt, int ntile, int tid,
;                                                 f32x16 (&acc)[2][2], unsigned char* smem) {
;     ...
;     acc_foreach(tid, acc, [&](int row, int col, float v) {
;       int t = m0 + row;
;       float o = v;
;       if (mode == 1) o = (t >= NPADR) ? v : 0.f;
;       if (mode == 2) o = sigmf(v);
;       sT[row * 136 + col] = f2bf(o);
;     });
.LBB0_663:
	v_bfe_u32 v63, v62, 16, 1
	v_add_u32_e32 v55, 0x110, v55
	v_add3_u32 v63, v62, v63, s78
	v_lshl_add_u32 v62, v106, 1, v55
	ds_write_b16_d16_hi v62, v63
	v_add3_u32 v63, s90, v96, 58
	v_cmp_lt_i32_e64 s[38:39], s76, v63
	s_nop 1

; __device__ __forceinline__ float sigmf(float x) { return 1.f / (1.f + __expf(-x)); }
; template <int MT, int NT, class F>
; __device__ __forceinline__ void acc_foreach(int tid, f32x16 (&acc)[MT][NT], F f) {
;     ...
;   for (int mt = 0; mt < MT; mt++)
; #pragma unroll
;     for (int nt = 0; nt < NT; nt++)
; #pragma unroll
;       for (int i = 0; i < 16; i++) {
;         int row = wm * (MT * 32) + mt * 32 + (i & 3) + 8 * (i >> 2) + 4 * hi;
;         int col = wn * (NT * 32) + nt * 32 + c;
;         f(row, col, acc[mt][nt][i]);
; __device__ __forceinline__ void inproj_epilogue(const Params& p, int layer, int mt, int ntile, int tid,
;                                                 f32x16 (&acc)[2][2], unsigned char* smem) {
;     ...
;     acc_foreach(tid, acc, [&](int row, int col, float v) {
;       int t = m0 + row;
;       float o = v;
;       if (mode == 1) o = (t >= NPADR) ? v : 0.f;
;       if (mode == 2) o = sigmf(v);
;       sT[row * 136 + col] = f2bf(o);
;     });
.LBB0_666:
	v_bfe_u32 v107, v63, 16, 1
	v_add_u32_e32 v55, 0x110, v55
	v_add3_u32 v63, v63, v107, s78
	v_lshl_add_u32 v55, v106, 1, v55
	ds_write_b16_d16_hi v55, v63
	v_add3_u32 v63, s90, v96, 59
	v_cmp_lt_i32_e64 s[40:41], s76, v63
	s_nop 1

; __device__ __forceinline__ float sigmf(float x) { return 1.f / (1.f + __expf(-x)); }
; template <int MT, int NT, class F>
; __device__ __forceinline__ void acc_foreach(int tid, f32x16 (&acc)[MT][NT], F f) {
;     ...
;   for (int mt = 0; mt < MT; mt++)
; #pragma unroll
;     for (int nt = 0; nt < NT; nt++)
; #pragma unroll
;       for (int i = 0; i < 16; i++) {
;         int row = wm * (MT * 32) + mt * 32 + (i & 3) + 8 * (i >> 2) + 4 * hi;
;         int col = wn * (NT * 32) + nt * 32 + c;
;         f(row, col, acc[mt][nt][i]);
; __device__ __forceinline__ void inproj_epilogue(const Params& p, int layer, int mt, int ntile, int tid,
;                                                 f32x16 (&acc)[2][2], unsigned char* smem) {
;     ...
;     acc_foreach(tid, acc, [&](int row, int col, float v) {
;       int t = m0 + row;
;       float o = v;
;       if (mode == 1) o = (t >= NPADR) ? v : 0.f;
;       if (mode == 2) o = sigmf(v);
;       sT[row * 136 + col] = f2bf(o);
;     });
.LBB0_669:
	v_bfe_u32 v96, v63, 16, 1
	v_add3_u32 v63, v63, v96, s78
	ds_write_b16_d16_hi v55, v63 offset:272
	s_nop 1

; __device__ __forceinline__ float sigmf(float x) { return 1.f / (1.f + __expf(-x)); }
; template <int MT, int NT, class F>
; __device__ __forceinline__ void acc_foreach(int tid, f32x16 (&acc)[MT][NT], F f) {
;     ...
;   for (int mt = 0; mt < MT; mt++)
; #pragma unroll
;     for (int nt = 0; nt < NT; nt++)
; #pragma unroll
;       for (int i = 0; i < 16; i++) {
;         int row = wm * (MT * 32) + mt * 32 + (i & 3) + 8 * (i >> 2) + 4 * hi;
;         int col = wn * (NT * 32) + nt * 32 + c;
;         f(row, col, acc[mt][nt][i]);
; __device__ __forceinline__ void inproj_epilogue(const Params& p, int layer, int mt, int ntile, int tid,
;                                                 f32x16 (&acc)[2][2], unsigned char* smem) {
;     ...
;     acc_foreach(tid, acc, [&](int row, int col, float v) {
;       int t = m0 + row;
;       float o = v;
;       if (mode == 1) o = (t >= NPADR) ? v : 0.f;
;       if (mode == 2) o = sigmf(v);
;       sT[row * 136 + col] = f2bf(o);
;     });
.LBB0_672:
	v_bfe_u32 v63, v32, 16, 1
	v_add3_u32 v32, v32, v63, s78
	ds_write_b16_d16_hi v48, v32 offset:64
	s_nop 1

; __device__ __forceinline__ float sigmf(float x) { return 1.f / (1.f + __expf(-x)); }
; template <int MT, int NT, class F>
; __device__ __forceinline__ void acc_foreach(int tid, f32x16 (&acc)[MT][NT], F f) {
;     ...
;   for (int mt = 0; mt < MT; mt++)
; #pragma unroll
;     for (int nt = 0; nt < NT; nt++)
; #pragma unroll
;       for (int i = 0; i < 16; i++) {
;         int row = wm * (MT * 32) + mt * 32 + (i & 3) + 8 * (i >> 2) + 4 * hi;
;         int col = wn * (NT * 32) + nt * 32 + c;
;         f(row, col, acc[mt][nt][i]);
; __device__ __forceinline__ void inproj_epilogue(const Params& p, int layer, int mt, int ntile, int tid,
;                                                 f32x16 (&acc)[2][2], unsigned char* smem) {
;     ...
;     acc_foreach(tid, acc, [&](int row, int col, float v) {
;       int t = m0 + row;
;       float o = v;
;       if (mode == 1) o = (t >= NPADR) ? v : 0.f;
;       if (mode == 2) o = sigmf(v);
;       sT[row * 136 + col] = f2bf(o);
;     });
.LBB0_675:
	v_bfe_u32 v33, v32, 16, 1
	v_add3_u32 v32, v32, v33, s78
	ds_write_b16_d16_hi v49, v32 offset:64
	s_nop 1

; __device__ __forceinline__ float sigmf(float x) { return 1.f / (1.f + __expf(-x)); }
; template <int MT, int NT, class F>
; __device__ __forceinline__ void acc_foreach(int tid, f32x16 (&acc)[MT][NT], F f) {
;     ...
;   for (int mt = 0; mt < MT; mt++)
; #pragma unroll
;     for (int nt = 0; nt < NT; nt++)
; #pragma unroll
;       for (int i = 0; i < 16; i++) {
;         int row = wm * (MT * 32) + mt * 32 + (i & 3) + 8 * (i >> 2) + 4 * hi;
;         int col = wn * (NT * 32) + nt * 32 + c;
;         f(row, col, acc[mt][nt][i]);
; __device__ __forceinline__ void inproj_epilogue(const Params& p, int layer, int mt, int ntile, int tid,
;                                                 f32x16 (&acc)[2][2], unsigned char* smem) {
;     ...
;     acc_foreach(tid, acc, [&](int row, int col, float v) {
;       int t = m0 + row;
;       float o = v;
;       if (mode == 1) o = (t >= NPADR) ? v : 0.f;
;       if (mode == 2) o = sigmf(v);
;       sT[row * 136 + col] = f2bf(o);
;     });
.LBB0_678:
	v_bfe_u32 v33, v32, 16, 1
	v_add3_u32 v32, v32, v33, s78
	ds_write_b16_d16_hi v50, v32 offset:64
	s_nop 1

; __device__ __forceinline__ float sigmf(float x) { return 1.f / (1.f + __expf(-x)); }
; template <int MT, int NT, class F>
; __device__ __forceinline__ void acc_foreach(int tid, f32x16 (&acc)[MT][NT], F f) {
;     ...
;   for (int mt = 0; mt < MT; mt++)
; #pragma unroll
;     for (int nt = 0; nt < NT; nt++)
; #pragma unroll
;       for (int i = 0; i < 16; i++) {
;         int row = wm * (MT * 32) + mt * 32 + (i & 3) + 8 * (i >> 2) + 4 * hi;
;         int col = wn * (NT * 32) + nt * 32 + c;
;         f(row, col, acc[mt][nt][i]);
; __device__ __forceinline__ void inproj_epilogue(const Params& p, int layer, int mt, int ntile, int tid,
;                                                 f32x16 (&acc)[2][2], unsigned char* smem) {
;     ...
;     acc_foreach(tid, acc, [&](int row, int col, float v) {
;       int t = m0 + row;
;       float o = v;
;       if (mode == 1) o = (t >= NPADR) ? v : 0.f;
;       if (mode == 2) o = sigmf(v);
;       sT[row * 136 + col] = f2bf(o);
;     });
.LBB0_681:
	v_bfe_u32 v33, v32, 16, 1
	v_add3_u32 v32, v32, v33, s78
	ds_write_b16_d16_hi v51, v32 offset:64
	s_nop 1

; __device__ __forceinline__ float sigmf(float x) { return 1.f / (1.f + __expf(-x)); }
; template <int MT, int NT, class F>
; __device__ __forceinline__ void acc_foreach(int tid, f32x16 (&acc)[MT][NT], F f) {
;     ...
;   for (int mt = 0; mt < MT; mt++)
; #pragma unroll
;     for (int nt = 0; nt < NT; nt++)
; #pragma unroll
;       for (int i = 0; i < 16; i++) {
;         int row = wm * (MT * 32) + mt * 32 + (i & 3) + 8 * (i >> 2) + 4 * hi;
;         int col = wn * (NT * 32) + nt * 32 + c;
;         f(row, col, acc[mt][nt][i]);
; __device__ __forceinline__ void inproj_epilogue(const Params& p, int layer, int mt, int ntile, int tid,
;                                                 f32x16 (&acc)[2][2], unsigned char* smem) {
;     ...
;     acc_foreach(tid, acc, [&](int row, int col, float v) {
;       int t = m0 + row;
;       float o = v;
;       if (mode == 1) o = (t >= NPADR) ? v : 0.f;
;       if (mode == 2) o = sigmf(v);
;       sT[row * 136 + col] = f2bf(o);
;     });
.LBB0_684:
	v_bfe_u32 v33, v32, 16, 1
	v_add3_u32 v32, v32, v33, s78
	ds_write_b16_d16_hi v52, v32 offset:64
	s_nop 1

; __device__ __forceinline__ float sigmf(float x) { return 1.f / (1.f + __expf(-x)); }
; template <int MT, int NT, class F>
; __device__ __forceinline__ void acc_foreach(int tid, f32x16 (&acc)[MT][NT], F f) {
;     ...
;   for (int mt = 0; mt < MT; mt++)
; #pragma unroll
;     for (int nt = 0; nt < NT; nt++)
; #pragma unroll
;       for (int i = 0; i < 16; i++) {
;         int row = wm * (MT * 32) + mt * 32 + (i & 3) + 8 * (i >> 2) + 4 * hi;
;         int col = wn * (NT * 32) + nt * 32 + c;
;         f(row, col, acc[mt][nt][i]);
; __device__ __forceinline__ void inproj_epilogue(const Params& p, int layer, int mt, int ntile, int tid,
;                                                 f32x16 (&acc)[2][2], unsigned char* smem) {
;     ...
;     acc_foreach(tid, acc, [&](int row, int col, float v) {
;       int t = m0 + row;
;       float o = v;
;       if (mode == 1) o = (t >= NPADR) ? v : 0.f;
;       if (mode == 2) o = sigmf(v);
;       sT[row * 136 + col] = f2bf(o);
;     });
.LBB0_687:
	v_bfe_u32 v33, v32, 16, 1
	v_add3_u32 v32, v32, v33, s78
	ds_write_b16_d16_hi v53, v32 offset:64
	s_nop 1

; __device__ __forceinline__ float sigmf(float x) { return 1.f / (1.f + __expf(-x)); }
; template <int MT, int NT, class F>
; __device__ __forceinline__ void acc_foreach(int tid, f32x16 (&acc)[MT][NT], F f) {
;     ...
;   for (int mt = 0; mt < MT; mt++)
; #pragma unroll
;     for (int nt = 0; nt < NT; nt++)
; #pragma unroll
;       for (int i = 0; i < 16; i++) {
;         int row = wm * (MT * 32) + mt * 32 + (i & 3) + 8 * (i >> 2) + 4 * hi;
;         int col = wn * (NT * 32) + nt * 32 + c;
;         f(row, col, acc[mt][nt][i]);
; __device__ __forceinline__ void inproj_epilogue(const Params& p, int layer, int mt, int ntile, int tid,
;                                                 f32x16 (&acc)[2][2], unsigned char* smem) {
;     ...
;     acc_foreach(tid, acc, [&](int row, int col, float v) {
;       int t = m0 + row;
;       float o = v;
;       if (mode == 1) o = (t >= NPADR) ? v : 0.f;
;       if (mode == 2) o = sigmf(v);
;       sT[row * 136 + col] = f2bf(o);
;     });
.LBB0_690:
	v_bfe_u32 v33, v32, 16, 1
	v_add3_u32 v32, v32, v33, s78
	ds_write_b16_d16_hi v54, v32 offset:64
	s_nop 1

; __device__ __forceinline__ float sigmf(float x) { return 1.f / (1.f + __expf(-x)); }
; template <int MT, int NT, class F>
; __device__ __forceinline__ void acc_foreach(int tid, f32x16 (&acc)[MT][NT], F f) {
;     ...
;   for (int mt = 0; mt < MT; mt++)
; #pragma unroll
;     for (int nt = 0; nt < NT; nt++)
; #pragma unroll
;       for (int i = 0; i < 16; i++) {
;         int row = wm * (MT * 32) + mt * 32 + (i & 3) + 8 * (i >> 2) + 4 * hi;
;         int col = wn * (NT * 32) + nt * 32 + c;
;         f(row, col, acc[mt][nt][i]);
; __device__ __forceinline__ void inproj_epilogue(const Params& p, int layer, int mt, int ntile, int tid,
;                                                 f32x16 (&acc)[2][2], unsigned char* smem) {
;     ...
;     acc_foreach(tid, acc, [&](int row, int col, float v) {
;       int t = m0 + row;
;       float o = v;
;       if (mode == 1) o = (t >= NPADR) ? v : 0.f;
;       if (mode == 2) o = sigmf(v);
;       sT[row * 136 + col] = f2bf(o);
;     });
.LBB0_693:
	v_bfe_u32 v33, v32, 16, 1
	v_add3_u32 v32, v32, v33, s78
	ds_write_b16_d16_hi v56, v32 offset:64
	s_nop 1

; __device__ __forceinline__ float sigmf(float x) { return 1.f / (1.f + __expf(-x)); }
; template <int MT, int NT, class F>
; __device__ __forceinline__ void acc_foreach(int tid, f32x16 (&acc)[MT][NT], F f) {
;     ...
;   for (int mt = 0; mt < MT; mt++)
; #pragma unroll
;     for (int nt = 0; nt < NT; nt++)
; #pragma unroll
;       for (int i = 0; i < 16; i++) {
;         int row = wm * (MT * 32) + mt * 32 + (i & 3) + 8 * (i >> 2) + 4 * hi;
;         int col = wn * (NT * 32) + nt * 32 + c;
;         f(row, col, acc[mt][nt][i]);
; __device__ __forceinline__ void inproj_epilogue(const Params& p, int layer, int mt, int ntile, int tid,
;                                                 f32x16 (&acc)[2][2], unsigned char* smem) {
;     ...
;     acc_foreach(tid, acc, [&](int row, int col, float v) {
;       int t = m0 + row;
;       float o = v;
;       if (mode == 1) o = (t >= NPADR) ? v : 0.f;
;       if (mode == 2) o = sigmf(v);
;       sT[row * 136 + col] = f2bf(o);
;     });
.LBB0_696:
	v_bfe_u32 v33, v32, 16, 1
	v_add3_u32 v32, v32, v33, s78
	ds_write_b16_d16_hi v57, v32 offset:64
	s_nop 1

; __device__ __forceinline__ float sigmf(float x) { return 1.f / (1.f + __expf(-x)); }
; template <int MT, int NT, class F>
; __device__ __forceinline__ void acc_foreach(int tid, f32x16 (&acc)[MT][NT], F f) {
;     ...
;   for (int mt = 0; mt < MT; mt++)
; #pragma unroll
;     for (int nt = 0; nt < NT; nt++)
; #pragma unroll
;       for (int i = 0; i < 16; i++) {
;         int row = wm * (MT * 32) + mt * 32 + (i & 3) + 8 * (i >> 2) + 4 * hi;
;         int col = wn * (NT * 32) + nt * 32 + c;
;         f(row, col, acc[mt][nt][i]);
; __device__ __forceinline__ void inproj_epilogue(const Params& p, int layer, int mt, int ntile, int tid,
;                                                 f32x16 (&acc)[2][2], unsigned char* smem) {
;     ...
;     acc_foreach(tid, acc, [&](int row, int col, float v) {
;       int t = m0 + row;
;       float o = v;
;       if (mode == 1) o = (t >= NPADR) ? v : 0.f;
;       if (mode == 2) o = sigmf(v);
;       sT[row * 136 + col] = f2bf(o);
;     });
.LBB0_699:
	v_bfe_u32 v33, v32, 16, 1
	v_add3_u32 v32, v32, v33, s78
	ds_write_b16_d16_hi v58, v32 offset:64
	s_nop 1

; __device__ __forceinline__ float sigmf(float x) { return 1.f / (1.f + __expf(-x)); }
; template <int MT, int NT, class F>
; __device__ __forceinline__ void acc_foreach(int tid, f32x16 (&acc)[MT][NT], F f) {
;     ...
;   for (int mt = 0; mt < MT; mt++)
; #pragma unroll
;     for (int nt = 0; nt < NT; nt++)
; #pragma unroll
;       for (int i = 0; i < 16; i++) {
;         int row = wm * (MT * 32) + mt * 32 + (i & 3) + 8 * (i >> 2) + 4 * hi;
;         int col = wn * (NT * 32) + nt * 32 + c;
;         f(row, col, acc[mt][nt][i]);
; __device__ __forceinline__ void inproj_epilogue(const Params& p, int layer, int mt, int ntile, int tid,
;                                                 f32x16 (&acc)[2][2], unsigned char* smem) {
;     ...
;     acc_foreach(tid, acc, [&](int row, int col, float v) {
;       int t = m0 + row;
;       float o = v;
;       if (mode == 1) o = (t >= NPADR) ? v : 0.f;
;       if (mode == 2) o = sigmf(v);
;       sT[row * 136 + col] = f2bf(o);
;     });
.LBB0_702:
	v_bfe_u32 v33, v32, 16, 1
	v_add3_u32 v32, v32, v33, s78
	ds_write_b16_d16_hi v59, v32 offset:64
	s_nop 1

; __device__ __forceinline__ float sigmf(float x) { return 1.f / (1.f + __expf(-x)); }
; template <int MT, int NT, class F>
; __device__ __forceinline__ void acc_foreach(int tid, f32x16 (&acc)[MT][NT], F f) {
;     ...
;   for (int mt = 0; mt < MT; mt++)
; #pragma unroll
;     for (int nt = 0; nt < NT; nt++)
; #pragma unroll
;       for (int i = 0; i < 16; i++) {
;         int row = wm * (MT * 32) + mt * 32 + (i & 3) + 8 * (i >> 2) + 4 * hi;
;         int col = wn * (NT * 32) + nt * 32 + c;
;         f(row, col, acc[mt][nt][i]);
; __device__ __forceinline__ void inproj_epilogue(const Params& p, int layer, int mt, int ntile, int tid,
;                                                 f32x16 (&acc)[2][2], unsigned char* smem) {
;     ...
;     acc_foreach(tid, acc, [&](int row, int col, float v) {
;       int t = m0 + row;
;       float o = v;
;       if (mode == 1) o = (t >= NPADR) ? v : 0.f;
;       if (mode == 2) o = sigmf(v);
;       sT[row * 136 + col] = f2bf(o);
;     });
.LBB0_705:
	v_bfe_u32 v33, v32, 16, 1
	v_add3_u32 v32, v32, v33, s78
	ds_write_b16_d16_hi v60, v32 offset:64
	s_nop 1

; __device__ __forceinline__ float sigmf(float x) { return 1.f / (1.f + __expf(-x)); }
; template <int MT, int NT, class F>
; __device__ __forceinline__ void acc_foreach(int tid, f32x16 (&acc)[MT][NT], F f) {
;     ...
;   for (int mt = 0; mt < MT; mt++)
; #pragma unroll
;     for (int nt = 0; nt < NT; nt++)
; #pragma unroll
;       for (int i = 0; i < 16; i++) {
;         int row = wm * (MT * 32) + mt * 32 + (i & 3) + 8 * (i >> 2) + 4 * hi;
;         int col = wn * (NT * 32) + nt * 32 + c;
;         f(row, col, acc[mt][nt][i]);
; __device__ __forceinline__ void inproj_epilogue(const Params& p, int layer, int mt, int ntile, int tid,
;                                                 f32x16 (&acc)[2][2], unsigned char* smem) {
;     ...
;     acc_foreach(tid, acc, [&](int row, int col, float v) {
;       int t = m0 + row;
;       float o = v;
;       if (mode == 1) o = (t >= NPADR) ? v : 0.f;
;       if (mode == 2) o = sigmf(v);
;       sT[row * 136 + col] = f2bf(o);
;     });
.LBB0_708:
	v_bfe_u32 v33, v32, 16, 1
	v_add3_u32 v32, v32, v33, s78
	ds_write_b16_d16_hi v61, v32 offset:64
	s_nop 1

; __device__ __forceinline__ float sigmf(float x) { return 1.f / (1.f + __expf(-x)); }
; template <int MT, int NT, class F>
; __device__ __forceinline__ void acc_foreach(int tid, f32x16 (&acc)[MT][NT], F f) {
;     ...
;   for (int mt = 0; mt < MT; mt++)
; #pragma unroll
;     for (int nt = 0; nt < NT; nt++)
; #pragma unroll
;       for (int i = 0; i < 16; i++) {
;         int row = wm * (MT * 32) + mt * 32 + (i & 3) + 8 * (i >> 2) + 4 * hi;
;         int col = wn * (NT * 32) + nt * 32 + c;
;         f(row, col, acc[mt][nt][i]);
; __device__ __forceinline__ void inproj_epilogue(const Params& p, int layer, int mt, int ntile, int tid,
;                                                 f32x16 (&acc)[2][2], unsigned char* smem) {
;     ...
;     acc_foreach(tid, acc, [&](int row, int col, float v) {
;       int t = m0 + row;
;       float o = v;
;       if (mode == 1) o = (t >= NPADR) ? v : 0.f;
;       if (mode == 2) o = sigmf(v);
;       sT[row * 136 + col] = f2bf(o);
;     });
.LBB0_711:
	v_bfe_u32 v33, v32, 16, 1
	v_add3_u32 v32, v32, v33, s78
	ds_write_b16_d16_hi v62, v32 offset:64
	s_nop 1

; __device__ __forceinline__ float sigmf(float x) { return 1.f / (1.f + __expf(-x)); }
; template <int MT, int NT, class F>
; __device__ __forceinline__ void acc_foreach(int tid, f32x16 (&acc)[MT][NT], F f) {
;     ...
;   for (int mt = 0; mt < MT; mt++)
; #pragma unroll
;     for (int nt = 0; nt < NT; nt++)
; #pragma unroll
;       for (int i = 0; i < 16; i++) {
;         int row = wm * (MT * 32) + mt * 32 + (i & 3) + 8 * (i >> 2) + 4 * hi;
;         int col = wn * (NT * 32) + nt * 32 + c;
;         f(row, col, acc[mt][nt][i]);
; __device__ __forceinline__ void inproj_epilogue(const Params& p, int layer, int mt, int ntile, int tid,
;                                                 f32x16 (&acc)[2][2], unsigned char* smem) {
;     ...
;     acc_foreach(tid, acc, [&](int row, int col, float v) {
;       int t = m0 + row;
;       float o = v;
;       if (mode == 1) o = (t >= NPADR) ? v : 0.f;
;       if (mode == 2) o = sigmf(v);
;       sT[row * 136 + col] = f2bf(o);
;     });
.LBB0_714:
	v_bfe_u32 v33, v32, 16, 1
	v_add3_u32 v32, v32, v33, s78
	ds_write_b16_d16_hi v55, v32 offset:64
	s_nop 1

; __device__ __forceinline__ float sigmf(float x) { return 1.f / (1.f + __expf(-x)); }
; template <int MT, int NT, class F>
; __device__ __forceinline__ void acc_foreach(int tid, f32x16 (&acc)[MT][NT], F f) {
;     ...
;   for (int mt = 0; mt < MT; mt++)
; #pragma unroll
;     for (int nt = 0; nt < NT; nt++)
; #pragma unroll
;       for (int i = 0; i < 16; i++) {
;         int row = wm * (MT * 32) + mt * 32 + (i & 3) + 8 * (i >> 2) + 4 * hi;
;         int col = wn * (NT * 32) + nt * 32 + c;
;         f(row, col, acc[mt][nt][i]);
; __device__ __forceinline__ void inproj_epilogue(const Params& p, int layer, int mt, int ntile, int tid,
;                                                 f32x16 (&acc)[2][2], unsigned char* smem) {
;     ...
;     acc_foreach(tid, acc, [&](int row, int col, float v) {
;       int t = m0 + row;
;       float o = v;
;       if (mode == 1) o = (t >= NPADR) ? v : 0.f;
;       if (mode == 2) o = sigmf(v);
;       sT[row * 136 + col] = f2bf(o);
;     });
.Lgv_1:
	v_mul_f32_e32 v107, 0xbfb8aa3b, v16
	v_exp_f32_e32 v107, v107
	s_nop 0
	v_add_f32_e32 v107, 1.0, v107
	v_div_scale_f32 v110, s[6:7], v107, v107, 1.0
	v_rcp_f32_e32 v111, v110
	v_div_scale_f32 v112, vcc, 1.0, v107, 1.0
	v_fma_f32 v113, -v110, v111, 1.0
	v_fmac_f32_e32 v111, v113, v111
	v_mul_f32_e32 v113, v112, v111
	v_fma_f32 v114, -v110, v113, v112
	v_fmac_f32_e32 v113, v114, v111
	v_fma_f32 v110, -v110, v113, v112
	v_div_fmas_f32 v110, v110, v111, v113
	v_div_fixup_f32 v107, v110, v107, 1.0
	v_bfe_u32 v110, v107, 16, 1
	v_and_b32_e32 v106, 0x5f, v106
	v_add3_u32 v111, v107, v110, s78
	v_mul_lo_u32 v110, v96, s79
	v_lshl_add_u32 v107, v106, 1, v110
	ds_write_b16_d16_hi v107, v111
	v_add3_u32 v111, s90, v96, 1
	v_cmp_lt_i32_e64 s[10:11], s76, v111
	v_cndmask_b32_e64 v111, 0, 1, s[12:13]
	v_cmp_ne_u32_e64 s[6:7], 1, v111
	s_andn2_b64 vcc, exec, s[12:13]
	v_mul_f32_e32 v111, 0xbfb8aa3b, v17
	v_exp_f32_e32 v111, v111
	s_nop 0
	v_add_f32_e32 v111, 1.0, v111
	v_div_scale_f32 v112, s[12:13], v111, v111, 1.0
	v_rcp_f32_e32 v113, v112
	v_div_scale_f32 v114, vcc, 1.0, v111, 1.0
	v_fma_f32 v115, -v112, v113, 1.0
	v_fmac_f32_e32 v113, v115, v113
	v_mul_f32_e32 v115, v114, v113
	v_fma_f32 v116, -v112, v115, v114
	v_fmac_f32_e32 v115, v116, v113
	v_fma_f32 v112, -v112, v115, v114
	v_div_fmas_f32 v112, v112, v113, v115
	v_div_fixup_f32 v111, v112, v111, 1.0
	v_bfe_u32 v112, v111, 16, 1
	v_add3_u32 v112, v111, v112, s78
	v_add_u32_e32 v111, 0x110, v110
	v_lshl_add_u32 v110, v106, 1, v111
	ds_write_b16_d16_hi v110, v112
	v_add3_u32 v112, s90, v96, 2
	s_and_b64 vcc, exec, s[6:7]
	v_cmp_lt_i32_e64 s[12:13], s76, v112
	v_mul_f32_e32 v112, 0xbfb8aa3b, v18
	v_exp_f32_e32 v112, v112
	s_nop 0
	v_add_f32_e32 v112, 1.0, v112
	v_div_scale_f32 v113, s[14:15], v112, v112, 1.0
	v_rcp_f32_e32 v114, v113
	v_div_scale_f32 v115, vcc, 1.0, v112, 1.0
	v_fma_f32 v116, -v113, v114, 1.0
	v_fmac_f32_e32 v114, v116, v114
	v_mul_f32_e32 v116, v115, v114
	v_fma_f32 v117, -v113, v116, v115
	v_fmac_f32_e32 v116, v117, v114
	v_fma_f32 v113, -v113, v116, v115
	v_div_fmas_f32 v113, v113, v114, v116
	v_div_fixup_f32 v112, v113, v112, 1.0
	v_bfe_u32 v113, v112, 16, 1
	v_add3_u32 v113, v112, v113, s78
	v_add_u32_e32 v112, 0x110, v111
	v_lshl_add_u32 v111, v106, 1, v112
	ds_write_b16_d16_hi v111, v113
	v_add3_u32 v113, s90, v96, 3
	s_and_b64 vcc, exec, s[6:7]
	v_cmp_lt_i32_e64 s[14:15], s76, v113
	v_mul_f32_e32 v113, 0xbfb8aa3b, v19
	v_exp_f32_e32 v113, v113
	s_nop 0
	v_add_f32_e32 v113, 1.0, v113
	v_div_scale_f32 v114, s[16:17], v113, v113, 1.0
	v_rcp_f32_e32 v115, v114
	v_div_scale_f32 v116, vcc, 1.0, v113, 1.0
	v_fma_f32 v117, -v114, v115, 1.0
	v_fmac_f32_e32 v115, v117, v115
	v_mul_f32_e32 v117, v116, v115
	v_fma_f32 v118, -v114, v117, v116
	v_fmac_f32_e32 v117, v118, v115
	v_fma_f32 v114, -v114, v117, v116
	v_div_fmas_f32 v114, v114, v115, v117
	v_div_fixup_f32 v113, v114, v113, 1.0
	v_bfe_u32 v114, v113, 16, 1
	v_add3_u32 v114, v113, v114, s78
	v_add_u32_e32 v113, 0x110, v112
	v_lshl_add_u32 v112, v106, 1, v113
	ds_write_b16_d16_hi v112, v114
	v_add3_u32 v114, s90, v96, 8
	s_and_b64 vcc, exec, s[6:7]
	v_cmp_lt_i32_e64 s[16:17], s76, v114
	v_mul_f32_e32 v114, 0xbfb8aa3b, v20
	v_exp_f32_e32 v114, v114
	s_nop 0
	v_add_f32_e32 v114, 1.0, v114
	v_div_scale_f32 v115, s[18:19], v114, v114, 1.0
	v_rcp_f32_e32 v116, v115
	v_div_scale_f32 v117, vcc, 1.0, v114, 1.0
	v_fma_f32 v118, -v115, v116, 1.0
	v_fmac_f32_e32 v116, v118, v116
	v_mul_f32_e32 v118, v117, v116
	v_fma_f32 v119, -v115, v118, v117
	v_fmac_f32_e32 v118, v119, v116
	v_fma_f32 v115, -v115, v118, v117
	v_div_fmas_f32 v115, v115, v116, v118
	v_div_fixup_f32 v114, v115, v114, 1.0
	v_bfe_u32 v115, v114, 16, 1
	v_add3_u32 v115, v114, v115, s78
	v_add_u32_e32 v114, 0x550, v113
	v_lshl_add_u32 v113, v106, 1, v114
	ds_write_b16_d16_hi v113, v115
	v_add3_u32 v115, s90, v96, 9
	s_and_b64 vcc, exec, s[6:7]
	v_cmp_lt_i32_e64 s[18:19], s76, v115
	v_mul_f32_e32 v115, 0xbfb8aa3b, v21
	v_exp_f32_e32 v115, v115
	s_nop 0
	v_add_f32_e32 v115, 1.0, v115
	v_div_scale_f32 v116, s[20:21], v115, v115, 1.0
	v_rcp_f32_e32 v117, v116
	v_div_scale_f32 v118, vcc, 1.0, v115, 1.0
	v_fma_f32 v119, -v116, v117, 1.0
	v_fmac_f32_e32 v117, v119, v117
	v_mul_f32_e32 v119, v118, v117
	v_fma_f32 v120, -v116, v119, v118
	v_fmac_f32_e32 v119, v120, v117
	v_fma_f32 v116, -v116, v119, v118
	v_div_fmas_f32 v116, v116, v117, v119
	v_div_fixup_f32 v115, v116, v115, 1.0
	v_bfe_u32 v116, v115, 16, 1
	v_add3_u32 v116, v115, v116, s78
	v_add_u32_e32 v115, 0x110, v114
	v_lshl_add_u32 v114, v106, 1, v115
	ds_write_b16_d16_hi v114, v116
	v_add3_u32 v116, s90, v96, 10
	s_and_b64 vcc, exec, s[6:7]
	v_cmp_lt_i32_e64 s[20:21], s76, v116
	v_mul_f32_e32 v116, 0xbfb8aa3b, v22
	v_exp_f32_e32 v116, v116
	s_nop 0
	v_add_f32_e32 v116, 1.0, v116
	v_div_scale_f32 v117, s[22:23], v116, v116, 1.0
	v_rcp_f32_e32 v118, v117
	v_div_scale_f32 v119, vcc, 1.0, v116, 1.0
	v_fma_f32 v120, -v117, v118, 1.0
	v_fmac_f32_e32 v118, v120, v118
	v_mul_f32_e32 v120, v119, v118
	v_fma_f32 v121, -v117, v120, v119
	v_fmac_f32_e32 v120, v121, v118
	v_fma_f32 v117, -v117, v120, v119
	v_div_fmas_f32 v117, v117, v118, v120
	v_div_fixup_f32 v116, v117, v116, 1.0
	v_bfe_u32 v117, v116, 16, 1
	v_add3_u32 v117, v116, v117, s78
	v_add_u32_e32 v116, 0x110, v115
	v_lshl_add_u32 v115, v106, 1, v116
	ds_write_b16_d16_hi v115, v117
	v_add3_u32 v117, s90, v96, 11
	s_and_b64 vcc, exec, s[6:7]
	v_cmp_lt_i32_e64 s[22:23], s76, v117
	v_mul_f32_e32 v117, 0xbfb8aa3b, v23
	v_exp_f32_e32 v117, v117
	s_nop 0
	v_add_f32_e32 v117, 1.0, v117
	v_div_scale_f32 v118, s[24:25], v117, v117, 1.0
	v_rcp_f32_e32 v119, v118
; __device__ __forceinline__ float sigmf(float x) { return 1.f / (1.f + __expf(-x)); }
; template <int MT, int NT, class F>
; __device__ __forceinline__ void acc_foreach(int tid, f32x16 (&acc)[MT][NT], F f) {
;     ...
;   for (int mt = 0; mt < MT; mt++)
; #pragma unroll
;     for (int nt = 0; nt < NT; nt++)
; #pragma unroll
;       for (int i = 0; i < 16; i++) {
;         int row = wm * (MT * 32) + mt * 32 + (i & 3) + 8 * (i >> 2) + 4 * hi;
;         int col = wn * (NT * 32) + nt * 32 + c;
;         f(row, col, acc[mt][nt][i]);
; __device__ __forceinline__ void inproj_epilogue(const Params& p, int layer, int mt, int ntile, int tid,
;                                                 f32x16 (&acc)[2][2], unsigned char* smem) {
;     ...
;     acc_foreach(tid, acc, [&](int row, int col, float v) {
;       int t = m0 + row;
;       float o = v;
;       if (mode == 1) o = (t >= NPADR) ? v : 0.f;
;       if (mode == 2) o = sigmf(v);
;       sT[row * 136 + col] = f2bf(o);
;     });
	v_div_scale_f32 v120, vcc, 1.0, v117, 1.0
	v_fma_f32 v121, -v118, v119, 1.0
	v_fmac_f32_e32 v119, v121, v119
	v_mul_f32_e32 v121, v120, v119
	v_fma_f32 v122, -v118, v121, v120
	v_fmac_f32_e32 v121, v122, v119
	v_fma_f32 v118, -v118, v121, v120
	v_div_fmas_f32 v118, v118, v119, v121
	v_div_fixup_f32 v117, v118, v117, 1.0
	v_bfe_u32 v118, v117, 16, 1
	v_add_u32_e32 v116, 0x110, v116
	v_add3_u32 v118, v117, v118, s78
	v_lshl_add_u32 v117, v106, 1, v116
	ds_write_b16_d16_hi v117, v118
	v_add3_u32 v118, s90, v96, 16
	s_and_b64 vcc, exec, s[6:7]
	v_cmp_lt_i32_e64 s[24:25], s76, v118
	v_mul_f32_e32 v118, 0xbfb8aa3b, v24
	v_exp_f32_e32 v118, v118
	s_nop 0
	v_add_f32_e32 v118, 1.0, v118
	v_div_scale_f32 v119, s[26:27], v118, v118, 1.0
	v_rcp_f32_e32 v120, v119
	v_div_scale_f32 v121, vcc, 1.0, v118, 1.0
	v_fma_f32 v122, -v119, v120, 1.0
	v_fmac_f32_e32 v120, v122, v120
	v_mul_f32_e32 v122, v121, v120
	v_fma_f32 v123, -v119, v122, v121
	v_fmac_f32_e32 v122, v123, v120
	v_fma_f32 v119, -v119, v122, v121
	v_div_fmas_f32 v119, v119, v120, v122
	v_div_fixup_f32 v118, v119, v118, 1.0
	v_bfe_u32 v119, v118, 16, 1
	v_add_u32_e32 v116, 0x550, v116
	v_add3_u32 v119, v118, v119, s78
	v_lshl_add_u32 v118, v106, 1, v116
	ds_write_b16_d16_hi v118, v119
	v_add3_u32 v119, s90, v96, 17
	s_and_b64 vcc, exec, s[6:7]
	v_cmp_lt_i32_e64 s[26:27], s76, v119
	v_mul_f32_e32 v119, 0xbfb8aa3b, v25
	v_exp_f32_e32 v119, v119
	s_nop 0
	v_add_f32_e32 v119, 1.0, v119
	v_div_scale_f32 v120, s[28:29], v119, v119, 1.0
	v_rcp_f32_e32 v121, v120
	v_div_scale_f32 v122, vcc, 1.0, v119, 1.0
	v_fma_f32 v123, -v120, v121, 1.0
	v_fmac_f32_e32 v121, v123, v121
	v_mul_f32_e32 v123, v122, v121
	v_fma_f32 v124, -v120, v123, v122
	v_fmac_f32_e32 v123, v124, v121
	v_fma_f32 v120, -v120, v123, v122
	v_div_fmas_f32 v120, v120, v121, v123
	v_div_fixup_f32 v119, v120, v119, 1.0
	v_bfe_u32 v120, v119, 16, 1
	v_add_u32_e32 v116, 0x110, v116
	v_add3_u32 v120, v119, v120, s78
	v_lshl_add_u32 v119, v106, 1, v116
	ds_write_b16_d16_hi v119, v120
	v_add3_u32 v120, s90, v96, 18
	s_and_b64 vcc, exec, s[6:7]
	v_cmp_lt_i32_e64 s[28:29], s76, v120
	v_mul_f32_e32 v120, 0xbfb8aa3b, v26
	v_exp_f32_e32 v120, v120
	s_nop 0
	v_add_f32_e32 v120, 1.0, v120
	v_div_scale_f32 v121, s[30:31], v120, v120, 1.0
	v_rcp_f32_e32 v122, v121
	v_div_scale_f32 v123, vcc, 1.0, v120, 1.0
	v_fma_f32 v124, -v121, v122, 1.0
	v_fmac_f32_e32 v122, v124, v122
	v_mul_f32_e32 v124, v123, v122
	v_fma_f32 v125, -v121, v124, v123
	v_fmac_f32_e32 v124, v125, v122
	v_fma_f32 v121, -v121, v124, v123
	v_div_fmas_f32 v121, v121, v122, v124
	v_div_fixup_f32 v120, v121, v120, 1.0
	v_bfe_u32 v121, v120, 16, 1
	v_add_u32_e32 v116, 0x110, v116
	v_add3_u32 v121, v120, v121, s78
	v_lshl_add_u32 v120, v106, 1, v116
	ds_write_b16_d16_hi v120, v121
	v_add3_u32 v121, s90, v96, 19
	s_and_b64 vcc, exec, s[6:7]
	v_cmp_lt_i32_e64 s[30:31], s76, v121
	v_mul_f32_e32 v121, 0xbfb8aa3b, v27
	v_exp_f32_e32 v121, v121
	s_nop 0
	v_add_f32_e32 v121, 1.0, v121
	v_div_scale_f32 v122, s[34:35], v121, v121, 1.0
	v_rcp_f32_e32 v123, v122
	v_div_scale_f32 v124, vcc, 1.0, v121, 1.0
	v_fma_f32 v125, -v122, v123, 1.0
	v_fmac_f32_e32 v123, v125, v123
	v_mul_f32_e32 v125, v124, v123
	v_fma_f32 v126, -v122, v125, v124
	v_fmac_f32_e32 v125, v126, v123
	v_fma_f32 v122, -v122, v125, v124
	v_div_fmas_f32 v122, v122, v123, v125
	v_div_fixup_f32 v121, v122, v121, 1.0
	v_bfe_u32 v122, v121, 16, 1
	v_add_u32_e32 v116, 0x110, v116
	v_add3_u32 v122, v121, v122, s78
	v_lshl_add_u32 v121, v106, 1, v116
	ds_write_b16_d16_hi v121, v122
	v_add3_u32 v122, s90, v96, 24
	s_and_b64 vcc, exec, s[6:7]
	v_cmp_lt_i32_e64 s[34:35], s76, v122
	v_mul_f32_e32 v122, 0xbfb8aa3b, v28
	v_exp_f32_e32 v122, v122
	s_nop 0
	v_add_f32_e32 v122, 1.0, v122
	v_div_scale_f32 v123, s[36:37], v122, v122, 1.0
	v_rcp_f32_e32 v124, v123
	v_div_scale_f32 v125, vcc, 1.0, v122, 1.0
	v_fma_f32 v126, -v123, v124, 1.0
	v_fmac_f32_e32 v124, v126, v124
	v_mul_f32_e32 v126, v125, v124
	v_fma_f32 v127, -v123, v126, v125
	v_fmac_f32_e32 v126, v127, v124
	v_fma_f32 v123, -v123, v126, v125
	v_div_fmas_f32 v123, v123, v124, v126
	v_div_fixup_f32 v122, v123, v122, 1.0
	v_bfe_u32 v123, v122, 16, 1
	v_add_u32_e32 v116, 0x550, v116
	v_add3_u32 v123, v122, v123, s78
	v_lshl_add_u32 v122, v106, 1, v116
	ds_write_b16_d16_hi v122, v123
	v_add3_u32 v123, s90, v96, 25
	s_and_b64 vcc, exec, s[6:7]
	v_cmp_lt_i32_e64 s[36:37], s76, v123
	v_mul_f32_e32 v123, 0xbfb8aa3b, v29
	v_exp_f32_e32 v123, v123
	s_nop 0
	v_add_f32_e32 v123, 1.0, v123
	v_div_scale_f32 v124, s[38:39], v123, v123, 1.0
	v_rcp_f32_e32 v125, v124
	v_div_scale_f32 v126, vcc, 1.0, v123, 1.0
	v_fma_f32 v127, -v124, v125, 1.0
	v_fmac_f32_e32 v125, v127, v125
	v_mul_f32_e32 v127, v126, v125
	v_fma_f32 v128, -v124, v127, v126
	v_fmac_f32_e32 v127, v128, v125
	v_fma_f32 v124, -v124, v127, v126
	v_div_fmas_f32 v124, v124, v125, v127
	v_div_fixup_f32 v123, v124, v123, 1.0
	v_bfe_u32 v124, v123, 16, 1
	v_add_u32_e32 v116, 0x110, v116
	v_add3_u32 v124, v123, v124, s78
	v_lshl_add_u32 v123, v106, 1, v116
	ds_write_b16_d16_hi v123, v124
	v_add3_u32 v124, s90, v96, 26
	s_and_b64 vcc, exec, s[6:7]
	v_cmp_lt_i32_e64 s[38:39], s76, v124
	v_mul_f32_e32 v124, 0xbfb8aa3b, v30
	v_exp_f32_e32 v124, v124
	s_nop 0
	v_add_f32_e32 v124, 1.0, v124
	v_div_scale_f32 v125, s[40:41], v124, v124, 1.0
	v_rcp_f32_e32 v126, v125
	v_div_scale_f32 v127, vcc, 1.0, v124, 1.0
	v_fma_f32 v128, -v125, v126, 1.0
	v_fmac_f32_e32 v126, v128, v126
	v_mul_f32_e32 v128, v127, v126
	v_fma_f32 v129, -v125, v128, v127
	v_fmac_f32_e32 v128, v129, v126
	v_fma_f32 v125, -v125, v128, v127
	v_div_fmas_f32 v125, v125, v126, v128
; __device__ __forceinline__ float sigmf(float x) { return 1.f / (1.f + __expf(-x)); }
; template <int MT, int NT, class F>
; __device__ __forceinline__ void acc_foreach(int tid, f32x16 (&acc)[MT][NT], F f) {
;     ...
;   for (int mt = 0; mt < MT; mt++)
; #pragma unroll
;     for (int nt = 0; nt < NT; nt++)
; #pragma unroll
;       for (int i = 0; i < 16; i++) {
;         int row = wm * (MT * 32) + mt * 32 + (i & 3) + 8 * (i >> 2) + 4 * hi;
;         int col = wn * (NT * 32) + nt * 32 + c;
;         f(row, col, acc[mt][nt][i]);
; __device__ __forceinline__ void inproj_epilogue(const Params& p, int layer, int mt, int ntile, int tid,
;                                                 f32x16 (&acc)[2][2], unsigned char* smem) {
;     ...
;     acc_foreach(tid, acc, [&](int row, int col, float v) {
;       int t = m0 + row;
;       float o = v;
;       if (mode == 1) o = (t >= NPADR) ? v : 0.f;
;       if (mode == 2) o = sigmf(v);
;       sT[row * 136 + col] = f2bf(o);
;     });
	v_div_fixup_f32 v124, v125, v124, 1.0
	v_bfe_u32 v125, v124, 16, 1
	v_add_u32_e32 v116, 0x110, v116
	v_add3_u32 v124, v124, v125, s78
	v_lshl_add_u32 v116, v106, 1, v116
	ds_write_b16_d16_hi v116, v124
	v_add3_u32 v124, s90, v96, 27
	s_and_b64 vcc, exec, s[6:7]
	v_cmp_lt_i32_e64 s[40:41], s76, v124
	v_mul_f32_e32 v124, 0xbfb8aa3b, v31
	v_exp_f32_e32 v124, v124
	s_nop 0
	v_add_f32_e32 v124, 1.0, v124
	v_div_scale_f32 v125, vcc, v124, v124, 1.0
	v_rcp_f32_e32 v126, v125
	v_div_scale_f32 v127, vcc, 1.0, v124, 1.0
	v_fma_f32 v128, -v125, v126, 1.0
	v_fmac_f32_e32 v126, v128, v126
	v_mul_f32_e32 v128, v127, v126
	v_fma_f32 v129, -v125, v128, v127
	v_fmac_f32_e32 v128, v129, v126
	v_fma_f32 v125, -v125, v128, v127
	v_div_fmas_f32 v125, v125, v126, v128
	v_div_fixup_f32 v124, v125, v124, 1.0
	v_bfe_u32 v125, v124, 16, 1
	v_add3_u32 v124, v124, v125, s78
	ds_write_b16_d16_hi v116, v124 offset:272
	s_and_b64 vcc, exec, s[6:7]
	v_mul_f32_e32 v48, 0xbfb8aa3b, v48
	v_exp_f32_e32 v48, v48
	s_nop 0
	v_add_f32_e32 v48, 1.0, v48
	v_div_scale_f32 v124, s[8:9], v48, v48, 1.0
	v_rcp_f32_e32 v125, v124
	v_div_scale_f32 v126, vcc, 1.0, v48, 1.0
	v_fma_f32 v127, -v124, v125, 1.0
	v_fmac_f32_e32 v125, v127, v125
	v_mul_f32_e32 v127, v126, v125
	v_fma_f32 v128, -v124, v127, v126
	v_fmac_f32_e32 v127, v128, v125
	v_fma_f32 v124, -v124, v127, v126
	v_div_fmas_f32 v124, v124, v125, v127
	v_div_fixup_f32 v48, v124, v48, 1.0
	v_bfe_u32 v124, v48, 16, 1
	v_add3_u32 v48, v48, v124, s78
	s_and_b64 vcc, exec, s[6:7]
	ds_write_b16_d16_hi v107, v48 offset:64
	v_mul_f32_e32 v48, 0xbfb8aa3b, v49
	v_exp_f32_e32 v48, v48
	s_nop 0
	v_add_f32_e32 v48, 1.0, v48
	v_div_scale_f32 v49, s[8:9], v48, v48, 1.0
	v_rcp_f32_e32 v107, v49
	v_div_scale_f32 v124, vcc, 1.0, v48, 1.0
	v_fma_f32 v125, -v49, v107, 1.0
	v_fmac_f32_e32 v107, v125, v107
	v_mul_f32_e32 v125, v124, v107
	v_fma_f32 v126, -v49, v125, v124
	v_fmac_f32_e32 v125, v126, v107
	v_fma_f32 v49, -v49, v125, v124
	v_div_fmas_f32 v49, v49, v107, v125
	v_div_fixup_f32 v48, v49, v48, 1.0
	v_bfe_u32 v49, v48, 16, 1
	v_add3_u32 v48, v48, v49, s78
	s_and_b64 vcc, exec, s[6:7]
	ds_write_b16_d16_hi v110, v48 offset:64
	v_mul_f32_e32 v48, 0xbfb8aa3b, v50
	v_exp_f32_e32 v48, v48
	s_nop 0
	v_add_f32_e32 v48, 1.0, v48
	v_div_scale_f32 v49, s[8:9], v48, v48, 1.0
	v_rcp_f32_e32 v50, v49
	v_div_scale_f32 v107, vcc, 1.0, v48, 1.0
	v_fma_f32 v110, -v49, v50, 1.0
	v_fmac_f32_e32 v50, v110, v50
	v_mul_f32_e32 v110, v107, v50
	v_fma_f32 v124, -v49, v110, v107
	v_fmac_f32_e32 v110, v124, v50
	v_fma_f32 v49, -v49, v110, v107
	v_div_fmas_f32 v49, v49, v50, v110
	v_div_fixup_f32 v48, v49, v48, 1.0
	v_bfe_u32 v49, v48, 16, 1
	v_add3_u32 v48, v48, v49, s78
	s_and_b64 vcc, exec, s[6:7]
	ds_write_b16_d16_hi v111, v48 offset:64
	v_mul_f32_e32 v48, 0xbfb8aa3b, v51
	v_exp_f32_e32 v48, v48
	s_nop 0
	v_add_f32_e32 v48, 1.0, v48
	v_div_scale_f32 v49, s[8:9], v48, v48, 1.0
	v_rcp_f32_e32 v50, v49
	v_div_scale_f32 v51, vcc, 1.0, v48, 1.0
	v_fma_f32 v107, -v49, v50, 1.0
	v_fmac_f32_e32 v50, v107, v50
	v_mul_f32_e32 v107, v51, v50
	v_fma_f32 v110, -v49, v107, v51
	v_fmac_f32_e32 v107, v110, v50
	v_fma_f32 v49, -v49, v107, v51
	v_div_fmas_f32 v49, v49, v50, v107
	v_div_fixup_f32 v48, v49, v48, 1.0
	v_bfe_u32 v49, v48, 16, 1
	v_add3_u32 v48, v48, v49, s78
	s_and_b64 vcc, exec, s[6:7]
	ds_write_b16_d16_hi v112, v48 offset:64
	v_mul_f32_e32 v48, 0xbfb8aa3b, v52
	v_exp_f32_e32 v48, v48
	s_nop 0
	v_add_f32_e32 v48, 1.0, v48
	v_div_scale_f32 v49, s[8:9], v48, v48, 1.0
	v_rcp_f32_e32 v50, v49
	v_div_scale_f32 v51, vcc, 1.0, v48, 1.0
	v_fma_f32 v52, -v49, v50, 1.0
	v_fmac_f32_e32 v50, v52, v50
	v_mul_f32_e32 v52, v51, v50
	v_fma_f32 v107, -v49, v52, v51
	v_fmac_f32_e32 v52, v107, v50
	v_fma_f32 v49, -v49, v52, v51
	v_div_fmas_f32 v49, v49, v50, v52
	v_div_fixup_f32 v48, v49, v48, 1.0
	v_bfe_u32 v49, v48, 16, 1
	v_add3_u32 v48, v48, v49, s78
	s_and_b64 vcc, exec, s[6:7]
	ds_write_b16_d16_hi v113, v48 offset:64
	v_mul_f32_e32 v48, 0xbfb8aa3b, v53
	v_exp_f32_e32 v48, v48
	s_nop 0
	v_add_f32_e32 v48, 1.0, v48
	v_div_scale_f32 v49, s[8:9], v48, v48, 1.0
	v_rcp_f32_e32 v50, v49
	v_div_scale_f32 v51, vcc, 1.0, v48, 1.0
	v_fma_f32 v52, -v49, v50, 1.0
	v_fmac_f32_e32 v50, v52, v50
	v_mul_f32_e32 v52, v51, v50
	v_fma_f32 v53, -v49, v52, v51
	v_fmac_f32_e32 v52, v53, v50
	v_fma_f32 v49, -v49, v52, v51
	v_div_fmas_f32 v49, v49, v50, v52
	v_div_fixup_f32 v48, v49, v48, 1.0
	v_bfe_u32 v49, v48, 16, 1
	v_add3_u32 v48, v48, v49, s78
	s_and_b64 vcc, exec, s[6:7]
	ds_write_b16_d16_hi v114, v48 offset:64
	v_mul_f32_e32 v48, 0xbfb8aa3b, v54
	v_exp_f32_e32 v48, v48
	s_nop 0
	v_add_f32_e32 v48, 1.0, v48
	v_div_scale_f32 v49, s[8:9], v48, v48, 1.0
	v_rcp_f32_e32 v50, v49
	v_div_scale_f32 v51, vcc, 1.0, v48, 1.0
	v_fma_f32 v52, -v49, v50, 1.0
	v_fmac_f32_e32 v50, v52, v50
	v_mul_f32_e32 v52, v51, v50
	v_fma_f32 v53, -v49, v52, v51
	v_fmac_f32_e32 v52, v53, v50
	v_fma_f32 v49, -v49, v52, v51
	v_div_fmas_f32 v49, v49, v50, v52
	v_div_fixup_f32 v48, v49, v48, 1.0
	v_bfe_u32 v49, v48, 16, 1
	v_add3_u32 v48, v48, v49, s78
	s_and_b64 vcc, exec, s[6:7]
	ds_write_b16_d16_hi v115, v48 offset:64
	v_mul_f32_e32 v48, 0xbfb8aa3b, v55
	v_exp_f32_e32 v48, v48
	s_nop 0
	v_add_f32_e32 v48, 1.0, v48
	v_div_scale_f32 v49, s[8:9], v48, v48, 1.0
	v_rcp_f32_e32 v50, v49
	v_div_scale_f32 v51, vcc, 1.0, v48, 1.0
	v_fma_f32 v52, -v49, v50, 1.0
	v_fmac_f32_e32 v50, v52, v50
	v_mul_f32_e32 v52, v51, v50
	v_fma_f32 v53, -v49, v52, v51
	v_fmac_f32_e32 v52, v53, v50
	v_fma_f32 v49, -v49, v52, v51
	v_div_fmas_f32 v49, v49, v50, v52
	v_div_fixup_f32 v48, v49, v48, 1.0
	v_bfe_u32 v49, v48, 16, 1
	v_add3_u32 v48, v48, v49, s78
; __device__ __forceinline__ bf16r f2bf(float f) {
;   unsigned u = __float_as_uint(f);
;   u += 0x7fffu + ((u >> 16) & 1u);
;   return (bf16r)(u >> 16);
; }
; __device__ __forceinline__ unsigned pack2(float a, float b) { return (unsigned)f2bf(a) | ((unsigned)f2bf(b) << 16); }
; __device__ __forceinline__ float lo16(unsigned v) { return __uint_as_float(v << 16); }
; __device__ __forceinline__ float hi16(unsigned v) { return __uint_as_float(v & 0xffff0000u); }
; __device__ __forceinline__ float siluf(float x) { return x / (1.f + __expf(-x)); }
; __device__ __forceinline__ float sigmf(float x) { return 1.f / (1.f + __expf(-x)); }
; __device__ __forceinline__ void inproj_epilogue(const Params& p, int layer, int mt, int ntile, int tid,
;                                                 f32x16 (&acc)[2][2], unsigned char* smem) {
;     ...
;     acc_foreach(tid, acc, [&](int row, int col, float v) {
;       int t = m0 + row;
;       float o = v;
;       if (mode == 1) o = (t >= NPADR) ? v : 0.f;
;       if (mode == 2) o = sigmf(v);
;       sT[row * 136 + col] = f2bf(o);
;     });
	s_and_b64 vcc, exec, s[6:7]
	ds_write_b16_d16_hi v117, v48 offset:64
	v_mul_f32_e32 v48, 0xbfb8aa3b, v56
	v_exp_f32_e32 v48, v48
	s_nop 0
	v_add_f32_e32 v48, 1.0, v48
	v_div_scale_f32 v49, s[8:9], v48, v48, 1.0
	v_rcp_f32_e32 v50, v49
	v_div_scale_f32 v51, vcc, 1.0, v48, 1.0
	v_fma_f32 v52, -v49, v50, 1.0
	v_fmac_f32_e32 v50, v52, v50
	v_mul_f32_e32 v52, v51, v50
	v_fma_f32 v53, -v49, v52, v51
	v_fmac_f32_e32 v52, v53, v50
	v_fma_f32 v49, -v49, v52, v51
	v_div_fmas_f32 v49, v49, v50, v52
	v_div_fixup_f32 v48, v49, v48, 1.0
	v_bfe_u32 v49, v48, 16, 1
	v_add3_u32 v48, v48, v49, s78
	s_and_b64 vcc, exec, s[6:7]
	ds_write_b16_d16_hi v118, v48 offset:64
	v_mul_f32_e32 v48, 0xbfb8aa3b, v57
	v_exp_f32_e32 v48, v48
	s_nop 0
	v_add_f32_e32 v48, 1.0, v48
	v_div_scale_f32 v49, s[8:9], v48, v48, 1.0
	v_rcp_f32_e32 v50, v49
	v_div_scale_f32 v51, vcc, 1.0, v48, 1.0
	v_fma_f32 v52, -v49, v50, 1.0
	v_fmac_f32_e32 v50, v52, v50
	v_mul_f32_e32 v52, v51, v50
	v_fma_f32 v53, -v49, v52, v51
	v_fmac_f32_e32 v52, v53, v50
	v_fma_f32 v49, -v49, v52, v51
	v_div_fmas_f32 v49, v49, v50, v52
	v_div_fixup_f32 v48, v49, v48, 1.0
	v_bfe_u32 v49, v48, 16, 1
	v_add3_u32 v48, v48, v49, s78
	s_and_b64 vcc, exec, s[6:7]
	ds_write_b16_d16_hi v119, v48 offset:64
	v_mul_f32_e32 v48, 0xbfb8aa3b, v58
	v_exp_f32_e32 v48, v48
	s_nop 0
	v_add_f32_e32 v48, 1.0, v48
	v_div_scale_f32 v49, s[8:9], v48, v48, 1.0
	v_rcp_f32_e32 v50, v49
	v_div_scale_f32 v51, vcc, 1.0, v48, 1.0
	v_fma_f32 v52, -v49, v50, 1.0
	v_fmac_f32_e32 v50, v52, v50
	v_mul_f32_e32 v52, v51, v50
	v_fma_f32 v53, -v49, v52, v51
	v_fmac_f32_e32 v52, v53, v50
	v_fma_f32 v49, -v49, v52, v51
	v_div_fmas_f32 v49, v49, v50, v52
	v_div_fixup_f32 v48, v49, v48, 1.0
	v_bfe_u32 v49, v48, 16, 1
	v_add3_u32 v48, v48, v49, s78
	s_and_b64 vcc, exec, s[6:7]
	ds_write_b16_d16_hi v120, v48 offset:64
	v_mul_f32_e32 v48, 0xbfb8aa3b, v59
	v_exp_f32_e32 v48, v48
	s_nop 0
	v_add_f32_e32 v48, 1.0, v48
	v_div_scale_f32 v49, s[8:9], v48, v48, 1.0
	v_rcp_f32_e32 v50, v49
	v_div_scale_f32 v51, vcc, 1.0, v48, 1.0
	v_fma_f32 v52, -v49, v50, 1.0
	v_fmac_f32_e32 v50, v52, v50
	v_mul_f32_e32 v52, v51, v50
	v_fma_f32 v53, -v49, v52, v51
	v_fmac_f32_e32 v52, v53, v50
	v_fma_f32 v49, -v49, v52, v51
	v_div_fmas_f32 v49, v49, v50, v52
	v_div_fixup_f32 v48, v49, v48, 1.0
	v_bfe_u32 v49, v48, 16, 1
	v_add3_u32 v48, v48, v49, s78
	s_and_b64 vcc, exec, s[6:7]
	ds_write_b16_d16_hi v121, v48 offset:64
	v_mul_f32_e32 v48, 0xbfb8aa3b, v60
	v_exp_f32_e32 v48, v48
	s_nop 0
	v_add_f32_e32 v48, 1.0, v48
	v_div_scale_f32 v49, s[8:9], v48, v48, 1.0
	v_rcp_f32_e32 v50, v49
	v_div_scale_f32 v51, vcc, 1.0, v48, 1.0
	v_fma_f32 v52, -v49, v50, 1.0
	v_fmac_f32_e32 v50, v52, v50
	v_mul_f32_e32 v52, v51, v50
	v_fma_f32 v53, -v49, v52, v51
	v_fmac_f32_e32 v52, v53, v50
	v_fma_f32 v49, -v49, v52, v51
	v_div_fmas_f32 v49, v49, v50, v52
	v_div_fixup_f32 v48, v49, v48, 1.0
	v_bfe_u32 v49, v48, 16, 1
	v_add3_u32 v48, v48, v49, s78
	s_and_b64 vcc, exec, s[6:7]
	ds_write_b16_d16_hi v122, v48 offset:64
	v_mul_f32_e32 v48, 0xbfb8aa3b, v61
	v_exp_f32_e32 v48, v48
	s_nop 0
	v_add_f32_e32 v48, 1.0, v48
	v_div_scale_f32 v49, s[8:9], v48, v48, 1.0
	v_rcp_f32_e32 v50, v49
	v_div_scale_f32 v51, vcc, 1.0, v48, 1.0
	v_fma_f32 v52, -v49, v50, 1.0
	v_fmac_f32_e32 v50, v52, v50
	v_mul_f32_e32 v52, v51, v50
	v_fma_f32 v53, -v49, v52, v51
	v_fmac_f32_e32 v52, v53, v50
	v_fma_f32 v49, -v49, v52, v51
	v_div_fmas_f32 v49, v49, v50, v52
	v_div_fixup_f32 v48, v49, v48, 1.0
	v_bfe_u32 v49, v48, 16, 1
	v_add3_u32 v48, v48, v49, s78
	s_and_b64 vcc, exec, s[6:7]
	ds_write_b16_d16_hi v123, v48 offset:64
	v_mul_f32_e32 v48, 0xbfb8aa3b, v62
	v_exp_f32_e32 v48, v48
	s_nop 0
	v_add_f32_e32 v48, 1.0, v48
	v_div_scale_f32 v49, s[8:9], v48, v48, 1.0
	v_rcp_f32_e32 v50, v49
	v_div_scale_f32 v51, vcc, 1.0, v48, 1.0
	v_fma_f32 v52, -v49, v50, 1.0
	v_fmac_f32_e32 v50, v52, v50
	v_mul_f32_e32 v52, v51, v50
	v_fma_f32 v53, -v49, v52, v51
	v_fmac_f32_e32 v52, v53, v50
	v_fma_f32 v49, -v49, v52, v51
	v_div_fmas_f32 v49, v49, v50, v52
	v_div_fixup_f32 v48, v49, v48, 1.0
	v_bfe_u32 v49, v48, 16, 1
	v_add3_u32 v48, v48, v49, s78
	s_and_b64 vcc, exec, s[6:7]
	ds_write_b16_d16_hi v116, v48 offset:64
	v_mul_f32_e32 v48, 0xbfb8aa3b, v63
	v_exp_f32_e32 v48, v48
	s_nop 0
	v_add_f32_e32 v48, 1.0, v48
	v_div_scale_f32 v49, s[8:9], v48, v48, 1.0
	v_rcp_f32_e32 v50, v49
	v_div_scale_f32 v51, vcc, 1.0, v48, 1.0
	v_fma_f32 v52, -v49, v50, 1.0
	v_fmac_f32_e32 v50, v52, v50
	v_mul_f32_e32 v52, v51, v50
	v_fma_f32 v53, -v49, v52, v51
	v_fmac_f32_e32 v52, v53, v50
	v_fma_f32 v49, -v49, v52, v51
	v_div_fmas_f32 v49, v49, v50, v52
	v_div_fixup_f32 v48, v49, v48, 1.0
	v_bfe_u32 v50, v48, 16, 1
	v_add_u32_e32 v49, 0x110, v116
	v_add3_u32 v48, v48, v50, s78
	ds_write_b16_d16_hi v49, v48 offset:64
	v_or_b32_e32 v48, 32, v96
	v_add_u32_e32 v49, s90, v48
	s_and_b64 vcc, exec, s[6:7]
	v_cmp_lt_i32_e64 s[8:9], s76, v49
	v_mul_f32_e32 v49, 0xbfb8aa3b, v0
	v_exp_f32_e32 v49, v49
	s_nop 0
	v_add_f32_e32 v49, 1.0, v49
	v_div_scale_f32 v50, s[10:11], v49, v49, 1.0
	v_rcp_f32_e32 v51, v50
	v_div_scale_f32 v52, vcc, 1.0, v49, 1.0
	v_fma_f32 v53, -v50, v51, 1.0
	v_fmac_f32_e32 v51, v53, v51
	v_mul_f32_e32 v53, v52, v51
	v_fma_f32 v54, -v50, v53, v52
	v_fmac_f32_e32 v53, v54, v51
	v_fma_f32 v50, -v50, v53, v52
	v_div_fmas_f32 v50, v50, v51, v53
	v_div_fixup_f32 v49, v50, v49, 1.0
	v_bfe_u32 v50, v49, 16, 1
	v_add3_u32 v50, v49, v50, s78
	v_mul_lo_u32 v49, v48, s79
	v_lshl_add_u32 v48, v106, 1, v49
	ds_write_b16_d16_hi v48, v50
	v_add3_u32 v50, s90, v96, 33
	s_and_b64 vcc, exec, s[6:7]
	v_cmp_lt_i32_e64 s[10:11], s76, v50
	v_mul_f32_e32 v50, 0xbfb8aa3b, v1
; __device__ __forceinline__ bf16r f2bf(float f) {
;   unsigned u = __float_as_uint(f);
;   u += 0x7fffu + ((u >> 16) & 1u);
;   return (bf16r)(u >> 16);
; }
; __device__ __forceinline__ unsigned pack2(float a, float b) { return (unsigned)f2bf(a) | ((unsigned)f2bf(b) << 16); }
; __device__ __forceinline__ float lo16(unsigned v) { return __uint_as_float(v << 16); }
; __device__ __forceinline__ float hi16(unsigned v) { return __uint_as_float(v & 0xffff0000u); }
; __device__ __forceinline__ float siluf(float x) { return x / (1.f + __expf(-x)); }
; __device__ __forceinline__ float sigmf(float x) { return 1.f / (1.f + __expf(-x)); }
; __device__ __forceinline__ void inproj_epilogue(const Params& p, int layer, int mt, int ntile, int tid,
;                                                 f32x16 (&acc)[2][2], unsigned char* smem) {
;     ...
;     acc_foreach(tid, acc, [&](int row, int col, float v) {
;       int t = m0 + row;
;       float o = v;
;       if (mode == 1) o = (t >= NPADR) ? v : 0.f;
;       if (mode == 2) o = sigmf(v);
;       sT[row * 136 + col] = f2bf(o);
;     });
	v_exp_f32_e32 v50, v50
	s_nop 0
	v_add_f32_e32 v50, 1.0, v50
	v_div_scale_f32 v51, s[12:13], v50, v50, 1.0
	v_rcp_f32_e32 v52, v51
	v_div_scale_f32 v53, vcc, 1.0, v50, 1.0
	v_fma_f32 v54, -v51, v52, 1.0
	v_fmac_f32_e32 v52, v54, v52
	v_mul_f32_e32 v54, v53, v52
	v_fma_f32 v55, -v51, v54, v53
	v_fmac_f32_e32 v54, v55, v52
	v_fma_f32 v51, -v51, v54, v53
	v_div_fmas_f32 v51, v51, v52, v54
	v_div_fixup_f32 v50, v51, v50, 1.0
	v_bfe_u32 v51, v50, 16, 1
	v_add3_u32 v51, v50, v51, s78
	v_add_u32_e32 v50, 0x110, v49
	v_lshl_add_u32 v49, v106, 1, v50
	ds_write_b16_d16_hi v49, v51
	v_add3_u32 v51, s90, v96, 34
	s_and_b64 vcc, exec, s[6:7]
	v_cmp_lt_i32_e64 s[12:13], s76, v51
	v_mul_f32_e32 v51, 0xbfb8aa3b, v2
	v_exp_f32_e32 v51, v51
	s_nop 0
	v_add_f32_e32 v51, 1.0, v51
	v_div_scale_f32 v52, s[14:15], v51, v51, 1.0
	v_rcp_f32_e32 v53, v52
	v_div_scale_f32 v54, vcc, 1.0, v51, 1.0
	v_fma_f32 v55, -v52, v53, 1.0
	v_fmac_f32_e32 v53, v55, v53
	v_mul_f32_e32 v55, v54, v53
	v_fma_f32 v56, -v52, v55, v54
	v_fmac_f32_e32 v55, v56, v53
	v_fma_f32 v52, -v52, v55, v54
	v_div_fmas_f32 v52, v52, v53, v55
	v_div_fixup_f32 v51, v52, v51, 1.0
	v_bfe_u32 v52, v51, 16, 1
	v_add3_u32 v52, v51, v52, s78
	v_add_u32_e32 v51, 0x110, v50
	v_lshl_add_u32 v50, v106, 1, v51
	ds_write_b16_d16_hi v50, v52
	v_add3_u32 v52, s90, v96, 35
	s_and_b64 vcc, exec, s[6:7]
	v_cmp_lt_i32_e64 s[14:15], s76, v52
	v_mul_f32_e32 v52, 0xbfb8aa3b, v3
	v_exp_f32_e32 v52, v52
	s_nop 0
	v_add_f32_e32 v52, 1.0, v52
	v_div_scale_f32 v53, s[16:17], v52, v52, 1.0
	v_rcp_f32_e32 v54, v53
	v_div_scale_f32 v55, vcc, 1.0, v52, 1.0
	v_fma_f32 v56, -v53, v54, 1.0
	v_fmac_f32_e32 v54, v56, v54
	v_mul_f32_e32 v56, v55, v54
	v_fma_f32 v57, -v53, v56, v55
	v_fmac_f32_e32 v56, v57, v54
	v_fma_f32 v53, -v53, v56, v55
	v_div_fmas_f32 v53, v53, v54, v56
	v_div_fixup_f32 v52, v53, v52, 1.0
	v_bfe_u32 v53, v52, 16, 1
	v_add3_u32 v53, v52, v53, s78
	v_add_u32_e32 v52, 0x110, v51
	v_lshl_add_u32 v51, v106, 1, v52
	ds_write_b16_d16_hi v51, v53
	v_add3_u32 v53, s90, v96, 40
	s_and_b64 vcc, exec, s[6:7]
	v_cmp_lt_i32_e64 s[16:17], s76, v53
	v_mul_f32_e32 v53, 0xbfb8aa3b, v4
	v_exp_f32_e32 v53, v53
	s_nop 0
	v_add_f32_e32 v53, 1.0, v53
	v_div_scale_f32 v54, s[18:19], v53, v53, 1.0
	v_rcp_f32_e32 v55, v54
	v_div_scale_f32 v56, vcc, 1.0, v53, 1.0
	v_fma_f32 v57, -v54, v55, 1.0
	v_fmac_f32_e32 v55, v57, v55
	v_mul_f32_e32 v57, v56, v55
	v_fma_f32 v58, -v54, v57, v56
	v_fmac_f32_e32 v57, v58, v55
	v_fma_f32 v54, -v54, v57, v56
	v_div_fmas_f32 v54, v54, v55, v57
	v_div_fixup_f32 v53, v54, v53, 1.0
	v_bfe_u32 v54, v53, 16, 1
	v_add3_u32 v54, v53, v54, s78
	v_add_u32_e32 v53, 0x550, v52
	v_lshl_add_u32 v52, v106, 1, v53
	ds_write_b16_d16_hi v52, v54
	v_add3_u32 v54, s90, v96, 41
	s_and_b64 vcc, exec, s[6:7]
	v_cmp_lt_i32_e64 s[18:19], s76, v54
	v_mul_f32_e32 v54, 0xbfb8aa3b, v5
	v_exp_f32_e32 v54, v54
	s_nop 0
	v_add_f32_e32 v54, 1.0, v54
	v_div_scale_f32 v55, s[20:21], v54, v54, 1.0
	v_rcp_f32_e32 v56, v55
	v_div_scale_f32 v57, vcc, 1.0, v54, 1.0
	v_fma_f32 v58, -v55, v56, 1.0
	v_fmac_f32_e32 v56, v58, v56
	v_mul_f32_e32 v58, v57, v56
	v_fma_f32 v59, -v55, v58, v57
	v_fmac_f32_e32 v58, v59, v56
	v_fma_f32 v55, -v55, v58, v57
	v_div_fmas_f32 v55, v55, v56, v58
	v_div_fixup_f32 v54, v55, v54, 1.0
	v_bfe_u32 v55, v54, 16, 1
	v_add3_u32 v55, v54, v55, s78
	v_add_u32_e32 v54, 0x110, v53
	v_lshl_add_u32 v53, v106, 1, v54
	ds_write_b16_d16_hi v53, v55
	v_add3_u32 v55, s90, v96, 42
	s_and_b64 vcc, exec, s[6:7]
	v_cmp_lt_i32_e64 s[20:21], s76, v55
	v_mul_f32_e32 v55, 0xbfb8aa3b, v6
	v_exp_f32_e32 v55, v55
	s_nop 0
	v_add_f32_e32 v55, 1.0, v55
	v_div_scale_f32 v56, s[22:23], v55, v55, 1.0
	v_rcp_f32_e32 v57, v56
	v_div_scale_f32 v58, vcc, 1.0, v55, 1.0
	v_fma_f32 v59, -v56, v57, 1.0
	v_fmac_f32_e32 v57, v59, v57
	v_mul_f32_e32 v59, v58, v57
	v_fma_f32 v60, -v56, v59, v58
	v_fmac_f32_e32 v59, v60, v57
	v_fma_f32 v56, -v56, v59, v58
	v_div_fmas_f32 v56, v56, v57, v59
	v_div_fixup_f32 v55, v56, v55, 1.0
	v_bfe_u32 v56, v55, 16, 1
	v_add3_u32 v56, v55, v56, s78
	v_add_u32_e32 v55, 0x110, v54
	v_lshl_add_u32 v54, v106, 1, v55
	ds_write_b16_d16_hi v54, v56
	v_add3_u32 v56, s90, v96, 43
	s_and_b64 vcc, exec, s[6:7]
	v_cmp_lt_i32_e64 s[22:23], s76, v56
	v_mul_f32_e32 v56, 0xbfb8aa3b, v7
	v_exp_f32_e32 v56, v56
	s_nop 0
	v_add_f32_e32 v56, 1.0, v56
	v_div_scale_f32 v57, s[24:25], v56, v56, 1.0
	v_rcp_f32_e32 v58, v57
	v_div_scale_f32 v59, vcc, 1.0, v56, 1.0
	v_fma_f32 v60, -v57, v58, 1.0
	v_fmac_f32_e32 v58, v60, v58
	v_mul_f32_e32 v60, v59, v58
	v_fma_f32 v61, -v57, v60, v59
	v_fmac_f32_e32 v60, v61, v58
	v_fma_f32 v57, -v57, v60, v59
	v_div_fmas_f32 v57, v57, v58, v60
	v_div_fixup_f32 v56, v57, v56, 1.0
	v_bfe_u32 v57, v56, 16, 1
	v_add_u32_e32 v55, 0x110, v55
	v_add3_u32 v57, v56, v57, s78
	v_lshl_add_u32 v56, v106, 1, v55
	ds_write_b16_d16_hi v56, v57
	v_add3_u32 v57, s90, v96, 48
	s_and_b64 vcc, exec, s[6:7]
	v_cmp_lt_i32_e64 s[24:25], s76, v57
	v_mul_f32_e32 v57, 0xbfb8aa3b, v8
	v_exp_f32_e32 v57, v57
	s_nop 0
	v_add_f32_e32 v57, 1.0, v57
	v_div_scale_f32 v58, s[26:27], v57, v57, 1.0
	v_rcp_f32_e32 v59, v58
	v_div_scale_f32 v60, vcc, 1.0, v57, 1.0
	v_fma_f32 v61, -v58, v59, 1.0
	v_fmac_f32_e32 v59, v61, v59
	v_mul_f32_e32 v61, v60, v59
	v_fma_f32 v62, -v58, v61, v60
	v_fmac_f32_e32 v61, v62, v59
	v_fma_f32 v58, -v58, v61, v60
	v_div_fmas_f32 v58, v58, v59, v61
	v_div_fixup_f32 v57, v58, v57, 1.0
	v_bfe_u32 v58, v57, 16, 1
	v_add_u32_e32 v55, 0x550, v55
	v_add3_u32 v58, v57, v58, s78
	v_lshl_add_u32 v57, v106, 1, v55
	ds_write_b16_d16_hi v57, v58
	v_add3_u32 v58, s90, v96, 49
	s_and_b64 vcc, exec, s[6:7]
	v_cmp_lt_i32_e64 s[26:27], s76, v58
; __device__ __forceinline__ bf16r f2bf(float f) {
;   unsigned u = __float_as_uint(f);
;   u += 0x7fffu + ((u >> 16) & 1u);
;   return (bf16r)(u >> 16);
; }
; __device__ __forceinline__ unsigned pack2(float a, float b) { return (unsigned)f2bf(a) | ((unsigned)f2bf(b) << 16); }
; __device__ __forceinline__ float lo16(unsigned v) { return __uint_as_float(v << 16); }
; __device__ __forceinline__ float hi16(unsigned v) { return __uint_as_float(v & 0xffff0000u); }
; __device__ __forceinline__ float siluf(float x) { return x / (1.f + __expf(-x)); }
; __device__ __forceinline__ float sigmf(float x) { return 1.f / (1.f + __expf(-x)); }
; __device__ __forceinline__ void inproj_epilogue(const Params& p, int layer, int mt, int ntile, int tid,
;                                                 f32x16 (&acc)[2][2], unsigned char* smem) {
;     ...
;     acc_foreach(tid, acc, [&](int row, int col, float v) {
;       int t = m0 + row;
;       float o = v;
;       if (mode == 1) o = (t >= NPADR) ? v : 0.f;
;       if (mode == 2) o = sigmf(v);
;       sT[row * 136 + col] = f2bf(o);
;     });
	v_mul_f32_e32 v58, 0xbfb8aa3b, v9
	v_exp_f32_e32 v58, v58
	s_nop 0
	v_add_f32_e32 v58, 1.0, v58
	v_div_scale_f32 v59, s[28:29], v58, v58, 1.0
	v_rcp_f32_e32 v60, v59
	v_div_scale_f32 v61, vcc, 1.0, v58, 1.0
	v_fma_f32 v62, -v59, v60, 1.0
	v_fmac_f32_e32 v60, v62, v60
	v_mul_f32_e32 v62, v61, v60
	v_fma_f32 v63, -v59, v62, v61
	v_fmac_f32_e32 v62, v63, v60
	v_fma_f32 v59, -v59, v62, v61
	v_div_fmas_f32 v59, v59, v60, v62
	v_div_fixup_f32 v58, v59, v58, 1.0
	v_bfe_u32 v59, v58, 16, 1
	v_add_u32_e32 v55, 0x110, v55
	v_add3_u32 v59, v58, v59, s78
	v_lshl_add_u32 v58, v106, 1, v55
	ds_write_b16_d16_hi v58, v59
	v_add3_u32 v59, s90, v96, 50
	s_and_b64 vcc, exec, s[6:7]
	v_cmp_lt_i32_e64 s[28:29], s76, v59
	v_mul_f32_e32 v59, 0xbfb8aa3b, v10
	v_exp_f32_e32 v59, v59
	s_nop 0
	v_add_f32_e32 v59, 1.0, v59
	v_div_scale_f32 v60, s[30:31], v59, v59, 1.0
	v_rcp_f32_e32 v61, v60
	v_div_scale_f32 v62, vcc, 1.0, v59, 1.0
	v_fma_f32 v63, -v60, v61, 1.0
	v_fmac_f32_e32 v61, v63, v61
	v_mul_f32_e32 v63, v62, v61
	v_fma_f32 v107, -v60, v63, v62
	v_fmac_f32_e32 v63, v107, v61
	v_fma_f32 v60, -v60, v63, v62
	v_div_fmas_f32 v60, v60, v61, v63
	v_div_fixup_f32 v59, v60, v59, 1.0
	v_bfe_u32 v60, v59, 16, 1
	v_add_u32_e32 v55, 0x110, v55
	v_add3_u32 v60, v59, v60, s78
	v_lshl_add_u32 v59, v106, 1, v55
	ds_write_b16_d16_hi v59, v60
	v_add3_u32 v60, s90, v96, 51
	s_and_b64 vcc, exec, s[6:7]
	v_cmp_lt_i32_e64 s[30:31], s76, v60
	v_mul_f32_e32 v60, 0xbfb8aa3b, v11
	v_exp_f32_e32 v60, v60
	s_nop 0
	v_add_f32_e32 v60, 1.0, v60
	v_div_scale_f32 v61, s[34:35], v60, v60, 1.0
	v_rcp_f32_e32 v62, v61
	v_div_scale_f32 v63, vcc, 1.0, v60, 1.0
	v_fma_f32 v107, -v61, v62, 1.0
	v_fmac_f32_e32 v62, v107, v62
	v_mul_f32_e32 v107, v63, v62
	v_fma_f32 v110, -v61, v107, v63
	v_fmac_f32_e32 v107, v110, v62
	v_fma_f32 v61, -v61, v107, v63
	v_div_fmas_f32 v61, v61, v62, v107
	v_div_fixup_f32 v60, v61, v60, 1.0
	v_bfe_u32 v61, v60, 16, 1
	v_add_u32_e32 v55, 0x110, v55
	v_add3_u32 v61, v60, v61, s78
	v_lshl_add_u32 v60, v106, 1, v55
	ds_write_b16_d16_hi v60, v61
	v_add3_u32 v61, s90, v96, 56
	s_and_b64 vcc, exec, s[6:7]
	v_cmp_lt_i32_e64 s[34:35], s76, v61
	v_mul_f32_e32 v61, 0xbfb8aa3b, v12
	v_exp_f32_e32 v61, v61
	s_nop 0
	v_add_f32_e32 v61, 1.0, v61
	v_div_scale_f32 v62, s[36:37], v61, v61, 1.0
	v_rcp_f32_e32 v63, v62
	v_div_scale_f32 v107, vcc, 1.0, v61, 1.0
	v_fma_f32 v110, -v62, v63, 1.0
	v_fmac_f32_e32 v63, v110, v63
	v_mul_f32_e32 v110, v107, v63
	v_fma_f32 v111, -v62, v110, v107
	v_fmac_f32_e32 v110, v111, v63
	v_fma_f32 v62, -v62, v110, v107
	v_div_fmas_f32 v62, v62, v63, v110
	v_div_fixup_f32 v61, v62, v61, 1.0
	v_bfe_u32 v62, v61, 16, 1
	v_add_u32_e32 v55, 0x550, v55
	v_add3_u32 v62, v61, v62, s78
	v_lshl_add_u32 v61, v106, 1, v55
	ds_write_b16_d16_hi v61, v62
	v_add3_u32 v62, s90, v96, 57
	s_and_b64 vcc, exec, s[6:7]
	v_cmp_lt_i32_e64 s[36:37], s76, v62
	v_mul_f32_e32 v62, 0xbfb8aa3b, v13
	v_exp_f32_e32 v62, v62
	s_nop 0
	v_add_f32_e32 v62, 1.0, v62
	v_div_scale_f32 v63, s[38:39], v62, v62, 1.0
	v_rcp_f32_e32 v107, v63
	v_div_scale_f32 v110, vcc, 1.0, v62, 1.0
	v_fma_f32 v111, -v63, v107, 1.0
	v_fmac_f32_e32 v107, v111, v107
	v_mul_f32_e32 v111, v110, v107
	v_fma_f32 v112, -v63, v111, v110
	v_fmac_f32_e32 v111, v112, v107
	v_fma_f32 v63, -v63, v111, v110
	v_div_fmas_f32 v63, v63, v107, v111
	v_div_fixup_f32 v62, v63, v62, 1.0
	v_bfe_u32 v63, v62, 16, 1
	v_add_u32_e32 v55, 0x110, v55
	v_add3_u32 v63, v62, v63, s78
	v_lshl_add_u32 v62, v106, 1, v55
	ds_write_b16_d16_hi v62, v63
	v_add3_u32 v63, s90, v96, 58
	s_and_b64 vcc, exec, s[6:7]
	v_cmp_lt_i32_e64 s[38:39], s76, v63
	v_mul_f32_e32 v63, 0xbfb8aa3b, v14
	v_exp_f32_e32 v63, v63
	s_nop 0
	v_add_f32_e32 v63, 1.0, v63
	v_div_scale_f32 v107, s[40:41], v63, v63, 1.0
	v_rcp_f32_e32 v110, v107
	v_div_scale_f32 v111, vcc, 1.0, v63, 1.0
	v_fma_f32 v112, -v107, v110, 1.0
	v_fmac_f32_e32 v110, v112, v110
	v_mul_f32_e32 v112, v111, v110
	v_fma_f32 v113, -v107, v112, v111
	v_fmac_f32_e32 v112, v113, v110
	v_fma_f32 v107, -v107, v112, v111
	v_div_fmas_f32 v107, v107, v110, v112
	v_div_fixup_f32 v63, v107, v63, 1.0
	v_bfe_u32 v107, v63, 16, 1
	v_add_u32_e32 v55, 0x110, v55
	v_add3_u32 v63, v63, v107, s78
	v_lshl_add_u32 v55, v106, 1, v55
	ds_write_b16_d16_hi v55, v63
	v_add3_u32 v63, s90, v96, 59
	s_and_b64 vcc, exec, s[6:7]
	v_cmp_lt_i32_e64 s[40:41], s76, v63
	v_mul_f32_e32 v63, 0xbfb8aa3b, v15
	v_exp_f32_e32 v63, v63
	s_nop 0
	v_add_f32_e32 v63, 1.0, v63
	v_div_scale_f32 v96, vcc, v63, v63, 1.0
	v_rcp_f32_e32 v106, v96
	v_div_scale_f32 v107, vcc, 1.0, v63, 1.0
	v_fma_f32 v110, -v96, v106, 1.0
	v_fmac_f32_e32 v106, v110, v106
	v_mul_f32_e32 v110, v107, v106
	v_fma_f32 v111, -v96, v110, v107
	v_fmac_f32_e32 v110, v111, v106
	v_fma_f32 v96, -v96, v110, v107
	v_div_fmas_f32 v96, v96, v106, v110
	v_div_fixup_f32 v63, v96, v63, 1.0
	v_bfe_u32 v96, v63, 16, 1
	v_add3_u32 v63, v63, v96, s78
	ds_write_b16_d16_hi v55, v63 offset:272
	s_and_b64 vcc, exec, s[6:7]
	v_mul_f32_e32 v32, 0xbfb8aa3b, v32
	v_exp_f32_e32 v32, v32
	s_nop 0
	v_add_f32_e32 v32, 1.0, v32
	v_div_scale_f32 v63, s[8:9], v32, v32, 1.0
	v_rcp_f32_e32 v96, v63
	v_div_scale_f32 v106, vcc, 1.0, v32, 1.0
	v_fma_f32 v107, -v63, v96, 1.0
	v_fmac_f32_e32 v96, v107, v96
	v_mul_f32_e32 v107, v106, v96
	v_fma_f32 v110, -v63, v107, v106
	v_fmac_f32_e32 v107, v110, v96
	v_fma_f32 v63, -v63, v107, v106
	v_div_fmas_f32 v63, v63, v96, v107
	v_div_fixup_f32 v32, v63, v32, 1.0
	v_bfe_u32 v63, v32, 16, 1
	v_add3_u32 v32, v32, v63, s78
	s_and_b64 vcc, exec, s[6:7]
	ds_write_b16_d16_hi v48, v32 offset:64
	v_mul_f32_e32 v32, 0xbfb8aa3b, v33
	v_exp_f32_e32 v32, v32
	s_nop 0
	v_add_f32_e32 v32, 1.0, v32
; __device__ __forceinline__ bf16r f2bf(float f) {
;   unsigned u = __float_as_uint(f);
;   u += 0x7fffu + ((u >> 16) & 1u);
;   return (bf16r)(u >> 16);
; }
; __device__ __forceinline__ unsigned pack2(float a, float b) { return (unsigned)f2bf(a) | ((unsigned)f2bf(b) << 16); }
; __device__ __forceinline__ float lo16(unsigned v) { return __uint_as_float(v << 16); }
; __device__ __forceinline__ float hi16(unsigned v) { return __uint_as_float(v & 0xffff0000u); }
; __device__ __forceinline__ float siluf(float x) { return x / (1.f + __expf(-x)); }
; __device__ __forceinline__ float sigmf(float x) { return 1.f / (1.f + __expf(-x)); }
; __device__ __forceinline__ void inproj_epilogue(const Params& p, int layer, int mt, int ntile, int tid,
;                                                 f32x16 (&acc)[2][2], unsigned char* smem) {
;     ...
;     acc_foreach(tid, acc, [&](int row, int col, float v) {
;       int t = m0 + row;
;       float o = v;
;       if (mode == 1) o = (t >= NPADR) ? v : 0.f;
;       if (mode == 2) o = sigmf(v);
;       sT[row * 136 + col] = f2bf(o);
;     });
	v_div_scale_f32 v33, s[8:9], v32, v32, 1.0
	v_rcp_f32_e32 v48, v33
	v_div_scale_f32 v63, vcc, 1.0, v32, 1.0
	v_fma_f32 v96, -v33, v48, 1.0
	v_fmac_f32_e32 v48, v96, v48
	v_mul_f32_e32 v96, v63, v48
	v_fma_f32 v106, -v33, v96, v63
	v_fmac_f32_e32 v96, v106, v48
	v_fma_f32 v33, -v33, v96, v63
	v_div_fmas_f32 v33, v33, v48, v96
	v_div_fixup_f32 v32, v33, v32, 1.0
	v_bfe_u32 v33, v32, 16, 1
	v_add3_u32 v32, v32, v33, s78
	s_and_b64 vcc, exec, s[6:7]
	ds_write_b16_d16_hi v49, v32 offset:64
	v_mul_f32_e32 v32, 0xbfb8aa3b, v34
	v_exp_f32_e32 v32, v32
	s_nop 0
	v_add_f32_e32 v32, 1.0, v32
	v_div_scale_f32 v33, s[8:9], v32, v32, 1.0
	v_rcp_f32_e32 v34, v33
	v_div_scale_f32 v48, vcc, 1.0, v32, 1.0
	v_fma_f32 v49, -v33, v34, 1.0
	v_fmac_f32_e32 v34, v49, v34
	v_mul_f32_e32 v49, v48, v34
	v_fma_f32 v63, -v33, v49, v48
	v_fmac_f32_e32 v49, v63, v34
	v_fma_f32 v33, -v33, v49, v48
	v_div_fmas_f32 v33, v33, v34, v49
	v_div_fixup_f32 v32, v33, v32, 1.0
	v_bfe_u32 v33, v32, 16, 1
	v_add3_u32 v32, v32, v33, s78
	s_and_b64 vcc, exec, s[6:7]
	ds_write_b16_d16_hi v50, v32 offset:64
	v_mul_f32_e32 v32, 0xbfb8aa3b, v35
	v_exp_f32_e32 v32, v32
	s_nop 0
	v_add_f32_e32 v32, 1.0, v32
	v_div_scale_f32 v33, s[8:9], v32, v32, 1.0
	v_rcp_f32_e32 v34, v33
	v_div_scale_f32 v35, vcc, 1.0, v32, 1.0
	v_fma_f32 v48, -v33, v34, 1.0
	v_fmac_f32_e32 v34, v48, v34
	v_mul_f32_e32 v48, v35, v34
	v_fma_f32 v49, -v33, v48, v35
	v_fmac_f32_e32 v48, v49, v34
	v_fma_f32 v33, -v33, v48, v35
	v_div_fmas_f32 v33, v33, v34, v48
	v_div_fixup_f32 v32, v33, v32, 1.0
	v_bfe_u32 v33, v32, 16, 1
	v_add3_u32 v32, v32, v33, s78
	s_and_b64 vcc, exec, s[6:7]
	ds_write_b16_d16_hi v51, v32 offset:64
	v_mul_f32_e32 v32, 0xbfb8aa3b, v36
	v_exp_f32_e32 v32, v32
	s_nop 0
	v_add_f32_e32 v32, 1.0, v32
	v_div_scale_f32 v33, s[8:9], v32, v32, 1.0
	v_rcp_f32_e32 v34, v33
	v_div_scale_f32 v35, vcc, 1.0, v32, 1.0
	v_fma_f32 v36, -v33, v34, 1.0
	v_fmac_f32_e32 v34, v36, v34
	v_mul_f32_e32 v36, v35, v34
	v_fma_f32 v48, -v33, v36, v35
	v_fmac_f32_e32 v36, v48, v34
	v_fma_f32 v33, -v33, v36, v35
	v_div_fmas_f32 v33, v33, v34, v36
	v_div_fixup_f32 v32, v33, v32, 1.0
	v_bfe_u32 v33, v32, 16, 1
	v_add3_u32 v32, v32, v33, s78
	s_and_b64 vcc, exec, s[6:7]
	ds_write_b16_d16_hi v52, v32 offset:64
	v_mul_f32_e32 v32, 0xbfb8aa3b, v37
	v_exp_f32_e32 v32, v32
	s_nop 0
	v_add_f32_e32 v32, 1.0, v32
	v_div_scale_f32 v33, s[8:9], v32, v32, 1.0
	v_rcp_f32_e32 v34, v33
	v_div_scale_f32 v35, vcc, 1.0, v32, 1.0
	v_fma_f32 v36, -v33, v34, 1.0
	v_fmac_f32_e32 v34, v36, v34
	v_mul_f32_e32 v36, v35, v34
	v_fma_f32 v37, -v33, v36, v35
	v_fmac_f32_e32 v36, v37, v34
	v_fma_f32 v33, -v33, v36, v35
	v_div_fmas_f32 v33, v33, v34, v36
	v_div_fixup_f32 v32, v33, v32, 1.0
	v_bfe_u32 v33, v32, 16, 1
	v_add3_u32 v32, v32, v33, s78
	s_and_b64 vcc, exec, s[6:7]
	ds_write_b16_d16_hi v53, v32 offset:64
	v_mul_f32_e32 v32, 0xbfb8aa3b, v38
	v_exp_f32_e32 v32, v32
	s_nop 0
	v_add_f32_e32 v32, 1.0, v32
	v_div_scale_f32 v33, s[8:9], v32, v32, 1.0
	v_rcp_f32_e32 v34, v33
	v_div_scale_f32 v35, vcc, 1.0, v32, 1.0
	v_fma_f32 v36, -v33, v34, 1.0
	v_fmac_f32_e32 v34, v36, v34
	v_mul_f32_e32 v36, v35, v34
	v_fma_f32 v37, -v33, v36, v35
	v_fmac_f32_e32 v36, v37, v34
	v_fma_f32 v33, -v33, v36, v35
	v_div_fmas_f32 v33, v33, v34, v36
	v_div_fixup_f32 v32, v33, v32, 1.0
	v_bfe_u32 v33, v32, 16, 1
	v_add3_u32 v32, v32, v33, s78
	s_and_b64 vcc, exec, s[6:7]
	ds_write_b16_d16_hi v54, v32 offset:64
	v_mul_f32_e32 v32, 0xbfb8aa3b, v39
	v_exp_f32_e32 v32, v32
	s_nop 0
	v_add_f32_e32 v32, 1.0, v32
	v_div_scale_f32 v33, s[8:9], v32, v32, 1.0
	v_rcp_f32_e32 v34, v33
	v_div_scale_f32 v35, vcc, 1.0, v32, 1.0
	v_fma_f32 v36, -v33, v34, 1.0
	v_fmac_f32_e32 v34, v36, v34
	v_mul_f32_e32 v36, v35, v34
	v_fma_f32 v37, -v33, v36, v35
	v_fmac_f32_e32 v36, v37, v34
	v_fma_f32 v33, -v33, v36, v35
	v_div_fmas_f32 v33, v33, v34, v36
	v_div_fixup_f32 v32, v33, v32, 1.0
	v_bfe_u32 v33, v32, 16, 1
	v_add3_u32 v32, v32, v33, s78
	s_and_b64 vcc, exec, s[6:7]
	ds_write_b16_d16_hi v56, v32 offset:64
	v_mul_f32_e32 v32, 0xbfb8aa3b, v40
	v_exp_f32_e32 v32, v32
	s_nop 0
	v_add_f32_e32 v32, 1.0, v32
	v_div_scale_f32 v33, s[8:9], v32, v32, 1.0
	v_rcp_f32_e32 v34, v33
	v_div_scale_f32 v35, vcc, 1.0, v32, 1.0
	v_fma_f32 v36, -v33, v34, 1.0
	v_fmac_f32_e32 v34, v36, v34
	v_mul_f32_e32 v36, v35, v34
; __device__ __forceinline__ bf16r f2bf(float f) {
;   unsigned u = __float_as_uint(f);
;   u += 0x7fffu + ((u >> 16) & 1u);
;   return (bf16r)(u >> 16);
; }
; __device__ __forceinline__ unsigned pack2(float a, float b) { return (unsigned)f2bf(a) | ((unsigned)f2bf(b) << 16); }
; __device__ __forceinline__ float lo16(unsigned v) { return __uint_as_float(v << 16); }
; __device__ __forceinline__ float hi16(unsigned v) { return __uint_as_float(v & 0xffff0000u); }
; __device__ __forceinline__ float siluf(float x) { return x / (1.f + __expf(-x)); }
; __device__ __forceinline__ float sigmf(float x) { return 1.f / (1.f + __expf(-x)); }
; __device__ __forceinline__ void inproj_epilogue(const Params& p, int layer, int mt, int ntile, int tid,
;                                                 f32x16 (&acc)[2][2], unsigned char* smem) {
;     ...
;     acc_foreach(tid, acc, [&](int row, int col, float v) {
;       int t = m0 + row;
;       float o = v;
;       if (mode == 1) o = (t >= NPADR) ? v : 0.f;
;       if (mode == 2) o = sigmf(v);
;       sT[row * 136 + col] = f2bf(o);
;     });
	v_fma_f32 v37, -v33, v36, v35
	v_fmac_f32_e32 v36, v37, v34
	v_fma_f32 v33, -v33, v36, v35
	v_div_fmas_f32 v33, v33, v34, v36
	v_div_fixup_f32 v32, v33, v32, 1.0
	v_bfe_u32 v33, v32, 16, 1
	v_add3_u32 v32, v32, v33, s78
	s_and_b64 vcc, exec, s[6:7]
	ds_write_b16_d16_hi v57, v32 offset:64
	v_mul_f32_e32 v32, 0xbfb8aa3b, v41
	v_exp_f32_e32 v32, v32
	s_nop 0
	v_add_f32_e32 v32, 1.0, v32
	v_div_scale_f32 v33, s[8:9], v32, v32, 1.0
	v_rcp_f32_e32 v34, v33
	v_div_scale_f32 v35, vcc, 1.0, v32, 1.0
	v_fma_f32 v36, -v33, v34, 1.0
	v_fmac_f32_e32 v34, v36, v34
	v_mul_f32_e32 v36, v35, v34
	v_fma_f32 v37, -v33, v36, v35
	v_fmac_f32_e32 v36, v37, v34
	v_fma_f32 v33, -v33, v36, v35
	v_div_fmas_f32 v33, v33, v34, v36
	v_div_fixup_f32 v32, v33, v32, 1.0
	v_bfe_u32 v33, v32, 16, 1
	v_add3_u32 v32, v32, v33, s78
	s_and_b64 vcc, exec, s[6:7]
	ds_write_b16_d16_hi v58, v32 offset:64
	v_mul_f32_e32 v32, 0xbfb8aa3b, v42
	v_exp_f32_e32 v32, v32
	s_nop 0
	v_add_f32_e32 v32, 1.0, v32
	v_div_scale_f32 v33, s[8:9], v32, v32, 1.0
	v_rcp_f32_e32 v34, v33
	v_div_scale_f32 v35, vcc, 1.0, v32, 1.0
	v_fma_f32 v36, -v33, v34, 1.0
	v_fmac_f32_e32 v34, v36, v34
	v_mul_f32_e32 v36, v35, v34
	v_fma_f32 v37, -v33, v36, v35
	v_fmac_f32_e32 v36, v37, v34
	v_fma_f32 v33, -v33, v36, v35
	v_div_fmas_f32 v33, v33, v34, v36
	v_div_fixup_f32 v32, v33, v32, 1.0
	v_bfe_u32 v33, v32, 16, 1
	v_add3_u32 v32, v32, v33, s78
	s_and_b64 vcc, exec, s[6:7]
	ds_write_b16_d16_hi v59, v32 offset:64
	v_mul_f32_e32 v32, 0xbfb8aa3b, v43
	v_exp_f32_e32 v32, v32
	s_nop 0
	v_add_f32_e32 v32, 1.0, v32
	v_div_scale_f32 v33, s[8:9], v32, v32, 1.0
	v_rcp_f32_e32 v34, v33
	v_div_scale_f32 v35, vcc, 1.0, v32, 1.0
	v_fma_f32 v36, -v33, v34, 1.0
	v_fmac_f32_e32 v34, v36, v34
	v_mul_f32_e32 v36, v35, v34
	v_fma_f32 v37, -v33, v36, v35
	v_fmac_f32_e32 v36, v37, v34
	v_fma_f32 v33, -v33, v36, v35
	v_div_fmas_f32 v33, v33, v34, v36
	v_div_fixup_f32 v32, v33, v32, 1.0
	v_bfe_u32 v33, v32, 16, 1
	v_add3_u32 v32, v32, v33, s78
	s_and_b64 vcc, exec, s[6:7]
	ds_write_b16_d16_hi v60, v32 offset:64
	v_mul_f32_e32 v32, 0xbfb8aa3b, v44
	v_exp_f32_e32 v32, v32
	s_nop 0
	v_add_f32_e32 v32, 1.0, v32
	v_div_scale_f32 v33, s[8:9], v32, v32, 1.0
	v_rcp_f32_e32 v34, v33
	v_div_scale_f32 v35, vcc, 1.0, v32, 1.0
	v_fma_f32 v36, -v33, v34, 1.0
	v_fmac_f32_e32 v34, v36, v34
	v_mul_f32_e32 v36, v35, v34
	v_fma_f32 v37, -v33, v36, v35
	v_fmac_f32_e32 v36, v37, v34
	v_fma_f32 v33, -v33, v36, v35
	v_div_fmas_f32 v33, v33, v34, v36
	v_div_fixup_f32 v32, v33, v32, 1.0
	v_bfe_u32 v33, v32, 16, 1
	v_add3_u32 v32, v32, v33, s78
	s_and_b64 vcc, exec, s[6:7]
	ds_write_b16_d16_hi v61, v32 offset:64
	v_mul_f32_e32 v32, 0xbfb8aa3b, v45
	v_exp_f32_e32 v32, v32
	s_nop 0
	v_add_f32_e32 v32, 1.0, v32
	v_div_scale_f32 v33, s[8:9], v32, v32, 1.0
	v_rcp_f32_e32 v34, v33
	v_div_scale_f32 v35, vcc, 1.0, v32, 1.0
	v_fma_f32 v36, -v33, v34, 1.0
	v_fmac_f32_e32 v34, v36, v34
	v_mul_f32_e32 v36, v35, v34
	v_fma_f32 v37, -v33, v36, v35
	v_fmac_f32_e32 v36, v37, v34
	v_fma_f32 v33, -v33, v36, v35
	v_div_fmas_f32 v33, v33, v34, v36
	v_div_fixup_f32 v32, v33, v32, 1.0
	v_bfe_u32 v33, v32, 16, 1
	v_add3_u32 v32, v32, v33, s78
	s_and_b64 vcc, exec, s[6:7]
	ds_write_b16_d16_hi v62, v32 offset:64
	v_mul_f32_e32 v32, 0xbfb8aa3b, v46
	v_exp_f32_e32 v32, v32
	s_nop 0
	v_add_f32_e32 v32, 1.0, v32
	v_div_scale_f32 v33, s[8:9], v32, v32, 1.0
	v_rcp_f32_e32 v34, v33
	v_div_scale_f32 v35, vcc, 1.0, v32, 1.0
	v_fma_f32 v36, -v33, v34, 1.0
	v_fmac_f32_e32 v34, v36, v34
	v_mul_f32_e32 v36, v35, v34
	v_fma_f32 v37, -v33, v36, v35
	v_fmac_f32_e32 v36, v37, v34
	v_fma_f32 v33, -v33, v36, v35
	v_div_fmas_f32 v33, v33, v34, v36
	v_div_fixup_f32 v32, v33, v32, 1.0
	v_bfe_u32 v33, v32, 16, 1
	v_add3_u32 v32, v32, v33, s78
	s_and_b64 vcc, exec, s[6:7]
	ds_write_b16_d16_hi v55, v32 offset:64
	v_mul_f32_e32 v32, 0xbfb8aa3b, v47
	v_exp_f32_e32 v32, v32
	s_nop 0
	v_add_f32_e32 v32, 1.0, v32
	v_div_scale_f32 v33, s[4:5], v32, v32, 1.0
	v_rcp_f32_e32 v34, v33
	v_div_scale_f32 v35, vcc, 1.0, v32, 1.0
	v_fma_f32 v36, -v33, v34, 1.0
	v_fmac_f32_e32 v34, v36, v34
	v_mul_f32_e32 v36, v35, v34
	v_fma_f32 v37, -v33, v36, v35
	v_fmac_f32_e32 v36, v37, v34
	v_fma_f32 v33, -v33, v36, v35
	v_div_fmas_f32 v33, v33, v34, v36
	v_div_fixup_f32 v32, v33, v32, 1.0
	s_branch .LBB0_717

; __device__ __forceinline__ float sigmf(float x) { return 1.f / (1.f + __expf(-x)); }
; __device__ __forceinline__ bf16r f2bf(float f) {
;   unsigned u = __float_as_uint(f);
;   u += 0x7fffu + ((u >> 16) & 1u);
;   return (bf16r)(u >> 16);
; }
; __device__ __forceinline__ void inproj_epilogue(const Params& p, int layer, int mt, int ntile, int tid,
;                                                 f32x16 (&acc)[2][2], unsigned char* smem) {
;     ...
;     acc_foreach(tid, acc, [&](int row, int col, float v) {
;       int t = m0 + row;
;       float o = v;
;       if (mode == 1) o = (t >= NPADR) ? v : 0.f;
;       if (mode == 2) o = sigmf(v);
;       sT[row * 136 + col] = f2bf(o);
;     });
.LBB0_862:
	v_bfe_u32 v110, v107, 16, 1
	v_and_b32_e32 v106, 0x5f, v106
	v_add3_u32 v111, v107, v110, s79
	v_mul_lo_u32 v110, v96, s80
	v_lshl_add_u32 v107, v106, 1, v110
	ds_write_b16_d16_hi v107, v111
	v_add3_u32 v111, s0, v96, 1
	v_cmp_lt_i32_e64 s[10:11], s77, v111
	v_cndmask_b32_e64 v111, 0, 1, s[12:13]
	v_cmp_ne_u32_e64 s[6:7], 1, v111
	s_nop 1

; __device__ __forceinline__ float sigmf(float x) { return 1.f / (1.f + __expf(-x)); }
; __device__ __forceinline__ bf16r f2bf(float f) {
;   unsigned u = __float_as_uint(f);
;   u += 0x7fffu + ((u >> 16) & 1u);
;   return (bf16r)(u >> 16);
; }
; __device__ __forceinline__ void inproj_epilogue(const Params& p, int layer, int mt, int ntile, int tid,
;                                                 f32x16 (&acc)[2][2], unsigned char* smem) {
;     ...
;     acc_foreach(tid, acc, [&](int row, int col, float v) {
;       int t = m0 + row;
;       float o = v;
;       if (mode == 1) o = (t >= NPADR) ? v : 0.f;
;       if (mode == 2) o = sigmf(v);
;       sT[row * 136 + col] = f2bf(o);
;     });
.LBB0_865:
	v_bfe_u32 v112, v111, 16, 1
	v_add3_u32 v112, v111, v112, s79
	v_add_u32_e32 v111, 0x110, v110
	v_lshl_add_u32 v110, v106, 1, v111
	ds_write_b16_d16_hi v110, v112
	v_add3_u32 v112, s0, v96, 2
	v_cmp_lt_i32_e64 s[12:13], s77, v112
	s_nop 1

; __device__ __forceinline__ float sigmf(float x) { return 1.f / (1.f + __expf(-x)); }
; __device__ __forceinline__ bf16r f2bf(float f) {
;   unsigned u = __float_as_uint(f);
;   u += 0x7fffu + ((u >> 16) & 1u);
;   return (bf16r)(u >> 16);
; }
; __device__ __forceinline__ void inproj_epilogue(const Params& p, int layer, int mt, int ntile, int tid,
;                                                 f32x16 (&acc)[2][2], unsigned char* smem) {
;     ...
;     acc_foreach(tid, acc, [&](int row, int col, float v) {
;       int t = m0 + row;
;       float o = v;
;       if (mode == 1) o = (t >= NPADR) ? v : 0.f;
;       if (mode == 2) o = sigmf(v);
;       sT[row * 136 + col] = f2bf(o);
;     });
.LBB0_868:
	v_bfe_u32 v113, v112, 16, 1
	v_add3_u32 v113, v112, v113, s79
	v_add_u32_e32 v112, 0x110, v111
	v_lshl_add_u32 v111, v106, 1, v112
	ds_write_b16_d16_hi v111, v113
	v_add3_u32 v113, s0, v96, 3
	v_cmp_lt_i32_e64 s[14:15], s77, v113
	s_nop 1

; __device__ __forceinline__ float sigmf(float x) { return 1.f / (1.f + __expf(-x)); }
; __device__ __forceinline__ bf16r f2bf(float f) {
;   unsigned u = __float_as_uint(f);
;   u += 0x7fffu + ((u >> 16) & 1u);
;   return (bf16r)(u >> 16);
; }
; __device__ __forceinline__ void inproj_epilogue(const Params& p, int layer, int mt, int ntile, int tid,
;                                                 f32x16 (&acc)[2][2], unsigned char* smem) {
;     ...
;     acc_foreach(tid, acc, [&](int row, int col, float v) {
;       int t = m0 + row;
;       float o = v;
;       if (mode == 1) o = (t >= NPADR) ? v : 0.f;
;       if (mode == 2) o = sigmf(v);
;       sT[row * 136 + col] = f2bf(o);
;     });
.LBB0_871:
	v_bfe_u32 v114, v113, 16, 1
	v_add3_u32 v114, v113, v114, s79
	v_add_u32_e32 v113, 0x110, v112
	v_lshl_add_u32 v112, v106, 1, v113
	ds_write_b16_d16_hi v112, v114
	v_add3_u32 v114, s0, v96, 8
	v_cmp_lt_i32_e64 s[16:17], s77, v114
	s_nop 1

; __device__ __forceinline__ float sigmf(float x) { return 1.f / (1.f + __expf(-x)); }
; __device__ __forceinline__ bf16r f2bf(float f) {
;   unsigned u = __float_as_uint(f);
;   u += 0x7fffu + ((u >> 16) & 1u);
;   return (bf16r)(u >> 16);
; }
; __device__ __forceinline__ void inproj_epilogue(const Params& p, int layer, int mt, int ntile, int tid,
;                                                 f32x16 (&acc)[2][2], unsigned char* smem) {
;     ...
;     acc_foreach(tid, acc, [&](int row, int col, float v) {
;       int t = m0 + row;
;       float o = v;
;       if (mode == 1) o = (t >= NPADR) ? v : 0.f;
;       if (mode == 2) o = sigmf(v);
;       sT[row * 136 + col] = f2bf(o);
;     });
.LBB0_874:
	v_bfe_u32 v115, v114, 16, 1
	v_add3_u32 v115, v114, v115, s79
	v_add_u32_e32 v114, 0x550, v113
	v_lshl_add_u32 v113, v106, 1, v114
	ds_write_b16_d16_hi v113, v115
	v_add3_u32 v115, s0, v96, 9
	v_cmp_lt_i32_e64 s[18:19], s77, v115
	s_nop 1

; __device__ __forceinline__ float sigmf(float x) { return 1.f / (1.f + __expf(-x)); }
; __device__ __forceinline__ bf16r f2bf(float f) {
;   unsigned u = __float_as_uint(f);
;   u += 0x7fffu + ((u >> 16) & 1u);
;   return (bf16r)(u >> 16);
; }
; __device__ __forceinline__ void inproj_epilogue(const Params& p, int layer, int mt, int ntile, int tid,
;                                                 f32x16 (&acc)[2][2], unsigned char* smem) {
;     ...
;     acc_foreach(tid, acc, [&](int row, int col, float v) {
;       int t = m0 + row;
;       float o = v;
;       if (mode == 1) o = (t >= NPADR) ? v : 0.f;
;       if (mode == 2) o = sigmf(v);
;       sT[row * 136 + col] = f2bf(o);
;     });
.LBB0_877:
	v_bfe_u32 v116, v115, 16, 1
	v_add3_u32 v116, v115, v116, s79
	v_add_u32_e32 v115, 0x110, v114
	v_lshl_add_u32 v114, v106, 1, v115
	ds_write_b16_d16_hi v114, v116
	v_add3_u32 v116, s0, v96, 10
	v_cmp_lt_i32_e64 s[20:21], s77, v116
	s_nop 1

; __device__ __forceinline__ float sigmf(float x) { return 1.f / (1.f + __expf(-x)); }
; __device__ __forceinline__ bf16r f2bf(float f) {
;   unsigned u = __float_as_uint(f);
;   u += 0x7fffu + ((u >> 16) & 1u);
;   return (bf16r)(u >> 16);
; }
; __device__ __forceinline__ void inproj_epilogue(const Params& p, int layer, int mt, int ntile, int tid,
;                                                 f32x16 (&acc)[2][2], unsigned char* smem) {
;     ...
;     acc_foreach(tid, acc, [&](int row, int col, float v) {
;       int t = m0 + row;
;       float o = v;
;       if (mode == 1) o = (t >= NPADR) ? v : 0.f;
;       if (mode == 2) o = sigmf(v);
;       sT[row * 136 + col] = f2bf(o);
;     });
.LBB0_880:
	v_bfe_u32 v117, v116, 16, 1
	v_add3_u32 v117, v116, v117, s79
	v_add_u32_e32 v116, 0x110, v115
	v_lshl_add_u32 v115, v106, 1, v116
	ds_write_b16_d16_hi v115, v117
	v_add3_u32 v117, s0, v96, 11
	v_cmp_lt_i32_e64 s[22:23], s77, v117
	s_nop 1

; __device__ __forceinline__ float sigmf(float x) { return 1.f / (1.f + __expf(-x)); }
; __device__ __forceinline__ bf16r f2bf(float f) {
;   unsigned u = __float_as_uint(f);
;   u += 0x7fffu + ((u >> 16) & 1u);
;   return (bf16r)(u >> 16);
; }
; __device__ __forceinline__ void inproj_epilogue(const Params& p, int layer, int mt, int ntile, int tid,
;                                                 f32x16 (&acc)[2][2], unsigned char* smem) {
;     ...
;     acc_foreach(tid, acc, [&](int row, int col, float v) {
;       int t = m0 + row;
;       float o = v;
;       if (mode == 1) o = (t >= NPADR) ? v : 0.f;
;       if (mode == 2) o = sigmf(v);
;       sT[row * 136 + col] = f2bf(o);
;     });
.LBB0_883:
	v_bfe_u32 v118, v117, 16, 1
	v_add_u32_e32 v116, 0x110, v116
	v_add3_u32 v118, v117, v118, s79
	v_lshl_add_u32 v117, v106, 1, v116
	ds_write_b16_d16_hi v117, v118
	v_add3_u32 v118, s0, v96, 16
	v_cmp_lt_i32_e64 s[24:25], s77, v118
	s_nop 1

; __device__ __forceinline__ float sigmf(float x) { return 1.f / (1.f + __expf(-x)); }
; __device__ __forceinline__ bf16r f2bf(float f) {
;   unsigned u = __float_as_uint(f);
;   u += 0x7fffu + ((u >> 16) & 1u);
;   return (bf16r)(u >> 16);
; }
; __device__ __forceinline__ void inproj_epilogue(const Params& p, int layer, int mt, int ntile, int tid,
;                                                 f32x16 (&acc)[2][2], unsigned char* smem) {
;     ...
;     acc_foreach(tid, acc, [&](int row, int col, float v) {
;       int t = m0 + row;
;       float o = v;
;       if (mode == 1) o = (t >= NPADR) ? v : 0.f;
;       if (mode == 2) o = sigmf(v);
;       sT[row * 136 + col] = f2bf(o);
;     });
.LBB0_886:
	v_bfe_u32 v119, v118, 16, 1
	v_add_u32_e32 v116, 0x550, v116
	v_add3_u32 v119, v118, v119, s79
	v_lshl_add_u32 v118, v106, 1, v116
	ds_write_b16_d16_hi v118, v119
	v_add3_u32 v119, s0, v96, 17
	v_cmp_lt_i32_e64 s[26:27], s77, v119
	s_nop 1

; __device__ __forceinline__ float sigmf(float x) { return 1.f / (1.f + __expf(-x)); }
; __device__ __forceinline__ bf16r f2bf(float f) {
;   unsigned u = __float_as_uint(f);
;   u += 0x7fffu + ((u >> 16) & 1u);
;   return (bf16r)(u >> 16);
; }
; __device__ __forceinline__ void inproj_epilogue(const Params& p, int layer, int mt, int ntile, int tid,
;                                                 f32x16 (&acc)[2][2], unsigned char* smem) {
;     ...
;     acc_foreach(tid, acc, [&](int row, int col, float v) {
;       int t = m0 + row;
;       float o = v;
;       if (mode == 1) o = (t >= NPADR) ? v : 0.f;
;       if (mode == 2) o = sigmf(v);
;       sT[row * 136 + col] = f2bf(o);
;     });
.LBB0_889:
	v_bfe_u32 v120, v119, 16, 1
	v_add_u32_e32 v116, 0x110, v116
	v_add3_u32 v120, v119, v120, s79
	v_lshl_add_u32 v119, v106, 1, v116
	ds_write_b16_d16_hi v119, v120
	v_add3_u32 v120, s0, v96, 18
	v_cmp_lt_i32_e64 s[28:29], s77, v120
	s_nop 1

; __device__ __forceinline__ float sigmf(float x) { return 1.f / (1.f + __expf(-x)); }
; __device__ __forceinline__ bf16r f2bf(float f) {
;   unsigned u = __float_as_uint(f);
;   u += 0x7fffu + ((u >> 16) & 1u);
;   return (bf16r)(u >> 16);
; }
; __device__ __forceinline__ void inproj_epilogue(const Params& p, int layer, int mt, int ntile, int tid,
;                                                 f32x16 (&acc)[2][2], unsigned char* smem) {
;     ...
;     acc_foreach(tid, acc, [&](int row, int col, float v) {
;       int t = m0 + row;
;       float o = v;
;       if (mode == 1) o = (t >= NPADR) ? v : 0.f;
;       if (mode == 2) o = sigmf(v);
;       sT[row * 136 + col] = f2bf(o);
;     });
.LBB0_892:
	v_bfe_u32 v121, v120, 16, 1
	v_add_u32_e32 v116, 0x110, v116
	v_add3_u32 v121, v120, v121, s79
	v_lshl_add_u32 v120, v106, 1, v116
	ds_write_b16_d16_hi v120, v121
	v_add3_u32 v121, s0, v96, 19
	v_cmp_lt_i32_e64 s[30:31], s77, v121
	s_nop 1

; __device__ __forceinline__ float sigmf(float x) { return 1.f / (1.f + __expf(-x)); }
; __device__ __forceinline__ bf16r f2bf(float f) {
;   unsigned u = __float_as_uint(f);
;   u += 0x7fffu + ((u >> 16) & 1u);
;   return (bf16r)(u >> 16);
; }
; __device__ __forceinline__ void inproj_epilogue(const Params& p, int layer, int mt, int ntile, int tid,
;                                                 f32x16 (&acc)[2][2], unsigned char* smem) {
;     ...
;     acc_foreach(tid, acc, [&](int row, int col, float v) {
;       int t = m0 + row;
;       float o = v;
;       if (mode == 1) o = (t >= NPADR) ? v : 0.f;
;       if (mode == 2) o = sigmf(v);
;       sT[row * 136 + col] = f2bf(o);
;     });
.LBB0_895:
	v_bfe_u32 v122, v121, 16, 1
	v_add_u32_e32 v116, 0x110, v116
	v_add3_u32 v122, v121, v122, s79
	v_lshl_add_u32 v121, v106, 1, v116
	ds_write_b16_d16_hi v121, v122
	v_add3_u32 v122, s0, v96, 24
	v_cmp_lt_i32_e64 s[34:35], s77, v122
	s_nop 1

; __device__ __forceinline__ float sigmf(float x) { return 1.f / (1.f + __expf(-x)); }
; __device__ __forceinline__ bf16r f2bf(float f) {
;   unsigned u = __float_as_uint(f);
;   u += 0x7fffu + ((u >> 16) & 1u);
;   return (bf16r)(u >> 16);
; }
; __device__ __forceinline__ void inproj_epilogue(const Params& p, int layer, int mt, int ntile, int tid,
;                                                 f32x16 (&acc)[2][2], unsigned char* smem) {
;     ...
;     acc_foreach(tid, acc, [&](int row, int col, float v) {
;       int t = m0 + row;
;       float o = v;
;       if (mode == 1) o = (t >= NPADR) ? v : 0.f;
;       if (mode == 2) o = sigmf(v);
;       sT[row * 136 + col] = f2bf(o);
;     });
.LBB0_898:
	v_bfe_u32 v123, v122, 16, 1
	v_add_u32_e32 v116, 0x550, v116
	v_add3_u32 v123, v122, v123, s79
	v_lshl_add_u32 v122, v106, 1, v116
	ds_write_b16_d16_hi v122, v123
	v_add3_u32 v123, s0, v96, 25
	v_cmp_lt_i32_e64 s[36:37], s77, v123
	s_nop 1

; __device__ __forceinline__ float sigmf(float x) { return 1.f / (1.f + __expf(-x)); }
; __device__ __forceinline__ bf16r f2bf(float f) {
;   unsigned u = __float_as_uint(f);
;   u += 0x7fffu + ((u >> 16) & 1u);
;   return (bf16r)(u >> 16);
; }
; __device__ __forceinline__ void inproj_epilogue(const Params& p, int layer, int mt, int ntile, int tid,
;                                                 f32x16 (&acc)[2][2], unsigned char* smem) {
;     ...
;     acc_foreach(tid, acc, [&](int row, int col, float v) {
;       int t = m0 + row;
;       float o = v;
;       if (mode == 1) o = (t >= NPADR) ? v : 0.f;
;       if (mode == 2) o = sigmf(v);
;       sT[row * 136 + col] = f2bf(o);
;     });
.LBB0_901:
	v_bfe_u32 v124, v123, 16, 1
	v_add_u32_e32 v116, 0x110, v116
	v_add3_u32 v124, v123, v124, s79
	v_lshl_add_u32 v123, v106, 1, v116
	ds_write_b16_d16_hi v123, v124
	v_add3_u32 v124, s0, v96, 26
	v_cmp_lt_i32_e64 s[38:39], s77, v124
	s_nop 1

; __device__ __forceinline__ float sigmf(float x) { return 1.f / (1.f + __expf(-x)); }
; __device__ __forceinline__ bf16r f2bf(float f) {
;   unsigned u = __float_as_uint(f);
;   u += 0x7fffu + ((u >> 16) & 1u);
;   return (bf16r)(u >> 16);
; }
; __device__ __forceinline__ void inproj_epilogue(const Params& p, int layer, int mt, int ntile, int tid,
;                                                 f32x16 (&acc)[2][2], unsigned char* smem) {
;     ...
;     acc_foreach(tid, acc, [&](int row, int col, float v) {
;       int t = m0 + row;
;       float o = v;
;       if (mode == 1) o = (t >= NPADR) ? v : 0.f;
;       if (mode == 2) o = sigmf(v);
;       sT[row * 136 + col] = f2bf(o);
;     });
.LBB0_904:
	v_bfe_u32 v125, v124, 16, 1
	v_add_u32_e32 v116, 0x110, v116
	v_add3_u32 v124, v124, v125, s79
	v_lshl_add_u32 v116, v106, 1, v116
	ds_write_b16_d16_hi v116, v124
	v_add3_u32 v124, s0, v96, 27
	v_cmp_lt_i32_e64 s[40:41], s77, v124
	s_nop 1

; __device__ __forceinline__ float sigmf(float x) { return 1.f / (1.f + __expf(-x)); }
; __device__ __forceinline__ bf16r f2bf(float f) {
;   unsigned u = __float_as_uint(f);
;   u += 0x7fffu + ((u >> 16) & 1u);
;   return (bf16r)(u >> 16);
; }
; __device__ __forceinline__ void inproj_epilogue(const Params& p, int layer, int mt, int ntile, int tid,
;                                                 f32x16 (&acc)[2][2], unsigned char* smem) {
;     ...
;     acc_foreach(tid, acc, [&](int row, int col, float v) {
;       int t = m0 + row;
;       float o = v;
;       if (mode == 1) o = (t >= NPADR) ? v : 0.f;
;       if (mode == 2) o = sigmf(v);
;       sT[row * 136 + col] = f2bf(o);
;     });
.LBB0_907:
	v_bfe_u32 v125, v124, 16, 1
	v_add3_u32 v124, v124, v125, s79
	ds_write_b16_d16_hi v116, v124 offset:272
	s_nop 1

; __device__ __forceinline__ float sigmf(float x) { return 1.f / (1.f + __expf(-x)); }
; __device__ __forceinline__ bf16r f2bf(float f) {
;   unsigned u = __float_as_uint(f);
;   u += 0x7fffu + ((u >> 16) & 1u);
;   return (bf16r)(u >> 16);
; }
; __device__ __forceinline__ void inproj_epilogue(const Params& p, int layer, int mt, int ntile, int tid,
;                                                 f32x16 (&acc)[2][2], unsigned char* smem) {
;     ...
;     acc_foreach(tid, acc, [&](int row, int col, float v) {
;       int t = m0 + row;
;       float o = v;
;       if (mode == 1) o = (t >= NPADR) ? v : 0.f;
;       if (mode == 2) o = sigmf(v);
;       sT[row * 136 + col] = f2bf(o);
;     });
.LBB0_910:
	v_bfe_u32 v124, v48, 16, 1
	v_add3_u32 v48, v48, v124, s79
	ds_write_b16_d16_hi v107, v48 offset:64
	s_nop 1

; __device__ __forceinline__ float sigmf(float x) { return 1.f / (1.f + __expf(-x)); }
; __device__ __forceinline__ bf16r f2bf(float f) {
;   unsigned u = __float_as_uint(f);
;   u += 0x7fffu + ((u >> 16) & 1u);
;   return (bf16r)(u >> 16);
; }
; __device__ __forceinline__ void inproj_epilogue(const Params& p, int layer, int mt, int ntile, int tid,
;                                                 f32x16 (&acc)[2][2], unsigned char* smem) {
;     ...
;     acc_foreach(tid, acc, [&](int row, int col, float v) {
;       int t = m0 + row;
;       float o = v;
;       if (mode == 1) o = (t >= NPADR) ? v : 0.f;
;       if (mode == 2) o = sigmf(v);
;       sT[row * 136 + col] = f2bf(o);
;     });
.LBB0_913:
	v_bfe_u32 v49, v48, 16, 1
	v_add3_u32 v48, v48, v49, s79
	ds_write_b16_d16_hi v110, v48 offset:64
	s_nop 1

; __device__ __forceinline__ float sigmf(float x) { return 1.f / (1.f + __expf(-x)); }
; __device__ __forceinline__ bf16r f2bf(float f) {
;   unsigned u = __float_as_uint(f);
;   u += 0x7fffu + ((u >> 16) & 1u);
;   return (bf16r)(u >> 16);
; }
; __device__ __forceinline__ void inproj_epilogue(const Params& p, int layer, int mt, int ntile, int tid,
;                                                 f32x16 (&acc)[2][2], unsigned char* smem) {
;     ...
;     acc_foreach(tid, acc, [&](int row, int col, float v) {
;       int t = m0 + row;
;       float o = v;
;       if (mode == 1) o = (t >= NPADR) ? v : 0.f;
;       if (mode == 2) o = sigmf(v);
;       sT[row * 136 + col] = f2bf(o);
;     });
.LBB0_916:
	v_bfe_u32 v49, v48, 16, 1
	v_add3_u32 v48, v48, v49, s79
	ds_write_b16_d16_hi v111, v48 offset:64
	s_nop 1

; __device__ __forceinline__ float sigmf(float x) { return 1.f / (1.f + __expf(-x)); }
; __device__ __forceinline__ bf16r f2bf(float f) {
;   unsigned u = __float_as_uint(f);
;   u += 0x7fffu + ((u >> 16) & 1u);
;   return (bf16r)(u >> 16);
; }
; __device__ __forceinline__ void inproj_epilogue(const Params& p, int layer, int mt, int ntile, int tid,
;                                                 f32x16 (&acc)[2][2], unsigned char* smem) {
;     ...
;     acc_foreach(tid, acc, [&](int row, int col, float v) {
;       int t = m0 + row;
;       float o = v;
;       if (mode == 1) o = (t >= NPADR) ? v : 0.f;
;       if (mode == 2) o = sigmf(v);
;       sT[row * 136 + col] = f2bf(o);
;     });
.LBB0_919:
	v_bfe_u32 v49, v48, 16, 1
	v_add3_u32 v48, v48, v49, s79
	ds_write_b16_d16_hi v112, v48 offset:64
	s_nop 1

; __device__ __forceinline__ float sigmf(float x) { return 1.f / (1.f + __expf(-x)); }
; __device__ __forceinline__ bf16r f2bf(float f) {
;   unsigned u = __float_as_uint(f);
;   u += 0x7fffu + ((u >> 16) & 1u);
;   return (bf16r)(u >> 16);
; }
; __device__ __forceinline__ void inproj_epilogue(const Params& p, int layer, int mt, int ntile, int tid,
;                                                 f32x16 (&acc)[2][2], unsigned char* smem) {
;     ...
;     acc_foreach(tid, acc, [&](int row, int col, float v) {
;       int t = m0 + row;
;       float o = v;
;       if (mode == 1) o = (t >= NPADR) ? v : 0.f;
;       if (mode == 2) o = sigmf(v);
;       sT[row * 136 + col] = f2bf(o);
;     });
.LBB0_922:
	v_bfe_u32 v49, v48, 16, 1
	v_add3_u32 v48, v48, v49, s79
	ds_write_b16_d16_hi v113, v48 offset:64
	s_nop 1

; __device__ __forceinline__ float sigmf(float x) { return 1.f / (1.f + __expf(-x)); }
; __device__ __forceinline__ bf16r f2bf(float f) {
;   unsigned u = __float_as_uint(f);
;   u += 0x7fffu + ((u >> 16) & 1u);
;   return (bf16r)(u >> 16);
; }
; __device__ __forceinline__ void inproj_epilogue(const Params& p, int layer, int mt, int ntile, int tid,
;                                                 f32x16 (&acc)[2][2], unsigned char* smem) {
;     ...
;     acc_foreach(tid, acc, [&](int row, int col, float v) {
;       int t = m0 + row;
;       float o = v;
;       if (mode == 1) o = (t >= NPADR) ? v : 0.f;
;       if (mode == 2) o = sigmf(v);
;       sT[row * 136 + col] = f2bf(o);
;     });
.LBB0_925:
	v_bfe_u32 v49, v48, 16, 1
	v_add3_u32 v48, v48, v49, s79
	ds_write_b16_d16_hi v114, v48 offset:64
	s_nop 1

; __device__ __forceinline__ float sigmf(float x) { return 1.f / (1.f + __expf(-x)); }
; __device__ __forceinline__ bf16r f2bf(float f) {
;   unsigned u = __float_as_uint(f);
;   u += 0x7fffu + ((u >> 16) & 1u);
;   return (bf16r)(u >> 16);
; }
; __device__ __forceinline__ void inproj_epilogue(const Params& p, int layer, int mt, int ntile, int tid,
;                                                 f32x16 (&acc)[2][2], unsigned char* smem) {
;     ...
;     acc_foreach(tid, acc, [&](int row, int col, float v) {
;       int t = m0 + row;
;       float o = v;
;       if (mode == 1) o = (t >= NPADR) ? v : 0.f;
;       if (mode == 2) o = sigmf(v);
;       sT[row * 136 + col] = f2bf(o);
;     });
.LBB0_928:
	v_bfe_u32 v49, v48, 16, 1
	v_add3_u32 v48, v48, v49, s79
	ds_write_b16_d16_hi v115, v48 offset:64
	s_nop 1

; __device__ __forceinline__ float sigmf(float x) { return 1.f / (1.f + __expf(-x)); }
; __device__ __forceinline__ bf16r f2bf(float f) {
;   unsigned u = __float_as_uint(f);
;   u += 0x7fffu + ((u >> 16) & 1u);
;   return (bf16r)(u >> 16);
; }
; __device__ __forceinline__ void inproj_epilogue(const Params& p, int layer, int mt, int ntile, int tid,
;                                                 f32x16 (&acc)[2][2], unsigned char* smem) {
;     ...
;     acc_foreach(tid, acc, [&](int row, int col, float v) {
;       int t = m0 + row;
;       float o = v;
;       if (mode == 1) o = (t >= NPADR) ? v : 0.f;
;       if (mode == 2) o = sigmf(v);
;       sT[row * 136 + col] = f2bf(o);
;     });
.LBB0_931:
	v_bfe_u32 v49, v48, 16, 1
	v_add3_u32 v48, v48, v49, s79
	ds_write_b16_d16_hi v117, v48 offset:64
	s_nop 1

; __device__ __forceinline__ float sigmf(float x) { return 1.f / (1.f + __expf(-x)); }
; __device__ __forceinline__ bf16r f2bf(float f) {
;   unsigned u = __float_as_uint(f);
;   u += 0x7fffu + ((u >> 16) & 1u);
;   return (bf16r)(u >> 16);
; }
; __device__ __forceinline__ void inproj_epilogue(const Params& p, int layer, int mt, int ntile, int tid,
;                                                 f32x16 (&acc)[2][2], unsigned char* smem) {
;     ...
;     acc_foreach(tid, acc, [&](int row, int col, float v) {
;       int t = m0 + row;
;       float o = v;
;       if (mode == 1) o = (t >= NPADR) ? v : 0.f;
;       if (mode == 2) o = sigmf(v);
;       sT[row * 136 + col] = f2bf(o);
;     });
.LBB0_934:
	v_bfe_u32 v49, v48, 16, 1
	v_add3_u32 v48, v48, v49, s79
	ds_write_b16_d16_hi v118, v48 offset:64
	s_nop 1

; __device__ __forceinline__ float sigmf(float x) { return 1.f / (1.f + __expf(-x)); }
; __device__ __forceinline__ bf16r f2bf(float f) {
;   unsigned u = __float_as_uint(f);
;   u += 0x7fffu + ((u >> 16) & 1u);
;   return (bf16r)(u >> 16);
; }
; __device__ __forceinline__ void inproj_epilogue(const Params& p, int layer, int mt, int ntile, int tid,
;                                                 f32x16 (&acc)[2][2], unsigned char* smem) {
;     ...
;     acc_foreach(tid, acc, [&](int row, int col, float v) {
;       int t = m0 + row;
;       float o = v;
;       if (mode == 1) o = (t >= NPADR) ? v : 0.f;
;       if (mode == 2) o = sigmf(v);
;       sT[row * 136 + col] = f2bf(o);
;     });
.LBB0_937:
	v_bfe_u32 v49, v48, 16, 1
	v_add3_u32 v48, v48, v49, s79
	ds_write_b16_d16_hi v119, v48 offset:64
	s_nop 1

; __device__ __forceinline__ float sigmf(float x) { return 1.f / (1.f + __expf(-x)); }
; __device__ __forceinline__ bf16r f2bf(float f) {
;   unsigned u = __float_as_uint(f);
;   u += 0x7fffu + ((u >> 16) & 1u);
;   return (bf16r)(u >> 16);
; }
; __device__ __forceinline__ void inproj_epilogue(const Params& p, int layer, int mt, int ntile, int tid,
;                                                 f32x16 (&acc)[2][2], unsigned char* smem) {
;     ...
;     acc_foreach(tid, acc, [&](int row, int col, float v) {
;       int t = m0 + row;
;       float o = v;
;       if (mode == 1) o = (t >= NPADR) ? v : 0.f;
;       if (mode == 2) o = sigmf(v);
;       sT[row * 136 + col] = f2bf(o);
;     });
.LBB0_940:
	v_bfe_u32 v49, v48, 16, 1
	v_add3_u32 v48, v48, v49, s79
	ds_write_b16_d16_hi v120, v48 offset:64
	s_nop 1

; __device__ __forceinline__ float sigmf(float x) { return 1.f / (1.f + __expf(-x)); }
; __device__ __forceinline__ bf16r f2bf(float f) {
;   unsigned u = __float_as_uint(f);
;   u += 0x7fffu + ((u >> 16) & 1u);
;   return (bf16r)(u >> 16);
; }
; __device__ __forceinline__ void inproj_epilogue(const Params& p, int layer, int mt, int ntile, int tid,
;                                                 f32x16 (&acc)[2][2], unsigned char* smem) {
;     ...
;     acc_foreach(tid, acc, [&](int row, int col, float v) {
;       int t = m0 + row;
;       float o = v;
;       if (mode == 1) o = (t >= NPADR) ? v : 0.f;
;       if (mode == 2) o = sigmf(v);
;       sT[row * 136 + col] = f2bf(o);
;     });
.LBB0_943:
	v_bfe_u32 v49, v48, 16, 1
	v_add3_u32 v48, v48, v49, s79
	ds_write_b16_d16_hi v121, v48 offset:64
	s_nop 1

; __device__ __forceinline__ float sigmf(float x) { return 1.f / (1.f + __expf(-x)); }
; __device__ __forceinline__ bf16r f2bf(float f) {
;   unsigned u = __float_as_uint(f);
;   u += 0x7fffu + ((u >> 16) & 1u);
;   return (bf16r)(u >> 16);
; }
; __device__ __forceinline__ void inproj_epilogue(const Params& p, int layer, int mt, int ntile, int tid,
;                                                 f32x16 (&acc)[2][2], unsigned char* smem) {
;     ...
;     acc_foreach(tid, acc, [&](int row, int col, float v) {
;       int t = m0 + row;
;       float o = v;
;       if (mode == 1) o = (t >= NPADR) ? v : 0.f;
;       if (mode == 2) o = sigmf(v);
;       sT[row * 136 + col] = f2bf(o);
;     });
.LBB0_946:
	v_bfe_u32 v49, v48, 16, 1
	v_add3_u32 v48, v48, v49, s79
	ds_write_b16_d16_hi v122, v48 offset:64
	s_nop 1

; __device__ __forceinline__ float sigmf(float x) { return 1.f / (1.f + __expf(-x)); }
; __device__ __forceinline__ bf16r f2bf(float f) {
;   unsigned u = __float_as_uint(f);
;   u += 0x7fffu + ((u >> 16) & 1u);
;   return (bf16r)(u >> 16);
; }
; __device__ __forceinline__ void inproj_epilogue(const Params& p, int layer, int mt, int ntile, int tid,
;                                                 f32x16 (&acc)[2][2], unsigned char* smem) {
;     ...
;     acc_foreach(tid, acc, [&](int row, int col, float v) {
;       int t = m0 + row;
;       float o = v;
;       if (mode == 1) o = (t >= NPADR) ? v : 0.f;
;       if (mode == 2) o = sigmf(v);
;       sT[row * 136 + col] = f2bf(o);
;     });
.LBB0_949:
	v_bfe_u32 v49, v48, 16, 1
	v_add3_u32 v48, v48, v49, s79
	ds_write_b16_d16_hi v123, v48 offset:64
	s_nop 1

; __device__ __forceinline__ float sigmf(float x) { return 1.f / (1.f + __expf(-x)); }
; __device__ __forceinline__ bf16r f2bf(float f) {
;   unsigned u = __float_as_uint(f);
;   u += 0x7fffu + ((u >> 16) & 1u);
;   return (bf16r)(u >> 16);
; }
; __device__ __forceinline__ void inproj_epilogue(const Params& p, int layer, int mt, int ntile, int tid,
;                                                 f32x16 (&acc)[2][2], unsigned char* smem) {
;     ...
;     acc_foreach(tid, acc, [&](int row, int col, float v) {
;       int t = m0 + row;
;       float o = v;
;       if (mode == 1) o = (t >= NPADR) ? v : 0.f;
;       if (mode == 2) o = sigmf(v);
;       sT[row * 136 + col] = f2bf(o);
;     });
.LBB0_952:
	v_bfe_u32 v49, v48, 16, 1
	v_add3_u32 v48, v48, v49, s79
	ds_write_b16_d16_hi v116, v48 offset:64
	s_nop 1

; __device__ __forceinline__ float sigmf(float x) { return 1.f / (1.f + __expf(-x)); }
; __device__ __forceinline__ bf16r f2bf(float f) {
;   unsigned u = __float_as_uint(f);
;   u += 0x7fffu + ((u >> 16) & 1u);
;   return (bf16r)(u >> 16);
; }
; __device__ __forceinline__ void inproj_epilogue(const Params& p, int layer, int mt, int ntile, int tid,
;                                                 f32x16 (&acc)[2][2], unsigned char* smem) {
;     ...
;     acc_foreach(tid, acc, [&](int row, int col, float v) {
;       int t = m0 + row;
;       float o = v;
;       if (mode == 1) o = (t >= NPADR) ? v : 0.f;
;       if (mode == 2) o = sigmf(v);
;       sT[row * 136 + col] = f2bf(o);
;     });
.LBB0_955:
	v_bfe_u32 v50, v48, 16, 1
	v_add_u32_e32 v49, 0x110, v116
	v_add3_u32 v48, v48, v50, s79
	ds_write_b16_d16_hi v49, v48 offset:64
	v_or_b32_e32 v48, 32, v96
	v_add_u32_e32 v49, s0, v48
	v_cmp_lt_i32_e64 s[8:9], s77, v49
	s_nop 1

; __device__ __forceinline__ float sigmf(float x) { return 1.f / (1.f + __expf(-x)); }
; __device__ __forceinline__ bf16r f2bf(float f) {
;   unsigned u = __float_as_uint(f);
;   u += 0x7fffu + ((u >> 16) & 1u);
;   return (bf16r)(u >> 16);
; }
; __device__ __forceinline__ void inproj_epilogue(const Params& p, int layer, int mt, int ntile, int tid,
;                                                 f32x16 (&acc)[2][2], unsigned char* smem) {
;     ...
;     acc_foreach(tid, acc, [&](int row, int col, float v) {
;       int t = m0 + row;
;       float o = v;
;       if (mode == 1) o = (t >= NPADR) ? v : 0.f;
;       if (mode == 2) o = sigmf(v);
;       sT[row * 136 + col] = f2bf(o);
;     });
.LBB0_958:
	v_bfe_u32 v50, v49, 16, 1
	v_add3_u32 v50, v49, v50, s79
	v_mul_lo_u32 v49, v48, s80
	v_lshl_add_u32 v48, v106, 1, v49
	ds_write_b16_d16_hi v48, v50
	v_add3_u32 v50, s0, v96, 33
	v_cmp_lt_i32_e64 s[10:11], s77, v50
	s_nop 1

; __device__ __forceinline__ float sigmf(float x) { return 1.f / (1.f + __expf(-x)); }
; __device__ __forceinline__ bf16r f2bf(float f) {
;   unsigned u = __float_as_uint(f);
;   u += 0x7fffu + ((u >> 16) & 1u);
;   return (bf16r)(u >> 16);
; }
; __device__ __forceinline__ void inproj_epilogue(const Params& p, int layer, int mt, int ntile, int tid,
;                                                 f32x16 (&acc)[2][2], unsigned char* smem) {
;     ...
;     acc_foreach(tid, acc, [&](int row, int col, float v) {
;       int t = m0 + row;
;       float o = v;
;       if (mode == 1) o = (t >= NPADR) ? v : 0.f;
;       if (mode == 2) o = sigmf(v);
;       sT[row * 136 + col] = f2bf(o);
;     });
.LBB0_961:
	v_bfe_u32 v51, v50, 16, 1
	v_add3_u32 v51, v50, v51, s79
	v_add_u32_e32 v50, 0x110, v49
	v_lshl_add_u32 v49, v106, 1, v50
	ds_write_b16_d16_hi v49, v51
	v_add3_u32 v51, s0, v96, 34
	v_cmp_lt_i32_e64 s[12:13], s77, v51
	s_nop 1

; __device__ __forceinline__ float sigmf(float x) { return 1.f / (1.f + __expf(-x)); }
; __device__ __forceinline__ bf16r f2bf(float f) {
;   unsigned u = __float_as_uint(f);
;   u += 0x7fffu + ((u >> 16) & 1u);
;   return (bf16r)(u >> 16);
; }
; __device__ __forceinline__ void inproj_epilogue(const Params& p, int layer, int mt, int ntile, int tid,
;                                                 f32x16 (&acc)[2][2], unsigned char* smem) {
;     ...
;     acc_foreach(tid, acc, [&](int row, int col, float v) {
;       int t = m0 + row;
;       float o = v;
;       if (mode == 1) o = (t >= NPADR) ? v : 0.f;
;       if (mode == 2) o = sigmf(v);
;       sT[row * 136 + col] = f2bf(o);
;     });
.LBB0_964:
	v_bfe_u32 v52, v51, 16, 1
	v_add3_u32 v52, v51, v52, s79
	v_add_u32_e32 v51, 0x110, v50
	v_lshl_add_u32 v50, v106, 1, v51
	ds_write_b16_d16_hi v50, v52
	v_add3_u32 v52, s0, v96, 35
	v_cmp_lt_i32_e64 s[14:15], s77, v52
	s_nop 1

; __device__ __forceinline__ float sigmf(float x) { return 1.f / (1.f + __expf(-x)); }
; __device__ __forceinline__ bf16r f2bf(float f) {
;   unsigned u = __float_as_uint(f);
;   u += 0x7fffu + ((u >> 16) & 1u);
;   return (bf16r)(u >> 16);
; }
; __device__ __forceinline__ void inproj_epilogue(const Params& p, int layer, int mt, int ntile, int tid,
;                                                 f32x16 (&acc)[2][2], unsigned char* smem) {
;     ...
;     acc_foreach(tid, acc, [&](int row, int col, float v) {
;       int t = m0 + row;
;       float o = v;
;       if (mode == 1) o = (t >= NPADR) ? v : 0.f;
;       if (mode == 2) o = sigmf(v);
;       sT[row * 136 + col] = f2bf(o);
;     });
.LBB0_967:
	v_bfe_u32 v53, v52, 16, 1
	v_add3_u32 v53, v52, v53, s79
	v_add_u32_e32 v52, 0x110, v51
	v_lshl_add_u32 v51, v106, 1, v52
	ds_write_b16_d16_hi v51, v53
	v_add3_u32 v53, s0, v96, 40
	v_cmp_lt_i32_e64 s[16:17], s77, v53
	s_nop 1

; __device__ __forceinline__ float sigmf(float x) { return 1.f / (1.f + __expf(-x)); }
; __device__ __forceinline__ bf16r f2bf(float f) {
;   unsigned u = __float_as_uint(f);
;   u += 0x7fffu + ((u >> 16) & 1u);
;   return (bf16r)(u >> 16);
; }
; __device__ __forceinline__ void inproj_epilogue(const Params& p, int layer, int mt, int ntile, int tid,
;                                                 f32x16 (&acc)[2][2], unsigned char* smem) {
;     ...
;     acc_foreach(tid, acc, [&](int row, int col, float v) {
;       int t = m0 + row;
;       float o = v;
;       if (mode == 1) o = (t >= NPADR) ? v : 0.f;
;       if (mode == 2) o = sigmf(v);
;       sT[row * 136 + col] = f2bf(o);
;     });
.LBB0_970:
	v_bfe_u32 v54, v53, 16, 1
	v_add3_u32 v54, v53, v54, s79
	v_add_u32_e32 v53, 0x550, v52
	v_lshl_add_u32 v52, v106, 1, v53
	ds_write_b16_d16_hi v52, v54
	v_add3_u32 v54, s0, v96, 41
	v_cmp_lt_i32_e64 s[18:19], s77, v54
	s_nop 1

; __device__ __forceinline__ float sigmf(float x) { return 1.f / (1.f + __expf(-x)); }
; __device__ __forceinline__ bf16r f2bf(float f) {
;   unsigned u = __float_as_uint(f);
;   u += 0x7fffu + ((u >> 16) & 1u);
;   return (bf16r)(u >> 16);
; }
; __device__ __forceinline__ void inproj_epilogue(const Params& p, int layer, int mt, int ntile, int tid,
;                                                 f32x16 (&acc)[2][2], unsigned char* smem) {
;     ...
;     acc_foreach(tid, acc, [&](int row, int col, float v) {
;       int t = m0 + row;
;       float o = v;
;       if (mode == 1) o = (t >= NPADR) ? v : 0.f;
;       if (mode == 2) o = sigmf(v);
;       sT[row * 136 + col] = f2bf(o);
;     });
.LBB0_973:
	v_bfe_u32 v55, v54, 16, 1
	v_add3_u32 v55, v54, v55, s79
	v_add_u32_e32 v54, 0x110, v53
	v_lshl_add_u32 v53, v106, 1, v54
	ds_write_b16_d16_hi v53, v55
	v_add3_u32 v55, s0, v96, 42
	v_cmp_lt_i32_e64 s[20:21], s77, v55
	s_nop 1

; __device__ __forceinline__ float sigmf(float x) { return 1.f / (1.f + __expf(-x)); }
; __device__ __forceinline__ bf16r f2bf(float f) {
;   unsigned u = __float_as_uint(f);
;   u += 0x7fffu + ((u >> 16) & 1u);
;   return (bf16r)(u >> 16);
; }
; __device__ __forceinline__ void inproj_epilogue(const Params& p, int layer, int mt, int ntile, int tid,
;                                                 f32x16 (&acc)[2][2], unsigned char* smem) {
;     ...
;     acc_foreach(tid, acc, [&](int row, int col, float v) {
;       int t = m0 + row;
;       float o = v;
;       if (mode == 1) o = (t >= NPADR) ? v : 0.f;
;       if (mode == 2) o = sigmf(v);
;       sT[row * 136 + col] = f2bf(o);
;     });
.LBB0_976:
	v_bfe_u32 v56, v55, 16, 1
	v_add3_u32 v56, v55, v56, s79
	v_add_u32_e32 v55, 0x110, v54
	v_lshl_add_u32 v54, v106, 1, v55
	ds_write_b16_d16_hi v54, v56
	v_add3_u32 v56, s0, v96, 43
	v_cmp_lt_i32_e64 s[22:23], s77, v56
	s_nop 1

; __device__ __forceinline__ float sigmf(float x) { return 1.f / (1.f + __expf(-x)); }
; __device__ __forceinline__ bf16r f2bf(float f) {
;   unsigned u = __float_as_uint(f);
;   u += 0x7fffu + ((u >> 16) & 1u);
;   return (bf16r)(u >> 16);
; }
; __device__ __forceinline__ void inproj_epilogue(const Params& p, int layer, int mt, int ntile, int tid,
;                                                 f32x16 (&acc)[2][2], unsigned char* smem) {
;     ...
;     acc_foreach(tid, acc, [&](int row, int col, float v) {
;       int t = m0 + row;
;       float o = v;
;       if (mode == 1) o = (t >= NPADR) ? v : 0.f;
;       if (mode == 2) o = sigmf(v);
;       sT[row * 136 + col] = f2bf(o);
;     });
.LBB0_979:
	v_bfe_u32 v57, v56, 16, 1
	v_add_u32_e32 v55, 0x110, v55
	v_add3_u32 v57, v56, v57, s79
	v_lshl_add_u32 v56, v106, 1, v55
	ds_write_b16_d16_hi v56, v57
	v_add3_u32 v57, s0, v96, 48
	v_cmp_lt_i32_e64 s[24:25], s77, v57
	s_nop 1

; __device__ __forceinline__ float sigmf(float x) { return 1.f / (1.f + __expf(-x)); }
; __device__ __forceinline__ bf16r f2bf(float f) {
;   unsigned u = __float_as_uint(f);
;   u += 0x7fffu + ((u >> 16) & 1u);
;   return (bf16r)(u >> 16);
; }
; __device__ __forceinline__ void inproj_epilogue(const Params& p, int layer, int mt, int ntile, int tid,
;                                                 f32x16 (&acc)[2][2], unsigned char* smem) {
;     ...
;     acc_foreach(tid, acc, [&](int row, int col, float v) {
;       int t = m0 + row;
;       float o = v;
;       if (mode == 1) o = (t >= NPADR) ? v : 0.f;
;       if (mode == 2) o = sigmf(v);
;       sT[row * 136 + col] = f2bf(o);
;     });
.LBB0_982:
	v_bfe_u32 v58, v57, 16, 1
	v_add_u32_e32 v55, 0x550, v55
	v_add3_u32 v58, v57, v58, s79
	v_lshl_add_u32 v57, v106, 1, v55
	ds_write_b16_d16_hi v57, v58
	v_add3_u32 v58, s0, v96, 49
	v_cmp_lt_i32_e64 s[26:27], s77, v58
	s_nop 1

; __device__ __forceinline__ float sigmf(float x) { return 1.f / (1.f + __expf(-x)); }
; __device__ __forceinline__ bf16r f2bf(float f) {
;   unsigned u = __float_as_uint(f);
;   u += 0x7fffu + ((u >> 16) & 1u);
;   return (bf16r)(u >> 16);
; }
; __device__ __forceinline__ void inproj_epilogue(const Params& p, int layer, int mt, int ntile, int tid,
;                                                 f32x16 (&acc)[2][2], unsigned char* smem) {
;     ...
;     acc_foreach(tid, acc, [&](int row, int col, float v) {
;       int t = m0 + row;
;       float o = v;
;       if (mode == 1) o = (t >= NPADR) ? v : 0.f;
;       if (mode == 2) o = sigmf(v);
;       sT[row * 136 + col] = f2bf(o);
;     });
.LBB0_985:
	v_bfe_u32 v59, v58, 16, 1
	v_add_u32_e32 v55, 0x110, v55
	v_add3_u32 v59, v58, v59, s79
	v_lshl_add_u32 v58, v106, 1, v55
	ds_write_b16_d16_hi v58, v59
	v_add3_u32 v59, s0, v96, 50
	v_cmp_lt_i32_e64 s[28:29], s77, v59
	s_nop 1

; __device__ __forceinline__ float sigmf(float x) { return 1.f / (1.f + __expf(-x)); }
; __device__ __forceinline__ bf16r f2bf(float f) {
;   unsigned u = __float_as_uint(f);
;   u += 0x7fffu + ((u >> 16) & 1u);
;   return (bf16r)(u >> 16);
; }
; __device__ __forceinline__ void inproj_epilogue(const Params& p, int layer, int mt, int ntile, int tid,
;                                                 f32x16 (&acc)[2][2], unsigned char* smem) {
;     ...
;     acc_foreach(tid, acc, [&](int row, int col, float v) {
;       int t = m0 + row;
;       float o = v;
;       if (mode == 1) o = (t >= NPADR) ? v : 0.f;
;       if (mode == 2) o = sigmf(v);
;       sT[row * 136 + col] = f2bf(o);
;     });
.LBB0_988:
	v_bfe_u32 v60, v59, 16, 1
	v_add_u32_e32 v55, 0x110, v55
	v_add3_u32 v60, v59, v60, s79
	v_lshl_add_u32 v59, v106, 1, v55
	ds_write_b16_d16_hi v59, v60
	v_add3_u32 v60, s0, v96, 51
	v_cmp_lt_i32_e64 s[30:31], s77, v60
	s_nop 1

; __device__ __forceinline__ float sigmf(float x) { return 1.f / (1.f + __expf(-x)); }
; __device__ __forceinline__ bf16r f2bf(float f) {
;   unsigned u = __float_as_uint(f);
;   u += 0x7fffu + ((u >> 16) & 1u);
;   return (bf16r)(u >> 16);
; }
; __device__ __forceinline__ void inproj_epilogue(const Params& p, int layer, int mt, int ntile, int tid,
;                                                 f32x16 (&acc)[2][2], unsigned char* smem) {
;     ...
;     acc_foreach(tid, acc, [&](int row, int col, float v) {
;       int t = m0 + row;
;       float o = v;
;       if (mode == 1) o = (t >= NPADR) ? v : 0.f;
;       if (mode == 2) o = sigmf(v);
;       sT[row * 136 + col] = f2bf(o);
;     });
.LBB0_991:
	v_bfe_u32 v61, v60, 16, 1
	v_add_u32_e32 v55, 0x110, v55
	v_add3_u32 v61, v60, v61, s79
	v_lshl_add_u32 v60, v106, 1, v55
	ds_write_b16_d16_hi v60, v61
	v_add3_u32 v61, s0, v96, 56
	v_cmp_lt_i32_e64 s[34:35], s77, v61
	s_nop 1

; __device__ __forceinline__ float sigmf(float x) { return 1.f / (1.f + __expf(-x)); }
; __device__ __forceinline__ bf16r f2bf(float f) {
;   unsigned u = __float_as_uint(f);
;   u += 0x7fffu + ((u >> 16) & 1u);
;   return (bf16r)(u >> 16);
; }
; __device__ __forceinline__ void inproj_epilogue(const Params& p, int layer, int mt, int ntile, int tid,
;                                                 f32x16 (&acc)[2][2], unsigned char* smem) {
;     ...
;     acc_foreach(tid, acc, [&](int row, int col, float v) {
;       int t = m0 + row;
;       float o = v;
;       if (mode == 1) o = (t >= NPADR) ? v : 0.f;
;       if (mode == 2) o = sigmf(v);
;       sT[row * 136 + col] = f2bf(o);
;     });
.LBB0_994:
	v_bfe_u32 v62, v61, 16, 1
	v_add_u32_e32 v55, 0x550, v55
	v_add3_u32 v62, v61, v62, s79
	v_lshl_add_u32 v61, v106, 1, v55
	ds_write_b16_d16_hi v61, v62
	v_add3_u32 v62, s0, v96, 57
	v_cmp_lt_i32_e64 s[36:37], s77, v62
	s_nop 1

; __device__ __forceinline__ float sigmf(float x) { return 1.f / (1.f + __expf(-x)); }
; __device__ __forceinline__ bf16r f2bf(float f) {
;   unsigned u = __float_as_uint(f);
;   u += 0x7fffu + ((u >> 16) & 1u);
;   return (bf16r)(u >> 16);
; }
; __device__ __forceinline__ void inproj_epilogue(const Params& p, int layer, int mt, int ntile, int tid,
;                                                 f32x16 (&acc)[2][2], unsigned char* smem) {
;     ...
;     acc_foreach(tid, acc, [&](int row, int col, float v) {
;       int t = m0 + row;
;       float o = v;
;       if (mode == 1) o = (t >= NPADR) ? v : 0.f;
;       if (mode == 2) o = sigmf(v);
;       sT[row * 136 + col] = f2bf(o);
;     });
.LBB0_997:
	v_bfe_u32 v63, v62, 16, 1
	v_add_u32_e32 v55, 0x110, v55
	v_add3_u32 v63, v62, v63, s79
	v_lshl_add_u32 v62, v106, 1, v55
	ds_write_b16_d16_hi v62, v63
	v_add3_u32 v63, s0, v96, 58
	v_cmp_lt_i32_e64 s[38:39], s77, v63
	s_nop 1

; __device__ __forceinline__ float sigmf(float x) { return 1.f / (1.f + __expf(-x)); }
; __device__ __forceinline__ bf16r f2bf(float f) {
;   unsigned u = __float_as_uint(f);
;   u += 0x7fffu + ((u >> 16) & 1u);
;   return (bf16r)(u >> 16);
; }
; __device__ __forceinline__ void inproj_epilogue(const Params& p, int layer, int mt, int ntile, int tid,
;                                                 f32x16 (&acc)[2][2], unsigned char* smem) {
;     ...
;     acc_foreach(tid, acc, [&](int row, int col, float v) {
;       int t = m0 + row;
;       float o = v;
;       if (mode == 1) o = (t >= NPADR) ? v : 0.f;
;       if (mode == 2) o = sigmf(v);
;       sT[row * 136 + col] = f2bf(o);
;     });
.LBB0_1000:
	v_bfe_u32 v107, v63, 16, 1
	v_add_u32_e32 v55, 0x110, v55
	v_add3_u32 v63, v63, v107, s79
	v_lshl_add_u32 v55, v106, 1, v55
	ds_write_b16_d16_hi v55, v63
	v_add3_u32 v63, s0, v96, 59
	v_cmp_lt_i32_e64 s[40:41], s77, v63
	s_nop 1

; __device__ __forceinline__ float sigmf(float x) { return 1.f / (1.f + __expf(-x)); }
; __device__ __forceinline__ bf16r f2bf(float f) {
;   unsigned u = __float_as_uint(f);
;   u += 0x7fffu + ((u >> 16) & 1u);
;   return (bf16r)(u >> 16);
; }
; __device__ __forceinline__ void inproj_epilogue(const Params& p, int layer, int mt, int ntile, int tid,
;                                                 f32x16 (&acc)[2][2], unsigned char* smem) {
;     ...
;     acc_foreach(tid, acc, [&](int row, int col, float v) {
;       int t = m0 + row;
;       float o = v;
;       if (mode == 1) o = (t >= NPADR) ? v : 0.f;
;       if (mode == 2) o = sigmf(v);
;       sT[row * 136 + col] = f2bf(o);
;     });
.LBB0_1003:
	v_bfe_u32 v96, v63, 16, 1
	v_add3_u32 v63, v63, v96, s79
	ds_write_b16_d16_hi v55, v63 offset:272
	s_nop 1

; __device__ __forceinline__ float sigmf(float x) { return 1.f / (1.f + __expf(-x)); }
; __device__ __forceinline__ bf16r f2bf(float f) {
;   unsigned u = __float_as_uint(f);
;   u += 0x7fffu + ((u >> 16) & 1u);
;   return (bf16r)(u >> 16);
; }
; __device__ __forceinline__ void inproj_epilogue(const Params& p, int layer, int mt, int ntile, int tid,
;                                                 f32x16 (&acc)[2][2], unsigned char* smem) {
;     ...
;     acc_foreach(tid, acc, [&](int row, int col, float v) {
;       int t = m0 + row;
;       float o = v;
;       if (mode == 1) o = (t >= NPADR) ? v : 0.f;
;       if (mode == 2) o = sigmf(v);
;       sT[row * 136 + col] = f2bf(o);
;     });
.LBB0_1006:
	v_bfe_u32 v63, v32, 16, 1
	v_add3_u32 v32, v32, v63, s79
	ds_write_b16_d16_hi v48, v32 offset:64
	s_nop 1

; __device__ __forceinline__ float sigmf(float x) { return 1.f / (1.f + __expf(-x)); }
; __device__ __forceinline__ bf16r f2bf(float f) {
;   unsigned u = __float_as_uint(f);
;   u += 0x7fffu + ((u >> 16) & 1u);
;   return (bf16r)(u >> 16);
; }
; __device__ __forceinline__ void inproj_epilogue(const Params& p, int layer, int mt, int ntile, int tid,
;                                                 f32x16 (&acc)[2][2], unsigned char* smem) {
;     ...
;     acc_foreach(tid, acc, [&](int row, int col, float v) {
;       int t = m0 + row;
;       float o = v;
;       if (mode == 1) o = (t >= NPADR) ? v : 0.f;
;       if (mode == 2) o = sigmf(v);
;       sT[row * 136 + col] = f2bf(o);
;     });
.LBB0_1009:
	v_bfe_u32 v33, v32, 16, 1
	v_add3_u32 v32, v32, v33, s79
	ds_write_b16_d16_hi v49, v32 offset:64
	s_nop 1

; __device__ __forceinline__ float sigmf(float x) { return 1.f / (1.f + __expf(-x)); }
; __device__ __forceinline__ bf16r f2bf(float f) {
;   unsigned u = __float_as_uint(f);
;   u += 0x7fffu + ((u >> 16) & 1u);
;   return (bf16r)(u >> 16);
; }
; __device__ __forceinline__ void inproj_epilogue(const Params& p, int layer, int mt, int ntile, int tid,
;                                                 f32x16 (&acc)[2][2], unsigned char* smem) {
;     ...
;     acc_foreach(tid, acc, [&](int row, int col, float v) {
;       int t = m0 + row;
;       float o = v;
;       if (mode == 1) o = (t >= NPADR) ? v : 0.f;
;       if (mode == 2) o = sigmf(v);
;       sT[row * 136 + col] = f2bf(o);
;     });
.LBB0_1012:
	v_bfe_u32 v33, v32, 16, 1
	v_add3_u32 v32, v32, v33, s79
	ds_write_b16_d16_hi v50, v32 offset:64
	s_nop 1

; __device__ __forceinline__ float sigmf(float x) { return 1.f / (1.f + __expf(-x)); }
; __device__ __forceinline__ bf16r f2bf(float f) {
;   unsigned u = __float_as_uint(f);
;   u += 0x7fffu + ((u >> 16) & 1u);
;   return (bf16r)(u >> 16);
; }
; __device__ __forceinline__ void inproj_epilogue(const Params& p, int layer, int mt, int ntile, int tid,
;                                                 f32x16 (&acc)[2][2], unsigned char* smem) {
;     ...
;     acc_foreach(tid, acc, [&](int row, int col, float v) {
;       int t = m0 + row;
;       float o = v;
;       if (mode == 1) o = (t >= NPADR) ? v : 0.f;
;       if (mode == 2) o = sigmf(v);
;       sT[row * 136 + col] = f2bf(o);
;     });
.LBB0_1015:
	v_bfe_u32 v33, v32, 16, 1
	v_add3_u32 v32, v32, v33, s79
	ds_write_b16_d16_hi v51, v32 offset:64
	s_nop 1

; __device__ __forceinline__ float sigmf(float x) { return 1.f / (1.f + __expf(-x)); }
; __device__ __forceinline__ bf16r f2bf(float f) {
;   unsigned u = __float_as_uint(f);
;   u += 0x7fffu + ((u >> 16) & 1u);
;   return (bf16r)(u >> 16);
; }
; __device__ __forceinline__ void inproj_epilogue(const Params& p, int layer, int mt, int ntile, int tid,
;                                                 f32x16 (&acc)[2][2], unsigned char* smem) {
;     ...
;     acc_foreach(tid, acc, [&](int row, int col, float v) {
;       int t = m0 + row;
;       float o = v;
;       if (mode == 1) o = (t >= NPADR) ? v : 0.f;
;       if (mode == 2) o = sigmf(v);
;       sT[row * 136 + col] = f2bf(o);
;     });
.LBB0_1018:
	v_bfe_u32 v33, v32, 16, 1
	v_add3_u32 v32, v32, v33, s79
	ds_write_b16_d16_hi v52, v32 offset:64
	s_nop 1

; __device__ __forceinline__ float sigmf(float x) { return 1.f / (1.f + __expf(-x)); }
; __device__ __forceinline__ bf16r f2bf(float f) {
;   unsigned u = __float_as_uint(f);
;   u += 0x7fffu + ((u >> 16) & 1u);
;   return (bf16r)(u >> 16);
; }
; __device__ __forceinline__ void inproj_epilogue(const Params& p, int layer, int mt, int ntile, int tid,
;                                                 f32x16 (&acc)[2][2], unsigned char* smem) {
;     ...
;     acc_foreach(tid, acc, [&](int row, int col, float v) {
;       int t = m0 + row;
;       float o = v;
;       if (mode == 1) o = (t >= NPADR) ? v : 0.f;
;       if (mode == 2) o = sigmf(v);
;       sT[row * 136 + col] = f2bf(o);
;     });
.LBB0_1021:
	v_bfe_u32 v33, v32, 16, 1
	v_add3_u32 v32, v32, v33, s79
	ds_write_b16_d16_hi v53, v32 offset:64
	s_nop 1

; __device__ __forceinline__ float sigmf(float x) { return 1.f / (1.f + __expf(-x)); }
; __device__ __forceinline__ bf16r f2bf(float f) {
;   unsigned u = __float_as_uint(f);
;   u += 0x7fffu + ((u >> 16) & 1u);
;   return (bf16r)(u >> 16);
; }
; __device__ __forceinline__ void inproj_epilogue(const Params& p, int layer, int mt, int ntile, int tid,
;                                                 f32x16 (&acc)[2][2], unsigned char* smem) {
;     ...
;     acc_foreach(tid, acc, [&](int row, int col, float v) {
;       int t = m0 + row;
;       float o = v;
;       if (mode == 1) o = (t >= NPADR) ? v : 0.f;
;       if (mode == 2) o = sigmf(v);
;       sT[row * 136 + col] = f2bf(o);
;     });
.LBB0_1024:
	v_bfe_u32 v33, v32, 16, 1
	v_add3_u32 v32, v32, v33, s79
	ds_write_b16_d16_hi v54, v32 offset:64
	s_nop 1

; __device__ __forceinline__ float sigmf(float x) { return 1.f / (1.f + __expf(-x)); }
; __device__ __forceinline__ void inproj_epilogue(const Params& p, int layer, int mt, int ntile, int tid,
;                                                 f32x16 (&acc)[2][2], unsigned char* smem) {
;     ...
;     acc_foreach(tid, acc, [&](int row, int col, float v) {
;       int t = m0 + row;
;       float o = v;
;       if (mode == 1) o = (t >= NPADR) ? v : 0.f;
;       if (mode == 2) o = sigmf(v);
;       sT[row * 136 + col] = f2bf(o);
;     });
.LBB0_1027:
	v_bfe_u32 v33, v32, 16, 1
	v_add3_u32 v32, v32, v33, s79
	ds_write_b16_d16_hi v56, v32 offset:64
	s_nop 1

; __device__ __forceinline__ float sigmf(float x) { return 1.f / (1.f + __expf(-x)); }
; __device__ __forceinline__ void inproj_epilogue(const Params& p, int layer, int mt, int ntile, int tid,
;                                                 f32x16 (&acc)[2][2], unsigned char* smem) {
;     ...
;     acc_foreach(tid, acc, [&](int row, int col, float v) {
;       int t = m0 + row;
;       float o = v;
;       if (mode == 1) o = (t >= NPADR) ? v : 0.f;
;       if (mode == 2) o = sigmf(v);
;       sT[row * 136 + col] = f2bf(o);
;     });
.LBB0_1030:
	v_bfe_u32 v33, v32, 16, 1
	v_add3_u32 v32, v32, v33, s79
	ds_write_b16_d16_hi v57, v32 offset:64
	s_nop 1

; __device__ __forceinline__ float sigmf(float x) { return 1.f / (1.f + __expf(-x)); }
; __device__ __forceinline__ void inproj_epilogue(const Params& p, int layer, int mt, int ntile, int tid,
;                                                 f32x16 (&acc)[2][2], unsigned char* smem) {
;     ...
;     acc_foreach(tid, acc, [&](int row, int col, float v) {
;       int t = m0 + row;
;       float o = v;
;       if (mode == 1) o = (t >= NPADR) ? v : 0.f;
;       if (mode == 2) o = sigmf(v);
;       sT[row * 136 + col] = f2bf(o);
;     });
.LBB0_1033:
	v_bfe_u32 v33, v32, 16, 1
	v_add3_u32 v32, v32, v33, s79
	ds_write_b16_d16_hi v58, v32 offset:64
	s_nop 1

; __device__ __forceinline__ float sigmf(float x) { return 1.f / (1.f + __expf(-x)); }
; __device__ __forceinline__ void inproj_epilogue(const Params& p, int layer, int mt, int ntile, int tid,
;                                                 f32x16 (&acc)[2][2], unsigned char* smem) {
;     ...
;     acc_foreach(tid, acc, [&](int row, int col, float v) {
;       int t = m0 + row;
;       float o = v;
;       if (mode == 1) o = (t >= NPADR) ? v : 0.f;
;       if (mode == 2) o = sigmf(v);
;       sT[row * 136 + col] = f2bf(o);
;     });
.LBB0_1036:
	v_bfe_u32 v33, v32, 16, 1
	v_add3_u32 v32, v32, v33, s79
	ds_write_b16_d16_hi v59, v32 offset:64
	s_nop 1

; __device__ __forceinline__ float sigmf(float x) { return 1.f / (1.f + __expf(-x)); }
; __device__ __forceinline__ void inproj_epilogue(const Params& p, int layer, int mt, int ntile, int tid,
;                                                 f32x16 (&acc)[2][2], unsigned char* smem) {
;     ...
;     acc_foreach(tid, acc, [&](int row, int col, float v) {
;       int t = m0 + row;
;       float o = v;
;       if (mode == 1) o = (t >= NPADR) ? v : 0.f;
;       if (mode == 2) o = sigmf(v);
;       sT[row * 136 + col] = f2bf(o);
;     });
.LBB0_1039:
	v_bfe_u32 v33, v32, 16, 1
	v_add3_u32 v32, v32, v33, s79
	ds_write_b16_d16_hi v60, v32 offset:64
	s_nop 1

; __device__ __forceinline__ float sigmf(float x) { return 1.f / (1.f + __expf(-x)); }
; __device__ __forceinline__ void inproj_epilogue(const Params& p, int layer, int mt, int ntile, int tid,
;                                                 f32x16 (&acc)[2][2], unsigned char* smem) {
;     ...
;     acc_foreach(tid, acc, [&](int row, int col, float v) {
;       int t = m0 + row;
;       float o = v;
;       if (mode == 1) o = (t >= NPADR) ? v : 0.f;
;       if (mode == 2) o = sigmf(v);
;       sT[row * 136 + col] = f2bf(o);
;     });
.LBB0_1042:
	v_bfe_u32 v33, v32, 16, 1
	v_add3_u32 v32, v32, v33, s79
	ds_write_b16_d16_hi v61, v32 offset:64
	s_nop 1

; __device__ __forceinline__ float sigmf(float x) { return 1.f / (1.f + __expf(-x)); }
; __device__ __forceinline__ void inproj_epilogue(const Params& p, int layer, int mt, int ntile, int tid,
;                                                 f32x16 (&acc)[2][2], unsigned char* smem) {
;     ...
;     acc_foreach(tid, acc, [&](int row, int col, float v) {
;       int t = m0 + row;
;       float o = v;
;       if (mode == 1) o = (t >= NPADR) ? v : 0.f;
;       if (mode == 2) o = sigmf(v);
;       sT[row * 136 + col] = f2bf(o);
;     });
.LBB0_1045:
	v_bfe_u32 v33, v32, 16, 1
	v_add3_u32 v32, v32, v33, s79
	ds_write_b16_d16_hi v62, v32 offset:64
	s_nop 1

; __device__ __forceinline__ float sigmf(float x) { return 1.f / (1.f + __expf(-x)); }
; __device__ __forceinline__ void inproj_epilogue(const Params& p, int layer, int mt, int ntile, int tid,
;                                                 f32x16 (&acc)[2][2], unsigned char* smem) {
;     ...
;     acc_foreach(tid, acc, [&](int row, int col, float v) {
;       int t = m0 + row;
;       float o = v;
;       if (mode == 1) o = (t >= NPADR) ? v : 0.f;
;       if (mode == 2) o = sigmf(v);
;       sT[row * 136 + col] = f2bf(o);
;     });
.LBB0_1048:
	v_bfe_u32 v33, v32, 16, 1
	v_add3_u32 v32, v32, v33, s79
	ds_write_b16_d16_hi v55, v32 offset:64
	s_nop 1

; __device__ __forceinline__ float sigmf(float x) { return 1.f / (1.f + __expf(-x)); }
; __device__ __forceinline__ void inproj_epilogue(const Params& p, int layer, int mt, int ntile, int tid,
;                                                 f32x16 (&acc)[2][2], unsigned char* smem) {
;     ...
;     acc_foreach(tid, acc, [&](int row, int col, float v) {
;       int t = m0 + row;
;       float o = v;
;       if (mode == 1) o = (t >= NPADR) ? v : 0.f;
;       if (mode == 2) o = sigmf(v);
;       sT[row * 136 + col] = f2bf(o);
;     });
.Lgv_2:
	v_mul_f32_e32 v107, 0xbfb8aa3b, v16
	v_exp_f32_e32 v107, v107
	s_nop 0
	v_add_f32_e32 v107, 1.0, v107
	v_div_scale_f32 v110, s[6:7], v107, v107, 1.0
	v_rcp_f32_e32 v111, v110
	v_div_scale_f32 v112, vcc, 1.0, v107, 1.0
	v_fma_f32 v113, -v110, v111, 1.0
	v_fmac_f32_e32 v111, v113, v111
	v_mul_f32_e32 v113, v112, v111
	v_fma_f32 v114, -v110, v113, v112
	v_fmac_f32_e32 v113, v114, v111
	v_fma_f32 v110, -v110, v113, v112
	v_div_fmas_f32 v110, v110, v111, v113
	v_div_fixup_f32 v107, v110, v107, 1.0
	v_bfe_u32 v110, v107, 16, 1
	v_and_b32_e32 v106, 0x5f, v106
	v_add3_u32 v111, v107, v110, s79
	v_mul_lo_u32 v110, v96, s80
	v_lshl_add_u32 v107, v106, 1, v110
	ds_write_b16_d16_hi v107, v111
	v_add3_u32 v111, s0, v96, 1
	v_cmp_lt_i32_e64 s[10:11], s77, v111
	v_cndmask_b32_e64 v111, 0, 1, s[12:13]
	v_cmp_ne_u32_e64 s[6:7], 1, v111
	s_andn2_b64 vcc, exec, s[12:13]
	v_mul_f32_e32 v111, 0xbfb8aa3b, v17
	v_exp_f32_e32 v111, v111
	s_nop 0
	v_add_f32_e32 v111, 1.0, v111
	v_div_scale_f32 v112, s[12:13], v111, v111, 1.0
	v_rcp_f32_e32 v113, v112
	v_div_scale_f32 v114, vcc, 1.0, v111, 1.0
	v_fma_f32 v115, -v112, v113, 1.0
	v_fmac_f32_e32 v113, v115, v113
	v_mul_f32_e32 v115, v114, v113
	v_fma_f32 v116, -v112, v115, v114
	v_fmac_f32_e32 v115, v116, v113
	v_fma_f32 v112, -v112, v115, v114
	v_div_fmas_f32 v112, v112, v113, v115
	v_div_fixup_f32 v111, v112, v111, 1.0
	v_bfe_u32 v112, v111, 16, 1
	v_add3_u32 v112, v111, v112, s79
	v_add_u32_e32 v111, 0x110, v110
	v_lshl_add_u32 v110, v106, 1, v111
	ds_write_b16_d16_hi v110, v112
	v_add3_u32 v112, s0, v96, 2
	s_and_b64 vcc, exec, s[6:7]
	v_cmp_lt_i32_e64 s[12:13], s77, v112
	v_mul_f32_e32 v112, 0xbfb8aa3b, v18
	v_exp_f32_e32 v112, v112
	s_nop 0
	v_add_f32_e32 v112, 1.0, v112
	v_div_scale_f32 v113, s[14:15], v112, v112, 1.0
	v_rcp_f32_e32 v114, v113
	v_div_scale_f32 v115, vcc, 1.0, v112, 1.0
	v_fma_f32 v116, -v113, v114, 1.0
	v_fmac_f32_e32 v114, v116, v114
	v_mul_f32_e32 v116, v115, v114
	v_fma_f32 v117, -v113, v116, v115
	v_fmac_f32_e32 v116, v117, v114
	v_fma_f32 v113, -v113, v116, v115
	v_div_fmas_f32 v113, v113, v114, v116
	v_div_fixup_f32 v112, v113, v112, 1.0
	v_bfe_u32 v113, v112, 16, 1
	v_add3_u32 v113, v112, v113, s79
	v_add_u32_e32 v112, 0x110, v111
	v_lshl_add_u32 v111, v106, 1, v112
	ds_write_b16_d16_hi v111, v113
	v_add3_u32 v113, s0, v96, 3
	s_and_b64 vcc, exec, s[6:7]
	v_cmp_lt_i32_e64 s[14:15], s77, v113
	v_mul_f32_e32 v113, 0xbfb8aa3b, v19
	v_exp_f32_e32 v113, v113
	s_nop 0
	v_add_f32_e32 v113, 1.0, v113
	v_div_scale_f32 v114, s[16:17], v113, v113, 1.0
	v_rcp_f32_e32 v115, v114
	v_div_scale_f32 v116, vcc, 1.0, v113, 1.0
	v_fma_f32 v117, -v114, v115, 1.0
	v_fmac_f32_e32 v115, v117, v115
	v_mul_f32_e32 v117, v116, v115
	v_fma_f32 v118, -v114, v117, v116
	v_fmac_f32_e32 v117, v118, v115
	v_fma_f32 v114, -v114, v117, v116
	v_div_fmas_f32 v114, v114, v115, v117
	v_div_fixup_f32 v113, v114, v113, 1.0
	v_bfe_u32 v114, v113, 16, 1
	v_add3_u32 v114, v113, v114, s79
	v_add_u32_e32 v113, 0x110, v112
	v_lshl_add_u32 v112, v106, 1, v113
	ds_write_b16_d16_hi v112, v114
	v_add3_u32 v114, s0, v96, 8
	s_and_b64 vcc, exec, s[6:7]
	v_cmp_lt_i32_e64 s[16:17], s77, v114
	v_mul_f32_e32 v114, 0xbfb8aa3b, v20
	v_exp_f32_e32 v114, v114
	s_nop 0
	v_add_f32_e32 v114, 1.0, v114
	v_div_scale_f32 v115, s[18:19], v114, v114, 1.0
	v_rcp_f32_e32 v116, v115
	v_div_scale_f32 v117, vcc, 1.0, v114, 1.0
	v_fma_f32 v118, -v115, v116, 1.0
	v_fmac_f32_e32 v116, v118, v116
	v_mul_f32_e32 v118, v117, v116
	v_fma_f32 v119, -v115, v118, v117
	v_fmac_f32_e32 v118, v119, v116
	v_fma_f32 v115, -v115, v118, v117
	v_div_fmas_f32 v115, v115, v116, v118
	v_div_fixup_f32 v114, v115, v114, 1.0
	v_bfe_u32 v115, v114, 16, 1
	v_add3_u32 v115, v114, v115, s79
	v_add_u32_e32 v114, 0x550, v113
	v_lshl_add_u32 v113, v106, 1, v114
	ds_write_b16_d16_hi v113, v115
	v_add3_u32 v115, s0, v96, 9
	s_and_b64 vcc, exec, s[6:7]
	v_cmp_lt_i32_e64 s[18:19], s77, v115
	v_mul_f32_e32 v115, 0xbfb8aa3b, v21
	v_exp_f32_e32 v115, v115
	s_nop 0
	v_add_f32_e32 v115, 1.0, v115
	v_div_scale_f32 v116, s[20:21], v115, v115, 1.0
	v_rcp_f32_e32 v117, v116
	v_div_scale_f32 v118, vcc, 1.0, v115, 1.0
	v_fma_f32 v119, -v116, v117, 1.0
	v_fmac_f32_e32 v117, v119, v117
	v_mul_f32_e32 v119, v118, v117
	v_fma_f32 v120, -v116, v119, v118
	v_fmac_f32_e32 v119, v120, v117
	v_fma_f32 v116, -v116, v119, v118
	v_div_fmas_f32 v116, v116, v117, v119
	v_div_fixup_f32 v115, v116, v115, 1.0
	v_bfe_u32 v116, v115, 16, 1
	v_add3_u32 v116, v115, v116, s79
	v_add_u32_e32 v115, 0x110, v114
	v_lshl_add_u32 v114, v106, 1, v115
	ds_write_b16_d16_hi v114, v116
	v_add3_u32 v116, s0, v96, 10
	s_and_b64 vcc, exec, s[6:7]
	v_cmp_lt_i32_e64 s[20:21], s77, v116
	v_mul_f32_e32 v116, 0xbfb8aa3b, v22
	v_exp_f32_e32 v116, v116
	s_nop 0
	v_add_f32_e32 v116, 1.0, v116
	v_div_scale_f32 v117, s[22:23], v116, v116, 1.0
	v_rcp_f32_e32 v118, v117
	v_div_scale_f32 v119, vcc, 1.0, v116, 1.0
	v_fma_f32 v120, -v117, v118, 1.0
	v_fmac_f32_e32 v118, v120, v118
	v_mul_f32_e32 v120, v119, v118
	v_fma_f32 v121, -v117, v120, v119
	v_fmac_f32_e32 v120, v121, v118
	v_fma_f32 v117, -v117, v120, v119
	v_div_fmas_f32 v117, v117, v118, v120
	v_div_fixup_f32 v116, v117, v116, 1.0
	v_bfe_u32 v117, v116, 16, 1
	v_add3_u32 v117, v116, v117, s79
	v_add_u32_e32 v116, 0x110, v115
	v_lshl_add_u32 v115, v106, 1, v116
	ds_write_b16_d16_hi v115, v117
	v_add3_u32 v117, s0, v96, 11
	s_and_b64 vcc, exec, s[6:7]
	v_cmp_lt_i32_e64 s[22:23], s77, v117
	v_mul_f32_e32 v117, 0xbfb8aa3b, v23
	v_exp_f32_e32 v117, v117
	s_nop 0
	v_add_f32_e32 v117, 1.0, v117
	v_div_scale_f32 v118, s[24:25], v117, v117, 1.0
	v_rcp_f32_e32 v119, v118
; __device__ __forceinline__ float sigmf(float x) { return 1.f / (1.f + __expf(-x)); }
; __device__ __forceinline__ void inproj_epilogue(const Params& p, int layer, int mt, int ntile, int tid,
;                                                 f32x16 (&acc)[2][2], unsigned char* smem) {
;     ...
;     acc_foreach(tid, acc, [&](int row, int col, float v) {
;       int t = m0 + row;
;       float o = v;
;       if (mode == 1) o = (t >= NPADR) ? v : 0.f;
;       if (mode == 2) o = sigmf(v);
;       sT[row * 136 + col] = f2bf(o);
;     });
	v_div_scale_f32 v120, vcc, 1.0, v117, 1.0
	v_fma_f32 v121, -v118, v119, 1.0
	v_fmac_f32_e32 v119, v121, v119
	v_mul_f32_e32 v121, v120, v119
	v_fma_f32 v122, -v118, v121, v120
	v_fmac_f32_e32 v121, v122, v119
	v_fma_f32 v118, -v118, v121, v120
	v_div_fmas_f32 v118, v118, v119, v121
	v_div_fixup_f32 v117, v118, v117, 1.0
	v_bfe_u32 v118, v117, 16, 1
	v_add_u32_e32 v116, 0x110, v116
	v_add3_u32 v118, v117, v118, s79
	v_lshl_add_u32 v117, v106, 1, v116
	ds_write_b16_d16_hi v117, v118
	v_add3_u32 v118, s0, v96, 16
	s_and_b64 vcc, exec, s[6:7]
	v_cmp_lt_i32_e64 s[24:25], s77, v118
	v_mul_f32_e32 v118, 0xbfb8aa3b, v24
	v_exp_f32_e32 v118, v118
	s_nop 0
	v_add_f32_e32 v118, 1.0, v118
	v_div_scale_f32 v119, s[26:27], v118, v118, 1.0
	v_rcp_f32_e32 v120, v119
	v_div_scale_f32 v121, vcc, 1.0, v118, 1.0
	v_fma_f32 v122, -v119, v120, 1.0
	v_fmac_f32_e32 v120, v122, v120
	v_mul_f32_e32 v122, v121, v120
	v_fma_f32 v123, -v119, v122, v121
	v_fmac_f32_e32 v122, v123, v120
	v_fma_f32 v119, -v119, v122, v121
	v_div_fmas_f32 v119, v119, v120, v122
	v_div_fixup_f32 v118, v119, v118, 1.0
	v_bfe_u32 v119, v118, 16, 1
	v_add_u32_e32 v116, 0x550, v116
	v_add3_u32 v119, v118, v119, s79
	v_lshl_add_u32 v118, v106, 1, v116
	ds_write_b16_d16_hi v118, v119
	v_add3_u32 v119, s0, v96, 17
	s_and_b64 vcc, exec, s[6:7]
	v_cmp_lt_i32_e64 s[26:27], s77, v119
	v_mul_f32_e32 v119, 0xbfb8aa3b, v25
	v_exp_f32_e32 v119, v119
	s_nop 0
	v_add_f32_e32 v119, 1.0, v119
	v_div_scale_f32 v120, s[28:29], v119, v119, 1.0
	v_rcp_f32_e32 v121, v120
	v_div_scale_f32 v122, vcc, 1.0, v119, 1.0
	v_fma_f32 v123, -v120, v121, 1.0
	v_fmac_f32_e32 v121, v123, v121
	v_mul_f32_e32 v123, v122, v121
	v_fma_f32 v124, -v120, v123, v122
	v_fmac_f32_e32 v123, v124, v121
	v_fma_f32 v120, -v120, v123, v122
	v_div_fmas_f32 v120, v120, v121, v123
	v_div_fixup_f32 v119, v120, v119, 1.0
	v_bfe_u32 v120, v119, 16, 1
	v_add_u32_e32 v116, 0x110, v116
	v_add3_u32 v120, v119, v120, s79
	v_lshl_add_u32 v119, v106, 1, v116
	ds_write_b16_d16_hi v119, v120
	v_add3_u32 v120, s0, v96, 18
	s_and_b64 vcc, exec, s[6:7]
	v_cmp_lt_i32_e64 s[28:29], s77, v120
	v_mul_f32_e32 v120, 0xbfb8aa3b, v26
	v_exp_f32_e32 v120, v120
	s_nop 0
	v_add_f32_e32 v120, 1.0, v120
	v_div_scale_f32 v121, s[30:31], v120, v120, 1.0
	v_rcp_f32_e32 v122, v121
	v_div_scale_f32 v123, vcc, 1.0, v120, 1.0
	v_fma_f32 v124, -v121, v122, 1.0
	v_fmac_f32_e32 v122, v124, v122
	v_mul_f32_e32 v124, v123, v122
	v_fma_f32 v125, -v121, v124, v123
	v_fmac_f32_e32 v124, v125, v122
	v_fma_f32 v121, -v121, v124, v123
	v_div_fmas_f32 v121, v121, v122, v124
	v_div_fixup_f32 v120, v121, v120, 1.0
	v_bfe_u32 v121, v120, 16, 1
	v_add_u32_e32 v116, 0x110, v116
	v_add3_u32 v121, v120, v121, s79
	v_lshl_add_u32 v120, v106, 1, v116
	ds_write_b16_d16_hi v120, v121
	v_add3_u32 v121, s0, v96, 19
	s_and_b64 vcc, exec, s[6:7]
	v_cmp_lt_i32_e64 s[30:31], s77, v121
	v_mul_f32_e32 v121, 0xbfb8aa3b, v27
	v_exp_f32_e32 v121, v121
	s_nop 0
	v_add_f32_e32 v121, 1.0, v121
	v_div_scale_f32 v122, s[34:35], v121, v121, 1.0
	v_rcp_f32_e32 v123, v122
	v_div_scale_f32 v124, vcc, 1.0, v121, 1.0
	v_fma_f32 v125, -v122, v123, 1.0
	v_fmac_f32_e32 v123, v125, v123
	v_mul_f32_e32 v125, v124, v123
	v_fma_f32 v126, -v122, v125, v124
	v_fmac_f32_e32 v125, v126, v123
	v_fma_f32 v122, -v122, v125, v124
	v_div_fmas_f32 v122, v122, v123, v125
	v_div_fixup_f32 v121, v122, v121, 1.0
	v_bfe_u32 v122, v121, 16, 1
	v_add_u32_e32 v116, 0x110, v116
	v_add3_u32 v122, v121, v122, s79
	v_lshl_add_u32 v121, v106, 1, v116
	ds_write_b16_d16_hi v121, v122
	v_add3_u32 v122, s0, v96, 24
	s_and_b64 vcc, exec, s[6:7]
	v_cmp_lt_i32_e64 s[34:35], s77, v122
	v_mul_f32_e32 v122, 0xbfb8aa3b, v28
	v_exp_f32_e32 v122, v122
	s_nop 0
	v_add_f32_e32 v122, 1.0, v122
	v_div_scale_f32 v123, s[36:37], v122, v122, 1.0
	v_rcp_f32_e32 v124, v123
	v_div_scale_f32 v125, vcc, 1.0, v122, 1.0
	v_fma_f32 v126, -v123, v124, 1.0
	v_fmac_f32_e32 v124, v126, v124
	v_mul_f32_e32 v126, v125, v124
	v_fma_f32 v127, -v123, v126, v125
	v_fmac_f32_e32 v126, v127, v124
	v_fma_f32 v123, -v123, v126, v125
	v_div_fmas_f32 v123, v123, v124, v126
	v_div_fixup_f32 v122, v123, v122, 1.0
	v_bfe_u32 v123, v122, 16, 1
	v_add_u32_e32 v116, 0x550, v116
	v_add3_u32 v123, v122, v123, s79
	v_lshl_add_u32 v122, v106, 1, v116
	ds_write_b16_d16_hi v122, v123
	v_add3_u32 v123, s0, v96, 25
	s_and_b64 vcc, exec, s[6:7]
	v_cmp_lt_i32_e64 s[36:37], s77, v123
	v_mul_f32_e32 v123, 0xbfb8aa3b, v29
	v_exp_f32_e32 v123, v123
	s_nop 0
	v_add_f32_e32 v123, 1.0, v123
	v_div_scale_f32 v124, s[38:39], v123, v123, 1.0
	v_rcp_f32_e32 v125, v124
	v_div_scale_f32 v126, vcc, 1.0, v123, 1.0
	v_fma_f32 v127, -v124, v125, 1.0
	v_fmac_f32_e32 v125, v127, v125
	v_mul_f32_e32 v127, v126, v125
	v_fma_f32 v128, -v124, v127, v126
	v_fmac_f32_e32 v127, v128, v125
	v_fma_f32 v124, -v124, v127, v126
	v_div_fmas_f32 v124, v124, v125, v127
	v_div_fixup_f32 v123, v124, v123, 1.0
	v_bfe_u32 v124, v123, 16, 1
	v_add_u32_e32 v116, 0x110, v116
	v_add3_u32 v124, v123, v124, s79
	v_lshl_add_u32 v123, v106, 1, v116
	ds_write_b16_d16_hi v123, v124
	v_add3_u32 v124, s0, v96, 26
	s_and_b64 vcc, exec, s[6:7]
	v_cmp_lt_i32_e64 s[38:39], s77, v124
	v_mul_f32_e32 v124, 0xbfb8aa3b, v30
	v_exp_f32_e32 v124, v124
	s_nop 0
	v_add_f32_e32 v124, 1.0, v124
	v_div_scale_f32 v125, s[40:41], v124, v124, 1.0
	v_rcp_f32_e32 v126, v125
	v_div_scale_f32 v127, vcc, 1.0, v124, 1.0
	v_fma_f32 v128, -v125, v126, 1.0
	v_fmac_f32_e32 v126, v128, v126
	v_mul_f32_e32 v128, v127, v126
	v_fma_f32 v129, -v125, v128, v127
	v_fmac_f32_e32 v128, v129, v126
	v_fma_f32 v125, -v125, v128, v127
	v_div_fmas_f32 v125, v125, v126, v128
	v_div_fixup_f32 v124, v125, v124, 1.0
; __device__ __forceinline__ float sigmf(float x) { return 1.f / (1.f + __expf(-x)); }
; __device__ __forceinline__ void inproj_epilogue(const Params& p, int layer, int mt, int ntile, int tid,
;                                                 f32x16 (&acc)[2][2], unsigned char* smem) {
;     ...
;     acc_foreach(tid, acc, [&](int row, int col, float v) {
;       int t = m0 + row;
;       float o = v;
;       if (mode == 1) o = (t >= NPADR) ? v : 0.f;
;       if (mode == 2) o = sigmf(v);
;       sT[row * 136 + col] = f2bf(o);
;     });
	v_bfe_u32 v125, v124, 16, 1
	v_add_u32_e32 v116, 0x110, v116
	v_add3_u32 v124, v124, v125, s79
	v_lshl_add_u32 v116, v106, 1, v116
	ds_write_b16_d16_hi v116, v124
	v_add3_u32 v124, s0, v96, 27
	s_and_b64 vcc, exec, s[6:7]
	v_cmp_lt_i32_e64 s[40:41], s77, v124
	v_mul_f32_e32 v124, 0xbfb8aa3b, v31
	v_exp_f32_e32 v124, v124
	s_nop 0
	v_add_f32_e32 v124, 1.0, v124
	v_div_scale_f32 v125, vcc, v124, v124, 1.0
	v_rcp_f32_e32 v126, v125
	v_div_scale_f32 v127, vcc, 1.0, v124, 1.0
	v_fma_f32 v128, -v125, v126, 1.0
	v_fmac_f32_e32 v126, v128, v126
	v_mul_f32_e32 v128, v127, v126
	v_fma_f32 v129, -v125, v128, v127
	v_fmac_f32_e32 v128, v129, v126
	v_fma_f32 v125, -v125, v128, v127
	v_div_fmas_f32 v125, v125, v126, v128
	v_div_fixup_f32 v124, v125, v124, 1.0
	v_bfe_u32 v125, v124, 16, 1
	v_add3_u32 v124, v124, v125, s79
	ds_write_b16_d16_hi v116, v124 offset:272
	s_and_b64 vcc, exec, s[6:7]
	v_mul_f32_e32 v48, 0xbfb8aa3b, v48
	v_exp_f32_e32 v48, v48
	s_nop 0
	v_add_f32_e32 v48, 1.0, v48
	v_div_scale_f32 v124, s[8:9], v48, v48, 1.0
	v_rcp_f32_e32 v125, v124
	v_div_scale_f32 v126, vcc, 1.0, v48, 1.0
	v_fma_f32 v127, -v124, v125, 1.0
	v_fmac_f32_e32 v125, v127, v125
	v_mul_f32_e32 v127, v126, v125
	v_fma_f32 v128, -v124, v127, v126
	v_fmac_f32_e32 v127, v128, v125
	v_fma_f32 v124, -v124, v127, v126
	v_div_fmas_f32 v124, v124, v125, v127
	v_div_fixup_f32 v48, v124, v48, 1.0
	v_bfe_u32 v124, v48, 16, 1
	v_add3_u32 v48, v48, v124, s79
	s_and_b64 vcc, exec, s[6:7]
	ds_write_b16_d16_hi v107, v48 offset:64
	v_mul_f32_e32 v48, 0xbfb8aa3b, v49
	v_exp_f32_e32 v48, v48
	s_nop 0
	v_add_f32_e32 v48, 1.0, v48
	v_div_scale_f32 v49, s[8:9], v48, v48, 1.0
	v_rcp_f32_e32 v107, v49
	v_div_scale_f32 v124, vcc, 1.0, v48, 1.0
	v_fma_f32 v125, -v49, v107, 1.0
	v_fmac_f32_e32 v107, v125, v107
	v_mul_f32_e32 v125, v124, v107
	v_fma_f32 v126, -v49, v125, v124
	v_fmac_f32_e32 v125, v126, v107
	v_fma_f32 v49, -v49, v125, v124
	v_div_fmas_f32 v49, v49, v107, v125
	v_div_fixup_f32 v48, v49, v48, 1.0
	v_bfe_u32 v49, v48, 16, 1
	v_add3_u32 v48, v48, v49, s79
	s_and_b64 vcc, exec, s[6:7]
	ds_write_b16_d16_hi v110, v48 offset:64
	v_mul_f32_e32 v48, 0xbfb8aa3b, v50
	v_exp_f32_e32 v48, v48
	s_nop 0
	v_add_f32_e32 v48, 1.0, v48
	v_div_scale_f32 v49, s[8:9], v48, v48, 1.0
	v_rcp_f32_e32 v50, v49
	v_div_scale_f32 v107, vcc, 1.0, v48, 1.0
	v_fma_f32 v110, -v49, v50, 1.0
	v_fmac_f32_e32 v50, v110, v50
	v_mul_f32_e32 v110, v107, v50
	v_fma_f32 v124, -v49, v110, v107
	v_fmac_f32_e32 v110, v124, v50
	v_fma_f32 v49, -v49, v110, v107
	v_div_fmas_f32 v49, v49, v50, v110
	v_div_fixup_f32 v48, v49, v48, 1.0
	v_bfe_u32 v49, v48, 16, 1
	v_add3_u32 v48, v48, v49, s79
	s_and_b64 vcc, exec, s[6:7]
	ds_write_b16_d16_hi v111, v48 offset:64
	v_mul_f32_e32 v48, 0xbfb8aa3b, v51
	v_exp_f32_e32 v48, v48
	s_nop 0
	v_add_f32_e32 v48, 1.0, v48
	v_div_scale_f32 v49, s[8:9], v48, v48, 1.0
	v_rcp_f32_e32 v50, v49
	v_div_scale_f32 v51, vcc, 1.0, v48, 1.0
	v_fma_f32 v107, -v49, v50, 1.0
	v_fmac_f32_e32 v50, v107, v50
	v_mul_f32_e32 v107, v51, v50
	v_fma_f32 v110, -v49, v107, v51
	v_fmac_f32_e32 v107, v110, v50
	v_fma_f32 v49, -v49, v107, v51
	v_div_fmas_f32 v49, v49, v50, v107
	v_div_fixup_f32 v48, v49, v48, 1.0
	v_bfe_u32 v49, v48, 16, 1
	v_add3_u32 v48, v48, v49, s79
	s_and_b64 vcc, exec, s[6:7]
	ds_write_b16_d16_hi v112, v48 offset:64
	v_mul_f32_e32 v48, 0xbfb8aa3b, v52
	v_exp_f32_e32 v48, v48
	s_nop 0
	v_add_f32_e32 v48, 1.0, v48
	v_div_scale_f32 v49, s[8:9], v48, v48, 1.0
	v_rcp_f32_e32 v50, v49
	v_div_scale_f32 v51, vcc, 1.0, v48, 1.0
	v_fma_f32 v52, -v49, v50, 1.0
	v_fmac_f32_e32 v50, v52, v50
	v_mul_f32_e32 v52, v51, v50
	v_fma_f32 v107, -v49, v52, v51
	v_fmac_f32_e32 v52, v107, v50
	v_fma_f32 v49, -v49, v52, v51
	v_div_fmas_f32 v49, v49, v50, v52
	v_div_fixup_f32 v48, v49, v48, 1.0
	v_bfe_u32 v49, v48, 16, 1
	v_add3_u32 v48, v48, v49, s79
	s_and_b64 vcc, exec, s[6:7]
	ds_write_b16_d16_hi v113, v48 offset:64
	v_mul_f32_e32 v48, 0xbfb8aa3b, v53
	v_exp_f32_e32 v48, v48
	s_nop 0
	v_add_f32_e32 v48, 1.0, v48
	v_div_scale_f32 v49, s[8:9], v48, v48, 1.0
	v_rcp_f32_e32 v50, v49
	v_div_scale_f32 v51, vcc, 1.0, v48, 1.0
	v_fma_f32 v52, -v49, v50, 1.0
	v_fmac_f32_e32 v50, v52, v50
	v_mul_f32_e32 v52, v51, v50
	v_fma_f32 v53, -v49, v52, v51
	v_fmac_f32_e32 v52, v53, v50
	v_fma_f32 v49, -v49, v52, v51
	v_div_fmas_f32 v49, v49, v50, v52
	v_div_fixup_f32 v48, v49, v48, 1.0
	v_bfe_u32 v49, v48, 16, 1
	v_add3_u32 v48, v48, v49, s79
	s_and_b64 vcc, exec, s[6:7]
	ds_write_b16_d16_hi v114, v48 offset:64
	v_mul_f32_e32 v48, 0xbfb8aa3b, v54
	v_exp_f32_e32 v48, v48
	s_nop 0
	v_add_f32_e32 v48, 1.0, v48
	v_div_scale_f32 v49, s[8:9], v48, v48, 1.0
	v_rcp_f32_e32 v50, v49
	v_div_scale_f32 v51, vcc, 1.0, v48, 1.0
	v_fma_f32 v52, -v49, v50, 1.0
	v_fmac_f32_e32 v50, v52, v50
	v_mul_f32_e32 v52, v51, v50
	v_fma_f32 v53, -v49, v52, v51
	v_fmac_f32_e32 v52, v53, v50
	v_fma_f32 v49, -v49, v52, v51
	v_div_fmas_f32 v49, v49, v50, v52
	v_div_fixup_f32 v48, v49, v48, 1.0
	v_bfe_u32 v49, v48, 16, 1
	v_add3_u32 v48, v48, v49, s79
	s_and_b64 vcc, exec, s[6:7]
	ds_write_b16_d16_hi v115, v48 offset:64
	v_mul_f32_e32 v48, 0xbfb8aa3b, v55
	v_exp_f32_e32 v48, v48
	s_nop 0
	v_add_f32_e32 v48, 1.0, v48
	v_div_scale_f32 v49, s[8:9], v48, v48, 1.0
	v_rcp_f32_e32 v50, v49
	v_div_scale_f32 v51, vcc, 1.0, v48, 1.0
	v_fma_f32 v52, -v49, v50, 1.0
	v_fmac_f32_e32 v50, v52, v50
	v_mul_f32_e32 v52, v51, v50
	v_fma_f32 v53, -v49, v52, v51
	v_fmac_f32_e32 v52, v53, v50
	v_fma_f32 v49, -v49, v52, v51
	v_div_fmas_f32 v49, v49, v50, v52
	v_div_fixup_f32 v48, v49, v48, 1.0
	v_bfe_u32 v49, v48, 16, 1
	v_add3_u32 v48, v48, v49, s79
	s_and_b64 vcc, exec, s[6:7]
; __device__ __forceinline__ float sigmf(float x) { return 1.f / (1.f + __expf(-x)); }
; __device__ __forceinline__ void inproj_epilogue(const Params& p, int layer, int mt, int ntile, int tid,
;                                                 f32x16 (&acc)[2][2], unsigned char* smem) {
;     ...
;     acc_foreach(tid, acc, [&](int row, int col, float v) {
;       int t = m0 + row;
;       float o = v;
;       if (mode == 1) o = (t >= NPADR) ? v : 0.f;
;       if (mode == 2) o = sigmf(v);
;       sT[row * 136 + col] = f2bf(o);
;     });
	ds_write_b16_d16_hi v117, v48 offset:64
	v_mul_f32_e32 v48, 0xbfb8aa3b, v56
	v_exp_f32_e32 v48, v48
	s_nop 0
	v_add_f32_e32 v48, 1.0, v48
	v_div_scale_f32 v49, s[8:9], v48, v48, 1.0
	v_rcp_f32_e32 v50, v49
	v_div_scale_f32 v51, vcc, 1.0, v48, 1.0
	v_fma_f32 v52, -v49, v50, 1.0
	v_fmac_f32_e32 v50, v52, v50
	v_mul_f32_e32 v52, v51, v50
	v_fma_f32 v53, -v49, v52, v51
	v_fmac_f32_e32 v52, v53, v50
	v_fma_f32 v49, -v49, v52, v51
	v_div_fmas_f32 v49, v49, v50, v52
	v_div_fixup_f32 v48, v49, v48, 1.0
	v_bfe_u32 v49, v48, 16, 1
	v_add3_u32 v48, v48, v49, s79
	s_and_b64 vcc, exec, s[6:7]
	ds_write_b16_d16_hi v118, v48 offset:64
	v_mul_f32_e32 v48, 0xbfb8aa3b, v57
	v_exp_f32_e32 v48, v48
	s_nop 0
	v_add_f32_e32 v48, 1.0, v48
	v_div_scale_f32 v49, s[8:9], v48, v48, 1.0
	v_rcp_f32_e32 v50, v49
	v_div_scale_f32 v51, vcc, 1.0, v48, 1.0
	v_fma_f32 v52, -v49, v50, 1.0
	v_fmac_f32_e32 v50, v52, v50
	v_mul_f32_e32 v52, v51, v50
	v_fma_f32 v53, -v49, v52, v51
	v_fmac_f32_e32 v52, v53, v50
	v_fma_f32 v49, -v49, v52, v51
	v_div_fmas_f32 v49, v49, v50, v52
	v_div_fixup_f32 v48, v49, v48, 1.0
	v_bfe_u32 v49, v48, 16, 1
	v_add3_u32 v48, v48, v49, s79
	s_and_b64 vcc, exec, s[6:7]
	ds_write_b16_d16_hi v119, v48 offset:64
	v_mul_f32_e32 v48, 0xbfb8aa3b, v58
	v_exp_f32_e32 v48, v48
	s_nop 0
	v_add_f32_e32 v48, 1.0, v48
	v_div_scale_f32 v49, s[8:9], v48, v48, 1.0
	v_rcp_f32_e32 v50, v49
	v_div_scale_f32 v51, vcc, 1.0, v48, 1.0
	v_fma_f32 v52, -v49, v50, 1.0
	v_fmac_f32_e32 v50, v52, v50
	v_mul_f32_e32 v52, v51, v50
	v_fma_f32 v53, -v49, v52, v51
	v_fmac_f32_e32 v52, v53, v50
	v_fma_f32 v49, -v49, v52, v51
	v_div_fmas_f32 v49, v49, v50, v52
	v_div_fixup_f32 v48, v49, v48, 1.0
	v_bfe_u32 v49, v48, 16, 1
	v_add3_u32 v48, v48, v49, s79
	s_and_b64 vcc, exec, s[6:7]
	ds_write_b16_d16_hi v120, v48 offset:64
	v_mul_f32_e32 v48, 0xbfb8aa3b, v59
	v_exp_f32_e32 v48, v48
	s_nop 0
	v_add_f32_e32 v48, 1.0, v48
	v_div_scale_f32 v49, s[8:9], v48, v48, 1.0
	v_rcp_f32_e32 v50, v49
	v_div_scale_f32 v51, vcc, 1.0, v48, 1.0
	v_fma_f32 v52, -v49, v50, 1.0
	v_fmac_f32_e32 v50, v52, v50
	v_mul_f32_e32 v52, v51, v50
	v_fma_f32 v53, -v49, v52, v51
	v_fmac_f32_e32 v52, v53, v50
	v_fma_f32 v49, -v49, v52, v51
	v_div_fmas_f32 v49, v49, v50, v52
	v_div_fixup_f32 v48, v49, v48, 1.0
	v_bfe_u32 v49, v48, 16, 1
	v_add3_u32 v48, v48, v49, s79
	s_and_b64 vcc, exec, s[6:7]
	ds_write_b16_d16_hi v121, v48 offset:64
	v_mul_f32_e32 v48, 0xbfb8aa3b, v60
	v_exp_f32_e32 v48, v48
	s_nop 0
	v_add_f32_e32 v48, 1.0, v48
	v_div_scale_f32 v49, s[8:9], v48, v48, 1.0
	v_rcp_f32_e32 v50, v49
	v_div_scale_f32 v51, vcc, 1.0, v48, 1.0
	v_fma_f32 v52, -v49, v50, 1.0
	v_fmac_f32_e32 v50, v52, v50
	v_mul_f32_e32 v52, v51, v50
	v_fma_f32 v53, -v49, v52, v51
	v_fmac_f32_e32 v52, v53, v50
	v_fma_f32 v49, -v49, v52, v51
	v_div_fmas_f32 v49, v49, v50, v52
	v_div_fixup_f32 v48, v49, v48, 1.0
	v_bfe_u32 v49, v48, 16, 1
	v_add3_u32 v48, v48, v49, s79
	s_and_b64 vcc, exec, s[6:7]
	ds_write_b16_d16_hi v122, v48 offset:64
	v_mul_f32_e32 v48, 0xbfb8aa3b, v61
	v_exp_f32_e32 v48, v48
	s_nop 0
	v_add_f32_e32 v48, 1.0, v48
	v_div_scale_f32 v49, s[8:9], v48, v48, 1.0
	v_rcp_f32_e32 v50, v49
	v_div_scale_f32 v51, vcc, 1.0, v48, 1.0
	v_fma_f32 v52, -v49, v50, 1.0
	v_fmac_f32_e32 v50, v52, v50
	v_mul_f32_e32 v52, v51, v50
	v_fma_f32 v53, -v49, v52, v51
	v_fmac_f32_e32 v52, v53, v50
	v_fma_f32 v49, -v49, v52, v51
	v_div_fmas_f32 v49, v49, v50, v52
	v_div_fixup_f32 v48, v49, v48, 1.0
	v_bfe_u32 v49, v48, 16, 1
	v_add3_u32 v48, v48, v49, s79
	s_and_b64 vcc, exec, s[6:7]
	ds_write_b16_d16_hi v123, v48 offset:64
	v_mul_f32_e32 v48, 0xbfb8aa3b, v62
	v_exp_f32_e32 v48, v48
	s_nop 0
	v_add_f32_e32 v48, 1.0, v48
	v_div_scale_f32 v49, s[8:9], v48, v48, 1.0
	v_rcp_f32_e32 v50, v49
	v_div_scale_f32 v51, vcc, 1.0, v48, 1.0
	v_fma_f32 v52, -v49, v50, 1.0
	v_fmac_f32_e32 v50, v52, v50
	v_mul_f32_e32 v52, v51, v50
	v_fma_f32 v53, -v49, v52, v51
	v_fmac_f32_e32 v52, v53, v50
	v_fma_f32 v49, -v49, v52, v51
	v_div_fmas_f32 v49, v49, v50, v52
	v_div_fixup_f32 v48, v49, v48, 1.0
	v_bfe_u32 v49, v48, 16, 1
	v_add3_u32 v48, v48, v49, s79
	s_and_b64 vcc, exec, s[6:7]
	ds_write_b16_d16_hi v116, v48 offset:64
	v_mul_f32_e32 v48, 0xbfb8aa3b, v63
	v_exp_f32_e32 v48, v48
	s_nop 0
	v_add_f32_e32 v48, 1.0, v48
	v_div_scale_f32 v49, s[8:9], v48, v48, 1.0
	v_rcp_f32_e32 v50, v49
	v_div_scale_f32 v51, vcc, 1.0, v48, 1.0
	v_fma_f32 v52, -v49, v50, 1.0
	v_fmac_f32_e32 v50, v52, v50
	v_mul_f32_e32 v52, v51, v50
	v_fma_f32 v53, -v49, v52, v51
	v_fmac_f32_e32 v52, v53, v50
	v_fma_f32 v49, -v49, v52, v51
	v_div_fmas_f32 v49, v49, v50, v52
	v_div_fixup_f32 v48, v49, v48, 1.0
	v_bfe_u32 v50, v48, 16, 1
	v_add_u32_e32 v49, 0x110, v116
	v_add3_u32 v48, v48, v50, s79
	ds_write_b16_d16_hi v49, v48 offset:64
	v_or_b32_e32 v48, 32, v96
	v_add_u32_e32 v49, s0, v48
	s_and_b64 vcc, exec, s[6:7]
	v_cmp_lt_i32_e64 s[8:9], s77, v49
	v_mul_f32_e32 v49, 0xbfb8aa3b, v0
	v_exp_f32_e32 v49, v49
	s_nop 0
	v_add_f32_e32 v49, 1.0, v49
	v_div_scale_f32 v50, s[10:11], v49, v49, 1.0
	v_rcp_f32_e32 v51, v50
	v_div_scale_f32 v52, vcc, 1.0, v49, 1.0
	v_fma_f32 v53, -v50, v51, 1.0
	v_fmac_f32_e32 v51, v53, v51
	v_mul_f32_e32 v53, v52, v51
	v_fma_f32 v54, -v50, v53, v52
	v_fmac_f32_e32 v53, v54, v51
	v_fma_f32 v50, -v50, v53, v52
	v_div_fmas_f32 v50, v50, v51, v53
	v_div_fixup_f32 v49, v50, v49, 1.0
	v_bfe_u32 v50, v49, 16, 1
	v_add3_u32 v50, v49, v50, s79
	v_mul_lo_u32 v49, v48, s80
	v_lshl_add_u32 v48, v106, 1, v49
	ds_write_b16_d16_hi v48, v50
	v_add3_u32 v50, s0, v96, 33
	s_and_b64 vcc, exec, s[6:7]
	v_cmp_lt_i32_e64 s[10:11], s77, v50
	v_mul_f32_e32 v50, 0xbfb8aa3b, v1
	v_exp_f32_e32 v50, v50
	s_nop 0
; __device__ __forceinline__ float sigmf(float x) { return 1.f / (1.f + __expf(-x)); }
; __device__ __forceinline__ void inproj_epilogue(const Params& p, int layer, int mt, int ntile, int tid,
;                                                 f32x16 (&acc)[2][2], unsigned char* smem) {
;     ...
;     acc_foreach(tid, acc, [&](int row, int col, float v) {
;       int t = m0 + row;
;       float o = v;
;       if (mode == 1) o = (t >= NPADR) ? v : 0.f;
;       if (mode == 2) o = sigmf(v);
;       sT[row * 136 + col] = f2bf(o);
;     });
	v_add_f32_e32 v50, 1.0, v50
	v_div_scale_f32 v51, s[12:13], v50, v50, 1.0
	v_rcp_f32_e32 v52, v51
	v_div_scale_f32 v53, vcc, 1.0, v50, 1.0
	v_fma_f32 v54, -v51, v52, 1.0
	v_fmac_f32_e32 v52, v54, v52
	v_mul_f32_e32 v54, v53, v52
	v_fma_f32 v55, -v51, v54, v53
	v_fmac_f32_e32 v54, v55, v52
	v_fma_f32 v51, -v51, v54, v53
	v_div_fmas_f32 v51, v51, v52, v54
	v_div_fixup_f32 v50, v51, v50, 1.0
	v_bfe_u32 v51, v50, 16, 1
	v_add3_u32 v51, v50, v51, s79
	v_add_u32_e32 v50, 0x110, v49
	v_lshl_add_u32 v49, v106, 1, v50
	ds_write_b16_d16_hi v49, v51
	v_add3_u32 v51, s0, v96, 34
	s_and_b64 vcc, exec, s[6:7]
	v_cmp_lt_i32_e64 s[12:13], s77, v51
	v_mul_f32_e32 v51, 0xbfb8aa3b, v2
	v_exp_f32_e32 v51, v51
	s_nop 0
	v_add_f32_e32 v51, 1.0, v51
	v_div_scale_f32 v52, s[14:15], v51, v51, 1.0
	v_rcp_f32_e32 v53, v52
	v_div_scale_f32 v54, vcc, 1.0, v51, 1.0
	v_fma_f32 v55, -v52, v53, 1.0
	v_fmac_f32_e32 v53, v55, v53
	v_mul_f32_e32 v55, v54, v53
	v_fma_f32 v56, -v52, v55, v54
	v_fmac_f32_e32 v55, v56, v53
	v_fma_f32 v52, -v52, v55, v54
	v_div_fmas_f32 v52, v52, v53, v55
	v_div_fixup_f32 v51, v52, v51, 1.0
	v_bfe_u32 v52, v51, 16, 1
	v_add3_u32 v52, v51, v52, s79
	v_add_u32_e32 v51, 0x110, v50
	v_lshl_add_u32 v50, v106, 1, v51
	ds_write_b16_d16_hi v50, v52
	v_add3_u32 v52, s0, v96, 35
	s_and_b64 vcc, exec, s[6:7]
	v_cmp_lt_i32_e64 s[14:15], s77, v52
	v_mul_f32_e32 v52, 0xbfb8aa3b, v3
	v_exp_f32_e32 v52, v52
	s_nop 0
	v_add_f32_e32 v52, 1.0, v52
	v_div_scale_f32 v53, s[16:17], v52, v52, 1.0
	v_rcp_f32_e32 v54, v53
	v_div_scale_f32 v55, vcc, 1.0, v52, 1.0
	v_fma_f32 v56, -v53, v54, 1.0
	v_fmac_f32_e32 v54, v56, v54
	v_mul_f32_e32 v56, v55, v54
	v_fma_f32 v57, -v53, v56, v55
	v_fmac_f32_e32 v56, v57, v54
	v_fma_f32 v53, -v53, v56, v55
	v_div_fmas_f32 v53, v53, v54, v56
	v_div_fixup_f32 v52, v53, v52, 1.0
	v_bfe_u32 v53, v52, 16, 1
	v_add3_u32 v53, v52, v53, s79
	v_add_u32_e32 v52, 0x110, v51
	v_lshl_add_u32 v51, v106, 1, v52
	ds_write_b16_d16_hi v51, v53
	v_add3_u32 v53, s0, v96, 40
	s_and_b64 vcc, exec, s[6:7]
	v_cmp_lt_i32_e64 s[16:17], s77, v53
	v_mul_f32_e32 v53, 0xbfb8aa3b, v4
	v_exp_f32_e32 v53, v53
	s_nop 0
	v_add_f32_e32 v53, 1.0, v53
	v_div_scale_f32 v54, s[18:19], v53, v53, 1.0
	v_rcp_f32_e32 v55, v54
	v_div_scale_f32 v56, vcc, 1.0, v53, 1.0
	v_fma_f32 v57, -v54, v55, 1.0
	v_fmac_f32_e32 v55, v57, v55
	v_mul_f32_e32 v57, v56, v55
	v_fma_f32 v58, -v54, v57, v56
	v_fmac_f32_e32 v57, v58, v55
	v_fma_f32 v54, -v54, v57, v56
	v_div_fmas_f32 v54, v54, v55, v57
	v_div_fixup_f32 v53, v54, v53, 1.0
	v_bfe_u32 v54, v53, 16, 1
	v_add3_u32 v54, v53, v54, s79
	v_add_u32_e32 v53, 0x550, v52
	v_lshl_add_u32 v52, v106, 1, v53
	ds_write_b16_d16_hi v52, v54
	v_add3_u32 v54, s0, v96, 41
	s_and_b64 vcc, exec, s[6:7]
	v_cmp_lt_i32_e64 s[18:19], s77, v54
	v_mul_f32_e32 v54, 0xbfb8aa3b, v5
	v_exp_f32_e32 v54, v54
	s_nop 0
	v_add_f32_e32 v54, 1.0, v54
	v_div_scale_f32 v55, s[20:21], v54, v54, 1.0
	v_rcp_f32_e32 v56, v55
	v_div_scale_f32 v57, vcc, 1.0, v54, 1.0
	v_fma_f32 v58, -v55, v56, 1.0
	v_fmac_f32_e32 v56, v58, v56
	v_mul_f32_e32 v58, v57, v56
	v_fma_f32 v59, -v55, v58, v57
	v_fmac_f32_e32 v58, v59, v56
	v_fma_f32 v55, -v55, v58, v57
	v_div_fmas_f32 v55, v55, v56, v58
	v_div_fixup_f32 v54, v55, v54, 1.0
	v_bfe_u32 v55, v54, 16, 1
	v_add3_u32 v55, v54, v55, s79
	v_add_u32_e32 v54, 0x110, v53
	v_lshl_add_u32 v53, v106, 1, v54
	ds_write_b16_d16_hi v53, v55
	v_add3_u32 v55, s0, v96, 42
	s_and_b64 vcc, exec, s[6:7]
	v_cmp_lt_i32_e64 s[20:21], s77, v55
	v_mul_f32_e32 v55, 0xbfb8aa3b, v6
	v_exp_f32_e32 v55, v55
	s_nop 0
	v_add_f32_e32 v55, 1.0, v55
	v_div_scale_f32 v56, s[22:23], v55, v55, 1.0
	v_rcp_f32_e32 v57, v56
	v_div_scale_f32 v58, vcc, 1.0, v55, 1.0
	v_fma_f32 v59, -v56, v57, 1.0
	v_fmac_f32_e32 v57, v59, v57
	v_mul_f32_e32 v59, v58, v57
	v_fma_f32 v60, -v56, v59, v58
	v_fmac_f32_e32 v59, v60, v57
	v_fma_f32 v56, -v56, v59, v58
	v_div_fmas_f32 v56, v56, v57, v59
	v_div_fixup_f32 v55, v56, v55, 1.0
	v_bfe_u32 v56, v55, 16, 1
	v_add3_u32 v56, v55, v56, s79
	v_add_u32_e32 v55, 0x110, v54
	v_lshl_add_u32 v54, v106, 1, v55
	ds_write_b16_d16_hi v54, v56
	v_add3_u32 v56, s0, v96, 43
	s_and_b64 vcc, exec, s[6:7]
	v_cmp_lt_i32_e64 s[22:23], s77, v56
	v_mul_f32_e32 v56, 0xbfb8aa3b, v7
	v_exp_f32_e32 v56, v56
	s_nop 0
	v_add_f32_e32 v56, 1.0, v56
	v_div_scale_f32 v57, s[24:25], v56, v56, 1.0
	v_rcp_f32_e32 v58, v57
	v_div_scale_f32 v59, vcc, 1.0, v56, 1.0
	v_fma_f32 v60, -v57, v58, 1.0
	v_fmac_f32_e32 v58, v60, v58
	v_mul_f32_e32 v60, v59, v58
	v_fma_f32 v61, -v57, v60, v59
	v_fmac_f32_e32 v60, v61, v58
	v_fma_f32 v57, -v57, v60, v59
	v_div_fmas_f32 v57, v57, v58, v60
	v_div_fixup_f32 v56, v57, v56, 1.0
	v_bfe_u32 v57, v56, 16, 1
	v_add_u32_e32 v55, 0x110, v55
	v_add3_u32 v57, v56, v57, s79
	v_lshl_add_u32 v56, v106, 1, v55
	ds_write_b16_d16_hi v56, v57
	v_add3_u32 v57, s0, v96, 48
	s_and_b64 vcc, exec, s[6:7]
	v_cmp_lt_i32_e64 s[24:25], s77, v57
	v_mul_f32_e32 v57, 0xbfb8aa3b, v8
	v_exp_f32_e32 v57, v57
	s_nop 0
	v_add_f32_e32 v57, 1.0, v57
	v_div_scale_f32 v58, s[26:27], v57, v57, 1.0
	v_rcp_f32_e32 v59, v58
	v_div_scale_f32 v60, vcc, 1.0, v57, 1.0
	v_fma_f32 v61, -v58, v59, 1.0
	v_fmac_f32_e32 v59, v61, v59
	v_mul_f32_e32 v61, v60, v59
	v_fma_f32 v62, -v58, v61, v60
	v_fmac_f32_e32 v61, v62, v59
	v_fma_f32 v58, -v58, v61, v60
	v_div_fmas_f32 v58, v58, v59, v61
	v_div_fixup_f32 v57, v58, v57, 1.0
	v_bfe_u32 v58, v57, 16, 1
	v_add_u32_e32 v55, 0x550, v55
	v_add3_u32 v58, v57, v58, s79
	v_lshl_add_u32 v57, v106, 1, v55
	ds_write_b16_d16_hi v57, v58
	v_add3_u32 v58, s0, v96, 49
	s_and_b64 vcc, exec, s[6:7]
	v_cmp_lt_i32_e64 s[26:27], s77, v58
	v_mul_f32_e32 v58, 0xbfb8aa3b, v9
; __device__ __forceinline__ float sigmf(float x) { return 1.f / (1.f + __expf(-x)); }
; __device__ __forceinline__ void inproj_epilogue(const Params& p, int layer, int mt, int ntile, int tid,
;                                                 f32x16 (&acc)[2][2], unsigned char* smem) {
;     ...
;     acc_foreach(tid, acc, [&](int row, int col, float v) {
;       int t = m0 + row;
;       float o = v;
;       if (mode == 1) o = (t >= NPADR) ? v : 0.f;
;       if (mode == 2) o = sigmf(v);
;       sT[row * 136 + col] = f2bf(o);
;     });
	v_exp_f32_e32 v58, v58
	s_nop 0
	v_add_f32_e32 v58, 1.0, v58
	v_div_scale_f32 v59, s[28:29], v58, v58, 1.0
	v_rcp_f32_e32 v60, v59
	v_div_scale_f32 v61, vcc, 1.0, v58, 1.0
	v_fma_f32 v62, -v59, v60, 1.0
	v_fmac_f32_e32 v60, v62, v60
	v_mul_f32_e32 v62, v61, v60
	v_fma_f32 v63, -v59, v62, v61
	v_fmac_f32_e32 v62, v63, v60
	v_fma_f32 v59, -v59, v62, v61
	v_div_fmas_f32 v59, v59, v60, v62
	v_div_fixup_f32 v58, v59, v58, 1.0
	v_bfe_u32 v59, v58, 16, 1
	v_add_u32_e32 v55, 0x110, v55
	v_add3_u32 v59, v58, v59, s79
	v_lshl_add_u32 v58, v106, 1, v55
	ds_write_b16_d16_hi v58, v59
	v_add3_u32 v59, s0, v96, 50
	s_and_b64 vcc, exec, s[6:7]
	v_cmp_lt_i32_e64 s[28:29], s77, v59
	v_mul_f32_e32 v59, 0xbfb8aa3b, v10
	v_exp_f32_e32 v59, v59
	s_nop 0
	v_add_f32_e32 v59, 1.0, v59
	v_div_scale_f32 v60, s[30:31], v59, v59, 1.0
	v_rcp_f32_e32 v61, v60
	v_div_scale_f32 v62, vcc, 1.0, v59, 1.0
	v_fma_f32 v63, -v60, v61, 1.0
	v_fmac_f32_e32 v61, v63, v61
	v_mul_f32_e32 v63, v62, v61
	v_fma_f32 v107, -v60, v63, v62
	v_fmac_f32_e32 v63, v107, v61
	v_fma_f32 v60, -v60, v63, v62
	v_div_fmas_f32 v60, v60, v61, v63
	v_div_fixup_f32 v59, v60, v59, 1.0
	v_bfe_u32 v60, v59, 16, 1
	v_add_u32_e32 v55, 0x110, v55
	v_add3_u32 v60, v59, v60, s79
	v_lshl_add_u32 v59, v106, 1, v55
	ds_write_b16_d16_hi v59, v60
	v_add3_u32 v60, s0, v96, 51
	s_and_b64 vcc, exec, s[6:7]
	v_cmp_lt_i32_e64 s[30:31], s77, v60
	v_mul_f32_e32 v60, 0xbfb8aa3b, v11
	v_exp_f32_e32 v60, v60
	s_nop 0
	v_add_f32_e32 v60, 1.0, v60
	v_div_scale_f32 v61, s[34:35], v60, v60, 1.0
	v_rcp_f32_e32 v62, v61
	v_div_scale_f32 v63, vcc, 1.0, v60, 1.0
	v_fma_f32 v107, -v61, v62, 1.0
	v_fmac_f32_e32 v62, v107, v62
	v_mul_f32_e32 v107, v63, v62
	v_fma_f32 v110, -v61, v107, v63
	v_fmac_f32_e32 v107, v110, v62
	v_fma_f32 v61, -v61, v107, v63
	v_div_fmas_f32 v61, v61, v62, v107
	v_div_fixup_f32 v60, v61, v60, 1.0
	v_bfe_u32 v61, v60, 16, 1
	v_add_u32_e32 v55, 0x110, v55
	v_add3_u32 v61, v60, v61, s79
	v_lshl_add_u32 v60, v106, 1, v55
	ds_write_b16_d16_hi v60, v61
	v_add3_u32 v61, s0, v96, 56
	s_and_b64 vcc, exec, s[6:7]
	v_cmp_lt_i32_e64 s[34:35], s77, v61
	v_mul_f32_e32 v61, 0xbfb8aa3b, v12
	v_exp_f32_e32 v61, v61
	s_nop 0
	v_add_f32_e32 v61, 1.0, v61
	v_div_scale_f32 v62, s[36:37], v61, v61, 1.0
	v_rcp_f32_e32 v63, v62
	v_div_scale_f32 v107, vcc, 1.0, v61, 1.0
	v_fma_f32 v110, -v62, v63, 1.0
	v_fmac_f32_e32 v63, v110, v63
	v_mul_f32_e32 v110, v107, v63
	v_fma_f32 v111, -v62, v110, v107
	v_fmac_f32_e32 v110, v111, v63
	v_fma_f32 v62, -v62, v110, v107
	v_div_fmas_f32 v62, v62, v63, v110
	v_div_fixup_f32 v61, v62, v61, 1.0
	v_bfe_u32 v62, v61, 16, 1
	v_add_u32_e32 v55, 0x550, v55
	v_add3_u32 v62, v61, v62, s79
	v_lshl_add_u32 v61, v106, 1, v55
	ds_write_b16_d16_hi v61, v62
	v_add3_u32 v62, s0, v96, 57
	s_and_b64 vcc, exec, s[6:7]
	v_cmp_lt_i32_e64 s[36:37], s77, v62
	v_mul_f32_e32 v62, 0xbfb8aa3b, v13
	v_exp_f32_e32 v62, v62
	s_nop 0
	v_add_f32_e32 v62, 1.0, v62
	v_div_scale_f32 v63, s[38:39], v62, v62, 1.0
	v_rcp_f32_e32 v107, v63
	v_div_scale_f32 v110, vcc, 1.0, v62, 1.0
	v_fma_f32 v111, -v63, v107, 1.0
	v_fmac_f32_e32 v107, v111, v107
	v_mul_f32_e32 v111, v110, v107
	v_fma_f32 v112, -v63, v111, v110
	v_fmac_f32_e32 v111, v112, v107
	v_fma_f32 v63, -v63, v111, v110
	v_div_fmas_f32 v63, v63, v107, v111
	v_div_fixup_f32 v62, v63, v62, 1.0
	v_bfe_u32 v63, v62, 16, 1
	v_add_u32_e32 v55, 0x110, v55
	v_add3_u32 v63, v62, v63, s79
	v_lshl_add_u32 v62, v106, 1, v55
	ds_write_b16_d16_hi v62, v63
	v_add3_u32 v63, s0, v96, 58
	s_and_b64 vcc, exec, s[6:7]
	v_cmp_lt_i32_e64 s[38:39], s77, v63
	v_mul_f32_e32 v63, 0xbfb8aa3b, v14
	v_exp_f32_e32 v63, v63
	s_nop 0
	v_add_f32_e32 v63, 1.0, v63
	v_div_scale_f32 v107, s[40:41], v63, v63, 1.0
	v_rcp_f32_e32 v110, v107
	v_div_scale_f32 v111, vcc, 1.0, v63, 1.0
	v_fma_f32 v112, -v107, v110, 1.0
	v_fmac_f32_e32 v110, v112, v110
	v_mul_f32_e32 v112, v111, v110
	v_fma_f32 v113, -v107, v112, v111
	v_fmac_f32_e32 v112, v113, v110
	v_fma_f32 v107, -v107, v112, v111
	v_div_fmas_f32 v107, v107, v110, v112
	v_div_fixup_f32 v63, v107, v63, 1.0
	v_bfe_u32 v107, v63, 16, 1
	v_add_u32_e32 v55, 0x110, v55
	v_add3_u32 v63, v63, v107, s79
	v_lshl_add_u32 v55, v106, 1, v55
	ds_write_b16_d16_hi v55, v63
	v_add3_u32 v63, s0, v96, 59
	s_and_b64 vcc, exec, s[6:7]
	v_cmp_lt_i32_e64 s[40:41], s77, v63
	v_mul_f32_e32 v63, 0xbfb8aa3b, v15
	v_exp_f32_e32 v63, v63
	s_nop 0
	v_add_f32_e32 v63, 1.0, v63
	v_div_scale_f32 v96, vcc, v63, v63, 1.0
	v_rcp_f32_e32 v106, v96
	v_div_scale_f32 v107, vcc, 1.0, v63, 1.0
	v_fma_f32 v110, -v96, v106, 1.0
	v_fmac_f32_e32 v106, v110, v106
	v_mul_f32_e32 v110, v107, v106
	v_fma_f32 v111, -v96, v110, v107
	v_fmac_f32_e32 v110, v111, v106
	v_fma_f32 v96, -v96, v110, v107
	v_div_fmas_f32 v96, v96, v106, v110
	v_div_fixup_f32 v63, v96, v63, 1.0
	v_bfe_u32 v96, v63, 16, 1
	v_add3_u32 v63, v63, v96, s79
	ds_write_b16_d16_hi v55, v63 offset:272
	s_and_b64 vcc, exec, s[6:7]
	v_mul_f32_e32 v32, 0xbfb8aa3b, v32
	v_exp_f32_e32 v32, v32
	s_nop 0
	v_add_f32_e32 v32, 1.0, v32
	v_div_scale_f32 v63, s[8:9], v32, v32, 1.0
	v_rcp_f32_e32 v96, v63
	v_div_scale_f32 v106, vcc, 1.0, v32, 1.0
	v_fma_f32 v107, -v63, v96, 1.0
	v_fmac_f32_e32 v96, v107, v96
	v_mul_f32_e32 v107, v106, v96
	v_fma_f32 v110, -v63, v107, v106
	v_fmac_f32_e32 v107, v110, v96
	v_fma_f32 v63, -v63, v107, v106
	v_div_fmas_f32 v63, v63, v96, v107
	v_div_fixup_f32 v32, v63, v32, 1.0
	v_bfe_u32 v63, v32, 16, 1
	v_add3_u32 v32, v32, v63, s79
	s_and_b64 vcc, exec, s[6:7]
	ds_write_b16_d16_hi v48, v32 offset:64
	v_mul_f32_e32 v32, 0xbfb8aa3b, v33
	v_exp_f32_e32 v32, v32
	s_nop 0
	v_add_f32_e32 v32, 1.0, v32
	v_div_scale_f32 v33, s[8:9], v32, v32, 1.0
; __device__ __forceinline__ float sigmf(float x) { return 1.f / (1.f + __expf(-x)); }
; __device__ __forceinline__ void inproj_epilogue(const Params& p, int layer, int mt, int ntile, int tid,
;                                                 f32x16 (&acc)[2][2], unsigned char* smem) {
;     ...
;     acc_foreach(tid, acc, [&](int row, int col, float v) {
;       int t = m0 + row;
;       float o = v;
;       if (mode == 1) o = (t >= NPADR) ? v : 0.f;
;       if (mode == 2) o = sigmf(v);
;       sT[row * 136 + col] = f2bf(o);
;     });
	v_rcp_f32_e32 v48, v33
	v_div_scale_f32 v63, vcc, 1.0, v32, 1.0
	v_fma_f32 v96, -v33, v48, 1.0
	v_fmac_f32_e32 v48, v96, v48
	v_mul_f32_e32 v96, v63, v48
	v_fma_f32 v106, -v33, v96, v63
	v_fmac_f32_e32 v96, v106, v48
	v_fma_f32 v33, -v33, v96, v63
	v_div_fmas_f32 v33, v33, v48, v96
	v_div_fixup_f32 v32, v33, v32, 1.0
	v_bfe_u32 v33, v32, 16, 1
	v_add3_u32 v32, v32, v33, s79
	s_and_b64 vcc, exec, s[6:7]
	ds_write_b16_d16_hi v49, v32 offset:64
	v_mul_f32_e32 v32, 0xbfb8aa3b, v34
	v_exp_f32_e32 v32, v32
	s_nop 0
	v_add_f32_e32 v32, 1.0, v32
	v_div_scale_f32 v33, s[8:9], v32, v32, 1.0
	v_rcp_f32_e32 v34, v33
	v_div_scale_f32 v48, vcc, 1.0, v32, 1.0
	v_fma_f32 v49, -v33, v34, 1.0
	v_fmac_f32_e32 v34, v49, v34
	v_mul_f32_e32 v49, v48, v34
	v_fma_f32 v63, -v33, v49, v48
	v_fmac_f32_e32 v49, v63, v34
	v_fma_f32 v33, -v33, v49, v48
	v_div_fmas_f32 v33, v33, v34, v49
	v_div_fixup_f32 v32, v33, v32, 1.0
	v_bfe_u32 v33, v32, 16, 1
	v_add3_u32 v32, v32, v33, s79
	s_and_b64 vcc, exec, s[6:7]
	ds_write_b16_d16_hi v50, v32 offset:64
	v_mul_f32_e32 v32, 0xbfb8aa3b, v35
	v_exp_f32_e32 v32, v32
	s_nop 0
	v_add_f32_e32 v32, 1.0, v32
	v_div_scale_f32 v33, s[8:9], v32, v32, 1.0
	v_rcp_f32_e32 v34, v33
	v_div_scale_f32 v35, vcc, 1.0, v32, 1.0
	v_fma_f32 v48, -v33, v34, 1.0
	v_fmac_f32_e32 v34, v48, v34
	v_mul_f32_e32 v48, v35, v34
	v_fma_f32 v49, -v33, v48, v35
	v_fmac_f32_e32 v48, v49, v34
	v_fma_f32 v33, -v33, v48, v35
	v_div_fmas_f32 v33, v33, v34, v48
	v_div_fixup_f32 v32, v33, v32, 1.0
	v_bfe_u32 v33, v32, 16, 1
	v_add3_u32 v32, v32, v33, s79
	s_and_b64 vcc, exec, s[6:7]
	ds_write_b16_d16_hi v51, v32 offset:64
	v_mul_f32_e32 v32, 0xbfb8aa3b, v36
	v_exp_f32_e32 v32, v32
	s_nop 0
	v_add_f32_e32 v32, 1.0, v32
	v_div_scale_f32 v33, s[8:9], v32, v32, 1.0
	v_rcp_f32_e32 v34, v33
	v_div_scale_f32 v35, vcc, 1.0, v32, 1.0
	v_fma_f32 v36, -v33, v34, 1.0
	v_fmac_f32_e32 v34, v36, v34
	v_mul_f32_e32 v36, v35, v34
	v_fma_f32 v48, -v33, v36, v35
	v_fmac_f32_e32 v36, v48, v34
	v_fma_f32 v33, -v33, v36, v35
	v_div_fmas_f32 v33, v33, v34, v36
	v_div_fixup_f32 v32, v33, v32, 1.0
	v_bfe_u32 v33, v32, 16, 1
	v_add3_u32 v32, v32, v33, s79
	s_and_b64 vcc, exec, s[6:7]
	ds_write_b16_d16_hi v52, v32 offset:64
	v_mul_f32_e32 v32, 0xbfb8aa3b, v37
	v_exp_f32_e32 v32, v32
	s_nop 0
	v_add_f32_e32 v32, 1.0, v32
	v_div_scale_f32 v33, s[8:9], v32, v32, 1.0
	v_rcp_f32_e32 v34, v33
	v_div_scale_f32 v35, vcc, 1.0, v32, 1.0
	v_fma_f32 v36, -v33, v34, 1.0
	v_fmac_f32_e32 v34, v36, v34
	v_mul_f32_e32 v36, v35, v34
	v_fma_f32 v37, -v33, v36, v35
	v_fmac_f32_e32 v36, v37, v34
	v_fma_f32 v33, -v33, v36, v35
	v_div_fmas_f32 v33, v33, v34, v36
	v_div_fixup_f32 v32, v33, v32, 1.0
	v_bfe_u32 v33, v32, 16, 1
	v_add3_u32 v32, v32, v33, s79
	s_and_b64 vcc, exec, s[6:7]
	ds_write_b16_d16_hi v53, v32 offset:64
	v_mul_f32_e32 v32, 0xbfb8aa3b, v38
	v_exp_f32_e32 v32, v32
	s_nop 0
	v_add_f32_e32 v32, 1.0, v32
	v_div_scale_f32 v33, s[8:9], v32, v32, 1.0
	v_rcp_f32_e32 v34, v33
	v_div_scale_f32 v35, vcc, 1.0, v32, 1.0
	v_fma_f32 v36, -v33, v34, 1.0
	v_fmac_f32_e32 v34, v36, v34
	v_mul_f32_e32 v36, v35, v34
	v_fma_f32 v37, -v33, v36, v35
	v_fmac_f32_e32 v36, v37, v34
	v_fma_f32 v33, -v33, v36, v35
	v_div_fmas_f32 v33, v33, v34, v36
	v_div_fixup_f32 v32, v33, v32, 1.0
	v_bfe_u32 v33, v32, 16, 1
	v_add3_u32 v32, v32, v33, s79
	s_and_b64 vcc, exec, s[6:7]
	ds_write_b16_d16_hi v54, v32 offset:64
	v_mul_f32_e32 v32, 0xbfb8aa3b, v39
	v_exp_f32_e32 v32, v32
	s_nop 0
	v_add_f32_e32 v32, 1.0, v32
	v_div_scale_f32 v33, s[8:9], v32, v32, 1.0
	v_rcp_f32_e32 v34, v33
	v_div_scale_f32 v35, vcc, 1.0, v32, 1.0
	v_fma_f32 v36, -v33, v34, 1.0
	v_fmac_f32_e32 v34, v36, v34
	v_mul_f32_e32 v36, v35, v34
	v_fma_f32 v37, -v33, v36, v35
	v_fmac_f32_e32 v36, v37, v34
	v_fma_f32 v33, -v33, v36, v35
	v_div_fmas_f32 v33, v33, v34, v36
	v_div_fixup_f32 v32, v33, v32, 1.0
	v_bfe_u32 v33, v32, 16, 1
	v_add3_u32 v32, v32, v33, s79
	s_and_b64 vcc, exec, s[6:7]
	ds_write_b16_d16_hi v56, v32 offset:64
	v_mul_f32_e32 v32, 0xbfb8aa3b, v40
	v_exp_f32_e32 v32, v32
	s_nop 0
	v_add_f32_e32 v32, 1.0, v32
	v_div_scale_f32 v33, s[8:9], v32, v32, 1.0
	v_rcp_f32_e32 v34, v33
	v_div_scale_f32 v35, vcc, 1.0, v32, 1.0
	v_fma_f32 v36, -v33, v34, 1.0
	v_fmac_f32_e32 v34, v36, v34
	v_mul_f32_e32 v36, v35, v34
; __device__ __forceinline__ float sigmf(float x) { return 1.f / (1.f + __expf(-x)); }
; __device__ __forceinline__ void inproj_epilogue(const Params& p, int layer, int mt, int ntile, int tid,
;                                                 f32x16 (&acc)[2][2], unsigned char* smem) {
;     ...
;     acc_foreach(tid, acc, [&](int row, int col, float v) {
;       int t = m0 + row;
;       float o = v;
;       if (mode == 1) o = (t >= NPADR) ? v : 0.f;
;       if (mode == 2) o = sigmf(v);
;       sT[row * 136 + col] = f2bf(o);
;     });
	v_fma_f32 v37, -v33, v36, v35
	v_fmac_f32_e32 v36, v37, v34
	v_fma_f32 v33, -v33, v36, v35
	v_div_fmas_f32 v33, v33, v34, v36
	v_div_fixup_f32 v32, v33, v32, 1.0
	v_bfe_u32 v33, v32, 16, 1
	v_add3_u32 v32, v32, v33, s79
	s_and_b64 vcc, exec, s[6:7]
	ds_write_b16_d16_hi v57, v32 offset:64
	v_mul_f32_e32 v32, 0xbfb8aa3b, v41
	v_exp_f32_e32 v32, v32
	s_nop 0
	v_add_f32_e32 v32, 1.0, v32
	v_div_scale_f32 v33, s[8:9], v32, v32, 1.0
	v_rcp_f32_e32 v34, v33
	v_div_scale_f32 v35, vcc, 1.0, v32, 1.0
	v_fma_f32 v36, -v33, v34, 1.0
	v_fmac_f32_e32 v34, v36, v34
	v_mul_f32_e32 v36, v35, v34
	v_fma_f32 v37, -v33, v36, v35
	v_fmac_f32_e32 v36, v37, v34
	v_fma_f32 v33, -v33, v36, v35
	v_div_fmas_f32 v33, v33, v34, v36
	v_div_fixup_f32 v32, v33, v32, 1.0
	v_bfe_u32 v33, v32, 16, 1
	v_add3_u32 v32, v32, v33, s79
	s_and_b64 vcc, exec, s[6:7]
	ds_write_b16_d16_hi v58, v32 offset:64
	v_mul_f32_e32 v32, 0xbfb8aa3b, v42
	v_exp_f32_e32 v32, v32
	s_nop 0
	v_add_f32_e32 v32, 1.0, v32
	v_div_scale_f32 v33, s[8:9], v32, v32, 1.0
	v_rcp_f32_e32 v34, v33
	v_div_scale_f32 v35, vcc, 1.0, v32, 1.0
	v_fma_f32 v36, -v33, v34, 1.0
	v_fmac_f32_e32 v34, v36, v34
	v_mul_f32_e32 v36, v35, v34
	v_fma_f32 v37, -v33, v36, v35
	v_fmac_f32_e32 v36, v37, v34
	v_fma_f32 v33, -v33, v36, v35
	v_div_fmas_f32 v33, v33, v34, v36
	v_div_fixup_f32 v32, v33, v32, 1.0
	v_bfe_u32 v33, v32, 16, 1
	v_add3_u32 v32, v32, v33, s79
	s_and_b64 vcc, exec, s[6:7]
	ds_write_b16_d16_hi v59, v32 offset:64
	v_mul_f32_e32 v32, 0xbfb8aa3b, v43
	v_exp_f32_e32 v32, v32
	s_nop 0
	v_add_f32_e32 v32, 1.0, v32
	v_div_scale_f32 v33, s[8:9], v32, v32, 1.0
	v_rcp_f32_e32 v34, v33
	v_div_scale_f32 v35, vcc, 1.0, v32, 1.0
	v_fma_f32 v36, -v33, v34, 1.0
	v_fmac_f32_e32 v34, v36, v34
	v_mul_f32_e32 v36, v35, v34
	v_fma_f32 v37, -v33, v36, v35
	v_fmac_f32_e32 v36, v37, v34
	v_fma_f32 v33, -v33, v36, v35
	v_div_fmas_f32 v33, v33, v34, v36
	v_div_fixup_f32 v32, v33, v32, 1.0
	v_bfe_u32 v33, v32, 16, 1
	v_add3_u32 v32, v32, v33, s79
	s_and_b64 vcc, exec, s[6:7]
	ds_write_b16_d16_hi v60, v32 offset:64
	v_mul_f32_e32 v32, 0xbfb8aa3b, v44
	v_exp_f32_e32 v32, v32
	s_nop 0
	v_add_f32_e32 v32, 1.0, v32
	v_div_scale_f32 v33, s[8:9], v32, v32, 1.0
	v_rcp_f32_e32 v34, v33
	v_div_scale_f32 v35, vcc, 1.0, v32, 1.0
	v_fma_f32 v36, -v33, v34, 1.0
	v_fmac_f32_e32 v34, v36, v34
	v_mul_f32_e32 v36, v35, v34
	v_fma_f32 v37, -v33, v36, v35
	v_fmac_f32_e32 v36, v37, v34
	v_fma_f32 v33, -v33, v36, v35
	v_div_fmas_f32 v33, v33, v34, v36
	v_div_fixup_f32 v32, v33, v32, 1.0
	v_bfe_u32 v33, v32, 16, 1
	v_add3_u32 v32, v32, v33, s79
	s_and_b64 vcc, exec, s[6:7]
	ds_write_b16_d16_hi v61, v32 offset:64
	v_mul_f32_e32 v32, 0xbfb8aa3b, v45
	v_exp_f32_e32 v32, v32
	s_nop 0
	v_add_f32_e32 v32, 1.0, v32
	v_div_scale_f32 v33, s[8:9], v32, v32, 1.0
	v_rcp_f32_e32 v34, v33
	v_div_scale_f32 v35, vcc, 1.0, v32, 1.0
	v_fma_f32 v36, -v33, v34, 1.0
	v_fmac_f32_e32 v34, v36, v34
	v_mul_f32_e32 v36, v35, v34
	v_fma_f32 v37, -v33, v36, v35
	v_fmac_f32_e32 v36, v37, v34
	v_fma_f32 v33, -v33, v36, v35
	v_div_fmas_f32 v33, v33, v34, v36
	v_div_fixup_f32 v32, v33, v32, 1.0
	v_bfe_u32 v33, v32, 16, 1
	v_add3_u32 v32, v32, v33, s79
	s_and_b64 vcc, exec, s[6:7]
	ds_write_b16_d16_hi v62, v32 offset:64
	v_mul_f32_e32 v32, 0xbfb8aa3b, v46
	v_exp_f32_e32 v32, v32
	s_nop 0
	v_add_f32_e32 v32, 1.0, v32
	v_div_scale_f32 v33, s[8:9], v32, v32, 1.0
	v_rcp_f32_e32 v34, v33
	v_div_scale_f32 v35, vcc, 1.0, v32, 1.0
	v_fma_f32 v36, -v33, v34, 1.0
	v_fmac_f32_e32 v34, v36, v34
	v_mul_f32_e32 v36, v35, v34
	v_fma_f32 v37, -v33, v36, v35
	v_fmac_f32_e32 v36, v37, v34
	v_fma_f32 v33, -v33, v36, v35
	v_div_fmas_f32 v33, v33, v34, v36
	v_div_fixup_f32 v32, v33, v32, 1.0
	v_bfe_u32 v33, v32, 16, 1
	v_add3_u32 v32, v32, v33, s79
	s_and_b64 vcc, exec, s[6:7]
	ds_write_b16_d16_hi v55, v32 offset:64
	v_mul_f32_e32 v32, 0xbfb8aa3b, v47
	v_exp_f32_e32 v32, v32
	s_nop 0
	v_add_f32_e32 v32, 1.0, v32
	v_div_scale_f32 v33, s[4:5], v32, v32, 1.0
	v_rcp_f32_e32 v34, v33
	v_div_scale_f32 v35, vcc, 1.0, v32, 1.0
	v_fma_f32 v36, -v33, v34, 1.0
	v_fmac_f32_e32 v34, v36, v34
	v_mul_f32_e32 v36, v35, v34
	v_fma_f32 v37, -v33, v36, v35
	v_fmac_f32_e32 v36, v37, v34
	v_fma_f32 v33, -v33, v36, v35
	v_div_fmas_f32 v33, v33, v34, v36
	v_div_fixup_f32 v32, v33, v32, 1.0
	s_branch .LBB0_1051

; __device__ __forceinline__ float sigmf(float x) { return 1.f / (1.f + __expf(-x)); }
; __device__ __forceinline__ void inproj_epilogue(const Params& p, int layer, int mt, int ntile, int tid,
;                                                 f32x16 (&acc)[2][2], unsigned char* smem) {
;     ...
;     acc_foreach(tid, acc, [&](int row, int col, float v) {
;       int t = m0 + row;
;       float o = v;
;       if (mode == 1) o = (t >= NPADR) ? v : 0.f;
;       if (mode == 2) o = sigmf(v);
;       sT[row * 136 + col] = f2bf(o);
;     });
.LBB0_1646:
	v_bfe_u32 v110, v107, 16, 1
	v_and_b32_e32 v106, 0x5f, v106
	v_add3_u32 v111, v107, v110, s78
	v_mul_lo_u32 v110, v96, s79
	v_lshl_add_u32 v107, v106, 1, v110
	ds_write_b16_d16_hi v107, v111
	v_add3_u32 v111, s96, v96, 1
	v_cmp_lt_i32_e64 s[10:11], s76, v111
	v_cndmask_b32_e64 v111, 0, 1, s[12:13]
	v_cmp_ne_u32_e64 s[6:7], 1, v111
	s_nop 1

; __device__ __forceinline__ float sigmf(float x) { return 1.f / (1.f + __expf(-x)); }
; __device__ __forceinline__ void inproj_epilogue(const Params& p, int layer, int mt, int ntile, int tid,
;                                                 f32x16 (&acc)[2][2], unsigned char* smem) {
;     ...
;     acc_foreach(tid, acc, [&](int row, int col, float v) {
;       int t = m0 + row;
;       float o = v;
;       if (mode == 1) o = (t >= NPADR) ? v : 0.f;
;       if (mode == 2) o = sigmf(v);
;       sT[row * 136 + col] = f2bf(o);
;     });
.LBB0_1649:
	v_bfe_u32 v112, v111, 16, 1
	v_add3_u32 v112, v111, v112, s78
	v_add_u32_e32 v111, 0x110, v110
	v_lshl_add_u32 v110, v106, 1, v111
	ds_write_b16_d16_hi v110, v112
	v_add3_u32 v112, s96, v96, 2
	v_cmp_lt_i32_e64 s[12:13], s76, v112
	s_nop 1

; __device__ __forceinline__ float sigmf(float x) { return 1.f / (1.f + __expf(-x)); }
; __device__ __forceinline__ void inproj_epilogue(const Params& p, int layer, int mt, int ntile, int tid,
;                                                 f32x16 (&acc)[2][2], unsigned char* smem) {
;     ...
;     acc_foreach(tid, acc, [&](int row, int col, float v) {
;       int t = m0 + row;
;       float o = v;
;       if (mode == 1) o = (t >= NPADR) ? v : 0.f;
;       if (mode == 2) o = sigmf(v);
;       sT[row * 136 + col] = f2bf(o);
;     });
.LBB0_1652:
	v_bfe_u32 v113, v112, 16, 1
	v_add3_u32 v113, v112, v113, s78
	v_add_u32_e32 v112, 0x110, v111
	v_lshl_add_u32 v111, v106, 1, v112
	ds_write_b16_d16_hi v111, v113
	v_add3_u32 v113, s96, v96, 3
	v_cmp_lt_i32_e64 s[14:15], s76, v113
	s_nop 1

; __device__ __forceinline__ float sigmf(float x) { return 1.f / (1.f + __expf(-x)); }
; __device__ __forceinline__ void inproj_epilogue(const Params& p, int layer, int mt, int ntile, int tid,
;                                                 f32x16 (&acc)[2][2], unsigned char* smem) {
;     ...
;     acc_foreach(tid, acc, [&](int row, int col, float v) {
;       int t = m0 + row;
;       float o = v;
;       if (mode == 1) o = (t >= NPADR) ? v : 0.f;
;       if (mode == 2) o = sigmf(v);
;       sT[row * 136 + col] = f2bf(o);
;     });
.LBB0_1655:
	v_bfe_u32 v114, v113, 16, 1
	v_add3_u32 v114, v113, v114, s78
	v_add_u32_e32 v113, 0x110, v112
	v_lshl_add_u32 v112, v106, 1, v113
	ds_write_b16_d16_hi v112, v114
	v_add3_u32 v114, s96, v96, 8
	v_cmp_lt_i32_e64 s[16:17], s76, v114
	s_nop 1

; __device__ __forceinline__ float sigmf(float x) { return 1.f / (1.f + __expf(-x)); }
; __device__ __forceinline__ void inproj_epilogue(const Params& p, int layer, int mt, int ntile, int tid,
;                                                 f32x16 (&acc)[2][2], unsigned char* smem) {
;     ...
;     acc_foreach(tid, acc, [&](int row, int col, float v) {
;       int t = m0 + row;
;       float o = v;
;       if (mode == 1) o = (t >= NPADR) ? v : 0.f;
;       if (mode == 2) o = sigmf(v);
;       sT[row * 136 + col] = f2bf(o);
;     });
.LBB0_1658:
	v_bfe_u32 v115, v114, 16, 1
	v_add3_u32 v115, v114, v115, s78
	v_add_u32_e32 v114, 0x550, v113
	v_lshl_add_u32 v113, v106, 1, v114
	ds_write_b16_d16_hi v113, v115
	v_add3_u32 v115, s96, v96, 9
	v_cmp_lt_i32_e64 s[18:19], s76, v115
	s_nop 1

; __device__ __forceinline__ float sigmf(float x) { return 1.f / (1.f + __expf(-x)); }
; __device__ __forceinline__ void inproj_epilogue(const Params& p, int layer, int mt, int ntile, int tid,
;                                                 f32x16 (&acc)[2][2], unsigned char* smem) {
;     ...
;     acc_foreach(tid, acc, [&](int row, int col, float v) {
;       int t = m0 + row;
;       float o = v;
;       if (mode == 1) o = (t >= NPADR) ? v : 0.f;
;       if (mode == 2) o = sigmf(v);
;       sT[row * 136 + col] = f2bf(o);
;     });
.LBB0_1661:
	v_bfe_u32 v116, v115, 16, 1
	v_add3_u32 v116, v115, v116, s78
	v_add_u32_e32 v115, 0x110, v114
	v_lshl_add_u32 v114, v106, 1, v115
	ds_write_b16_d16_hi v114, v116
	v_add3_u32 v116, s96, v96, 10
	v_cmp_lt_i32_e64 s[20:21], s76, v116
	s_nop 1

; __device__ __forceinline__ float sigmf(float x) { return 1.f / (1.f + __expf(-x)); }
; __device__ __forceinline__ void inproj_epilogue(const Params& p, int layer, int mt, int ntile, int tid,
;                                                 f32x16 (&acc)[2][2], unsigned char* smem) {
;     ...
;     acc_foreach(tid, acc, [&](int row, int col, float v) {
;       int t = m0 + row;
;       float o = v;
;       if (mode == 1) o = (t >= NPADR) ? v : 0.f;
;       if (mode == 2) o = sigmf(v);
;       sT[row * 136 + col] = f2bf(o);
;     });
.LBB0_1664:
	v_bfe_u32 v117, v116, 16, 1
	v_add3_u32 v117, v116, v117, s78
	v_add_u32_e32 v116, 0x110, v115
	v_lshl_add_u32 v115, v106, 1, v116
	ds_write_b16_d16_hi v115, v117
	v_add3_u32 v117, s96, v96, 11
	v_cmp_lt_i32_e64 s[22:23], s76, v117
	s_nop 1

; __device__ __forceinline__ float sigmf(float x) { return 1.f / (1.f + __expf(-x)); }
; __device__ __forceinline__ void inproj_epilogue(const Params& p, int layer, int mt, int ntile, int tid,
;                                                 f32x16 (&acc)[2][2], unsigned char* smem) {
;     ...
;     acc_foreach(tid, acc, [&](int row, int col, float v) {
;       int t = m0 + row;
;       float o = v;
;       if (mode == 1) o = (t >= NPADR) ? v : 0.f;
;       if (mode == 2) o = sigmf(v);
;       sT[row * 136 + col] = f2bf(o);
;     });
.LBB0_1667:
	v_bfe_u32 v118, v117, 16, 1
	v_add_u32_e32 v116, 0x110, v116
	v_add3_u32 v118, v117, v118, s78
	v_lshl_add_u32 v117, v106, 1, v116
	ds_write_b16_d16_hi v117, v118
	v_add3_u32 v118, s96, v96, 16
	v_cmp_lt_i32_e64 s[24:25], s76, v118
	s_nop 1

; __device__ __forceinline__ float sigmf(float x) { return 1.f / (1.f + __expf(-x)); }
; __device__ __forceinline__ void inproj_epilogue(const Params& p, int layer, int mt, int ntile, int tid,
;                                                 f32x16 (&acc)[2][2], unsigned char* smem) {
;     ...
;     acc_foreach(tid, acc, [&](int row, int col, float v) {
;       int t = m0 + row;
;       float o = v;
;       if (mode == 1) o = (t >= NPADR) ? v : 0.f;
;       if (mode == 2) o = sigmf(v);
;       sT[row * 136 + col] = f2bf(o);
;     });
.LBB0_1670:
	v_bfe_u32 v119, v118, 16, 1
	v_add_u32_e32 v116, 0x550, v116
	v_add3_u32 v119, v118, v119, s78
	v_lshl_add_u32 v118, v106, 1, v116
	ds_write_b16_d16_hi v118, v119
	v_add3_u32 v119, s96, v96, 17
	v_cmp_lt_i32_e64 s[26:27], s76, v119
	s_nop 1

; __device__ __forceinline__ float sigmf(float x) { return 1.f / (1.f + __expf(-x)); }
; __device__ __forceinline__ void inproj_epilogue(const Params& p, int layer, int mt, int ntile, int tid,
;                                                 f32x16 (&acc)[2][2], unsigned char* smem) {
;     ...
;     acc_foreach(tid, acc, [&](int row, int col, float v) {
;       int t = m0 + row;
;       float o = v;
;       if (mode == 1) o = (t >= NPADR) ? v : 0.f;
;       if (mode == 2) o = sigmf(v);
;       sT[row * 136 + col] = f2bf(o);
;     });
.LBB0_1673:
	v_bfe_u32 v120, v119, 16, 1
	v_add_u32_e32 v116, 0x110, v116
	v_add3_u32 v120, v119, v120, s78
	v_lshl_add_u32 v119, v106, 1, v116
	ds_write_b16_d16_hi v119, v120
	v_add3_u32 v120, s96, v96, 18
	v_cmp_lt_i32_e64 s[28:29], s76, v120
	s_nop 1

; __device__ __forceinline__ float sigmf(float x) { return 1.f / (1.f + __expf(-x)); }
; __device__ __forceinline__ void inproj_epilogue(const Params& p, int layer, int mt, int ntile, int tid,
;                                                 f32x16 (&acc)[2][2], unsigned char* smem) {
;     ...
;     acc_foreach(tid, acc, [&](int row, int col, float v) {
;       int t = m0 + row;
;       float o = v;
;       if (mode == 1) o = (t >= NPADR) ? v : 0.f;
;       if (mode == 2) o = sigmf(v);
;       sT[row * 136 + col] = f2bf(o);
;     });
.LBB0_1676:
	v_bfe_u32 v121, v120, 16, 1
	v_add_u32_e32 v116, 0x110, v116
	v_add3_u32 v121, v120, v121, s78
	v_lshl_add_u32 v120, v106, 1, v116
	ds_write_b16_d16_hi v120, v121
	v_add3_u32 v121, s96, v96, 19
	v_cmp_lt_i32_e64 s[30:31], s76, v121
	s_nop 1

; __device__ __forceinline__ float sigmf(float x) { return 1.f / (1.f + __expf(-x)); }
; __device__ __forceinline__ void inproj_epilogue(const Params& p, int layer, int mt, int ntile, int tid,
;                                                 f32x16 (&acc)[2][2], unsigned char* smem) {
;     ...
;     acc_foreach(tid, acc, [&](int row, int col, float v) {
;       int t = m0 + row;
;       float o = v;
;       if (mode == 1) o = (t >= NPADR) ? v : 0.f;
;       if (mode == 2) o = sigmf(v);
;       sT[row * 136 + col] = f2bf(o);
;     });
.LBB0_1679:
	v_bfe_u32 v122, v121, 16, 1
	v_add_u32_e32 v116, 0x110, v116
	v_add3_u32 v122, v121, v122, s78
	v_lshl_add_u32 v121, v106, 1, v116
	ds_write_b16_d16_hi v121, v122
	v_add3_u32 v122, s96, v96, 24
	v_cmp_lt_i32_e64 s[34:35], s76, v122
	s_nop 1

; __device__ __forceinline__ float sigmf(float x) { return 1.f / (1.f + __expf(-x)); }
; __device__ __forceinline__ void inproj_epilogue(const Params& p, int layer, int mt, int ntile, int tid,
;                                                 f32x16 (&acc)[2][2], unsigned char* smem) {
;     ...
;     acc_foreach(tid, acc, [&](int row, int col, float v) {
;       int t = m0 + row;
;       float o = v;
;       if (mode == 1) o = (t >= NPADR) ? v : 0.f;
;       if (mode == 2) o = sigmf(v);
;       sT[row * 136 + col] = f2bf(o);
;     });
.LBB0_1682:
	v_bfe_u32 v123, v122, 16, 1
	v_add_u32_e32 v116, 0x550, v116
	v_add3_u32 v123, v122, v123, s78
	v_lshl_add_u32 v122, v106, 1, v116
	ds_write_b16_d16_hi v122, v123
	v_add3_u32 v123, s96, v96, 25
	v_cmp_lt_i32_e64 s[36:37], s76, v123
	s_nop 1

; __device__ __forceinline__ float sigmf(float x) { return 1.f / (1.f + __expf(-x)); }
; __device__ __forceinline__ void inproj_epilogue(const Params& p, int layer, int mt, int ntile, int tid,
;                                                 f32x16 (&acc)[2][2], unsigned char* smem) {
;     ...
;     acc_foreach(tid, acc, [&](int row, int col, float v) {
;       int t = m0 + row;
;       float o = v;
;       if (mode == 1) o = (t >= NPADR) ? v : 0.f;
;       if (mode == 2) o = sigmf(v);
;       sT[row * 136 + col] = f2bf(o);
;     });
.LBB0_1685:
	v_bfe_u32 v124, v123, 16, 1
	v_add_u32_e32 v116, 0x110, v116
	v_add3_u32 v124, v123, v124, s78
	v_lshl_add_u32 v123, v106, 1, v116
	ds_write_b16_d16_hi v123, v124
	v_add3_u32 v124, s96, v96, 26
	v_cmp_lt_i32_e64 s[38:39], s76, v124
	s_nop 1

; __device__ __forceinline__ float sigmf(float x) { return 1.f / (1.f + __expf(-x)); }
; __device__ __forceinline__ void inproj_epilogue(const Params& p, int layer, int mt, int ntile, int tid,
;                                                 f32x16 (&acc)[2][2], unsigned char* smem) {
;     ...
;     acc_foreach(tid, acc, [&](int row, int col, float v) {
;       int t = m0 + row;
;       float o = v;
;       if (mode == 1) o = (t >= NPADR) ? v : 0.f;
;       if (mode == 2) o = sigmf(v);
;       sT[row * 136 + col] = f2bf(o);
;     });
.LBB0_1688:
	v_bfe_u32 v125, v124, 16, 1
	v_add_u32_e32 v116, 0x110, v116
	v_add3_u32 v124, v124, v125, s78
	v_lshl_add_u32 v116, v106, 1, v116
	ds_write_b16_d16_hi v116, v124
	v_add3_u32 v124, s96, v96, 27
	v_cmp_lt_i32_e64 s[40:41], s76, v124
	s_nop 1

; __device__ __forceinline__ float sigmf(float x) { return 1.f / (1.f + __expf(-x)); }
; __device__ __forceinline__ void inproj_epilogue(const Params& p, int layer, int mt, int ntile, int tid,
;                                                 f32x16 (&acc)[2][2], unsigned char* smem) {
;     ...
;     acc_foreach(tid, acc, [&](int row, int col, float v) {
;       int t = m0 + row;
;       float o = v;
;       if (mode == 1) o = (t >= NPADR) ? v : 0.f;
;       if (mode == 2) o = sigmf(v);
;       sT[row * 136 + col] = f2bf(o);
;     });
.LBB0_1739:
	v_bfe_u32 v50, v48, 16, 1
	v_add_u32_e32 v49, 0x110, v116
	v_add3_u32 v48, v48, v50, s78
	ds_write_b16_d16_hi v49, v48 offset:64
	v_or_b32_e32 v48, 32, v96
	v_add_u32_e32 v49, s96, v48
	v_cmp_lt_i32_e64 s[8:9], s76, v49
	s_nop 1

; __device__ __forceinline__ float sigmf(float x) { return 1.f / (1.f + __expf(-x)); }
; __device__ __forceinline__ void inproj_epilogue(const Params& p, int layer, int mt, int ntile, int tid,
;                                                 f32x16 (&acc)[2][2], unsigned char* smem) {
;     ...
;     acc_foreach(tid, acc, [&](int row, int col, float v) {
;       int t = m0 + row;
;       float o = v;
;       if (mode == 1) o = (t >= NPADR) ? v : 0.f;
;       if (mode == 2) o = sigmf(v);
;       sT[row * 136 + col] = f2bf(o);
;     });
.LBB0_1742:
	v_bfe_u32 v50, v49, 16, 1
	v_add3_u32 v50, v49, v50, s78
	v_mul_lo_u32 v49, v48, s79
	v_lshl_add_u32 v48, v106, 1, v49
	ds_write_b16_d16_hi v48, v50
	v_add3_u32 v50, s96, v96, 33
	v_cmp_lt_i32_e64 s[10:11], s76, v50
	s_nop 1

; __device__ __forceinline__ float sigmf(float x) { return 1.f / (1.f + __expf(-x)); }
; __device__ __forceinline__ void inproj_epilogue(const Params& p, int layer, int mt, int ntile, int tid,
;                                                 f32x16 (&acc)[2][2], unsigned char* smem) {
;     ...
;     acc_foreach(tid, acc, [&](int row, int col, float v) {
;       int t = m0 + row;
;       float o = v;
;       if (mode == 1) o = (t >= NPADR) ? v : 0.f;
;       if (mode == 2) o = sigmf(v);
;       sT[row * 136 + col] = f2bf(o);
;     });
.LBB0_1745:
	v_bfe_u32 v51, v50, 16, 1
	v_add3_u32 v51, v50, v51, s78
	v_add_u32_e32 v50, 0x110, v49
	v_lshl_add_u32 v49, v106, 1, v50
	ds_write_b16_d16_hi v49, v51
	v_add3_u32 v51, s96, v96, 34
	v_cmp_lt_i32_e64 s[12:13], s76, v51
	s_nop 1

; __device__ __forceinline__ float sigmf(float x) { return 1.f / (1.f + __expf(-x)); }
; __device__ __forceinline__ void inproj_epilogue(const Params& p, int layer, int mt, int ntile, int tid,
;                                                 f32x16 (&acc)[2][2], unsigned char* smem) {
;     ...
;     acc_foreach(tid, acc, [&](int row, int col, float v) {
;       int t = m0 + row;
;       float o = v;
;       if (mode == 1) o = (t >= NPADR) ? v : 0.f;
;       if (mode == 2) o = sigmf(v);
;       sT[row * 136 + col] = f2bf(o);
;     });
.LBB0_1748:
	v_bfe_u32 v52, v51, 16, 1
	v_add3_u32 v52, v51, v52, s78
	v_add_u32_e32 v51, 0x110, v50
	v_lshl_add_u32 v50, v106, 1, v51
	ds_write_b16_d16_hi v50, v52
	v_add3_u32 v52, s96, v96, 35
	v_cmp_lt_i32_e64 s[14:15], s76, v52
	s_nop 1

; __device__ __forceinline__ float sigmf(float x) { return 1.f / (1.f + __expf(-x)); }
; __device__ __forceinline__ void inproj_epilogue(const Params& p, int layer, int mt, int ntile, int tid,
;                                                 f32x16 (&acc)[2][2], unsigned char* smem) {
;     ...
;     acc_foreach(tid, acc, [&](int row, int col, float v) {
;       int t = m0 + row;
;       float o = v;
;       if (mode == 1) o = (t >= NPADR) ? v : 0.f;
;       if (mode == 2) o = sigmf(v);
;       sT[row * 136 + col] = f2bf(o);
;     });
.LBB0_1751:
	v_bfe_u32 v53, v52, 16, 1
	v_add3_u32 v53, v52, v53, s78
	v_add_u32_e32 v52, 0x110, v51
	v_lshl_add_u32 v51, v106, 1, v52
	ds_write_b16_d16_hi v51, v53
	v_add3_u32 v53, s96, v96, 40
	v_cmp_lt_i32_e64 s[16:17], s76, v53
	s_nop 1

; __device__ __forceinline__ float sigmf(float x) { return 1.f / (1.f + __expf(-x)); }
; __device__ __forceinline__ void inproj_epilogue(const Params& p, int layer, int mt, int ntile, int tid,
;                                                 f32x16 (&acc)[2][2], unsigned char* smem) {
;     ...
;     acc_foreach(tid, acc, [&](int row, int col, float v) {
;       int t = m0 + row;
;       float o = v;
;       if (mode == 1) o = (t >= NPADR) ? v : 0.f;
;       if (mode == 2) o = sigmf(v);
;       sT[row * 136 + col] = f2bf(o);
;     });
.LBB0_1754:
	v_bfe_u32 v54, v53, 16, 1
	v_add3_u32 v54, v53, v54, s78
	v_add_u32_e32 v53, 0x550, v52
	v_lshl_add_u32 v52, v106, 1, v53
	ds_write_b16_d16_hi v52, v54
	v_add3_u32 v54, s96, v96, 41
	v_cmp_lt_i32_e64 s[18:19], s76, v54
	s_nop 1

; __device__ __forceinline__ float sigmf(float x) { return 1.f / (1.f + __expf(-x)); }
; __device__ __forceinline__ void inproj_epilogue(const Params& p, int layer, int mt, int ntile, int tid,
;                                                 f32x16 (&acc)[2][2], unsigned char* smem) {
;     ...
;     acc_foreach(tid, acc, [&](int row, int col, float v) {
;       int t = m0 + row;
;       float o = v;
;       if (mode == 1) o = (t >= NPADR) ? v : 0.f;
;       if (mode == 2) o = sigmf(v);
;       sT[row * 136 + col] = f2bf(o);
;     });
.LBB0_1757:
	v_bfe_u32 v55, v54, 16, 1
	v_add3_u32 v55, v54, v55, s78
	v_add_u32_e32 v54, 0x110, v53
	v_lshl_add_u32 v53, v106, 1, v54
	ds_write_b16_d16_hi v53, v55
	v_add3_u32 v55, s96, v96, 42
	v_cmp_lt_i32_e64 s[20:21], s76, v55
	s_nop 1

; __device__ __forceinline__ float sigmf(float x) { return 1.f / (1.f + __expf(-x)); }
; __device__ __forceinline__ void inproj_epilogue(const Params& p, int layer, int mt, int ntile, int tid,
;                                                 f32x16 (&acc)[2][2], unsigned char* smem) {
;     ...
;     acc_foreach(tid, acc, [&](int row, int col, float v) {
;       int t = m0 + row;
;       float o = v;
;       if (mode == 1) o = (t >= NPADR) ? v : 0.f;
;       if (mode == 2) o = sigmf(v);
;       sT[row * 136 + col] = f2bf(o);
;     });
.LBB0_1760:
	v_bfe_u32 v56, v55, 16, 1
	v_add3_u32 v56, v55, v56, s78
	v_add_u32_e32 v55, 0x110, v54
	v_lshl_add_u32 v54, v106, 1, v55
	ds_write_b16_d16_hi v54, v56
	v_add3_u32 v56, s96, v96, 43
	v_cmp_lt_i32_e64 s[22:23], s76, v56
	s_nop 1

; __device__ __forceinline__ float sigmf(float x) { return 1.f / (1.f + __expf(-x)); }
; __device__ __forceinline__ void inproj_epilogue(const Params& p, int layer, int mt, int ntile, int tid,
;                                                 f32x16 (&acc)[2][2], unsigned char* smem) {
;     ...
;     acc_foreach(tid, acc, [&](int row, int col, float v) {
;       int t = m0 + row;
;       float o = v;
;       if (mode == 1) o = (t >= NPADR) ? v : 0.f;
;       if (mode == 2) o = sigmf(v);
;       sT[row * 136 + col] = f2bf(o);
;     });
.LBB0_1763:
	v_bfe_u32 v57, v56, 16, 1
	v_add_u32_e32 v55, 0x110, v55
	v_add3_u32 v57, v56, v57, s78
	v_lshl_add_u32 v56, v106, 1, v55
	ds_write_b16_d16_hi v56, v57
	v_add3_u32 v57, s96, v96, 48
	v_cmp_lt_i32_e64 s[24:25], s76, v57
	s_nop 1

; __device__ __forceinline__ float sigmf(float x) { return 1.f / (1.f + __expf(-x)); }
; __device__ __forceinline__ void inproj_epilogue(const Params& p, int layer, int mt, int ntile, int tid,
;                                                 f32x16 (&acc)[2][2], unsigned char* smem) {
;     ...
;     acc_foreach(tid, acc, [&](int row, int col, float v) {
;       int t = m0 + row;
;       float o = v;
;       if (mode == 1) o = (t >= NPADR) ? v : 0.f;
;       if (mode == 2) o = sigmf(v);
;       sT[row * 136 + col] = f2bf(o);
;     });
.LBB0_1766:
	v_bfe_u32 v58, v57, 16, 1
	v_add_u32_e32 v55, 0x550, v55
	v_add3_u32 v58, v57, v58, s78
	v_lshl_add_u32 v57, v106, 1, v55
	ds_write_b16_d16_hi v57, v58
	v_add3_u32 v58, s96, v96, 49
	v_cmp_lt_i32_e64 s[26:27], s76, v58
	s_nop 1

; __device__ __forceinline__ float sigmf(float x) { return 1.f / (1.f + __expf(-x)); }
; __device__ __forceinline__ void inproj_epilogue(const Params& p, int layer, int mt, int ntile, int tid,
;                                                 f32x16 (&acc)[2][2], unsigned char* smem) {
;     ...
;     acc_foreach(tid, acc, [&](int row, int col, float v) {
;       int t = m0 + row;
;       float o = v;
;       if (mode == 1) o = (t >= NPADR) ? v : 0.f;
;       if (mode == 2) o = sigmf(v);
;       sT[row * 136 + col] = f2bf(o);
;     });
.LBB0_1769:
	v_bfe_u32 v59, v58, 16, 1
	v_add_u32_e32 v55, 0x110, v55
	v_add3_u32 v59, v58, v59, s78
	v_lshl_add_u32 v58, v106, 1, v55
	ds_write_b16_d16_hi v58, v59
	v_add3_u32 v59, s96, v96, 50
	v_cmp_lt_i32_e64 s[28:29], s76, v59
	s_nop 1

; __device__ __forceinline__ float sigmf(float x) { return 1.f / (1.f + __expf(-x)); }
; __device__ __forceinline__ void inproj_epilogue(const Params& p, int layer, int mt, int ntile, int tid,
;                                                 f32x16 (&acc)[2][2], unsigned char* smem) {
;     ...
;     acc_foreach(tid, acc, [&](int row, int col, float v) {
;       int t = m0 + row;
;       float o = v;
;       if (mode == 1) o = (t >= NPADR) ? v : 0.f;
;       if (mode == 2) o = sigmf(v);
;       sT[row * 136 + col] = f2bf(o);
;     });
.LBB0_1772:
	v_bfe_u32 v60, v59, 16, 1
	v_add_u32_e32 v55, 0x110, v55
	v_add3_u32 v60, v59, v60, s78
	v_lshl_add_u32 v59, v106, 1, v55
	ds_write_b16_d16_hi v59, v60
	v_add3_u32 v60, s96, v96, 51
	v_cmp_lt_i32_e64 s[30:31], s76, v60
	s_nop 1

; __device__ __forceinline__ float sigmf(float x) { return 1.f / (1.f + __expf(-x)); }
; __device__ __forceinline__ void inproj_epilogue(const Params& p, int layer, int mt, int ntile, int tid,
;                                                 f32x16 (&acc)[2][2], unsigned char* smem) {
;     ...
;     acc_foreach(tid, acc, [&](int row, int col, float v) {
;       int t = m0 + row;
;       float o = v;
;       if (mode == 1) o = (t >= NPADR) ? v : 0.f;
;       if (mode == 2) o = sigmf(v);
;       sT[row * 136 + col] = f2bf(o);
;     });
.LBB0_1775:
	v_bfe_u32 v61, v60, 16, 1
	v_add_u32_e32 v55, 0x110, v55
	v_add3_u32 v61, v60, v61, s78
	v_lshl_add_u32 v60, v106, 1, v55
	ds_write_b16_d16_hi v60, v61
	v_add3_u32 v61, s96, v96, 56
	v_cmp_lt_i32_e64 s[34:35], s76, v61
	s_nop 1

; __device__ __forceinline__ float sigmf(float x) { return 1.f / (1.f + __expf(-x)); }
; __device__ __forceinline__ void inproj_epilogue(const Params& p, int layer, int mt, int ntile, int tid,
;                                                 f32x16 (&acc)[2][2], unsigned char* smem) {
;     ...
;     acc_foreach(tid, acc, [&](int row, int col, float v) {
;       int t = m0 + row;
;       float o = v;
;       if (mode == 1) o = (t >= NPADR) ? v : 0.f;
;       if (mode == 2) o = sigmf(v);
;       sT[row * 136 + col] = f2bf(o);
;     });
.LBB0_1778:
	v_bfe_u32 v62, v61, 16, 1
	v_add_u32_e32 v55, 0x550, v55
	v_add3_u32 v62, v61, v62, s78
	v_lshl_add_u32 v61, v106, 1, v55
	ds_write_b16_d16_hi v61, v62
	v_add3_u32 v62, s96, v96, 57
	v_cmp_lt_i32_e64 s[36:37], s76, v62
	s_nop 1

; __device__ __forceinline__ float sigmf(float x) { return 1.f / (1.f + __expf(-x)); }
; __device__ __forceinline__ void inproj_epilogue(const Params& p, int layer, int mt, int ntile, int tid,
;                                                 f32x16 (&acc)[2][2], unsigned char* smem) {
;     ...
;     acc_foreach(tid, acc, [&](int row, int col, float v) {
;       int t = m0 + row;
;       float o = v;
;       if (mode == 1) o = (t >= NPADR) ? v : 0.f;
;       if (mode == 2) o = sigmf(v);
;       sT[row * 136 + col] = f2bf(o);
;     });
.LBB0_1781:
	v_bfe_u32 v63, v62, 16, 1
	v_add_u32_e32 v55, 0x110, v55
	v_add3_u32 v63, v62, v63, s78
	v_lshl_add_u32 v62, v106, 1, v55
	ds_write_b16_d16_hi v62, v63
	v_add3_u32 v63, s96, v96, 58
	v_cmp_lt_i32_e64 s[38:39], s76, v63
	s_nop 1

; __device__ __forceinline__ float sigmf(float x) { return 1.f / (1.f + __expf(-x)); }
; __device__ __forceinline__ void inproj_epilogue(const Params& p, int layer, int mt, int ntile, int tid,
;                                                 f32x16 (&acc)[2][2], unsigned char* smem) {
;     ...
;     acc_foreach(tid, acc, [&](int row, int col, float v) {
;       int t = m0 + row;
;       float o = v;
;       if (mode == 1) o = (t >= NPADR) ? v : 0.f;
;       if (mode == 2) o = sigmf(v);
;       sT[row * 136 + col] = f2bf(o);
;     });
.LBB0_1784:
	v_bfe_u32 v107, v63, 16, 1
	v_add_u32_e32 v55, 0x110, v55
	v_add3_u32 v63, v63, v107, s78
	v_lshl_add_u32 v55, v106, 1, v55
	ds_write_b16_d16_hi v55, v63
	v_add3_u32 v63, s96, v96, 59
	v_cmp_lt_i32_e64 s[40:41], s76, v63
	s_nop 1

; __device__ __forceinline__ float sigmf(float x) { return 1.f / (1.f + __expf(-x)); }
; __device__ __forceinline__ void inproj_epilogue(const Params& p, int layer, int mt, int ntile, int tid,
;                                                 f32x16 (&acc)[2][2], unsigned char* smem) {
;     ...
;     acc_foreach(tid, acc, [&](int row, int col, float v) {
;       int t = m0 + row;
;       float o = v;
;       if (mode == 1) o = (t >= NPADR) ? v : 0.f;
;       if (mode == 2) o = sigmf(v);
;       sT[row * 136 + col] = f2bf(o);
;     });
.Lgv_3:
	v_mul_f32_e32 v107, 0xbfb8aa3b, v16
	v_exp_f32_e32 v107, v107
	s_nop 0
	v_add_f32_e32 v107, 1.0, v107
	v_div_scale_f32 v110, s[6:7], v107, v107, 1.0
	v_rcp_f32_e32 v111, v110
	v_div_scale_f32 v112, vcc, 1.0, v107, 1.0
	v_fma_f32 v113, -v110, v111, 1.0
	v_fmac_f32_e32 v111, v113, v111
	v_mul_f32_e32 v113, v112, v111
	v_fma_f32 v114, -v110, v113, v112
	v_fmac_f32_e32 v113, v114, v111
	v_fma_f32 v110, -v110, v113, v112
	v_div_fmas_f32 v110, v110, v111, v113
	v_div_fixup_f32 v107, v110, v107, 1.0
	v_bfe_u32 v110, v107, 16, 1
	v_and_b32_e32 v106, 0x5f, v106
	v_add3_u32 v111, v107, v110, s78
	v_mul_lo_u32 v110, v96, s79
	v_lshl_add_u32 v107, v106, 1, v110
	ds_write_b16_d16_hi v107, v111
	v_add3_u32 v111, s96, v96, 1
	v_cmp_lt_i32_e64 s[10:11], s76, v111
	v_cndmask_b32_e64 v111, 0, 1, s[12:13]
	v_cmp_ne_u32_e64 s[6:7], 1, v111
	s_andn2_b64 vcc, exec, s[12:13]
	v_mul_f32_e32 v111, 0xbfb8aa3b, v17
	v_exp_f32_e32 v111, v111
	s_nop 0
	v_add_f32_e32 v111, 1.0, v111
	v_div_scale_f32 v112, s[12:13], v111, v111, 1.0
	v_rcp_f32_e32 v113, v112
	v_div_scale_f32 v114, vcc, 1.0, v111, 1.0
	v_fma_f32 v115, -v112, v113, 1.0
	v_fmac_f32_e32 v113, v115, v113
	v_mul_f32_e32 v115, v114, v113
	v_fma_f32 v116, -v112, v115, v114
	v_fmac_f32_e32 v115, v116, v113
	v_fma_f32 v112, -v112, v115, v114
	v_div_fmas_f32 v112, v112, v113, v115
	v_div_fixup_f32 v111, v112, v111, 1.0
	v_bfe_u32 v112, v111, 16, 1
	v_add3_u32 v112, v111, v112, s78
	v_add_u32_e32 v111, 0x110, v110
	v_lshl_add_u32 v110, v106, 1, v111
	ds_write_b16_d16_hi v110, v112
	v_add3_u32 v112, s96, v96, 2
	s_and_b64 vcc, exec, s[6:7]
	v_cmp_lt_i32_e64 s[12:13], s76, v112
	v_mul_f32_e32 v112, 0xbfb8aa3b, v18
	v_exp_f32_e32 v112, v112
	s_nop 0
	v_add_f32_e32 v112, 1.0, v112
	v_div_scale_f32 v113, s[14:15], v112, v112, 1.0
	v_rcp_f32_e32 v114, v113
	v_div_scale_f32 v115, vcc, 1.0, v112, 1.0
	v_fma_f32 v116, -v113, v114, 1.0
	v_fmac_f32_e32 v114, v116, v114
	v_mul_f32_e32 v116, v115, v114
	v_fma_f32 v117, -v113, v116, v115
	v_fmac_f32_e32 v116, v117, v114
	v_fma_f32 v113, -v113, v116, v115
	v_div_fmas_f32 v113, v113, v114, v116
	v_div_fixup_f32 v112, v113, v112, 1.0
	v_bfe_u32 v113, v112, 16, 1
	v_add3_u32 v113, v112, v113, s78
	v_add_u32_e32 v112, 0x110, v111
	v_lshl_add_u32 v111, v106, 1, v112
	ds_write_b16_d16_hi v111, v113
	v_add3_u32 v113, s96, v96, 3
	s_and_b64 vcc, exec, s[6:7]
	v_cmp_lt_i32_e64 s[14:15], s76, v113
	v_mul_f32_e32 v113, 0xbfb8aa3b, v19
	v_exp_f32_e32 v113, v113
	s_nop 0
	v_add_f32_e32 v113, 1.0, v113
	v_div_scale_f32 v114, s[16:17], v113, v113, 1.0
	v_rcp_f32_e32 v115, v114
	v_div_scale_f32 v116, vcc, 1.0, v113, 1.0
	v_fma_f32 v117, -v114, v115, 1.0
	v_fmac_f32_e32 v115, v117, v115
	v_mul_f32_e32 v117, v116, v115
	v_fma_f32 v118, -v114, v117, v116
	v_fmac_f32_e32 v117, v118, v115
	v_fma_f32 v114, -v114, v117, v116
	v_div_fmas_f32 v114, v114, v115, v117
	v_div_fixup_f32 v113, v114, v113, 1.0
	v_bfe_u32 v114, v113, 16, 1
	v_add3_u32 v114, v113, v114, s78
	v_add_u32_e32 v113, 0x110, v112
	v_lshl_add_u32 v112, v106, 1, v113
	ds_write_b16_d16_hi v112, v114
	v_add3_u32 v114, s96, v96, 8
	s_and_b64 vcc, exec, s[6:7]
	v_cmp_lt_i32_e64 s[16:17], s76, v114
	v_mul_f32_e32 v114, 0xbfb8aa3b, v20
	v_exp_f32_e32 v114, v114
	s_nop 0
	v_add_f32_e32 v114, 1.0, v114
	v_div_scale_f32 v115, s[18:19], v114, v114, 1.0
	v_rcp_f32_e32 v116, v115
	v_div_scale_f32 v117, vcc, 1.0, v114, 1.0
	v_fma_f32 v118, -v115, v116, 1.0
	v_fmac_f32_e32 v116, v118, v116
	v_mul_f32_e32 v118, v117, v116
	v_fma_f32 v119, -v115, v118, v117
	v_fmac_f32_e32 v118, v119, v116
	v_fma_f32 v115, -v115, v118, v117
	v_div_fmas_f32 v115, v115, v116, v118
	v_div_fixup_f32 v114, v115, v114, 1.0
	v_bfe_u32 v115, v114, 16, 1
	v_add3_u32 v115, v114, v115, s78
	v_add_u32_e32 v114, 0x550, v113
	v_lshl_add_u32 v113, v106, 1, v114
	ds_write_b16_d16_hi v113, v115
	v_add3_u32 v115, s96, v96, 9
	s_and_b64 vcc, exec, s[6:7]
	v_cmp_lt_i32_e64 s[18:19], s76, v115
	v_mul_f32_e32 v115, 0xbfb8aa3b, v21
	v_exp_f32_e32 v115, v115
	s_nop 0
	v_add_f32_e32 v115, 1.0, v115
	v_div_scale_f32 v116, s[20:21], v115, v115, 1.0
	v_rcp_f32_e32 v117, v116
	v_div_scale_f32 v118, vcc, 1.0, v115, 1.0
	v_fma_f32 v119, -v116, v117, 1.0
	v_fmac_f32_e32 v117, v119, v117
	v_mul_f32_e32 v119, v118, v117
	v_fma_f32 v120, -v116, v119, v118
	v_fmac_f32_e32 v119, v120, v117
	v_fma_f32 v116, -v116, v119, v118
	v_div_fmas_f32 v116, v116, v117, v119
	v_div_fixup_f32 v115, v116, v115, 1.0
	v_bfe_u32 v116, v115, 16, 1
	v_add3_u32 v116, v115, v116, s78
	v_add_u32_e32 v115, 0x110, v114
	v_lshl_add_u32 v114, v106, 1, v115
	ds_write_b16_d16_hi v114, v116
	v_add3_u32 v116, s96, v96, 10
	s_and_b64 vcc, exec, s[6:7]
	v_cmp_lt_i32_e64 s[20:21], s76, v116
	v_mul_f32_e32 v116, 0xbfb8aa3b, v22
	v_exp_f32_e32 v116, v116
	s_nop 0
	v_add_f32_e32 v116, 1.0, v116
	v_div_scale_f32 v117, s[22:23], v116, v116, 1.0
	v_rcp_f32_e32 v118, v117
	v_div_scale_f32 v119, vcc, 1.0, v116, 1.0
	v_fma_f32 v120, -v117, v118, 1.0
	v_fmac_f32_e32 v118, v120, v118
	v_mul_f32_e32 v120, v119, v118
	v_fma_f32 v121, -v117, v120, v119
	v_fmac_f32_e32 v120, v121, v118
	v_fma_f32 v117, -v117, v120, v119
	v_div_fmas_f32 v117, v117, v118, v120
	v_div_fixup_f32 v116, v117, v116, 1.0
	v_bfe_u32 v117, v116, 16, 1
	v_add3_u32 v117, v116, v117, s78
	v_add_u32_e32 v116, 0x110, v115
	v_lshl_add_u32 v115, v106, 1, v116
	ds_write_b16_d16_hi v115, v117
	v_add3_u32 v117, s96, v96, 11
	s_and_b64 vcc, exec, s[6:7]
	v_cmp_lt_i32_e64 s[22:23], s76, v117
	v_mul_f32_e32 v117, 0xbfb8aa3b, v23
	v_exp_f32_e32 v117, v117
	s_nop 0
	v_add_f32_e32 v117, 1.0, v117
	v_div_scale_f32 v118, s[24:25], v117, v117, 1.0
	v_rcp_f32_e32 v119, v118
; __device__ __forceinline__ float sigmf(float x) { return 1.f / (1.f + __expf(-x)); }
; __device__ __forceinline__ void inproj_epilogue(const Params& p, int layer, int mt, int ntile, int tid,
;                                                 f32x16 (&acc)[2][2], unsigned char* smem) {
;     ...
;     acc_foreach(tid, acc, [&](int row, int col, float v) {
;       int t = m0 + row;
;       float o = v;
;       if (mode == 1) o = (t >= NPADR) ? v : 0.f;
;       if (mode == 2) o = sigmf(v);
;       sT[row * 136 + col] = f2bf(o);
;     });
	v_div_scale_f32 v120, vcc, 1.0, v117, 1.0
	v_fma_f32 v121, -v118, v119, 1.0
	v_fmac_f32_e32 v119, v121, v119
	v_mul_f32_e32 v121, v120, v119
	v_fma_f32 v122, -v118, v121, v120
	v_fmac_f32_e32 v121, v122, v119
	v_fma_f32 v118, -v118, v121, v120
	v_div_fmas_f32 v118, v118, v119, v121
	v_div_fixup_f32 v117, v118, v117, 1.0
	v_bfe_u32 v118, v117, 16, 1
	v_add_u32_e32 v116, 0x110, v116
	v_add3_u32 v118, v117, v118, s78
	v_lshl_add_u32 v117, v106, 1, v116
	ds_write_b16_d16_hi v117, v118
	v_add3_u32 v118, s96, v96, 16
	s_and_b64 vcc, exec, s[6:7]
	v_cmp_lt_i32_e64 s[24:25], s76, v118
	v_mul_f32_e32 v118, 0xbfb8aa3b, v24
	v_exp_f32_e32 v118, v118
	s_nop 0
	v_add_f32_e32 v118, 1.0, v118
	v_div_scale_f32 v119, s[26:27], v118, v118, 1.0
	v_rcp_f32_e32 v120, v119
	v_div_scale_f32 v121, vcc, 1.0, v118, 1.0
	v_fma_f32 v122, -v119, v120, 1.0
	v_fmac_f32_e32 v120, v122, v120
	v_mul_f32_e32 v122, v121, v120
	v_fma_f32 v123, -v119, v122, v121
	v_fmac_f32_e32 v122, v123, v120
	v_fma_f32 v119, -v119, v122, v121
	v_div_fmas_f32 v119, v119, v120, v122
	v_div_fixup_f32 v118, v119, v118, 1.0
	v_bfe_u32 v119, v118, 16, 1
	v_add_u32_e32 v116, 0x550, v116
	v_add3_u32 v119, v118, v119, s78
	v_lshl_add_u32 v118, v106, 1, v116
	ds_write_b16_d16_hi v118, v119
	v_add3_u32 v119, s96, v96, 17
	s_and_b64 vcc, exec, s[6:7]
	v_cmp_lt_i32_e64 s[26:27], s76, v119
	v_mul_f32_e32 v119, 0xbfb8aa3b, v25
	v_exp_f32_e32 v119, v119
	s_nop 0
	v_add_f32_e32 v119, 1.0, v119
	v_div_scale_f32 v120, s[28:29], v119, v119, 1.0
	v_rcp_f32_e32 v121, v120
	v_div_scale_f32 v122, vcc, 1.0, v119, 1.0
	v_fma_f32 v123, -v120, v121, 1.0
	v_fmac_f32_e32 v121, v123, v121
	v_mul_f32_e32 v123, v122, v121
	v_fma_f32 v124, -v120, v123, v122
	v_fmac_f32_e32 v123, v124, v121
	v_fma_f32 v120, -v120, v123, v122
	v_div_fmas_f32 v120, v120, v121, v123
	v_div_fixup_f32 v119, v120, v119, 1.0
	v_bfe_u32 v120, v119, 16, 1
	v_add_u32_e32 v116, 0x110, v116
	v_add3_u32 v120, v119, v120, s78
	v_lshl_add_u32 v119, v106, 1, v116
	ds_write_b16_d16_hi v119, v120
	v_add3_u32 v120, s96, v96, 18
	s_and_b64 vcc, exec, s[6:7]
	v_cmp_lt_i32_e64 s[28:29], s76, v120
	v_mul_f32_e32 v120, 0xbfb8aa3b, v26
	v_exp_f32_e32 v120, v120
	s_nop 0
	v_add_f32_e32 v120, 1.0, v120
	v_div_scale_f32 v121, s[30:31], v120, v120, 1.0
	v_rcp_f32_e32 v122, v121
	v_div_scale_f32 v123, vcc, 1.0, v120, 1.0
	v_fma_f32 v124, -v121, v122, 1.0
	v_fmac_f32_e32 v122, v124, v122
	v_mul_f32_e32 v124, v123, v122
	v_fma_f32 v125, -v121, v124, v123
	v_fmac_f32_e32 v124, v125, v122
	v_fma_f32 v121, -v121, v124, v123
	v_div_fmas_f32 v121, v121, v122, v124
	v_div_fixup_f32 v120, v121, v120, 1.0
	v_bfe_u32 v121, v120, 16, 1
	v_add_u32_e32 v116, 0x110, v116
	v_add3_u32 v121, v120, v121, s78
	v_lshl_add_u32 v120, v106, 1, v116
	ds_write_b16_d16_hi v120, v121
	v_add3_u32 v121, s96, v96, 19
	s_and_b64 vcc, exec, s[6:7]
	v_cmp_lt_i32_e64 s[30:31], s76, v121
	v_mul_f32_e32 v121, 0xbfb8aa3b, v27
	v_exp_f32_e32 v121, v121
	s_nop 0
	v_add_f32_e32 v121, 1.0, v121
	v_div_scale_f32 v122, s[34:35], v121, v121, 1.0
	v_rcp_f32_e32 v123, v122
	v_div_scale_f32 v124, vcc, 1.0, v121, 1.0
	v_fma_f32 v125, -v122, v123, 1.0
	v_fmac_f32_e32 v123, v125, v123
	v_mul_f32_e32 v125, v124, v123
	v_fma_f32 v126, -v122, v125, v124
	v_fmac_f32_e32 v125, v126, v123
	v_fma_f32 v122, -v122, v125, v124
	v_div_fmas_f32 v122, v122, v123, v125
	v_div_fixup_f32 v121, v122, v121, 1.0
	v_bfe_u32 v122, v121, 16, 1
	v_add_u32_e32 v116, 0x110, v116
	v_add3_u32 v122, v121, v122, s78
	v_lshl_add_u32 v121, v106, 1, v116
	ds_write_b16_d16_hi v121, v122
	v_add3_u32 v122, s96, v96, 24
	s_and_b64 vcc, exec, s[6:7]
	v_cmp_lt_i32_e64 s[34:35], s76, v122
	v_mul_f32_e32 v122, 0xbfb8aa3b, v28
	v_exp_f32_e32 v122, v122
	s_nop 0
	v_add_f32_e32 v122, 1.0, v122
	v_div_scale_f32 v123, s[36:37], v122, v122, 1.0
	v_rcp_f32_e32 v124, v123
	v_div_scale_f32 v125, vcc, 1.0, v122, 1.0
	v_fma_f32 v126, -v123, v124, 1.0
	v_fmac_f32_e32 v124, v126, v124
	v_mul_f32_e32 v126, v125, v124
	v_fma_f32 v127, -v123, v126, v125
	v_fmac_f32_e32 v126, v127, v124
	v_fma_f32 v123, -v123, v126, v125
	v_div_fmas_f32 v123, v123, v124, v126
	v_div_fixup_f32 v122, v123, v122, 1.0
	v_bfe_u32 v123, v122, 16, 1
	v_add_u32_e32 v116, 0x550, v116
	v_add3_u32 v123, v122, v123, s78
	v_lshl_add_u32 v122, v106, 1, v116
	ds_write_b16_d16_hi v122, v123
	v_add3_u32 v123, s96, v96, 25
	s_and_b64 vcc, exec, s[6:7]
	v_cmp_lt_i32_e64 s[36:37], s76, v123
	v_mul_f32_e32 v123, 0xbfb8aa3b, v29
	v_exp_f32_e32 v123, v123
	s_nop 0
	v_add_f32_e32 v123, 1.0, v123
	v_div_scale_f32 v124, s[38:39], v123, v123, 1.0
	v_rcp_f32_e32 v125, v124
	v_div_scale_f32 v126, vcc, 1.0, v123, 1.0
	v_fma_f32 v127, -v124, v125, 1.0
	v_fmac_f32_e32 v125, v127, v125
	v_mul_f32_e32 v127, v126, v125
	v_fma_f32 v128, -v124, v127, v126
	v_fmac_f32_e32 v127, v128, v125
	v_fma_f32 v124, -v124, v127, v126
	v_div_fmas_f32 v124, v124, v125, v127
	v_div_fixup_f32 v123, v124, v123, 1.0
	v_bfe_u32 v124, v123, 16, 1
	v_add_u32_e32 v116, 0x110, v116
	v_add3_u32 v124, v123, v124, s78
	v_lshl_add_u32 v123, v106, 1, v116
	ds_write_b16_d16_hi v123, v124
	v_add3_u32 v124, s96, v96, 26
	s_and_b64 vcc, exec, s[6:7]
	v_cmp_lt_i32_e64 s[38:39], s76, v124
	v_mul_f32_e32 v124, 0xbfb8aa3b, v30
	v_exp_f32_e32 v124, v124
	s_nop 0
	v_add_f32_e32 v124, 1.0, v124
	v_div_scale_f32 v125, s[40:41], v124, v124, 1.0
	v_rcp_f32_e32 v126, v125
	v_div_scale_f32 v127, vcc, 1.0, v124, 1.0
	v_fma_f32 v128, -v125, v126, 1.0
	v_fmac_f32_e32 v126, v128, v126
	v_mul_f32_e32 v128, v127, v126
	v_fma_f32 v129, -v125, v128, v127
	v_fmac_f32_e32 v128, v129, v126
	v_fma_f32 v125, -v125, v128, v127
	v_div_fmas_f32 v125, v125, v126, v128
; __device__ __forceinline__ float sigmf(float x) { return 1.f / (1.f + __expf(-x)); }
; __device__ __forceinline__ void inproj_epilogue(const Params& p, int layer, int mt, int ntile, int tid,
;                                                 f32x16 (&acc)[2][2], unsigned char* smem) {
;     ...
;     acc_foreach(tid, acc, [&](int row, int col, float v) {
;       int t = m0 + row;
;       float o = v;
;       if (mode == 1) o = (t >= NPADR) ? v : 0.f;
;       if (mode == 2) o = sigmf(v);
;       sT[row * 136 + col] = f2bf(o);
;     });
	v_div_fixup_f32 v124, v125, v124, 1.0
	v_bfe_u32 v125, v124, 16, 1
	v_add_u32_e32 v116, 0x110, v116
	v_add3_u32 v124, v124, v125, s78
	v_lshl_add_u32 v116, v106, 1, v116
	ds_write_b16_d16_hi v116, v124
	v_add3_u32 v124, s96, v96, 27
	s_and_b64 vcc, exec, s[6:7]
	v_cmp_lt_i32_e64 s[40:41], s76, v124
	v_mul_f32_e32 v124, 0xbfb8aa3b, v31
	v_exp_f32_e32 v124, v124
	s_nop 0
	v_add_f32_e32 v124, 1.0, v124
	v_div_scale_f32 v125, vcc, v124, v124, 1.0
	v_rcp_f32_e32 v126, v125
	v_div_scale_f32 v127, vcc, 1.0, v124, 1.0
	v_fma_f32 v128, -v125, v126, 1.0
	v_fmac_f32_e32 v126, v128, v126
	v_mul_f32_e32 v128, v127, v126
	v_fma_f32 v129, -v125, v128, v127
	v_fmac_f32_e32 v128, v129, v126
	v_fma_f32 v125, -v125, v128, v127
	v_div_fmas_f32 v125, v125, v126, v128
	v_div_fixup_f32 v124, v125, v124, 1.0
	v_bfe_u32 v125, v124, 16, 1
	v_add3_u32 v124, v124, v125, s78
	ds_write_b16_d16_hi v116, v124 offset:272
	s_and_b64 vcc, exec, s[6:7]
	v_mul_f32_e32 v48, 0xbfb8aa3b, v48
	v_exp_f32_e32 v48, v48
	s_nop 0
	v_add_f32_e32 v48, 1.0, v48
	v_div_scale_f32 v124, s[8:9], v48, v48, 1.0
	v_rcp_f32_e32 v125, v124
	v_div_scale_f32 v126, vcc, 1.0, v48, 1.0
	v_fma_f32 v127, -v124, v125, 1.0
	v_fmac_f32_e32 v125, v127, v125
	v_mul_f32_e32 v127, v126, v125
	v_fma_f32 v128, -v124, v127, v126
	v_fmac_f32_e32 v127, v128, v125
	v_fma_f32 v124, -v124, v127, v126
	v_div_fmas_f32 v124, v124, v125, v127
	v_div_fixup_f32 v48, v124, v48, 1.0
	v_bfe_u32 v124, v48, 16, 1
	v_add3_u32 v48, v48, v124, s78
	s_and_b64 vcc, exec, s[6:7]
	ds_write_b16_d16_hi v107, v48 offset:64
	v_mul_f32_e32 v48, 0xbfb8aa3b, v49
	v_exp_f32_e32 v48, v48
	s_nop 0
	v_add_f32_e32 v48, 1.0, v48
	v_div_scale_f32 v49, s[8:9], v48, v48, 1.0
	v_rcp_f32_e32 v107, v49
	v_div_scale_f32 v124, vcc, 1.0, v48, 1.0
	v_fma_f32 v125, -v49, v107, 1.0
	v_fmac_f32_e32 v107, v125, v107
	v_mul_f32_e32 v125, v124, v107
	v_fma_f32 v126, -v49, v125, v124
	v_fmac_f32_e32 v125, v126, v107
	v_fma_f32 v49, -v49, v125, v124
	v_div_fmas_f32 v49, v49, v107, v125
	v_div_fixup_f32 v48, v49, v48, 1.0
	v_bfe_u32 v49, v48, 16, 1
	v_add3_u32 v48, v48, v49, s78
	s_and_b64 vcc, exec, s[6:7]
	ds_write_b16_d16_hi v110, v48 offset:64
	v_mul_f32_e32 v48, 0xbfb8aa3b, v50
	v_exp_f32_e32 v48, v48
	s_nop 0
	v_add_f32_e32 v48, 1.0, v48
	v_div_scale_f32 v49, s[8:9], v48, v48, 1.0
	v_rcp_f32_e32 v50, v49
	v_div_scale_f32 v107, vcc, 1.0, v48, 1.0
	v_fma_f32 v110, -v49, v50, 1.0
	v_fmac_f32_e32 v50, v110, v50
	v_mul_f32_e32 v110, v107, v50
	v_fma_f32 v124, -v49, v110, v107
	v_fmac_f32_e32 v110, v124, v50
	v_fma_f32 v49, -v49, v110, v107
	v_div_fmas_f32 v49, v49, v50, v110
	v_div_fixup_f32 v48, v49, v48, 1.0
	v_bfe_u32 v49, v48, 16, 1
	v_add3_u32 v48, v48, v49, s78
	s_and_b64 vcc, exec, s[6:7]
	ds_write_b16_d16_hi v111, v48 offset:64
	v_mul_f32_e32 v48, 0xbfb8aa3b, v51
	v_exp_f32_e32 v48, v48
	s_nop 0
	v_add_f32_e32 v48, 1.0, v48
	v_div_scale_f32 v49, s[8:9], v48, v48, 1.0
	v_rcp_f32_e32 v50, v49
	v_div_scale_f32 v51, vcc, 1.0, v48, 1.0
	v_fma_f32 v107, -v49, v50, 1.0
	v_fmac_f32_e32 v50, v107, v50
	v_mul_f32_e32 v107, v51, v50
	v_fma_f32 v110, -v49, v107, v51
	v_fmac_f32_e32 v107, v110, v50
	v_fma_f32 v49, -v49, v107, v51
	v_div_fmas_f32 v49, v49, v50, v107
	v_div_fixup_f32 v48, v49, v48, 1.0
	v_bfe_u32 v49, v48, 16, 1
	v_add3_u32 v48, v48, v49, s78
	s_and_b64 vcc, exec, s[6:7]
	ds_write_b16_d16_hi v112, v48 offset:64
	v_mul_f32_e32 v48, 0xbfb8aa3b, v52
	v_exp_f32_e32 v48, v48
	s_nop 0
	v_add_f32_e32 v48, 1.0, v48
	v_div_scale_f32 v49, s[8:9], v48, v48, 1.0
	v_rcp_f32_e32 v50, v49
	v_div_scale_f32 v51, vcc, 1.0, v48, 1.0
	v_fma_f32 v52, -v49, v50, 1.0
	v_fmac_f32_e32 v50, v52, v50
	v_mul_f32_e32 v52, v51, v50
	v_fma_f32 v107, -v49, v52, v51
	v_fmac_f32_e32 v52, v107, v50
	v_fma_f32 v49, -v49, v52, v51
	v_div_fmas_f32 v49, v49, v50, v52
	v_div_fixup_f32 v48, v49, v48, 1.0
	v_bfe_u32 v49, v48, 16, 1
	v_add3_u32 v48, v48, v49, s78
	s_and_b64 vcc, exec, s[6:7]
	ds_write_b16_d16_hi v113, v48 offset:64
	v_mul_f32_e32 v48, 0xbfb8aa3b, v53
	v_exp_f32_e32 v48, v48
	s_nop 0
	v_add_f32_e32 v48, 1.0, v48
	v_div_scale_f32 v49, s[8:9], v48, v48, 1.0
	v_rcp_f32_e32 v50, v49
	v_div_scale_f32 v51, vcc, 1.0, v48, 1.0
	v_fma_f32 v52, -v49, v50, 1.0
	v_fmac_f32_e32 v50, v52, v50
	v_mul_f32_e32 v52, v51, v50
	v_fma_f32 v53, -v49, v52, v51
	v_fmac_f32_e32 v52, v53, v50
	v_fma_f32 v49, -v49, v52, v51
	v_div_fmas_f32 v49, v49, v50, v52
	v_div_fixup_f32 v48, v49, v48, 1.0
	v_bfe_u32 v49, v48, 16, 1
	v_add3_u32 v48, v48, v49, s78
	s_and_b64 vcc, exec, s[6:7]
	ds_write_b16_d16_hi v114, v48 offset:64
	v_mul_f32_e32 v48, 0xbfb8aa3b, v54
	v_exp_f32_e32 v48, v48
	s_nop 0
	v_add_f32_e32 v48, 1.0, v48
	v_div_scale_f32 v49, s[8:9], v48, v48, 1.0
	v_rcp_f32_e32 v50, v49
	v_div_scale_f32 v51, vcc, 1.0, v48, 1.0
	v_fma_f32 v52, -v49, v50, 1.0
	v_fmac_f32_e32 v50, v52, v50
	v_mul_f32_e32 v52, v51, v50
	v_fma_f32 v53, -v49, v52, v51
	v_fmac_f32_e32 v52, v53, v50
	v_fma_f32 v49, -v49, v52, v51
	v_div_fmas_f32 v49, v49, v50, v52
	v_div_fixup_f32 v48, v49, v48, 1.0
	v_bfe_u32 v49, v48, 16, 1
	v_add3_u32 v48, v48, v49, s78
	s_and_b64 vcc, exec, s[6:7]
	ds_write_b16_d16_hi v115, v48 offset:64
	v_mul_f32_e32 v48, 0xbfb8aa3b, v55
	v_exp_f32_e32 v48, v48
	s_nop 0
	v_add_f32_e32 v48, 1.0, v48
	v_div_scale_f32 v49, s[8:9], v48, v48, 1.0
	v_rcp_f32_e32 v50, v49
	v_div_scale_f32 v51, vcc, 1.0, v48, 1.0
	v_fma_f32 v52, -v49, v50, 1.0
	v_fmac_f32_e32 v50, v52, v50
	v_mul_f32_e32 v52, v51, v50
	v_fma_f32 v53, -v49, v52, v51
	v_fmac_f32_e32 v52, v53, v50
	v_fma_f32 v49, -v49, v52, v51
	v_div_fmas_f32 v49, v49, v50, v52
	v_div_fixup_f32 v48, v49, v48, 1.0
	v_bfe_u32 v49, v48, 16, 1
	v_add3_u32 v48, v48, v49, s78
; __device__ __forceinline__ float sigmf(float x) { return 1.f / (1.f + __expf(-x)); }
; __device__ __forceinline__ void inproj_epilogue(const Params& p, int layer, int mt, int ntile, int tid,
;                                                 f32x16 (&acc)[2][2], unsigned char* smem) {
;     ...
;     acc_foreach(tid, acc, [&](int row, int col, float v) {
;       int t = m0 + row;
;       float o = v;
;       if (mode == 1) o = (t >= NPADR) ? v : 0.f;
;       if (mode == 2) o = sigmf(v);
;       sT[row * 136 + col] = f2bf(o);
;     });
	s_and_b64 vcc, exec, s[6:7]
	ds_write_b16_d16_hi v117, v48 offset:64
	v_mul_f32_e32 v48, 0xbfb8aa3b, v56
	v_exp_f32_e32 v48, v48
	s_nop 0
	v_add_f32_e32 v48, 1.0, v48
	v_div_scale_f32 v49, s[8:9], v48, v48, 1.0
	v_rcp_f32_e32 v50, v49
	v_div_scale_f32 v51, vcc, 1.0, v48, 1.0
	v_fma_f32 v52, -v49, v50, 1.0
	v_fmac_f32_e32 v50, v52, v50
	v_mul_f32_e32 v52, v51, v50
	v_fma_f32 v53, -v49, v52, v51
	v_fmac_f32_e32 v52, v53, v50
	v_fma_f32 v49, -v49, v52, v51
	v_div_fmas_f32 v49, v49, v50, v52
	v_div_fixup_f32 v48, v49, v48, 1.0
	v_bfe_u32 v49, v48, 16, 1
	v_add3_u32 v48, v48, v49, s78
	s_and_b64 vcc, exec, s[6:7]
	ds_write_b16_d16_hi v118, v48 offset:64
	v_mul_f32_e32 v48, 0xbfb8aa3b, v57
	v_exp_f32_e32 v48, v48
	s_nop 0
	v_add_f32_e32 v48, 1.0, v48
	v_div_scale_f32 v49, s[8:9], v48, v48, 1.0
	v_rcp_f32_e32 v50, v49
	v_div_scale_f32 v51, vcc, 1.0, v48, 1.0
	v_fma_f32 v52, -v49, v50, 1.0
	v_fmac_f32_e32 v50, v52, v50
	v_mul_f32_e32 v52, v51, v50
	v_fma_f32 v53, -v49, v52, v51
	v_fmac_f32_e32 v52, v53, v50
	v_fma_f32 v49, -v49, v52, v51
	v_div_fmas_f32 v49, v49, v50, v52
	v_div_fixup_f32 v48, v49, v48, 1.0
	v_bfe_u32 v49, v48, 16, 1
	v_add3_u32 v48, v48, v49, s78
	s_and_b64 vcc, exec, s[6:7]
	ds_write_b16_d16_hi v119, v48 offset:64
	v_mul_f32_e32 v48, 0xbfb8aa3b, v58
	v_exp_f32_e32 v48, v48
	s_nop 0
	v_add_f32_e32 v48, 1.0, v48
	v_div_scale_f32 v49, s[8:9], v48, v48, 1.0
	v_rcp_f32_e32 v50, v49
	v_div_scale_f32 v51, vcc, 1.0, v48, 1.0
	v_fma_f32 v52, -v49, v50, 1.0
	v_fmac_f32_e32 v50, v52, v50
	v_mul_f32_e32 v52, v51, v50
	v_fma_f32 v53, -v49, v52, v51
	v_fmac_f32_e32 v52, v53, v50
	v_fma_f32 v49, -v49, v52, v51
	v_div_fmas_f32 v49, v49, v50, v52
	v_div_fixup_f32 v48, v49, v48, 1.0
	v_bfe_u32 v49, v48, 16, 1
	v_add3_u32 v48, v48, v49, s78
	s_and_b64 vcc, exec, s[6:7]
	ds_write_b16_d16_hi v120, v48 offset:64
	v_mul_f32_e32 v48, 0xbfb8aa3b, v59
	v_exp_f32_e32 v48, v48
	s_nop 0
	v_add_f32_e32 v48, 1.0, v48
	v_div_scale_f32 v49, s[8:9], v48, v48, 1.0
	v_rcp_f32_e32 v50, v49
	v_div_scale_f32 v51, vcc, 1.0, v48, 1.0
	v_fma_f32 v52, -v49, v50, 1.0
	v_fmac_f32_e32 v50, v52, v50
	v_mul_f32_e32 v52, v51, v50
	v_fma_f32 v53, -v49, v52, v51
	v_fmac_f32_e32 v52, v53, v50
	v_fma_f32 v49, -v49, v52, v51
	v_div_fmas_f32 v49, v49, v50, v52
	v_div_fixup_f32 v48, v49, v48, 1.0
	v_bfe_u32 v49, v48, 16, 1
	v_add3_u32 v48, v48, v49, s78
	s_and_b64 vcc, exec, s[6:7]
	ds_write_b16_d16_hi v121, v48 offset:64
	v_mul_f32_e32 v48, 0xbfb8aa3b, v60
	v_exp_f32_e32 v48, v48
	s_nop 0
	v_add_f32_e32 v48, 1.0, v48
	v_div_scale_f32 v49, s[8:9], v48, v48, 1.0
	v_rcp_f32_e32 v50, v49
	v_div_scale_f32 v51, vcc, 1.0, v48, 1.0
	v_fma_f32 v52, -v49, v50, 1.0
	v_fmac_f32_e32 v50, v52, v50
	v_mul_f32_e32 v52, v51, v50
	v_fma_f32 v53, -v49, v52, v51
	v_fmac_f32_e32 v52, v53, v50
	v_fma_f32 v49, -v49, v52, v51
	v_div_fmas_f32 v49, v49, v50, v52
	v_div_fixup_f32 v48, v49, v48, 1.0
	v_bfe_u32 v49, v48, 16, 1
	v_add3_u32 v48, v48, v49, s78
	s_and_b64 vcc, exec, s[6:7]
	ds_write_b16_d16_hi v122, v48 offset:64
	v_mul_f32_e32 v48, 0xbfb8aa3b, v61
	v_exp_f32_e32 v48, v48
	s_nop 0
	v_add_f32_e32 v48, 1.0, v48
	v_div_scale_f32 v49, s[8:9], v48, v48, 1.0
	v_rcp_f32_e32 v50, v49
	v_div_scale_f32 v51, vcc, 1.0, v48, 1.0
	v_fma_f32 v52, -v49, v50, 1.0
	v_fmac_f32_e32 v50, v52, v50
	v_mul_f32_e32 v52, v51, v50
	v_fma_f32 v53, -v49, v52, v51
	v_fmac_f32_e32 v52, v53, v50
	v_fma_f32 v49, -v49, v52, v51
	v_div_fmas_f32 v49, v49, v50, v52
	v_div_fixup_f32 v48, v49, v48, 1.0
	v_bfe_u32 v49, v48, 16, 1
	v_add3_u32 v48, v48, v49, s78
	s_and_b64 vcc, exec, s[6:7]
	ds_write_b16_d16_hi v123, v48 offset:64
	v_mul_f32_e32 v48, 0xbfb8aa3b, v62
	v_exp_f32_e32 v48, v48
	s_nop 0
	v_add_f32_e32 v48, 1.0, v48
	v_div_scale_f32 v49, s[8:9], v48, v48, 1.0
	v_rcp_f32_e32 v50, v49
	v_div_scale_f32 v51, vcc, 1.0, v48, 1.0
	v_fma_f32 v52, -v49, v50, 1.0
	v_fmac_f32_e32 v50, v52, v50
	v_mul_f32_e32 v52, v51, v50
	v_fma_f32 v53, -v49, v52, v51
	v_fmac_f32_e32 v52, v53, v50
	v_fma_f32 v49, -v49, v52, v51
	v_div_fmas_f32 v49, v49, v50, v52
	v_div_fixup_f32 v48, v49, v48, 1.0
	v_bfe_u32 v49, v48, 16, 1
	v_add3_u32 v48, v48, v49, s78
	s_and_b64 vcc, exec, s[6:7]
	ds_write_b16_d16_hi v116, v48 offset:64
	v_mul_f32_e32 v48, 0xbfb8aa3b, v63
	v_exp_f32_e32 v48, v48
	s_nop 0
	v_add_f32_e32 v48, 1.0, v48
	v_div_scale_f32 v49, s[8:9], v48, v48, 1.0
	v_rcp_f32_e32 v50, v49
	v_div_scale_f32 v51, vcc, 1.0, v48, 1.0
	v_fma_f32 v52, -v49, v50, 1.0
	v_fmac_f32_e32 v50, v52, v50
	v_mul_f32_e32 v52, v51, v50
	v_fma_f32 v53, -v49, v52, v51
	v_fmac_f32_e32 v52, v53, v50
	v_fma_f32 v49, -v49, v52, v51
	v_div_fmas_f32 v49, v49, v50, v52
	v_div_fixup_f32 v48, v49, v48, 1.0
	v_bfe_u32 v50, v48, 16, 1
	v_add_u32_e32 v49, 0x110, v116
	v_add3_u32 v48, v48, v50, s78
	ds_write_b16_d16_hi v49, v48 offset:64
	v_or_b32_e32 v48, 32, v96
	v_add_u32_e32 v49, s96, v48
	s_and_b64 vcc, exec, s[6:7]
	v_cmp_lt_i32_e64 s[8:9], s76, v49
	v_mul_f32_e32 v49, 0xbfb8aa3b, v0
	v_exp_f32_e32 v49, v49
	s_nop 0
	v_add_f32_e32 v49, 1.0, v49
	v_div_scale_f32 v50, s[10:11], v49, v49, 1.0
	v_rcp_f32_e32 v51, v50
	v_div_scale_f32 v52, vcc, 1.0, v49, 1.0
	v_fma_f32 v53, -v50, v51, 1.0
	v_fmac_f32_e32 v51, v53, v51
	v_mul_f32_e32 v53, v52, v51
	v_fma_f32 v54, -v50, v53, v52
	v_fmac_f32_e32 v53, v54, v51
	v_fma_f32 v50, -v50, v53, v52
	v_div_fmas_f32 v50, v50, v51, v53
	v_div_fixup_f32 v49, v50, v49, 1.0
	v_bfe_u32 v50, v49, 16, 1
	v_add3_u32 v50, v49, v50, s78
	v_mul_lo_u32 v49, v48, s79
	v_lshl_add_u32 v48, v106, 1, v49
	ds_write_b16_d16_hi v48, v50
	v_add3_u32 v50, s96, v96, 33
	s_and_b64 vcc, exec, s[6:7]
	v_cmp_lt_i32_e64 s[10:11], s76, v50
	v_mul_f32_e32 v50, 0xbfb8aa3b, v1
; __device__ __forceinline__ float sigmf(float x) { return 1.f / (1.f + __expf(-x)); }
; __device__ __forceinline__ void inproj_epilogue(const Params& p, int layer, int mt, int ntile, int tid,
;                                                 f32x16 (&acc)[2][2], unsigned char* smem) {
;     ...
;     acc_foreach(tid, acc, [&](int row, int col, float v) {
;       int t = m0 + row;
;       float o = v;
;       if (mode == 1) o = (t >= NPADR) ? v : 0.f;
;       if (mode == 2) o = sigmf(v);
;       sT[row * 136 + col] = f2bf(o);
;     });
	v_exp_f32_e32 v50, v50
	s_nop 0
	v_add_f32_e32 v50, 1.0, v50
	v_div_scale_f32 v51, s[12:13], v50, v50, 1.0
	v_rcp_f32_e32 v52, v51
	v_div_scale_f32 v53, vcc, 1.0, v50, 1.0
	v_fma_f32 v54, -v51, v52, 1.0
	v_fmac_f32_e32 v52, v54, v52
	v_mul_f32_e32 v54, v53, v52
	v_fma_f32 v55, -v51, v54, v53
	v_fmac_f32_e32 v54, v55, v52
	v_fma_f32 v51, -v51, v54, v53
	v_div_fmas_f32 v51, v51, v52, v54
	v_div_fixup_f32 v50, v51, v50, 1.0
	v_bfe_u32 v51, v50, 16, 1
	v_add3_u32 v51, v50, v51, s78
	v_add_u32_e32 v50, 0x110, v49
	v_lshl_add_u32 v49, v106, 1, v50
	ds_write_b16_d16_hi v49, v51
	v_add3_u32 v51, s96, v96, 34
	s_and_b64 vcc, exec, s[6:7]
	v_cmp_lt_i32_e64 s[12:13], s76, v51
	v_mul_f32_e32 v51, 0xbfb8aa3b, v2
	v_exp_f32_e32 v51, v51
	s_nop 0
	v_add_f32_e32 v51, 1.0, v51
	v_div_scale_f32 v52, s[14:15], v51, v51, 1.0
	v_rcp_f32_e32 v53, v52
	v_div_scale_f32 v54, vcc, 1.0, v51, 1.0
	v_fma_f32 v55, -v52, v53, 1.0
	v_fmac_f32_e32 v53, v55, v53
	v_mul_f32_e32 v55, v54, v53
	v_fma_f32 v56, -v52, v55, v54
	v_fmac_f32_e32 v55, v56, v53
	v_fma_f32 v52, -v52, v55, v54
	v_div_fmas_f32 v52, v52, v53, v55
	v_div_fixup_f32 v51, v52, v51, 1.0
	v_bfe_u32 v52, v51, 16, 1
	v_add3_u32 v52, v51, v52, s78
	v_add_u32_e32 v51, 0x110, v50
	v_lshl_add_u32 v50, v106, 1, v51
	ds_write_b16_d16_hi v50, v52
	v_add3_u32 v52, s96, v96, 35
	s_and_b64 vcc, exec, s[6:7]
	v_cmp_lt_i32_e64 s[14:15], s76, v52
	v_mul_f32_e32 v52, 0xbfb8aa3b, v3
	v_exp_f32_e32 v52, v52
	s_nop 0
	v_add_f32_e32 v52, 1.0, v52
	v_div_scale_f32 v53, s[16:17], v52, v52, 1.0
	v_rcp_f32_e32 v54, v53
	v_div_scale_f32 v55, vcc, 1.0, v52, 1.0
	v_fma_f32 v56, -v53, v54, 1.0
	v_fmac_f32_e32 v54, v56, v54
	v_mul_f32_e32 v56, v55, v54
	v_fma_f32 v57, -v53, v56, v55
	v_fmac_f32_e32 v56, v57, v54
	v_fma_f32 v53, -v53, v56, v55
	v_div_fmas_f32 v53, v53, v54, v56
	v_div_fixup_f32 v52, v53, v52, 1.0
	v_bfe_u32 v53, v52, 16, 1
	v_add3_u32 v53, v52, v53, s78
	v_add_u32_e32 v52, 0x110, v51
	v_lshl_add_u32 v51, v106, 1, v52
	ds_write_b16_d16_hi v51, v53
	v_add3_u32 v53, s96, v96, 40
	s_and_b64 vcc, exec, s[6:7]
	v_cmp_lt_i32_e64 s[16:17], s76, v53
	v_mul_f32_e32 v53, 0xbfb8aa3b, v4
	v_exp_f32_e32 v53, v53
	s_nop 0
	v_add_f32_e32 v53, 1.0, v53
	v_div_scale_f32 v54, s[18:19], v53, v53, 1.0
	v_rcp_f32_e32 v55, v54
	v_div_scale_f32 v56, vcc, 1.0, v53, 1.0
	v_fma_f32 v57, -v54, v55, 1.0
	v_fmac_f32_e32 v55, v57, v55
	v_mul_f32_e32 v57, v56, v55
	v_fma_f32 v58, -v54, v57, v56
	v_fmac_f32_e32 v57, v58, v55
	v_fma_f32 v54, -v54, v57, v56
	v_div_fmas_f32 v54, v54, v55, v57
	v_div_fixup_f32 v53, v54, v53, 1.0
	v_bfe_u32 v54, v53, 16, 1
	v_add3_u32 v54, v53, v54, s78
	v_add_u32_e32 v53, 0x550, v52
	v_lshl_add_u32 v52, v106, 1, v53
	ds_write_b16_d16_hi v52, v54
	v_add3_u32 v54, s96, v96, 41
	s_and_b64 vcc, exec, s[6:7]
	v_cmp_lt_i32_e64 s[18:19], s76, v54
	v_mul_f32_e32 v54, 0xbfb8aa3b, v5
	v_exp_f32_e32 v54, v54
	s_nop 0
	v_add_f32_e32 v54, 1.0, v54
	v_div_scale_f32 v55, s[20:21], v54, v54, 1.0
	v_rcp_f32_e32 v56, v55
	v_div_scale_f32 v57, vcc, 1.0, v54, 1.0
	v_fma_f32 v58, -v55, v56, 1.0
	v_fmac_f32_e32 v56, v58, v56
	v_mul_f32_e32 v58, v57, v56
	v_fma_f32 v59, -v55, v58, v57
	v_fmac_f32_e32 v58, v59, v56
	v_fma_f32 v55, -v55, v58, v57
	v_div_fmas_f32 v55, v55, v56, v58
	v_div_fixup_f32 v54, v55, v54, 1.0
	v_bfe_u32 v55, v54, 16, 1
	v_add3_u32 v55, v54, v55, s78
	v_add_u32_e32 v54, 0x110, v53
	v_lshl_add_u32 v53, v106, 1, v54
	ds_write_b16_d16_hi v53, v55
	v_add3_u32 v55, s96, v96, 42
	s_and_b64 vcc, exec, s[6:7]
	v_cmp_lt_i32_e64 s[20:21], s76, v55
	v_mul_f32_e32 v55, 0xbfb8aa3b, v6
	v_exp_f32_e32 v55, v55
	s_nop 0
	v_add_f32_e32 v55, 1.0, v55
	v_div_scale_f32 v56, s[22:23], v55, v55, 1.0
	v_rcp_f32_e32 v57, v56
	v_div_scale_f32 v58, vcc, 1.0, v55, 1.0
	v_fma_f32 v59, -v56, v57, 1.0
	v_fmac_f32_e32 v57, v59, v57
	v_mul_f32_e32 v59, v58, v57
	v_fma_f32 v60, -v56, v59, v58
	v_fmac_f32_e32 v59, v60, v57
	v_fma_f32 v56, -v56, v59, v58
	v_div_fmas_f32 v56, v56, v57, v59
	v_div_fixup_f32 v55, v56, v55, 1.0
	v_bfe_u32 v56, v55, 16, 1
	v_add3_u32 v56, v55, v56, s78
	v_add_u32_e32 v55, 0x110, v54
	v_lshl_add_u32 v54, v106, 1, v55
	ds_write_b16_d16_hi v54, v56
	v_add3_u32 v56, s96, v96, 43
	s_and_b64 vcc, exec, s[6:7]
	v_cmp_lt_i32_e64 s[22:23], s76, v56
	v_mul_f32_e32 v56, 0xbfb8aa3b, v7
	v_exp_f32_e32 v56, v56
	s_nop 0
	v_add_f32_e32 v56, 1.0, v56
	v_div_scale_f32 v57, s[24:25], v56, v56, 1.0
	v_rcp_f32_e32 v58, v57
	v_div_scale_f32 v59, vcc, 1.0, v56, 1.0
	v_fma_f32 v60, -v57, v58, 1.0
	v_fmac_f32_e32 v58, v60, v58
	v_mul_f32_e32 v60, v59, v58
	v_fma_f32 v61, -v57, v60, v59
	v_fmac_f32_e32 v60, v61, v58
	v_fma_f32 v57, -v57, v60, v59
	v_div_fmas_f32 v57, v57, v58, v60
	v_div_fixup_f32 v56, v57, v56, 1.0
	v_bfe_u32 v57, v56, 16, 1
	v_add_u32_e32 v55, 0x110, v55
	v_add3_u32 v57, v56, v57, s78
	v_lshl_add_u32 v56, v106, 1, v55
	ds_write_b16_d16_hi v56, v57
	v_add3_u32 v57, s96, v96, 48
	s_and_b64 vcc, exec, s[6:7]
	v_cmp_lt_i32_e64 s[24:25], s76, v57
	v_mul_f32_e32 v57, 0xbfb8aa3b, v8
	v_exp_f32_e32 v57, v57
	s_nop 0
	v_add_f32_e32 v57, 1.0, v57
	v_div_scale_f32 v58, s[26:27], v57, v57, 1.0
	v_rcp_f32_e32 v59, v58
	v_div_scale_f32 v60, vcc, 1.0, v57, 1.0
	v_fma_f32 v61, -v58, v59, 1.0
	v_fmac_f32_e32 v59, v61, v59
	v_mul_f32_e32 v61, v60, v59
	v_fma_f32 v62, -v58, v61, v60
	v_fmac_f32_e32 v61, v62, v59
	v_fma_f32 v58, -v58, v61, v60
	v_div_fmas_f32 v58, v58, v59, v61
	v_div_fixup_f32 v57, v58, v57, 1.0
	v_bfe_u32 v58, v57, 16, 1
	v_add_u32_e32 v55, 0x550, v55
	v_add3_u32 v58, v57, v58, s78
	v_lshl_add_u32 v57, v106, 1, v55
	ds_write_b16_d16_hi v57, v58
	v_add3_u32 v58, s96, v96, 49
	s_and_b64 vcc, exec, s[6:7]
	v_cmp_lt_i32_e64 s[26:27], s76, v58
; __device__ __forceinline__ float sigmf(float x) { return 1.f / (1.f + __expf(-x)); }
; __device__ __forceinline__ void inproj_epilogue(const Params& p, int layer, int mt, int ntile, int tid,
;                                                 f32x16 (&acc)[2][2], unsigned char* smem) {
;     ...
;     acc_foreach(tid, acc, [&](int row, int col, float v) {
;       int t = m0 + row;
;       float o = v;
;       if (mode == 1) o = (t >= NPADR) ? v : 0.f;
;       if (mode == 2) o = sigmf(v);
;       sT[row * 136 + col] = f2bf(o);
;     });
	v_mul_f32_e32 v58, 0xbfb8aa3b, v9
	v_exp_f32_e32 v58, v58
	s_nop 0
	v_add_f32_e32 v58, 1.0, v58
	v_div_scale_f32 v59, s[28:29], v58, v58, 1.0
	v_rcp_f32_e32 v60, v59
	v_div_scale_f32 v61, vcc, 1.0, v58, 1.0
	v_fma_f32 v62, -v59, v60, 1.0
	v_fmac_f32_e32 v60, v62, v60
	v_mul_f32_e32 v62, v61, v60
	v_fma_f32 v63, -v59, v62, v61
	v_fmac_f32_e32 v62, v63, v60
	v_fma_f32 v59, -v59, v62, v61
	v_div_fmas_f32 v59, v59, v60, v62
	v_div_fixup_f32 v58, v59, v58, 1.0
	v_bfe_u32 v59, v58, 16, 1
	v_add_u32_e32 v55, 0x110, v55
	v_add3_u32 v59, v58, v59, s78
	v_lshl_add_u32 v58, v106, 1, v55
	ds_write_b16_d16_hi v58, v59
	v_add3_u32 v59, s96, v96, 50
	s_and_b64 vcc, exec, s[6:7]
	v_cmp_lt_i32_e64 s[28:29], s76, v59
	v_mul_f32_e32 v59, 0xbfb8aa3b, v10
	v_exp_f32_e32 v59, v59
	s_nop 0
	v_add_f32_e32 v59, 1.0, v59
	v_div_scale_f32 v60, s[30:31], v59, v59, 1.0
	v_rcp_f32_e32 v61, v60
	v_div_scale_f32 v62, vcc, 1.0, v59, 1.0
	v_fma_f32 v63, -v60, v61, 1.0
	v_fmac_f32_e32 v61, v63, v61
	v_mul_f32_e32 v63, v62, v61
	v_fma_f32 v107, -v60, v63, v62
	v_fmac_f32_e32 v63, v107, v61
	v_fma_f32 v60, -v60, v63, v62
	v_div_fmas_f32 v60, v60, v61, v63
	v_div_fixup_f32 v59, v60, v59, 1.0
	v_bfe_u32 v60, v59, 16, 1
	v_add_u32_e32 v55, 0x110, v55
	v_add3_u32 v60, v59, v60, s78
	v_lshl_add_u32 v59, v106, 1, v55
	ds_write_b16_d16_hi v59, v60
	v_add3_u32 v60, s96, v96, 51
	s_and_b64 vcc, exec, s[6:7]
	v_cmp_lt_i32_e64 s[30:31], s76, v60
	v_mul_f32_e32 v60, 0xbfb8aa3b, v11
	v_exp_f32_e32 v60, v60
	s_nop 0
	v_add_f32_e32 v60, 1.0, v60
	v_div_scale_f32 v61, s[34:35], v60, v60, 1.0
	v_rcp_f32_e32 v62, v61
	v_div_scale_f32 v63, vcc, 1.0, v60, 1.0
	v_fma_f32 v107, -v61, v62, 1.0
	v_fmac_f32_e32 v62, v107, v62
	v_mul_f32_e32 v107, v63, v62
	v_fma_f32 v110, -v61, v107, v63
	v_fmac_f32_e32 v107, v110, v62
	v_fma_f32 v61, -v61, v107, v63
	v_div_fmas_f32 v61, v61, v62, v107
	v_div_fixup_f32 v60, v61, v60, 1.0
	v_bfe_u32 v61, v60, 16, 1
	v_add_u32_e32 v55, 0x110, v55
	v_add3_u32 v61, v60, v61, s78
	v_lshl_add_u32 v60, v106, 1, v55
	ds_write_b16_d16_hi v60, v61
	v_add3_u32 v61, s96, v96, 56
	s_and_b64 vcc, exec, s[6:7]
	v_cmp_lt_i32_e64 s[34:35], s76, v61
	v_mul_f32_e32 v61, 0xbfb8aa3b, v12
	v_exp_f32_e32 v61, v61
	s_nop 0
	v_add_f32_e32 v61, 1.0, v61
	v_div_scale_f32 v62, s[36:37], v61, v61, 1.0
	v_rcp_f32_e32 v63, v62
	v_div_scale_f32 v107, vcc, 1.0, v61, 1.0
	v_fma_f32 v110, -v62, v63, 1.0
	v_fmac_f32_e32 v63, v110, v63
	v_mul_f32_e32 v110, v107, v63
	v_fma_f32 v111, -v62, v110, v107
	v_fmac_f32_e32 v110, v111, v63
	v_fma_f32 v62, -v62, v110, v107
	v_div_fmas_f32 v62, v62, v63, v110
	v_div_fixup_f32 v61, v62, v61, 1.0
	v_bfe_u32 v62, v61, 16, 1
	v_add_u32_e32 v55, 0x550, v55
	v_add3_u32 v62, v61, v62, s78
	v_lshl_add_u32 v61, v106, 1, v55
	ds_write_b16_d16_hi v61, v62
	v_add3_u32 v62, s96, v96, 57
	s_and_b64 vcc, exec, s[6:7]
	v_cmp_lt_i32_e64 s[36:37], s76, v62
	v_mul_f32_e32 v62, 0xbfb8aa3b, v13
	v_exp_f32_e32 v62, v62
	s_nop 0
	v_add_f32_e32 v62, 1.0, v62
	v_div_scale_f32 v63, s[38:39], v62, v62, 1.0
	v_rcp_f32_e32 v107, v63
	v_div_scale_f32 v110, vcc, 1.0, v62, 1.0
	v_fma_f32 v111, -v63, v107, 1.0
	v_fmac_f32_e32 v107, v111, v107
	v_mul_f32_e32 v111, v110, v107
	v_fma_f32 v112, -v63, v111, v110
	v_fmac_f32_e32 v111, v112, v107
	v_fma_f32 v63, -v63, v111, v110
	v_div_fmas_f32 v63, v63, v107, v111
	v_div_fixup_f32 v62, v63, v62, 1.0
	v_bfe_u32 v63, v62, 16, 1
	v_add_u32_e32 v55, 0x110, v55
	v_add3_u32 v63, v62, v63, s78
	v_lshl_add_u32 v62, v106, 1, v55
	ds_write_b16_d16_hi v62, v63
	v_add3_u32 v63, s96, v96, 58
	s_and_b64 vcc, exec, s[6:7]
	v_cmp_lt_i32_e64 s[38:39], s76, v63
	v_mul_f32_e32 v63, 0xbfb8aa3b, v14
	v_exp_f32_e32 v63, v63
	s_nop 0
	v_add_f32_e32 v63, 1.0, v63
	v_div_scale_f32 v107, s[40:41], v63, v63, 1.0
	v_rcp_f32_e32 v110, v107
	v_div_scale_f32 v111, vcc, 1.0, v63, 1.0
	v_fma_f32 v112, -v107, v110, 1.0
	v_fmac_f32_e32 v110, v112, v110
	v_mul_f32_e32 v112, v111, v110
	v_fma_f32 v113, -v107, v112, v111
	v_fmac_f32_e32 v112, v113, v110
	v_fma_f32 v107, -v107, v112, v111
	v_div_fmas_f32 v107, v107, v110, v112
	v_div_fixup_f32 v63, v107, v63, 1.0
	v_bfe_u32 v107, v63, 16, 1
	v_add_u32_e32 v55, 0x110, v55
	v_add3_u32 v63, v63, v107, s78
	v_lshl_add_u32 v55, v106, 1, v55
	ds_write_b16_d16_hi v55, v63
	v_add3_u32 v63, s96, v96, 59
	s_and_b64 vcc, exec, s[6:7]
	v_cmp_lt_i32_e64 s[40:41], s76, v63
	v_mul_f32_e32 v63, 0xbfb8aa3b, v15
	v_exp_f32_e32 v63, v63
	s_nop 0
	v_add_f32_e32 v63, 1.0, v63
	v_div_scale_f32 v96, vcc, v63, v63, 1.0
	v_rcp_f32_e32 v106, v96
	v_div_scale_f32 v107, vcc, 1.0, v63, 1.0
	v_fma_f32 v110, -v96, v106, 1.0
	v_fmac_f32_e32 v106, v110, v106
	v_mul_f32_e32 v110, v107, v106
	v_fma_f32 v111, -v96, v110, v107
	v_fmac_f32_e32 v110, v111, v106
	v_fma_f32 v96, -v96, v110, v107
	v_div_fmas_f32 v96, v96, v106, v110
	v_div_fixup_f32 v63, v96, v63, 1.0
	v_bfe_u32 v96, v63, 16, 1
	v_add3_u32 v63, v63, v96, s78
	ds_write_b16_d16_hi v55, v63 offset:272
	s_and_b64 vcc, exec, s[6:7]
	v_mul_f32_e32 v32, 0xbfb8aa3b, v32
	v_exp_f32_e32 v32, v32
	s_nop 0
	v_add_f32_e32 v32, 1.0, v32
	v_div_scale_f32 v63, s[8:9], v32, v32, 1.0
	v_rcp_f32_e32 v96, v63
	v_div_scale_f32 v106, vcc, 1.0, v32, 1.0
	v_fma_f32 v107, -v63, v96, 1.0
	v_fmac_f32_e32 v96, v107, v96
	v_mul_f32_e32 v107, v106, v96
	v_fma_f32 v110, -v63, v107, v106
	v_fmac_f32_e32 v107, v110, v96
	v_fma_f32 v63, -v63, v107, v106
	v_div_fmas_f32 v63, v63, v96, v107
	v_div_fixup_f32 v32, v63, v32, 1.0
	v_bfe_u32 v63, v32, 16, 1
	v_add3_u32 v32, v32, v63, s78
	s_and_b64 vcc, exec, s[6:7]
	ds_write_b16_d16_hi v48, v32 offset:64
	v_mul_f32_e32 v32, 0xbfb8aa3b, v33
	v_exp_f32_e32 v32, v32
	s_nop 0
	v_add_f32_e32 v32, 1.0, v32
; __device__ __forceinline__ float sigmf(float x) { return 1.f / (1.f + __expf(-x)); }
; __device__ __forceinline__ void inproj_epilogue(const Params& p, int layer, int mt, int ntile, int tid,
;                                                 f32x16 (&acc)[2][2], unsigned char* smem) {
;     ...
;     acc_foreach(tid, acc, [&](int row, int col, float v) {
;       int t = m0 + row;
;       float o = v;
;       if (mode == 1) o = (t >= NPADR) ? v : 0.f;
;       if (mode == 2) o = sigmf(v);
;       sT[row * 136 + col] = f2bf(o);
;     });
	v_div_scale_f32 v33, s[8:9], v32, v32, 1.0
	v_rcp_f32_e32 v48, v33
	v_div_scale_f32 v63, vcc, 1.0, v32, 1.0
	v_fma_f32 v96, -v33, v48, 1.0
	v_fmac_f32_e32 v48, v96, v48
	v_mul_f32_e32 v96, v63, v48
	v_fma_f32 v106, -v33, v96, v63
	v_fmac_f32_e32 v96, v106, v48
	v_fma_f32 v33, -v33, v96, v63
	v_div_fmas_f32 v33, v33, v48, v96
	v_div_fixup_f32 v32, v33, v32, 1.0
	v_bfe_u32 v33, v32, 16, 1
	v_add3_u32 v32, v32, v33, s78
	s_and_b64 vcc, exec, s[6:7]
	ds_write_b16_d16_hi v49, v32 offset:64
	v_mul_f32_e32 v32, 0xbfb8aa3b, v34
	v_exp_f32_e32 v32, v32
	s_nop 0
	v_add_f32_e32 v32, 1.0, v32
	v_div_scale_f32 v33, s[8:9], v32, v32, 1.0
	v_rcp_f32_e32 v34, v33
	v_div_scale_f32 v48, vcc, 1.0, v32, 1.0
	v_fma_f32 v49, -v33, v34, 1.0
	v_fmac_f32_e32 v34, v49, v34
	v_mul_f32_e32 v49, v48, v34
	v_fma_f32 v63, -v33, v49, v48
	v_fmac_f32_e32 v49, v63, v34
	v_fma_f32 v33, -v33, v49, v48
	v_div_fmas_f32 v33, v33, v34, v49
	v_div_fixup_f32 v32, v33, v32, 1.0
	v_bfe_u32 v33, v32, 16, 1
	v_add3_u32 v32, v32, v33, s78
	s_and_b64 vcc, exec, s[6:7]
	ds_write_b16_d16_hi v50, v32 offset:64
	v_mul_f32_e32 v32, 0xbfb8aa3b, v35
	v_exp_f32_e32 v32, v32
	s_nop 0
	v_add_f32_e32 v32, 1.0, v32
	v_div_scale_f32 v33, s[8:9], v32, v32, 1.0
	v_rcp_f32_e32 v34, v33
	v_div_scale_f32 v35, vcc, 1.0, v32, 1.0
	v_fma_f32 v48, -v33, v34, 1.0
	v_fmac_f32_e32 v34, v48, v34
	v_mul_f32_e32 v48, v35, v34
	v_fma_f32 v49, -v33, v48, v35
	v_fmac_f32_e32 v48, v49, v34
	v_fma_f32 v33, -v33, v48, v35
	v_div_fmas_f32 v33, v33, v34, v48
	v_div_fixup_f32 v32, v33, v32, 1.0
	v_bfe_u32 v33, v32, 16, 1
	v_add3_u32 v32, v32, v33, s78
	s_and_b64 vcc, exec, s[6:7]
	ds_write_b16_d16_hi v51, v32 offset:64
	v_mul_f32_e32 v32, 0xbfb8aa3b, v36
	v_exp_f32_e32 v32, v32
	s_nop 0
	v_add_f32_e32 v32, 1.0, v32
	v_div_scale_f32 v33, s[8:9], v32, v32, 1.0
	v_rcp_f32_e32 v34, v33
	v_div_scale_f32 v35, vcc, 1.0, v32, 1.0
	v_fma_f32 v36, -v33, v34, 1.0
	v_fmac_f32_e32 v34, v36, v34
	v_mul_f32_e32 v36, v35, v34
	v_fma_f32 v48, -v33, v36, v35
	v_fmac_f32_e32 v36, v48, v34
	v_fma_f32 v33, -v33, v36, v35
	v_div_fmas_f32 v33, v33, v34, v36
	v_div_fixup_f32 v32, v33, v32, 1.0
	v_bfe_u32 v33, v32, 16, 1
	v_add3_u32 v32, v32, v33, s78
	s_and_b64 vcc, exec, s[6:7]
	ds_write_b16_d16_hi v52, v32 offset:64
	v_mul_f32_e32 v32, 0xbfb8aa3b, v37
	v_exp_f32_e32 v32, v32
	s_nop 0
	v_add_f32_e32 v32, 1.0, v32
	v_div_scale_f32 v33, s[8:9], v32, v32, 1.0
	v_rcp_f32_e32 v34, v33
	v_div_scale_f32 v35, vcc, 1.0, v32, 1.0
	v_fma_f32 v36, -v33, v34, 1.0
	v_fmac_f32_e32 v34, v36, v34
	v_mul_f32_e32 v36, v35, v34
	v_fma_f32 v37, -v33, v36, v35
	v_fmac_f32_e32 v36, v37, v34
	v_fma_f32 v33, -v33, v36, v35
	v_div_fmas_f32 v33, v33, v34, v36
	v_div_fixup_f32 v32, v33, v32, 1.0
	v_bfe_u32 v33, v32, 16, 1
	v_add3_u32 v32, v32, v33, s78
	s_and_b64 vcc, exec, s[6:7]
	ds_write_b16_d16_hi v53, v32 offset:64
	v_mul_f32_e32 v32, 0xbfb8aa3b, v38
	v_exp_f32_e32 v32, v32
	s_nop 0
	v_add_f32_e32 v32, 1.0, v32
	v_div_scale_f32 v33, s[8:9], v32, v32, 1.0
	v_rcp_f32_e32 v34, v33
	v_div_scale_f32 v35, vcc, 1.0, v32, 1.0
	v_fma_f32 v36, -v33, v34, 1.0
	v_fmac_f32_e32 v34, v36, v34
	v_mul_f32_e32 v36, v35, v34
	v_fma_f32 v37, -v33, v36, v35
	v_fmac_f32_e32 v36, v37, v34
	v_fma_f32 v33, -v33, v36, v35
	v_div_fmas_f32 v33, v33, v34, v36
	v_div_fixup_f32 v32, v33, v32, 1.0
	v_bfe_u32 v33, v32, 16, 1
	v_add3_u32 v32, v32, v33, s78
	s_and_b64 vcc, exec, s[6:7]
	ds_write_b16_d16_hi v54, v32 offset:64
	v_mul_f32_e32 v32, 0xbfb8aa3b, v39
	v_exp_f32_e32 v32, v32
	s_nop 0
	v_add_f32_e32 v32, 1.0, v32
	v_div_scale_f32 v33, s[8:9], v32, v32, 1.0
	v_rcp_f32_e32 v34, v33
	v_div_scale_f32 v35, vcc, 1.0, v32, 1.0
	v_fma_f32 v36, -v33, v34, 1.0
	v_fmac_f32_e32 v34, v36, v34
	v_mul_f32_e32 v36, v35, v34
	v_fma_f32 v37, -v33, v36, v35
	v_fmac_f32_e32 v36, v37, v34
	v_fma_f32 v33, -v33, v36, v35
	v_div_fmas_f32 v33, v33, v34, v36
	v_div_fixup_f32 v32, v33, v32, 1.0
	v_bfe_u32 v33, v32, 16, 1
	v_add3_u32 v32, v32, v33, s78
	s_and_b64 vcc, exec, s[6:7]
	ds_write_b16_d16_hi v56, v32 offset:64
	v_mul_f32_e32 v32, 0xbfb8aa3b, v40
	v_exp_f32_e32 v32, v32
	s_nop 0
	v_add_f32_e32 v32, 1.0, v32
	v_div_scale_f32 v33, s[8:9], v32, v32, 1.0
	v_rcp_f32_e32 v34, v33
	v_div_scale_f32 v35, vcc, 1.0, v32, 1.0
	v_fma_f32 v36, -v33, v34, 1.0
	v_fmac_f32_e32 v34, v36, v34
	v_mul_f32_e32 v36, v35, v34
; __device__ __forceinline__ float sigmf(float x) { return 1.f / (1.f + __expf(-x)); }
; __device__ __forceinline__ void inproj_epilogue(const Params& p, int layer, int mt, int ntile, int tid,
;                                                 f32x16 (&acc)[2][2], unsigned char* smem) {
;     ...
;     acc_foreach(tid, acc, [&](int row, int col, float v) {
;       int t = m0 + row;
;       float o = v;
;       if (mode == 1) o = (t >= NPADR) ? v : 0.f;
;       if (mode == 2) o = sigmf(v);
;       sT[row * 136 + col] = f2bf(o);
;     });
	v_fma_f32 v37, -v33, v36, v35
	v_fmac_f32_e32 v36, v37, v34
	v_fma_f32 v33, -v33, v36, v35
	v_div_fmas_f32 v33, v33, v34, v36
	v_div_fixup_f32 v32, v33, v32, 1.0
	v_bfe_u32 v33, v32, 16, 1
	v_add3_u32 v32, v32, v33, s78
	s_and_b64 vcc, exec, s[6:7]
	ds_write_b16_d16_hi v57, v32 offset:64
	v_mul_f32_e32 v32, 0xbfb8aa3b, v41
	v_exp_f32_e32 v32, v32
	s_nop 0
	v_add_f32_e32 v32, 1.0, v32
	v_div_scale_f32 v33, s[8:9], v32, v32, 1.0
	v_rcp_f32_e32 v34, v33
	v_div_scale_f32 v35, vcc, 1.0, v32, 1.0
	v_fma_f32 v36, -v33, v34, 1.0
	v_fmac_f32_e32 v34, v36, v34
	v_mul_f32_e32 v36, v35, v34
	v_fma_f32 v37, -v33, v36, v35
	v_fmac_f32_e32 v36, v37, v34
	v_fma_f32 v33, -v33, v36, v35
	v_div_fmas_f32 v33, v33, v34, v36
	v_div_fixup_f32 v32, v33, v32, 1.0
	v_bfe_u32 v33, v32, 16, 1
	v_add3_u32 v32, v32, v33, s78
	s_and_b64 vcc, exec, s[6:7]
	ds_write_b16_d16_hi v58, v32 offset:64
	v_mul_f32_e32 v32, 0xbfb8aa3b, v42
	v_exp_f32_e32 v32, v32
	s_nop 0
	v_add_f32_e32 v32, 1.0, v32
	v_div_scale_f32 v33, s[8:9], v32, v32, 1.0
	v_rcp_f32_e32 v34, v33
	v_div_scale_f32 v35, vcc, 1.0, v32, 1.0
	v_fma_f32 v36, -v33, v34, 1.0
	v_fmac_f32_e32 v34, v36, v34
	v_mul_f32_e32 v36, v35, v34
	v_fma_f32 v37, -v33, v36, v35
	v_fmac_f32_e32 v36, v37, v34
	v_fma_f32 v33, -v33, v36, v35
	v_div_fmas_f32 v33, v33, v34, v36
	v_div_fixup_f32 v32, v33, v32, 1.0
	v_bfe_u32 v33, v32, 16, 1
	v_add3_u32 v32, v32, v33, s78
	s_and_b64 vcc, exec, s[6:7]
	ds_write_b16_d16_hi v59, v32 offset:64
	v_mul_f32_e32 v32, 0xbfb8aa3b, v43
	v_exp_f32_e32 v32, v32
	s_nop 0
	v_add_f32_e32 v32, 1.0, v32
	v_div_scale_f32 v33, s[8:9], v32, v32, 1.0
	v_rcp_f32_e32 v34, v33
	v_div_scale_f32 v35, vcc, 1.0, v32, 1.0
	v_fma_f32 v36, -v33, v34, 1.0
	v_fmac_f32_e32 v34, v36, v34
	v_mul_f32_e32 v36, v35, v34
	v_fma_f32 v37, -v33, v36, v35
	v_fmac_f32_e32 v36, v37, v34
	v_fma_f32 v33, -v33, v36, v35
	v_div_fmas_f32 v33, v33, v34, v36
	v_div_fixup_f32 v32, v33, v32, 1.0
	v_bfe_u32 v33, v32, 16, 1
	v_add3_u32 v32, v32, v33, s78
	s_and_b64 vcc, exec, s[6:7]
	ds_write_b16_d16_hi v60, v32 offset:64
	v_mul_f32_e32 v32, 0xbfb8aa3b, v44
	v_exp_f32_e32 v32, v32
	s_nop 0
	v_add_f32_e32 v32, 1.0, v32
	v_div_scale_f32 v33, s[8:9], v32, v32, 1.0
	v_rcp_f32_e32 v34, v33
	v_div_scale_f32 v35, vcc, 1.0, v32, 1.0
	v_fma_f32 v36, -v33, v34, 1.0
	v_fmac_f32_e32 v34, v36, v34
	v_mul_f32_e32 v36, v35, v34
	v_fma_f32 v37, -v33, v36, v35
	v_fmac_f32_e32 v36, v37, v34
	v_fma_f32 v33, -v33, v36, v35
	v_div_fmas_f32 v33, v33, v34, v36
	v_div_fixup_f32 v32, v33, v32, 1.0
	v_bfe_u32 v33, v32, 16, 1
	v_add3_u32 v32, v32, v33, s78
	s_and_b64 vcc, exec, s[6:7]
	ds_write_b16_d16_hi v61, v32 offset:64
	v_mul_f32_e32 v32, 0xbfb8aa3b, v45
	v_exp_f32_e32 v32, v32
	s_nop 0
	v_add_f32_e32 v32, 1.0, v32
	v_div_scale_f32 v33, s[8:9], v32, v32, 1.0
	v_rcp_f32_e32 v34, v33
	v_div_scale_f32 v35, vcc, 1.0, v32, 1.0
	v_fma_f32 v36, -v33, v34, 1.0
	v_fmac_f32_e32 v34, v36, v34
	v_mul_f32_e32 v36, v35, v34
	v_fma_f32 v37, -v33, v36, v35
	v_fmac_f32_e32 v36, v37, v34
	v_fma_f32 v33, -v33, v36, v35
	v_div_fmas_f32 v33, v33, v34, v36
	v_div_fixup_f32 v32, v33, v32, 1.0
	v_bfe_u32 v33, v32, 16, 1
	v_add3_u32 v32, v32, v33, s78
	s_and_b64 vcc, exec, s[6:7]
	ds_write_b16_d16_hi v62, v32 offset:64
	v_mul_f32_e32 v32, 0xbfb8aa3b, v46
	v_exp_f32_e32 v32, v32
	s_nop 0
	v_add_f32_e32 v32, 1.0, v32
	v_div_scale_f32 v33, s[8:9], v32, v32, 1.0
	v_rcp_f32_e32 v34, v33
	v_div_scale_f32 v35, vcc, 1.0, v32, 1.0
	v_fma_f32 v36, -v33, v34, 1.0
	v_fmac_f32_e32 v34, v36, v34
	v_mul_f32_e32 v36, v35, v34
	v_fma_f32 v37, -v33, v36, v35
	v_fmac_f32_e32 v36, v37, v34
	v_fma_f32 v33, -v33, v36, v35
	v_div_fmas_f32 v33, v33, v34, v36
	v_div_fixup_f32 v32, v33, v32, 1.0
	v_bfe_u32 v33, v32, 16, 1
	v_add3_u32 v32, v32, v33, s78
	s_and_b64 vcc, exec, s[6:7]
	ds_write_b16_d16_hi v55, v32 offset:64
	v_mul_f32_e32 v32, 0xbfb8aa3b, v47
	v_exp_f32_e32 v32, v32
	s_nop 0
	v_add_f32_e32 v32, 1.0, v32
	v_div_scale_f32 v33, s[4:5], v32, v32, 1.0
	v_rcp_f32_e32 v34, v33
	v_div_scale_f32 v35, vcc, 1.0, v32, 1.0
	v_fma_f32 v36, -v33, v34, 1.0
	v_fmac_f32_e32 v34, v36, v34
	v_mul_f32_e32 v36, v35, v34
	v_fma_f32 v37, -v33, v36, v35
	v_fmac_f32_e32 v36, v37, v34
	v_fma_f32 v33, -v33, v36, v35
	v_div_fmas_f32 v33, v33, v34, v36
	v_div_fixup_f32 v32, v33, v32, 1.0
	s_branch .LBB0_1835

; __device__ __forceinline__ float sigmf(float x) { return 1.f / (1.f + __expf(-x)); }
; __device__ __forceinline__ void inproj_epilogue(const Params& p, int layer, int mt, int ntile, int tid,
;                                                 f32x16 (&acc)[2][2], unsigned char* smem) {
;     ...
;     acc_foreach(tid, acc, [&](int row, int col, float v) {
;       int t = m0 + row;
;       float o = v;
;       if (mode == 1) o = (t >= NPADR) ? v : 0.f;
;       if (mode == 2) o = sigmf(v);
;       sT[row * 136 + col] = f2bf(o);
;     });
.LBB0_2037:
	v_bfe_u32 v110, v107, 16, 1
	v_and_b32_e32 v106, 0x5f, v106
	v_add3_u32 v111, v107, v110, s78
	v_mul_lo_u32 v110, v96, s79
	v_lshl_add_u32 v107, v106, 1, v110
	ds_write_b16_d16_hi v107, v111
	v_add3_u32 v111, s84, v96, 1
	v_cmp_lt_i32_e64 s[10:11], s76, v111
	v_cndmask_b32_e64 v111, 0, 1, s[12:13]
	v_cmp_ne_u32_e64 s[6:7], 1, v111
	s_nop 1

; __device__ __forceinline__ float sigmf(float x) { return 1.f / (1.f + __expf(-x)); }
; __device__ __forceinline__ void inproj_epilogue(const Params& p, int layer, int mt, int ntile, int tid,
;                                                 f32x16 (&acc)[2][2], unsigned char* smem) {
;     ...
;     acc_foreach(tid, acc, [&](int row, int col, float v) {
;       int t = m0 + row;
;       float o = v;
;       if (mode == 1) o = (t >= NPADR) ? v : 0.f;
;       if (mode == 2) o = sigmf(v);
;       sT[row * 136 + col] = f2bf(o);
;     });
.LBB0_2040:
	v_bfe_u32 v112, v111, 16, 1
	v_add3_u32 v112, v111, v112, s78
	v_add_u32_e32 v111, 0x110, v110
	v_lshl_add_u32 v110, v106, 1, v111
	ds_write_b16_d16_hi v110, v112
	v_add3_u32 v112, s84, v96, 2
	v_cmp_lt_i32_e64 s[12:13], s76, v112
	s_nop 1

; __device__ __forceinline__ float sigmf(float x) { return 1.f / (1.f + __expf(-x)); }
; __device__ __forceinline__ void inproj_epilogue(const Params& p, int layer, int mt, int ntile, int tid,
;                                                 f32x16 (&acc)[2][2], unsigned char* smem) {
;     ...
;     acc_foreach(tid, acc, [&](int row, int col, float v) {
;       int t = m0 + row;
;       float o = v;
;       if (mode == 1) o = (t >= NPADR) ? v : 0.f;
;       if (mode == 2) o = sigmf(v);
;       sT[row * 136 + col] = f2bf(o);
;     });
.LBB0_2043:
	v_bfe_u32 v113, v112, 16, 1
	v_add3_u32 v113, v112, v113, s78
	v_add_u32_e32 v112, 0x110, v111
	v_lshl_add_u32 v111, v106, 1, v112
	ds_write_b16_d16_hi v111, v113
	v_add3_u32 v113, s84, v96, 3
	v_cmp_lt_i32_e64 s[14:15], s76, v113
	s_nop 1

; __device__ __forceinline__ float sigmf(float x) { return 1.f / (1.f + __expf(-x)); }
; __device__ __forceinline__ void inproj_epilogue(const Params& p, int layer, int mt, int ntile, int tid,
;                                                 f32x16 (&acc)[2][2], unsigned char* smem) {
;     ...
;     acc_foreach(tid, acc, [&](int row, int col, float v) {
;       int t = m0 + row;
;       float o = v;
;       if (mode == 1) o = (t >= NPADR) ? v : 0.f;
;       if (mode == 2) o = sigmf(v);
;       sT[row * 136 + col] = f2bf(o);
;     });
.LBB0_2046:
	v_bfe_u32 v114, v113, 16, 1
	v_add3_u32 v114, v113, v114, s78
	v_add_u32_e32 v113, 0x110, v112
	v_lshl_add_u32 v112, v106, 1, v113
	ds_write_b16_d16_hi v112, v114
	v_add3_u32 v114, s84, v96, 8
	v_cmp_lt_i32_e64 s[16:17], s76, v114
	s_nop 1

; __device__ __forceinline__ float sigmf(float x) { return 1.f / (1.f + __expf(-x)); }
; __device__ __forceinline__ void inproj_epilogue(const Params& p, int layer, int mt, int ntile, int tid,
;                                                 f32x16 (&acc)[2][2], unsigned char* smem) {
;     ...
;     acc_foreach(tid, acc, [&](int row, int col, float v) {
;       int t = m0 + row;
;       float o = v;
;       if (mode == 1) o = (t >= NPADR) ? v : 0.f;
;       if (mode == 2) o = sigmf(v);
;       sT[row * 136 + col] = f2bf(o);
;     });
.LBB0_2049:
	v_bfe_u32 v115, v114, 16, 1
	v_add3_u32 v115, v114, v115, s78
	v_add_u32_e32 v114, 0x550, v113
	v_lshl_add_u32 v113, v106, 1, v114
	ds_write_b16_d16_hi v113, v115
	v_add3_u32 v115, s84, v96, 9
	v_cmp_lt_i32_e64 s[18:19], s76, v115
	s_nop 1

; __device__ __forceinline__ float sigmf(float x) { return 1.f / (1.f + __expf(-x)); }
; __device__ __forceinline__ bf16r f2bf(float f) {
;   unsigned u = __float_as_uint(f);
;   u += 0x7fffu + ((u >> 16) & 1u);
;   return (bf16r)(u >> 16);
; }
; __device__ __forceinline__ void inproj_epilogue(const Params& p, int layer, int mt, int ntile, int tid,
;                                                 f32x16 (&acc)[2][2], unsigned char* smem) {
;     ...
;     acc_foreach(tid, acc, [&](int row, int col, float v) {
;       int t = m0 + row;
;       float o = v;
;       if (mode == 1) o = (t >= NPADR) ? v : 0.f;
;       if (mode == 2) o = sigmf(v);
;       sT[row * 136 + col] = f2bf(o);
;     });
.LBB0_2052:
	v_bfe_u32 v116, v115, 16, 1
	v_add3_u32 v116, v115, v116, s78
	v_add_u32_e32 v115, 0x110, v114
	v_lshl_add_u32 v114, v106, 1, v115
	ds_write_b16_d16_hi v114, v116
	v_add3_u32 v116, s84, v96, 10
	v_cmp_lt_i32_e64 s[20:21], s76, v116
	s_nop 1

; __device__ __forceinline__ float sigmf(float x) { return 1.f / (1.f + __expf(-x)); }
; __device__ __forceinline__ bf16r f2bf(float f) {
;   unsigned u = __float_as_uint(f);
;   u += 0x7fffu + ((u >> 16) & 1u);
;   return (bf16r)(u >> 16);
; }
; __device__ __forceinline__ void inproj_epilogue(const Params& p, int layer, int mt, int ntile, int tid,
;                                                 f32x16 (&acc)[2][2], unsigned char* smem) {
;     ...
;     acc_foreach(tid, acc, [&](int row, int col, float v) {
;       int t = m0 + row;
;       float o = v;
;       if (mode == 1) o = (t >= NPADR) ? v : 0.f;
;       if (mode == 2) o = sigmf(v);
;       sT[row * 136 + col] = f2bf(o);
;     });
.LBB0_2055:
	v_bfe_u32 v117, v116, 16, 1
	v_add3_u32 v117, v116, v117, s78
	v_add_u32_e32 v116, 0x110, v115
	v_lshl_add_u32 v115, v106, 1, v116
	ds_write_b16_d16_hi v115, v117
	v_add3_u32 v117, s84, v96, 11
	v_cmp_lt_i32_e64 s[22:23], s76, v117
	s_nop 1

; __device__ __forceinline__ float sigmf(float x) { return 1.f / (1.f + __expf(-x)); }
; __device__ __forceinline__ bf16r f2bf(float f) {
;   unsigned u = __float_as_uint(f);
;   u += 0x7fffu + ((u >> 16) & 1u);
;   return (bf16r)(u >> 16);
; }
; __device__ __forceinline__ void inproj_epilogue(const Params& p, int layer, int mt, int ntile, int tid,
;                                                 f32x16 (&acc)[2][2], unsigned char* smem) {
;     ...
;     acc_foreach(tid, acc, [&](int row, int col, float v) {
;       int t = m0 + row;
;       float o = v;
;       if (mode == 1) o = (t >= NPADR) ? v : 0.f;
;       if (mode == 2) o = sigmf(v);
;       sT[row * 136 + col] = f2bf(o);
;     });
.LBB0_2058:
	v_bfe_u32 v118, v117, 16, 1
	v_add_u32_e32 v116, 0x110, v116
	v_add3_u32 v118, v117, v118, s78
	v_lshl_add_u32 v117, v106, 1, v116
	ds_write_b16_d16_hi v117, v118
	v_add3_u32 v118, s84, v96, 16
	v_cmp_lt_i32_e64 s[24:25], s76, v118
	s_nop 1

; __device__ __forceinline__ float sigmf(float x) { return 1.f / (1.f + __expf(-x)); }
; __device__ __forceinline__ bf16r f2bf(float f) {
;   unsigned u = __float_as_uint(f);
;   u += 0x7fffu + ((u >> 16) & 1u);
;   return (bf16r)(u >> 16);
; }
; __device__ __forceinline__ void inproj_epilogue(const Params& p, int layer, int mt, int ntile, int tid,
;                                                 f32x16 (&acc)[2][2], unsigned char* smem) {
;     ...
;     acc_foreach(tid, acc, [&](int row, int col, float v) {
;       int t = m0 + row;
;       float o = v;
;       if (mode == 1) o = (t >= NPADR) ? v : 0.f;
;       if (mode == 2) o = sigmf(v);
;       sT[row * 136 + col] = f2bf(o);
;     });
.LBB0_2061:
	v_bfe_u32 v119, v118, 16, 1
	v_add_u32_e32 v116, 0x550, v116
	v_add3_u32 v119, v118, v119, s78
	v_lshl_add_u32 v118, v106, 1, v116
	ds_write_b16_d16_hi v118, v119
	v_add3_u32 v119, s84, v96, 17
	v_cmp_lt_i32_e64 s[26:27], s76, v119
	s_nop 1

; __device__ __forceinline__ float sigmf(float x) { return 1.f / (1.f + __expf(-x)); }
; __device__ __forceinline__ bf16r f2bf(float f) {
;   unsigned u = __float_as_uint(f);
;   u += 0x7fffu + ((u >> 16) & 1u);
;   return (bf16r)(u >> 16);
; }
; __device__ __forceinline__ void inproj_epilogue(const Params& p, int layer, int mt, int ntile, int tid,
;                                                 f32x16 (&acc)[2][2], unsigned char* smem) {
;     ...
;     acc_foreach(tid, acc, [&](int row, int col, float v) {
;       int t = m0 + row;
;       float o = v;
;       if (mode == 1) o = (t >= NPADR) ? v : 0.f;
;       if (mode == 2) o = sigmf(v);
;       sT[row * 136 + col] = f2bf(o);
;     });
.LBB0_2064:
	v_bfe_u32 v120, v119, 16, 1
	v_add_u32_e32 v116, 0x110, v116
	v_add3_u32 v120, v119, v120, s78
	v_lshl_add_u32 v119, v106, 1, v116
	ds_write_b16_d16_hi v119, v120
	v_add3_u32 v120, s84, v96, 18
	v_cmp_lt_i32_e64 s[28:29], s76, v120
	s_nop 1

; __device__ __forceinline__ float sigmf(float x) { return 1.f / (1.f + __expf(-x)); }
; __device__ __forceinline__ bf16r f2bf(float f) {
;   unsigned u = __float_as_uint(f);
;   u += 0x7fffu + ((u >> 16) & 1u);
;   return (bf16r)(u >> 16);
; }
; __device__ __forceinline__ void inproj_epilogue(const Params& p, int layer, int mt, int ntile, int tid,
;                                                 f32x16 (&acc)[2][2], unsigned char* smem) {
;     ...
;     acc_foreach(tid, acc, [&](int row, int col, float v) {
;       int t = m0 + row;
;       float o = v;
;       if (mode == 1) o = (t >= NPADR) ? v : 0.f;
;       if (mode == 2) o = sigmf(v);
;       sT[row * 136 + col] = f2bf(o);
;     });
.LBB0_2067:
	v_bfe_u32 v121, v120, 16, 1
	v_add_u32_e32 v116, 0x110, v116
	v_add3_u32 v121, v120, v121, s78
	v_lshl_add_u32 v120, v106, 1, v116
	ds_write_b16_d16_hi v120, v121
	v_add3_u32 v121, s84, v96, 19
	v_cmp_lt_i32_e64 s[30:31], s76, v121
	s_nop 1

; __device__ __forceinline__ float sigmf(float x) { return 1.f / (1.f + __expf(-x)); }
; __device__ __forceinline__ bf16r f2bf(float f) {
;   unsigned u = __float_as_uint(f);
;   u += 0x7fffu + ((u >> 16) & 1u);
;   return (bf16r)(u >> 16);
; }
; __device__ __forceinline__ void inproj_epilogue(const Params& p, int layer, int mt, int ntile, int tid,
;                                                 f32x16 (&acc)[2][2], unsigned char* smem) {
;     ...
;     acc_foreach(tid, acc, [&](int row, int col, float v) {
;       int t = m0 + row;
;       float o = v;
;       if (mode == 1) o = (t >= NPADR) ? v : 0.f;
;       if (mode == 2) o = sigmf(v);
;       sT[row * 136 + col] = f2bf(o);
;     });
.LBB0_2070:
	v_bfe_u32 v122, v121, 16, 1
	v_add_u32_e32 v116, 0x110, v116
	v_add3_u32 v122, v121, v122, s78
	v_lshl_add_u32 v121, v106, 1, v116
	ds_write_b16_d16_hi v121, v122
	v_add3_u32 v122, s84, v96, 24
	v_cmp_lt_i32_e64 s[34:35], s76, v122
	s_nop 1

; __device__ __forceinline__ float sigmf(float x) { return 1.f / (1.f + __expf(-x)); }
; __device__ __forceinline__ bf16r f2bf(float f) {
;   unsigned u = __float_as_uint(f);
;   u += 0x7fffu + ((u >> 16) & 1u);
;   return (bf16r)(u >> 16);
; }
; __device__ __forceinline__ void inproj_epilogue(const Params& p, int layer, int mt, int ntile, int tid,
;                                                 f32x16 (&acc)[2][2], unsigned char* smem) {
;     ...
;     acc_foreach(tid, acc, [&](int row, int col, float v) {
;       int t = m0 + row;
;       float o = v;
;       if (mode == 1) o = (t >= NPADR) ? v : 0.f;
;       if (mode == 2) o = sigmf(v);
;       sT[row * 136 + col] = f2bf(o);
;     });
.LBB0_2073:
	v_bfe_u32 v123, v122, 16, 1
	v_add_u32_e32 v116, 0x550, v116
	v_add3_u32 v123, v122, v123, s78
	v_lshl_add_u32 v122, v106, 1, v116
	ds_write_b16_d16_hi v122, v123
	v_add3_u32 v123, s84, v96, 25
	v_cmp_lt_i32_e64 s[36:37], s76, v123
	s_nop 1

; __device__ __forceinline__ float sigmf(float x) { return 1.f / (1.f + __expf(-x)); }
; __device__ __forceinline__ bf16r f2bf(float f) {
;   unsigned u = __float_as_uint(f);
;   u += 0x7fffu + ((u >> 16) & 1u);
;   return (bf16r)(u >> 16);
; }
; __device__ __forceinline__ void inproj_epilogue(const Params& p, int layer, int mt, int ntile, int tid,
;                                                 f32x16 (&acc)[2][2], unsigned char* smem) {
;     ...
;     acc_foreach(tid, acc, [&](int row, int col, float v) {
;       int t = m0 + row;
;       float o = v;
;       if (mode == 1) o = (t >= NPADR) ? v : 0.f;
;       if (mode == 2) o = sigmf(v);
;       sT[row * 136 + col] = f2bf(o);
;     });
.LBB0_2076:
	v_bfe_u32 v124, v123, 16, 1
	v_add_u32_e32 v116, 0x110, v116
	v_add3_u32 v124, v123, v124, s78
	v_lshl_add_u32 v123, v106, 1, v116
	ds_write_b16_d16_hi v123, v124
	v_add3_u32 v124, s84, v96, 26
	v_cmp_lt_i32_e64 s[38:39], s76, v124
	s_nop 1

; __device__ __forceinline__ float sigmf(float x) { return 1.f / (1.f + __expf(-x)); }
; __device__ __forceinline__ bf16r f2bf(float f) {
;   unsigned u = __float_as_uint(f);
;   u += 0x7fffu + ((u >> 16) & 1u);
;   return (bf16r)(u >> 16);
; }
; __device__ __forceinline__ void inproj_epilogue(const Params& p, int layer, int mt, int ntile, int tid,
;                                                 f32x16 (&acc)[2][2], unsigned char* smem) {
;     ...
;     acc_foreach(tid, acc, [&](int row, int col, float v) {
;       int t = m0 + row;
;       float o = v;
;       if (mode == 1) o = (t >= NPADR) ? v : 0.f;
;       if (mode == 2) o = sigmf(v);
;       sT[row * 136 + col] = f2bf(o);
;     });
.LBB0_2079:
	v_bfe_u32 v125, v124, 16, 1
	v_add_u32_e32 v116, 0x110, v116
	v_add3_u32 v124, v124, v125, s78
	v_lshl_add_u32 v116, v106, 1, v116
	ds_write_b16_d16_hi v116, v124
	v_add3_u32 v124, s84, v96, 27
	v_cmp_lt_i32_e64 s[40:41], s76, v124
	s_nop 1

; __device__ __forceinline__ float sigmf(float x) { return 1.f / (1.f + __expf(-x)); }
; __device__ __forceinline__ bf16r f2bf(float f) {
;   unsigned u = __float_as_uint(f);
;   u += 0x7fffu + ((u >> 16) & 1u);
;   return (bf16r)(u >> 16);
; }
; __device__ __forceinline__ void inproj_epilogue(const Params& p, int layer, int mt, int ntile, int tid,
;                                                 f32x16 (&acc)[2][2], unsigned char* smem) {
;     ...
;     acc_foreach(tid, acc, [&](int row, int col, float v) {
;       int t = m0 + row;
;       float o = v;
;       if (mode == 1) o = (t >= NPADR) ? v : 0.f;
;       if (mode == 2) o = sigmf(v);
;       sT[row * 136 + col] = f2bf(o);
;     });
.LBB0_2130:
	v_bfe_u32 v50, v48, 16, 1
	v_add_u32_e32 v49, 0x110, v116
	v_add3_u32 v48, v48, v50, s78
	ds_write_b16_d16_hi v49, v48 offset:64
	v_or_b32_e32 v48, 32, v96
	v_add_u32_e32 v49, s84, v48
	v_cmp_lt_i32_e64 s[8:9], s76, v49
	s_nop 1

; __device__ __forceinline__ float sigmf(float x) { return 1.f / (1.f + __expf(-x)); }
; __device__ __forceinline__ bf16r f2bf(float f) {
;   unsigned u = __float_as_uint(f);
;   u += 0x7fffu + ((u >> 16) & 1u);
;   return (bf16r)(u >> 16);
; }
; __device__ __forceinline__ void inproj_epilogue(const Params& p, int layer, int mt, int ntile, int tid,
;                                                 f32x16 (&acc)[2][2], unsigned char* smem) {
;     ...
;     acc_foreach(tid, acc, [&](int row, int col, float v) {
;       int t = m0 + row;
;       float o = v;
;       if (mode == 1) o = (t >= NPADR) ? v : 0.f;
;       if (mode == 2) o = sigmf(v);
;       sT[row * 136 + col] = f2bf(o);
;     });
.LBB0_2133:
	v_bfe_u32 v50, v49, 16, 1
	v_add3_u32 v50, v49, v50, s78
	v_mul_lo_u32 v49, v48, s79
	v_lshl_add_u32 v48, v106, 1, v49
	ds_write_b16_d16_hi v48, v50
	v_add3_u32 v50, s84, v96, 33
	v_cmp_lt_i32_e64 s[10:11], s76, v50
	s_nop 1

; __device__ __forceinline__ float sigmf(float x) { return 1.f / (1.f + __expf(-x)); }
; __device__ __forceinline__ bf16r f2bf(float f) {
;   unsigned u = __float_as_uint(f);
;   u += 0x7fffu + ((u >> 16) & 1u);
;   return (bf16r)(u >> 16);
; }
; __device__ __forceinline__ void inproj_epilogue(const Params& p, int layer, int mt, int ntile, int tid,
;                                                 f32x16 (&acc)[2][2], unsigned char* smem) {
;     ...
;     acc_foreach(tid, acc, [&](int row, int col, float v) {
;       int t = m0 + row;
;       float o = v;
;       if (mode == 1) o = (t >= NPADR) ? v : 0.f;
;       if (mode == 2) o = sigmf(v);
;       sT[row * 136 + col] = f2bf(o);
;     });
.LBB0_2136:
	v_bfe_u32 v51, v50, 16, 1
	v_add3_u32 v51, v50, v51, s78
	v_add_u32_e32 v50, 0x110, v49
	v_lshl_add_u32 v49, v106, 1, v50
	ds_write_b16_d16_hi v49, v51
	v_add3_u32 v51, s84, v96, 34
	v_cmp_lt_i32_e64 s[12:13], s76, v51
	s_nop 1

; __device__ __forceinline__ float sigmf(float x) { return 1.f / (1.f + __expf(-x)); }
; __device__ __forceinline__ bf16r f2bf(float f) {
;   unsigned u = __float_as_uint(f);
;   u += 0x7fffu + ((u >> 16) & 1u);
;   return (bf16r)(u >> 16);
; }
; __device__ __forceinline__ void inproj_epilogue(const Params& p, int layer, int mt, int ntile, int tid,
;                                                 f32x16 (&acc)[2][2], unsigned char* smem) {
;     ...
;     acc_foreach(tid, acc, [&](int row, int col, float v) {
;       int t = m0 + row;
;       float o = v;
;       if (mode == 1) o = (t >= NPADR) ? v : 0.f;
;       if (mode == 2) o = sigmf(v);
;       sT[row * 136 + col] = f2bf(o);
;     });
.LBB0_2139:
	v_bfe_u32 v52, v51, 16, 1
	v_add3_u32 v52, v51, v52, s78
	v_add_u32_e32 v51, 0x110, v50
	v_lshl_add_u32 v50, v106, 1, v51
	ds_write_b16_d16_hi v50, v52
	v_add3_u32 v52, s84, v96, 35
	v_cmp_lt_i32_e64 s[14:15], s76, v52
	s_nop 1

; __device__ __forceinline__ float sigmf(float x) { return 1.f / (1.f + __expf(-x)); }
; __device__ __forceinline__ bf16r f2bf(float f) {
;   unsigned u = __float_as_uint(f);
;   u += 0x7fffu + ((u >> 16) & 1u);
;   return (bf16r)(u >> 16);
; }
; __device__ __forceinline__ void inproj_epilogue(const Params& p, int layer, int mt, int ntile, int tid,
;                                                 f32x16 (&acc)[2][2], unsigned char* smem) {
;     ...
;     acc_foreach(tid, acc, [&](int row, int col, float v) {
;       int t = m0 + row;
;       float o = v;
;       if (mode == 1) o = (t >= NPADR) ? v : 0.f;
;       if (mode == 2) o = sigmf(v);
;       sT[row * 136 + col] = f2bf(o);
;     });
.LBB0_2142:
	v_bfe_u32 v53, v52, 16, 1
	v_add3_u32 v53, v52, v53, s78
	v_add_u32_e32 v52, 0x110, v51
	v_lshl_add_u32 v51, v106, 1, v52
	ds_write_b16_d16_hi v51, v53
	v_add3_u32 v53, s84, v96, 40
	v_cmp_lt_i32_e64 s[16:17], s76, v53
	s_nop 1

; __device__ __forceinline__ float sigmf(float x) { return 1.f / (1.f + __expf(-x)); }
; __device__ __forceinline__ bf16r f2bf(float f) {
;   unsigned u = __float_as_uint(f);
;   u += 0x7fffu + ((u >> 16) & 1u);
;   return (bf16r)(u >> 16);
; }
; __device__ __forceinline__ void inproj_epilogue(const Params& p, int layer, int mt, int ntile, int tid,
;                                                 f32x16 (&acc)[2][2], unsigned char* smem) {
;     ...
;     acc_foreach(tid, acc, [&](int row, int col, float v) {
;       int t = m0 + row;
;       float o = v;
;       if (mode == 1) o = (t >= NPADR) ? v : 0.f;
;       if (mode == 2) o = sigmf(v);
;       sT[row * 136 + col] = f2bf(o);
;     });
.LBB0_2145:
	v_bfe_u32 v54, v53, 16, 1
	v_add3_u32 v54, v53, v54, s78
	v_add_u32_e32 v53, 0x550, v52
	v_lshl_add_u32 v52, v106, 1, v53
	ds_write_b16_d16_hi v52, v54
	v_add3_u32 v54, s84, v96, 41
	v_cmp_lt_i32_e64 s[18:19], s76, v54
	s_nop 1

; __device__ __forceinline__ float sigmf(float x) { return 1.f / (1.f + __expf(-x)); }
; __device__ __forceinline__ bf16r f2bf(float f) {
;   unsigned u = __float_as_uint(f);
;   u += 0x7fffu + ((u >> 16) & 1u);
;   return (bf16r)(u >> 16);
; }
; __device__ __forceinline__ void inproj_epilogue(const Params& p, int layer, int mt, int ntile, int tid,
;                                                 f32x16 (&acc)[2][2], unsigned char* smem) {
;     ...
;     acc_foreach(tid, acc, [&](int row, int col, float v) {
;       int t = m0 + row;
;       float o = v;
;       if (mode == 1) o = (t >= NPADR) ? v : 0.f;
;       if (mode == 2) o = sigmf(v);
;       sT[row * 136 + col] = f2bf(o);
;     });
.LBB0_2148:
	v_bfe_u32 v55, v54, 16, 1
	v_add3_u32 v55, v54, v55, s78
	v_add_u32_e32 v54, 0x110, v53
	v_lshl_add_u32 v53, v106, 1, v54
	ds_write_b16_d16_hi v53, v55
	v_add3_u32 v55, s84, v96, 42
	v_cmp_lt_i32_e64 s[20:21], s76, v55
	s_nop 1

; __device__ __forceinline__ float sigmf(float x) { return 1.f / (1.f + __expf(-x)); }
; __device__ __forceinline__ bf16r f2bf(float f) {
;   unsigned u = __float_as_uint(f);
;   u += 0x7fffu + ((u >> 16) & 1u);
;   return (bf16r)(u >> 16);
; }
; __device__ __forceinline__ void inproj_epilogue(const Params& p, int layer, int mt, int ntile, int tid,
;                                                 f32x16 (&acc)[2][2], unsigned char* smem) {
;     ...
;     acc_foreach(tid, acc, [&](int row, int col, float v) {
;       int t = m0 + row;
;       float o = v;
;       if (mode == 1) o = (t >= NPADR) ? v : 0.f;
;       if (mode == 2) o = sigmf(v);
;       sT[row * 136 + col] = f2bf(o);
;     });
.LBB0_2151:
	v_bfe_u32 v56, v55, 16, 1
	v_add3_u32 v56, v55, v56, s78
	v_add_u32_e32 v55, 0x110, v54
	v_lshl_add_u32 v54, v106, 1, v55
	ds_write_b16_d16_hi v54, v56
	v_add3_u32 v56, s84, v96, 43
	v_cmp_lt_i32_e64 s[22:23], s76, v56
	s_nop 1

; __device__ __forceinline__ float sigmf(float x) { return 1.f / (1.f + __expf(-x)); }
; __device__ __forceinline__ bf16r f2bf(float f) {
;   unsigned u = __float_as_uint(f);
;   u += 0x7fffu + ((u >> 16) & 1u);
;   return (bf16r)(u >> 16);
; }
; __device__ __forceinline__ void inproj_epilogue(const Params& p, int layer, int mt, int ntile, int tid,
;                                                 f32x16 (&acc)[2][2], unsigned char* smem) {
;     ...
;     acc_foreach(tid, acc, [&](int row, int col, float v) {
;       int t = m0 + row;
;       float o = v;
;       if (mode == 1) o = (t >= NPADR) ? v : 0.f;
;       if (mode == 2) o = sigmf(v);
;       sT[row * 136 + col] = f2bf(o);
;     });
.LBB0_2154:
	v_bfe_u32 v57, v56, 16, 1
	v_add_u32_e32 v55, 0x110, v55
	v_add3_u32 v57, v56, v57, s78
	v_lshl_add_u32 v56, v106, 1, v55
	ds_write_b16_d16_hi v56, v57
	v_add3_u32 v57, s84, v96, 48
	v_cmp_lt_i32_e64 s[24:25], s76, v57
	s_nop 1

; __device__ __forceinline__ float sigmf(float x) { return 1.f / (1.f + __expf(-x)); }
; __device__ __forceinline__ bf16r f2bf(float f) {
;   unsigned u = __float_as_uint(f);
;   u += 0x7fffu + ((u >> 16) & 1u);
;   return (bf16r)(u >> 16);
; }
; __device__ __forceinline__ void inproj_epilogue(const Params& p, int layer, int mt, int ntile, int tid,
;                                                 f32x16 (&acc)[2][2], unsigned char* smem) {
;     ...
;     acc_foreach(tid, acc, [&](int row, int col, float v) {
;       int t = m0 + row;
;       float o = v;
;       if (mode == 1) o = (t >= NPADR) ? v : 0.f;
;       if (mode == 2) o = sigmf(v);
;       sT[row * 136 + col] = f2bf(o);
;     });
.LBB0_2157:
	v_bfe_u32 v58, v57, 16, 1
	v_add_u32_e32 v55, 0x550, v55
	v_add3_u32 v58, v57, v58, s78
	v_lshl_add_u32 v57, v106, 1, v55
	ds_write_b16_d16_hi v57, v58
	v_add3_u32 v58, s84, v96, 49
	v_cmp_lt_i32_e64 s[26:27], s76, v58
	s_nop 1

; __device__ __forceinline__ float sigmf(float x) { return 1.f / (1.f + __expf(-x)); }
; __device__ __forceinline__ bf16r f2bf(float f) {
;   unsigned u = __float_as_uint(f);
;   u += 0x7fffu + ((u >> 16) & 1u);
;   return (bf16r)(u >> 16);
; }
; __device__ __forceinline__ void inproj_epilogue(const Params& p, int layer, int mt, int ntile, int tid,
;                                                 f32x16 (&acc)[2][2], unsigned char* smem) {
;     ...
;     acc_foreach(tid, acc, [&](int row, int col, float v) {
;       int t = m0 + row;
;       float o = v;
;       if (mode == 1) o = (t >= NPADR) ? v : 0.f;
;       if (mode == 2) o = sigmf(v);
;       sT[row * 136 + col] = f2bf(o);
;     });
.LBB0_2160:
	v_bfe_u32 v59, v58, 16, 1
	v_add_u32_e32 v55, 0x110, v55
	v_add3_u32 v59, v58, v59, s78
	v_lshl_add_u32 v58, v106, 1, v55
	ds_write_b16_d16_hi v58, v59
	v_add3_u32 v59, s84, v96, 50
	v_cmp_lt_i32_e64 s[28:29], s76, v59
	s_nop 1

; __device__ __forceinline__ float sigmf(float x) { return 1.f / (1.f + __expf(-x)); }
; __device__ __forceinline__ bf16r f2bf(float f) {
;   unsigned u = __float_as_uint(f);
;   u += 0x7fffu + ((u >> 16) & 1u);
;   return (bf16r)(u >> 16);
; }
; __device__ __forceinline__ void inproj_epilogue(const Params& p, int layer, int mt, int ntile, int tid,
;                                                 f32x16 (&acc)[2][2], unsigned char* smem) {
;     ...
;     acc_foreach(tid, acc, [&](int row, int col, float v) {
;       int t = m0 + row;
;       float o = v;
;       if (mode == 1) o = (t >= NPADR) ? v : 0.f;
;       if (mode == 2) o = sigmf(v);
;       sT[row * 136 + col] = f2bf(o);
;     });
.LBB0_2163:
	v_bfe_u32 v60, v59, 16, 1
	v_add_u32_e32 v55, 0x110, v55
	v_add3_u32 v60, v59, v60, s78
	v_lshl_add_u32 v59, v106, 1, v55
	ds_write_b16_d16_hi v59, v60
	v_add3_u32 v60, s84, v96, 51
	v_cmp_lt_i32_e64 s[30:31], s76, v60
	s_nop 1

; __device__ __forceinline__ float sigmf(float x) { return 1.f / (1.f + __expf(-x)); }
; __device__ __forceinline__ bf16r f2bf(float f) {
;   unsigned u = __float_as_uint(f);
;   u += 0x7fffu + ((u >> 16) & 1u);
;   return (bf16r)(u >> 16);
; }
; __device__ __forceinline__ void inproj_epilogue(const Params& p, int layer, int mt, int ntile, int tid,
;                                                 f32x16 (&acc)[2][2], unsigned char* smem) {
;     ...
;     acc_foreach(tid, acc, [&](int row, int col, float v) {
;       int t = m0 + row;
;       float o = v;
;       if (mode == 1) o = (t >= NPADR) ? v : 0.f;
;       if (mode == 2) o = sigmf(v);
;       sT[row * 136 + col] = f2bf(o);
;     });
.LBB0_2166:
	v_bfe_u32 v61, v60, 16, 1
	v_add_u32_e32 v55, 0x110, v55
	v_add3_u32 v61, v60, v61, s78
	v_lshl_add_u32 v60, v106, 1, v55
	ds_write_b16_d16_hi v60, v61
	v_add3_u32 v61, s84, v96, 56
	v_cmp_lt_i32_e64 s[34:35], s76, v61
	s_nop 1

; __device__ __forceinline__ float sigmf(float x) { return 1.f / (1.f + __expf(-x)); }
; __device__ __forceinline__ bf16r f2bf(float f) {
;   unsigned u = __float_as_uint(f);
;   u += 0x7fffu + ((u >> 16) & 1u);
;   return (bf16r)(u >> 16);
; }
; __device__ __forceinline__ void inproj_epilogue(const Params& p, int layer, int mt, int ntile, int tid,
;                                                 f32x16 (&acc)[2][2], unsigned char* smem) {
;     ...
;     acc_foreach(tid, acc, [&](int row, int col, float v) {
;       int t = m0 + row;
;       float o = v;
;       if (mode == 1) o = (t >= NPADR) ? v : 0.f;
;       if (mode == 2) o = sigmf(v);
;       sT[row * 136 + col] = f2bf(o);
;     });
.LBB0_2169:
	v_bfe_u32 v62, v61, 16, 1
	v_add_u32_e32 v55, 0x550, v55
	v_add3_u32 v62, v61, v62, s78
	v_lshl_add_u32 v61, v106, 1, v55
	ds_write_b16_d16_hi v61, v62
	v_add3_u32 v62, s84, v96, 57
	v_cmp_lt_i32_e64 s[36:37], s76, v62
	s_nop 1

; __device__ __forceinline__ float sigmf(float x) { return 1.f / (1.f + __expf(-x)); }
; __device__ __forceinline__ bf16r f2bf(float f) {
;   unsigned u = __float_as_uint(f);
;   u += 0x7fffu + ((u >> 16) & 1u);
;   return (bf16r)(u >> 16);
; }
; __device__ __forceinline__ void inproj_epilogue(const Params& p, int layer, int mt, int ntile, int tid,
;                                                 f32x16 (&acc)[2][2], unsigned char* smem) {
;     ...
;     acc_foreach(tid, acc, [&](int row, int col, float v) {
;       int t = m0 + row;
;       float o = v;
;       if (mode == 1) o = (t >= NPADR) ? v : 0.f;
;       if (mode == 2) o = sigmf(v);
;       sT[row * 136 + col] = f2bf(o);
;     });
.LBB0_2172:
	v_bfe_u32 v63, v62, 16, 1
	v_add_u32_e32 v55, 0x110, v55
	v_add3_u32 v63, v62, v63, s78
	v_lshl_add_u32 v62, v106, 1, v55
	ds_write_b16_d16_hi v62, v63
	v_add3_u32 v63, s84, v96, 58
	v_cmp_lt_i32_e64 s[38:39], s76, v63
	s_nop 1

; __device__ __forceinline__ float sigmf(float x) { return 1.f / (1.f + __expf(-x)); }
; __device__ __forceinline__ bf16r f2bf(float f) {
;   unsigned u = __float_as_uint(f);
;   u += 0x7fffu + ((u >> 16) & 1u);
;   return (bf16r)(u >> 16);
; }
; __device__ __forceinline__ void inproj_epilogue(const Params& p, int layer, int mt, int ntile, int tid,
;                                                 f32x16 (&acc)[2][2], unsigned char* smem) {
;     ...
;     acc_foreach(tid, acc, [&](int row, int col, float v) {
;       int t = m0 + row;
;       float o = v;
;       if (mode == 1) o = (t >= NPADR) ? v : 0.f;
;       if (mode == 2) o = sigmf(v);
;       sT[row * 136 + col] = f2bf(o);
;     });
.LBB0_2175:
	v_bfe_u32 v107, v63, 16, 1
	v_add_u32_e32 v55, 0x110, v55
	v_add3_u32 v63, v63, v107, s78
	v_lshl_add_u32 v55, v106, 1, v55
	ds_write_b16_d16_hi v55, v63
	v_add3_u32 v63, s84, v96, 59
	v_cmp_lt_i32_e64 s[40:41], s76, v63
	s_nop 1

; __device__ __forceinline__ bf16r f2bf(float f) {
;   unsigned u = __float_as_uint(f);
;   u += 0x7fffu + ((u >> 16) & 1u);
;   return (bf16r)(u >> 16);
; }
; __device__ __forceinline__ unsigned pack2(float a, float b) { return (unsigned)f2bf(a) | ((unsigned)f2bf(b) << 16); }
; __device__ __forceinline__ float lo16(unsigned v) { return __uint_as_float(v << 16); }
; __device__ __forceinline__ float hi16(unsigned v) { return __uint_as_float(v & 0xffff0000u); }
; __device__ __forceinline__ float siluf(float x) { return x / (1.f + __expf(-x)); }
; __device__ __forceinline__ float sigmf(float x) { return 1.f / (1.f + __expf(-x)); }
; __device__ __forceinline__ void inproj_epilogue(const Params& p, int layer, int mt, int ntile, int tid,
;                                                 f32x16 (&acc)[2][2], unsigned char* smem) {
;     ...
;     acc_foreach(tid, acc, [&](int row, int col, float v) {
;       int t = m0 + row;
;       float o = v;
;       if (mode == 1) o = (t >= NPADR) ? v : 0.f;
;       if (mode == 2) o = sigmf(v);
;       sT[row * 136 + col] = f2bf(o);
;     });
.Lgv_4:
	v_mul_f32_e32 v107, 0xbfb8aa3b, v16
	v_exp_f32_e32 v107, v107
	s_nop 0
	v_add_f32_e32 v107, 1.0, v107
	v_div_scale_f32 v110, s[6:7], v107, v107, 1.0
	v_rcp_f32_e32 v111, v110
	v_div_scale_f32 v112, vcc, 1.0, v107, 1.0
	v_fma_f32 v113, -v110, v111, 1.0
	v_fmac_f32_e32 v111, v113, v111
	v_mul_f32_e32 v113, v112, v111
	v_fma_f32 v114, -v110, v113, v112
	v_fmac_f32_e32 v113, v114, v111
	v_fma_f32 v110, -v110, v113, v112
	v_div_fmas_f32 v110, v110, v111, v113
	v_div_fixup_f32 v107, v110, v107, 1.0
	v_bfe_u32 v110, v107, 16, 1
	v_and_b32_e32 v106, 0x5f, v106
	v_add3_u32 v111, v107, v110, s78
	v_mul_lo_u32 v110, v96, s79
	v_lshl_add_u32 v107, v106, 1, v110
	ds_write_b16_d16_hi v107, v111
	v_add3_u32 v111, s84, v96, 1
	v_cmp_lt_i32_e64 s[10:11], s76, v111
	v_cndmask_b32_e64 v111, 0, 1, s[12:13]
	v_cmp_ne_u32_e64 s[6:7], 1, v111
	s_andn2_b64 vcc, exec, s[12:13]
	v_mul_f32_e32 v111, 0xbfb8aa3b, v17
	v_exp_f32_e32 v111, v111
	s_nop 0
	v_add_f32_e32 v111, 1.0, v111
	v_div_scale_f32 v112, s[12:13], v111, v111, 1.0
	v_rcp_f32_e32 v113, v112
	v_div_scale_f32 v114, vcc, 1.0, v111, 1.0
	v_fma_f32 v115, -v112, v113, 1.0
	v_fmac_f32_e32 v113, v115, v113
	v_mul_f32_e32 v115, v114, v113
	v_fma_f32 v116, -v112, v115, v114
	v_fmac_f32_e32 v115, v116, v113
	v_fma_f32 v112, -v112, v115, v114
	v_div_fmas_f32 v112, v112, v113, v115
	v_div_fixup_f32 v111, v112, v111, 1.0
	v_bfe_u32 v112, v111, 16, 1
	v_add3_u32 v112, v111, v112, s78
	v_add_u32_e32 v111, 0x110, v110
	v_lshl_add_u32 v110, v106, 1, v111
	ds_write_b16_d16_hi v110, v112
	v_add3_u32 v112, s84, v96, 2
	s_and_b64 vcc, exec, s[6:7]
	v_cmp_lt_i32_e64 s[12:13], s76, v112
	v_mul_f32_e32 v112, 0xbfb8aa3b, v18
	v_exp_f32_e32 v112, v112
	s_nop 0
	v_add_f32_e32 v112, 1.0, v112
	v_div_scale_f32 v113, s[14:15], v112, v112, 1.0
	v_rcp_f32_e32 v114, v113
	v_div_scale_f32 v115, vcc, 1.0, v112, 1.0
	v_fma_f32 v116, -v113, v114, 1.0
	v_fmac_f32_e32 v114, v116, v114
	v_mul_f32_e32 v116, v115, v114
	v_fma_f32 v117, -v113, v116, v115
	v_fmac_f32_e32 v116, v117, v114
	v_fma_f32 v113, -v113, v116, v115
	v_div_fmas_f32 v113, v113, v114, v116
	v_div_fixup_f32 v112, v113, v112, 1.0
	v_bfe_u32 v113, v112, 16, 1
	v_add3_u32 v113, v112, v113, s78
	v_add_u32_e32 v112, 0x110, v111
	v_lshl_add_u32 v111, v106, 1, v112
	ds_write_b16_d16_hi v111, v113
	v_add3_u32 v113, s84, v96, 3
	s_and_b64 vcc, exec, s[6:7]
	v_cmp_lt_i32_e64 s[14:15], s76, v113
	v_mul_f32_e32 v113, 0xbfb8aa3b, v19
	v_exp_f32_e32 v113, v113
	s_nop 0
	v_add_f32_e32 v113, 1.0, v113
	v_div_scale_f32 v114, s[16:17], v113, v113, 1.0
	v_rcp_f32_e32 v115, v114
	v_div_scale_f32 v116, vcc, 1.0, v113, 1.0
	v_fma_f32 v117, -v114, v115, 1.0
	v_fmac_f32_e32 v115, v117, v115
	v_mul_f32_e32 v117, v116, v115
	v_fma_f32 v118, -v114, v117, v116
	v_fmac_f32_e32 v117, v118, v115
	v_fma_f32 v114, -v114, v117, v116
	v_div_fmas_f32 v114, v114, v115, v117
	v_div_fixup_f32 v113, v114, v113, 1.0
	v_bfe_u32 v114, v113, 16, 1
	v_add3_u32 v114, v113, v114, s78
	v_add_u32_e32 v113, 0x110, v112
	v_lshl_add_u32 v112, v106, 1, v113
	ds_write_b16_d16_hi v112, v114
	v_add3_u32 v114, s84, v96, 8
	s_and_b64 vcc, exec, s[6:7]
	v_cmp_lt_i32_e64 s[16:17], s76, v114
	v_mul_f32_e32 v114, 0xbfb8aa3b, v20
	v_exp_f32_e32 v114, v114
	s_nop 0
	v_add_f32_e32 v114, 1.0, v114
	v_div_scale_f32 v115, s[18:19], v114, v114, 1.0
	v_rcp_f32_e32 v116, v115
	v_div_scale_f32 v117, vcc, 1.0, v114, 1.0
	v_fma_f32 v118, -v115, v116, 1.0
	v_fmac_f32_e32 v116, v118, v116
	v_mul_f32_e32 v118, v117, v116
	v_fma_f32 v119, -v115, v118, v117
	v_fmac_f32_e32 v118, v119, v116
	v_fma_f32 v115, -v115, v118, v117
	v_div_fmas_f32 v115, v115, v116, v118
	v_div_fixup_f32 v114, v115, v114, 1.0
	v_bfe_u32 v115, v114, 16, 1
	v_add3_u32 v115, v114, v115, s78
	v_add_u32_e32 v114, 0x550, v113
	v_lshl_add_u32 v113, v106, 1, v114
	ds_write_b16_d16_hi v113, v115
	v_add3_u32 v115, s84, v96, 9
	s_and_b64 vcc, exec, s[6:7]
	v_cmp_lt_i32_e64 s[18:19], s76, v115
	v_mul_f32_e32 v115, 0xbfb8aa3b, v21
	v_exp_f32_e32 v115, v115
	s_nop 0
	v_add_f32_e32 v115, 1.0, v115
	v_div_scale_f32 v116, s[20:21], v115, v115, 1.0
	v_rcp_f32_e32 v117, v116
	v_div_scale_f32 v118, vcc, 1.0, v115, 1.0
	v_fma_f32 v119, -v116, v117, 1.0
	v_fmac_f32_e32 v117, v119, v117
	v_mul_f32_e32 v119, v118, v117
	v_fma_f32 v120, -v116, v119, v118
	v_fmac_f32_e32 v119, v120, v117
	v_fma_f32 v116, -v116, v119, v118
	v_div_fmas_f32 v116, v116, v117, v119
	v_div_fixup_f32 v115, v116, v115, 1.0
	v_bfe_u32 v116, v115, 16, 1
	v_add3_u32 v116, v115, v116, s78
	v_add_u32_e32 v115, 0x110, v114
	v_lshl_add_u32 v114, v106, 1, v115
	ds_write_b16_d16_hi v114, v116
	v_add3_u32 v116, s84, v96, 10
	s_and_b64 vcc, exec, s[6:7]
	v_cmp_lt_i32_e64 s[20:21], s76, v116
	v_mul_f32_e32 v116, 0xbfb8aa3b, v22
	v_exp_f32_e32 v116, v116
	s_nop 0
	v_add_f32_e32 v116, 1.0, v116
	v_div_scale_f32 v117, s[22:23], v116, v116, 1.0
	v_rcp_f32_e32 v118, v117
	v_div_scale_f32 v119, vcc, 1.0, v116, 1.0
	v_fma_f32 v120, -v117, v118, 1.0
	v_fmac_f32_e32 v118, v120, v118
	v_mul_f32_e32 v120, v119, v118
	v_fma_f32 v121, -v117, v120, v119
	v_fmac_f32_e32 v120, v121, v118
	v_fma_f32 v117, -v117, v120, v119
	v_div_fmas_f32 v117, v117, v118, v120
	v_div_fixup_f32 v116, v117, v116, 1.0
	v_bfe_u32 v117, v116, 16, 1
	v_add3_u32 v117, v116, v117, s78
	v_add_u32_e32 v116, 0x110, v115
	v_lshl_add_u32 v115, v106, 1, v116
	ds_write_b16_d16_hi v115, v117
	v_add3_u32 v117, s84, v96, 11
	s_and_b64 vcc, exec, s[6:7]
	v_cmp_lt_i32_e64 s[22:23], s76, v117
	v_mul_f32_e32 v117, 0xbfb8aa3b, v23
	v_exp_f32_e32 v117, v117
	s_nop 0
	v_add_f32_e32 v117, 1.0, v117
	v_div_scale_f32 v118, s[24:25], v117, v117, 1.0
	v_rcp_f32_e32 v119, v118
; __device__ __forceinline__ bf16r f2bf(float f) {
;   unsigned u = __float_as_uint(f);
;   u += 0x7fffu + ((u >> 16) & 1u);
;   return (bf16r)(u >> 16);
; }
; __device__ __forceinline__ unsigned pack2(float a, float b) { return (unsigned)f2bf(a) | ((unsigned)f2bf(b) << 16); }
; __device__ __forceinline__ float lo16(unsigned v) { return __uint_as_float(v << 16); }
; __device__ __forceinline__ float hi16(unsigned v) { return __uint_as_float(v & 0xffff0000u); }
; __device__ __forceinline__ float siluf(float x) { return x / (1.f + __expf(-x)); }
; __device__ __forceinline__ float sigmf(float x) { return 1.f / (1.f + __expf(-x)); }
; __device__ __forceinline__ void inproj_epilogue(const Params& p, int layer, int mt, int ntile, int tid,
;                                                 f32x16 (&acc)[2][2], unsigned char* smem) {
;     ...
;     acc_foreach(tid, acc, [&](int row, int col, float v) {
;       int t = m0 + row;
;       float o = v;
;       if (mode == 1) o = (t >= NPADR) ? v : 0.f;
;       if (mode == 2) o = sigmf(v);
;       sT[row * 136 + col] = f2bf(o);
;     });
	v_div_scale_f32 v120, vcc, 1.0, v117, 1.0
	v_fma_f32 v121, -v118, v119, 1.0
	v_fmac_f32_e32 v119, v121, v119
	v_mul_f32_e32 v121, v120, v119
	v_fma_f32 v122, -v118, v121, v120
	v_fmac_f32_e32 v121, v122, v119
	v_fma_f32 v118, -v118, v121, v120
	v_div_fmas_f32 v118, v118, v119, v121
	v_div_fixup_f32 v117, v118, v117, 1.0
	v_bfe_u32 v118, v117, 16, 1
	v_add_u32_e32 v116, 0x110, v116
	v_add3_u32 v118, v117, v118, s78
	v_lshl_add_u32 v117, v106, 1, v116
	ds_write_b16_d16_hi v117, v118
	v_add3_u32 v118, s84, v96, 16
	s_and_b64 vcc, exec, s[6:7]
	v_cmp_lt_i32_e64 s[24:25], s76, v118
	v_mul_f32_e32 v118, 0xbfb8aa3b, v24
	v_exp_f32_e32 v118, v118
	s_nop 0
	v_add_f32_e32 v118, 1.0, v118
	v_div_scale_f32 v119, s[26:27], v118, v118, 1.0
	v_rcp_f32_e32 v120, v119
	v_div_scale_f32 v121, vcc, 1.0, v118, 1.0
	v_fma_f32 v122, -v119, v120, 1.0
	v_fmac_f32_e32 v120, v122, v120
	v_mul_f32_e32 v122, v121, v120
	v_fma_f32 v123, -v119, v122, v121
	v_fmac_f32_e32 v122, v123, v120
	v_fma_f32 v119, -v119, v122, v121
	v_div_fmas_f32 v119, v119, v120, v122
	v_div_fixup_f32 v118, v119, v118, 1.0
	v_bfe_u32 v119, v118, 16, 1
	v_add_u32_e32 v116, 0x550, v116
	v_add3_u32 v119, v118, v119, s78
	v_lshl_add_u32 v118, v106, 1, v116
	ds_write_b16_d16_hi v118, v119
	v_add3_u32 v119, s84, v96, 17
	s_and_b64 vcc, exec, s[6:7]
	v_cmp_lt_i32_e64 s[26:27], s76, v119
	v_mul_f32_e32 v119, 0xbfb8aa3b, v25
	v_exp_f32_e32 v119, v119
	s_nop 0
	v_add_f32_e32 v119, 1.0, v119
	v_div_scale_f32 v120, s[28:29], v119, v119, 1.0
	v_rcp_f32_e32 v121, v120
	v_div_scale_f32 v122, vcc, 1.0, v119, 1.0
	v_fma_f32 v123, -v120, v121, 1.0
	v_fmac_f32_e32 v121, v123, v121
	v_mul_f32_e32 v123, v122, v121
	v_fma_f32 v124, -v120, v123, v122
	v_fmac_f32_e32 v123, v124, v121
	v_fma_f32 v120, -v120, v123, v122
	v_div_fmas_f32 v120, v120, v121, v123
	v_div_fixup_f32 v119, v120, v119, 1.0
	v_bfe_u32 v120, v119, 16, 1
	v_add_u32_e32 v116, 0x110, v116
	v_add3_u32 v120, v119, v120, s78
	v_lshl_add_u32 v119, v106, 1, v116
	ds_write_b16_d16_hi v119, v120
	v_add3_u32 v120, s84, v96, 18
	s_and_b64 vcc, exec, s[6:7]
	v_cmp_lt_i32_e64 s[28:29], s76, v120
	v_mul_f32_e32 v120, 0xbfb8aa3b, v26
	v_exp_f32_e32 v120, v120
	s_nop 0
	v_add_f32_e32 v120, 1.0, v120
	v_div_scale_f32 v121, s[30:31], v120, v120, 1.0
	v_rcp_f32_e32 v122, v121
	v_div_scale_f32 v123, vcc, 1.0, v120, 1.0
	v_fma_f32 v124, -v121, v122, 1.0
	v_fmac_f32_e32 v122, v124, v122
	v_mul_f32_e32 v124, v123, v122
	v_fma_f32 v125, -v121, v124, v123
	v_fmac_f32_e32 v124, v125, v122
	v_fma_f32 v121, -v121, v124, v123
	v_div_fmas_f32 v121, v121, v122, v124
	v_div_fixup_f32 v120, v121, v120, 1.0
	v_bfe_u32 v121, v120, 16, 1
	v_add_u32_e32 v116, 0x110, v116
	v_add3_u32 v121, v120, v121, s78
	v_lshl_add_u32 v120, v106, 1, v116
	ds_write_b16_d16_hi v120, v121
	v_add3_u32 v121, s84, v96, 19
	s_and_b64 vcc, exec, s[6:7]
	v_cmp_lt_i32_e64 s[30:31], s76, v121
	v_mul_f32_e32 v121, 0xbfb8aa3b, v27
	v_exp_f32_e32 v121, v121
	s_nop 0
	v_add_f32_e32 v121, 1.0, v121
	v_div_scale_f32 v122, s[34:35], v121, v121, 1.0
	v_rcp_f32_e32 v123, v122
	v_div_scale_f32 v124, vcc, 1.0, v121, 1.0
	v_fma_f32 v125, -v122, v123, 1.0
	v_fmac_f32_e32 v123, v125, v123
	v_mul_f32_e32 v125, v124, v123
	v_fma_f32 v126, -v122, v125, v124
	v_fmac_f32_e32 v125, v126, v123
	v_fma_f32 v122, -v122, v125, v124
	v_div_fmas_f32 v122, v122, v123, v125
	v_div_fixup_f32 v121, v122, v121, 1.0
	v_bfe_u32 v122, v121, 16, 1
	v_add_u32_e32 v116, 0x110, v116
	v_add3_u32 v122, v121, v122, s78
	v_lshl_add_u32 v121, v106, 1, v116
	ds_write_b16_d16_hi v121, v122
	v_add3_u32 v122, s84, v96, 24
	s_and_b64 vcc, exec, s[6:7]
	v_cmp_lt_i32_e64 s[34:35], s76, v122
	v_mul_f32_e32 v122, 0xbfb8aa3b, v28
	v_exp_f32_e32 v122, v122
	s_nop 0
	v_add_f32_e32 v122, 1.0, v122
	v_div_scale_f32 v123, s[36:37], v122, v122, 1.0
	v_rcp_f32_e32 v124, v123
	v_div_scale_f32 v125, vcc, 1.0, v122, 1.0
	v_fma_f32 v126, -v123, v124, 1.0
	v_fmac_f32_e32 v124, v126, v124
	v_mul_f32_e32 v126, v125, v124
	v_fma_f32 v127, -v123, v126, v125
	v_fmac_f32_e32 v126, v127, v124
	v_fma_f32 v123, -v123, v126, v125
	v_div_fmas_f32 v123, v123, v124, v126
	v_div_fixup_f32 v122, v123, v122, 1.0
	v_bfe_u32 v123, v122, 16, 1
	v_add_u32_e32 v116, 0x550, v116
	v_add3_u32 v123, v122, v123, s78
	v_lshl_add_u32 v122, v106, 1, v116
	ds_write_b16_d16_hi v122, v123
	v_add3_u32 v123, s84, v96, 25
	s_and_b64 vcc, exec, s[6:7]
	v_cmp_lt_i32_e64 s[36:37], s76, v123
	v_mul_f32_e32 v123, 0xbfb8aa3b, v29
	v_exp_f32_e32 v123, v123
	s_nop 0
	v_add_f32_e32 v123, 1.0, v123
	v_div_scale_f32 v124, s[38:39], v123, v123, 1.0
	v_rcp_f32_e32 v125, v124
	v_div_scale_f32 v126, vcc, 1.0, v123, 1.0
	v_fma_f32 v127, -v124, v125, 1.0
	v_fmac_f32_e32 v125, v127, v125
	v_mul_f32_e32 v127, v126, v125
	v_fma_f32 v128, -v124, v127, v126
	v_fmac_f32_e32 v127, v128, v125
	v_fma_f32 v124, -v124, v127, v126
	v_div_fmas_f32 v124, v124, v125, v127
	v_div_fixup_f32 v123, v124, v123, 1.0
	v_bfe_u32 v124, v123, 16, 1
	v_add_u32_e32 v116, 0x110, v116
	v_add3_u32 v124, v123, v124, s78
	v_lshl_add_u32 v123, v106, 1, v116
	ds_write_b16_d16_hi v123, v124
	v_add3_u32 v124, s84, v96, 26
	s_and_b64 vcc, exec, s[6:7]
	v_cmp_lt_i32_e64 s[38:39], s76, v124
	v_mul_f32_e32 v124, 0xbfb8aa3b, v30
	v_exp_f32_e32 v124, v124
	s_nop 0
	v_add_f32_e32 v124, 1.0, v124
	v_div_scale_f32 v125, s[40:41], v124, v124, 1.0
	v_rcp_f32_e32 v126, v125
	v_div_scale_f32 v127, vcc, 1.0, v124, 1.0
	v_fma_f32 v128, -v125, v126, 1.0
	v_fmac_f32_e32 v126, v128, v126
	v_mul_f32_e32 v128, v127, v126
	v_fma_f32 v129, -v125, v128, v127
	v_fmac_f32_e32 v128, v129, v126
	v_fma_f32 v125, -v125, v128, v127
	v_div_fmas_f32 v125, v125, v126, v128
; __device__ __forceinline__ bf16r f2bf(float f) {
;   unsigned u = __float_as_uint(f);
;   u += 0x7fffu + ((u >> 16) & 1u);
;   return (bf16r)(u >> 16);
; }
; __device__ __forceinline__ unsigned pack2(float a, float b) { return (unsigned)f2bf(a) | ((unsigned)f2bf(b) << 16); }
; __device__ __forceinline__ float lo16(unsigned v) { return __uint_as_float(v << 16); }
; __device__ __forceinline__ float hi16(unsigned v) { return __uint_as_float(v & 0xffff0000u); }
; __device__ __forceinline__ float siluf(float x) { return x / (1.f + __expf(-x)); }
; __device__ __forceinline__ float sigmf(float x) { return 1.f / (1.f + __expf(-x)); }
; __device__ __forceinline__ void inproj_epilogue(const Params& p, int layer, int mt, int ntile, int tid,
;                                                 f32x16 (&acc)[2][2], unsigned char* smem) {
;     ...
;     acc_foreach(tid, acc, [&](int row, int col, float v) {
;       int t = m0 + row;
;       float o = v;
;       if (mode == 1) o = (t >= NPADR) ? v : 0.f;
;       if (mode == 2) o = sigmf(v);
;       sT[row * 136 + col] = f2bf(o);
;     });
	v_div_fixup_f32 v124, v125, v124, 1.0
	v_bfe_u32 v125, v124, 16, 1
	v_add_u32_e32 v116, 0x110, v116
	v_add3_u32 v124, v124, v125, s78
	v_lshl_add_u32 v116, v106, 1, v116
	ds_write_b16_d16_hi v116, v124
	v_add3_u32 v124, s84, v96, 27
	s_and_b64 vcc, exec, s[6:7]
	v_cmp_lt_i32_e64 s[40:41], s76, v124
	v_mul_f32_e32 v124, 0xbfb8aa3b, v31
	v_exp_f32_e32 v124, v124
	s_nop 0
	v_add_f32_e32 v124, 1.0, v124
	v_div_scale_f32 v125, vcc, v124, v124, 1.0
	v_rcp_f32_e32 v126, v125
	v_div_scale_f32 v127, vcc, 1.0, v124, 1.0
	v_fma_f32 v128, -v125, v126, 1.0
	v_fmac_f32_e32 v126, v128, v126
	v_mul_f32_e32 v128, v127, v126
	v_fma_f32 v129, -v125, v128, v127
	v_fmac_f32_e32 v128, v129, v126
	v_fma_f32 v125, -v125, v128, v127
	v_div_fmas_f32 v125, v125, v126, v128
	v_div_fixup_f32 v124, v125, v124, 1.0
	v_bfe_u32 v125, v124, 16, 1
	v_add3_u32 v124, v124, v125, s78
	ds_write_b16_d16_hi v116, v124 offset:272
	s_and_b64 vcc, exec, s[6:7]
	v_mul_f32_e32 v48, 0xbfb8aa3b, v48
	v_exp_f32_e32 v48, v48
	s_nop 0
	v_add_f32_e32 v48, 1.0, v48
	v_div_scale_f32 v124, s[8:9], v48, v48, 1.0
	v_rcp_f32_e32 v125, v124
	v_div_scale_f32 v126, vcc, 1.0, v48, 1.0
	v_fma_f32 v127, -v124, v125, 1.0
	v_fmac_f32_e32 v125, v127, v125
	v_mul_f32_e32 v127, v126, v125
	v_fma_f32 v128, -v124, v127, v126
	v_fmac_f32_e32 v127, v128, v125
	v_fma_f32 v124, -v124, v127, v126
	v_div_fmas_f32 v124, v124, v125, v127
	v_div_fixup_f32 v48, v124, v48, 1.0
	v_bfe_u32 v124, v48, 16, 1
	v_add3_u32 v48, v48, v124, s78
	s_and_b64 vcc, exec, s[6:7]
	ds_write_b16_d16_hi v107, v48 offset:64
	v_mul_f32_e32 v48, 0xbfb8aa3b, v49
	v_exp_f32_e32 v48, v48
	s_nop 0
	v_add_f32_e32 v48, 1.0, v48
	v_div_scale_f32 v49, s[8:9], v48, v48, 1.0
	v_rcp_f32_e32 v107, v49
	v_div_scale_f32 v124, vcc, 1.0, v48, 1.0
	v_fma_f32 v125, -v49, v107, 1.0
	v_fmac_f32_e32 v107, v125, v107
	v_mul_f32_e32 v125, v124, v107
	v_fma_f32 v126, -v49, v125, v124
	v_fmac_f32_e32 v125, v126, v107
	v_fma_f32 v49, -v49, v125, v124
	v_div_fmas_f32 v49, v49, v107, v125
	v_div_fixup_f32 v48, v49, v48, 1.0
	v_bfe_u32 v49, v48, 16, 1
	v_add3_u32 v48, v48, v49, s78
	s_and_b64 vcc, exec, s[6:7]
	ds_write_b16_d16_hi v110, v48 offset:64
	v_mul_f32_e32 v48, 0xbfb8aa3b, v50
	v_exp_f32_e32 v48, v48
	s_nop 0
	v_add_f32_e32 v48, 1.0, v48
	v_div_scale_f32 v49, s[8:9], v48, v48, 1.0
	v_rcp_f32_e32 v50, v49
	v_div_scale_f32 v107, vcc, 1.0, v48, 1.0
	v_fma_f32 v110, -v49, v50, 1.0
	v_fmac_f32_e32 v50, v110, v50
	v_mul_f32_e32 v110, v107, v50
	v_fma_f32 v124, -v49, v110, v107
	v_fmac_f32_e32 v110, v124, v50
	v_fma_f32 v49, -v49, v110, v107
	v_div_fmas_f32 v49, v49, v50, v110
	v_div_fixup_f32 v48, v49, v48, 1.0
	v_bfe_u32 v49, v48, 16, 1
	v_add3_u32 v48, v48, v49, s78
	s_and_b64 vcc, exec, s[6:7]
	ds_write_b16_d16_hi v111, v48 offset:64
	v_mul_f32_e32 v48, 0xbfb8aa3b, v51
	v_exp_f32_e32 v48, v48
	s_nop 0
	v_add_f32_e32 v48, 1.0, v48
	v_div_scale_f32 v49, s[8:9], v48, v48, 1.0
	v_rcp_f32_e32 v50, v49
	v_div_scale_f32 v51, vcc, 1.0, v48, 1.0
	v_fma_f32 v107, -v49, v50, 1.0
	v_fmac_f32_e32 v50, v107, v50
	v_mul_f32_e32 v107, v51, v50
	v_fma_f32 v110, -v49, v107, v51
	v_fmac_f32_e32 v107, v110, v50
	v_fma_f32 v49, -v49, v107, v51
	v_div_fmas_f32 v49, v49, v50, v107
	v_div_fixup_f32 v48, v49, v48, 1.0
	v_bfe_u32 v49, v48, 16, 1
	v_add3_u32 v48, v48, v49, s78
	s_and_b64 vcc, exec, s[6:7]
	ds_write_b16_d16_hi v112, v48 offset:64
	v_mul_f32_e32 v48, 0xbfb8aa3b, v52
	v_exp_f32_e32 v48, v48
	s_nop 0
	v_add_f32_e32 v48, 1.0, v48
	v_div_scale_f32 v49, s[8:9], v48, v48, 1.0
	v_rcp_f32_e32 v50, v49
	v_div_scale_f32 v51, vcc, 1.0, v48, 1.0
	v_fma_f32 v52, -v49, v50, 1.0
	v_fmac_f32_e32 v50, v52, v50
	v_mul_f32_e32 v52, v51, v50
	v_fma_f32 v107, -v49, v52, v51
	v_fmac_f32_e32 v52, v107, v50
	v_fma_f32 v49, -v49, v52, v51
	v_div_fmas_f32 v49, v49, v50, v52
	v_div_fixup_f32 v48, v49, v48, 1.0
	v_bfe_u32 v49, v48, 16, 1
	v_add3_u32 v48, v48, v49, s78
	s_and_b64 vcc, exec, s[6:7]
	ds_write_b16_d16_hi v113, v48 offset:64
	v_mul_f32_e32 v48, 0xbfb8aa3b, v53
	v_exp_f32_e32 v48, v48
	s_nop 0
	v_add_f32_e32 v48, 1.0, v48
	v_div_scale_f32 v49, s[8:9], v48, v48, 1.0
	v_rcp_f32_e32 v50, v49
	v_div_scale_f32 v51, vcc, 1.0, v48, 1.0
	v_fma_f32 v52, -v49, v50, 1.0
	v_fmac_f32_e32 v50, v52, v50
	v_mul_f32_e32 v52, v51, v50
	v_fma_f32 v53, -v49, v52, v51
	v_fmac_f32_e32 v52, v53, v50
	v_fma_f32 v49, -v49, v52, v51
	v_div_fmas_f32 v49, v49, v50, v52
	v_div_fixup_f32 v48, v49, v48, 1.0
	v_bfe_u32 v49, v48, 16, 1
	v_add3_u32 v48, v48, v49, s78
	s_and_b64 vcc, exec, s[6:7]
	ds_write_b16_d16_hi v114, v48 offset:64
	v_mul_f32_e32 v48, 0xbfb8aa3b, v54
	v_exp_f32_e32 v48, v48
	s_nop 0
	v_add_f32_e32 v48, 1.0, v48
	v_div_scale_f32 v49, s[8:9], v48, v48, 1.0
	v_rcp_f32_e32 v50, v49
	v_div_scale_f32 v51, vcc, 1.0, v48, 1.0
	v_fma_f32 v52, -v49, v50, 1.0
	v_fmac_f32_e32 v50, v52, v50
	v_mul_f32_e32 v52, v51, v50
	v_fma_f32 v53, -v49, v52, v51
	v_fmac_f32_e32 v52, v53, v50
	v_fma_f32 v49, -v49, v52, v51
	v_div_fmas_f32 v49, v49, v50, v52
	v_div_fixup_f32 v48, v49, v48, 1.0
	v_bfe_u32 v49, v48, 16, 1
	v_add3_u32 v48, v48, v49, s78
	s_and_b64 vcc, exec, s[6:7]
	ds_write_b16_d16_hi v115, v48 offset:64
	v_mul_f32_e32 v48, 0xbfb8aa3b, v55
	v_exp_f32_e32 v48, v48
	s_nop 0
	v_add_f32_e32 v48, 1.0, v48
	v_div_scale_f32 v49, s[8:9], v48, v48, 1.0
	v_rcp_f32_e32 v50, v49
	v_div_scale_f32 v51, vcc, 1.0, v48, 1.0
	v_fma_f32 v52, -v49, v50, 1.0
	v_fmac_f32_e32 v50, v52, v50
	v_mul_f32_e32 v52, v51, v50
	v_fma_f32 v53, -v49, v52, v51
	v_fmac_f32_e32 v52, v53, v50
	v_fma_f32 v49, -v49, v52, v51
	v_div_fmas_f32 v49, v49, v50, v52
	v_div_fixup_f32 v48, v49, v48, 1.0
	v_bfe_u32 v49, v48, 16, 1
	v_add3_u32 v48, v48, v49, s78
; __device__ __forceinline__ bf16r f2bf(float f) {
;   unsigned u = __float_as_uint(f);
;   u += 0x7fffu + ((u >> 16) & 1u);
;   return (bf16r)(u >> 16);
; }
; __device__ __forceinline__ unsigned pack2(float a, float b) { return (unsigned)f2bf(a) | ((unsigned)f2bf(b) << 16); }
; __device__ __forceinline__ float lo16(unsigned v) { return __uint_as_float(v << 16); }
; __device__ __forceinline__ float hi16(unsigned v) { return __uint_as_float(v & 0xffff0000u); }
; __device__ __forceinline__ float siluf(float x) { return x / (1.f + __expf(-x)); }
; __device__ __forceinline__ float sigmf(float x) { return 1.f / (1.f + __expf(-x)); }
; __device__ __forceinline__ void inproj_epilogue(const Params& p, int layer, int mt, int ntile, int tid,
;                                                 f32x16 (&acc)[2][2], unsigned char* smem) {
;     ...
;     acc_foreach(tid, acc, [&](int row, int col, float v) {
;       int t = m0 + row;
;       float o = v;
;       if (mode == 1) o = (t >= NPADR) ? v : 0.f;
;       if (mode == 2) o = sigmf(v);
;       sT[row * 136 + col] = f2bf(o);
;     });
	s_and_b64 vcc, exec, s[6:7]
	ds_write_b16_d16_hi v117, v48 offset:64
	v_mul_f32_e32 v48, 0xbfb8aa3b, v56
	v_exp_f32_e32 v48, v48
	s_nop 0
	v_add_f32_e32 v48, 1.0, v48
	v_div_scale_f32 v49, s[8:9], v48, v48, 1.0
	v_rcp_f32_e32 v50, v49
	v_div_scale_f32 v51, vcc, 1.0, v48, 1.0
	v_fma_f32 v52, -v49, v50, 1.0
	v_fmac_f32_e32 v50, v52, v50
	v_mul_f32_e32 v52, v51, v50
	v_fma_f32 v53, -v49, v52, v51
	v_fmac_f32_e32 v52, v53, v50
	v_fma_f32 v49, -v49, v52, v51
	v_div_fmas_f32 v49, v49, v50, v52
	v_div_fixup_f32 v48, v49, v48, 1.0
	v_bfe_u32 v49, v48, 16, 1
	v_add3_u32 v48, v48, v49, s78
	s_and_b64 vcc, exec, s[6:7]
	ds_write_b16_d16_hi v118, v48 offset:64
	v_mul_f32_e32 v48, 0xbfb8aa3b, v57
	v_exp_f32_e32 v48, v48
	s_nop 0
	v_add_f32_e32 v48, 1.0, v48
	v_div_scale_f32 v49, s[8:9], v48, v48, 1.0
	v_rcp_f32_e32 v50, v49
	v_div_scale_f32 v51, vcc, 1.0, v48, 1.0
	v_fma_f32 v52, -v49, v50, 1.0
	v_fmac_f32_e32 v50, v52, v50
	v_mul_f32_e32 v52, v51, v50
	v_fma_f32 v53, -v49, v52, v51
	v_fmac_f32_e32 v52, v53, v50
	v_fma_f32 v49, -v49, v52, v51
	v_div_fmas_f32 v49, v49, v50, v52
	v_div_fixup_f32 v48, v49, v48, 1.0
	v_bfe_u32 v49, v48, 16, 1
	v_add3_u32 v48, v48, v49, s78
	s_and_b64 vcc, exec, s[6:7]
	ds_write_b16_d16_hi v119, v48 offset:64
	v_mul_f32_e32 v48, 0xbfb8aa3b, v58
	v_exp_f32_e32 v48, v48
	s_nop 0
	v_add_f32_e32 v48, 1.0, v48
	v_div_scale_f32 v49, s[8:9], v48, v48, 1.0
	v_rcp_f32_e32 v50, v49
	v_div_scale_f32 v51, vcc, 1.0, v48, 1.0
	v_fma_f32 v52, -v49, v50, 1.0
	v_fmac_f32_e32 v50, v52, v50
	v_mul_f32_e32 v52, v51, v50
	v_fma_f32 v53, -v49, v52, v51
	v_fmac_f32_e32 v52, v53, v50
	v_fma_f32 v49, -v49, v52, v51
	v_div_fmas_f32 v49, v49, v50, v52
	v_div_fixup_f32 v48, v49, v48, 1.0
	v_bfe_u32 v49, v48, 16, 1
	v_add3_u32 v48, v48, v49, s78
	s_and_b64 vcc, exec, s[6:7]
	ds_write_b16_d16_hi v120, v48 offset:64
	v_mul_f32_e32 v48, 0xbfb8aa3b, v59
	v_exp_f32_e32 v48, v48
	s_nop 0
	v_add_f32_e32 v48, 1.0, v48
	v_div_scale_f32 v49, s[8:9], v48, v48, 1.0
	v_rcp_f32_e32 v50, v49
	v_div_scale_f32 v51, vcc, 1.0, v48, 1.0
	v_fma_f32 v52, -v49, v50, 1.0
	v_fmac_f32_e32 v50, v52, v50
	v_mul_f32_e32 v52, v51, v50
	v_fma_f32 v53, -v49, v52, v51
	v_fmac_f32_e32 v52, v53, v50
	v_fma_f32 v49, -v49, v52, v51
	v_div_fmas_f32 v49, v49, v50, v52
	v_div_fixup_f32 v48, v49, v48, 1.0
	v_bfe_u32 v49, v48, 16, 1
	v_add3_u32 v48, v48, v49, s78
	s_and_b64 vcc, exec, s[6:7]
	ds_write_b16_d16_hi v121, v48 offset:64
	v_mul_f32_e32 v48, 0xbfb8aa3b, v60
	v_exp_f32_e32 v48, v48
	s_nop 0
	v_add_f32_e32 v48, 1.0, v48
	v_div_scale_f32 v49, s[8:9], v48, v48, 1.0
	v_rcp_f32_e32 v50, v49
	v_div_scale_f32 v51, vcc, 1.0, v48, 1.0
	v_fma_f32 v52, -v49, v50, 1.0
	v_fmac_f32_e32 v50, v52, v50
	v_mul_f32_e32 v52, v51, v50
	v_fma_f32 v53, -v49, v52, v51
	v_fmac_f32_e32 v52, v53, v50
	v_fma_f32 v49, -v49, v52, v51
	v_div_fmas_f32 v49, v49, v50, v52
	v_div_fixup_f32 v48, v49, v48, 1.0
	v_bfe_u32 v49, v48, 16, 1
	v_add3_u32 v48, v48, v49, s78
	s_and_b64 vcc, exec, s[6:7]
	ds_write_b16_d16_hi v122, v48 offset:64
	v_mul_f32_e32 v48, 0xbfb8aa3b, v61
	v_exp_f32_e32 v48, v48
	s_nop 0
	v_add_f32_e32 v48, 1.0, v48
	v_div_scale_f32 v49, s[8:9], v48, v48, 1.0
	v_rcp_f32_e32 v50, v49
	v_div_scale_f32 v51, vcc, 1.0, v48, 1.0
	v_fma_f32 v52, -v49, v50, 1.0
	v_fmac_f32_e32 v50, v52, v50
	v_mul_f32_e32 v52, v51, v50
	v_fma_f32 v53, -v49, v52, v51
	v_fmac_f32_e32 v52, v53, v50
	v_fma_f32 v49, -v49, v52, v51
	v_div_fmas_f32 v49, v49, v50, v52
	v_div_fixup_f32 v48, v49, v48, 1.0
	v_bfe_u32 v49, v48, 16, 1
	v_add3_u32 v48, v48, v49, s78
	s_and_b64 vcc, exec, s[6:7]
	ds_write_b16_d16_hi v123, v48 offset:64
	v_mul_f32_e32 v48, 0xbfb8aa3b, v62
	v_exp_f32_e32 v48, v48
	s_nop 0
	v_add_f32_e32 v48, 1.0, v48
	v_div_scale_f32 v49, s[8:9], v48, v48, 1.0
	v_rcp_f32_e32 v50, v49
	v_div_scale_f32 v51, vcc, 1.0, v48, 1.0
	v_fma_f32 v52, -v49, v50, 1.0
	v_fmac_f32_e32 v50, v52, v50
	v_mul_f32_e32 v52, v51, v50
	v_fma_f32 v53, -v49, v52, v51
	v_fmac_f32_e32 v52, v53, v50
	v_fma_f32 v49, -v49, v52, v51
	v_div_fmas_f32 v49, v49, v50, v52
	v_div_fixup_f32 v48, v49, v48, 1.0
	v_bfe_u32 v49, v48, 16, 1
	v_add3_u32 v48, v48, v49, s78
	s_and_b64 vcc, exec, s[6:7]
	ds_write_b16_d16_hi v116, v48 offset:64
	v_mul_f32_e32 v48, 0xbfb8aa3b, v63
	v_exp_f32_e32 v48, v48
	s_nop 0
	v_add_f32_e32 v48, 1.0, v48
	v_div_scale_f32 v49, s[8:9], v48, v48, 1.0
	v_rcp_f32_e32 v50, v49
	v_div_scale_f32 v51, vcc, 1.0, v48, 1.0
	v_fma_f32 v52, -v49, v50, 1.0
	v_fmac_f32_e32 v50, v52, v50
	v_mul_f32_e32 v52, v51, v50
	v_fma_f32 v53, -v49, v52, v51
	v_fmac_f32_e32 v52, v53, v50
	v_fma_f32 v49, -v49, v52, v51
	v_div_fmas_f32 v49, v49, v50, v52
	v_div_fixup_f32 v48, v49, v48, 1.0
	v_bfe_u32 v50, v48, 16, 1
	v_add_u32_e32 v49, 0x110, v116
	v_add3_u32 v48, v48, v50, s78
	ds_write_b16_d16_hi v49, v48 offset:64
	v_or_b32_e32 v48, 32, v96
	v_add_u32_e32 v49, s84, v48
	s_and_b64 vcc, exec, s[6:7]
	v_cmp_lt_i32_e64 s[8:9], s76, v49
	v_mul_f32_e32 v49, 0xbfb8aa3b, v0
	v_exp_f32_e32 v49, v49
	s_nop 0
	v_add_f32_e32 v49, 1.0, v49
	v_div_scale_f32 v50, s[10:11], v49, v49, 1.0
	v_rcp_f32_e32 v51, v50
	v_div_scale_f32 v52, vcc, 1.0, v49, 1.0
	v_fma_f32 v53, -v50, v51, 1.0
	v_fmac_f32_e32 v51, v53, v51
	v_mul_f32_e32 v53, v52, v51
	v_fma_f32 v54, -v50, v53, v52
	v_fmac_f32_e32 v53, v54, v51
	v_fma_f32 v50, -v50, v53, v52
	v_div_fmas_f32 v50, v50, v51, v53
	v_div_fixup_f32 v49, v50, v49, 1.0
	v_bfe_u32 v50, v49, 16, 1
	v_add3_u32 v50, v49, v50, s78
	v_mul_lo_u32 v49, v48, s79
	v_lshl_add_u32 v48, v106, 1, v49
	ds_write_b16_d16_hi v48, v50
	v_add3_u32 v50, s84, v96, 33
	s_and_b64 vcc, exec, s[6:7]
	v_cmp_lt_i32_e64 s[10:11], s76, v50
	v_mul_f32_e32 v50, 0xbfb8aa3b, v1
; __device__ __forceinline__ bf16r f2bf(float f) {
;   unsigned u = __float_as_uint(f);
;   u += 0x7fffu + ((u >> 16) & 1u);
;   return (bf16r)(u >> 16);
; }
; __device__ __forceinline__ unsigned pack2(float a, float b) { return (unsigned)f2bf(a) | ((unsigned)f2bf(b) << 16); }
; __device__ __forceinline__ float lo16(unsigned v) { return __uint_as_float(v << 16); }
; __device__ __forceinline__ float hi16(unsigned v) { return __uint_as_float(v & 0xffff0000u); }
; __device__ __forceinline__ float siluf(float x) { return x / (1.f + __expf(-x)); }
; __device__ __forceinline__ float sigmf(float x) { return 1.f / (1.f + __expf(-x)); }
; __device__ __forceinline__ void inproj_epilogue(const Params& p, int layer, int mt, int ntile, int tid,
;                                                 f32x16 (&acc)[2][2], unsigned char* smem) {
;     ...
;     acc_foreach(tid, acc, [&](int row, int col, float v) {
;       int t = m0 + row;
;       float o = v;
;       if (mode == 1) o = (t >= NPADR) ? v : 0.f;
;       if (mode == 2) o = sigmf(v);
;       sT[row * 136 + col] = f2bf(o);
;     });
	v_exp_f32_e32 v50, v50
	s_nop 0
	v_add_f32_e32 v50, 1.0, v50
	v_div_scale_f32 v51, s[12:13], v50, v50, 1.0
	v_rcp_f32_e32 v52, v51
	v_div_scale_f32 v53, vcc, 1.0, v50, 1.0
	v_fma_f32 v54, -v51, v52, 1.0
	v_fmac_f32_e32 v52, v54, v52
	v_mul_f32_e32 v54, v53, v52
	v_fma_f32 v55, -v51, v54, v53
	v_fmac_f32_e32 v54, v55, v52
	v_fma_f32 v51, -v51, v54, v53
	v_div_fmas_f32 v51, v51, v52, v54
	v_div_fixup_f32 v50, v51, v50, 1.0
	v_bfe_u32 v51, v50, 16, 1
	v_add3_u32 v51, v50, v51, s78
	v_add_u32_e32 v50, 0x110, v49
	v_lshl_add_u32 v49, v106, 1, v50
	ds_write_b16_d16_hi v49, v51
	v_add3_u32 v51, s84, v96, 34
	s_and_b64 vcc, exec, s[6:7]
	v_cmp_lt_i32_e64 s[12:13], s76, v51
	v_mul_f32_e32 v51, 0xbfb8aa3b, v2
	v_exp_f32_e32 v51, v51
	s_nop 0
	v_add_f32_e32 v51, 1.0, v51
	v_div_scale_f32 v52, s[14:15], v51, v51, 1.0
	v_rcp_f32_e32 v53, v52
	v_div_scale_f32 v54, vcc, 1.0, v51, 1.0
	v_fma_f32 v55, -v52, v53, 1.0
	v_fmac_f32_e32 v53, v55, v53
	v_mul_f32_e32 v55, v54, v53
	v_fma_f32 v56, -v52, v55, v54
	v_fmac_f32_e32 v55, v56, v53
	v_fma_f32 v52, -v52, v55, v54
	v_div_fmas_f32 v52, v52, v53, v55
	v_div_fixup_f32 v51, v52, v51, 1.0
	v_bfe_u32 v52, v51, 16, 1
	v_add3_u32 v52, v51, v52, s78
	v_add_u32_e32 v51, 0x110, v50
	v_lshl_add_u32 v50, v106, 1, v51
	ds_write_b16_d16_hi v50, v52
	v_add3_u32 v52, s84, v96, 35
	s_and_b64 vcc, exec, s[6:7]
	v_cmp_lt_i32_e64 s[14:15], s76, v52
	v_mul_f32_e32 v52, 0xbfb8aa3b, v3
	v_exp_f32_e32 v52, v52
	s_nop 0
	v_add_f32_e32 v52, 1.0, v52
	v_div_scale_f32 v53, s[16:17], v52, v52, 1.0
	v_rcp_f32_e32 v54, v53
	v_div_scale_f32 v55, vcc, 1.0, v52, 1.0
	v_fma_f32 v56, -v53, v54, 1.0
	v_fmac_f32_e32 v54, v56, v54
	v_mul_f32_e32 v56, v55, v54
	v_fma_f32 v57, -v53, v56, v55
	v_fmac_f32_e32 v56, v57, v54
	v_fma_f32 v53, -v53, v56, v55
	v_div_fmas_f32 v53, v53, v54, v56
	v_div_fixup_f32 v52, v53, v52, 1.0
	v_bfe_u32 v53, v52, 16, 1
	v_add3_u32 v53, v52, v53, s78
	v_add_u32_e32 v52, 0x110, v51
	v_lshl_add_u32 v51, v106, 1, v52
	ds_write_b16_d16_hi v51, v53
	v_add3_u32 v53, s84, v96, 40
	s_and_b64 vcc, exec, s[6:7]
	v_cmp_lt_i32_e64 s[16:17], s76, v53
	v_mul_f32_e32 v53, 0xbfb8aa3b, v4
	v_exp_f32_e32 v53, v53
	s_nop 0
	v_add_f32_e32 v53, 1.0, v53
	v_div_scale_f32 v54, s[18:19], v53, v53, 1.0
	v_rcp_f32_e32 v55, v54
	v_div_scale_f32 v56, vcc, 1.0, v53, 1.0
	v_fma_f32 v57, -v54, v55, 1.0
	v_fmac_f32_e32 v55, v57, v55
	v_mul_f32_e32 v57, v56, v55
	v_fma_f32 v58, -v54, v57, v56
	v_fmac_f32_e32 v57, v58, v55
	v_fma_f32 v54, -v54, v57, v56
	v_div_fmas_f32 v54, v54, v55, v57
	v_div_fixup_f32 v53, v54, v53, 1.0
	v_bfe_u32 v54, v53, 16, 1
	v_add3_u32 v54, v53, v54, s78
	v_add_u32_e32 v53, 0x550, v52
	v_lshl_add_u32 v52, v106, 1, v53
	ds_write_b16_d16_hi v52, v54
	v_add3_u32 v54, s84, v96, 41
	s_and_b64 vcc, exec, s[6:7]
	v_cmp_lt_i32_e64 s[18:19], s76, v54
	v_mul_f32_e32 v54, 0xbfb8aa3b, v5
	v_exp_f32_e32 v54, v54
	s_nop 0
	v_add_f32_e32 v54, 1.0, v54
	v_div_scale_f32 v55, s[20:21], v54, v54, 1.0
	v_rcp_f32_e32 v56, v55
	v_div_scale_f32 v57, vcc, 1.0, v54, 1.0
	v_fma_f32 v58, -v55, v56, 1.0
	v_fmac_f32_e32 v56, v58, v56
	v_mul_f32_e32 v58, v57, v56
	v_fma_f32 v59, -v55, v58, v57
	v_fmac_f32_e32 v58, v59, v56
	v_fma_f32 v55, -v55, v58, v57
	v_div_fmas_f32 v55, v55, v56, v58
	v_div_fixup_f32 v54, v55, v54, 1.0
	v_bfe_u32 v55, v54, 16, 1
	v_add3_u32 v55, v54, v55, s78
	v_add_u32_e32 v54, 0x110, v53
	v_lshl_add_u32 v53, v106, 1, v54
	ds_write_b16_d16_hi v53, v55
	v_add3_u32 v55, s84, v96, 42
	s_and_b64 vcc, exec, s[6:7]
	v_cmp_lt_i32_e64 s[20:21], s76, v55
	v_mul_f32_e32 v55, 0xbfb8aa3b, v6
	v_exp_f32_e32 v55, v55
	s_nop 0
	v_add_f32_e32 v55, 1.0, v55
	v_div_scale_f32 v56, s[22:23], v55, v55, 1.0
	v_rcp_f32_e32 v57, v56
	v_div_scale_f32 v58, vcc, 1.0, v55, 1.0
	v_fma_f32 v59, -v56, v57, 1.0
	v_fmac_f32_e32 v57, v59, v57
	v_mul_f32_e32 v59, v58, v57
	v_fma_f32 v60, -v56, v59, v58
	v_fmac_f32_e32 v59, v60, v57
	v_fma_f32 v56, -v56, v59, v58
	v_div_fmas_f32 v56, v56, v57, v59
	v_div_fixup_f32 v55, v56, v55, 1.0
	v_bfe_u32 v56, v55, 16, 1
	v_add3_u32 v56, v55, v56, s78
	v_add_u32_e32 v55, 0x110, v54
	v_lshl_add_u32 v54, v106, 1, v55
	ds_write_b16_d16_hi v54, v56
	v_add3_u32 v56, s84, v96, 43
	s_and_b64 vcc, exec, s[6:7]
	v_cmp_lt_i32_e64 s[22:23], s76, v56
	v_mul_f32_e32 v56, 0xbfb8aa3b, v7
	v_exp_f32_e32 v56, v56
	s_nop 0
	v_add_f32_e32 v56, 1.0, v56
	v_div_scale_f32 v57, s[24:25], v56, v56, 1.0
	v_rcp_f32_e32 v58, v57
	v_div_scale_f32 v59, vcc, 1.0, v56, 1.0
	v_fma_f32 v60, -v57, v58, 1.0
	v_fmac_f32_e32 v58, v60, v58
	v_mul_f32_e32 v60, v59, v58
	v_fma_f32 v61, -v57, v60, v59
	v_fmac_f32_e32 v60, v61, v58
	v_fma_f32 v57, -v57, v60, v59
	v_div_fmas_f32 v57, v57, v58, v60
	v_div_fixup_f32 v56, v57, v56, 1.0
	v_bfe_u32 v57, v56, 16, 1
	v_add_u32_e32 v55, 0x110, v55
	v_add3_u32 v57, v56, v57, s78
	v_lshl_add_u32 v56, v106, 1, v55
	ds_write_b16_d16_hi v56, v57
	v_add3_u32 v57, s84, v96, 48
	s_and_b64 vcc, exec, s[6:7]
	v_cmp_lt_i32_e64 s[24:25], s76, v57
	v_mul_f32_e32 v57, 0xbfb8aa3b, v8
	v_exp_f32_e32 v57, v57
	s_nop 0
	v_add_f32_e32 v57, 1.0, v57
	v_div_scale_f32 v58, s[26:27], v57, v57, 1.0
	v_rcp_f32_e32 v59, v58
	v_div_scale_f32 v60, vcc, 1.0, v57, 1.0
	v_fma_f32 v61, -v58, v59, 1.0
	v_fmac_f32_e32 v59, v61, v59
	v_mul_f32_e32 v61, v60, v59
	v_fma_f32 v62, -v58, v61, v60
	v_fmac_f32_e32 v61, v62, v59
	v_fma_f32 v58, -v58, v61, v60
	v_div_fmas_f32 v58, v58, v59, v61
	v_div_fixup_f32 v57, v58, v57, 1.0
	v_bfe_u32 v58, v57, 16, 1
	v_add_u32_e32 v55, 0x550, v55
	v_add3_u32 v58, v57, v58, s78
	v_lshl_add_u32 v57, v106, 1, v55
	ds_write_b16_d16_hi v57, v58
	v_add3_u32 v58, s84, v96, 49
	s_and_b64 vcc, exec, s[6:7]
	v_cmp_lt_i32_e64 s[26:27], s76, v58
; __device__ __forceinline__ bf16r f2bf(float f) {
;   unsigned u = __float_as_uint(f);
;   u += 0x7fffu + ((u >> 16) & 1u);
;   return (bf16r)(u >> 16);
; }
; __device__ __forceinline__ unsigned pack2(float a, float b) { return (unsigned)f2bf(a) | ((unsigned)f2bf(b) << 16); }
; __device__ __forceinline__ float lo16(unsigned v) { return __uint_as_float(v << 16); }
; __device__ __forceinline__ float hi16(unsigned v) { return __uint_as_float(v & 0xffff0000u); }
; __device__ __forceinline__ float siluf(float x) { return x / (1.f + __expf(-x)); }
; __device__ __forceinline__ float sigmf(float x) { return 1.f / (1.f + __expf(-x)); }
; __device__ __forceinline__ void inproj_epilogue(const Params& p, int layer, int mt, int ntile, int tid,
;                                                 f32x16 (&acc)[2][2], unsigned char* smem) {
;     ...
;     acc_foreach(tid, acc, [&](int row, int col, float v) {
;       int t = m0 + row;
;       float o = v;
;       if (mode == 1) o = (t >= NPADR) ? v : 0.f;
;       if (mode == 2) o = sigmf(v);
;       sT[row * 136 + col] = f2bf(o);
;     });
	v_mul_f32_e32 v58, 0xbfb8aa3b, v9
	v_exp_f32_e32 v58, v58
	s_nop 0
	v_add_f32_e32 v58, 1.0, v58
	v_div_scale_f32 v59, s[28:29], v58, v58, 1.0
	v_rcp_f32_e32 v60, v59
	v_div_scale_f32 v61, vcc, 1.0, v58, 1.0
	v_fma_f32 v62, -v59, v60, 1.0
	v_fmac_f32_e32 v60, v62, v60
	v_mul_f32_e32 v62, v61, v60
	v_fma_f32 v63, -v59, v62, v61
	v_fmac_f32_e32 v62, v63, v60
	v_fma_f32 v59, -v59, v62, v61
	v_div_fmas_f32 v59, v59, v60, v62
	v_div_fixup_f32 v58, v59, v58, 1.0
	v_bfe_u32 v59, v58, 16, 1
	v_add_u32_e32 v55, 0x110, v55
	v_add3_u32 v59, v58, v59, s78
	v_lshl_add_u32 v58, v106, 1, v55
	ds_write_b16_d16_hi v58, v59
	v_add3_u32 v59, s84, v96, 50
	s_and_b64 vcc, exec, s[6:7]
	v_cmp_lt_i32_e64 s[28:29], s76, v59
	v_mul_f32_e32 v59, 0xbfb8aa3b, v10
	v_exp_f32_e32 v59, v59
	s_nop 0
	v_add_f32_e32 v59, 1.0, v59
	v_div_scale_f32 v60, s[30:31], v59, v59, 1.0
	v_rcp_f32_e32 v61, v60
	v_div_scale_f32 v62, vcc, 1.0, v59, 1.0
	v_fma_f32 v63, -v60, v61, 1.0
	v_fmac_f32_e32 v61, v63, v61
	v_mul_f32_e32 v63, v62, v61
	v_fma_f32 v107, -v60, v63, v62
	v_fmac_f32_e32 v63, v107, v61
	v_fma_f32 v60, -v60, v63, v62
	v_div_fmas_f32 v60, v60, v61, v63
	v_div_fixup_f32 v59, v60, v59, 1.0
	v_bfe_u32 v60, v59, 16, 1
	v_add_u32_e32 v55, 0x110, v55
	v_add3_u32 v60, v59, v60, s78
	v_lshl_add_u32 v59, v106, 1, v55
	ds_write_b16_d16_hi v59, v60
	v_add3_u32 v60, s84, v96, 51
	s_and_b64 vcc, exec, s[6:7]
	v_cmp_lt_i32_e64 s[30:31], s76, v60
	v_mul_f32_e32 v60, 0xbfb8aa3b, v11
	v_exp_f32_e32 v60, v60
	s_nop 0
	v_add_f32_e32 v60, 1.0, v60
	v_div_scale_f32 v61, s[34:35], v60, v60, 1.0
	v_rcp_f32_e32 v62, v61
	v_div_scale_f32 v63, vcc, 1.0, v60, 1.0
	v_fma_f32 v107, -v61, v62, 1.0
	v_fmac_f32_e32 v62, v107, v62
	v_mul_f32_e32 v107, v63, v62
	v_fma_f32 v110, -v61, v107, v63
	v_fmac_f32_e32 v107, v110, v62
	v_fma_f32 v61, -v61, v107, v63
	v_div_fmas_f32 v61, v61, v62, v107
	v_div_fixup_f32 v60, v61, v60, 1.0
	v_bfe_u32 v61, v60, 16, 1
	v_add_u32_e32 v55, 0x110, v55
	v_add3_u32 v61, v60, v61, s78
	v_lshl_add_u32 v60, v106, 1, v55
	ds_write_b16_d16_hi v60, v61
	v_add3_u32 v61, s84, v96, 56
	s_and_b64 vcc, exec, s[6:7]
	v_cmp_lt_i32_e64 s[34:35], s76, v61
	v_mul_f32_e32 v61, 0xbfb8aa3b, v12
	v_exp_f32_e32 v61, v61
	s_nop 0
	v_add_f32_e32 v61, 1.0, v61
	v_div_scale_f32 v62, s[36:37], v61, v61, 1.0
	v_rcp_f32_e32 v63, v62
	v_div_scale_f32 v107, vcc, 1.0, v61, 1.0
	v_fma_f32 v110, -v62, v63, 1.0
	v_fmac_f32_e32 v63, v110, v63
	v_mul_f32_e32 v110, v107, v63
	v_fma_f32 v111, -v62, v110, v107
	v_fmac_f32_e32 v110, v111, v63
	v_fma_f32 v62, -v62, v110, v107
	v_div_fmas_f32 v62, v62, v63, v110
	v_div_fixup_f32 v61, v62, v61, 1.0
	v_bfe_u32 v62, v61, 16, 1
	v_add_u32_e32 v55, 0x550, v55
	v_add3_u32 v62, v61, v62, s78
	v_lshl_add_u32 v61, v106, 1, v55
	ds_write_b16_d16_hi v61, v62
	v_add3_u32 v62, s84, v96, 57
	s_and_b64 vcc, exec, s[6:7]
	v_cmp_lt_i32_e64 s[36:37], s76, v62
	v_mul_f32_e32 v62, 0xbfb8aa3b, v13
	v_exp_f32_e32 v62, v62
	s_nop 0
	v_add_f32_e32 v62, 1.0, v62
	v_div_scale_f32 v63, s[38:39], v62, v62, 1.0
	v_rcp_f32_e32 v107, v63
	v_div_scale_f32 v110, vcc, 1.0, v62, 1.0
	v_fma_f32 v111, -v63, v107, 1.0
	v_fmac_f32_e32 v107, v111, v107
	v_mul_f32_e32 v111, v110, v107
	v_fma_f32 v112, -v63, v111, v110
	v_fmac_f32_e32 v111, v112, v107
	v_fma_f32 v63, -v63, v111, v110
	v_div_fmas_f32 v63, v63, v107, v111
	v_div_fixup_f32 v62, v63, v62, 1.0
	v_bfe_u32 v63, v62, 16, 1
	v_add_u32_e32 v55, 0x110, v55
	v_add3_u32 v63, v62, v63, s78
	v_lshl_add_u32 v62, v106, 1, v55
	ds_write_b16_d16_hi v62, v63
	v_add3_u32 v63, s84, v96, 58
	s_and_b64 vcc, exec, s[6:7]
	v_cmp_lt_i32_e64 s[38:39], s76, v63
	v_mul_f32_e32 v63, 0xbfb8aa3b, v14
	v_exp_f32_e32 v63, v63
	s_nop 0
	v_add_f32_e32 v63, 1.0, v63
	v_div_scale_f32 v107, s[40:41], v63, v63, 1.0
	v_rcp_f32_e32 v110, v107
	v_div_scale_f32 v111, vcc, 1.0, v63, 1.0
	v_fma_f32 v112, -v107, v110, 1.0
	v_fmac_f32_e32 v110, v112, v110
	v_mul_f32_e32 v112, v111, v110
	v_fma_f32 v113, -v107, v112, v111
	v_fmac_f32_e32 v112, v113, v110
	v_fma_f32 v107, -v107, v112, v111
	v_div_fmas_f32 v107, v107, v110, v112
	v_div_fixup_f32 v63, v107, v63, 1.0
	v_bfe_u32 v107, v63, 16, 1
	v_add_u32_e32 v55, 0x110, v55
	v_add3_u32 v63, v63, v107, s78
	v_lshl_add_u32 v55, v106, 1, v55
	ds_write_b16_d16_hi v55, v63
	v_add3_u32 v63, s84, v96, 59
	s_and_b64 vcc, exec, s[6:7]
	v_cmp_lt_i32_e64 s[40:41], s76, v63
	v_mul_f32_e32 v63, 0xbfb8aa3b, v15
	v_exp_f32_e32 v63, v63
	s_nop 0
	v_add_f32_e32 v63, 1.0, v63
	v_div_scale_f32 v96, vcc, v63, v63, 1.0
	v_rcp_f32_e32 v106, v96
	v_div_scale_f32 v107, vcc, 1.0, v63, 1.0
	v_fma_f32 v110, -v96, v106, 1.0
	v_fmac_f32_e32 v106, v110, v106
	v_mul_f32_e32 v110, v107, v106
	v_fma_f32 v111, -v96, v110, v107
	v_fmac_f32_e32 v110, v111, v106
	v_fma_f32 v96, -v96, v110, v107
	v_div_fmas_f32 v96, v96, v106, v110
	v_div_fixup_f32 v63, v96, v63, 1.0
	v_bfe_u32 v96, v63, 16, 1
	v_add3_u32 v63, v63, v96, s78
	ds_write_b16_d16_hi v55, v63 offset:272
	s_and_b64 vcc, exec, s[6:7]
	v_mul_f32_e32 v32, 0xbfb8aa3b, v32
	v_exp_f32_e32 v32, v32
	s_nop 0
	v_add_f32_e32 v32, 1.0, v32
	v_div_scale_f32 v63, s[8:9], v32, v32, 1.0
	v_rcp_f32_e32 v96, v63
	v_div_scale_f32 v106, vcc, 1.0, v32, 1.0
	v_fma_f32 v107, -v63, v96, 1.0
	v_fmac_f32_e32 v96, v107, v96
	v_mul_f32_e32 v107, v106, v96
	v_fma_f32 v110, -v63, v107, v106
	v_fmac_f32_e32 v107, v110, v96
	v_fma_f32 v63, -v63, v107, v106
	v_div_fmas_f32 v63, v63, v96, v107
	v_div_fixup_f32 v32, v63, v32, 1.0
	v_bfe_u32 v63, v32, 16, 1
	v_add3_u32 v32, v32, v63, s78
	s_and_b64 vcc, exec, s[6:7]
	ds_write_b16_d16_hi v48, v32 offset:64
	v_mul_f32_e32 v32, 0xbfb8aa3b, v33
	v_exp_f32_e32 v32, v32
	s_nop 0
	v_add_f32_e32 v32, 1.0, v32
; __device__ __forceinline__ bf16r f2bf(float f) {
;   unsigned u = __float_as_uint(f);
;   u += 0x7fffu + ((u >> 16) & 1u);
;   return (bf16r)(u >> 16);
; }
; __device__ __forceinline__ unsigned pack2(float a, float b) { return (unsigned)f2bf(a) | ((unsigned)f2bf(b) << 16); }
; __device__ __forceinline__ float lo16(unsigned v) { return __uint_as_float(v << 16); }
; __device__ __forceinline__ float hi16(unsigned v) { return __uint_as_float(v & 0xffff0000u); }
; __device__ __forceinline__ float siluf(float x) { return x / (1.f + __expf(-x)); }
; __device__ __forceinline__ float sigmf(float x) { return 1.f / (1.f + __expf(-x)); }
; __device__ __forceinline__ void inproj_epilogue(const Params& p, int layer, int mt, int ntile, int tid,
;                                                 f32x16 (&acc)[2][2], unsigned char* smem) {
;     ...
;     acc_foreach(tid, acc, [&](int row, int col, float v) {
;       int t = m0 + row;
;       float o = v;
;       if (mode == 1) o = (t >= NPADR) ? v : 0.f;
;       if (mode == 2) o = sigmf(v);
;       sT[row * 136 + col] = f2bf(o);
;     });
	v_div_scale_f32 v33, s[8:9], v32, v32, 1.0
	v_rcp_f32_e32 v48, v33
	v_div_scale_f32 v63, vcc, 1.0, v32, 1.0
	v_fma_f32 v96, -v33, v48, 1.0
	v_fmac_f32_e32 v48, v96, v48
	v_mul_f32_e32 v96, v63, v48
	v_fma_f32 v106, -v33, v96, v63
	v_fmac_f32_e32 v96, v106, v48
	v_fma_f32 v33, -v33, v96, v63
	v_div_fmas_f32 v33, v33, v48, v96
	v_div_fixup_f32 v32, v33, v32, 1.0
	v_bfe_u32 v33, v32, 16, 1
	v_add3_u32 v32, v32, v33, s78
	s_and_b64 vcc, exec, s[6:7]
	ds_write_b16_d16_hi v49, v32 offset:64
	v_mul_f32_e32 v32, 0xbfb8aa3b, v34
	v_exp_f32_e32 v32, v32
	s_nop 0
	v_add_f32_e32 v32, 1.0, v32
	v_div_scale_f32 v33, s[8:9], v32, v32, 1.0
	v_rcp_f32_e32 v34, v33
	v_div_scale_f32 v48, vcc, 1.0, v32, 1.0
	v_fma_f32 v49, -v33, v34, 1.0
	v_fmac_f32_e32 v34, v49, v34
	v_mul_f32_e32 v49, v48, v34
	v_fma_f32 v63, -v33, v49, v48
	v_fmac_f32_e32 v49, v63, v34
	v_fma_f32 v33, -v33, v49, v48
	v_div_fmas_f32 v33, v33, v34, v49
	v_div_fixup_f32 v32, v33, v32, 1.0
	v_bfe_u32 v33, v32, 16, 1
	v_add3_u32 v32, v32, v33, s78
	s_and_b64 vcc, exec, s[6:7]
	ds_write_b16_d16_hi v50, v32 offset:64
	v_mul_f32_e32 v32, 0xbfb8aa3b, v35
	v_exp_f32_e32 v32, v32
	s_nop 0
	v_add_f32_e32 v32, 1.0, v32
	v_div_scale_f32 v33, s[8:9], v32, v32, 1.0
	v_rcp_f32_e32 v34, v33
	v_div_scale_f32 v35, vcc, 1.0, v32, 1.0
	v_fma_f32 v48, -v33, v34, 1.0
	v_fmac_f32_e32 v34, v48, v34
	v_mul_f32_e32 v48, v35, v34
	v_fma_f32 v49, -v33, v48, v35
	v_fmac_f32_e32 v48, v49, v34
	v_fma_f32 v33, -v33, v48, v35
	v_div_fmas_f32 v33, v33, v34, v48
	v_div_fixup_f32 v32, v33, v32, 1.0
	v_bfe_u32 v33, v32, 16, 1
	v_add3_u32 v32, v32, v33, s78
	s_and_b64 vcc, exec, s[6:7]
	ds_write_b16_d16_hi v51, v32 offset:64
	v_mul_f32_e32 v32, 0xbfb8aa3b, v36
	v_exp_f32_e32 v32, v32
	s_nop 0
	v_add_f32_e32 v32, 1.0, v32
	v_div_scale_f32 v33, s[8:9], v32, v32, 1.0
	v_rcp_f32_e32 v34, v33
	v_div_scale_f32 v35, vcc, 1.0, v32, 1.0
	v_fma_f32 v36, -v33, v34, 1.0
	v_fmac_f32_e32 v34, v36, v34
	v_mul_f32_e32 v36, v35, v34
	v_fma_f32 v48, -v33, v36, v35
	v_fmac_f32_e32 v36, v48, v34
	v_fma_f32 v33, -v33, v36, v35
	v_div_fmas_f32 v33, v33, v34, v36
	v_div_fixup_f32 v32, v33, v32, 1.0
	v_bfe_u32 v33, v32, 16, 1
	v_add3_u32 v32, v32, v33, s78
	s_and_b64 vcc, exec, s[6:7]
	ds_write_b16_d16_hi v52, v32 offset:64
	v_mul_f32_e32 v32, 0xbfb8aa3b, v37
	v_exp_f32_e32 v32, v32
	s_nop 0
	v_add_f32_e32 v32, 1.0, v32
	v_div_scale_f32 v33, s[8:9], v32, v32, 1.0
	v_rcp_f32_e32 v34, v33
	v_div_scale_f32 v35, vcc, 1.0, v32, 1.0
	v_fma_f32 v36, -v33, v34, 1.0
	v_fmac_f32_e32 v34, v36, v34
	v_mul_f32_e32 v36, v35, v34
	v_fma_f32 v37, -v33, v36, v35
	v_fmac_f32_e32 v36, v37, v34
	v_fma_f32 v33, -v33, v36, v35
	v_div_fmas_f32 v33, v33, v34, v36
	v_div_fixup_f32 v32, v33, v32, 1.0
	v_bfe_u32 v33, v32, 16, 1
	v_add3_u32 v32, v32, v33, s78
	s_and_b64 vcc, exec, s[6:7]
	ds_write_b16_d16_hi v53, v32 offset:64
	v_mul_f32_e32 v32, 0xbfb8aa3b, v38
	v_exp_f32_e32 v32, v32
	s_nop 0
	v_add_f32_e32 v32, 1.0, v32
	v_div_scale_f32 v33, s[8:9], v32, v32, 1.0
	v_rcp_f32_e32 v34, v33
	v_div_scale_f32 v35, vcc, 1.0, v32, 1.0
	v_fma_f32 v36, -v33, v34, 1.0
	v_fmac_f32_e32 v34, v36, v34
	v_mul_f32_e32 v36, v35, v34
	v_fma_f32 v37, -v33, v36, v35
	v_fmac_f32_e32 v36, v37, v34
	v_fma_f32 v33, -v33, v36, v35
	v_div_fmas_f32 v33, v33, v34, v36
	v_div_fixup_f32 v32, v33, v32, 1.0
	v_bfe_u32 v33, v32, 16, 1
	v_add3_u32 v32, v32, v33, s78
	s_and_b64 vcc, exec, s[6:7]
	ds_write_b16_d16_hi v54, v32 offset:64
	v_mul_f32_e32 v32, 0xbfb8aa3b, v39
	v_exp_f32_e32 v32, v32
	s_nop 0
	v_add_f32_e32 v32, 1.0, v32
	v_div_scale_f32 v33, s[8:9], v32, v32, 1.0
	v_rcp_f32_e32 v34, v33
	v_div_scale_f32 v35, vcc, 1.0, v32, 1.0
	v_fma_f32 v36, -v33, v34, 1.0
	v_fmac_f32_e32 v34, v36, v34
	v_mul_f32_e32 v36, v35, v34
	v_fma_f32 v37, -v33, v36, v35
	v_fmac_f32_e32 v36, v37, v34
	v_fma_f32 v33, -v33, v36, v35
	v_div_fmas_f32 v33, v33, v34, v36
	v_div_fixup_f32 v32, v33, v32, 1.0
	v_bfe_u32 v33, v32, 16, 1
	v_add3_u32 v32, v32, v33, s78
	s_and_b64 vcc, exec, s[6:7]
	ds_write_b16_d16_hi v56, v32 offset:64
	v_mul_f32_e32 v32, 0xbfb8aa3b, v40
	v_exp_f32_e32 v32, v32
	s_nop 0
	v_add_f32_e32 v32, 1.0, v32
	v_div_scale_f32 v33, s[8:9], v32, v32, 1.0
	v_rcp_f32_e32 v34, v33
	v_div_scale_f32 v35, vcc, 1.0, v32, 1.0
	v_fma_f32 v36, -v33, v34, 1.0
	v_fmac_f32_e32 v34, v36, v34
	v_mul_f32_e32 v36, v35, v34
; __device__ __forceinline__ bf16r f2bf(float f) {
;   unsigned u = __float_as_uint(f);
;   u += 0x7fffu + ((u >> 16) & 1u);
;   return (bf16r)(u >> 16);
; }
; __device__ __forceinline__ unsigned pack2(float a, float b) { return (unsigned)f2bf(a) | ((unsigned)f2bf(b) << 16); }
; __device__ __forceinline__ float lo16(unsigned v) { return __uint_as_float(v << 16); }
; __device__ __forceinline__ float hi16(unsigned v) { return __uint_as_float(v & 0xffff0000u); }
; __device__ __forceinline__ float siluf(float x) { return x / (1.f + __expf(-x)); }
; __device__ __forceinline__ float sigmf(float x) { return 1.f / (1.f + __expf(-x)); }
; __device__ __forceinline__ void inproj_epilogue(const Params& p, int layer, int mt, int ntile, int tid,
;                                                 f32x16 (&acc)[2][2], unsigned char* smem) {
;     ...
;     acc_foreach(tid, acc, [&](int row, int col, float v) {
;       int t = m0 + row;
;       float o = v;
;       if (mode == 1) o = (t >= NPADR) ? v : 0.f;
;       if (mode == 2) o = sigmf(v);
;       sT[row * 136 + col] = f2bf(o);
;     });
	v_fma_f32 v37, -v33, v36, v35
	v_fmac_f32_e32 v36, v37, v34
	v_fma_f32 v33, -v33, v36, v35
	v_div_fmas_f32 v33, v33, v34, v36
	v_div_fixup_f32 v32, v33, v32, 1.0
	v_bfe_u32 v33, v32, 16, 1
	v_add3_u32 v32, v32, v33, s78
	s_and_b64 vcc, exec, s[6:7]
	ds_write_b16_d16_hi v57, v32 offset:64
	v_mul_f32_e32 v32, 0xbfb8aa3b, v41
	v_exp_f32_e32 v32, v32
	s_nop 0
	v_add_f32_e32 v32, 1.0, v32
	v_div_scale_f32 v33, s[8:9], v32, v32, 1.0
	v_rcp_f32_e32 v34, v33
	v_div_scale_f32 v35, vcc, 1.0, v32, 1.0
	v_fma_f32 v36, -v33, v34, 1.0
	v_fmac_f32_e32 v34, v36, v34
	v_mul_f32_e32 v36, v35, v34
	v_fma_f32 v37, -v33, v36, v35
	v_fmac_f32_e32 v36, v37, v34
	v_fma_f32 v33, -v33, v36, v35
	v_div_fmas_f32 v33, v33, v34, v36
	v_div_fixup_f32 v32, v33, v32, 1.0
	v_bfe_u32 v33, v32, 16, 1
	v_add3_u32 v32, v32, v33, s78
	s_and_b64 vcc, exec, s[6:7]
	ds_write_b16_d16_hi v58, v32 offset:64
	v_mul_f32_e32 v32, 0xbfb8aa3b, v42
	v_exp_f32_e32 v32, v32
	s_nop 0
	v_add_f32_e32 v32, 1.0, v32
	v_div_scale_f32 v33, s[8:9], v32, v32, 1.0
	v_rcp_f32_e32 v34, v33
	v_div_scale_f32 v35, vcc, 1.0, v32, 1.0
	v_fma_f32 v36, -v33, v34, 1.0
	v_fmac_f32_e32 v34, v36, v34
	v_mul_f32_e32 v36, v35, v34
	v_fma_f32 v37, -v33, v36, v35
	v_fmac_f32_e32 v36, v37, v34
	v_fma_f32 v33, -v33, v36, v35
	v_div_fmas_f32 v33, v33, v34, v36
	v_div_fixup_f32 v32, v33, v32, 1.0
	v_bfe_u32 v33, v32, 16, 1
	v_add3_u32 v32, v32, v33, s78
	s_and_b64 vcc, exec, s[6:7]
	ds_write_b16_d16_hi v59, v32 offset:64
	v_mul_f32_e32 v32, 0xbfb8aa3b, v43
	v_exp_f32_e32 v32, v32
	s_nop 0
	v_add_f32_e32 v32, 1.0, v32
	v_div_scale_f32 v33, s[8:9], v32, v32, 1.0
	v_rcp_f32_e32 v34, v33
	v_div_scale_f32 v35, vcc, 1.0, v32, 1.0
	v_fma_f32 v36, -v33, v34, 1.0
	v_fmac_f32_e32 v34, v36, v34
	v_mul_f32_e32 v36, v35, v34
	v_fma_f32 v37, -v33, v36, v35
	v_fmac_f32_e32 v36, v37, v34
	v_fma_f32 v33, -v33, v36, v35
	v_div_fmas_f32 v33, v33, v34, v36
	v_div_fixup_f32 v32, v33, v32, 1.0
	v_bfe_u32 v33, v32, 16, 1
	v_add3_u32 v32, v32, v33, s78
	s_and_b64 vcc, exec, s[6:7]
	ds_write_b16_d16_hi v60, v32 offset:64
	v_mul_f32_e32 v32, 0xbfb8aa3b, v44
	v_exp_f32_e32 v32, v32
	s_nop 0
	v_add_f32_e32 v32, 1.0, v32
	v_div_scale_f32 v33, s[8:9], v32, v32, 1.0
	v_rcp_f32_e32 v34, v33
	v_div_scale_f32 v35, vcc, 1.0, v32, 1.0
	v_fma_f32 v36, -v33, v34, 1.0
	v_fmac_f32_e32 v34, v36, v34
	v_mul_f32_e32 v36, v35, v34
	v_fma_f32 v37, -v33, v36, v35
	v_fmac_f32_e32 v36, v37, v34
	v_fma_f32 v33, -v33, v36, v35
	v_div_fmas_f32 v33, v33, v34, v36
	v_div_fixup_f32 v32, v33, v32, 1.0
	v_bfe_u32 v33, v32, 16, 1
	v_add3_u32 v32, v32, v33, s78
	s_and_b64 vcc, exec, s[6:7]
	ds_write_b16_d16_hi v61, v32 offset:64
	v_mul_f32_e32 v32, 0xbfb8aa3b, v45
	v_exp_f32_e32 v32, v32
	s_nop 0
	v_add_f32_e32 v32, 1.0, v32
	v_div_scale_f32 v33, s[8:9], v32, v32, 1.0
	v_rcp_f32_e32 v34, v33
	v_div_scale_f32 v35, vcc, 1.0, v32, 1.0
	v_fma_f32 v36, -v33, v34, 1.0
	v_fmac_f32_e32 v34, v36, v34
	v_mul_f32_e32 v36, v35, v34
	v_fma_f32 v37, -v33, v36, v35
	v_fmac_f32_e32 v36, v37, v34
	v_fma_f32 v33, -v33, v36, v35
	v_div_fmas_f32 v33, v33, v34, v36
	v_div_fixup_f32 v32, v33, v32, 1.0
	v_bfe_u32 v33, v32, 16, 1
	v_add3_u32 v32, v32, v33, s78
	s_and_b64 vcc, exec, s[6:7]
	ds_write_b16_d16_hi v62, v32 offset:64
	v_mul_f32_e32 v32, 0xbfb8aa3b, v46
	v_exp_f32_e32 v32, v32
	s_nop 0
	v_add_f32_e32 v32, 1.0, v32
	v_div_scale_f32 v33, s[8:9], v32, v32, 1.0
	v_rcp_f32_e32 v34, v33
	v_div_scale_f32 v35, vcc, 1.0, v32, 1.0
	v_fma_f32 v36, -v33, v34, 1.0
	v_fmac_f32_e32 v34, v36, v34
	v_mul_f32_e32 v36, v35, v34
	v_fma_f32 v37, -v33, v36, v35
	v_fmac_f32_e32 v36, v37, v34
	v_fma_f32 v33, -v33, v36, v35
	v_div_fmas_f32 v33, v33, v34, v36
	v_div_fixup_f32 v32, v33, v32, 1.0
	v_bfe_u32 v33, v32, 16, 1
	v_add3_u32 v32, v32, v33, s78
	s_and_b64 vcc, exec, s[6:7]
	ds_write_b16_d16_hi v55, v32 offset:64
	v_mul_f32_e32 v32, 0xbfb8aa3b, v47
	v_exp_f32_e32 v32, v32
	s_nop 0
	v_add_f32_e32 v32, 1.0, v32
	v_div_scale_f32 v33, s[4:5], v32, v32, 1.0
	v_rcp_f32_e32 v34, v33
	v_div_scale_f32 v35, vcc, 1.0, v32, 1.0
	v_fma_f32 v36, -v33, v34, 1.0
	v_fmac_f32_e32 v34, v36, v34
	v_mul_f32_e32 v36, v35, v34
	v_fma_f32 v37, -v33, v36, v35
	v_fmac_f32_e32 v36, v37, v34
	v_fma_f32 v33, -v33, v36, v35
	v_div_fmas_f32 v33, v33, v34, v36
	v_div_fixup_f32 v32, v33, v32, 1.0
	s_branch .LBB0_2226

; __device__ __forceinline__ float sigmf(float x) { return 1.f / (1.f + __expf(-x)); }
; __device__ __forceinline__ bf16r f2bf(float f) {
;   unsigned u = __float_as_uint(f);
;   u += 0x7fffu + ((u >> 16) & 1u);
;   return (bf16r)(u >> 16);
; }
; __device__ __forceinline__ void inproj_epilogue(const Params& p, int layer, int mt, int ntile, int tid,
;                                                 f32x16 (&acc)[2][2], unsigned char* smem) {
;     ...
;     acc_foreach(tid, acc, [&](int row, int col, float v) {
;       int t = m0 + row;
;       float o = v;
;       if (mode == 1) o = (t >= NPADR) ? v : 0.f;
;       if (mode == 2) o = sigmf(v);
;       sT[row * 136 + col] = f2bf(o);
;     });
.LBB0_2717:
	v_bfe_u32 v110, v107, 16, 1
	v_and_b32_e32 v106, 0x5f, v106
	v_add3_u32 v111, v107, v110, s81
	v_mul_lo_u32 v110, v96, s82
	v_lshl_add_u32 v107, v106, 1, v110
	ds_write_b16_d16_hi v107, v111
	v_add3_u32 v111, s96, v96, 1
	v_cndmask_b32_e64 v112, 0, 1, s[10:11]
	v_cmp_ne_u32_e64 s[6:7], 1, v112
	v_cmp_lt_i32_e64 s[10:11], s79, v111
	s_nop 1

; __device__ __forceinline__ float sigmf(float x) { return 1.f / (1.f + __expf(-x)); }
; __device__ __forceinline__ bf16r f2bf(float f) {
;   unsigned u = __float_as_uint(f);
;   u += 0x7fffu + ((u >> 16) & 1u);
;   return (bf16r)(u >> 16);
; }
; __device__ __forceinline__ void inproj_epilogue(const Params& p, int layer, int mt, int ntile, int tid,
;                                                 f32x16 (&acc)[2][2], unsigned char* smem) {
;     ...
;     acc_foreach(tid, acc, [&](int row, int col, float v) {
;       int t = m0 + row;
;       float o = v;
;       if (mode == 1) o = (t >= NPADR) ? v : 0.f;
;       if (mode == 2) o = sigmf(v);
;       sT[row * 136 + col] = f2bf(o);
;     });
.LBB0_2720:
	v_bfe_u32 v112, v111, 16, 1
	v_add3_u32 v112, v111, v112, s81
	v_add_u32_e32 v111, 0x110, v110
	v_lshl_add_u32 v110, v106, 1, v111
	ds_write_b16_d16_hi v110, v112
	v_add3_u32 v112, s96, v96, 2
	v_cmp_lt_i32_e64 s[12:13], s79, v112
	s_nop 1

; __device__ __forceinline__ float sigmf(float x) { return 1.f / (1.f + __expf(-x)); }
; __device__ __forceinline__ bf16r f2bf(float f) {
;   unsigned u = __float_as_uint(f);
;   u += 0x7fffu + ((u >> 16) & 1u);
;   return (bf16r)(u >> 16);
; }
; __device__ __forceinline__ void inproj_epilogue(const Params& p, int layer, int mt, int ntile, int tid,
;                                                 f32x16 (&acc)[2][2], unsigned char* smem) {
;     ...
;     acc_foreach(tid, acc, [&](int row, int col, float v) {
;       int t = m0 + row;
;       float o = v;
;       if (mode == 1) o = (t >= NPADR) ? v : 0.f;
;       if (mode == 2) o = sigmf(v);
;       sT[row * 136 + col] = f2bf(o);
;     });
.LBB0_2723:
	v_bfe_u32 v113, v112, 16, 1
	v_add3_u32 v113, v112, v113, s81
	v_add_u32_e32 v112, 0x110, v111
	v_lshl_add_u32 v111, v106, 1, v112
	ds_write_b16_d16_hi v111, v113
	v_add3_u32 v113, s96, v96, 3
	v_cmp_lt_i32_e64 s[14:15], s79, v113
	s_nop 1

; __device__ __forceinline__ float sigmf(float x) { return 1.f / (1.f + __expf(-x)); }
; __device__ __forceinline__ bf16r f2bf(float f) {
;   unsigned u = __float_as_uint(f);
;   u += 0x7fffu + ((u >> 16) & 1u);
;   return (bf16r)(u >> 16);
; }
; __device__ __forceinline__ void inproj_epilogue(const Params& p, int layer, int mt, int ntile, int tid,
;                                                 f32x16 (&acc)[2][2], unsigned char* smem) {
;     ...
;     acc_foreach(tid, acc, [&](int row, int col, float v) {
;       int t = m0 + row;
;       float o = v;
;       if (mode == 1) o = (t >= NPADR) ? v : 0.f;
;       if (mode == 2) o = sigmf(v);
;       sT[row * 136 + col] = f2bf(o);
;     });
.LBB0_2726:
	v_bfe_u32 v114, v113, 16, 1
	v_add3_u32 v114, v113, v114, s81
	v_add_u32_e32 v113, 0x110, v112
	v_lshl_add_u32 v112, v106, 1, v113
	ds_write_b16_d16_hi v112, v114
	v_add3_u32 v114, s96, v96, 8
	v_cmp_lt_i32_e64 s[16:17], s79, v114
	s_nop 1

; __device__ __forceinline__ float sigmf(float x) { return 1.f / (1.f + __expf(-x)); }
; __device__ __forceinline__ bf16r f2bf(float f) {
;   unsigned u = __float_as_uint(f);
;   u += 0x7fffu + ((u >> 16) & 1u);
;   return (bf16r)(u >> 16);
; }
; __device__ __forceinline__ void inproj_epilogue(const Params& p, int layer, int mt, int ntile, int tid,
;                                                 f32x16 (&acc)[2][2], unsigned char* smem) {
;     ...
;     acc_foreach(tid, acc, [&](int row, int col, float v) {
;       int t = m0 + row;
;       float o = v;
;       if (mode == 1) o = (t >= NPADR) ? v : 0.f;
;       if (mode == 2) o = sigmf(v);
;       sT[row * 136 + col] = f2bf(o);
;     });
.LBB0_2729:
	v_bfe_u32 v115, v114, 16, 1
	v_add3_u32 v115, v114, v115, s81
	v_add_u32_e32 v114, 0x550, v113
	v_lshl_add_u32 v113, v106, 1, v114
	ds_write_b16_d16_hi v113, v115
	v_add3_u32 v115, s96, v96, 9
	v_cmp_lt_i32_e64 s[18:19], s79, v115
	s_nop 1

; __device__ __forceinline__ float sigmf(float x) { return 1.f / (1.f + __expf(-x)); }
; __device__ __forceinline__ bf16r f2bf(float f) {
;   unsigned u = __float_as_uint(f);
;   u += 0x7fffu + ((u >> 16) & 1u);
;   return (bf16r)(u >> 16);
; }
; __device__ __forceinline__ void inproj_epilogue(const Params& p, int layer, int mt, int ntile, int tid,
;                                                 f32x16 (&acc)[2][2], unsigned char* smem) {
;     ...
;     acc_foreach(tid, acc, [&](int row, int col, float v) {
;       int t = m0 + row;
;       float o = v;
;       if (mode == 1) o = (t >= NPADR) ? v : 0.f;
;       if (mode == 2) o = sigmf(v);
;       sT[row * 136 + col] = f2bf(o);
;     });
.LBB0_2732:
	v_bfe_u32 v116, v115, 16, 1
	v_add3_u32 v116, v115, v116, s81
	v_add_u32_e32 v115, 0x110, v114
	v_lshl_add_u32 v114, v106, 1, v115
	ds_write_b16_d16_hi v114, v116
	v_add3_u32 v116, s96, v96, 10
	v_cmp_lt_i32_e64 s[20:21], s79, v116
	s_nop 1

; __device__ __forceinline__ float sigmf(float x) { return 1.f / (1.f + __expf(-x)); }
; __device__ __forceinline__ bf16r f2bf(float f) {
;   unsigned u = __float_as_uint(f);
;   u += 0x7fffu + ((u >> 16) & 1u);
;   return (bf16r)(u >> 16);
; }
; __device__ __forceinline__ void inproj_epilogue(const Params& p, int layer, int mt, int ntile, int tid,
;                                                 f32x16 (&acc)[2][2], unsigned char* smem) {
;     ...
;     acc_foreach(tid, acc, [&](int row, int col, float v) {
;       int t = m0 + row;
;       float o = v;
;       if (mode == 1) o = (t >= NPADR) ? v : 0.f;
;       if (mode == 2) o = sigmf(v);
;       sT[row * 136 + col] = f2bf(o);
;     });
.LBB0_2735:
	v_bfe_u32 v117, v116, 16, 1
	v_add3_u32 v117, v116, v117, s81
	v_add_u32_e32 v116, 0x110, v115
	v_lshl_add_u32 v115, v106, 1, v116
	ds_write_b16_d16_hi v115, v117
	v_add3_u32 v117, s96, v96, 11
	v_cmp_lt_i32_e64 s[22:23], s79, v117
	s_nop 1

; __device__ __forceinline__ float sigmf(float x) { return 1.f / (1.f + __expf(-x)); }
; __device__ __forceinline__ bf16r f2bf(float f) {
;   unsigned u = __float_as_uint(f);
;   u += 0x7fffu + ((u >> 16) & 1u);
;   return (bf16r)(u >> 16);
; }
; __device__ __forceinline__ void inproj_epilogue(const Params& p, int layer, int mt, int ntile, int tid,
;                                                 f32x16 (&acc)[2][2], unsigned char* smem) {
;     ...
;     acc_foreach(tid, acc, [&](int row, int col, float v) {
;       int t = m0 + row;
;       float o = v;
;       if (mode == 1) o = (t >= NPADR) ? v : 0.f;
;       if (mode == 2) o = sigmf(v);
;       sT[row * 136 + col] = f2bf(o);
;     });
.LBB0_2738:
	v_bfe_u32 v118, v117, 16, 1
	v_add_u32_e32 v116, 0x110, v116
	v_add3_u32 v118, v117, v118, s81
	v_lshl_add_u32 v117, v106, 1, v116
	ds_write_b16_d16_hi v117, v118
	v_add3_u32 v118, s96, v96, 16
	v_cmp_lt_i32_e64 s[24:25], s79, v118
	s_nop 1

; __device__ __forceinline__ float sigmf(float x) { return 1.f / (1.f + __expf(-x)); }
; __device__ __forceinline__ bf16r f2bf(float f) {
;   unsigned u = __float_as_uint(f);
;   u += 0x7fffu + ((u >> 16) & 1u);
;   return (bf16r)(u >> 16);
; }
; __device__ __forceinline__ void inproj_epilogue(const Params& p, int layer, int mt, int ntile, int tid,
;                                                 f32x16 (&acc)[2][2], unsigned char* smem) {
;     ...
;     acc_foreach(tid, acc, [&](int row, int col, float v) {
;       int t = m0 + row;
;       float o = v;
;       if (mode == 1) o = (t >= NPADR) ? v : 0.f;
;       if (mode == 2) o = sigmf(v);
;       sT[row * 136 + col] = f2bf(o);
;     });
.LBB0_2741:
	v_bfe_u32 v119, v118, 16, 1
	v_add_u32_e32 v116, 0x550, v116
	v_add3_u32 v119, v118, v119, s81
	v_lshl_add_u32 v118, v106, 1, v116
	ds_write_b16_d16_hi v118, v119
	v_add3_u32 v119, s96, v96, 17
	v_cmp_lt_i32_e64 s[26:27], s79, v119
	s_nop 1

; __device__ __forceinline__ float sigmf(float x) { return 1.f / (1.f + __expf(-x)); }
; __device__ __forceinline__ bf16r f2bf(float f) {
;   unsigned u = __float_as_uint(f);
;   u += 0x7fffu + ((u >> 16) & 1u);
;   return (bf16r)(u >> 16);
; }
; __device__ __forceinline__ void inproj_epilogue(const Params& p, int layer, int mt, int ntile, int tid,
;                                                 f32x16 (&acc)[2][2], unsigned char* smem) {
;     ...
;     acc_foreach(tid, acc, [&](int row, int col, float v) {
;       int t = m0 + row;
;       float o = v;
;       if (mode == 1) o = (t >= NPADR) ? v : 0.f;
;       if (mode == 2) o = sigmf(v);
;       sT[row * 136 + col] = f2bf(o);
;     });
.LBB0_2744:
	v_bfe_u32 v120, v119, 16, 1
	v_add_u32_e32 v116, 0x110, v116
	v_add3_u32 v120, v119, v120, s81
	v_lshl_add_u32 v119, v106, 1, v116
	ds_write_b16_d16_hi v119, v120
	v_add3_u32 v120, s96, v96, 18
	v_cmp_lt_i32_e64 s[28:29], s79, v120
	s_nop 1

; __device__ __forceinline__ float sigmf(float x) { return 1.f / (1.f + __expf(-x)); }
; __device__ __forceinline__ bf16r f2bf(float f) {
;   unsigned u = __float_as_uint(f);
;   u += 0x7fffu + ((u >> 16) & 1u);
;   return (bf16r)(u >> 16);
; }
; __device__ __forceinline__ void inproj_epilogue(const Params& p, int layer, int mt, int ntile, int tid,
;                                                 f32x16 (&acc)[2][2], unsigned char* smem) {
;     ...
;     acc_foreach(tid, acc, [&](int row, int col, float v) {
;       int t = m0 + row;
;       float o = v;
;       if (mode == 1) o = (t >= NPADR) ? v : 0.f;
;       if (mode == 2) o = sigmf(v);
;       sT[row * 136 + col] = f2bf(o);
;     });
.LBB0_2747:
	v_bfe_u32 v121, v120, 16, 1
	v_add_u32_e32 v116, 0x110, v116
	v_add3_u32 v121, v120, v121, s81
	v_lshl_add_u32 v120, v106, 1, v116
	ds_write_b16_d16_hi v120, v121
	v_add3_u32 v121, s96, v96, 19
	v_cmp_lt_i32_e64 s[30:31], s79, v121
	s_nop 1

; __device__ __forceinline__ float sigmf(float x) { return 1.f / (1.f + __expf(-x)); }
; __device__ __forceinline__ bf16r f2bf(float f) {
;   unsigned u = __float_as_uint(f);
;   u += 0x7fffu + ((u >> 16) & 1u);
;   return (bf16r)(u >> 16);
; }
; __device__ __forceinline__ void inproj_epilogue(const Params& p, int layer, int mt, int ntile, int tid,
;                                                 f32x16 (&acc)[2][2], unsigned char* smem) {
;     ...
;     acc_foreach(tid, acc, [&](int row, int col, float v) {
;       int t = m0 + row;
;       float o = v;
;       if (mode == 1) o = (t >= NPADR) ? v : 0.f;
;       if (mode == 2) o = sigmf(v);
;       sT[row * 136 + col] = f2bf(o);
;     });
.LBB0_2750:
	v_bfe_u32 v122, v121, 16, 1
	v_add_u32_e32 v116, 0x110, v116
	v_add3_u32 v122, v121, v122, s81
	v_lshl_add_u32 v121, v106, 1, v116
	ds_write_b16_d16_hi v121, v122
	v_add3_u32 v122, s96, v96, 24
	v_cmp_lt_i32_e64 s[34:35], s79, v122
	s_nop 1

; __device__ __forceinline__ float sigmf(float x) { return 1.f / (1.f + __expf(-x)); }
; __device__ __forceinline__ bf16r f2bf(float f) {
;   unsigned u = __float_as_uint(f);
;   u += 0x7fffu + ((u >> 16) & 1u);
;   return (bf16r)(u >> 16);
; }
; __device__ __forceinline__ void inproj_epilogue(const Params& p, int layer, int mt, int ntile, int tid,
;                                                 f32x16 (&acc)[2][2], unsigned char* smem) {
;     ...
;     acc_foreach(tid, acc, [&](int row, int col, float v) {
;       int t = m0 + row;
;       float o = v;
;       if (mode == 1) o = (t >= NPADR) ? v : 0.f;
;       if (mode == 2) o = sigmf(v);
;       sT[row * 136 + col] = f2bf(o);
;     });
.LBB0_2753:
	v_bfe_u32 v123, v122, 16, 1
	v_add_u32_e32 v116, 0x550, v116
	v_add3_u32 v123, v122, v123, s81
	v_lshl_add_u32 v122, v106, 1, v116
	ds_write_b16_d16_hi v122, v123
	v_add3_u32 v123, s96, v96, 25
	v_cmp_lt_i32_e64 s[36:37], s79, v123
	s_nop 1

; __device__ __forceinline__ float sigmf(float x) { return 1.f / (1.f + __expf(-x)); }
; __device__ __forceinline__ bf16r f2bf(float f) {
;   unsigned u = __float_as_uint(f);
;   u += 0x7fffu + ((u >> 16) & 1u);
;   return (bf16r)(u >> 16);
; }
; __device__ __forceinline__ void inproj_epilogue(const Params& p, int layer, int mt, int ntile, int tid,
;                                                 f32x16 (&acc)[2][2], unsigned char* smem) {
;     ...
;     acc_foreach(tid, acc, [&](int row, int col, float v) {
;       int t = m0 + row;
;       float o = v;
;       if (mode == 1) o = (t >= NPADR) ? v : 0.f;
;       if (mode == 2) o = sigmf(v);
;       sT[row * 136 + col] = f2bf(o);
;     });
.LBB0_2756:
	v_bfe_u32 v124, v123, 16, 1
	v_add_u32_e32 v116, 0x110, v116
	v_add3_u32 v124, v123, v124, s81
	v_lshl_add_u32 v123, v106, 1, v116
	ds_write_b16_d16_hi v123, v124
	v_add3_u32 v124, s96, v96, 26
	v_cmp_lt_i32_e64 s[38:39], s79, v124
	s_nop 1

; __device__ __forceinline__ float sigmf(float x) { return 1.f / (1.f + __expf(-x)); }
; __device__ __forceinline__ bf16r f2bf(float f) {
;   unsigned u = __float_as_uint(f);
;   u += 0x7fffu + ((u >> 16) & 1u);
;   return (bf16r)(u >> 16);
; }
; __device__ __forceinline__ void inproj_epilogue(const Params& p, int layer, int mt, int ntile, int tid,
;                                                 f32x16 (&acc)[2][2], unsigned char* smem) {
;     ...
;     acc_foreach(tid, acc, [&](int row, int col, float v) {
;       int t = m0 + row;
;       float o = v;
;       if (mode == 1) o = (t >= NPADR) ? v : 0.f;
;       if (mode == 2) o = sigmf(v);
;       sT[row * 136 + col] = f2bf(o);
;     });
.LBB0_2759:
	v_bfe_u32 v125, v124, 16, 1
	v_add_u32_e32 v116, 0x110, v116
	v_add3_u32 v124, v124, v125, s81
	v_lshl_add_u32 v116, v106, 1, v116
	ds_write_b16_d16_hi v116, v124
	v_add3_u32 v124, s96, v96, 27
	v_cmp_lt_i32_e64 s[40:41], s79, v124
	s_nop 1

; __device__ __forceinline__ float sigmf(float x) { return 1.f / (1.f + __expf(-x)); }
; __device__ __forceinline__ bf16r f2bf(float f) {
;   unsigned u = __float_as_uint(f);
;   u += 0x7fffu + ((u >> 16) & 1u);
;   return (bf16r)(u >> 16);
; }
; __device__ __forceinline__ void inproj_epilogue(const Params& p, int layer, int mt, int ntile, int tid,
;                                                 f32x16 (&acc)[2][2], unsigned char* smem) {
;     ...
;     acc_foreach(tid, acc, [&](int row, int col, float v) {
;       int t = m0 + row;
;       float o = v;
;       if (mode == 1) o = (t >= NPADR) ? v : 0.f;
;       if (mode == 2) o = sigmf(v);
;       sT[row * 136 + col] = f2bf(o);
;     });
.LBB0_2762:
	v_bfe_u32 v125, v124, 16, 1
	v_add3_u32 v124, v124, v125, s81
	ds_write_b16_d16_hi v116, v124 offset:272
	s_nop 1

; __device__ __forceinline__ float sigmf(float x) { return 1.f / (1.f + __expf(-x)); }
; __device__ __forceinline__ bf16r f2bf(float f) {
;   unsigned u = __float_as_uint(f);
;   u += 0x7fffu + ((u >> 16) & 1u);
;   return (bf16r)(u >> 16);
; }
; __device__ __forceinline__ void inproj_epilogue(const Params& p, int layer, int mt, int ntile, int tid,
;                                                 f32x16 (&acc)[2][2], unsigned char* smem) {
;     ...
;     acc_foreach(tid, acc, [&](int row, int col, float v) {
;       int t = m0 + row;
;       float o = v;
;       if (mode == 1) o = (t >= NPADR) ? v : 0.f;
;       if (mode == 2) o = sigmf(v);
;       sT[row * 136 + col] = f2bf(o);
;     });
.LBB0_2765:
	v_bfe_u32 v124, v48, 16, 1
	v_add3_u32 v48, v48, v124, s81
	ds_write_b16_d16_hi v107, v48 offset:64
	s_nop 1

; __device__ __forceinline__ float sigmf(float x) { return 1.f / (1.f + __expf(-x)); }
; __device__ __forceinline__ bf16r f2bf(float f) {
;   unsigned u = __float_as_uint(f);
;   u += 0x7fffu + ((u >> 16) & 1u);
;   return (bf16r)(u >> 16);
; }
; __device__ __forceinline__ void inproj_epilogue(const Params& p, int layer, int mt, int ntile, int tid,
;                                                 f32x16 (&acc)[2][2], unsigned char* smem) {
;     ...
;     acc_foreach(tid, acc, [&](int row, int col, float v) {
;       int t = m0 + row;
;       float o = v;
;       if (mode == 1) o = (t >= NPADR) ? v : 0.f;
;       if (mode == 2) o = sigmf(v);
;       sT[row * 136 + col] = f2bf(o);
;     });
.LBB0_2768:
	v_bfe_u32 v49, v48, 16, 1
	v_add3_u32 v48, v48, v49, s81
	ds_write_b16_d16_hi v110, v48 offset:64
	s_nop 1

; __device__ __forceinline__ float sigmf(float x) { return 1.f / (1.f + __expf(-x)); }
; __device__ __forceinline__ bf16r f2bf(float f) {
;   unsigned u = __float_as_uint(f);
;   u += 0x7fffu + ((u >> 16) & 1u);
;   return (bf16r)(u >> 16);
; }
; __device__ __forceinline__ void inproj_epilogue(const Params& p, int layer, int mt, int ntile, int tid,
;                                                 f32x16 (&acc)[2][2], unsigned char* smem) {
;     ...
;     acc_foreach(tid, acc, [&](int row, int col, float v) {
;       int t = m0 + row;
;       float o = v;
;       if (mode == 1) o = (t >= NPADR) ? v : 0.f;
;       if (mode == 2) o = sigmf(v);
;       sT[row * 136 + col] = f2bf(o);
;     });
.LBB0_2771:
	v_bfe_u32 v49, v48, 16, 1
	v_add3_u32 v48, v48, v49, s81
	ds_write_b16_d16_hi v111, v48 offset:64
	s_nop 1

; __device__ __forceinline__ float sigmf(float x) { return 1.f / (1.f + __expf(-x)); }
; __device__ __forceinline__ bf16r f2bf(float f) {
;   unsigned u = __float_as_uint(f);
;   u += 0x7fffu + ((u >> 16) & 1u);
;   return (bf16r)(u >> 16);
; }
; __device__ __forceinline__ void inproj_epilogue(const Params& p, int layer, int mt, int ntile, int tid,
;                                                 f32x16 (&acc)[2][2], unsigned char* smem) {
;     ...
;     acc_foreach(tid, acc, [&](int row, int col, float v) {
;       int t = m0 + row;
;       float o = v;
;       if (mode == 1) o = (t >= NPADR) ? v : 0.f;
;       if (mode == 2) o = sigmf(v);
;       sT[row * 136 + col] = f2bf(o);
;     });
.LBB0_2774:
	v_bfe_u32 v49, v48, 16, 1
	v_add3_u32 v48, v48, v49, s81
	ds_write_b16_d16_hi v112, v48 offset:64
	s_nop 1

; __device__ __forceinline__ float sigmf(float x) { return 1.f / (1.f + __expf(-x)); }
; __device__ __forceinline__ bf16r f2bf(float f) {
;   unsigned u = __float_as_uint(f);
;   u += 0x7fffu + ((u >> 16) & 1u);
;   return (bf16r)(u >> 16);
; }
; __device__ __forceinline__ void inproj_epilogue(const Params& p, int layer, int mt, int ntile, int tid,
;                                                 f32x16 (&acc)[2][2], unsigned char* smem) {
;     ...
;     acc_foreach(tid, acc, [&](int row, int col, float v) {
;       int t = m0 + row;
;       float o = v;
;       if (mode == 1) o = (t >= NPADR) ? v : 0.f;
;       if (mode == 2) o = sigmf(v);
;       sT[row * 136 + col] = f2bf(o);
;     });
.LBB0_2777:
	v_bfe_u32 v49, v48, 16, 1
	v_add3_u32 v48, v48, v49, s81
	ds_write_b16_d16_hi v113, v48 offset:64
	s_nop 1

; __device__ __forceinline__ float sigmf(float x) { return 1.f / (1.f + __expf(-x)); }
; __device__ __forceinline__ bf16r f2bf(float f) {
;   unsigned u = __float_as_uint(f);
;   u += 0x7fffu + ((u >> 16) & 1u);
;   return (bf16r)(u >> 16);
; }
; __device__ __forceinline__ void inproj_epilogue(const Params& p, int layer, int mt, int ntile, int tid,
;                                                 f32x16 (&acc)[2][2], unsigned char* smem) {
;     ...
;     acc_foreach(tid, acc, [&](int row, int col, float v) {
;       int t = m0 + row;
;       float o = v;
;       if (mode == 1) o = (t >= NPADR) ? v : 0.f;
;       if (mode == 2) o = sigmf(v);
;       sT[row * 136 + col] = f2bf(o);
;     });
.LBB0_2780:
	v_bfe_u32 v49, v48, 16, 1
	v_add3_u32 v48, v48, v49, s81
	ds_write_b16_d16_hi v114, v48 offset:64
	s_nop 1

; __device__ __forceinline__ float sigmf(float x) { return 1.f / (1.f + __expf(-x)); }
; __device__ __forceinline__ bf16r f2bf(float f) {
;   unsigned u = __float_as_uint(f);
;   u += 0x7fffu + ((u >> 16) & 1u);
;   return (bf16r)(u >> 16);
; }
; __device__ __forceinline__ void inproj_epilogue(const Params& p, int layer, int mt, int ntile, int tid,
;                                                 f32x16 (&acc)[2][2], unsigned char* smem) {
;     ...
;     acc_foreach(tid, acc, [&](int row, int col, float v) {
;       int t = m0 + row;
;       float o = v;
;       if (mode == 1) o = (t >= NPADR) ? v : 0.f;
;       if (mode == 2) o = sigmf(v);
;       sT[row * 136 + col] = f2bf(o);
;     });
.LBB0_2783:
	v_bfe_u32 v49, v48, 16, 1
	v_add3_u32 v48, v48, v49, s81
	ds_write_b16_d16_hi v115, v48 offset:64
	s_nop 1

; __device__ __forceinline__ float sigmf(float x) { return 1.f / (1.f + __expf(-x)); }
; __device__ __forceinline__ bf16r f2bf(float f) {
;   unsigned u = __float_as_uint(f);
;   u += 0x7fffu + ((u >> 16) & 1u);
;   return (bf16r)(u >> 16);
; }
; __device__ __forceinline__ void inproj_epilogue(const Params& p, int layer, int mt, int ntile, int tid,
;                                                 f32x16 (&acc)[2][2], unsigned char* smem) {
;     ...
;     acc_foreach(tid, acc, [&](int row, int col, float v) {
;       int t = m0 + row;
;       float o = v;
;       if (mode == 1) o = (t >= NPADR) ? v : 0.f;
;       if (mode == 2) o = sigmf(v);
;       sT[row * 136 + col] = f2bf(o);
;     });
.LBB0_2786:
	v_bfe_u32 v49, v48, 16, 1
	v_add3_u32 v48, v48, v49, s81
	ds_write_b16_d16_hi v117, v48 offset:64
	s_nop 1

; __device__ __forceinline__ float sigmf(float x) { return 1.f / (1.f + __expf(-x)); }
; __device__ __forceinline__ bf16r f2bf(float f) {
;   unsigned u = __float_as_uint(f);
;   u += 0x7fffu + ((u >> 16) & 1u);
;   return (bf16r)(u >> 16);
; }
; __device__ __forceinline__ void inproj_epilogue(const Params& p, int layer, int mt, int ntile, int tid,
;                                                 f32x16 (&acc)[2][2], unsigned char* smem) {
;     ...
;     acc_foreach(tid, acc, [&](int row, int col, float v) {
;       int t = m0 + row;
;       float o = v;
;       if (mode == 1) o = (t >= NPADR) ? v : 0.f;
;       if (mode == 2) o = sigmf(v);
;       sT[row * 136 + col] = f2bf(o);
;     });
.LBB0_2789:
	v_bfe_u32 v49, v48, 16, 1
	v_add3_u32 v48, v48, v49, s81
	ds_write_b16_d16_hi v118, v48 offset:64
	s_nop 1

; __device__ __forceinline__ float sigmf(float x) { return 1.f / (1.f + __expf(-x)); }
; __device__ __forceinline__ bf16r f2bf(float f) {
;   unsigned u = __float_as_uint(f);
;   u += 0x7fffu + ((u >> 16) & 1u);
;   return (bf16r)(u >> 16);
; }
; __device__ __forceinline__ void inproj_epilogue(const Params& p, int layer, int mt, int ntile, int tid,
;                                                 f32x16 (&acc)[2][2], unsigned char* smem) {
;     ...
;     acc_foreach(tid, acc, [&](int row, int col, float v) {
;       int t = m0 + row;
;       float o = v;
;       if (mode == 1) o = (t >= NPADR) ? v : 0.f;
;       if (mode == 2) o = sigmf(v);
;       sT[row * 136 + col] = f2bf(o);
;     });
.LBB0_2792:
	v_bfe_u32 v49, v48, 16, 1
	v_add3_u32 v48, v48, v49, s81
	ds_write_b16_d16_hi v119, v48 offset:64
	s_nop 1

; __device__ __forceinline__ float sigmf(float x) { return 1.f / (1.f + __expf(-x)); }
; __device__ __forceinline__ bf16r f2bf(float f) {
;   unsigned u = __float_as_uint(f);
;   u += 0x7fffu + ((u >> 16) & 1u);
;   return (bf16r)(u >> 16);
; }
; __device__ __forceinline__ void inproj_epilogue(const Params& p, int layer, int mt, int ntile, int tid,
;                                                 f32x16 (&acc)[2][2], unsigned char* smem) {
;     ...
;     acc_foreach(tid, acc, [&](int row, int col, float v) {
;       int t = m0 + row;
;       float o = v;
;       if (mode == 1) o = (t >= NPADR) ? v : 0.f;
;       if (mode == 2) o = sigmf(v);
;       sT[row * 136 + col] = f2bf(o);
;     });
.LBB0_2795:
	v_bfe_u32 v49, v48, 16, 1
	v_add3_u32 v48, v48, v49, s81
	ds_write_b16_d16_hi v120, v48 offset:64
	s_nop 1

; __device__ __forceinline__ float sigmf(float x) { return 1.f / (1.f + __expf(-x)); }
; __device__ __forceinline__ bf16r f2bf(float f) {
;   unsigned u = __float_as_uint(f);
;   u += 0x7fffu + ((u >> 16) & 1u);
;   return (bf16r)(u >> 16);
; }
; __device__ __forceinline__ void inproj_epilogue(const Params& p, int layer, int mt, int ntile, int tid,
;                                                 f32x16 (&acc)[2][2], unsigned char* smem) {
;     ...
;     acc_foreach(tid, acc, [&](int row, int col, float v) {
;       int t = m0 + row;
;       float o = v;
;       if (mode == 1) o = (t >= NPADR) ? v : 0.f;
;       if (mode == 2) o = sigmf(v);
;       sT[row * 136 + col] = f2bf(o);
;     });
.LBB0_2798:
	v_bfe_u32 v49, v48, 16, 1
	v_add3_u32 v48, v48, v49, s81
	ds_write_b16_d16_hi v121, v48 offset:64
	s_nop 1

; __device__ __forceinline__ float sigmf(float x) { return 1.f / (1.f + __expf(-x)); }
; __device__ __forceinline__ bf16r f2bf(float f) {
;   unsigned u = __float_as_uint(f);
;   u += 0x7fffu + ((u >> 16) & 1u);
;   return (bf16r)(u >> 16);
; }
; __device__ __forceinline__ void inproj_epilogue(const Params& p, int layer, int mt, int ntile, int tid,
;                                                 f32x16 (&acc)[2][2], unsigned char* smem) {
;     ...
;     acc_foreach(tid, acc, [&](int row, int col, float v) {
;       int t = m0 + row;
;       float o = v;
;       if (mode == 1) o = (t >= NPADR) ? v : 0.f;
;       if (mode == 2) o = sigmf(v);
;       sT[row * 136 + col] = f2bf(o);
;     });
.LBB0_2801:
	v_bfe_u32 v49, v48, 16, 1
	v_add3_u32 v48, v48, v49, s81
	ds_write_b16_d16_hi v122, v48 offset:64
	s_nop 1

; __device__ __forceinline__ float sigmf(float x) { return 1.f / (1.f + __expf(-x)); }
; __device__ __forceinline__ bf16r f2bf(float f) {
;   unsigned u = __float_as_uint(f);
;   u += 0x7fffu + ((u >> 16) & 1u);
;   return (bf16r)(u >> 16);
; }
; __device__ __forceinline__ void inproj_epilogue(const Params& p, int layer, int mt, int ntile, int tid,
;                                                 f32x16 (&acc)[2][2], unsigned char* smem) {
;     ...
;     acc_foreach(tid, acc, [&](int row, int col, float v) {
;       int t = m0 + row;
;       float o = v;
;       if (mode == 1) o = (t >= NPADR) ? v : 0.f;
;       if (mode == 2) o = sigmf(v);
;       sT[row * 136 + col] = f2bf(o);
;     });
.LBB0_2804:
	v_bfe_u32 v49, v48, 16, 1
	v_add3_u32 v48, v48, v49, s81
	ds_write_b16_d16_hi v123, v48 offset:64
	s_nop 1

; __device__ __forceinline__ float sigmf(float x) { return 1.f / (1.f + __expf(-x)); }
; __device__ __forceinline__ bf16r f2bf(float f) {
;   unsigned u = __float_as_uint(f);
;   u += 0x7fffu + ((u >> 16) & 1u);
;   return (bf16r)(u >> 16);
; }
; __device__ __forceinline__ void inproj_epilogue(const Params& p, int layer, int mt, int ntile, int tid,
;                                                 f32x16 (&acc)[2][2], unsigned char* smem) {
;     ...
;     acc_foreach(tid, acc, [&](int row, int col, float v) {
;       int t = m0 + row;
;       float o = v;
;       if (mode == 1) o = (t >= NPADR) ? v : 0.f;
;       if (mode == 2) o = sigmf(v);
;       sT[row * 136 + col] = f2bf(o);
;     });
.LBB0_2807:
	v_bfe_u32 v49, v48, 16, 1
	v_add3_u32 v48, v48, v49, s81
	ds_write_b16_d16_hi v116, v48 offset:64
	s_nop 1

; __device__ __forceinline__ float sigmf(float x) { return 1.f / (1.f + __expf(-x)); }
; __device__ __forceinline__ bf16r f2bf(float f) {
;   unsigned u = __float_as_uint(f);
;   u += 0x7fffu + ((u >> 16) & 1u);
;   return (bf16r)(u >> 16);
; }
; template <int MT, int NT, class F>
; __device__ __forceinline__ void acc_foreach(int tid, f32x16 (&acc)[MT][NT], F f) {
;     ...
;         int row = wm * (MT * 32) + mt * 32 + (i & 3) + 8 * (i >> 2) + 4 * hi;
;         int col = wn * (NT * 32) + nt * 32 + c;
;         f(row, col, acc[mt][nt][i]);
; __device__ __forceinline__ void inproj_epilogue(const Params& p, int layer, int mt, int ntile, int tid,
;                                                 f32x16 (&acc)[2][2], unsigned char* smem) {
;     ...
;     acc_foreach(tid, acc, [&](int row, int col, float v) {
;       int t = m0 + row;
;       float o = v;
;       if (mode == 1) o = (t >= NPADR) ? v : 0.f;
;       if (mode == 2) o = sigmf(v);
;       sT[row * 136 + col] = f2bf(o);
;     });
.LBB0_2810:
	v_bfe_u32 v50, v48, 16, 1
	v_add_u32_e32 v49, 0x110, v116
	v_add3_u32 v48, v48, v50, s81
	ds_write_b16_d16_hi v49, v48 offset:64
	v_or_b32_e32 v48, 32, v96
	v_add_u32_e32 v49, s96, v48
	v_cmp_lt_i32_e64 s[8:9], s79, v49
	s_nop 1

; __device__ __forceinline__ float sigmf(float x) { return 1.f / (1.f + __expf(-x)); }
; __device__ __forceinline__ bf16r f2bf(float f) {
;   unsigned u = __float_as_uint(f);
;   u += 0x7fffu + ((u >> 16) & 1u);
;   return (bf16r)(u >> 16);
; }
; template <int MT, int NT, class F>
; __device__ __forceinline__ void acc_foreach(int tid, f32x16 (&acc)[MT][NT], F f) {
;     ...
;         int row = wm * (MT * 32) + mt * 32 + (i & 3) + 8 * (i >> 2) + 4 * hi;
;         int col = wn * (NT * 32) + nt * 32 + c;
;         f(row, col, acc[mt][nt][i]);
; __device__ __forceinline__ void inproj_epilogue(const Params& p, int layer, int mt, int ntile, int tid,
;                                                 f32x16 (&acc)[2][2], unsigned char* smem) {
;     ...
;     acc_foreach(tid, acc, [&](int row, int col, float v) {
;       int t = m0 + row;
;       float o = v;
;       if (mode == 1) o = (t >= NPADR) ? v : 0.f;
;       if (mode == 2) o = sigmf(v);
;       sT[row * 136 + col] = f2bf(o);
;     });
.LBB0_2813:
	v_bfe_u32 v50, v49, 16, 1
	v_add3_u32 v50, v49, v50, s81
	v_mul_lo_u32 v49, v48, s82
	v_lshl_add_u32 v48, v106, 1, v49
	ds_write_b16_d16_hi v48, v50
	v_add3_u32 v50, s96, v96, 33
	v_cmp_lt_i32_e64 s[10:11], s79, v50
	s_nop 1

; __device__ __forceinline__ float sigmf(float x) { return 1.f / (1.f + __expf(-x)); }
; __device__ __forceinline__ bf16r f2bf(float f) {
;   unsigned u = __float_as_uint(f);
;   u += 0x7fffu + ((u >> 16) & 1u);
;   return (bf16r)(u >> 16);
; }
; template <int MT, int NT, class F>
; __device__ __forceinline__ void acc_foreach(int tid, f32x16 (&acc)[MT][NT], F f) {
;     ...
;         int row = wm * (MT * 32) + mt * 32 + (i & 3) + 8 * (i >> 2) + 4 * hi;
;         int col = wn * (NT * 32) + nt * 32 + c;
;         f(row, col, acc[mt][nt][i]);
; __device__ __forceinline__ void inproj_epilogue(const Params& p, int layer, int mt, int ntile, int tid,
;                                                 f32x16 (&acc)[2][2], unsigned char* smem) {
;     ...
;     acc_foreach(tid, acc, [&](int row, int col, float v) {
;       int t = m0 + row;
;       float o = v;
;       if (mode == 1) o = (t >= NPADR) ? v : 0.f;
;       if (mode == 2) o = sigmf(v);
;       sT[row * 136 + col] = f2bf(o);
;     });
.LBB0_2816:
	v_bfe_u32 v51, v50, 16, 1
	v_add3_u32 v51, v50, v51, s81
	v_add_u32_e32 v50, 0x110, v49
	v_lshl_add_u32 v49, v106, 1, v50
	ds_write_b16_d16_hi v49, v51
	v_add3_u32 v51, s96, v96, 34
	v_cmp_lt_i32_e64 s[12:13], s79, v51
	s_nop 1

; __device__ __forceinline__ float sigmf(float x) { return 1.f / (1.f + __expf(-x)); }
; __device__ __forceinline__ bf16r f2bf(float f) {
;   unsigned u = __float_as_uint(f);
;   u += 0x7fffu + ((u >> 16) & 1u);
;   return (bf16r)(u >> 16);
; }
; template <int MT, int NT, class F>
; __device__ __forceinline__ void acc_foreach(int tid, f32x16 (&acc)[MT][NT], F f) {
;     ...
;         int row = wm * (MT * 32) + mt * 32 + (i & 3) + 8 * (i >> 2) + 4 * hi;
;         int col = wn * (NT * 32) + nt * 32 + c;
;         f(row, col, acc[mt][nt][i]);
; __device__ __forceinline__ void inproj_epilogue(const Params& p, int layer, int mt, int ntile, int tid,
;                                                 f32x16 (&acc)[2][2], unsigned char* smem) {
;     ...
;     acc_foreach(tid, acc, [&](int row, int col, float v) {
;       int t = m0 + row;
;       float o = v;
;       if (mode == 1) o = (t >= NPADR) ? v : 0.f;
;       if (mode == 2) o = sigmf(v);
;       sT[row * 136 + col] = f2bf(o);
;     });
.LBB0_2819:
	v_bfe_u32 v52, v51, 16, 1
	v_add3_u32 v52, v51, v52, s81
	v_add_u32_e32 v51, 0x110, v50
	v_lshl_add_u32 v50, v106, 1, v51
	ds_write_b16_d16_hi v50, v52
	v_add3_u32 v52, s96, v96, 35
	v_cmp_lt_i32_e64 s[14:15], s79, v52
	s_nop 1

; __device__ __forceinline__ float sigmf(float x) { return 1.f / (1.f + __expf(-x)); }
; __device__ __forceinline__ bf16r f2bf(float f) {
;   unsigned u = __float_as_uint(f);
;   u += 0x7fffu + ((u >> 16) & 1u);
;   return (bf16r)(u >> 16);
; }
; template <int MT, int NT, class F>
; __device__ __forceinline__ void acc_foreach(int tid, f32x16 (&acc)[MT][NT], F f) {
;     ...
;         int row = wm * (MT * 32) + mt * 32 + (i & 3) + 8 * (i >> 2) + 4 * hi;
;         int col = wn * (NT * 32) + nt * 32 + c;
;         f(row, col, acc[mt][nt][i]);
; __device__ __forceinline__ void inproj_epilogue(const Params& p, int layer, int mt, int ntile, int tid,
;                                                 f32x16 (&acc)[2][2], unsigned char* smem) {
;     ...
;     acc_foreach(tid, acc, [&](int row, int col, float v) {
;       int t = m0 + row;
;       float o = v;
;       if (mode == 1) o = (t >= NPADR) ? v : 0.f;
;       if (mode == 2) o = sigmf(v);
;       sT[row * 136 + col] = f2bf(o);
;     });
.LBB0_2822:
	v_bfe_u32 v53, v52, 16, 1
	v_add3_u32 v53, v52, v53, s81
	v_add_u32_e32 v52, 0x110, v51
	v_lshl_add_u32 v51, v106, 1, v52
	ds_write_b16_d16_hi v51, v53
	v_add3_u32 v53, s96, v96, 40
	v_cmp_lt_i32_e64 s[16:17], s79, v53
	s_nop 1

; __device__ __forceinline__ float sigmf(float x) { return 1.f / (1.f + __expf(-x)); }
; __device__ __forceinline__ bf16r f2bf(float f) {
;   unsigned u = __float_as_uint(f);
;   u += 0x7fffu + ((u >> 16) & 1u);
;   return (bf16r)(u >> 16);
; }
; template <int MT, int NT, class F>
; __device__ __forceinline__ void acc_foreach(int tid, f32x16 (&acc)[MT][NT], F f) {
;     ...
;         int row = wm * (MT * 32) + mt * 32 + (i & 3) + 8 * (i >> 2) + 4 * hi;
;         int col = wn * (NT * 32) + nt * 32 + c;
;         f(row, col, acc[mt][nt][i]);
; __device__ __forceinline__ void inproj_epilogue(const Params& p, int layer, int mt, int ntile, int tid,
;                                                 f32x16 (&acc)[2][2], unsigned char* smem) {
;     ...
;     acc_foreach(tid, acc, [&](int row, int col, float v) {
;       int t = m0 + row;
;       float o = v;
;       if (mode == 1) o = (t >= NPADR) ? v : 0.f;
;       if (mode == 2) o = sigmf(v);
;       sT[row * 136 + col] = f2bf(o);
;     });
.LBB0_2825:
	v_bfe_u32 v54, v53, 16, 1
	v_add3_u32 v54, v53, v54, s81
	v_add_u32_e32 v53, 0x550, v52
	v_lshl_add_u32 v52, v106, 1, v53
	ds_write_b16_d16_hi v52, v54
	v_add3_u32 v54, s96, v96, 41
	v_cmp_lt_i32_e64 s[18:19], s79, v54
	s_nop 1

; __device__ __forceinline__ float sigmf(float x) { return 1.f / (1.f + __expf(-x)); }
; __device__ __forceinline__ bf16r f2bf(float f) {
;   unsigned u = __float_as_uint(f);
;   u += 0x7fffu + ((u >> 16) & 1u);
;   return (bf16r)(u >> 16);
; }
; template <int MT, int NT, class F>
; __device__ __forceinline__ void acc_foreach(int tid, f32x16 (&acc)[MT][NT], F f) {
;     ...
;         int row = wm * (MT * 32) + mt * 32 + (i & 3) + 8 * (i >> 2) + 4 * hi;
;         int col = wn * (NT * 32) + nt * 32 + c;
;         f(row, col, acc[mt][nt][i]);
; __device__ __forceinline__ void inproj_epilogue(const Params& p, int layer, int mt, int ntile, int tid,
;                                                 f32x16 (&acc)[2][2], unsigned char* smem) {
;     ...
;     acc_foreach(tid, acc, [&](int row, int col, float v) {
;       int t = m0 + row;
;       float o = v;
;       if (mode == 1) o = (t >= NPADR) ? v : 0.f;
;       if (mode == 2) o = sigmf(v);
;       sT[row * 136 + col] = f2bf(o);
;     });
.LBB0_2828:
	v_bfe_u32 v55, v54, 16, 1
	v_add3_u32 v55, v54, v55, s81
	v_add_u32_e32 v54, 0x110, v53
	v_lshl_add_u32 v53, v106, 1, v54
	ds_write_b16_d16_hi v53, v55
	v_add3_u32 v55, s96, v96, 42
	v_cmp_lt_i32_e64 s[20:21], s79, v55
	s_nop 1

; __device__ __forceinline__ float sigmf(float x) { return 1.f / (1.f + __expf(-x)); }
; __device__ __forceinline__ bf16r f2bf(float f) {
;   unsigned u = __float_as_uint(f);
;   u += 0x7fffu + ((u >> 16) & 1u);
;   return (bf16r)(u >> 16);
; }
; template <int MT, int NT, class F>
; __device__ __forceinline__ void acc_foreach(int tid, f32x16 (&acc)[MT][NT], F f) {
;     ...
;         int row = wm * (MT * 32) + mt * 32 + (i & 3) + 8 * (i >> 2) + 4 * hi;
;         int col = wn * (NT * 32) + nt * 32 + c;
;         f(row, col, acc[mt][nt][i]);
; __device__ __forceinline__ void inproj_epilogue(const Params& p, int layer, int mt, int ntile, int tid,
;                                                 f32x16 (&acc)[2][2], unsigned char* smem) {
;     ...
;     acc_foreach(tid, acc, [&](int row, int col, float v) {
;       int t = m0 + row;
;       float o = v;
;       if (mode == 1) o = (t >= NPADR) ? v : 0.f;
;       if (mode == 2) o = sigmf(v);
;       sT[row * 136 + col] = f2bf(o);
;     });
.LBB0_2831:
	v_bfe_u32 v56, v55, 16, 1
	v_add3_u32 v56, v55, v56, s81
	v_add_u32_e32 v55, 0x110, v54
	v_lshl_add_u32 v54, v106, 1, v55
	ds_write_b16_d16_hi v54, v56
	v_add3_u32 v56, s96, v96, 43
	v_cmp_lt_i32_e64 s[22:23], s79, v56
	s_nop 1

; __device__ __forceinline__ float sigmf(float x) { return 1.f / (1.f + __expf(-x)); }
; __device__ __forceinline__ bf16r f2bf(float f) {
;   unsigned u = __float_as_uint(f);
;   u += 0x7fffu + ((u >> 16) & 1u);
;   return (bf16r)(u >> 16);
; }
; template <int MT, int NT, class F>
; __device__ __forceinline__ void acc_foreach(int tid, f32x16 (&acc)[MT][NT], F f) {
;     ...
;         int row = wm * (MT * 32) + mt * 32 + (i & 3) + 8 * (i >> 2) + 4 * hi;
;         int col = wn * (NT * 32) + nt * 32 + c;
;         f(row, col, acc[mt][nt][i]);
; __device__ __forceinline__ void inproj_epilogue(const Params& p, int layer, int mt, int ntile, int tid,
;                                                 f32x16 (&acc)[2][2], unsigned char* smem) {
;     ...
;     acc_foreach(tid, acc, [&](int row, int col, float v) {
;       int t = m0 + row;
;       float o = v;
;       if (mode == 1) o = (t >= NPADR) ? v : 0.f;
;       if (mode == 2) o = sigmf(v);
;       sT[row * 136 + col] = f2bf(o);
;     });
.LBB0_2834:
	v_bfe_u32 v57, v56, 16, 1
	v_add_u32_e32 v55, 0x110, v55
	v_add3_u32 v57, v56, v57, s81
	v_lshl_add_u32 v56, v106, 1, v55
	ds_write_b16_d16_hi v56, v57
	v_add3_u32 v57, s96, v96, 48
	v_cmp_lt_i32_e64 s[24:25], s79, v57
	s_nop 1

; __device__ __forceinline__ float sigmf(float x) { return 1.f / (1.f + __expf(-x)); }
; __device__ __forceinline__ bf16r f2bf(float f) {
;   unsigned u = __float_as_uint(f);
;   u += 0x7fffu + ((u >> 16) & 1u);
;   return (bf16r)(u >> 16);
; }
; template <int MT, int NT, class F>
; __device__ __forceinline__ void acc_foreach(int tid, f32x16 (&acc)[MT][NT], F f) {
;     ...
;         int row = wm * (MT * 32) + mt * 32 + (i & 3) + 8 * (i >> 2) + 4 * hi;
;         int col = wn * (NT * 32) + nt * 32 + c;
;         f(row, col, acc[mt][nt][i]);
; __device__ __forceinline__ void inproj_epilogue(const Params& p, int layer, int mt, int ntile, int tid,
;                                                 f32x16 (&acc)[2][2], unsigned char* smem) {
;     ...
;     acc_foreach(tid, acc, [&](int row, int col, float v) {
;       int t = m0 + row;
;       float o = v;
;       if (mode == 1) o = (t >= NPADR) ? v : 0.f;
;       if (mode == 2) o = sigmf(v);
;       sT[row * 136 + col] = f2bf(o);
;     });
.LBB0_2837:
	v_bfe_u32 v58, v57, 16, 1
	v_add_u32_e32 v55, 0x550, v55
	v_add3_u32 v58, v57, v58, s81
	v_lshl_add_u32 v57, v106, 1, v55
	ds_write_b16_d16_hi v57, v58
	v_add3_u32 v58, s96, v96, 49
	v_cmp_lt_i32_e64 s[26:27], s79, v58
	s_nop 1

; __device__ __forceinline__ float sigmf(float x) { return 1.f / (1.f + __expf(-x)); }
; __device__ __forceinline__ bf16r f2bf(float f) {
;   unsigned u = __float_as_uint(f);
;   u += 0x7fffu + ((u >> 16) & 1u);
;   return (bf16r)(u >> 16);
; }
; template <int MT, int NT, class F>
; __device__ __forceinline__ void acc_foreach(int tid, f32x16 (&acc)[MT][NT], F f) {
;     ...
;         int row = wm * (MT * 32) + mt * 32 + (i & 3) + 8 * (i >> 2) + 4 * hi;
;         int col = wn * (NT * 32) + nt * 32 + c;
;         f(row, col, acc[mt][nt][i]);
; __device__ __forceinline__ void inproj_epilogue(const Params& p, int layer, int mt, int ntile, int tid,
;                                                 f32x16 (&acc)[2][2], unsigned char* smem) {
;     ...
;     acc_foreach(tid, acc, [&](int row, int col, float v) {
;       int t = m0 + row;
;       float o = v;
;       if (mode == 1) o = (t >= NPADR) ? v : 0.f;
;       if (mode == 2) o = sigmf(v);
;       sT[row * 136 + col] = f2bf(o);
;     });
.LBB0_2840:
	v_bfe_u32 v59, v58, 16, 1
	v_add_u32_e32 v55, 0x110, v55
	v_add3_u32 v59, v58, v59, s81
	v_lshl_add_u32 v58, v106, 1, v55
	ds_write_b16_d16_hi v58, v59
	v_add3_u32 v59, s96, v96, 50
	v_cmp_lt_i32_e64 s[28:29], s79, v59
	s_nop 1

; __device__ __forceinline__ float sigmf(float x) { return 1.f / (1.f + __expf(-x)); }
; __device__ __forceinline__ bf16r f2bf(float f) {
;   unsigned u = __float_as_uint(f);
;   u += 0x7fffu + ((u >> 16) & 1u);
;   return (bf16r)(u >> 16);
; }
; template <int MT, int NT, class F>
; __device__ __forceinline__ void acc_foreach(int tid, f32x16 (&acc)[MT][NT], F f) {
;     ...
;         int row = wm * (MT * 32) + mt * 32 + (i & 3) + 8 * (i >> 2) + 4 * hi;
;         int col = wn * (NT * 32) + nt * 32 + c;
;         f(row, col, acc[mt][nt][i]);
; __device__ __forceinline__ void inproj_epilogue(const Params& p, int layer, int mt, int ntile, int tid,
;                                                 f32x16 (&acc)[2][2], unsigned char* smem) {
;     ...
;     acc_foreach(tid, acc, [&](int row, int col, float v) {
;       int t = m0 + row;
;       float o = v;
;       if (mode == 1) o = (t >= NPADR) ? v : 0.f;
;       if (mode == 2) o = sigmf(v);
;       sT[row * 136 + col] = f2bf(o);
;     });
.LBB0_2843:
	v_bfe_u32 v60, v59, 16, 1
	v_add_u32_e32 v55, 0x110, v55
	v_add3_u32 v60, v59, v60, s81
	v_lshl_add_u32 v59, v106, 1, v55
	ds_write_b16_d16_hi v59, v60
	v_add3_u32 v60, s96, v96, 51
	v_cmp_lt_i32_e64 s[30:31], s79, v60
	s_nop 1

; __device__ __forceinline__ float sigmf(float x) { return 1.f / (1.f + __expf(-x)); }
; __device__ __forceinline__ bf16r f2bf(float f) {
;   unsigned u = __float_as_uint(f);
;   u += 0x7fffu + ((u >> 16) & 1u);
;   return (bf16r)(u >> 16);
; }
; template <int MT, int NT, class F>
; __device__ __forceinline__ void acc_foreach(int tid, f32x16 (&acc)[MT][NT], F f) {
;     ...
;         int row = wm * (MT * 32) + mt * 32 + (i & 3) + 8 * (i >> 2) + 4 * hi;
;         int col = wn * (NT * 32) + nt * 32 + c;
;         f(row, col, acc[mt][nt][i]);
; __device__ __forceinline__ void inproj_epilogue(const Params& p, int layer, int mt, int ntile, int tid,
;                                                 f32x16 (&acc)[2][2], unsigned char* smem) {
;     ...
;     acc_foreach(tid, acc, [&](int row, int col, float v) {
;       int t = m0 + row;
;       float o = v;
;       if (mode == 1) o = (t >= NPADR) ? v : 0.f;
;       if (mode == 2) o = sigmf(v);
;       sT[row * 136 + col] = f2bf(o);
;     });
.LBB0_2846:
	v_bfe_u32 v61, v60, 16, 1
	v_add_u32_e32 v55, 0x110, v55
	v_add3_u32 v61, v60, v61, s81
	v_lshl_add_u32 v60, v106, 1, v55
	ds_write_b16_d16_hi v60, v61
	v_add3_u32 v61, s96, v96, 56
	v_cmp_lt_i32_e64 s[34:35], s79, v61
	s_nop 1

; __device__ __forceinline__ float sigmf(float x) { return 1.f / (1.f + __expf(-x)); }
; __device__ __forceinline__ bf16r f2bf(float f) {
;   unsigned u = __float_as_uint(f);
;   u += 0x7fffu + ((u >> 16) & 1u);
;   return (bf16r)(u >> 16);
; }
; template <int MT, int NT, class F>
; __device__ __forceinline__ void acc_foreach(int tid, f32x16 (&acc)[MT][NT], F f) {
;     ...
;         int row = wm * (MT * 32) + mt * 32 + (i & 3) + 8 * (i >> 2) + 4 * hi;
;         int col = wn * (NT * 32) + nt * 32 + c;
;         f(row, col, acc[mt][nt][i]);
; __device__ __forceinline__ void inproj_epilogue(const Params& p, int layer, int mt, int ntile, int tid,
;                                                 f32x16 (&acc)[2][2], unsigned char* smem) {
;     ...
;     acc_foreach(tid, acc, [&](int row, int col, float v) {
;       int t = m0 + row;
;       float o = v;
;       if (mode == 1) o = (t >= NPADR) ? v : 0.f;
;       if (mode == 2) o = sigmf(v);
;       sT[row * 136 + col] = f2bf(o);
;     });
.LBB0_2849:
	v_bfe_u32 v62, v61, 16, 1
	v_add_u32_e32 v55, 0x550, v55
	v_add3_u32 v62, v61, v62, s81
	v_lshl_add_u32 v61, v106, 1, v55
	ds_write_b16_d16_hi v61, v62
	v_add3_u32 v62, s96, v96, 57
	v_cmp_lt_i32_e64 s[36:37], s79, v62
	s_nop 1

; __device__ __forceinline__ float sigmf(float x) { return 1.f / (1.f + __expf(-x)); }
; __device__ __forceinline__ bf16r f2bf(float f) {
;   unsigned u = __float_as_uint(f);
;   u += 0x7fffu + ((u >> 16) & 1u);
;   return (bf16r)(u >> 16);
; }
; template <int MT, int NT, class F>
; __device__ __forceinline__ void acc_foreach(int tid, f32x16 (&acc)[MT][NT], F f) {
;     ...
;         int row = wm * (MT * 32) + mt * 32 + (i & 3) + 8 * (i >> 2) + 4 * hi;
;         int col = wn * (NT * 32) + nt * 32 + c;
;         f(row, col, acc[mt][nt][i]);
; __device__ __forceinline__ void inproj_epilogue(const Params& p, int layer, int mt, int ntile, int tid,
;                                                 f32x16 (&acc)[2][2], unsigned char* smem) {
;     ...
;     acc_foreach(tid, acc, [&](int row, int col, float v) {
;       int t = m0 + row;
;       float o = v;
;       if (mode == 1) o = (t >= NPADR) ? v : 0.f;
;       if (mode == 2) o = sigmf(v);
;       sT[row * 136 + col] = f2bf(o);
;     });
.LBB0_2852:
	v_bfe_u32 v63, v62, 16, 1
	v_add_u32_e32 v55, 0x110, v55
	v_add3_u32 v63, v62, v63, s81
	v_lshl_add_u32 v62, v106, 1, v55
	ds_write_b16_d16_hi v62, v63
	v_add3_u32 v63, s96, v96, 58
	v_cmp_lt_i32_e64 s[38:39], s79, v63
	s_nop 1

; __device__ __forceinline__ float sigmf(float x) { return 1.f / (1.f + __expf(-x)); }
; __device__ __forceinline__ bf16r f2bf(float f) {
;   unsigned u = __float_as_uint(f);
;   u += 0x7fffu + ((u >> 16) & 1u);
;   return (bf16r)(u >> 16);
; }
; template <int MT, int NT, class F>
; __device__ __forceinline__ void acc_foreach(int tid, f32x16 (&acc)[MT][NT], F f) {
;     ...
;         int row = wm * (MT * 32) + mt * 32 + (i & 3) + 8 * (i >> 2) + 4 * hi;
;         int col = wn * (NT * 32) + nt * 32 + c;
;         f(row, col, acc[mt][nt][i]);
; __device__ __forceinline__ void inproj_epilogue(const Params& p, int layer, int mt, int ntile, int tid,
;                                                 f32x16 (&acc)[2][2], unsigned char* smem) {
;     ...
;     acc_foreach(tid, acc, [&](int row, int col, float v) {
;       int t = m0 + row;
;       float o = v;
;       if (mode == 1) o = (t >= NPADR) ? v : 0.f;
;       if (mode == 2) o = sigmf(v);
;       sT[row * 136 + col] = f2bf(o);
;     });
.LBB0_2855:
	v_bfe_u32 v107, v63, 16, 1
	v_add_u32_e32 v55, 0x110, v55
	v_add3_u32 v63, v63, v107, s81
	v_lshl_add_u32 v55, v106, 1, v55
	ds_write_b16_d16_hi v55, v63
	v_add3_u32 v63, s96, v96, 59
	v_cmp_lt_i32_e64 s[40:41], s79, v63
	s_nop 1

; __device__ __forceinline__ float sigmf(float x) { return 1.f / (1.f + __expf(-x)); }
; __device__ __forceinline__ bf16r f2bf(float f) {
;   unsigned u = __float_as_uint(f);
;   u += 0x7fffu + ((u >> 16) & 1u);
;   return (bf16r)(u >> 16);
; }
; __device__ __forceinline__ void inproj_epilogue(const Params& p, int layer, int mt, int ntile, int tid,
;                                                 f32x16 (&acc)[2][2], unsigned char* smem) {
;     ...
;     acc_foreach(tid, acc, [&](int row, int col, float v) {
;       int t = m0 + row;
;       float o = v;
;       if (mode == 1) o = (t >= NPADR) ? v : 0.f;
;       if (mode == 2) o = sigmf(v);
;       sT[row * 136 + col] = f2bf(o);
;     });
.LBB0_2858:
	v_bfe_u32 v96, v63, 16, 1
	v_add3_u32 v63, v63, v96, s81
	ds_write_b16_d16_hi v55, v63 offset:272
	s_nop 1

; __device__ __forceinline__ float sigmf(float x) { return 1.f / (1.f + __expf(-x)); }
; __device__ __forceinline__ bf16r f2bf(float f) {
;   unsigned u = __float_as_uint(f);
;   u += 0x7fffu + ((u >> 16) & 1u);
;   return (bf16r)(u >> 16);
; }
; __device__ __forceinline__ void inproj_epilogue(const Params& p, int layer, int mt, int ntile, int tid,
;                                                 f32x16 (&acc)[2][2], unsigned char* smem) {
;     ...
;     acc_foreach(tid, acc, [&](int row, int col, float v) {
;       int t = m0 + row;
;       float o = v;
;       if (mode == 1) o = (t >= NPADR) ? v : 0.f;
;       if (mode == 2) o = sigmf(v);
;       sT[row * 136 + col] = f2bf(o);
;     });
.LBB0_2861:
	v_bfe_u32 v63, v32, 16, 1
	v_add3_u32 v32, v32, v63, s81
	ds_write_b16_d16_hi v48, v32 offset:64
	s_nop 1

; __device__ __forceinline__ float sigmf(float x) { return 1.f / (1.f + __expf(-x)); }
; __device__ __forceinline__ bf16r f2bf(float f) {
;   unsigned u = __float_as_uint(f);
;   u += 0x7fffu + ((u >> 16) & 1u);
;   return (bf16r)(u >> 16);
; }
; __device__ __forceinline__ void inproj_epilogue(const Params& p, int layer, int mt, int ntile, int tid,
;                                                 f32x16 (&acc)[2][2], unsigned char* smem) {
;     ...
;     acc_foreach(tid, acc, [&](int row, int col, float v) {
;       int t = m0 + row;
;       float o = v;
;       if (mode == 1) o = (t >= NPADR) ? v : 0.f;
;       if (mode == 2) o = sigmf(v);
;       sT[row * 136 + col] = f2bf(o);
;     });
.LBB0_2864:
	v_bfe_u32 v33, v32, 16, 1
	v_add3_u32 v32, v32, v33, s81
	ds_write_b16_d16_hi v49, v32 offset:64
	s_nop 1

; __device__ __forceinline__ float sigmf(float x) { return 1.f / (1.f + __expf(-x)); }
; __device__ __forceinline__ bf16r f2bf(float f) {
;   unsigned u = __float_as_uint(f);
;   u += 0x7fffu + ((u >> 16) & 1u);
;   return (bf16r)(u >> 16);
; }
; __device__ __forceinline__ void inproj_epilogue(const Params& p, int layer, int mt, int ntile, int tid,
;                                                 f32x16 (&acc)[2][2], unsigned char* smem) {
;     ...
;     acc_foreach(tid, acc, [&](int row, int col, float v) {
;       int t = m0 + row;
;       float o = v;
;       if (mode == 1) o = (t >= NPADR) ? v : 0.f;
;       if (mode == 2) o = sigmf(v);
;       sT[row * 136 + col] = f2bf(o);
;     });
.LBB0_2867:
	v_bfe_u32 v33, v32, 16, 1
	v_add3_u32 v32, v32, v33, s81
	ds_write_b16_d16_hi v50, v32 offset:64
	s_nop 1

; __device__ __forceinline__ float sigmf(float x) { return 1.f / (1.f + __expf(-x)); }
; __device__ __forceinline__ bf16r f2bf(float f) {
;   unsigned u = __float_as_uint(f);
;   u += 0x7fffu + ((u >> 16) & 1u);
;   return (bf16r)(u >> 16);
; }
; __device__ __forceinline__ void inproj_epilogue(const Params& p, int layer, int mt, int ntile, int tid,
;                                                 f32x16 (&acc)[2][2], unsigned char* smem) {
;     ...
;     acc_foreach(tid, acc, [&](int row, int col, float v) {
;       int t = m0 + row;
;       float o = v;
;       if (mode == 1) o = (t >= NPADR) ? v : 0.f;
;       if (mode == 2) o = sigmf(v);
;       sT[row * 136 + col] = f2bf(o);
;     });
.LBB0_2870:
	v_bfe_u32 v33, v32, 16, 1
	v_add3_u32 v32, v32, v33, s81
	ds_write_b16_d16_hi v51, v32 offset:64
	s_nop 1

; __device__ __forceinline__ float sigmf(float x) { return 1.f / (1.f + __expf(-x)); }
; __device__ __forceinline__ bf16r f2bf(float f) {
;   unsigned u = __float_as_uint(f);
;   u += 0x7fffu + ((u >> 16) & 1u);
;   return (bf16r)(u >> 16);
; }
; __device__ __forceinline__ void inproj_epilogue(const Params& p, int layer, int mt, int ntile, int tid,
;                                                 f32x16 (&acc)[2][2], unsigned char* smem) {
;     ...
;     acc_foreach(tid, acc, [&](int row, int col, float v) {
;       int t = m0 + row;
;       float o = v;
;       if (mode == 1) o = (t >= NPADR) ? v : 0.f;
;       if (mode == 2) o = sigmf(v);
;       sT[row * 136 + col] = f2bf(o);
;     });
.LBB0_2873:
	v_bfe_u32 v33, v32, 16, 1
	v_add3_u32 v32, v32, v33, s81
	ds_write_b16_d16_hi v52, v32 offset:64
	s_nop 1

; __device__ __forceinline__ float sigmf(float x) { return 1.f / (1.f + __expf(-x)); }
; __device__ __forceinline__ bf16r f2bf(float f) {
;   unsigned u = __float_as_uint(f);
;   u += 0x7fffu + ((u >> 16) & 1u);
;   return (bf16r)(u >> 16);
; }
; __device__ __forceinline__ void inproj_epilogue(const Params& p, int layer, int mt, int ntile, int tid,
;                                                 f32x16 (&acc)[2][2], unsigned char* smem) {
;     ...
;     acc_foreach(tid, acc, [&](int row, int col, float v) {
;       int t = m0 + row;
;       float o = v;
;       if (mode == 1) o = (t >= NPADR) ? v : 0.f;
;       if (mode == 2) o = sigmf(v);
;       sT[row * 136 + col] = f2bf(o);
;     });
.LBB0_2876:
	v_bfe_u32 v33, v32, 16, 1
	v_add3_u32 v32, v32, v33, s81
	ds_write_b16_d16_hi v53, v32 offset:64
	s_nop 1

; __device__ __forceinline__ float sigmf(float x) { return 1.f / (1.f + __expf(-x)); }
; __device__ __forceinline__ bf16r f2bf(float f) {
;   unsigned u = __float_as_uint(f);
;   u += 0x7fffu + ((u >> 16) & 1u);
;   return (bf16r)(u >> 16);
; }
; __device__ __forceinline__ void inproj_epilogue(const Params& p, int layer, int mt, int ntile, int tid,
;                                                 f32x16 (&acc)[2][2], unsigned char* smem) {
;     ...
;     acc_foreach(tid, acc, [&](int row, int col, float v) {
;       int t = m0 + row;
;       float o = v;
;       if (mode == 1) o = (t >= NPADR) ? v : 0.f;
;       if (mode == 2) o = sigmf(v);
;       sT[row * 136 + col] = f2bf(o);
;     });
.LBB0_2879:
	v_bfe_u32 v33, v32, 16, 1
	v_add3_u32 v32, v32, v33, s81
	ds_write_b16_d16_hi v54, v32 offset:64
	s_nop 1

; __device__ __forceinline__ float sigmf(float x) { return 1.f / (1.f + __expf(-x)); }
; __device__ __forceinline__ bf16r f2bf(float f) {
;   unsigned u = __float_as_uint(f);
;   u += 0x7fffu + ((u >> 16) & 1u);
;   return (bf16r)(u >> 16);
; }
; __device__ __forceinline__ void inproj_epilogue(const Params& p, int layer, int mt, int ntile, int tid,
;                                                 f32x16 (&acc)[2][2], unsigned char* smem) {
;     ...
;     acc_foreach(tid, acc, [&](int row, int col, float v) {
;       int t = m0 + row;
;       float o = v;
;       if (mode == 1) o = (t >= NPADR) ? v : 0.f;
;       if (mode == 2) o = sigmf(v);
;       sT[row * 136 + col] = f2bf(o);
;     });
.LBB0_2882:
	v_bfe_u32 v33, v32, 16, 1
	v_add3_u32 v32, v32, v33, s81
	ds_write_b16_d16_hi v56, v32 offset:64
	s_nop 1

; __device__ __forceinline__ float sigmf(float x) { return 1.f / (1.f + __expf(-x)); }
; __device__ __forceinline__ bf16r f2bf(float f) {
;   unsigned u = __float_as_uint(f);
;   u += 0x7fffu + ((u >> 16) & 1u);
;   return (bf16r)(u >> 16);
; }
; __device__ __forceinline__ void inproj_epilogue(const Params& p, int layer, int mt, int ntile, int tid,
;                                                 f32x16 (&acc)[2][2], unsigned char* smem) {
;     ...
;     acc_foreach(tid, acc, [&](int row, int col, float v) {
;       int t = m0 + row;
;       float o = v;
;       if (mode == 1) o = (t >= NPADR) ? v : 0.f;
;       if (mode == 2) o = sigmf(v);
;       sT[row * 136 + col] = f2bf(o);
;     });
.LBB0_2885:
	v_bfe_u32 v33, v32, 16, 1
	v_add3_u32 v32, v32, v33, s81
	ds_write_b16_d16_hi v57, v32 offset:64
	s_nop 1

; __device__ __forceinline__ float sigmf(float x) { return 1.f / (1.f + __expf(-x)); }
; __device__ __forceinline__ bf16r f2bf(float f) {
;   unsigned u = __float_as_uint(f);
;   u += 0x7fffu + ((u >> 16) & 1u);
;   return (bf16r)(u >> 16);
; }
; __device__ __forceinline__ void inproj_epilogue(const Params& p, int layer, int mt, int ntile, int tid,
;                                                 f32x16 (&acc)[2][2], unsigned char* smem) {
;     ...
;     acc_foreach(tid, acc, [&](int row, int col, float v) {
;       int t = m0 + row;
;       float o = v;
;       if (mode == 1) o = (t >= NPADR) ? v : 0.f;
;       if (mode == 2) o = sigmf(v);
;       sT[row * 136 + col] = f2bf(o);
;     });
.LBB0_2888:
	v_bfe_u32 v33, v32, 16, 1
	v_add3_u32 v32, v32, v33, s81
	ds_write_b16_d16_hi v58, v32 offset:64
	s_nop 1

; __device__ __forceinline__ float sigmf(float x) { return 1.f / (1.f + __expf(-x)); }
; __device__ __forceinline__ bf16r f2bf(float f) {
;   unsigned u = __float_as_uint(f);
;   u += 0x7fffu + ((u >> 16) & 1u);
;   return (bf16r)(u >> 16);
; }
; __device__ __forceinline__ void inproj_epilogue(const Params& p, int layer, int mt, int ntile, int tid,
;                                                 f32x16 (&acc)[2][2], unsigned char* smem) {
;     ...
;     acc_foreach(tid, acc, [&](int row, int col, float v) {
;       int t = m0 + row;
;       float o = v;
;       if (mode == 1) o = (t >= NPADR) ? v : 0.f;
;       if (mode == 2) o = sigmf(v);
;       sT[row * 136 + col] = f2bf(o);
;     });
.LBB0_2891:
	v_bfe_u32 v33, v32, 16, 1
	v_add3_u32 v32, v32, v33, s81
	ds_write_b16_d16_hi v59, v32 offset:64
	s_nop 1

; __device__ __forceinline__ float sigmf(float x) { return 1.f / (1.f + __expf(-x)); }
; __device__ __forceinline__ bf16r f2bf(float f) {
;   unsigned u = __float_as_uint(f);
;   u += 0x7fffu + ((u >> 16) & 1u);
;   return (bf16r)(u >> 16);
; }
; __device__ __forceinline__ void inproj_epilogue(const Params& p, int layer, int mt, int ntile, int tid,
;                                                 f32x16 (&acc)[2][2], unsigned char* smem) {
;     ...
;     acc_foreach(tid, acc, [&](int row, int col, float v) {
;       int t = m0 + row;
;       float o = v;
;       if (mode == 1) o = (t >= NPADR) ? v : 0.f;
;       if (mode == 2) o = sigmf(v);
;       sT[row * 136 + col] = f2bf(o);
;     });
.LBB0_2894:
	v_bfe_u32 v33, v32, 16, 1
	v_add3_u32 v32, v32, v33, s81
	ds_write_b16_d16_hi v60, v32 offset:64
	s_nop 1

; __device__ __forceinline__ float sigmf(float x) { return 1.f / (1.f + __expf(-x)); }
; __device__ __forceinline__ bf16r f2bf(float f) {
;   unsigned u = __float_as_uint(f);
;   u += 0x7fffu + ((u >> 16) & 1u);
;   return (bf16r)(u >> 16);
; }
; __device__ __forceinline__ void inproj_epilogue(const Params& p, int layer, int mt, int ntile, int tid,
;                                                 f32x16 (&acc)[2][2], unsigned char* smem) {
;     ...
;     acc_foreach(tid, acc, [&](int row, int col, float v) {
;       int t = m0 + row;
;       float o = v;
;       if (mode == 1) o = (t >= NPADR) ? v : 0.f;
;       if (mode == 2) o = sigmf(v);
;       sT[row * 136 + col] = f2bf(o);
;     });
.LBB0_2897:
	v_bfe_u32 v33, v32, 16, 1
	v_add3_u32 v32, v32, v33, s81
	ds_write_b16_d16_hi v61, v32 offset:64
	s_nop 1

; __device__ __forceinline__ float sigmf(float x) { return 1.f / (1.f + __expf(-x)); }
; __device__ __forceinline__ bf16r f2bf(float f) {
;   unsigned u = __float_as_uint(f);
;   u += 0x7fffu + ((u >> 16) & 1u);
;   return (bf16r)(u >> 16);
; }
; __device__ __forceinline__ void inproj_epilogue(const Params& p, int layer, int mt, int ntile, int tid,
;                                                 f32x16 (&acc)[2][2], unsigned char* smem) {
;     ...
;     acc_foreach(tid, acc, [&](int row, int col, float v) {
;       int t = m0 + row;
;       float o = v;
;       if (mode == 1) o = (t >= NPADR) ? v : 0.f;
;       if (mode == 2) o = sigmf(v);
;       sT[row * 136 + col] = f2bf(o);
;     });
.LBB0_2900:
	v_bfe_u32 v33, v32, 16, 1
	v_add3_u32 v32, v32, v33, s81
	ds_write_b16_d16_hi v62, v32 offset:64
	s_nop 1

; __device__ __forceinline__ float sigmf(float x) { return 1.f / (1.f + __expf(-x)); }
; __device__ __forceinline__ bf16r f2bf(float f) {
;   unsigned u = __float_as_uint(f);
;   u += 0x7fffu + ((u >> 16) & 1u);
;   return (bf16r)(u >> 16);
; }
; __device__ __forceinline__ void inproj_epilogue(const Params& p, int layer, int mt, int ntile, int tid,
;                                                 f32x16 (&acc)[2][2], unsigned char* smem) {
;     ...
;     acc_foreach(tid, acc, [&](int row, int col, float v) {
;       int t = m0 + row;
;       float o = v;
;       if (mode == 1) o = (t >= NPADR) ? v : 0.f;
;       if (mode == 2) o = sigmf(v);
;       sT[row * 136 + col] = f2bf(o);
;     });
.LBB0_2903:
	v_bfe_u32 v33, v32, 16, 1
	v_add3_u32 v32, v32, v33, s81
	ds_write_b16_d16_hi v55, v32 offset:64
	s_nop 1

; __device__ __forceinline__ bf16r f2bf(float f) {
;   unsigned u = __float_as_uint(f);
;   u += 0x7fffu + ((u >> 16) & 1u);
;   return (bf16r)(u >> 16);
; }
; __device__ __forceinline__ unsigned pack2(float a, float b) { return (unsigned)f2bf(a) | ((unsigned)f2bf(b) << 16); }
; __device__ __forceinline__ float lo16(unsigned v) { return __uint_as_float(v << 16); }
; __device__ __forceinline__ float hi16(unsigned v) { return __uint_as_float(v & 0xffff0000u); }
; __device__ __forceinline__ float siluf(float x) { return x / (1.f + __expf(-x)); }
; __device__ __forceinline__ float sigmf(float x) { return 1.f / (1.f + __expf(-x)); }
; __device__ __forceinline__ void inproj_epilogue(const Params& p, int layer, int mt, int ntile, int tid,
;                                                 f32x16 (&acc)[2][2], unsigned char* smem) {
;     ...
;     acc_foreach(tid, acc, [&](int row, int col, float v) {
;       int t = m0 + row;
;       float o = v;
;       if (mode == 1) o = (t >= NPADR) ? v : 0.f;
;       if (mode == 2) o = sigmf(v);
;       sT[row * 136 + col] = f2bf(o);
;     });
.Lgv_5:
	v_mul_f32_e32 v107, 0xbfb8aa3b, v16
	v_exp_f32_e32 v107, v107
	s_nop 0
	v_add_f32_e32 v107, 1.0, v107
	v_div_scale_f32 v110, s[6:7], v107, v107, 1.0
	v_rcp_f32_e32 v111, v110
	v_div_scale_f32 v112, vcc, 1.0, v107, 1.0
	v_fma_f32 v113, -v110, v111, 1.0
	v_fmac_f32_e32 v111, v113, v111
	v_mul_f32_e32 v113, v112, v111
	v_fma_f32 v114, -v110, v113, v112
	v_fmac_f32_e32 v113, v114, v111
	v_fma_f32 v110, -v110, v113, v112
	v_div_fmas_f32 v110, v110, v111, v113
	v_div_fixup_f32 v107, v110, v107, 1.0
	v_bfe_u32 v110, v107, 16, 1
	v_and_b32_e32 v106, 0x5f, v106
	v_add3_u32 v111, v107, v110, s81
	v_mul_lo_u32 v110, v96, s82
	v_lshl_add_u32 v107, v106, 1, v110
	ds_write_b16_d16_hi v107, v111
	v_add3_u32 v111, s96, v96, 1
	v_cndmask_b32_e64 v112, 0, 1, s[10:11]
	v_cmp_ne_u32_e64 s[6:7], 1, v112
	s_andn2_b64 vcc, exec, s[10:11]
	v_cmp_lt_i32_e64 s[10:11], s79, v111
	v_mul_f32_e32 v111, 0xbfb8aa3b, v17
	v_exp_f32_e32 v111, v111
	s_nop 0
	v_add_f32_e32 v111, 1.0, v111
	v_div_scale_f32 v112, s[12:13], v111, v111, 1.0
	v_rcp_f32_e32 v113, v112
	v_div_scale_f32 v114, vcc, 1.0, v111, 1.0
	v_fma_f32 v115, -v112, v113, 1.0
	v_fmac_f32_e32 v113, v115, v113
	v_mul_f32_e32 v115, v114, v113
	v_fma_f32 v116, -v112, v115, v114
	v_fmac_f32_e32 v115, v116, v113
	v_fma_f32 v112, -v112, v115, v114
	v_div_fmas_f32 v112, v112, v113, v115
	v_div_fixup_f32 v111, v112, v111, 1.0
	v_bfe_u32 v112, v111, 16, 1
	v_add3_u32 v112, v111, v112, s81
	v_add_u32_e32 v111, 0x110, v110
	v_lshl_add_u32 v110, v106, 1, v111
	ds_write_b16_d16_hi v110, v112
	v_add3_u32 v112, s96, v96, 2
	s_and_b64 vcc, exec, s[6:7]
	v_cmp_lt_i32_e64 s[12:13], s79, v112
	v_mul_f32_e32 v112, 0xbfb8aa3b, v18
	v_exp_f32_e32 v112, v112
	s_nop 0
	v_add_f32_e32 v112, 1.0, v112
	v_div_scale_f32 v113, s[14:15], v112, v112, 1.0
	v_rcp_f32_e32 v114, v113
	v_div_scale_f32 v115, vcc, 1.0, v112, 1.0
	v_fma_f32 v116, -v113, v114, 1.0
	v_fmac_f32_e32 v114, v116, v114
	v_mul_f32_e32 v116, v115, v114
	v_fma_f32 v117, -v113, v116, v115
	v_fmac_f32_e32 v116, v117, v114
	v_fma_f32 v113, -v113, v116, v115
	v_div_fmas_f32 v113, v113, v114, v116
	v_div_fixup_f32 v112, v113, v112, 1.0
	v_bfe_u32 v113, v112, 16, 1
	v_add3_u32 v113, v112, v113, s81
	v_add_u32_e32 v112, 0x110, v111
	v_lshl_add_u32 v111, v106, 1, v112
	ds_write_b16_d16_hi v111, v113
	v_add3_u32 v113, s96, v96, 3
	s_and_b64 vcc, exec, s[6:7]
	v_cmp_lt_i32_e64 s[14:15], s79, v113
	v_mul_f32_e32 v113, 0xbfb8aa3b, v19
	v_exp_f32_e32 v113, v113
	s_nop 0
	v_add_f32_e32 v113, 1.0, v113
	v_div_scale_f32 v114, s[16:17], v113, v113, 1.0
	v_rcp_f32_e32 v115, v114
	v_div_scale_f32 v116, vcc, 1.0, v113, 1.0
	v_fma_f32 v117, -v114, v115, 1.0
	v_fmac_f32_e32 v115, v117, v115
	v_mul_f32_e32 v117, v116, v115
	v_fma_f32 v118, -v114, v117, v116
	v_fmac_f32_e32 v117, v118, v115
	v_fma_f32 v114, -v114, v117, v116
	v_div_fmas_f32 v114, v114, v115, v117
	v_div_fixup_f32 v113, v114, v113, 1.0
	v_bfe_u32 v114, v113, 16, 1
	v_add3_u32 v114, v113, v114, s81
	v_add_u32_e32 v113, 0x110, v112
	v_lshl_add_u32 v112, v106, 1, v113
	ds_write_b16_d16_hi v112, v114
	v_add3_u32 v114, s96, v96, 8
	s_and_b64 vcc, exec, s[6:7]
	v_cmp_lt_i32_e64 s[16:17], s79, v114
	v_mul_f32_e32 v114, 0xbfb8aa3b, v20
	v_exp_f32_e32 v114, v114
	s_nop 0
	v_add_f32_e32 v114, 1.0, v114
	v_div_scale_f32 v115, s[18:19], v114, v114, 1.0
	v_rcp_f32_e32 v116, v115
	v_div_scale_f32 v117, vcc, 1.0, v114, 1.0
	v_fma_f32 v118, -v115, v116, 1.0
	v_fmac_f32_e32 v116, v118, v116
	v_mul_f32_e32 v118, v117, v116
	v_fma_f32 v119, -v115, v118, v117
	v_fmac_f32_e32 v118, v119, v116
	v_fma_f32 v115, -v115, v118, v117
	v_div_fmas_f32 v115, v115, v116, v118
	v_div_fixup_f32 v114, v115, v114, 1.0
	v_bfe_u32 v115, v114, 16, 1
	v_add3_u32 v115, v114, v115, s81
	v_add_u32_e32 v114, 0x550, v113
	v_lshl_add_u32 v113, v106, 1, v114
	ds_write_b16_d16_hi v113, v115
	v_add3_u32 v115, s96, v96, 9
	s_and_b64 vcc, exec, s[6:7]
	v_cmp_lt_i32_e64 s[18:19], s79, v115
	v_mul_f32_e32 v115, 0xbfb8aa3b, v21
	v_exp_f32_e32 v115, v115
	s_nop 0
	v_add_f32_e32 v115, 1.0, v115
	v_div_scale_f32 v116, s[20:21], v115, v115, 1.0
	v_rcp_f32_e32 v117, v116
	v_div_scale_f32 v118, vcc, 1.0, v115, 1.0
	v_fma_f32 v119, -v116, v117, 1.0
	v_fmac_f32_e32 v117, v119, v117
	v_mul_f32_e32 v119, v118, v117
	v_fma_f32 v120, -v116, v119, v118
	v_fmac_f32_e32 v119, v120, v117
	v_fma_f32 v116, -v116, v119, v118
	v_div_fmas_f32 v116, v116, v117, v119
	v_div_fixup_f32 v115, v116, v115, 1.0
	v_bfe_u32 v116, v115, 16, 1
	v_add3_u32 v116, v115, v116, s81
	v_add_u32_e32 v115, 0x110, v114
	v_lshl_add_u32 v114, v106, 1, v115
	ds_write_b16_d16_hi v114, v116
	v_add3_u32 v116, s96, v96, 10
	s_and_b64 vcc, exec, s[6:7]
	v_cmp_lt_i32_e64 s[20:21], s79, v116
	v_mul_f32_e32 v116, 0xbfb8aa3b, v22
	v_exp_f32_e32 v116, v116
	s_nop 0
	v_add_f32_e32 v116, 1.0, v116
	v_div_scale_f32 v117, s[22:23], v116, v116, 1.0
	v_rcp_f32_e32 v118, v117
	v_div_scale_f32 v119, vcc, 1.0, v116, 1.0
	v_fma_f32 v120, -v117, v118, 1.0
	v_fmac_f32_e32 v118, v120, v118
	v_mul_f32_e32 v120, v119, v118
	v_fma_f32 v121, -v117, v120, v119
	v_fmac_f32_e32 v120, v121, v118
	v_fma_f32 v117, -v117, v120, v119
	v_div_fmas_f32 v117, v117, v118, v120
	v_div_fixup_f32 v116, v117, v116, 1.0
	v_bfe_u32 v117, v116, 16, 1
	v_add3_u32 v117, v116, v117, s81
	v_add_u32_e32 v116, 0x110, v115
	v_lshl_add_u32 v115, v106, 1, v116
	ds_write_b16_d16_hi v115, v117
	v_add3_u32 v117, s96, v96, 11
	s_and_b64 vcc, exec, s[6:7]
	v_cmp_lt_i32_e64 s[22:23], s79, v117
	v_mul_f32_e32 v117, 0xbfb8aa3b, v23
	v_exp_f32_e32 v117, v117
	s_nop 0
	v_add_f32_e32 v117, 1.0, v117
	v_div_scale_f32 v118, s[24:25], v117, v117, 1.0
	v_rcp_f32_e32 v119, v118
; __device__ __forceinline__ bf16r f2bf(float f) {
;   unsigned u = __float_as_uint(f);
;   u += 0x7fffu + ((u >> 16) & 1u);
;   return (bf16r)(u >> 16);
; }
; __device__ __forceinline__ unsigned pack2(float a, float b) { return (unsigned)f2bf(a) | ((unsigned)f2bf(b) << 16); }
; __device__ __forceinline__ float lo16(unsigned v) { return __uint_as_float(v << 16); }
; __device__ __forceinline__ float hi16(unsigned v) { return __uint_as_float(v & 0xffff0000u); }
; __device__ __forceinline__ float siluf(float x) { return x / (1.f + __expf(-x)); }
; __device__ __forceinline__ float sigmf(float x) { return 1.f / (1.f + __expf(-x)); }
; __device__ __forceinline__ void inproj_epilogue(const Params& p, int layer, int mt, int ntile, int tid,
;                                                 f32x16 (&acc)[2][2], unsigned char* smem) {
;     ...
;     acc_foreach(tid, acc, [&](int row, int col, float v) {
;       int t = m0 + row;
;       float o = v;
;       if (mode == 1) o = (t >= NPADR) ? v : 0.f;
;       if (mode == 2) o = sigmf(v);
;       sT[row * 136 + col] = f2bf(o);
;     });
	v_div_scale_f32 v120, vcc, 1.0, v117, 1.0
	v_fma_f32 v121, -v118, v119, 1.0
	v_fmac_f32_e32 v119, v121, v119
	v_mul_f32_e32 v121, v120, v119
	v_fma_f32 v122, -v118, v121, v120
	v_fmac_f32_e32 v121, v122, v119
	v_fma_f32 v118, -v118, v121, v120
	v_div_fmas_f32 v118, v118, v119, v121
	v_div_fixup_f32 v117, v118, v117, 1.0
	v_bfe_u32 v118, v117, 16, 1
	v_add_u32_e32 v116, 0x110, v116
	v_add3_u32 v118, v117, v118, s81
	v_lshl_add_u32 v117, v106, 1, v116
	ds_write_b16_d16_hi v117, v118
	v_add3_u32 v118, s96, v96, 16
	s_and_b64 vcc, exec, s[6:7]
	v_cmp_lt_i32_e64 s[24:25], s79, v118
	v_mul_f32_e32 v118, 0xbfb8aa3b, v24
	v_exp_f32_e32 v118, v118
	s_nop 0
	v_add_f32_e32 v118, 1.0, v118
	v_div_scale_f32 v119, s[26:27], v118, v118, 1.0
	v_rcp_f32_e32 v120, v119
	v_div_scale_f32 v121, vcc, 1.0, v118, 1.0
	v_fma_f32 v122, -v119, v120, 1.0
	v_fmac_f32_e32 v120, v122, v120
	v_mul_f32_e32 v122, v121, v120
	v_fma_f32 v123, -v119, v122, v121
	v_fmac_f32_e32 v122, v123, v120
	v_fma_f32 v119, -v119, v122, v121
	v_div_fmas_f32 v119, v119, v120, v122
	v_div_fixup_f32 v118, v119, v118, 1.0
	v_bfe_u32 v119, v118, 16, 1
	v_add_u32_e32 v116, 0x550, v116
	v_add3_u32 v119, v118, v119, s81
	v_lshl_add_u32 v118, v106, 1, v116
	ds_write_b16_d16_hi v118, v119
	v_add3_u32 v119, s96, v96, 17
	s_and_b64 vcc, exec, s[6:7]
	v_cmp_lt_i32_e64 s[26:27], s79, v119
	v_mul_f32_e32 v119, 0xbfb8aa3b, v25
	v_exp_f32_e32 v119, v119
	s_nop 0
	v_add_f32_e32 v119, 1.0, v119
	v_div_scale_f32 v120, s[28:29], v119, v119, 1.0
	v_rcp_f32_e32 v121, v120
	v_div_scale_f32 v122, vcc, 1.0, v119, 1.0
	v_fma_f32 v123, -v120, v121, 1.0
	v_fmac_f32_e32 v121, v123, v121
	v_mul_f32_e32 v123, v122, v121
	v_fma_f32 v124, -v120, v123, v122
	v_fmac_f32_e32 v123, v124, v121
	v_fma_f32 v120, -v120, v123, v122
	v_div_fmas_f32 v120, v120, v121, v123
	v_div_fixup_f32 v119, v120, v119, 1.0
	v_bfe_u32 v120, v119, 16, 1
	v_add_u32_e32 v116, 0x110, v116
	v_add3_u32 v120, v119, v120, s81
	v_lshl_add_u32 v119, v106, 1, v116
	ds_write_b16_d16_hi v119, v120
	v_add3_u32 v120, s96, v96, 18
	s_and_b64 vcc, exec, s[6:7]
	v_cmp_lt_i32_e64 s[28:29], s79, v120
	v_mul_f32_e32 v120, 0xbfb8aa3b, v26
	v_exp_f32_e32 v120, v120
	s_nop 0
	v_add_f32_e32 v120, 1.0, v120
	v_div_scale_f32 v121, s[30:31], v120, v120, 1.0
	v_rcp_f32_e32 v122, v121
	v_div_scale_f32 v123, vcc, 1.0, v120, 1.0
	v_fma_f32 v124, -v121, v122, 1.0
	v_fmac_f32_e32 v122, v124, v122
	v_mul_f32_e32 v124, v123, v122
	v_fma_f32 v125, -v121, v124, v123
	v_fmac_f32_e32 v124, v125, v122
	v_fma_f32 v121, -v121, v124, v123
	v_div_fmas_f32 v121, v121, v122, v124
	v_div_fixup_f32 v120, v121, v120, 1.0
	v_bfe_u32 v121, v120, 16, 1
	v_add_u32_e32 v116, 0x110, v116
	v_add3_u32 v121, v120, v121, s81
	v_lshl_add_u32 v120, v106, 1, v116
	ds_write_b16_d16_hi v120, v121
	v_add3_u32 v121, s96, v96, 19
	s_and_b64 vcc, exec, s[6:7]
	v_cmp_lt_i32_e64 s[30:31], s79, v121
	v_mul_f32_e32 v121, 0xbfb8aa3b, v27
	v_exp_f32_e32 v121, v121
	s_nop 0
	v_add_f32_e32 v121, 1.0, v121
	v_div_scale_f32 v122, s[34:35], v121, v121, 1.0
	v_rcp_f32_e32 v123, v122
	v_div_scale_f32 v124, vcc, 1.0, v121, 1.0
	v_fma_f32 v125, -v122, v123, 1.0
	v_fmac_f32_e32 v123, v125, v123
	v_mul_f32_e32 v125, v124, v123
	v_fma_f32 v126, -v122, v125, v124
	v_fmac_f32_e32 v125, v126, v123
	v_fma_f32 v122, -v122, v125, v124
	v_div_fmas_f32 v122, v122, v123, v125
	v_div_fixup_f32 v121, v122, v121, 1.0
	v_bfe_u32 v122, v121, 16, 1
	v_add_u32_e32 v116, 0x110, v116
	v_add3_u32 v122, v121, v122, s81
	v_lshl_add_u32 v121, v106, 1, v116
	ds_write_b16_d16_hi v121, v122
	v_add3_u32 v122, s96, v96, 24
	s_and_b64 vcc, exec, s[6:7]
	v_cmp_lt_i32_e64 s[34:35], s79, v122
	v_mul_f32_e32 v122, 0xbfb8aa3b, v28
	v_exp_f32_e32 v122, v122
	s_nop 0
	v_add_f32_e32 v122, 1.0, v122
	v_div_scale_f32 v123, s[36:37], v122, v122, 1.0
	v_rcp_f32_e32 v124, v123
	v_div_scale_f32 v125, vcc, 1.0, v122, 1.0
	v_fma_f32 v126, -v123, v124, 1.0
	v_fmac_f32_e32 v124, v126, v124
	v_mul_f32_e32 v126, v125, v124
	v_fma_f32 v127, -v123, v126, v125
	v_fmac_f32_e32 v126, v127, v124
	v_fma_f32 v123, -v123, v126, v125
	v_div_fmas_f32 v123, v123, v124, v126
	v_div_fixup_f32 v122, v123, v122, 1.0
	v_bfe_u32 v123, v122, 16, 1
	v_add_u32_e32 v116, 0x550, v116
	v_add3_u32 v123, v122, v123, s81
	v_lshl_add_u32 v122, v106, 1, v116
	ds_write_b16_d16_hi v122, v123
	v_add3_u32 v123, s96, v96, 25
	s_and_b64 vcc, exec, s[6:7]
	v_cmp_lt_i32_e64 s[36:37], s79, v123
	v_mul_f32_e32 v123, 0xbfb8aa3b, v29
	v_exp_f32_e32 v123, v123
	s_nop 0
	v_add_f32_e32 v123, 1.0, v123
	v_div_scale_f32 v124, s[38:39], v123, v123, 1.0
	v_rcp_f32_e32 v125, v124
	v_div_scale_f32 v126, vcc, 1.0, v123, 1.0
	v_fma_f32 v127, -v124, v125, 1.0
	v_fmac_f32_e32 v125, v127, v125
	v_mul_f32_e32 v127, v126, v125
	v_fma_f32 v128, -v124, v127, v126
	v_fmac_f32_e32 v127, v128, v125
	v_fma_f32 v124, -v124, v127, v126
	v_div_fmas_f32 v124, v124, v125, v127
	v_div_fixup_f32 v123, v124, v123, 1.0
	v_bfe_u32 v124, v123, 16, 1
	v_add_u32_e32 v116, 0x110, v116
	v_add3_u32 v124, v123, v124, s81
	v_lshl_add_u32 v123, v106, 1, v116
	ds_write_b16_d16_hi v123, v124
	v_add3_u32 v124, s96, v96, 26
	s_and_b64 vcc, exec, s[6:7]
	v_cmp_lt_i32_e64 s[38:39], s79, v124
	v_mul_f32_e32 v124, 0xbfb8aa3b, v30
	v_exp_f32_e32 v124, v124
	s_nop 0
	v_add_f32_e32 v124, 1.0, v124
	v_div_scale_f32 v125, s[40:41], v124, v124, 1.0
	v_rcp_f32_e32 v126, v125
	v_div_scale_f32 v127, vcc, 1.0, v124, 1.0
	v_fma_f32 v128, -v125, v126, 1.0
	v_fmac_f32_e32 v126, v128, v126
	v_mul_f32_e32 v128, v127, v126
	v_fma_f32 v129, -v125, v128, v127
	v_fmac_f32_e32 v128, v129, v126
	v_fma_f32 v125, -v125, v128, v127
	v_div_fmas_f32 v125, v125, v126, v128
; __device__ __forceinline__ bf16r f2bf(float f) {
;   unsigned u = __float_as_uint(f);
;   u += 0x7fffu + ((u >> 16) & 1u);
;   return (bf16r)(u >> 16);
; }
; __device__ __forceinline__ unsigned pack2(float a, float b) { return (unsigned)f2bf(a) | ((unsigned)f2bf(b) << 16); }
; __device__ __forceinline__ float lo16(unsigned v) { return __uint_as_float(v << 16); }
; __device__ __forceinline__ float hi16(unsigned v) { return __uint_as_float(v & 0xffff0000u); }
; __device__ __forceinline__ float siluf(float x) { return x / (1.f + __expf(-x)); }
; __device__ __forceinline__ float sigmf(float x) { return 1.f / (1.f + __expf(-x)); }
; __device__ __forceinline__ void inproj_epilogue(const Params& p, int layer, int mt, int ntile, int tid,
;                                                 f32x16 (&acc)[2][2], unsigned char* smem) {
;     ...
;     acc_foreach(tid, acc, [&](int row, int col, float v) {
;       int t = m0 + row;
;       float o = v;
;       if (mode == 1) o = (t >= NPADR) ? v : 0.f;
;       if (mode == 2) o = sigmf(v);
;       sT[row * 136 + col] = f2bf(o);
;     });
	v_div_fixup_f32 v124, v125, v124, 1.0
	v_bfe_u32 v125, v124, 16, 1
	v_add_u32_e32 v116, 0x110, v116
	v_add3_u32 v124, v124, v125, s81
	v_lshl_add_u32 v116, v106, 1, v116
	ds_write_b16_d16_hi v116, v124
	v_add3_u32 v124, s96, v96, 27
	s_and_b64 vcc, exec, s[6:7]
	v_cmp_lt_i32_e64 s[40:41], s79, v124
	v_mul_f32_e32 v124, 0xbfb8aa3b, v31
	v_exp_f32_e32 v124, v124
	s_nop 0
	v_add_f32_e32 v124, 1.0, v124
	v_div_scale_f32 v125, vcc, v124, v124, 1.0
	v_rcp_f32_e32 v126, v125
	v_div_scale_f32 v127, vcc, 1.0, v124, 1.0
	v_fma_f32 v128, -v125, v126, 1.0
	v_fmac_f32_e32 v126, v128, v126
	v_mul_f32_e32 v128, v127, v126
	v_fma_f32 v129, -v125, v128, v127
	v_fmac_f32_e32 v128, v129, v126
	v_fma_f32 v125, -v125, v128, v127
	v_div_fmas_f32 v125, v125, v126, v128
	v_div_fixup_f32 v124, v125, v124, 1.0
	v_bfe_u32 v125, v124, 16, 1
	v_add3_u32 v124, v124, v125, s81
	ds_write_b16_d16_hi v116, v124 offset:272
	s_and_b64 vcc, exec, s[6:7]
	v_mul_f32_e32 v48, 0xbfb8aa3b, v48
	v_exp_f32_e32 v48, v48
	s_nop 0
	v_add_f32_e32 v48, 1.0, v48
	v_div_scale_f32 v124, s[8:9], v48, v48, 1.0
	v_rcp_f32_e32 v125, v124
	v_div_scale_f32 v126, vcc, 1.0, v48, 1.0
	v_fma_f32 v127, -v124, v125, 1.0
	v_fmac_f32_e32 v125, v127, v125
	v_mul_f32_e32 v127, v126, v125
	v_fma_f32 v128, -v124, v127, v126
	v_fmac_f32_e32 v127, v128, v125
	v_fma_f32 v124, -v124, v127, v126
	v_div_fmas_f32 v124, v124, v125, v127
	v_div_fixup_f32 v48, v124, v48, 1.0
	v_bfe_u32 v124, v48, 16, 1
	v_add3_u32 v48, v48, v124, s81
	s_and_b64 vcc, exec, s[6:7]
	ds_write_b16_d16_hi v107, v48 offset:64
	v_mul_f32_e32 v48, 0xbfb8aa3b, v49
	v_exp_f32_e32 v48, v48
	s_nop 0
	v_add_f32_e32 v48, 1.0, v48
	v_div_scale_f32 v49, s[8:9], v48, v48, 1.0
	v_rcp_f32_e32 v107, v49
	v_div_scale_f32 v124, vcc, 1.0, v48, 1.0
	v_fma_f32 v125, -v49, v107, 1.0
	v_fmac_f32_e32 v107, v125, v107
	v_mul_f32_e32 v125, v124, v107
	v_fma_f32 v126, -v49, v125, v124
	v_fmac_f32_e32 v125, v126, v107
	v_fma_f32 v49, -v49, v125, v124
	v_div_fmas_f32 v49, v49, v107, v125
	v_div_fixup_f32 v48, v49, v48, 1.0
	v_bfe_u32 v49, v48, 16, 1
	v_add3_u32 v48, v48, v49, s81
	s_and_b64 vcc, exec, s[6:7]
	ds_write_b16_d16_hi v110, v48 offset:64
	v_mul_f32_e32 v48, 0xbfb8aa3b, v50
	v_exp_f32_e32 v48, v48
	s_nop 0
	v_add_f32_e32 v48, 1.0, v48
	v_div_scale_f32 v49, s[8:9], v48, v48, 1.0
	v_rcp_f32_e32 v50, v49
	v_div_scale_f32 v107, vcc, 1.0, v48, 1.0
	v_fma_f32 v110, -v49, v50, 1.0
	v_fmac_f32_e32 v50, v110, v50
	v_mul_f32_e32 v110, v107, v50
	v_fma_f32 v124, -v49, v110, v107
	v_fmac_f32_e32 v110, v124, v50
	v_fma_f32 v49, -v49, v110, v107
	v_div_fmas_f32 v49, v49, v50, v110
	v_div_fixup_f32 v48, v49, v48, 1.0
	v_bfe_u32 v49, v48, 16, 1
	v_add3_u32 v48, v48, v49, s81
	s_and_b64 vcc, exec, s[6:7]
	ds_write_b16_d16_hi v111, v48 offset:64
	v_mul_f32_e32 v48, 0xbfb8aa3b, v51
	v_exp_f32_e32 v48, v48
	s_nop 0
	v_add_f32_e32 v48, 1.0, v48
	v_div_scale_f32 v49, s[8:9], v48, v48, 1.0
	v_rcp_f32_e32 v50, v49
	v_div_scale_f32 v51, vcc, 1.0, v48, 1.0
	v_fma_f32 v107, -v49, v50, 1.0
	v_fmac_f32_e32 v50, v107, v50
	v_mul_f32_e32 v107, v51, v50
	v_fma_f32 v110, -v49, v107, v51
	v_fmac_f32_e32 v107, v110, v50
	v_fma_f32 v49, -v49, v107, v51
	v_div_fmas_f32 v49, v49, v50, v107
	v_div_fixup_f32 v48, v49, v48, 1.0
	v_bfe_u32 v49, v48, 16, 1
	v_add3_u32 v48, v48, v49, s81
	s_and_b64 vcc, exec, s[6:7]
	ds_write_b16_d16_hi v112, v48 offset:64
	v_mul_f32_e32 v48, 0xbfb8aa3b, v52
	v_exp_f32_e32 v48, v48
	s_nop 0
	v_add_f32_e32 v48, 1.0, v48
	v_div_scale_f32 v49, s[8:9], v48, v48, 1.0
	v_rcp_f32_e32 v50, v49
	v_div_scale_f32 v51, vcc, 1.0, v48, 1.0
	v_fma_f32 v52, -v49, v50, 1.0
	v_fmac_f32_e32 v50, v52, v50
	v_mul_f32_e32 v52, v51, v50
	v_fma_f32 v107, -v49, v52, v51
	v_fmac_f32_e32 v52, v107, v50
	v_fma_f32 v49, -v49, v52, v51
	v_div_fmas_f32 v49, v49, v50, v52
	v_div_fixup_f32 v48, v49, v48, 1.0
	v_bfe_u32 v49, v48, 16, 1
	v_add3_u32 v48, v48, v49, s81
	s_and_b64 vcc, exec, s[6:7]
	ds_write_b16_d16_hi v113, v48 offset:64
	v_mul_f32_e32 v48, 0xbfb8aa3b, v53
	v_exp_f32_e32 v48, v48
	s_nop 0
	v_add_f32_e32 v48, 1.0, v48
	v_div_scale_f32 v49, s[8:9], v48, v48, 1.0
	v_rcp_f32_e32 v50, v49
	v_div_scale_f32 v51, vcc, 1.0, v48, 1.0
	v_fma_f32 v52, -v49, v50, 1.0
	v_fmac_f32_e32 v50, v52, v50
	v_mul_f32_e32 v52, v51, v50
	v_fma_f32 v53, -v49, v52, v51
	v_fmac_f32_e32 v52, v53, v50
	v_fma_f32 v49, -v49, v52, v51
	v_div_fmas_f32 v49, v49, v50, v52
	v_div_fixup_f32 v48, v49, v48, 1.0
	v_bfe_u32 v49, v48, 16, 1
	v_add3_u32 v48, v48, v49, s81
	s_and_b64 vcc, exec, s[6:7]
	ds_write_b16_d16_hi v114, v48 offset:64
	v_mul_f32_e32 v48, 0xbfb8aa3b, v54
	v_exp_f32_e32 v48, v48
	s_nop 0
	v_add_f32_e32 v48, 1.0, v48
	v_div_scale_f32 v49, s[8:9], v48, v48, 1.0
	v_rcp_f32_e32 v50, v49
	v_div_scale_f32 v51, vcc, 1.0, v48, 1.0
	v_fma_f32 v52, -v49, v50, 1.0
	v_fmac_f32_e32 v50, v52, v50
	v_mul_f32_e32 v52, v51, v50
	v_fma_f32 v53, -v49, v52, v51
	v_fmac_f32_e32 v52, v53, v50
	v_fma_f32 v49, -v49, v52, v51
	v_div_fmas_f32 v49, v49, v50, v52
	v_div_fixup_f32 v48, v49, v48, 1.0
	v_bfe_u32 v49, v48, 16, 1
	v_add3_u32 v48, v48, v49, s81
	s_and_b64 vcc, exec, s[6:7]
	ds_write_b16_d16_hi v115, v48 offset:64
	v_mul_f32_e32 v48, 0xbfb8aa3b, v55
	v_exp_f32_e32 v48, v48
	s_nop 0
	v_add_f32_e32 v48, 1.0, v48
	v_div_scale_f32 v49, s[8:9], v48, v48, 1.0
	v_rcp_f32_e32 v50, v49
	v_div_scale_f32 v51, vcc, 1.0, v48, 1.0
	v_fma_f32 v52, -v49, v50, 1.0
	v_fmac_f32_e32 v50, v52, v50
	v_mul_f32_e32 v52, v51, v50
	v_fma_f32 v53, -v49, v52, v51
	v_fmac_f32_e32 v52, v53, v50
	v_fma_f32 v49, -v49, v52, v51
	v_div_fmas_f32 v49, v49, v50, v52
	v_div_fixup_f32 v48, v49, v48, 1.0
	v_bfe_u32 v49, v48, 16, 1
	v_add3_u32 v48, v48, v49, s81
; __device__ __forceinline__ bf16r f2bf(float f) {
;   unsigned u = __float_as_uint(f);
;   u += 0x7fffu + ((u >> 16) & 1u);
;   return (bf16r)(u >> 16);
; }
; __device__ __forceinline__ unsigned pack2(float a, float b) { return (unsigned)f2bf(a) | ((unsigned)f2bf(b) << 16); }
; __device__ __forceinline__ float lo16(unsigned v) { return __uint_as_float(v << 16); }
; __device__ __forceinline__ float hi16(unsigned v) { return __uint_as_float(v & 0xffff0000u); }
; __device__ __forceinline__ float siluf(float x) { return x / (1.f + __expf(-x)); }
; __device__ __forceinline__ float sigmf(float x) { return 1.f / (1.f + __expf(-x)); }
; __device__ __forceinline__ void inproj_epilogue(const Params& p, int layer, int mt, int ntile, int tid,
;                                                 f32x16 (&acc)[2][2], unsigned char* smem) {
;     ...
;     acc_foreach(tid, acc, [&](int row, int col, float v) {
;       int t = m0 + row;
;       float o = v;
;       if (mode == 1) o = (t >= NPADR) ? v : 0.f;
;       if (mode == 2) o = sigmf(v);
;       sT[row * 136 + col] = f2bf(o);
;     });
	s_and_b64 vcc, exec, s[6:7]
	ds_write_b16_d16_hi v117, v48 offset:64
	v_mul_f32_e32 v48, 0xbfb8aa3b, v56
	v_exp_f32_e32 v48, v48
	s_nop 0
	v_add_f32_e32 v48, 1.0, v48
	v_div_scale_f32 v49, s[8:9], v48, v48, 1.0
	v_rcp_f32_e32 v50, v49
	v_div_scale_f32 v51, vcc, 1.0, v48, 1.0
	v_fma_f32 v52, -v49, v50, 1.0
	v_fmac_f32_e32 v50, v52, v50
	v_mul_f32_e32 v52, v51, v50
	v_fma_f32 v53, -v49, v52, v51
	v_fmac_f32_e32 v52, v53, v50
	v_fma_f32 v49, -v49, v52, v51
	v_div_fmas_f32 v49, v49, v50, v52
	v_div_fixup_f32 v48, v49, v48, 1.0
	v_bfe_u32 v49, v48, 16, 1
	v_add3_u32 v48, v48, v49, s81
	s_and_b64 vcc, exec, s[6:7]
	ds_write_b16_d16_hi v118, v48 offset:64
	v_mul_f32_e32 v48, 0xbfb8aa3b, v57
	v_exp_f32_e32 v48, v48
	s_nop 0
	v_add_f32_e32 v48, 1.0, v48
	v_div_scale_f32 v49, s[8:9], v48, v48, 1.0
	v_rcp_f32_e32 v50, v49
	v_div_scale_f32 v51, vcc, 1.0, v48, 1.0
	v_fma_f32 v52, -v49, v50, 1.0
	v_fmac_f32_e32 v50, v52, v50
	v_mul_f32_e32 v52, v51, v50
	v_fma_f32 v53, -v49, v52, v51
	v_fmac_f32_e32 v52, v53, v50
	v_fma_f32 v49, -v49, v52, v51
	v_div_fmas_f32 v49, v49, v50, v52
	v_div_fixup_f32 v48, v49, v48, 1.0
	v_bfe_u32 v49, v48, 16, 1
	v_add3_u32 v48, v48, v49, s81
	s_and_b64 vcc, exec, s[6:7]
	ds_write_b16_d16_hi v119, v48 offset:64
	v_mul_f32_e32 v48, 0xbfb8aa3b, v58
	v_exp_f32_e32 v48, v48
	s_nop 0
	v_add_f32_e32 v48, 1.0, v48
	v_div_scale_f32 v49, s[8:9], v48, v48, 1.0
	v_rcp_f32_e32 v50, v49
	v_div_scale_f32 v51, vcc, 1.0, v48, 1.0
	v_fma_f32 v52, -v49, v50, 1.0
	v_fmac_f32_e32 v50, v52, v50
	v_mul_f32_e32 v52, v51, v50
	v_fma_f32 v53, -v49, v52, v51
	v_fmac_f32_e32 v52, v53, v50
	v_fma_f32 v49, -v49, v52, v51
	v_div_fmas_f32 v49, v49, v50, v52
	v_div_fixup_f32 v48, v49, v48, 1.0
	v_bfe_u32 v49, v48, 16, 1
	v_add3_u32 v48, v48, v49, s81
	s_and_b64 vcc, exec, s[6:7]
	ds_write_b16_d16_hi v120, v48 offset:64
	v_mul_f32_e32 v48, 0xbfb8aa3b, v59
	v_exp_f32_e32 v48, v48
	s_nop 0
	v_add_f32_e32 v48, 1.0, v48
	v_div_scale_f32 v49, s[8:9], v48, v48, 1.0
	v_rcp_f32_e32 v50, v49
	v_div_scale_f32 v51, vcc, 1.0, v48, 1.0
	v_fma_f32 v52, -v49, v50, 1.0
	v_fmac_f32_e32 v50, v52, v50
	v_mul_f32_e32 v52, v51, v50
	v_fma_f32 v53, -v49, v52, v51
	v_fmac_f32_e32 v52, v53, v50
	v_fma_f32 v49, -v49, v52, v51
	v_div_fmas_f32 v49, v49, v50, v52
	v_div_fixup_f32 v48, v49, v48, 1.0
	v_bfe_u32 v49, v48, 16, 1
	v_add3_u32 v48, v48, v49, s81
	s_and_b64 vcc, exec, s[6:7]
	ds_write_b16_d16_hi v121, v48 offset:64
	v_mul_f32_e32 v48, 0xbfb8aa3b, v60
	v_exp_f32_e32 v48, v48
	s_nop 0
	v_add_f32_e32 v48, 1.0, v48
	v_div_scale_f32 v49, s[8:9], v48, v48, 1.0
	v_rcp_f32_e32 v50, v49
	v_div_scale_f32 v51, vcc, 1.0, v48, 1.0
	v_fma_f32 v52, -v49, v50, 1.0
	v_fmac_f32_e32 v50, v52, v50
	v_mul_f32_e32 v52, v51, v50
	v_fma_f32 v53, -v49, v52, v51
	v_fmac_f32_e32 v52, v53, v50
	v_fma_f32 v49, -v49, v52, v51
	v_div_fmas_f32 v49, v49, v50, v52
	v_div_fixup_f32 v48, v49, v48, 1.0
	v_bfe_u32 v49, v48, 16, 1
	v_add3_u32 v48, v48, v49, s81
	s_and_b64 vcc, exec, s[6:7]
	ds_write_b16_d16_hi v122, v48 offset:64
	v_mul_f32_e32 v48, 0xbfb8aa3b, v61
	v_exp_f32_e32 v48, v48
	s_nop 0
	v_add_f32_e32 v48, 1.0, v48
	v_div_scale_f32 v49, s[8:9], v48, v48, 1.0
	v_rcp_f32_e32 v50, v49
	v_div_scale_f32 v51, vcc, 1.0, v48, 1.0
	v_fma_f32 v52, -v49, v50, 1.0
	v_fmac_f32_e32 v50, v52, v50
	v_mul_f32_e32 v52, v51, v50
	v_fma_f32 v53, -v49, v52, v51
	v_fmac_f32_e32 v52, v53, v50
	v_fma_f32 v49, -v49, v52, v51
	v_div_fmas_f32 v49, v49, v50, v52
	v_div_fixup_f32 v48, v49, v48, 1.0
	v_bfe_u32 v49, v48, 16, 1
	v_add3_u32 v48, v48, v49, s81
	s_and_b64 vcc, exec, s[6:7]
	ds_write_b16_d16_hi v123, v48 offset:64
	v_mul_f32_e32 v48, 0xbfb8aa3b, v62
	v_exp_f32_e32 v48, v48
	s_nop 0
	v_add_f32_e32 v48, 1.0, v48
	v_div_scale_f32 v49, s[8:9], v48, v48, 1.0
	v_rcp_f32_e32 v50, v49
	v_div_scale_f32 v51, vcc, 1.0, v48, 1.0
	v_fma_f32 v52, -v49, v50, 1.0
	v_fmac_f32_e32 v50, v52, v50
	v_mul_f32_e32 v52, v51, v50
	v_fma_f32 v53, -v49, v52, v51
	v_fmac_f32_e32 v52, v53, v50
	v_fma_f32 v49, -v49, v52, v51
	v_div_fmas_f32 v49, v49, v50, v52
	v_div_fixup_f32 v48, v49, v48, 1.0
	v_bfe_u32 v49, v48, 16, 1
	v_add3_u32 v48, v48, v49, s81
	s_and_b64 vcc, exec, s[6:7]
	ds_write_b16_d16_hi v116, v48 offset:64
	v_mul_f32_e32 v48, 0xbfb8aa3b, v63
	v_exp_f32_e32 v48, v48
	s_nop 0
	v_add_f32_e32 v48, 1.0, v48
	v_div_scale_f32 v49, s[8:9], v48, v48, 1.0
	v_rcp_f32_e32 v50, v49
	v_div_scale_f32 v51, vcc, 1.0, v48, 1.0
	v_fma_f32 v52, -v49, v50, 1.0
	v_fmac_f32_e32 v50, v52, v50
	v_mul_f32_e32 v52, v51, v50
	v_fma_f32 v53, -v49, v52, v51
	v_fmac_f32_e32 v52, v53, v50
	v_fma_f32 v49, -v49, v52, v51
	v_div_fmas_f32 v49, v49, v50, v52
	v_div_fixup_f32 v48, v49, v48, 1.0
	v_bfe_u32 v50, v48, 16, 1
	v_add_u32_e32 v49, 0x110, v116
	v_add3_u32 v48, v48, v50, s81
	ds_write_b16_d16_hi v49, v48 offset:64
	v_or_b32_e32 v48, 32, v96
	v_add_u32_e32 v49, s96, v48
	s_and_b64 vcc, exec, s[6:7]
	v_cmp_lt_i32_e64 s[8:9], s79, v49
	v_mul_f32_e32 v49, 0xbfb8aa3b, v0
	v_exp_f32_e32 v49, v49
	s_nop 0
	v_add_f32_e32 v49, 1.0, v49
	v_div_scale_f32 v50, s[10:11], v49, v49, 1.0
	v_rcp_f32_e32 v51, v50
	v_div_scale_f32 v52, vcc, 1.0, v49, 1.0
	v_fma_f32 v53, -v50, v51, 1.0
	v_fmac_f32_e32 v51, v53, v51
	v_mul_f32_e32 v53, v52, v51
	v_fma_f32 v54, -v50, v53, v52
	v_fmac_f32_e32 v53, v54, v51
	v_fma_f32 v50, -v50, v53, v52
	v_div_fmas_f32 v50, v50, v51, v53
	v_div_fixup_f32 v49, v50, v49, 1.0
	v_bfe_u32 v50, v49, 16, 1
	v_add3_u32 v50, v49, v50, s81
	v_mul_lo_u32 v49, v48, s82
	v_lshl_add_u32 v48, v106, 1, v49
	ds_write_b16_d16_hi v48, v50
	v_add3_u32 v50, s96, v96, 33
	s_and_b64 vcc, exec, s[6:7]
	v_cmp_lt_i32_e64 s[10:11], s79, v50
	v_mul_f32_e32 v50, 0xbfb8aa3b, v1
; __device__ __forceinline__ bf16r f2bf(float f) {
;   unsigned u = __float_as_uint(f);
;   u += 0x7fffu + ((u >> 16) & 1u);
;   return (bf16r)(u >> 16);
; }
; __device__ __forceinline__ unsigned pack2(float a, float b) { return (unsigned)f2bf(a) | ((unsigned)f2bf(b) << 16); }
; __device__ __forceinline__ float lo16(unsigned v) { return __uint_as_float(v << 16); }
; __device__ __forceinline__ float hi16(unsigned v) { return __uint_as_float(v & 0xffff0000u); }
; __device__ __forceinline__ float siluf(float x) { return x / (1.f + __expf(-x)); }
; __device__ __forceinline__ float sigmf(float x) { return 1.f / (1.f + __expf(-x)); }
; __device__ __forceinline__ void inproj_epilogue(const Params& p, int layer, int mt, int ntile, int tid,
;                                                 f32x16 (&acc)[2][2], unsigned char* smem) {
;     ...
;     acc_foreach(tid, acc, [&](int row, int col, float v) {
;       int t = m0 + row;
;       float o = v;
;       if (mode == 1) o = (t >= NPADR) ? v : 0.f;
;       if (mode == 2) o = sigmf(v);
;       sT[row * 136 + col] = f2bf(o);
;     });
	v_exp_f32_e32 v50, v50
	s_nop 0
	v_add_f32_e32 v50, 1.0, v50
	v_div_scale_f32 v51, s[12:13], v50, v50, 1.0
	v_rcp_f32_e32 v52, v51
	v_div_scale_f32 v53, vcc, 1.0, v50, 1.0
	v_fma_f32 v54, -v51, v52, 1.0
	v_fmac_f32_e32 v52, v54, v52
	v_mul_f32_e32 v54, v53, v52
	v_fma_f32 v55, -v51, v54, v53
	v_fmac_f32_e32 v54, v55, v52
	v_fma_f32 v51, -v51, v54, v53
	v_div_fmas_f32 v51, v51, v52, v54
	v_div_fixup_f32 v50, v51, v50, 1.0
	v_bfe_u32 v51, v50, 16, 1
	v_add3_u32 v51, v50, v51, s81
	v_add_u32_e32 v50, 0x110, v49
	v_lshl_add_u32 v49, v106, 1, v50
	ds_write_b16_d16_hi v49, v51
	v_add3_u32 v51, s96, v96, 34
	s_and_b64 vcc, exec, s[6:7]
	v_cmp_lt_i32_e64 s[12:13], s79, v51
	v_mul_f32_e32 v51, 0xbfb8aa3b, v2
	v_exp_f32_e32 v51, v51
	s_nop 0
	v_add_f32_e32 v51, 1.0, v51
	v_div_scale_f32 v52, s[14:15], v51, v51, 1.0
	v_rcp_f32_e32 v53, v52
	v_div_scale_f32 v54, vcc, 1.0, v51, 1.0
	v_fma_f32 v55, -v52, v53, 1.0
	v_fmac_f32_e32 v53, v55, v53
	v_mul_f32_e32 v55, v54, v53
	v_fma_f32 v56, -v52, v55, v54
	v_fmac_f32_e32 v55, v56, v53
	v_fma_f32 v52, -v52, v55, v54
	v_div_fmas_f32 v52, v52, v53, v55
	v_div_fixup_f32 v51, v52, v51, 1.0
	v_bfe_u32 v52, v51, 16, 1
	v_add3_u32 v52, v51, v52, s81
	v_add_u32_e32 v51, 0x110, v50
	v_lshl_add_u32 v50, v106, 1, v51
	ds_write_b16_d16_hi v50, v52
	v_add3_u32 v52, s96, v96, 35
	s_and_b64 vcc, exec, s[6:7]
	v_cmp_lt_i32_e64 s[14:15], s79, v52
	v_mul_f32_e32 v52, 0xbfb8aa3b, v3
	v_exp_f32_e32 v52, v52
	s_nop 0
	v_add_f32_e32 v52, 1.0, v52
	v_div_scale_f32 v53, s[16:17], v52, v52, 1.0
	v_rcp_f32_e32 v54, v53
	v_div_scale_f32 v55, vcc, 1.0, v52, 1.0
	v_fma_f32 v56, -v53, v54, 1.0
	v_fmac_f32_e32 v54, v56, v54
	v_mul_f32_e32 v56, v55, v54
	v_fma_f32 v57, -v53, v56, v55
	v_fmac_f32_e32 v56, v57, v54
	v_fma_f32 v53, -v53, v56, v55
	v_div_fmas_f32 v53, v53, v54, v56
	v_div_fixup_f32 v52, v53, v52, 1.0
	v_bfe_u32 v53, v52, 16, 1
	v_add3_u32 v53, v52, v53, s81
	v_add_u32_e32 v52, 0x110, v51
	v_lshl_add_u32 v51, v106, 1, v52
	ds_write_b16_d16_hi v51, v53
	v_add3_u32 v53, s96, v96, 40
	s_and_b64 vcc, exec, s[6:7]
	v_cmp_lt_i32_e64 s[16:17], s79, v53
	v_mul_f32_e32 v53, 0xbfb8aa3b, v4
	v_exp_f32_e32 v53, v53
	s_nop 0
	v_add_f32_e32 v53, 1.0, v53
	v_div_scale_f32 v54, s[18:19], v53, v53, 1.0
	v_rcp_f32_e32 v55, v54
	v_div_scale_f32 v56, vcc, 1.0, v53, 1.0
	v_fma_f32 v57, -v54, v55, 1.0
	v_fmac_f32_e32 v55, v57, v55
	v_mul_f32_e32 v57, v56, v55
	v_fma_f32 v58, -v54, v57, v56
	v_fmac_f32_e32 v57, v58, v55
	v_fma_f32 v54, -v54, v57, v56
	v_div_fmas_f32 v54, v54, v55, v57
	v_div_fixup_f32 v53, v54, v53, 1.0
	v_bfe_u32 v54, v53, 16, 1
	v_add3_u32 v54, v53, v54, s81
	v_add_u32_e32 v53, 0x550, v52
	v_lshl_add_u32 v52, v106, 1, v53
	ds_write_b16_d16_hi v52, v54
	v_add3_u32 v54, s96, v96, 41
	s_and_b64 vcc, exec, s[6:7]
	v_cmp_lt_i32_e64 s[18:19], s79, v54
	v_mul_f32_e32 v54, 0xbfb8aa3b, v5
	v_exp_f32_e32 v54, v54
	s_nop 0
	v_add_f32_e32 v54, 1.0, v54
	v_div_scale_f32 v55, s[20:21], v54, v54, 1.0
	v_rcp_f32_e32 v56, v55
	v_div_scale_f32 v57, vcc, 1.0, v54, 1.0
	v_fma_f32 v58, -v55, v56, 1.0
	v_fmac_f32_e32 v56, v58, v56
	v_mul_f32_e32 v58, v57, v56
	v_fma_f32 v59, -v55, v58, v57
	v_fmac_f32_e32 v58, v59, v56
	v_fma_f32 v55, -v55, v58, v57
	v_div_fmas_f32 v55, v55, v56, v58
	v_div_fixup_f32 v54, v55, v54, 1.0
	v_bfe_u32 v55, v54, 16, 1
	v_add3_u32 v55, v54, v55, s81
	v_add_u32_e32 v54, 0x110, v53
	v_lshl_add_u32 v53, v106, 1, v54
	ds_write_b16_d16_hi v53, v55
	v_add3_u32 v55, s96, v96, 42
	s_and_b64 vcc, exec, s[6:7]
	v_cmp_lt_i32_e64 s[20:21], s79, v55
	v_mul_f32_e32 v55, 0xbfb8aa3b, v6
	v_exp_f32_e32 v55, v55
	s_nop 0
	v_add_f32_e32 v55, 1.0, v55
	v_div_scale_f32 v56, s[22:23], v55, v55, 1.0
	v_rcp_f32_e32 v57, v56
	v_div_scale_f32 v58, vcc, 1.0, v55, 1.0
	v_fma_f32 v59, -v56, v57, 1.0
	v_fmac_f32_e32 v57, v59, v57
	v_mul_f32_e32 v59, v58, v57
	v_fma_f32 v60, -v56, v59, v58
	v_fmac_f32_e32 v59, v60, v57
	v_fma_f32 v56, -v56, v59, v58
	v_div_fmas_f32 v56, v56, v57, v59
	v_div_fixup_f32 v55, v56, v55, 1.0
	v_bfe_u32 v56, v55, 16, 1
	v_add3_u32 v56, v55, v56, s81
	v_add_u32_e32 v55, 0x110, v54
	v_lshl_add_u32 v54, v106, 1, v55
	ds_write_b16_d16_hi v54, v56
	v_add3_u32 v56, s96, v96, 43
	s_and_b64 vcc, exec, s[6:7]
	v_cmp_lt_i32_e64 s[22:23], s79, v56
	v_mul_f32_e32 v56, 0xbfb8aa3b, v7
	v_exp_f32_e32 v56, v56
	s_nop 0
	v_add_f32_e32 v56, 1.0, v56
	v_div_scale_f32 v57, s[24:25], v56, v56, 1.0
	v_rcp_f32_e32 v58, v57
	v_div_scale_f32 v59, vcc, 1.0, v56, 1.0
	v_fma_f32 v60, -v57, v58, 1.0
	v_fmac_f32_e32 v58, v60, v58
	v_mul_f32_e32 v60, v59, v58
	v_fma_f32 v61, -v57, v60, v59
	v_fmac_f32_e32 v60, v61, v58
	v_fma_f32 v57, -v57, v60, v59
	v_div_fmas_f32 v57, v57, v58, v60
	v_div_fixup_f32 v56, v57, v56, 1.0
	v_bfe_u32 v57, v56, 16, 1
	v_add_u32_e32 v55, 0x110, v55
	v_add3_u32 v57, v56, v57, s81
	v_lshl_add_u32 v56, v106, 1, v55
	ds_write_b16_d16_hi v56, v57
	v_add3_u32 v57, s96, v96, 48
	s_and_b64 vcc, exec, s[6:7]
	v_cmp_lt_i32_e64 s[24:25], s79, v57
	v_mul_f32_e32 v57, 0xbfb8aa3b, v8
	v_exp_f32_e32 v57, v57
	s_nop 0
	v_add_f32_e32 v57, 1.0, v57
	v_div_scale_f32 v58, s[26:27], v57, v57, 1.0
	v_rcp_f32_e32 v59, v58
	v_div_scale_f32 v60, vcc, 1.0, v57, 1.0
	v_fma_f32 v61, -v58, v59, 1.0
	v_fmac_f32_e32 v59, v61, v59
	v_mul_f32_e32 v61, v60, v59
	v_fma_f32 v62, -v58, v61, v60
	v_fmac_f32_e32 v61, v62, v59
	v_fma_f32 v58, -v58, v61, v60
	v_div_fmas_f32 v58, v58, v59, v61
	v_div_fixup_f32 v57, v58, v57, 1.0
	v_bfe_u32 v58, v57, 16, 1
	v_add_u32_e32 v55, 0x550, v55
	v_add3_u32 v58, v57, v58, s81
	v_lshl_add_u32 v57, v106, 1, v55
	ds_write_b16_d16_hi v57, v58
	v_add3_u32 v58, s96, v96, 49
	s_and_b64 vcc, exec, s[6:7]
	v_cmp_lt_i32_e64 s[26:27], s79, v58
; __device__ __forceinline__ bf16r f2bf(float f) {
;   unsigned u = __float_as_uint(f);
;   u += 0x7fffu + ((u >> 16) & 1u);
;   return (bf16r)(u >> 16);
; }
; __device__ __forceinline__ unsigned pack2(float a, float b) { return (unsigned)f2bf(a) | ((unsigned)f2bf(b) << 16); }
; __device__ __forceinline__ float lo16(unsigned v) { return __uint_as_float(v << 16); }
; __device__ __forceinline__ float hi16(unsigned v) { return __uint_as_float(v & 0xffff0000u); }
; __device__ __forceinline__ float siluf(float x) { return x / (1.f + __expf(-x)); }
; __device__ __forceinline__ float sigmf(float x) { return 1.f / (1.f + __expf(-x)); }
; __device__ __forceinline__ void inproj_epilogue(const Params& p, int layer, int mt, int ntile, int tid,
;                                                 f32x16 (&acc)[2][2], unsigned char* smem) {
;     ...
;     acc_foreach(tid, acc, [&](int row, int col, float v) {
;       int t = m0 + row;
;       float o = v;
;       if (mode == 1) o = (t >= NPADR) ? v : 0.f;
;       if (mode == 2) o = sigmf(v);
;       sT[row * 136 + col] = f2bf(o);
;     });
	v_mul_f32_e32 v58, 0xbfb8aa3b, v9
	v_exp_f32_e32 v58, v58
	s_nop 0
	v_add_f32_e32 v58, 1.0, v58
	v_div_scale_f32 v59, s[28:29], v58, v58, 1.0
	v_rcp_f32_e32 v60, v59
	v_div_scale_f32 v61, vcc, 1.0, v58, 1.0
	v_fma_f32 v62, -v59, v60, 1.0
	v_fmac_f32_e32 v60, v62, v60
	v_mul_f32_e32 v62, v61, v60
	v_fma_f32 v63, -v59, v62, v61
	v_fmac_f32_e32 v62, v63, v60
	v_fma_f32 v59, -v59, v62, v61
	v_div_fmas_f32 v59, v59, v60, v62
	v_div_fixup_f32 v58, v59, v58, 1.0
	v_bfe_u32 v59, v58, 16, 1
	v_add_u32_e32 v55, 0x110, v55
	v_add3_u32 v59, v58, v59, s81
	v_lshl_add_u32 v58, v106, 1, v55
	ds_write_b16_d16_hi v58, v59
	v_add3_u32 v59, s96, v96, 50
	s_and_b64 vcc, exec, s[6:7]
	v_cmp_lt_i32_e64 s[28:29], s79, v59
	v_mul_f32_e32 v59, 0xbfb8aa3b, v10
	v_exp_f32_e32 v59, v59
	s_nop 0
	v_add_f32_e32 v59, 1.0, v59
	v_div_scale_f32 v60, s[30:31], v59, v59, 1.0
	v_rcp_f32_e32 v61, v60
	v_div_scale_f32 v62, vcc, 1.0, v59, 1.0
	v_fma_f32 v63, -v60, v61, 1.0
	v_fmac_f32_e32 v61, v63, v61
	v_mul_f32_e32 v63, v62, v61
	v_fma_f32 v107, -v60, v63, v62
	v_fmac_f32_e32 v63, v107, v61
	v_fma_f32 v60, -v60, v63, v62
	v_div_fmas_f32 v60, v60, v61, v63
	v_div_fixup_f32 v59, v60, v59, 1.0
	v_bfe_u32 v60, v59, 16, 1
	v_add_u32_e32 v55, 0x110, v55
	v_add3_u32 v60, v59, v60, s81
	v_lshl_add_u32 v59, v106, 1, v55
	ds_write_b16_d16_hi v59, v60
	v_add3_u32 v60, s96, v96, 51
	s_and_b64 vcc, exec, s[6:7]
	v_cmp_lt_i32_e64 s[30:31], s79, v60
	v_mul_f32_e32 v60, 0xbfb8aa3b, v11
	v_exp_f32_e32 v60, v60
	s_nop 0
	v_add_f32_e32 v60, 1.0, v60
	v_div_scale_f32 v61, s[34:35], v60, v60, 1.0
	v_rcp_f32_e32 v62, v61
	v_div_scale_f32 v63, vcc, 1.0, v60, 1.0
	v_fma_f32 v107, -v61, v62, 1.0
	v_fmac_f32_e32 v62, v107, v62
	v_mul_f32_e32 v107, v63, v62
	v_fma_f32 v110, -v61, v107, v63
	v_fmac_f32_e32 v107, v110, v62
	v_fma_f32 v61, -v61, v107, v63
	v_div_fmas_f32 v61, v61, v62, v107
	v_div_fixup_f32 v60, v61, v60, 1.0
	v_bfe_u32 v61, v60, 16, 1
	v_add_u32_e32 v55, 0x110, v55
	v_add3_u32 v61, v60, v61, s81
	v_lshl_add_u32 v60, v106, 1, v55
	ds_write_b16_d16_hi v60, v61
	v_add3_u32 v61, s96, v96, 56
	s_and_b64 vcc, exec, s[6:7]
	v_cmp_lt_i32_e64 s[34:35], s79, v61
	v_mul_f32_e32 v61, 0xbfb8aa3b, v12
	v_exp_f32_e32 v61, v61
	s_nop 0
	v_add_f32_e32 v61, 1.0, v61
	v_div_scale_f32 v62, s[36:37], v61, v61, 1.0
	v_rcp_f32_e32 v63, v62
	v_div_scale_f32 v107, vcc, 1.0, v61, 1.0
	v_fma_f32 v110, -v62, v63, 1.0
	v_fmac_f32_e32 v63, v110, v63
	v_mul_f32_e32 v110, v107, v63
	v_fma_f32 v111, -v62, v110, v107
	v_fmac_f32_e32 v110, v111, v63
	v_fma_f32 v62, -v62, v110, v107
	v_div_fmas_f32 v62, v62, v63, v110
	v_div_fixup_f32 v61, v62, v61, 1.0
	v_bfe_u32 v62, v61, 16, 1
	v_add_u32_e32 v55, 0x550, v55
	v_add3_u32 v62, v61, v62, s81
	v_lshl_add_u32 v61, v106, 1, v55
	ds_write_b16_d16_hi v61, v62
	v_add3_u32 v62, s96, v96, 57
	s_and_b64 vcc, exec, s[6:7]
	v_cmp_lt_i32_e64 s[36:37], s79, v62
	v_mul_f32_e32 v62, 0xbfb8aa3b, v13
	v_exp_f32_e32 v62, v62
	s_nop 0
	v_add_f32_e32 v62, 1.0, v62
	v_div_scale_f32 v63, s[38:39], v62, v62, 1.0
	v_rcp_f32_e32 v107, v63
	v_div_scale_f32 v110, vcc, 1.0, v62, 1.0
	v_fma_f32 v111, -v63, v107, 1.0
	v_fmac_f32_e32 v107, v111, v107
	v_mul_f32_e32 v111, v110, v107
	v_fma_f32 v112, -v63, v111, v110
	v_fmac_f32_e32 v111, v112, v107
	v_fma_f32 v63, -v63, v111, v110
	v_div_fmas_f32 v63, v63, v107, v111
	v_div_fixup_f32 v62, v63, v62, 1.0
	v_bfe_u32 v63, v62, 16, 1
	v_add_u32_e32 v55, 0x110, v55
	v_add3_u32 v63, v62, v63, s81
	v_lshl_add_u32 v62, v106, 1, v55
	ds_write_b16_d16_hi v62, v63
	v_add3_u32 v63, s96, v96, 58
	s_and_b64 vcc, exec, s[6:7]
	v_cmp_lt_i32_e64 s[38:39], s79, v63
	v_mul_f32_e32 v63, 0xbfb8aa3b, v14
	v_exp_f32_e32 v63, v63
	s_nop 0
	v_add_f32_e32 v63, 1.0, v63
	v_div_scale_f32 v107, s[40:41], v63, v63, 1.0
	v_rcp_f32_e32 v110, v107
	v_div_scale_f32 v111, vcc, 1.0, v63, 1.0
	v_fma_f32 v112, -v107, v110, 1.0
	v_fmac_f32_e32 v110, v112, v110
	v_mul_f32_e32 v112, v111, v110
	v_fma_f32 v113, -v107, v112, v111
	v_fmac_f32_e32 v112, v113, v110
	v_fma_f32 v107, -v107, v112, v111
	v_div_fmas_f32 v107, v107, v110, v112
	v_div_fixup_f32 v63, v107, v63, 1.0
	v_bfe_u32 v107, v63, 16, 1
	v_add_u32_e32 v55, 0x110, v55
	v_add3_u32 v63, v63, v107, s81
	v_lshl_add_u32 v55, v106, 1, v55
	ds_write_b16_d16_hi v55, v63
	v_add3_u32 v63, s96, v96, 59
	s_and_b64 vcc, exec, s[6:7]
	v_cmp_lt_i32_e64 s[40:41], s79, v63
	v_mul_f32_e32 v63, 0xbfb8aa3b, v15
	v_exp_f32_e32 v63, v63
	s_nop 0
	v_add_f32_e32 v63, 1.0, v63
	v_div_scale_f32 v96, vcc, v63, v63, 1.0
	v_rcp_f32_e32 v106, v96
	v_div_scale_f32 v107, vcc, 1.0, v63, 1.0
	v_fma_f32 v110, -v96, v106, 1.0
	v_fmac_f32_e32 v106, v110, v106
	v_mul_f32_e32 v110, v107, v106
	v_fma_f32 v111, -v96, v110, v107
	v_fmac_f32_e32 v110, v111, v106
	v_fma_f32 v96, -v96, v110, v107
	v_div_fmas_f32 v96, v96, v106, v110
	v_div_fixup_f32 v63, v96, v63, 1.0
	v_bfe_u32 v96, v63, 16, 1
	v_add3_u32 v63, v63, v96, s81
	ds_write_b16_d16_hi v55, v63 offset:272
	s_and_b64 vcc, exec, s[6:7]
	v_mul_f32_e32 v32, 0xbfb8aa3b, v32
	v_exp_f32_e32 v32, v32
	s_nop 0
	v_add_f32_e32 v32, 1.0, v32
	v_div_scale_f32 v63, s[8:9], v32, v32, 1.0
	v_rcp_f32_e32 v96, v63
	v_div_scale_f32 v106, vcc, 1.0, v32, 1.0
	v_fma_f32 v107, -v63, v96, 1.0
	v_fmac_f32_e32 v96, v107, v96
	v_mul_f32_e32 v107, v106, v96
	v_fma_f32 v110, -v63, v107, v106
	v_fmac_f32_e32 v107, v110, v96
	v_fma_f32 v63, -v63, v107, v106
	v_div_fmas_f32 v63, v63, v96, v107
	v_div_fixup_f32 v32, v63, v32, 1.0
	v_bfe_u32 v63, v32, 16, 1
	v_add3_u32 v32, v32, v63, s81
	s_and_b64 vcc, exec, s[6:7]
	ds_write_b16_d16_hi v48, v32 offset:64
	v_mul_f32_e32 v32, 0xbfb8aa3b, v33
	v_exp_f32_e32 v32, v32
	s_nop 0
	v_add_f32_e32 v32, 1.0, v32
; __device__ __forceinline__ bf16r f2bf(float f) {
;   unsigned u = __float_as_uint(f);
;   u += 0x7fffu + ((u >> 16) & 1u);
;   return (bf16r)(u >> 16);
; }
; __device__ __forceinline__ unsigned pack2(float a, float b) { return (unsigned)f2bf(a) | ((unsigned)f2bf(b) << 16); }
; __device__ __forceinline__ float lo16(unsigned v) { return __uint_as_float(v << 16); }
; __device__ __forceinline__ float hi16(unsigned v) { return __uint_as_float(v & 0xffff0000u); }
; __device__ __forceinline__ float siluf(float x) { return x / (1.f + __expf(-x)); }
; __device__ __forceinline__ float sigmf(float x) { return 1.f / (1.f + __expf(-x)); }
; __device__ __forceinline__ void inproj_epilogue(const Params& p, int layer, int mt, int ntile, int tid,
;                                                 f32x16 (&acc)[2][2], unsigned char* smem) {
;     ...
;     acc_foreach(tid, acc, [&](int row, int col, float v) {
;       int t = m0 + row;
;       float o = v;
;       if (mode == 1) o = (t >= NPADR) ? v : 0.f;
;       if (mode == 2) o = sigmf(v);
;       sT[row * 136 + col] = f2bf(o);
;     });
	v_div_scale_f32 v33, s[8:9], v32, v32, 1.0
	v_rcp_f32_e32 v48, v33
	v_div_scale_f32 v63, vcc, 1.0, v32, 1.0
	v_fma_f32 v96, -v33, v48, 1.0
	v_fmac_f32_e32 v48, v96, v48
	v_mul_f32_e32 v96, v63, v48
	v_fma_f32 v106, -v33, v96, v63
	v_fmac_f32_e32 v96, v106, v48
	v_fma_f32 v33, -v33, v96, v63
	v_div_fmas_f32 v33, v33, v48, v96
	v_div_fixup_f32 v32, v33, v32, 1.0
	v_bfe_u32 v33, v32, 16, 1
	v_add3_u32 v32, v32, v33, s81
	s_and_b64 vcc, exec, s[6:7]
	ds_write_b16_d16_hi v49, v32 offset:64
	v_mul_f32_e32 v32, 0xbfb8aa3b, v34
	v_exp_f32_e32 v32, v32
	s_nop 0
	v_add_f32_e32 v32, 1.0, v32
	v_div_scale_f32 v33, s[8:9], v32, v32, 1.0
	v_rcp_f32_e32 v34, v33
	v_div_scale_f32 v48, vcc, 1.0, v32, 1.0
	v_fma_f32 v49, -v33, v34, 1.0
	v_fmac_f32_e32 v34, v49, v34
	v_mul_f32_e32 v49, v48, v34
	v_fma_f32 v63, -v33, v49, v48
	v_fmac_f32_e32 v49, v63, v34
	v_fma_f32 v33, -v33, v49, v48
	v_div_fmas_f32 v33, v33, v34, v49
	v_div_fixup_f32 v32, v33, v32, 1.0
	v_bfe_u32 v33, v32, 16, 1
	v_add3_u32 v32, v32, v33, s81
	s_and_b64 vcc, exec, s[6:7]
	ds_write_b16_d16_hi v50, v32 offset:64
	v_mul_f32_e32 v32, 0xbfb8aa3b, v35
	v_exp_f32_e32 v32, v32
	s_nop 0
	v_add_f32_e32 v32, 1.0, v32
	v_div_scale_f32 v33, s[8:9], v32, v32, 1.0
	v_rcp_f32_e32 v34, v33
	v_div_scale_f32 v35, vcc, 1.0, v32, 1.0
	v_fma_f32 v48, -v33, v34, 1.0
	v_fmac_f32_e32 v34, v48, v34
	v_mul_f32_e32 v48, v35, v34
	v_fma_f32 v49, -v33, v48, v35
	v_fmac_f32_e32 v48, v49, v34
	v_fma_f32 v33, -v33, v48, v35
	v_div_fmas_f32 v33, v33, v34, v48
	v_div_fixup_f32 v32, v33, v32, 1.0
	v_bfe_u32 v33, v32, 16, 1
	v_add3_u32 v32, v32, v33, s81
	s_and_b64 vcc, exec, s[6:7]
	ds_write_b16_d16_hi v51, v32 offset:64
	v_mul_f32_e32 v32, 0xbfb8aa3b, v36
	v_exp_f32_e32 v32, v32
	s_nop 0
	v_add_f32_e32 v32, 1.0, v32
	v_div_scale_f32 v33, s[8:9], v32, v32, 1.0
	v_rcp_f32_e32 v34, v33
	v_div_scale_f32 v35, vcc, 1.0, v32, 1.0
	v_fma_f32 v36, -v33, v34, 1.0
	v_fmac_f32_e32 v34, v36, v34
	v_mul_f32_e32 v36, v35, v34
	v_fma_f32 v48, -v33, v36, v35
	v_fmac_f32_e32 v36, v48, v34
	v_fma_f32 v33, -v33, v36, v35
	v_div_fmas_f32 v33, v33, v34, v36
	v_div_fixup_f32 v32, v33, v32, 1.0
	v_bfe_u32 v33, v32, 16, 1
	v_add3_u32 v32, v32, v33, s81
	s_and_b64 vcc, exec, s[6:7]
	ds_write_b16_d16_hi v52, v32 offset:64
	v_mul_f32_e32 v32, 0xbfb8aa3b, v37
	v_exp_f32_e32 v32, v32
	s_nop 0
	v_add_f32_e32 v32, 1.0, v32
	v_div_scale_f32 v33, s[8:9], v32, v32, 1.0
	v_rcp_f32_e32 v34, v33
	v_div_scale_f32 v35, vcc, 1.0, v32, 1.0
	v_fma_f32 v36, -v33, v34, 1.0
	v_fmac_f32_e32 v34, v36, v34
	v_mul_f32_e32 v36, v35, v34
	v_fma_f32 v37, -v33, v36, v35
	v_fmac_f32_e32 v36, v37, v34
	v_fma_f32 v33, -v33, v36, v35
	v_div_fmas_f32 v33, v33, v34, v36
	v_div_fixup_f32 v32, v33, v32, 1.0
	v_bfe_u32 v33, v32, 16, 1
	v_add3_u32 v32, v32, v33, s81
	s_and_b64 vcc, exec, s[6:7]
	ds_write_b16_d16_hi v53, v32 offset:64
	v_mul_f32_e32 v32, 0xbfb8aa3b, v38
	v_exp_f32_e32 v32, v32
	s_nop 0
	v_add_f32_e32 v32, 1.0, v32
	v_div_scale_f32 v33, s[8:9], v32, v32, 1.0
	v_rcp_f32_e32 v34, v33
	v_div_scale_f32 v35, vcc, 1.0, v32, 1.0
	v_fma_f32 v36, -v33, v34, 1.0
	v_fmac_f32_e32 v34, v36, v34
	v_mul_f32_e32 v36, v35, v34
	v_fma_f32 v37, -v33, v36, v35
	v_fmac_f32_e32 v36, v37, v34
	v_fma_f32 v33, -v33, v36, v35
	v_div_fmas_f32 v33, v33, v34, v36
	v_div_fixup_f32 v32, v33, v32, 1.0
	v_bfe_u32 v33, v32, 16, 1
	v_add3_u32 v32, v32, v33, s81
	s_and_b64 vcc, exec, s[6:7]
	ds_write_b16_d16_hi v54, v32 offset:64
	v_mul_f32_e32 v32, 0xbfb8aa3b, v39
	v_exp_f32_e32 v32, v32
	s_nop 0
	v_add_f32_e32 v32, 1.0, v32
	v_div_scale_f32 v33, s[8:9], v32, v32, 1.0
	v_rcp_f32_e32 v34, v33
	v_div_scale_f32 v35, vcc, 1.0, v32, 1.0
	v_fma_f32 v36, -v33, v34, 1.0
	v_fmac_f32_e32 v34, v36, v34
	v_mul_f32_e32 v36, v35, v34
	v_fma_f32 v37, -v33, v36, v35
	v_fmac_f32_e32 v36, v37, v34
	v_fma_f32 v33, -v33, v36, v35
	v_div_fmas_f32 v33, v33, v34, v36
	v_div_fixup_f32 v32, v33, v32, 1.0
	v_bfe_u32 v33, v32, 16, 1
	v_add3_u32 v32, v32, v33, s81
	s_and_b64 vcc, exec, s[6:7]
	ds_write_b16_d16_hi v56, v32 offset:64
	v_mul_f32_e32 v32, 0xbfb8aa3b, v40
	v_exp_f32_e32 v32, v32
	s_nop 0
	v_add_f32_e32 v32, 1.0, v32
	v_div_scale_f32 v33, s[8:9], v32, v32, 1.0
	v_rcp_f32_e32 v34, v33
	v_div_scale_f32 v35, vcc, 1.0, v32, 1.0
	v_fma_f32 v36, -v33, v34, 1.0
	v_fmac_f32_e32 v34, v36, v34
	v_mul_f32_e32 v36, v35, v34
; __device__ __forceinline__ bf16r f2bf(float f) {
;   unsigned u = __float_as_uint(f);
;   u += 0x7fffu + ((u >> 16) & 1u);
;   return (bf16r)(u >> 16);
; }
; __device__ __forceinline__ unsigned pack2(float a, float b) { return (unsigned)f2bf(a) | ((unsigned)f2bf(b) << 16); }
; __device__ __forceinline__ float lo16(unsigned v) { return __uint_as_float(v << 16); }
; __device__ __forceinline__ float hi16(unsigned v) { return __uint_as_float(v & 0xffff0000u); }
; __device__ __forceinline__ float siluf(float x) { return x / (1.f + __expf(-x)); }
; __device__ __forceinline__ float sigmf(float x) { return 1.f / (1.f + __expf(-x)); }
; __device__ __forceinline__ void inproj_epilogue(const Params& p, int layer, int mt, int ntile, int tid,
;                                                 f32x16 (&acc)[2][2], unsigned char* smem) {
;     ...
;     acc_foreach(tid, acc, [&](int row, int col, float v) {
;       int t = m0 + row;
;       float o = v;
;       if (mode == 1) o = (t >= NPADR) ? v : 0.f;
;       if (mode == 2) o = sigmf(v);
;       sT[row * 136 + col] = f2bf(o);
;     });
	v_fma_f32 v37, -v33, v36, v35
	v_fmac_f32_e32 v36, v37, v34
	v_fma_f32 v33, -v33, v36, v35
	v_div_fmas_f32 v33, v33, v34, v36
	v_div_fixup_f32 v32, v33, v32, 1.0
	v_bfe_u32 v33, v32, 16, 1
	v_add3_u32 v32, v32, v33, s81
	s_and_b64 vcc, exec, s[6:7]
	ds_write_b16_d16_hi v57, v32 offset:64
	v_mul_f32_e32 v32, 0xbfb8aa3b, v41
	v_exp_f32_e32 v32, v32
	s_nop 0
	v_add_f32_e32 v32, 1.0, v32
	v_div_scale_f32 v33, s[8:9], v32, v32, 1.0
	v_rcp_f32_e32 v34, v33
	v_div_scale_f32 v35, vcc, 1.0, v32, 1.0
	v_fma_f32 v36, -v33, v34, 1.0
	v_fmac_f32_e32 v34, v36, v34
	v_mul_f32_e32 v36, v35, v34
	v_fma_f32 v37, -v33, v36, v35
	v_fmac_f32_e32 v36, v37, v34
	v_fma_f32 v33, -v33, v36, v35
	v_div_fmas_f32 v33, v33, v34, v36
	v_div_fixup_f32 v32, v33, v32, 1.0
	v_bfe_u32 v33, v32, 16, 1
	v_add3_u32 v32, v32, v33, s81
	s_and_b64 vcc, exec, s[6:7]
	ds_write_b16_d16_hi v58, v32 offset:64
	v_mul_f32_e32 v32, 0xbfb8aa3b, v42
	v_exp_f32_e32 v32, v32
	s_nop 0
	v_add_f32_e32 v32, 1.0, v32
	v_div_scale_f32 v33, s[8:9], v32, v32, 1.0
	v_rcp_f32_e32 v34, v33
	v_div_scale_f32 v35, vcc, 1.0, v32, 1.0
	v_fma_f32 v36, -v33, v34, 1.0
	v_fmac_f32_e32 v34, v36, v34
	v_mul_f32_e32 v36, v35, v34
	v_fma_f32 v37, -v33, v36, v35
	v_fmac_f32_e32 v36, v37, v34
	v_fma_f32 v33, -v33, v36, v35
	v_div_fmas_f32 v33, v33, v34, v36
	v_div_fixup_f32 v32, v33, v32, 1.0
	v_bfe_u32 v33, v32, 16, 1
	v_add3_u32 v32, v32, v33, s81
	s_and_b64 vcc, exec, s[6:7]
	ds_write_b16_d16_hi v59, v32 offset:64
	v_mul_f32_e32 v32, 0xbfb8aa3b, v43
	v_exp_f32_e32 v32, v32
	s_nop 0
	v_add_f32_e32 v32, 1.0, v32
	v_div_scale_f32 v33, s[8:9], v32, v32, 1.0
	v_rcp_f32_e32 v34, v33
	v_div_scale_f32 v35, vcc, 1.0, v32, 1.0
	v_fma_f32 v36, -v33, v34, 1.0
	v_fmac_f32_e32 v34, v36, v34
	v_mul_f32_e32 v36, v35, v34
	v_fma_f32 v37, -v33, v36, v35
	v_fmac_f32_e32 v36, v37, v34
	v_fma_f32 v33, -v33, v36, v35
	v_div_fmas_f32 v33, v33, v34, v36
	v_div_fixup_f32 v32, v33, v32, 1.0
	v_bfe_u32 v33, v32, 16, 1
	v_add3_u32 v32, v32, v33, s81
	s_and_b64 vcc, exec, s[6:7]
	ds_write_b16_d16_hi v60, v32 offset:64
	v_mul_f32_e32 v32, 0xbfb8aa3b, v44
	v_exp_f32_e32 v32, v32
	s_nop 0
	v_add_f32_e32 v32, 1.0, v32
	v_div_scale_f32 v33, s[8:9], v32, v32, 1.0
	v_rcp_f32_e32 v34, v33
	v_div_scale_f32 v35, vcc, 1.0, v32, 1.0
	v_fma_f32 v36, -v33, v34, 1.0
	v_fmac_f32_e32 v34, v36, v34
	v_mul_f32_e32 v36, v35, v34
	v_fma_f32 v37, -v33, v36, v35
	v_fmac_f32_e32 v36, v37, v34
	v_fma_f32 v33, -v33, v36, v35
	v_div_fmas_f32 v33, v33, v34, v36
	v_div_fixup_f32 v32, v33, v32, 1.0
	v_bfe_u32 v33, v32, 16, 1
	v_add3_u32 v32, v32, v33, s81
	s_and_b64 vcc, exec, s[6:7]
	ds_write_b16_d16_hi v61, v32 offset:64
	v_mul_f32_e32 v32, 0xbfb8aa3b, v45
	v_exp_f32_e32 v32, v32
	s_nop 0
	v_add_f32_e32 v32, 1.0, v32
	v_div_scale_f32 v33, s[8:9], v32, v32, 1.0
	v_rcp_f32_e32 v34, v33
	v_div_scale_f32 v35, vcc, 1.0, v32, 1.0
	v_fma_f32 v36, -v33, v34, 1.0
	v_fmac_f32_e32 v34, v36, v34
	v_mul_f32_e32 v36, v35, v34
	v_fma_f32 v37, -v33, v36, v35
	v_fmac_f32_e32 v36, v37, v34
	v_fma_f32 v33, -v33, v36, v35
	v_div_fmas_f32 v33, v33, v34, v36
	v_div_fixup_f32 v32, v33, v32, 1.0
	v_bfe_u32 v33, v32, 16, 1
	v_add3_u32 v32, v32, v33, s81
	s_and_b64 vcc, exec, s[6:7]
	ds_write_b16_d16_hi v62, v32 offset:64
	v_mul_f32_e32 v32, 0xbfb8aa3b, v46
	v_exp_f32_e32 v32, v32
	s_nop 0
	v_add_f32_e32 v32, 1.0, v32
	v_div_scale_f32 v33, s[8:9], v32, v32, 1.0
	v_rcp_f32_e32 v34, v33
	v_div_scale_f32 v35, vcc, 1.0, v32, 1.0
	v_fma_f32 v36, -v33, v34, 1.0
	v_fmac_f32_e32 v34, v36, v34
	v_mul_f32_e32 v36, v35, v34
	v_fma_f32 v37, -v33, v36, v35
	v_fmac_f32_e32 v36, v37, v34
	v_fma_f32 v33, -v33, v36, v35
	v_div_fmas_f32 v33, v33, v34, v36
	v_div_fixup_f32 v32, v33, v32, 1.0
	v_bfe_u32 v33, v32, 16, 1
	v_add3_u32 v32, v32, v33, s81
	s_and_b64 vcc, exec, s[6:7]
	ds_write_b16_d16_hi v55, v32 offset:64
	v_mul_f32_e32 v32, 0xbfb8aa3b, v47
	v_exp_f32_e32 v32, v32
	s_nop 0
	v_add_f32_e32 v32, 1.0, v32
	v_div_scale_f32 v33, s[4:5], v32, v32, 1.0
	v_rcp_f32_e32 v34, v33
	v_div_scale_f32 v35, vcc, 1.0, v32, 1.0
	v_fma_f32 v36, -v33, v34, 1.0
	v_fmac_f32_e32 v34, v36, v34
	v_mul_f32_e32 v36, v35, v34
	v_fma_f32 v37, -v33, v36, v35
	v_fmac_f32_e32 v36, v37, v34
	v_fma_f32 v33, -v33, v36, v35
	v_div_fmas_f32 v33, v33, v34, v36
	v_div_fixup_f32 v32, v33, v32, 1.0
	s_branch .LBB0_2906

; __device__ __forceinline__ float sigmf(float x) { return 1.f / (1.f + __expf(-x)); }
; __device__ __forceinline__ bf16r f2bf(float f) {
;   unsigned u = __float_as_uint(f);
;   u += 0x7fffu + ((u >> 16) & 1u);
;   return (bf16r)(u >> 16);
; }
; __device__ __forceinline__ void inproj_epilogue(const Params& p, int layer, int mt, int ntile, int tid,
;                                                 f32x16 (&acc)[2][2], unsigned char* smem) {
;     ...
;     acc_foreach(tid, acc, [&](int row, int col, float v) {
;       int t = m0 + row;
;       float o = v;
;       if (mode == 1) o = (t >= NPADR) ? v : 0.f;
;       if (mode == 2) o = sigmf(v);
;       sT[row * 136 + col] = f2bf(o);
;     });
.LBB0_3036:
	v_bfe_u32 v110, v107, 16, 1
	v_and_b32_e32 v106, 0x5f, v106
	v_add3_u32 v111, v107, v110, s79
	v_mul_lo_u32 v110, v96, s80
	v_lshl_add_u32 v107, v106, 1, v110
	ds_write_b16_d16_hi v107, v111
	v_add3_u32 v111, s94, v96, 1
	v_cndmask_b32_e64 v112, 0, 1, s[10:11]
	v_cmp_ne_u32_e64 s[6:7], 1, v112
	v_cmp_lt_i32_e64 s[10:11], s77, v111
	s_nop 1

; __device__ __forceinline__ float sigmf(float x) { return 1.f / (1.f + __expf(-x)); }
; __device__ __forceinline__ bf16r f2bf(float f) {
;   unsigned u = __float_as_uint(f);
;   u += 0x7fffu + ((u >> 16) & 1u);
;   return (bf16r)(u >> 16);
; }
; __device__ __forceinline__ void inproj_epilogue(const Params& p, int layer, int mt, int ntile, int tid,
;                                                 f32x16 (&acc)[2][2], unsigned char* smem) {
;     ...
;     acc_foreach(tid, acc, [&](int row, int col, float v) {
;       int t = m0 + row;
;       float o = v;
;       if (mode == 1) o = (t >= NPADR) ? v : 0.f;
;       if (mode == 2) o = sigmf(v);
;       sT[row * 136 + col] = f2bf(o);
;     });
.LBB0_3039:
	v_bfe_u32 v112, v111, 16, 1
	v_add3_u32 v112, v111, v112, s79
	v_add_u32_e32 v111, 0x110, v110
	v_lshl_add_u32 v110, v106, 1, v111
	ds_write_b16_d16_hi v110, v112
	v_add3_u32 v112, s94, v96, 2
	v_cmp_lt_i32_e64 s[12:13], s77, v112
	s_nop 1

; __device__ __forceinline__ float sigmf(float x) { return 1.f / (1.f + __expf(-x)); }
; __device__ __forceinline__ bf16r f2bf(float f) {
;   unsigned u = __float_as_uint(f);
;   u += 0x7fffu + ((u >> 16) & 1u);
;   return (bf16r)(u >> 16);
; }
; __device__ __forceinline__ void inproj_epilogue(const Params& p, int layer, int mt, int ntile, int tid,
;                                                 f32x16 (&acc)[2][2], unsigned char* smem) {
;     ...
;     acc_foreach(tid, acc, [&](int row, int col, float v) {
;       int t = m0 + row;
;       float o = v;
;       if (mode == 1) o = (t >= NPADR) ? v : 0.f;
;       if (mode == 2) o = sigmf(v);
;       sT[row * 136 + col] = f2bf(o);
;     });
.LBB0_3042:
	v_bfe_u32 v113, v112, 16, 1
	v_add3_u32 v113, v112, v113, s79
	v_add_u32_e32 v112, 0x110, v111
	v_lshl_add_u32 v111, v106, 1, v112
	ds_write_b16_d16_hi v111, v113
	v_add3_u32 v113, s94, v96, 3
	v_cmp_lt_i32_e64 s[14:15], s77, v113
	s_nop 1

; __device__ __forceinline__ float sigmf(float x) { return 1.f / (1.f + __expf(-x)); }
; __device__ __forceinline__ bf16r f2bf(float f) {
;   unsigned u = __float_as_uint(f);
;   u += 0x7fffu + ((u >> 16) & 1u);
;   return (bf16r)(u >> 16);
; }
; __device__ __forceinline__ void inproj_epilogue(const Params& p, int layer, int mt, int ntile, int tid,
;                                                 f32x16 (&acc)[2][2], unsigned char* smem) {
;     ...
;     acc_foreach(tid, acc, [&](int row, int col, float v) {
;       int t = m0 + row;
;       float o = v;
;       if (mode == 1) o = (t >= NPADR) ? v : 0.f;
;       if (mode == 2) o = sigmf(v);
;       sT[row * 136 + col] = f2bf(o);
;     });
.LBB0_3045:
	v_bfe_u32 v114, v113, 16, 1
	v_add3_u32 v114, v113, v114, s79
	v_add_u32_e32 v113, 0x110, v112
	v_lshl_add_u32 v112, v106, 1, v113
	ds_write_b16_d16_hi v112, v114
	v_add3_u32 v114, s94, v96, 8
	v_cmp_lt_i32_e64 s[16:17], s77, v114
	s_nop 1

; __device__ __forceinline__ float sigmf(float x) { return 1.f / (1.f + __expf(-x)); }
; __device__ __forceinline__ bf16r f2bf(float f) {
;   unsigned u = __float_as_uint(f);
;   u += 0x7fffu + ((u >> 16) & 1u);
;   return (bf16r)(u >> 16);
; }
; __device__ __forceinline__ void inproj_epilogue(const Params& p, int layer, int mt, int ntile, int tid,
;                                                 f32x16 (&acc)[2][2], unsigned char* smem) {
;     ...
;     acc_foreach(tid, acc, [&](int row, int col, float v) {
;       int t = m0 + row;
;       float o = v;
;       if (mode == 1) o = (t >= NPADR) ? v : 0.f;
;       if (mode == 2) o = sigmf(v);
;       sT[row * 136 + col] = f2bf(o);
;     });
.LBB0_3048:
	v_bfe_u32 v115, v114, 16, 1
	v_add3_u32 v115, v114, v115, s79
	v_add_u32_e32 v114, 0x550, v113
	v_lshl_add_u32 v113, v106, 1, v114
	ds_write_b16_d16_hi v113, v115
	v_add3_u32 v115, s94, v96, 9
	v_cmp_lt_i32_e64 s[18:19], s77, v115
	s_nop 1

; __device__ __forceinline__ float sigmf(float x) { return 1.f / (1.f + __expf(-x)); }
; __device__ __forceinline__ bf16r f2bf(float f) {
;   unsigned u = __float_as_uint(f);
;   u += 0x7fffu + ((u >> 16) & 1u);
;   return (bf16r)(u >> 16);
; }
; __device__ __forceinline__ void inproj_epilogue(const Params& p, int layer, int mt, int ntile, int tid,
;                                                 f32x16 (&acc)[2][2], unsigned char* smem) {
;     ...
;     acc_foreach(tid, acc, [&](int row, int col, float v) {
;       int t = m0 + row;
;       float o = v;
;       if (mode == 1) o = (t >= NPADR) ? v : 0.f;
;       if (mode == 2) o = sigmf(v);
;       sT[row * 136 + col] = f2bf(o);
;     });
.LBB0_3051:
	v_bfe_u32 v116, v115, 16, 1
	v_add3_u32 v116, v115, v116, s79
	v_add_u32_e32 v115, 0x110, v114
	v_lshl_add_u32 v114, v106, 1, v115
	ds_write_b16_d16_hi v114, v116
	v_add3_u32 v116, s94, v96, 10
	v_cmp_lt_i32_e64 s[20:21], s77, v116
	s_nop 1

; __device__ __forceinline__ float sigmf(float x) { return 1.f / (1.f + __expf(-x)); }
; __device__ __forceinline__ bf16r f2bf(float f) {
;   unsigned u = __float_as_uint(f);
;   u += 0x7fffu + ((u >> 16) & 1u);
;   return (bf16r)(u >> 16);
; }
; __device__ __forceinline__ void inproj_epilogue(const Params& p, int layer, int mt, int ntile, int tid,
;                                                 f32x16 (&acc)[2][2], unsigned char* smem) {
;     ...
;     acc_foreach(tid, acc, [&](int row, int col, float v) {
;       int t = m0 + row;
;       float o = v;
;       if (mode == 1) o = (t >= NPADR) ? v : 0.f;
;       if (mode == 2) o = sigmf(v);
;       sT[row * 136 + col] = f2bf(o);
;     });
.LBB0_3054:
	v_bfe_u32 v117, v116, 16, 1
	v_add3_u32 v117, v116, v117, s79
	v_add_u32_e32 v116, 0x110, v115
	v_lshl_add_u32 v115, v106, 1, v116
	ds_write_b16_d16_hi v115, v117
	v_add3_u32 v117, s94, v96, 11
	v_cmp_lt_i32_e64 s[22:23], s77, v117
	s_nop 1

; __device__ __forceinline__ float sigmf(float x) { return 1.f / (1.f + __expf(-x)); }
; __device__ __forceinline__ bf16r f2bf(float f) {
;   unsigned u = __float_as_uint(f);
;   u += 0x7fffu + ((u >> 16) & 1u);
;   return (bf16r)(u >> 16);
; }
; __device__ __forceinline__ void inproj_epilogue(const Params& p, int layer, int mt, int ntile, int tid,
;                                                 f32x16 (&acc)[2][2], unsigned char* smem) {
;     ...
;     acc_foreach(tid, acc, [&](int row, int col, float v) {
;       int t = m0 + row;
;       float o = v;
;       if (mode == 1) o = (t >= NPADR) ? v : 0.f;
;       if (mode == 2) o = sigmf(v);
;       sT[row * 136 + col] = f2bf(o);
;     });
.LBB0_3057:
	v_bfe_u32 v118, v117, 16, 1
	v_add_u32_e32 v116, 0x110, v116
	v_add3_u32 v118, v117, v118, s79
	v_lshl_add_u32 v117, v106, 1, v116
	ds_write_b16_d16_hi v117, v118
	v_add3_u32 v118, s94, v96, 16
	v_cmp_lt_i32_e64 s[24:25], s77, v118
	s_nop 1

; __device__ __forceinline__ float sigmf(float x) { return 1.f / (1.f + __expf(-x)); }
; __device__ __forceinline__ bf16r f2bf(float f) {
;   unsigned u = __float_as_uint(f);
;   u += 0x7fffu + ((u >> 16) & 1u);
;   return (bf16r)(u >> 16);
; }
; __device__ __forceinline__ void inproj_epilogue(const Params& p, int layer, int mt, int ntile, int tid,
;                                                 f32x16 (&acc)[2][2], unsigned char* smem) {
;     ...
;     acc_foreach(tid, acc, [&](int row, int col, float v) {
;       int t = m0 + row;
;       float o = v;
;       if (mode == 1) o = (t >= NPADR) ? v : 0.f;
;       if (mode == 2) o = sigmf(v);
;       sT[row * 136 + col] = f2bf(o);
;     });
.LBB0_3060:
	v_bfe_u32 v119, v118, 16, 1
	v_add_u32_e32 v116, 0x550, v116
	v_add3_u32 v119, v118, v119, s79
	v_lshl_add_u32 v118, v106, 1, v116
	ds_write_b16_d16_hi v118, v119
	v_add3_u32 v119, s94, v96, 17
	v_cmp_lt_i32_e64 s[26:27], s77, v119
	s_nop 1

; __device__ __forceinline__ float sigmf(float x) { return 1.f / (1.f + __expf(-x)); }
; __device__ __forceinline__ bf16r f2bf(float f) {
;   unsigned u = __float_as_uint(f);
;   u += 0x7fffu + ((u >> 16) & 1u);
;   return (bf16r)(u >> 16);
; }
; __device__ __forceinline__ void inproj_epilogue(const Params& p, int layer, int mt, int ntile, int tid,
;                                                 f32x16 (&acc)[2][2], unsigned char* smem) {
;     ...
;     acc_foreach(tid, acc, [&](int row, int col, float v) {
;       int t = m0 + row;
;       float o = v;
;       if (mode == 1) o = (t >= NPADR) ? v : 0.f;
;       if (mode == 2) o = sigmf(v);
;       sT[row * 136 + col] = f2bf(o);
;     });
.LBB0_3063:
	v_bfe_u32 v120, v119, 16, 1
	v_add_u32_e32 v116, 0x110, v116
	v_add3_u32 v120, v119, v120, s79
	v_lshl_add_u32 v119, v106, 1, v116
	ds_write_b16_d16_hi v119, v120
	v_add3_u32 v120, s94, v96, 18
	v_cmp_lt_i32_e64 s[28:29], s77, v120
	s_nop 1

; __device__ __forceinline__ float sigmf(float x) { return 1.f / (1.f + __expf(-x)); }
; __device__ __forceinline__ bf16r f2bf(float f) {
;   unsigned u = __float_as_uint(f);
;   u += 0x7fffu + ((u >> 16) & 1u);
;   return (bf16r)(u >> 16);
; }
; __device__ __forceinline__ void inproj_epilogue(const Params& p, int layer, int mt, int ntile, int tid,
;                                                 f32x16 (&acc)[2][2], unsigned char* smem) {
;     ...
;     acc_foreach(tid, acc, [&](int row, int col, float v) {
;       int t = m0 + row;
;       float o = v;
;       if (mode == 1) o = (t >= NPADR) ? v : 0.f;
;       if (mode == 2) o = sigmf(v);
;       sT[row * 136 + col] = f2bf(o);
;     });
.LBB0_3066:
	v_bfe_u32 v121, v120, 16, 1
	v_add_u32_e32 v116, 0x110, v116
	v_add3_u32 v121, v120, v121, s79
	v_lshl_add_u32 v120, v106, 1, v116
	ds_write_b16_d16_hi v120, v121
	v_add3_u32 v121, s94, v96, 19
	v_cmp_lt_i32_e64 s[30:31], s77, v121
	s_nop 1

; __device__ __forceinline__ float sigmf(float x) { return 1.f / (1.f + __expf(-x)); }
; __device__ __forceinline__ bf16r f2bf(float f) {
;   unsigned u = __float_as_uint(f);
;   u += 0x7fffu + ((u >> 16) & 1u);
;   return (bf16r)(u >> 16);
; }
; __device__ __forceinline__ void inproj_epilogue(const Params& p, int layer, int mt, int ntile, int tid,
;                                                 f32x16 (&acc)[2][2], unsigned char* smem) {
;     ...
;     acc_foreach(tid, acc, [&](int row, int col, float v) {
;       int t = m0 + row;
;       float o = v;
;       if (mode == 1) o = (t >= NPADR) ? v : 0.f;
;       if (mode == 2) o = sigmf(v);
;       sT[row * 136 + col] = f2bf(o);
;     });
.LBB0_3069:
	v_bfe_u32 v122, v121, 16, 1
	v_add_u32_e32 v116, 0x110, v116
	v_add3_u32 v122, v121, v122, s79
	v_lshl_add_u32 v121, v106, 1, v116
	ds_write_b16_d16_hi v121, v122
	v_add3_u32 v122, s94, v96, 24
	v_cmp_lt_i32_e64 s[34:35], s77, v122
	s_nop 1

; __device__ __forceinline__ float sigmf(float x) { return 1.f / (1.f + __expf(-x)); }
; __device__ __forceinline__ bf16r f2bf(float f) {
;   unsigned u = __float_as_uint(f);
;   u += 0x7fffu + ((u >> 16) & 1u);
;   return (bf16r)(u >> 16);
; }
; __device__ __forceinline__ void inproj_epilogue(const Params& p, int layer, int mt, int ntile, int tid,
;                                                 f32x16 (&acc)[2][2], unsigned char* smem) {
;     ...
;     acc_foreach(tid, acc, [&](int row, int col, float v) {
;       int t = m0 + row;
;       float o = v;
;       if (mode == 1) o = (t >= NPADR) ? v : 0.f;
;       if (mode == 2) o = sigmf(v);
;       sT[row * 136 + col] = f2bf(o);
;     });
.LBB0_3072:
	v_bfe_u32 v123, v122, 16, 1
	v_add_u32_e32 v116, 0x550, v116
	v_add3_u32 v123, v122, v123, s79
	v_lshl_add_u32 v122, v106, 1, v116
	ds_write_b16_d16_hi v122, v123
	v_add3_u32 v123, s94, v96, 25
	v_cmp_lt_i32_e64 s[36:37], s77, v123
	s_nop 1

; __device__ __forceinline__ float sigmf(float x) { return 1.f / (1.f + __expf(-x)); }
; __device__ __forceinline__ bf16r f2bf(float f) {
;   unsigned u = __float_as_uint(f);
;   u += 0x7fffu + ((u >> 16) & 1u);
;   return (bf16r)(u >> 16);
; }
; __device__ __forceinline__ void inproj_epilogue(const Params& p, int layer, int mt, int ntile, int tid,
;                                                 f32x16 (&acc)[2][2], unsigned char* smem) {
;     ...
;     acc_foreach(tid, acc, [&](int row, int col, float v) {
;       int t = m0 + row;
;       float o = v;
;       if (mode == 1) o = (t >= NPADR) ? v : 0.f;
;       if (mode == 2) o = sigmf(v);
;       sT[row * 136 + col] = f2bf(o);
;     });
.LBB0_3075:
	v_bfe_u32 v124, v123, 16, 1
	v_add_u32_e32 v116, 0x110, v116
	v_add3_u32 v124, v123, v124, s79
	v_lshl_add_u32 v123, v106, 1, v116
	ds_write_b16_d16_hi v123, v124
	v_add3_u32 v124, s94, v96, 26
	v_cmp_lt_i32_e64 s[38:39], s77, v124
	s_nop 1

; __device__ __forceinline__ float sigmf(float x) { return 1.f / (1.f + __expf(-x)); }
; __device__ __forceinline__ bf16r f2bf(float f) {
;   unsigned u = __float_as_uint(f);
;   u += 0x7fffu + ((u >> 16) & 1u);
;   return (bf16r)(u >> 16);
; }
; __device__ __forceinline__ void inproj_epilogue(const Params& p, int layer, int mt, int ntile, int tid,
;                                                 f32x16 (&acc)[2][2], unsigned char* smem) {
;     ...
;     acc_foreach(tid, acc, [&](int row, int col, float v) {
;       int t = m0 + row;
;       float o = v;
;       if (mode == 1) o = (t >= NPADR) ? v : 0.f;
;       if (mode == 2) o = sigmf(v);
;       sT[row * 136 + col] = f2bf(o);
;     });
.LBB0_3078:
	v_bfe_u32 v125, v124, 16, 1
	v_add_u32_e32 v116, 0x110, v116
	v_add3_u32 v124, v124, v125, s79
	v_lshl_add_u32 v116, v106, 1, v116
	ds_write_b16_d16_hi v116, v124
	v_add3_u32 v124, s94, v96, 27
	v_cmp_lt_i32_e64 s[40:41], s77, v124
	s_nop 1

; __device__ __forceinline__ float sigmf(float x) { return 1.f / (1.f + __expf(-x)); }
; __device__ __forceinline__ bf16r f2bf(float f) {
;   unsigned u = __float_as_uint(f);
;   u += 0x7fffu + ((u >> 16) & 1u);
;   return (bf16r)(u >> 16);
; }
; __device__ __forceinline__ void inproj_epilogue(const Params& p, int layer, int mt, int ntile, int tid,
;                                                 f32x16 (&acc)[2][2], unsigned char* smem) {
;     ...
;     acc_foreach(tid, acc, [&](int row, int col, float v) {
;       int t = m0 + row;
;       float o = v;
;       if (mode == 1) o = (t >= NPADR) ? v : 0.f;
;       if (mode == 2) o = sigmf(v);
;       sT[row * 136 + col] = f2bf(o);
;     });
.LBB0_3129:
	v_bfe_u32 v50, v48, 16, 1
	v_add_u32_e32 v49, 0x110, v116
	v_add3_u32 v48, v48, v50, s79
	ds_write_b16_d16_hi v49, v48 offset:64
	v_or_b32_e32 v48, 32, v96
	v_add_u32_e32 v49, s94, v48
	v_cmp_lt_i32_e64 s[8:9], s77, v49
	s_nop 1

; __device__ __forceinline__ float sigmf(float x) { return 1.f / (1.f + __expf(-x)); }
; __device__ __forceinline__ bf16r f2bf(float f) {
;   unsigned u = __float_as_uint(f);
;   u += 0x7fffu + ((u >> 16) & 1u);
;   return (bf16r)(u >> 16);
; }
; __device__ __forceinline__ void inproj_epilogue(const Params& p, int layer, int mt, int ntile, int tid,
;                                                 f32x16 (&acc)[2][2], unsigned char* smem) {
;     ...
;     acc_foreach(tid, acc, [&](int row, int col, float v) {
;       int t = m0 + row;
;       float o = v;
;       if (mode == 1) o = (t >= NPADR) ? v : 0.f;
;       if (mode == 2) o = sigmf(v);
;       sT[row * 136 + col] = f2bf(o);
;     });
.LBB0_3132:
	v_bfe_u32 v50, v49, 16, 1
	v_add3_u32 v50, v49, v50, s79
	v_mul_lo_u32 v49, v48, s80
	v_lshl_add_u32 v48, v106, 1, v49
	ds_write_b16_d16_hi v48, v50
	v_add3_u32 v50, s94, v96, 33
	v_cmp_lt_i32_e64 s[10:11], s77, v50
	s_nop 1

; __device__ __forceinline__ float sigmf(float x) { return 1.f / (1.f + __expf(-x)); }
; __device__ __forceinline__ bf16r f2bf(float f) {
;   unsigned u = __float_as_uint(f);
;   u += 0x7fffu + ((u >> 16) & 1u);
;   return (bf16r)(u >> 16);
; }
; __device__ __forceinline__ void inproj_epilogue(const Params& p, int layer, int mt, int ntile, int tid,
;                                                 f32x16 (&acc)[2][2], unsigned char* smem) {
;     ...
;     acc_foreach(tid, acc, [&](int row, int col, float v) {
;       int t = m0 + row;
;       float o = v;
;       if (mode == 1) o = (t >= NPADR) ? v : 0.f;
;       if (mode == 2) o = sigmf(v);
;       sT[row * 136 + col] = f2bf(o);
;     });
.LBB0_3135:
	v_bfe_u32 v51, v50, 16, 1
	v_add3_u32 v51, v50, v51, s79
	v_add_u32_e32 v50, 0x110, v49
	v_lshl_add_u32 v49, v106, 1, v50
	ds_write_b16_d16_hi v49, v51
	v_add3_u32 v51, s94, v96, 34
	v_cmp_lt_i32_e64 s[12:13], s77, v51
	s_nop 1

; __device__ __forceinline__ float sigmf(float x) { return 1.f / (1.f + __expf(-x)); }
; __device__ __forceinline__ bf16r f2bf(float f) {
;   unsigned u = __float_as_uint(f);
;   u += 0x7fffu + ((u >> 16) & 1u);
;   return (bf16r)(u >> 16);
; }
; __device__ __forceinline__ void inproj_epilogue(const Params& p, int layer, int mt, int ntile, int tid,
;                                                 f32x16 (&acc)[2][2], unsigned char* smem) {
;     ...
;     acc_foreach(tid, acc, [&](int row, int col, float v) {
;       int t = m0 + row;
;       float o = v;
;       if (mode == 1) o = (t >= NPADR) ? v : 0.f;
;       if (mode == 2) o = sigmf(v);
;       sT[row * 136 + col] = f2bf(o);
;     });
.LBB0_3138:
	v_bfe_u32 v52, v51, 16, 1
	v_add3_u32 v52, v51, v52, s79
	v_add_u32_e32 v51, 0x110, v50
	v_lshl_add_u32 v50, v106, 1, v51
	ds_write_b16_d16_hi v50, v52
	v_add3_u32 v52, s94, v96, 35
	v_cmp_lt_i32_e64 s[14:15], s77, v52
	s_nop 1

; __device__ __forceinline__ float sigmf(float x) { return 1.f / (1.f + __expf(-x)); }
; __device__ __forceinline__ bf16r f2bf(float f) {
;   unsigned u = __float_as_uint(f);
;   u += 0x7fffu + ((u >> 16) & 1u);
;   return (bf16r)(u >> 16);
; }
; __device__ __forceinline__ void inproj_epilogue(const Params& p, int layer, int mt, int ntile, int tid,
;                                                 f32x16 (&acc)[2][2], unsigned char* smem) {
;     ...
;     acc_foreach(tid, acc, [&](int row, int col, float v) {
;       int t = m0 + row;
;       float o = v;
;       if (mode == 1) o = (t >= NPADR) ? v : 0.f;
;       if (mode == 2) o = sigmf(v);
;       sT[row * 136 + col] = f2bf(o);
;     });
.LBB0_3141:
	v_bfe_u32 v53, v52, 16, 1
	v_add3_u32 v53, v52, v53, s79
	v_add_u32_e32 v52, 0x110, v51
	v_lshl_add_u32 v51, v106, 1, v52
	ds_write_b16_d16_hi v51, v53
	v_add3_u32 v53, s94, v96, 40
	v_cmp_lt_i32_e64 s[16:17], s77, v53
	s_nop 1

; __device__ __forceinline__ float sigmf(float x) { return 1.f / (1.f + __expf(-x)); }
; __device__ __forceinline__ bf16r f2bf(float f) {
;   unsigned u = __float_as_uint(f);
;   u += 0x7fffu + ((u >> 16) & 1u);
;   return (bf16r)(u >> 16);
; }
; __device__ __forceinline__ void inproj_epilogue(const Params& p, int layer, int mt, int ntile, int tid,
;                                                 f32x16 (&acc)[2][2], unsigned char* smem) {
;     ...
;     acc_foreach(tid, acc, [&](int row, int col, float v) {
;       int t = m0 + row;
;       float o = v;
;       if (mode == 1) o = (t >= NPADR) ? v : 0.f;
;       if (mode == 2) o = sigmf(v);
;       sT[row * 136 + col] = f2bf(o);
;     });
.LBB0_3144:
	v_bfe_u32 v54, v53, 16, 1
	v_add3_u32 v54, v53, v54, s79
	v_add_u32_e32 v53, 0x550, v52
	v_lshl_add_u32 v52, v106, 1, v53
	ds_write_b16_d16_hi v52, v54
	v_add3_u32 v54, s94, v96, 41
	v_cmp_lt_i32_e64 s[18:19], s77, v54
	s_nop 1

; __device__ __forceinline__ float sigmf(float x) { return 1.f / (1.f + __expf(-x)); }
; __device__ __forceinline__ bf16r f2bf(float f) {
;   unsigned u = __float_as_uint(f);
;   u += 0x7fffu + ((u >> 16) & 1u);
;   return (bf16r)(u >> 16);
; }
; __device__ __forceinline__ void inproj_epilogue(const Params& p, int layer, int mt, int ntile, int tid,
;                                                 f32x16 (&acc)[2][2], unsigned char* smem) {
;     ...
;     acc_foreach(tid, acc, [&](int row, int col, float v) {
;       int t = m0 + row;
;       float o = v;
;       if (mode == 1) o = (t >= NPADR) ? v : 0.f;
;       if (mode == 2) o = sigmf(v);
;       sT[row * 136 + col] = f2bf(o);
;     });
.LBB0_3147:
	v_bfe_u32 v55, v54, 16, 1
	v_add3_u32 v55, v54, v55, s79
	v_add_u32_e32 v54, 0x110, v53
	v_lshl_add_u32 v53, v106, 1, v54
	ds_write_b16_d16_hi v53, v55
	v_add3_u32 v55, s94, v96, 42
	v_cmp_lt_i32_e64 s[20:21], s77, v55
	s_nop 1

; __device__ __forceinline__ float sigmf(float x) { return 1.f / (1.f + __expf(-x)); }
; __device__ __forceinline__ bf16r f2bf(float f) {
;   unsigned u = __float_as_uint(f);
;   u += 0x7fffu + ((u >> 16) & 1u);
;   return (bf16r)(u >> 16);
; }
; __device__ __forceinline__ void inproj_epilogue(const Params& p, int layer, int mt, int ntile, int tid,
;                                                 f32x16 (&acc)[2][2], unsigned char* smem) {
;     ...
;     acc_foreach(tid, acc, [&](int row, int col, float v) {
;       int t = m0 + row;
;       float o = v;
;       if (mode == 1) o = (t >= NPADR) ? v : 0.f;
;       if (mode == 2) o = sigmf(v);
;       sT[row * 136 + col] = f2bf(o);
;     });
.LBB0_3150:
	v_bfe_u32 v56, v55, 16, 1
	v_add3_u32 v56, v55, v56, s79
	v_add_u32_e32 v55, 0x110, v54
	v_lshl_add_u32 v54, v106, 1, v55
	ds_write_b16_d16_hi v54, v56
	v_add3_u32 v56, s94, v96, 43
	v_cmp_lt_i32_e64 s[22:23], s77, v56
	s_nop 1

; __device__ __forceinline__ float sigmf(float x) { return 1.f / (1.f + __expf(-x)); }
; __device__ __forceinline__ bf16r f2bf(float f) {
;   unsigned u = __float_as_uint(f);
;   u += 0x7fffu + ((u >> 16) & 1u);
;   return (bf16r)(u >> 16);
; }
; __device__ __forceinline__ void inproj_epilogue(const Params& p, int layer, int mt, int ntile, int tid,
;                                                 f32x16 (&acc)[2][2], unsigned char* smem) {
;     ...
;     acc_foreach(tid, acc, [&](int row, int col, float v) {
;       int t = m0 + row;
;       float o = v;
;       if (mode == 1) o = (t >= NPADR) ? v : 0.f;
;       if (mode == 2) o = sigmf(v);
;       sT[row * 136 + col] = f2bf(o);
;     });
.LBB0_3153:
	v_bfe_u32 v57, v56, 16, 1
	v_add_u32_e32 v55, 0x110, v55
	v_add3_u32 v57, v56, v57, s79
	v_lshl_add_u32 v56, v106, 1, v55
	ds_write_b16_d16_hi v56, v57
	v_add3_u32 v57, s94, v96, 48
	v_cmp_lt_i32_e64 s[24:25], s77, v57
	s_nop 1

; __device__ __forceinline__ float sigmf(float x) { return 1.f / (1.f + __expf(-x)); }
; __device__ __forceinline__ bf16r f2bf(float f) {
;   unsigned u = __float_as_uint(f);
;   u += 0x7fffu + ((u >> 16) & 1u);
;   return (bf16r)(u >> 16);
; }
; __device__ __forceinline__ void inproj_epilogue(const Params& p, int layer, int mt, int ntile, int tid,
;                                                 f32x16 (&acc)[2][2], unsigned char* smem) {
;     ...
;     acc_foreach(tid, acc, [&](int row, int col, float v) {
;       int t = m0 + row;
;       float o = v;
;       if (mode == 1) o = (t >= NPADR) ? v : 0.f;
;       if (mode == 2) o = sigmf(v);
;       sT[row * 136 + col] = f2bf(o);
;     });
.LBB0_3156:
	v_bfe_u32 v58, v57, 16, 1
	v_add_u32_e32 v55, 0x550, v55
	v_add3_u32 v58, v57, v58, s79
	v_lshl_add_u32 v57, v106, 1, v55
	ds_write_b16_d16_hi v57, v58
	v_add3_u32 v58, s94, v96, 49
	v_cmp_lt_i32_e64 s[26:27], s77, v58
	s_nop 1

; __device__ __forceinline__ float sigmf(float x) { return 1.f / (1.f + __expf(-x)); }
; __device__ __forceinline__ bf16r f2bf(float f) {
;   unsigned u = __float_as_uint(f);
;   u += 0x7fffu + ((u >> 16) & 1u);
;   return (bf16r)(u >> 16);
; }
; __device__ __forceinline__ void inproj_epilogue(const Params& p, int layer, int mt, int ntile, int tid,
;                                                 f32x16 (&acc)[2][2], unsigned char* smem) {
;     ...
;     acc_foreach(tid, acc, [&](int row, int col, float v) {
;       int t = m0 + row;
;       float o = v;
;       if (mode == 1) o = (t >= NPADR) ? v : 0.f;
;       if (mode == 2) o = sigmf(v);
;       sT[row * 136 + col] = f2bf(o);
;     });
.LBB0_3159:
	v_bfe_u32 v59, v58, 16, 1
	v_add_u32_e32 v55, 0x110, v55
	v_add3_u32 v59, v58, v59, s79
	v_lshl_add_u32 v58, v106, 1, v55
	ds_write_b16_d16_hi v58, v59
	v_add3_u32 v59, s94, v96, 50
	v_cmp_lt_i32_e64 s[28:29], s77, v59
	s_nop 1

; __device__ __forceinline__ float sigmf(float x) { return 1.f / (1.f + __expf(-x)); }
; __device__ __forceinline__ bf16r f2bf(float f) {
;   unsigned u = __float_as_uint(f);
;   u += 0x7fffu + ((u >> 16) & 1u);
;   return (bf16r)(u >> 16);
; }
; __device__ __forceinline__ void inproj_epilogue(const Params& p, int layer, int mt, int ntile, int tid,
;                                                 f32x16 (&acc)[2][2], unsigned char* smem) {
;     ...
;     acc_foreach(tid, acc, [&](int row, int col, float v) {
;       int t = m0 + row;
;       float o = v;
;       if (mode == 1) o = (t >= NPADR) ? v : 0.f;
;       if (mode == 2) o = sigmf(v);
;       sT[row * 136 + col] = f2bf(o);
;     });
.LBB0_3162:
	v_bfe_u32 v60, v59, 16, 1
	v_add_u32_e32 v55, 0x110, v55
	v_add3_u32 v60, v59, v60, s79
	v_lshl_add_u32 v59, v106, 1, v55
	ds_write_b16_d16_hi v59, v60
	v_add3_u32 v60, s94, v96, 51
	v_cmp_lt_i32_e64 s[30:31], s77, v60
	s_nop 1

; __device__ __forceinline__ float sigmf(float x) { return 1.f / (1.f + __expf(-x)); }
; __device__ __forceinline__ bf16r f2bf(float f) {
;   unsigned u = __float_as_uint(f);
;   u += 0x7fffu + ((u >> 16) & 1u);
;   return (bf16r)(u >> 16);
; }
; __device__ __forceinline__ void inproj_epilogue(const Params& p, int layer, int mt, int ntile, int tid,
;                                                 f32x16 (&acc)[2][2], unsigned char* smem) {
;     ...
;     acc_foreach(tid, acc, [&](int row, int col, float v) {
;       int t = m0 + row;
;       float o = v;
;       if (mode == 1) o = (t >= NPADR) ? v : 0.f;
;       if (mode == 2) o = sigmf(v);
;       sT[row * 136 + col] = f2bf(o);
;     });
.LBB0_3165:
	v_bfe_u32 v61, v60, 16, 1
	v_add_u32_e32 v55, 0x110, v55
	v_add3_u32 v61, v60, v61, s79
	v_lshl_add_u32 v60, v106, 1, v55
	ds_write_b16_d16_hi v60, v61
	v_add3_u32 v61, s94, v96, 56
	v_cmp_lt_i32_e64 s[34:35], s77, v61
	s_nop 1

; __device__ __forceinline__ float sigmf(float x) { return 1.f / (1.f + __expf(-x)); }
; __device__ __forceinline__ bf16r f2bf(float f) {
;   unsigned u = __float_as_uint(f);
;   u += 0x7fffu + ((u >> 16) & 1u);
;   return (bf16r)(u >> 16);
; }
; __device__ __forceinline__ void inproj_epilogue(const Params& p, int layer, int mt, int ntile, int tid,
;                                                 f32x16 (&acc)[2][2], unsigned char* smem) {
;     ...
;     acc_foreach(tid, acc, [&](int row, int col, float v) {
;       int t = m0 + row;
;       float o = v;
;       if (mode == 1) o = (t >= NPADR) ? v : 0.f;
;       if (mode == 2) o = sigmf(v);
;       sT[row * 136 + col] = f2bf(o);
;     });
.LBB0_3168:
	v_bfe_u32 v62, v61, 16, 1
	v_add_u32_e32 v55, 0x550, v55
	v_add3_u32 v62, v61, v62, s79
	v_lshl_add_u32 v61, v106, 1, v55
	ds_write_b16_d16_hi v61, v62
	v_add3_u32 v62, s94, v96, 57
	v_cmp_lt_i32_e64 s[36:37], s77, v62
	s_nop 1

; __device__ __forceinline__ float sigmf(float x) { return 1.f / (1.f + __expf(-x)); }
; __device__ __forceinline__ bf16r f2bf(float f) {
;   unsigned u = __float_as_uint(f);
;   u += 0x7fffu + ((u >> 16) & 1u);
;   return (bf16r)(u >> 16);
; }
; __device__ __forceinline__ void inproj_epilogue(const Params& p, int layer, int mt, int ntile, int tid,
;                                                 f32x16 (&acc)[2][2], unsigned char* smem) {
;     ...
;     acc_foreach(tid, acc, [&](int row, int col, float v) {
;       int t = m0 + row;
;       float o = v;
;       if (mode == 1) o = (t >= NPADR) ? v : 0.f;
;       if (mode == 2) o = sigmf(v);
;       sT[row * 136 + col] = f2bf(o);
;     });
.LBB0_3171:
	v_bfe_u32 v63, v62, 16, 1
	v_add_u32_e32 v55, 0x110, v55
	v_add3_u32 v63, v62, v63, s79
	v_lshl_add_u32 v62, v106, 1, v55
	ds_write_b16_d16_hi v62, v63
	v_add3_u32 v63, s94, v96, 58
	v_cmp_lt_i32_e64 s[38:39], s77, v63
	s_nop 1

; __device__ __forceinline__ float sigmf(float x) { return 1.f / (1.f + __expf(-x)); }
; __device__ __forceinline__ bf16r f2bf(float f) {
;   unsigned u = __float_as_uint(f);
;   u += 0x7fffu + ((u >> 16) & 1u);
;   return (bf16r)(u >> 16);
; }
; __device__ __forceinline__ void inproj_epilogue(const Params& p, int layer, int mt, int ntile, int tid,
;                                                 f32x16 (&acc)[2][2], unsigned char* smem) {
;     ...
;     acc_foreach(tid, acc, [&](int row, int col, float v) {
;       int t = m0 + row;
;       float o = v;
;       if (mode == 1) o = (t >= NPADR) ? v : 0.f;
;       if (mode == 2) o = sigmf(v);
;       sT[row * 136 + col] = f2bf(o);
;     });
.LBB0_3174:
	v_bfe_u32 v107, v63, 16, 1
	v_add_u32_e32 v55, 0x110, v55
	v_add3_u32 v63, v63, v107, s79
	v_lshl_add_u32 v55, v106, 1, v55
	ds_write_b16_d16_hi v55, v63
	v_add3_u32 v63, s94, v96, 59
	v_cmp_lt_i32_e64 s[40:41], s77, v63
	s_nop 1

; __device__ __forceinline__ bf16r f2bf(float f) {
;   unsigned u = __float_as_uint(f);
;   u += 0x7fffu + ((u >> 16) & 1u);
;   return (bf16r)(u >> 16);
; }
; __device__ __forceinline__ unsigned pack2(float a, float b) { return (unsigned)f2bf(a) | ((unsigned)f2bf(b) << 16); }
; __device__ __forceinline__ float lo16(unsigned v) { return __uint_as_float(v << 16); }
; __device__ __forceinline__ float hi16(unsigned v) { return __uint_as_float(v & 0xffff0000u); }
; __device__ __forceinline__ float siluf(float x) { return x / (1.f + __expf(-x)); }
; __device__ __forceinline__ float sigmf(float x) { return 1.f / (1.f + __expf(-x)); }
; __device__ __forceinline__ void inproj_epilogue(const Params& p, int layer, int mt, int ntile, int tid,
;                                                 f32x16 (&acc)[2][2], unsigned char* smem) {
;     ...
;     acc_foreach(tid, acc, [&](int row, int col, float v) {
;       int t = m0 + row;
;       float o = v;
;       if (mode == 1) o = (t >= NPADR) ? v : 0.f;
;       if (mode == 2) o = sigmf(v);
;       sT[row * 136 + col] = f2bf(o);
;     });
.Lgv_6:
	v_mul_f32_e32 v107, 0xbfb8aa3b, v16
	v_exp_f32_e32 v107, v107
	s_nop 0
	v_add_f32_e32 v107, 1.0, v107
	v_div_scale_f32 v110, s[6:7], v107, v107, 1.0
	v_rcp_f32_e32 v111, v110
	v_div_scale_f32 v112, vcc, 1.0, v107, 1.0
	v_fma_f32 v113, -v110, v111, 1.0
	v_fmac_f32_e32 v111, v113, v111
	v_mul_f32_e32 v113, v112, v111
	v_fma_f32 v114, -v110, v113, v112
	v_fmac_f32_e32 v113, v114, v111
	v_fma_f32 v110, -v110, v113, v112
	v_div_fmas_f32 v110, v110, v111, v113
	v_div_fixup_f32 v107, v110, v107, 1.0
	v_bfe_u32 v110, v107, 16, 1
	v_and_b32_e32 v106, 0x5f, v106
	v_add3_u32 v111, v107, v110, s79
	v_mul_lo_u32 v110, v96, s80
	v_lshl_add_u32 v107, v106, 1, v110
	ds_write_b16_d16_hi v107, v111
	v_add3_u32 v111, s94, v96, 1
	v_cndmask_b32_e64 v112, 0, 1, s[10:11]
	v_cmp_ne_u32_e64 s[6:7], 1, v112
	s_andn2_b64 vcc, exec, s[10:11]
	v_cmp_lt_i32_e64 s[10:11], s77, v111
	v_mul_f32_e32 v111, 0xbfb8aa3b, v17
	v_exp_f32_e32 v111, v111
	s_nop 0
	v_add_f32_e32 v111, 1.0, v111
	v_div_scale_f32 v112, s[12:13], v111, v111, 1.0
	v_rcp_f32_e32 v113, v112
	v_div_scale_f32 v114, vcc, 1.0, v111, 1.0
	v_fma_f32 v115, -v112, v113, 1.0
	v_fmac_f32_e32 v113, v115, v113
	v_mul_f32_e32 v115, v114, v113
	v_fma_f32 v116, -v112, v115, v114
	v_fmac_f32_e32 v115, v116, v113
	v_fma_f32 v112, -v112, v115, v114
	v_div_fmas_f32 v112, v112, v113, v115
	v_div_fixup_f32 v111, v112, v111, 1.0
	v_bfe_u32 v112, v111, 16, 1
	v_add3_u32 v112, v111, v112, s79
	v_add_u32_e32 v111, 0x110, v110
	v_lshl_add_u32 v110, v106, 1, v111
	ds_write_b16_d16_hi v110, v112
	v_add3_u32 v112, s94, v96, 2
	s_and_b64 vcc, exec, s[6:7]
	v_cmp_lt_i32_e64 s[12:13], s77, v112
	v_mul_f32_e32 v112, 0xbfb8aa3b, v18
	v_exp_f32_e32 v112, v112
	s_nop 0
	v_add_f32_e32 v112, 1.0, v112
	v_div_scale_f32 v113, s[14:15], v112, v112, 1.0
	v_rcp_f32_e32 v114, v113
	v_div_scale_f32 v115, vcc, 1.0, v112, 1.0
	v_fma_f32 v116, -v113, v114, 1.0
	v_fmac_f32_e32 v114, v116, v114
	v_mul_f32_e32 v116, v115, v114
	v_fma_f32 v117, -v113, v116, v115
	v_fmac_f32_e32 v116, v117, v114
	v_fma_f32 v113, -v113, v116, v115
	v_div_fmas_f32 v113, v113, v114, v116
	v_div_fixup_f32 v112, v113, v112, 1.0
	v_bfe_u32 v113, v112, 16, 1
	v_add3_u32 v113, v112, v113, s79
	v_add_u32_e32 v112, 0x110, v111
	v_lshl_add_u32 v111, v106, 1, v112
	ds_write_b16_d16_hi v111, v113
	v_add3_u32 v113, s94, v96, 3
	s_and_b64 vcc, exec, s[6:7]
	v_cmp_lt_i32_e64 s[14:15], s77, v113
	v_mul_f32_e32 v113, 0xbfb8aa3b, v19
	v_exp_f32_e32 v113, v113
	s_nop 0
	v_add_f32_e32 v113, 1.0, v113
	v_div_scale_f32 v114, s[16:17], v113, v113, 1.0
	v_rcp_f32_e32 v115, v114
	v_div_scale_f32 v116, vcc, 1.0, v113, 1.0
	v_fma_f32 v117, -v114, v115, 1.0
	v_fmac_f32_e32 v115, v117, v115
	v_mul_f32_e32 v117, v116, v115
	v_fma_f32 v118, -v114, v117, v116
	v_fmac_f32_e32 v117, v118, v115
	v_fma_f32 v114, -v114, v117, v116
	v_div_fmas_f32 v114, v114, v115, v117
	v_div_fixup_f32 v113, v114, v113, 1.0
	v_bfe_u32 v114, v113, 16, 1
	v_add3_u32 v114, v113, v114, s79
	v_add_u32_e32 v113, 0x110, v112
	v_lshl_add_u32 v112, v106, 1, v113
	ds_write_b16_d16_hi v112, v114
	v_add3_u32 v114, s94, v96, 8
	s_and_b64 vcc, exec, s[6:7]
	v_cmp_lt_i32_e64 s[16:17], s77, v114
	v_mul_f32_e32 v114, 0xbfb8aa3b, v20
	v_exp_f32_e32 v114, v114
	s_nop 0
	v_add_f32_e32 v114, 1.0, v114
	v_div_scale_f32 v115, s[18:19], v114, v114, 1.0
	v_rcp_f32_e32 v116, v115
	v_div_scale_f32 v117, vcc, 1.0, v114, 1.0
	v_fma_f32 v118, -v115, v116, 1.0
	v_fmac_f32_e32 v116, v118, v116
	v_mul_f32_e32 v118, v117, v116
	v_fma_f32 v119, -v115, v118, v117
	v_fmac_f32_e32 v118, v119, v116
	v_fma_f32 v115, -v115, v118, v117
	v_div_fmas_f32 v115, v115, v116, v118
	v_div_fixup_f32 v114, v115, v114, 1.0
	v_bfe_u32 v115, v114, 16, 1
	v_add3_u32 v115, v114, v115, s79
	v_add_u32_e32 v114, 0x550, v113
	v_lshl_add_u32 v113, v106, 1, v114
	ds_write_b16_d16_hi v113, v115
	v_add3_u32 v115, s94, v96, 9
	s_and_b64 vcc, exec, s[6:7]
	v_cmp_lt_i32_e64 s[18:19], s77, v115
	v_mul_f32_e32 v115, 0xbfb8aa3b, v21
	v_exp_f32_e32 v115, v115
	s_nop 0
	v_add_f32_e32 v115, 1.0, v115
	v_div_scale_f32 v116, s[20:21], v115, v115, 1.0
	v_rcp_f32_e32 v117, v116
	v_div_scale_f32 v118, vcc, 1.0, v115, 1.0
	v_fma_f32 v119, -v116, v117, 1.0
	v_fmac_f32_e32 v117, v119, v117
	v_mul_f32_e32 v119, v118, v117
	v_fma_f32 v120, -v116, v119, v118
	v_fmac_f32_e32 v119, v120, v117
	v_fma_f32 v116, -v116, v119, v118
	v_div_fmas_f32 v116, v116, v117, v119
	v_div_fixup_f32 v115, v116, v115, 1.0
	v_bfe_u32 v116, v115, 16, 1
	v_add3_u32 v116, v115, v116, s79
	v_add_u32_e32 v115, 0x110, v114
	v_lshl_add_u32 v114, v106, 1, v115
	ds_write_b16_d16_hi v114, v116
	v_add3_u32 v116, s94, v96, 10
	s_and_b64 vcc, exec, s[6:7]
	v_cmp_lt_i32_e64 s[20:21], s77, v116
	v_mul_f32_e32 v116, 0xbfb8aa3b, v22
	v_exp_f32_e32 v116, v116
	s_nop 0
	v_add_f32_e32 v116, 1.0, v116
	v_div_scale_f32 v117, s[22:23], v116, v116, 1.0
	v_rcp_f32_e32 v118, v117
	v_div_scale_f32 v119, vcc, 1.0, v116, 1.0
	v_fma_f32 v120, -v117, v118, 1.0
	v_fmac_f32_e32 v118, v120, v118
	v_mul_f32_e32 v120, v119, v118
	v_fma_f32 v121, -v117, v120, v119
	v_fmac_f32_e32 v120, v121, v118
	v_fma_f32 v117, -v117, v120, v119
	v_div_fmas_f32 v117, v117, v118, v120
	v_div_fixup_f32 v116, v117, v116, 1.0
	v_bfe_u32 v117, v116, 16, 1
	v_add3_u32 v117, v116, v117, s79
	v_add_u32_e32 v116, 0x110, v115
	v_lshl_add_u32 v115, v106, 1, v116
	ds_write_b16_d16_hi v115, v117
	v_add3_u32 v117, s94, v96, 11
	s_and_b64 vcc, exec, s[6:7]
	v_cmp_lt_i32_e64 s[22:23], s77, v117
	v_mul_f32_e32 v117, 0xbfb8aa3b, v23
	v_exp_f32_e32 v117, v117
	s_nop 0
	v_add_f32_e32 v117, 1.0, v117
	v_div_scale_f32 v118, s[24:25], v117, v117, 1.0
	v_rcp_f32_e32 v119, v118
; __device__ __forceinline__ bf16r f2bf(float f) {
;   unsigned u = __float_as_uint(f);
;   u += 0x7fffu + ((u >> 16) & 1u);
;   return (bf16r)(u >> 16);
; }
; __device__ __forceinline__ unsigned pack2(float a, float b) { return (unsigned)f2bf(a) | ((unsigned)f2bf(b) << 16); }
; __device__ __forceinline__ float lo16(unsigned v) { return __uint_as_float(v << 16); }
; __device__ __forceinline__ float hi16(unsigned v) { return __uint_as_float(v & 0xffff0000u); }
; __device__ __forceinline__ float siluf(float x) { return x / (1.f + __expf(-x)); }
; __device__ __forceinline__ float sigmf(float x) { return 1.f / (1.f + __expf(-x)); }
; __device__ __forceinline__ void inproj_epilogue(const Params& p, int layer, int mt, int ntile, int tid,
;                                                 f32x16 (&acc)[2][2], unsigned char* smem) {
;     ...
;     acc_foreach(tid, acc, [&](int row, int col, float v) {
;       int t = m0 + row;
;       float o = v;
;       if (mode == 1) o = (t >= NPADR) ? v : 0.f;
;       if (mode == 2) o = sigmf(v);
;       sT[row * 136 + col] = f2bf(o);
;     });
	v_div_scale_f32 v120, vcc, 1.0, v117, 1.0
	v_fma_f32 v121, -v118, v119, 1.0
	v_fmac_f32_e32 v119, v121, v119
	v_mul_f32_e32 v121, v120, v119
	v_fma_f32 v122, -v118, v121, v120
	v_fmac_f32_e32 v121, v122, v119
	v_fma_f32 v118, -v118, v121, v120
	v_div_fmas_f32 v118, v118, v119, v121
	v_div_fixup_f32 v117, v118, v117, 1.0
	v_bfe_u32 v118, v117, 16, 1
	v_add_u32_e32 v116, 0x110, v116
	v_add3_u32 v118, v117, v118, s79
	v_lshl_add_u32 v117, v106, 1, v116
	ds_write_b16_d16_hi v117, v118
	v_add3_u32 v118, s94, v96, 16
	s_and_b64 vcc, exec, s[6:7]
	v_cmp_lt_i32_e64 s[24:25], s77, v118
	v_mul_f32_e32 v118, 0xbfb8aa3b, v24
	v_exp_f32_e32 v118, v118
	s_nop 0
	v_add_f32_e32 v118, 1.0, v118
	v_div_scale_f32 v119, s[26:27], v118, v118, 1.0
	v_rcp_f32_e32 v120, v119
	v_div_scale_f32 v121, vcc, 1.0, v118, 1.0
	v_fma_f32 v122, -v119, v120, 1.0
	v_fmac_f32_e32 v120, v122, v120
	v_mul_f32_e32 v122, v121, v120
	v_fma_f32 v123, -v119, v122, v121
	v_fmac_f32_e32 v122, v123, v120
	v_fma_f32 v119, -v119, v122, v121
	v_div_fmas_f32 v119, v119, v120, v122
	v_div_fixup_f32 v118, v119, v118, 1.0
	v_bfe_u32 v119, v118, 16, 1
	v_add_u32_e32 v116, 0x550, v116
	v_add3_u32 v119, v118, v119, s79
	v_lshl_add_u32 v118, v106, 1, v116
	ds_write_b16_d16_hi v118, v119
	v_add3_u32 v119, s94, v96, 17
	s_and_b64 vcc, exec, s[6:7]
	v_cmp_lt_i32_e64 s[26:27], s77, v119
	v_mul_f32_e32 v119, 0xbfb8aa3b, v25
	v_exp_f32_e32 v119, v119
	s_nop 0
	v_add_f32_e32 v119, 1.0, v119
	v_div_scale_f32 v120, s[28:29], v119, v119, 1.0
	v_rcp_f32_e32 v121, v120
	v_div_scale_f32 v122, vcc, 1.0, v119, 1.0
	v_fma_f32 v123, -v120, v121, 1.0
	v_fmac_f32_e32 v121, v123, v121
	v_mul_f32_e32 v123, v122, v121
	v_fma_f32 v124, -v120, v123, v122
	v_fmac_f32_e32 v123, v124, v121
	v_fma_f32 v120, -v120, v123, v122
	v_div_fmas_f32 v120, v120, v121, v123
	v_div_fixup_f32 v119, v120, v119, 1.0
	v_bfe_u32 v120, v119, 16, 1
	v_add_u32_e32 v116, 0x110, v116
	v_add3_u32 v120, v119, v120, s79
	v_lshl_add_u32 v119, v106, 1, v116
	ds_write_b16_d16_hi v119, v120
	v_add3_u32 v120, s94, v96, 18
	s_and_b64 vcc, exec, s[6:7]
	v_cmp_lt_i32_e64 s[28:29], s77, v120
	v_mul_f32_e32 v120, 0xbfb8aa3b, v26
	v_exp_f32_e32 v120, v120
	s_nop 0
	v_add_f32_e32 v120, 1.0, v120
	v_div_scale_f32 v121, s[30:31], v120, v120, 1.0
	v_rcp_f32_e32 v122, v121
	v_div_scale_f32 v123, vcc, 1.0, v120, 1.0
	v_fma_f32 v124, -v121, v122, 1.0
	v_fmac_f32_e32 v122, v124, v122
	v_mul_f32_e32 v124, v123, v122
	v_fma_f32 v125, -v121, v124, v123
	v_fmac_f32_e32 v124, v125, v122
	v_fma_f32 v121, -v121, v124, v123
	v_div_fmas_f32 v121, v121, v122, v124
	v_div_fixup_f32 v120, v121, v120, 1.0
	v_bfe_u32 v121, v120, 16, 1
	v_add_u32_e32 v116, 0x110, v116
	v_add3_u32 v121, v120, v121, s79
	v_lshl_add_u32 v120, v106, 1, v116
	ds_write_b16_d16_hi v120, v121
	v_add3_u32 v121, s94, v96, 19
	s_and_b64 vcc, exec, s[6:7]
	v_cmp_lt_i32_e64 s[30:31], s77, v121
	v_mul_f32_e32 v121, 0xbfb8aa3b, v27
	v_exp_f32_e32 v121, v121
	s_nop 0
	v_add_f32_e32 v121, 1.0, v121
	v_div_scale_f32 v122, s[34:35], v121, v121, 1.0
	v_rcp_f32_e32 v123, v122
	v_div_scale_f32 v124, vcc, 1.0, v121, 1.0
	v_fma_f32 v125, -v122, v123, 1.0
	v_fmac_f32_e32 v123, v125, v123
	v_mul_f32_e32 v125, v124, v123
	v_fma_f32 v126, -v122, v125, v124
	v_fmac_f32_e32 v125, v126, v123
	v_fma_f32 v122, -v122, v125, v124
	v_div_fmas_f32 v122, v122, v123, v125
	v_div_fixup_f32 v121, v122, v121, 1.0
	v_bfe_u32 v122, v121, 16, 1
	v_add_u32_e32 v116, 0x110, v116
	v_add3_u32 v122, v121, v122, s79
	v_lshl_add_u32 v121, v106, 1, v116
	ds_write_b16_d16_hi v121, v122
	v_add3_u32 v122, s94, v96, 24
	s_and_b64 vcc, exec, s[6:7]
	v_cmp_lt_i32_e64 s[34:35], s77, v122
	v_mul_f32_e32 v122, 0xbfb8aa3b, v28
	v_exp_f32_e32 v122, v122
	s_nop 0
	v_add_f32_e32 v122, 1.0, v122
	v_div_scale_f32 v123, s[36:37], v122, v122, 1.0
	v_rcp_f32_e32 v124, v123
	v_div_scale_f32 v125, vcc, 1.0, v122, 1.0
	v_fma_f32 v126, -v123, v124, 1.0
	v_fmac_f32_e32 v124, v126, v124
	v_mul_f32_e32 v126, v125, v124
	v_fma_f32 v127, -v123, v126, v125
	v_fmac_f32_e32 v126, v127, v124
	v_fma_f32 v123, -v123, v126, v125
	v_div_fmas_f32 v123, v123, v124, v126
	v_div_fixup_f32 v122, v123, v122, 1.0
	v_bfe_u32 v123, v122, 16, 1
	v_add_u32_e32 v116, 0x550, v116
	v_add3_u32 v123, v122, v123, s79
	v_lshl_add_u32 v122, v106, 1, v116
	ds_write_b16_d16_hi v122, v123
	v_add3_u32 v123, s94, v96, 25
	s_and_b64 vcc, exec, s[6:7]
	v_cmp_lt_i32_e64 s[36:37], s77, v123
	v_mul_f32_e32 v123, 0xbfb8aa3b, v29
	v_exp_f32_e32 v123, v123
	s_nop 0
	v_add_f32_e32 v123, 1.0, v123
	v_div_scale_f32 v124, s[38:39], v123, v123, 1.0
	v_rcp_f32_e32 v125, v124
	v_div_scale_f32 v126, vcc, 1.0, v123, 1.0
	v_fma_f32 v127, -v124, v125, 1.0
	v_fmac_f32_e32 v125, v127, v125
	v_mul_f32_e32 v127, v126, v125
	v_fma_f32 v128, -v124, v127, v126
	v_fmac_f32_e32 v127, v128, v125
	v_fma_f32 v124, -v124, v127, v126
	v_div_fmas_f32 v124, v124, v125, v127
	v_div_fixup_f32 v123, v124, v123, 1.0
	v_bfe_u32 v124, v123, 16, 1
	v_add_u32_e32 v116, 0x110, v116
	v_add3_u32 v124, v123, v124, s79
	v_lshl_add_u32 v123, v106, 1, v116
	ds_write_b16_d16_hi v123, v124
	v_add3_u32 v124, s94, v96, 26
	s_and_b64 vcc, exec, s[6:7]
	v_cmp_lt_i32_e64 s[38:39], s77, v124
	v_mul_f32_e32 v124, 0xbfb8aa3b, v30
	v_exp_f32_e32 v124, v124
	s_nop 0
	v_add_f32_e32 v124, 1.0, v124
	v_div_scale_f32 v125, s[40:41], v124, v124, 1.0
	v_rcp_f32_e32 v126, v125
	v_div_scale_f32 v127, vcc, 1.0, v124, 1.0
	v_fma_f32 v128, -v125, v126, 1.0
	v_fmac_f32_e32 v126, v128, v126
	v_mul_f32_e32 v128, v127, v126
	v_fma_f32 v129, -v125, v128, v127
	v_fmac_f32_e32 v128, v129, v126
	v_fma_f32 v125, -v125, v128, v127
	v_div_fmas_f32 v125, v125, v126, v128
; __device__ __forceinline__ bf16r f2bf(float f) {
;   unsigned u = __float_as_uint(f);
;   u += 0x7fffu + ((u >> 16) & 1u);
;   return (bf16r)(u >> 16);
; }
; __device__ __forceinline__ unsigned pack2(float a, float b) { return (unsigned)f2bf(a) | ((unsigned)f2bf(b) << 16); }
; __device__ __forceinline__ float lo16(unsigned v) { return __uint_as_float(v << 16); }
; __device__ __forceinline__ float hi16(unsigned v) { return __uint_as_float(v & 0xffff0000u); }
; __device__ __forceinline__ float siluf(float x) { return x / (1.f + __expf(-x)); }
; __device__ __forceinline__ float sigmf(float x) { return 1.f / (1.f + __expf(-x)); }
; __device__ __forceinline__ void inproj_epilogue(const Params& p, int layer, int mt, int ntile, int tid,
;                                                 f32x16 (&acc)[2][2], unsigned char* smem) {
;     ...
;     acc_foreach(tid, acc, [&](int row, int col, float v) {
;       int t = m0 + row;
;       float o = v;
;       if (mode == 1) o = (t >= NPADR) ? v : 0.f;
;       if (mode == 2) o = sigmf(v);
;       sT[row * 136 + col] = f2bf(o);
;     });
	v_div_fixup_f32 v124, v125, v124, 1.0
	v_bfe_u32 v125, v124, 16, 1
	v_add_u32_e32 v116, 0x110, v116
	v_add3_u32 v124, v124, v125, s79
	v_lshl_add_u32 v116, v106, 1, v116
	ds_write_b16_d16_hi v116, v124
	v_add3_u32 v124, s94, v96, 27
	s_and_b64 vcc, exec, s[6:7]
	v_cmp_lt_i32_e64 s[40:41], s77, v124
	v_mul_f32_e32 v124, 0xbfb8aa3b, v31
	v_exp_f32_e32 v124, v124
	s_nop 0
	v_add_f32_e32 v124, 1.0, v124
	v_div_scale_f32 v125, vcc, v124, v124, 1.0
	v_rcp_f32_e32 v126, v125
	v_div_scale_f32 v127, vcc, 1.0, v124, 1.0
	v_fma_f32 v128, -v125, v126, 1.0
	v_fmac_f32_e32 v126, v128, v126
	v_mul_f32_e32 v128, v127, v126
	v_fma_f32 v129, -v125, v128, v127
	v_fmac_f32_e32 v128, v129, v126
	v_fma_f32 v125, -v125, v128, v127
	v_div_fmas_f32 v125, v125, v126, v128
	v_div_fixup_f32 v124, v125, v124, 1.0
	v_bfe_u32 v125, v124, 16, 1
	v_add3_u32 v124, v124, v125, s79
	ds_write_b16_d16_hi v116, v124 offset:272
	s_and_b64 vcc, exec, s[6:7]
	v_mul_f32_e32 v48, 0xbfb8aa3b, v48
	v_exp_f32_e32 v48, v48
	s_nop 0
	v_add_f32_e32 v48, 1.0, v48
	v_div_scale_f32 v124, s[8:9], v48, v48, 1.0
	v_rcp_f32_e32 v125, v124
	v_div_scale_f32 v126, vcc, 1.0, v48, 1.0
	v_fma_f32 v127, -v124, v125, 1.0
	v_fmac_f32_e32 v125, v127, v125
	v_mul_f32_e32 v127, v126, v125
	v_fma_f32 v128, -v124, v127, v126
	v_fmac_f32_e32 v127, v128, v125
	v_fma_f32 v124, -v124, v127, v126
	v_div_fmas_f32 v124, v124, v125, v127
	v_div_fixup_f32 v48, v124, v48, 1.0
	v_bfe_u32 v124, v48, 16, 1
	v_add3_u32 v48, v48, v124, s79
	s_and_b64 vcc, exec, s[6:7]
	ds_write_b16_d16_hi v107, v48 offset:64
	v_mul_f32_e32 v48, 0xbfb8aa3b, v49
	v_exp_f32_e32 v48, v48
	s_nop 0
	v_add_f32_e32 v48, 1.0, v48
	v_div_scale_f32 v49, s[8:9], v48, v48, 1.0
	v_rcp_f32_e32 v107, v49
	v_div_scale_f32 v124, vcc, 1.0, v48, 1.0
	v_fma_f32 v125, -v49, v107, 1.0
	v_fmac_f32_e32 v107, v125, v107
	v_mul_f32_e32 v125, v124, v107
	v_fma_f32 v126, -v49, v125, v124
	v_fmac_f32_e32 v125, v126, v107
	v_fma_f32 v49, -v49, v125, v124
	v_div_fmas_f32 v49, v49, v107, v125
	v_div_fixup_f32 v48, v49, v48, 1.0
	v_bfe_u32 v49, v48, 16, 1
	v_add3_u32 v48, v48, v49, s79
	s_and_b64 vcc, exec, s[6:7]
	ds_write_b16_d16_hi v110, v48 offset:64
	v_mul_f32_e32 v48, 0xbfb8aa3b, v50
	v_exp_f32_e32 v48, v48
	s_nop 0
	v_add_f32_e32 v48, 1.0, v48
	v_div_scale_f32 v49, s[8:9], v48, v48, 1.0
	v_rcp_f32_e32 v50, v49
	v_div_scale_f32 v107, vcc, 1.0, v48, 1.0
	v_fma_f32 v110, -v49, v50, 1.0
	v_fmac_f32_e32 v50, v110, v50
	v_mul_f32_e32 v110, v107, v50
	v_fma_f32 v124, -v49, v110, v107
	v_fmac_f32_e32 v110, v124, v50
	v_fma_f32 v49, -v49, v110, v107
	v_div_fmas_f32 v49, v49, v50, v110
	v_div_fixup_f32 v48, v49, v48, 1.0
	v_bfe_u32 v49, v48, 16, 1
	v_add3_u32 v48, v48, v49, s79
	s_and_b64 vcc, exec, s[6:7]
	ds_write_b16_d16_hi v111, v48 offset:64
	v_mul_f32_e32 v48, 0xbfb8aa3b, v51
	v_exp_f32_e32 v48, v48
	s_nop 0
	v_add_f32_e32 v48, 1.0, v48
	v_div_scale_f32 v49, s[8:9], v48, v48, 1.0
	v_rcp_f32_e32 v50, v49
	v_div_scale_f32 v51, vcc, 1.0, v48, 1.0
	v_fma_f32 v107, -v49, v50, 1.0
	v_fmac_f32_e32 v50, v107, v50
	v_mul_f32_e32 v107, v51, v50
	v_fma_f32 v110, -v49, v107, v51
	v_fmac_f32_e32 v107, v110, v50
	v_fma_f32 v49, -v49, v107, v51
	v_div_fmas_f32 v49, v49, v50, v107
	v_div_fixup_f32 v48, v49, v48, 1.0
	v_bfe_u32 v49, v48, 16, 1
	v_add3_u32 v48, v48, v49, s79
	s_and_b64 vcc, exec, s[6:7]
	ds_write_b16_d16_hi v112, v48 offset:64
	v_mul_f32_e32 v48, 0xbfb8aa3b, v52
	v_exp_f32_e32 v48, v48
	s_nop 0
	v_add_f32_e32 v48, 1.0, v48
	v_div_scale_f32 v49, s[8:9], v48, v48, 1.0
	v_rcp_f32_e32 v50, v49
	v_div_scale_f32 v51, vcc, 1.0, v48, 1.0
	v_fma_f32 v52, -v49, v50, 1.0
	v_fmac_f32_e32 v50, v52, v50
	v_mul_f32_e32 v52, v51, v50
	v_fma_f32 v107, -v49, v52, v51
	v_fmac_f32_e32 v52, v107, v50
	v_fma_f32 v49, -v49, v52, v51
	v_div_fmas_f32 v49, v49, v50, v52
	v_div_fixup_f32 v48, v49, v48, 1.0
	v_bfe_u32 v49, v48, 16, 1
	v_add3_u32 v48, v48, v49, s79
	s_and_b64 vcc, exec, s[6:7]
	ds_write_b16_d16_hi v113, v48 offset:64
	v_mul_f32_e32 v48, 0xbfb8aa3b, v53
	v_exp_f32_e32 v48, v48
	s_nop 0
	v_add_f32_e32 v48, 1.0, v48
	v_div_scale_f32 v49, s[8:9], v48, v48, 1.0
	v_rcp_f32_e32 v50, v49
	v_div_scale_f32 v51, vcc, 1.0, v48, 1.0
	v_fma_f32 v52, -v49, v50, 1.0
	v_fmac_f32_e32 v50, v52, v50
	v_mul_f32_e32 v52, v51, v50
	v_fma_f32 v53, -v49, v52, v51
	v_fmac_f32_e32 v52, v53, v50
	v_fma_f32 v49, -v49, v52, v51
	v_div_fmas_f32 v49, v49, v50, v52
	v_div_fixup_f32 v48, v49, v48, 1.0
	v_bfe_u32 v49, v48, 16, 1
	v_add3_u32 v48, v48, v49, s79
	s_and_b64 vcc, exec, s[6:7]
	ds_write_b16_d16_hi v114, v48 offset:64
	v_mul_f32_e32 v48, 0xbfb8aa3b, v54
	v_exp_f32_e32 v48, v48
	s_nop 0
	v_add_f32_e32 v48, 1.0, v48
	v_div_scale_f32 v49, s[8:9], v48, v48, 1.0
	v_rcp_f32_e32 v50, v49
	v_div_scale_f32 v51, vcc, 1.0, v48, 1.0
	v_fma_f32 v52, -v49, v50, 1.0
	v_fmac_f32_e32 v50, v52, v50
	v_mul_f32_e32 v52, v51, v50
	v_fma_f32 v53, -v49, v52, v51
	v_fmac_f32_e32 v52, v53, v50
	v_fma_f32 v49, -v49, v52, v51
	v_div_fmas_f32 v49, v49, v50, v52
	v_div_fixup_f32 v48, v49, v48, 1.0
	v_bfe_u32 v49, v48, 16, 1
	v_add3_u32 v48, v48, v49, s79
	s_and_b64 vcc, exec, s[6:7]
	ds_write_b16_d16_hi v115, v48 offset:64
	v_mul_f32_e32 v48, 0xbfb8aa3b, v55
	v_exp_f32_e32 v48, v48
	s_nop 0
	v_add_f32_e32 v48, 1.0, v48
	v_div_scale_f32 v49, s[8:9], v48, v48, 1.0
	v_rcp_f32_e32 v50, v49
	v_div_scale_f32 v51, vcc, 1.0, v48, 1.0
	v_fma_f32 v52, -v49, v50, 1.0
	v_fmac_f32_e32 v50, v52, v50
	v_mul_f32_e32 v52, v51, v50
	v_fma_f32 v53, -v49, v52, v51
	v_fmac_f32_e32 v52, v53, v50
	v_fma_f32 v49, -v49, v52, v51
	v_div_fmas_f32 v49, v49, v50, v52
	v_div_fixup_f32 v48, v49, v48, 1.0
	v_bfe_u32 v49, v48, 16, 1
	v_add3_u32 v48, v48, v49, s79
; __device__ __forceinline__ bf16r f2bf(float f) {
;   unsigned u = __float_as_uint(f);
;   u += 0x7fffu + ((u >> 16) & 1u);
;   return (bf16r)(u >> 16);
; }
; __device__ __forceinline__ unsigned pack2(float a, float b) { return (unsigned)f2bf(a) | ((unsigned)f2bf(b) << 16); }
; __device__ __forceinline__ float lo16(unsigned v) { return __uint_as_float(v << 16); }
; __device__ __forceinline__ float hi16(unsigned v) { return __uint_as_float(v & 0xffff0000u); }
; __device__ __forceinline__ float siluf(float x) { return x / (1.f + __expf(-x)); }
; __device__ __forceinline__ float sigmf(float x) { return 1.f / (1.f + __expf(-x)); }
; __device__ __forceinline__ void inproj_epilogue(const Params& p, int layer, int mt, int ntile, int tid,
;                                                 f32x16 (&acc)[2][2], unsigned char* smem) {
;     ...
;     acc_foreach(tid, acc, [&](int row, int col, float v) {
;       int t = m0 + row;
;       float o = v;
;       if (mode == 1) o = (t >= NPADR) ? v : 0.f;
;       if (mode == 2) o = sigmf(v);
;       sT[row * 136 + col] = f2bf(o);
;     });
	s_and_b64 vcc, exec, s[6:7]
	ds_write_b16_d16_hi v117, v48 offset:64
	v_mul_f32_e32 v48, 0xbfb8aa3b, v56
	v_exp_f32_e32 v48, v48
	s_nop 0
	v_add_f32_e32 v48, 1.0, v48
	v_div_scale_f32 v49, s[8:9], v48, v48, 1.0
	v_rcp_f32_e32 v50, v49
	v_div_scale_f32 v51, vcc, 1.0, v48, 1.0
	v_fma_f32 v52, -v49, v50, 1.0
	v_fmac_f32_e32 v50, v52, v50
	v_mul_f32_e32 v52, v51, v50
	v_fma_f32 v53, -v49, v52, v51
	v_fmac_f32_e32 v52, v53, v50
	v_fma_f32 v49, -v49, v52, v51
	v_div_fmas_f32 v49, v49, v50, v52
	v_div_fixup_f32 v48, v49, v48, 1.0
	v_bfe_u32 v49, v48, 16, 1
	v_add3_u32 v48, v48, v49, s79
	s_and_b64 vcc, exec, s[6:7]
	ds_write_b16_d16_hi v118, v48 offset:64
	v_mul_f32_e32 v48, 0xbfb8aa3b, v57
	v_exp_f32_e32 v48, v48
	s_nop 0
	v_add_f32_e32 v48, 1.0, v48
	v_div_scale_f32 v49, s[8:9], v48, v48, 1.0
	v_rcp_f32_e32 v50, v49
	v_div_scale_f32 v51, vcc, 1.0, v48, 1.0
	v_fma_f32 v52, -v49, v50, 1.0
	v_fmac_f32_e32 v50, v52, v50
	v_mul_f32_e32 v52, v51, v50
	v_fma_f32 v53, -v49, v52, v51
	v_fmac_f32_e32 v52, v53, v50
	v_fma_f32 v49, -v49, v52, v51
	v_div_fmas_f32 v49, v49, v50, v52
	v_div_fixup_f32 v48, v49, v48, 1.0
	v_bfe_u32 v49, v48, 16, 1
	v_add3_u32 v48, v48, v49, s79
	s_and_b64 vcc, exec, s[6:7]
	ds_write_b16_d16_hi v119, v48 offset:64
	v_mul_f32_e32 v48, 0xbfb8aa3b, v58
	v_exp_f32_e32 v48, v48
	s_nop 0
	v_add_f32_e32 v48, 1.0, v48
	v_div_scale_f32 v49, s[8:9], v48, v48, 1.0
	v_rcp_f32_e32 v50, v49
	v_div_scale_f32 v51, vcc, 1.0, v48, 1.0
	v_fma_f32 v52, -v49, v50, 1.0
	v_fmac_f32_e32 v50, v52, v50
	v_mul_f32_e32 v52, v51, v50
	v_fma_f32 v53, -v49, v52, v51
	v_fmac_f32_e32 v52, v53, v50
	v_fma_f32 v49, -v49, v52, v51
	v_div_fmas_f32 v49, v49, v50, v52
	v_div_fixup_f32 v48, v49, v48, 1.0
	v_bfe_u32 v49, v48, 16, 1
	v_add3_u32 v48, v48, v49, s79
	s_and_b64 vcc, exec, s[6:7]
	ds_write_b16_d16_hi v120, v48 offset:64
	v_mul_f32_e32 v48, 0xbfb8aa3b, v59
	v_exp_f32_e32 v48, v48
	s_nop 0
	v_add_f32_e32 v48, 1.0, v48
	v_div_scale_f32 v49, s[8:9], v48, v48, 1.0
	v_rcp_f32_e32 v50, v49
	v_div_scale_f32 v51, vcc, 1.0, v48, 1.0
	v_fma_f32 v52, -v49, v50, 1.0
	v_fmac_f32_e32 v50, v52, v50
	v_mul_f32_e32 v52, v51, v50
	v_fma_f32 v53, -v49, v52, v51
	v_fmac_f32_e32 v52, v53, v50
	v_fma_f32 v49, -v49, v52, v51
	v_div_fmas_f32 v49, v49, v50, v52
	v_div_fixup_f32 v48, v49, v48, 1.0
	v_bfe_u32 v49, v48, 16, 1
	v_add3_u32 v48, v48, v49, s79
	s_and_b64 vcc, exec, s[6:7]
	ds_write_b16_d16_hi v121, v48 offset:64
	v_mul_f32_e32 v48, 0xbfb8aa3b, v60
	v_exp_f32_e32 v48, v48
	s_nop 0
	v_add_f32_e32 v48, 1.0, v48
	v_div_scale_f32 v49, s[8:9], v48, v48, 1.0
	v_rcp_f32_e32 v50, v49
	v_div_scale_f32 v51, vcc, 1.0, v48, 1.0
	v_fma_f32 v52, -v49, v50, 1.0
	v_fmac_f32_e32 v50, v52, v50
	v_mul_f32_e32 v52, v51, v50
	v_fma_f32 v53, -v49, v52, v51
	v_fmac_f32_e32 v52, v53, v50
	v_fma_f32 v49, -v49, v52, v51
	v_div_fmas_f32 v49, v49, v50, v52
	v_div_fixup_f32 v48, v49, v48, 1.0
	v_bfe_u32 v49, v48, 16, 1
	v_add3_u32 v48, v48, v49, s79
	s_and_b64 vcc, exec, s[6:7]
	ds_write_b16_d16_hi v122, v48 offset:64
	v_mul_f32_e32 v48, 0xbfb8aa3b, v61
	v_exp_f32_e32 v48, v48
	s_nop 0
	v_add_f32_e32 v48, 1.0, v48
	v_div_scale_f32 v49, s[8:9], v48, v48, 1.0
	v_rcp_f32_e32 v50, v49
	v_div_scale_f32 v51, vcc, 1.0, v48, 1.0
	v_fma_f32 v52, -v49, v50, 1.0
	v_fmac_f32_e32 v50, v52, v50
	v_mul_f32_e32 v52, v51, v50
	v_fma_f32 v53, -v49, v52, v51
	v_fmac_f32_e32 v52, v53, v50
	v_fma_f32 v49, -v49, v52, v51
	v_div_fmas_f32 v49, v49, v50, v52
	v_div_fixup_f32 v48, v49, v48, 1.0
	v_bfe_u32 v49, v48, 16, 1
	v_add3_u32 v48, v48, v49, s79
	s_and_b64 vcc, exec, s[6:7]
	ds_write_b16_d16_hi v123, v48 offset:64
	v_mul_f32_e32 v48, 0xbfb8aa3b, v62
	v_exp_f32_e32 v48, v48
	s_nop 0
	v_add_f32_e32 v48, 1.0, v48
	v_div_scale_f32 v49, s[8:9], v48, v48, 1.0
	v_rcp_f32_e32 v50, v49
	v_div_scale_f32 v51, vcc, 1.0, v48, 1.0
	v_fma_f32 v52, -v49, v50, 1.0
	v_fmac_f32_e32 v50, v52, v50
	v_mul_f32_e32 v52, v51, v50
	v_fma_f32 v53, -v49, v52, v51
	v_fmac_f32_e32 v52, v53, v50
	v_fma_f32 v49, -v49, v52, v51
	v_div_fmas_f32 v49, v49, v50, v52
	v_div_fixup_f32 v48, v49, v48, 1.0
	v_bfe_u32 v49, v48, 16, 1
	v_add3_u32 v48, v48, v49, s79
	s_and_b64 vcc, exec, s[6:7]
	ds_write_b16_d16_hi v116, v48 offset:64
	v_mul_f32_e32 v48, 0xbfb8aa3b, v63
	v_exp_f32_e32 v48, v48
	s_nop 0
	v_add_f32_e32 v48, 1.0, v48
	v_div_scale_f32 v49, s[8:9], v48, v48, 1.0
	v_rcp_f32_e32 v50, v49
	v_div_scale_f32 v51, vcc, 1.0, v48, 1.0
	v_fma_f32 v52, -v49, v50, 1.0
	v_fmac_f32_e32 v50, v52, v50
	v_mul_f32_e32 v52, v51, v50
	v_fma_f32 v53, -v49, v52, v51
	v_fmac_f32_e32 v52, v53, v50
	v_fma_f32 v49, -v49, v52, v51
	v_div_fmas_f32 v49, v49, v50, v52
	v_div_fixup_f32 v48, v49, v48, 1.0
	v_bfe_u32 v50, v48, 16, 1
	v_add_u32_e32 v49, 0x110, v116
	v_add3_u32 v48, v48, v50, s79
	ds_write_b16_d16_hi v49, v48 offset:64
	v_or_b32_e32 v48, 32, v96
	v_add_u32_e32 v49, s94, v48
	s_and_b64 vcc, exec, s[6:7]
	v_cmp_lt_i32_e64 s[8:9], s77, v49
	v_mul_f32_e32 v49, 0xbfb8aa3b, v0
	v_exp_f32_e32 v49, v49
	s_nop 0
	v_add_f32_e32 v49, 1.0, v49
	v_div_scale_f32 v50, s[10:11], v49, v49, 1.0
	v_rcp_f32_e32 v51, v50
	v_div_scale_f32 v52, vcc, 1.0, v49, 1.0
	v_fma_f32 v53, -v50, v51, 1.0
	v_fmac_f32_e32 v51, v53, v51
	v_mul_f32_e32 v53, v52, v51
	v_fma_f32 v54, -v50, v53, v52
	v_fmac_f32_e32 v53, v54, v51
	v_fma_f32 v50, -v50, v53, v52
	v_div_fmas_f32 v50, v50, v51, v53
	v_div_fixup_f32 v49, v50, v49, 1.0
	v_bfe_u32 v50, v49, 16, 1
	v_add3_u32 v50, v49, v50, s79
	v_mul_lo_u32 v49, v48, s80
	v_lshl_add_u32 v48, v106, 1, v49
	ds_write_b16_d16_hi v48, v50
	v_add3_u32 v50, s94, v96, 33
	s_and_b64 vcc, exec, s[6:7]
	v_cmp_lt_i32_e64 s[10:11], s77, v50
	v_mul_f32_e32 v50, 0xbfb8aa3b, v1
; __device__ __forceinline__ bf16r f2bf(float f) {
;   unsigned u = __float_as_uint(f);
;   u += 0x7fffu + ((u >> 16) & 1u);
;   return (bf16r)(u >> 16);
; }
; __device__ __forceinline__ unsigned pack2(float a, float b) { return (unsigned)f2bf(a) | ((unsigned)f2bf(b) << 16); }
; __device__ __forceinline__ float lo16(unsigned v) { return __uint_as_float(v << 16); }
; __device__ __forceinline__ float hi16(unsigned v) { return __uint_as_float(v & 0xffff0000u); }
; __device__ __forceinline__ float siluf(float x) { return x / (1.f + __expf(-x)); }
; __device__ __forceinline__ float sigmf(float x) { return 1.f / (1.f + __expf(-x)); }
; __device__ __forceinline__ void inproj_epilogue(const Params& p, int layer, int mt, int ntile, int tid,
;                                                 f32x16 (&acc)[2][2], unsigned char* smem) {
;     ...
;     acc_foreach(tid, acc, [&](int row, int col, float v) {
;       int t = m0 + row;
;       float o = v;
;       if (mode == 1) o = (t >= NPADR) ? v : 0.f;
;       if (mode == 2) o = sigmf(v);
;       sT[row * 136 + col] = f2bf(o);
;     });
	v_exp_f32_e32 v50, v50
	s_nop 0
	v_add_f32_e32 v50, 1.0, v50
	v_div_scale_f32 v51, s[12:13], v50, v50, 1.0
	v_rcp_f32_e32 v52, v51
	v_div_scale_f32 v53, vcc, 1.0, v50, 1.0
	v_fma_f32 v54, -v51, v52, 1.0
	v_fmac_f32_e32 v52, v54, v52
	v_mul_f32_e32 v54, v53, v52
	v_fma_f32 v55, -v51, v54, v53
	v_fmac_f32_e32 v54, v55, v52
	v_fma_f32 v51, -v51, v54, v53
	v_div_fmas_f32 v51, v51, v52, v54
	v_div_fixup_f32 v50, v51, v50, 1.0
	v_bfe_u32 v51, v50, 16, 1
	v_add3_u32 v51, v50, v51, s79
	v_add_u32_e32 v50, 0x110, v49
	v_lshl_add_u32 v49, v106, 1, v50
	ds_write_b16_d16_hi v49, v51
	v_add3_u32 v51, s94, v96, 34
	s_and_b64 vcc, exec, s[6:7]
	v_cmp_lt_i32_e64 s[12:13], s77, v51
	v_mul_f32_e32 v51, 0xbfb8aa3b, v2
	v_exp_f32_e32 v51, v51
	s_nop 0
	v_add_f32_e32 v51, 1.0, v51
	v_div_scale_f32 v52, s[14:15], v51, v51, 1.0
	v_rcp_f32_e32 v53, v52
	v_div_scale_f32 v54, vcc, 1.0, v51, 1.0
	v_fma_f32 v55, -v52, v53, 1.0
	v_fmac_f32_e32 v53, v55, v53
	v_mul_f32_e32 v55, v54, v53
	v_fma_f32 v56, -v52, v55, v54
	v_fmac_f32_e32 v55, v56, v53
	v_fma_f32 v52, -v52, v55, v54
	v_div_fmas_f32 v52, v52, v53, v55
	v_div_fixup_f32 v51, v52, v51, 1.0
	v_bfe_u32 v52, v51, 16, 1
	v_add3_u32 v52, v51, v52, s79
	v_add_u32_e32 v51, 0x110, v50
	v_lshl_add_u32 v50, v106, 1, v51
	ds_write_b16_d16_hi v50, v52
	v_add3_u32 v52, s94, v96, 35
	s_and_b64 vcc, exec, s[6:7]
	v_cmp_lt_i32_e64 s[14:15], s77, v52
	v_mul_f32_e32 v52, 0xbfb8aa3b, v3
	v_exp_f32_e32 v52, v52
	s_nop 0
	v_add_f32_e32 v52, 1.0, v52
	v_div_scale_f32 v53, s[16:17], v52, v52, 1.0
	v_rcp_f32_e32 v54, v53
	v_div_scale_f32 v55, vcc, 1.0, v52, 1.0
	v_fma_f32 v56, -v53, v54, 1.0
	v_fmac_f32_e32 v54, v56, v54
	v_mul_f32_e32 v56, v55, v54
	v_fma_f32 v57, -v53, v56, v55
	v_fmac_f32_e32 v56, v57, v54
	v_fma_f32 v53, -v53, v56, v55
	v_div_fmas_f32 v53, v53, v54, v56
	v_div_fixup_f32 v52, v53, v52, 1.0
	v_bfe_u32 v53, v52, 16, 1
	v_add3_u32 v53, v52, v53, s79
	v_add_u32_e32 v52, 0x110, v51
	v_lshl_add_u32 v51, v106, 1, v52
	ds_write_b16_d16_hi v51, v53
	v_add3_u32 v53, s94, v96, 40
	s_and_b64 vcc, exec, s[6:7]
	v_cmp_lt_i32_e64 s[16:17], s77, v53
	v_mul_f32_e32 v53, 0xbfb8aa3b, v4
	v_exp_f32_e32 v53, v53
	s_nop 0
	v_add_f32_e32 v53, 1.0, v53
	v_div_scale_f32 v54, s[18:19], v53, v53, 1.0
	v_rcp_f32_e32 v55, v54
	v_div_scale_f32 v56, vcc, 1.0, v53, 1.0
	v_fma_f32 v57, -v54, v55, 1.0
	v_fmac_f32_e32 v55, v57, v55
	v_mul_f32_e32 v57, v56, v55
	v_fma_f32 v58, -v54, v57, v56
	v_fmac_f32_e32 v57, v58, v55
	v_fma_f32 v54, -v54, v57, v56
	v_div_fmas_f32 v54, v54, v55, v57
	v_div_fixup_f32 v53, v54, v53, 1.0
	v_bfe_u32 v54, v53, 16, 1
	v_add3_u32 v54, v53, v54, s79
	v_add_u32_e32 v53, 0x550, v52
	v_lshl_add_u32 v52, v106, 1, v53
	ds_write_b16_d16_hi v52, v54
	v_add3_u32 v54, s94, v96, 41
	s_and_b64 vcc, exec, s[6:7]
	v_cmp_lt_i32_e64 s[18:19], s77, v54
	v_mul_f32_e32 v54, 0xbfb8aa3b, v5
	v_exp_f32_e32 v54, v54
	s_nop 0
	v_add_f32_e32 v54, 1.0, v54
	v_div_scale_f32 v55, s[20:21], v54, v54, 1.0
	v_rcp_f32_e32 v56, v55
	v_div_scale_f32 v57, vcc, 1.0, v54, 1.0
	v_fma_f32 v58, -v55, v56, 1.0
	v_fmac_f32_e32 v56, v58, v56
	v_mul_f32_e32 v58, v57, v56
	v_fma_f32 v59, -v55, v58, v57
	v_fmac_f32_e32 v58, v59, v56
	v_fma_f32 v55, -v55, v58, v57
	v_div_fmas_f32 v55, v55, v56, v58
	v_div_fixup_f32 v54, v55, v54, 1.0
	v_bfe_u32 v55, v54, 16, 1
	v_add3_u32 v55, v54, v55, s79
	v_add_u32_e32 v54, 0x110, v53
	v_lshl_add_u32 v53, v106, 1, v54
	ds_write_b16_d16_hi v53, v55
	v_add3_u32 v55, s94, v96, 42
	s_and_b64 vcc, exec, s[6:7]
	v_cmp_lt_i32_e64 s[20:21], s77, v55
	v_mul_f32_e32 v55, 0xbfb8aa3b, v6
	v_exp_f32_e32 v55, v55
	s_nop 0
	v_add_f32_e32 v55, 1.0, v55
	v_div_scale_f32 v56, s[22:23], v55, v55, 1.0
	v_rcp_f32_e32 v57, v56
	v_div_scale_f32 v58, vcc, 1.0, v55, 1.0
	v_fma_f32 v59, -v56, v57, 1.0
	v_fmac_f32_e32 v57, v59, v57
	v_mul_f32_e32 v59, v58, v57
	v_fma_f32 v60, -v56, v59, v58
	v_fmac_f32_e32 v59, v60, v57
	v_fma_f32 v56, -v56, v59, v58
	v_div_fmas_f32 v56, v56, v57, v59
	v_div_fixup_f32 v55, v56, v55, 1.0
	v_bfe_u32 v56, v55, 16, 1
	v_add3_u32 v56, v55, v56, s79
	v_add_u32_e32 v55, 0x110, v54
	v_lshl_add_u32 v54, v106, 1, v55
	ds_write_b16_d16_hi v54, v56
	v_add3_u32 v56, s94, v96, 43
	s_and_b64 vcc, exec, s[6:7]
	v_cmp_lt_i32_e64 s[22:23], s77, v56
	v_mul_f32_e32 v56, 0xbfb8aa3b, v7
	v_exp_f32_e32 v56, v56
	s_nop 0
	v_add_f32_e32 v56, 1.0, v56
	v_div_scale_f32 v57, s[24:25], v56, v56, 1.0
	v_rcp_f32_e32 v58, v57
	v_div_scale_f32 v59, vcc, 1.0, v56, 1.0
	v_fma_f32 v60, -v57, v58, 1.0
	v_fmac_f32_e32 v58, v60, v58
	v_mul_f32_e32 v60, v59, v58
	v_fma_f32 v61, -v57, v60, v59
	v_fmac_f32_e32 v60, v61, v58
	v_fma_f32 v57, -v57, v60, v59
	v_div_fmas_f32 v57, v57, v58, v60
	v_div_fixup_f32 v56, v57, v56, 1.0
	v_bfe_u32 v57, v56, 16, 1
	v_add_u32_e32 v55, 0x110, v55
	v_add3_u32 v57, v56, v57, s79
	v_lshl_add_u32 v56, v106, 1, v55
	ds_write_b16_d16_hi v56, v57
	v_add3_u32 v57, s94, v96, 48
	s_and_b64 vcc, exec, s[6:7]
	v_cmp_lt_i32_e64 s[24:25], s77, v57
	v_mul_f32_e32 v57, 0xbfb8aa3b, v8
	v_exp_f32_e32 v57, v57
	s_nop 0
	v_add_f32_e32 v57, 1.0, v57
	v_div_scale_f32 v58, s[26:27], v57, v57, 1.0
	v_rcp_f32_e32 v59, v58
	v_div_scale_f32 v60, vcc, 1.0, v57, 1.0
	v_fma_f32 v61, -v58, v59, 1.0
	v_fmac_f32_e32 v59, v61, v59
	v_mul_f32_e32 v61, v60, v59
	v_fma_f32 v62, -v58, v61, v60
	v_fmac_f32_e32 v61, v62, v59
	v_fma_f32 v58, -v58, v61, v60
	v_div_fmas_f32 v58, v58, v59, v61
	v_div_fixup_f32 v57, v58, v57, 1.0
	v_bfe_u32 v58, v57, 16, 1
	v_add_u32_e32 v55, 0x550, v55
	v_add3_u32 v58, v57, v58, s79
	v_lshl_add_u32 v57, v106, 1, v55
	ds_write_b16_d16_hi v57, v58
	v_add3_u32 v58, s94, v96, 49
	s_and_b64 vcc, exec, s[6:7]
	v_cmp_lt_i32_e64 s[26:27], s77, v58
; __device__ __forceinline__ bf16r f2bf(float f) {
;   unsigned u = __float_as_uint(f);
;   u += 0x7fffu + ((u >> 16) & 1u);
;   return (bf16r)(u >> 16);
; }
; __device__ __forceinline__ unsigned pack2(float a, float b) { return (unsigned)f2bf(a) | ((unsigned)f2bf(b) << 16); }
; __device__ __forceinline__ float lo16(unsigned v) { return __uint_as_float(v << 16); }
; __device__ __forceinline__ float hi16(unsigned v) { return __uint_as_float(v & 0xffff0000u); }
; __device__ __forceinline__ float siluf(float x) { return x / (1.f + __expf(-x)); }
; __device__ __forceinline__ float sigmf(float x) { return 1.f / (1.f + __expf(-x)); }
; __device__ __forceinline__ void inproj_epilogue(const Params& p, int layer, int mt, int ntile, int tid,
;                                                 f32x16 (&acc)[2][2], unsigned char* smem) {
;     ...
;     acc_foreach(tid, acc, [&](int row, int col, float v) {
;       int t = m0 + row;
;       float o = v;
;       if (mode == 1) o = (t >= NPADR) ? v : 0.f;
;       if (mode == 2) o = sigmf(v);
;       sT[row * 136 + col] = f2bf(o);
;     });
	v_mul_f32_e32 v58, 0xbfb8aa3b, v9
	v_exp_f32_e32 v58, v58
	s_nop 0
	v_add_f32_e32 v58, 1.0, v58
	v_div_scale_f32 v59, s[28:29], v58, v58, 1.0
	v_rcp_f32_e32 v60, v59
	v_div_scale_f32 v61, vcc, 1.0, v58, 1.0
	v_fma_f32 v62, -v59, v60, 1.0
	v_fmac_f32_e32 v60, v62, v60
	v_mul_f32_e32 v62, v61, v60
	v_fma_f32 v63, -v59, v62, v61
	v_fmac_f32_e32 v62, v63, v60
	v_fma_f32 v59, -v59, v62, v61
	v_div_fmas_f32 v59, v59, v60, v62
	v_div_fixup_f32 v58, v59, v58, 1.0
	v_bfe_u32 v59, v58, 16, 1
	v_add_u32_e32 v55, 0x110, v55
	v_add3_u32 v59, v58, v59, s79
	v_lshl_add_u32 v58, v106, 1, v55
	ds_write_b16_d16_hi v58, v59
	v_add3_u32 v59, s94, v96, 50
	s_and_b64 vcc, exec, s[6:7]
	v_cmp_lt_i32_e64 s[28:29], s77, v59
	v_mul_f32_e32 v59, 0xbfb8aa3b, v10
	v_exp_f32_e32 v59, v59
	s_nop 0
	v_add_f32_e32 v59, 1.0, v59
	v_div_scale_f32 v60, s[30:31], v59, v59, 1.0
	v_rcp_f32_e32 v61, v60
	v_div_scale_f32 v62, vcc, 1.0, v59, 1.0
	v_fma_f32 v63, -v60, v61, 1.0
	v_fmac_f32_e32 v61, v63, v61
	v_mul_f32_e32 v63, v62, v61
	v_fma_f32 v107, -v60, v63, v62
	v_fmac_f32_e32 v63, v107, v61
	v_fma_f32 v60, -v60, v63, v62
	v_div_fmas_f32 v60, v60, v61, v63
	v_div_fixup_f32 v59, v60, v59, 1.0
	v_bfe_u32 v60, v59, 16, 1
	v_add_u32_e32 v55, 0x110, v55
	v_add3_u32 v60, v59, v60, s79
	v_lshl_add_u32 v59, v106, 1, v55
	ds_write_b16_d16_hi v59, v60
	v_add3_u32 v60, s94, v96, 51
	s_and_b64 vcc, exec, s[6:7]
	v_cmp_lt_i32_e64 s[30:31], s77, v60
	v_mul_f32_e32 v60, 0xbfb8aa3b, v11
	v_exp_f32_e32 v60, v60
	s_nop 0
	v_add_f32_e32 v60, 1.0, v60
	v_div_scale_f32 v61, s[34:35], v60, v60, 1.0
	v_rcp_f32_e32 v62, v61
	v_div_scale_f32 v63, vcc, 1.0, v60, 1.0
	v_fma_f32 v107, -v61, v62, 1.0
	v_fmac_f32_e32 v62, v107, v62
	v_mul_f32_e32 v107, v63, v62
	v_fma_f32 v110, -v61, v107, v63
	v_fmac_f32_e32 v107, v110, v62
	v_fma_f32 v61, -v61, v107, v63
	v_div_fmas_f32 v61, v61, v62, v107
	v_div_fixup_f32 v60, v61, v60, 1.0
	v_bfe_u32 v61, v60, 16, 1
	v_add_u32_e32 v55, 0x110, v55
	v_add3_u32 v61, v60, v61, s79
	v_lshl_add_u32 v60, v106, 1, v55
	ds_write_b16_d16_hi v60, v61
	v_add3_u32 v61, s94, v96, 56
	s_and_b64 vcc, exec, s[6:7]
	v_cmp_lt_i32_e64 s[34:35], s77, v61
	v_mul_f32_e32 v61, 0xbfb8aa3b, v12
	v_exp_f32_e32 v61, v61
	s_nop 0
	v_add_f32_e32 v61, 1.0, v61
	v_div_scale_f32 v62, s[36:37], v61, v61, 1.0
	v_rcp_f32_e32 v63, v62
	v_div_scale_f32 v107, vcc, 1.0, v61, 1.0
	v_fma_f32 v110, -v62, v63, 1.0
	v_fmac_f32_e32 v63, v110, v63
	v_mul_f32_e32 v110, v107, v63
	v_fma_f32 v111, -v62, v110, v107
	v_fmac_f32_e32 v110, v111, v63
	v_fma_f32 v62, -v62, v110, v107
	v_div_fmas_f32 v62, v62, v63, v110
	v_div_fixup_f32 v61, v62, v61, 1.0
	v_bfe_u32 v62, v61, 16, 1
	v_add_u32_e32 v55, 0x550, v55
	v_add3_u32 v62, v61, v62, s79
	v_lshl_add_u32 v61, v106, 1, v55
	ds_write_b16_d16_hi v61, v62
	v_add3_u32 v62, s94, v96, 57
	s_and_b64 vcc, exec, s[6:7]
	v_cmp_lt_i32_e64 s[36:37], s77, v62
	v_mul_f32_e32 v62, 0xbfb8aa3b, v13
	v_exp_f32_e32 v62, v62
	s_nop 0
	v_add_f32_e32 v62, 1.0, v62
	v_div_scale_f32 v63, s[38:39], v62, v62, 1.0
	v_rcp_f32_e32 v107, v63
	v_div_scale_f32 v110, vcc, 1.0, v62, 1.0
	v_fma_f32 v111, -v63, v107, 1.0
	v_fmac_f32_e32 v107, v111, v107
	v_mul_f32_e32 v111, v110, v107
	v_fma_f32 v112, -v63, v111, v110
	v_fmac_f32_e32 v111, v112, v107
	v_fma_f32 v63, -v63, v111, v110
	v_div_fmas_f32 v63, v63, v107, v111
	v_div_fixup_f32 v62, v63, v62, 1.0
	v_bfe_u32 v63, v62, 16, 1
	v_add_u32_e32 v55, 0x110, v55
	v_add3_u32 v63, v62, v63, s79
	v_lshl_add_u32 v62, v106, 1, v55
	ds_write_b16_d16_hi v62, v63
	v_add3_u32 v63, s94, v96, 58
	s_and_b64 vcc, exec, s[6:7]
	v_cmp_lt_i32_e64 s[38:39], s77, v63
	v_mul_f32_e32 v63, 0xbfb8aa3b, v14
	v_exp_f32_e32 v63, v63
	s_nop 0
	v_add_f32_e32 v63, 1.0, v63
	v_div_scale_f32 v107, s[40:41], v63, v63, 1.0
	v_rcp_f32_e32 v110, v107
	v_div_scale_f32 v111, vcc, 1.0, v63, 1.0
	v_fma_f32 v112, -v107, v110, 1.0
	v_fmac_f32_e32 v110, v112, v110
	v_mul_f32_e32 v112, v111, v110
	v_fma_f32 v113, -v107, v112, v111
	v_fmac_f32_e32 v112, v113, v110
	v_fma_f32 v107, -v107, v112, v111
	v_div_fmas_f32 v107, v107, v110, v112
	v_div_fixup_f32 v63, v107, v63, 1.0
	v_bfe_u32 v107, v63, 16, 1
	v_add_u32_e32 v55, 0x110, v55
	v_add3_u32 v63, v63, v107, s79
	v_lshl_add_u32 v55, v106, 1, v55
	ds_write_b16_d16_hi v55, v63
	v_add3_u32 v63, s94, v96, 59
	s_and_b64 vcc, exec, s[6:7]
	v_cmp_lt_i32_e64 s[40:41], s77, v63
	v_mul_f32_e32 v63, 0xbfb8aa3b, v15
	v_exp_f32_e32 v63, v63
	s_nop 0
	v_add_f32_e32 v63, 1.0, v63
	v_div_scale_f32 v96, vcc, v63, v63, 1.0
	v_rcp_f32_e32 v106, v96
	v_div_scale_f32 v107, vcc, 1.0, v63, 1.0
	v_fma_f32 v110, -v96, v106, 1.0
	v_fmac_f32_e32 v106, v110, v106
	v_mul_f32_e32 v110, v107, v106
	v_fma_f32 v111, -v96, v110, v107
	v_fmac_f32_e32 v110, v111, v106
	v_fma_f32 v96, -v96, v110, v107
	v_div_fmas_f32 v96, v96, v106, v110
	v_div_fixup_f32 v63, v96, v63, 1.0
	v_bfe_u32 v96, v63, 16, 1
	v_add3_u32 v63, v63, v96, s79
	ds_write_b16_d16_hi v55, v63 offset:272
	s_and_b64 vcc, exec, s[6:7]
	v_mul_f32_e32 v32, 0xbfb8aa3b, v32
	v_exp_f32_e32 v32, v32
	s_nop 0
	v_add_f32_e32 v32, 1.0, v32
	v_div_scale_f32 v63, s[8:9], v32, v32, 1.0
	v_rcp_f32_e32 v96, v63
	v_div_scale_f32 v106, vcc, 1.0, v32, 1.0
	v_fma_f32 v107, -v63, v96, 1.0
	v_fmac_f32_e32 v96, v107, v96
	v_mul_f32_e32 v107, v106, v96
	v_fma_f32 v110, -v63, v107, v106
	v_fmac_f32_e32 v107, v110, v96
	v_fma_f32 v63, -v63, v107, v106
	v_div_fmas_f32 v63, v63, v96, v107
	v_div_fixup_f32 v32, v63, v32, 1.0
	v_bfe_u32 v63, v32, 16, 1
	v_add3_u32 v32, v32, v63, s79
	s_and_b64 vcc, exec, s[6:7]
	ds_write_b16_d16_hi v48, v32 offset:64
	v_mul_f32_e32 v32, 0xbfb8aa3b, v33
	v_exp_f32_e32 v32, v32
	s_nop 0
	v_add_f32_e32 v32, 1.0, v32
; __device__ __forceinline__ bf16r f2bf(float f) {
;   unsigned u = __float_as_uint(f);
;   u += 0x7fffu + ((u >> 16) & 1u);
;   return (bf16r)(u >> 16);
; }
; __device__ __forceinline__ unsigned pack2(float a, float b) { return (unsigned)f2bf(a) | ((unsigned)f2bf(b) << 16); }
; __device__ __forceinline__ float lo16(unsigned v) { return __uint_as_float(v << 16); }
; __device__ __forceinline__ float hi16(unsigned v) { return __uint_as_float(v & 0xffff0000u); }
; __device__ __forceinline__ float siluf(float x) { return x / (1.f + __expf(-x)); }
; __device__ __forceinline__ float sigmf(float x) { return 1.f / (1.f + __expf(-x)); }
; __device__ __forceinline__ void inproj_epilogue(const Params& p, int layer, int mt, int ntile, int tid,
;                                                 f32x16 (&acc)[2][2], unsigned char* smem) {
;     ...
;     acc_foreach(tid, acc, [&](int row, int col, float v) {
;       int t = m0 + row;
;       float o = v;
;       if (mode == 1) o = (t >= NPADR) ? v : 0.f;
;       if (mode == 2) o = sigmf(v);
;       sT[row * 136 + col] = f2bf(o);
;     });
	v_div_scale_f32 v33, s[8:9], v32, v32, 1.0
	v_rcp_f32_e32 v48, v33
	v_div_scale_f32 v63, vcc, 1.0, v32, 1.0
	v_fma_f32 v96, -v33, v48, 1.0
	v_fmac_f32_e32 v48, v96, v48
	v_mul_f32_e32 v96, v63, v48
	v_fma_f32 v106, -v33, v96, v63
	v_fmac_f32_e32 v96, v106, v48
	v_fma_f32 v33, -v33, v96, v63
	v_div_fmas_f32 v33, v33, v48, v96
	v_div_fixup_f32 v32, v33, v32, 1.0
	v_bfe_u32 v33, v32, 16, 1
	v_add3_u32 v32, v32, v33, s79
	s_and_b64 vcc, exec, s[6:7]
	ds_write_b16_d16_hi v49, v32 offset:64
	v_mul_f32_e32 v32, 0xbfb8aa3b, v34
	v_exp_f32_e32 v32, v32
	s_nop 0
	v_add_f32_e32 v32, 1.0, v32
	v_div_scale_f32 v33, s[8:9], v32, v32, 1.0
	v_rcp_f32_e32 v34, v33
	v_div_scale_f32 v48, vcc, 1.0, v32, 1.0
	v_fma_f32 v49, -v33, v34, 1.0
	v_fmac_f32_e32 v34, v49, v34
	v_mul_f32_e32 v49, v48, v34
	v_fma_f32 v63, -v33, v49, v48
	v_fmac_f32_e32 v49, v63, v34
	v_fma_f32 v33, -v33, v49, v48
	v_div_fmas_f32 v33, v33, v34, v49
	v_div_fixup_f32 v32, v33, v32, 1.0
	v_bfe_u32 v33, v32, 16, 1
	v_add3_u32 v32, v32, v33, s79
	s_and_b64 vcc, exec, s[6:7]
	ds_write_b16_d16_hi v50, v32 offset:64
	v_mul_f32_e32 v32, 0xbfb8aa3b, v35
	v_exp_f32_e32 v32, v32
	s_nop 0
	v_add_f32_e32 v32, 1.0, v32
	v_div_scale_f32 v33, s[8:9], v32, v32, 1.0
	v_rcp_f32_e32 v34, v33
	v_div_scale_f32 v35, vcc, 1.0, v32, 1.0
	v_fma_f32 v48, -v33, v34, 1.0
	v_fmac_f32_e32 v34, v48, v34
	v_mul_f32_e32 v48, v35, v34
	v_fma_f32 v49, -v33, v48, v35
	v_fmac_f32_e32 v48, v49, v34
	v_fma_f32 v33, -v33, v48, v35
	v_div_fmas_f32 v33, v33, v34, v48
	v_div_fixup_f32 v32, v33, v32, 1.0
	v_bfe_u32 v33, v32, 16, 1
	v_add3_u32 v32, v32, v33, s79
	s_and_b64 vcc, exec, s[6:7]
	ds_write_b16_d16_hi v51, v32 offset:64
	v_mul_f32_e32 v32, 0xbfb8aa3b, v36
	v_exp_f32_e32 v32, v32
	s_nop 0
	v_add_f32_e32 v32, 1.0, v32
	v_div_scale_f32 v33, s[8:9], v32, v32, 1.0
	v_rcp_f32_e32 v34, v33
	v_div_scale_f32 v35, vcc, 1.0, v32, 1.0
	v_fma_f32 v36, -v33, v34, 1.0
	v_fmac_f32_e32 v34, v36, v34
	v_mul_f32_e32 v36, v35, v34
	v_fma_f32 v48, -v33, v36, v35
	v_fmac_f32_e32 v36, v48, v34
	v_fma_f32 v33, -v33, v36, v35
	v_div_fmas_f32 v33, v33, v34, v36
	v_div_fixup_f32 v32, v33, v32, 1.0
	v_bfe_u32 v33, v32, 16, 1
	v_add3_u32 v32, v32, v33, s79
	s_and_b64 vcc, exec, s[6:7]
	ds_write_b16_d16_hi v52, v32 offset:64
	v_mul_f32_e32 v32, 0xbfb8aa3b, v37
	v_exp_f32_e32 v32, v32
	s_nop 0
	v_add_f32_e32 v32, 1.0, v32
	v_div_scale_f32 v33, s[8:9], v32, v32, 1.0
	v_rcp_f32_e32 v34, v33
	v_div_scale_f32 v35, vcc, 1.0, v32, 1.0
	v_fma_f32 v36, -v33, v34, 1.0
	v_fmac_f32_e32 v34, v36, v34
	v_mul_f32_e32 v36, v35, v34
	v_fma_f32 v37, -v33, v36, v35
	v_fmac_f32_e32 v36, v37, v34
	v_fma_f32 v33, -v33, v36, v35
	v_div_fmas_f32 v33, v33, v34, v36
	v_div_fixup_f32 v32, v33, v32, 1.0
	v_bfe_u32 v33, v32, 16, 1
	v_add3_u32 v32, v32, v33, s79
	s_and_b64 vcc, exec, s[6:7]
	ds_write_b16_d16_hi v53, v32 offset:64
	v_mul_f32_e32 v32, 0xbfb8aa3b, v38
	v_exp_f32_e32 v32, v32
	s_nop 0
	v_add_f32_e32 v32, 1.0, v32
	v_div_scale_f32 v33, s[8:9], v32, v32, 1.0
	v_rcp_f32_e32 v34, v33
	v_div_scale_f32 v35, vcc, 1.0, v32, 1.0
	v_fma_f32 v36, -v33, v34, 1.0
	v_fmac_f32_e32 v34, v36, v34
	v_mul_f32_e32 v36, v35, v34
	v_fma_f32 v37, -v33, v36, v35
	v_fmac_f32_e32 v36, v37, v34
	v_fma_f32 v33, -v33, v36, v35
	v_div_fmas_f32 v33, v33, v34, v36
	v_div_fixup_f32 v32, v33, v32, 1.0
	v_bfe_u32 v33, v32, 16, 1
	v_add3_u32 v32, v32, v33, s79
	s_and_b64 vcc, exec, s[6:7]
	ds_write_b16_d16_hi v54, v32 offset:64
	v_mul_f32_e32 v32, 0xbfb8aa3b, v39
	v_exp_f32_e32 v32, v32
	s_nop 0
	v_add_f32_e32 v32, 1.0, v32
	v_div_scale_f32 v33, s[8:9], v32, v32, 1.0
	v_rcp_f32_e32 v34, v33
	v_div_scale_f32 v35, vcc, 1.0, v32, 1.0
	v_fma_f32 v36, -v33, v34, 1.0
	v_fmac_f32_e32 v34, v36, v34
	v_mul_f32_e32 v36, v35, v34
	v_fma_f32 v37, -v33, v36, v35
	v_fmac_f32_e32 v36, v37, v34
	v_fma_f32 v33, -v33, v36, v35
	v_div_fmas_f32 v33, v33, v34, v36
	v_div_fixup_f32 v32, v33, v32, 1.0
	v_bfe_u32 v33, v32, 16, 1
	v_add3_u32 v32, v32, v33, s79
	s_and_b64 vcc, exec, s[6:7]
	ds_write_b16_d16_hi v56, v32 offset:64
	v_mul_f32_e32 v32, 0xbfb8aa3b, v40
	v_exp_f32_e32 v32, v32
	s_nop 0
	v_add_f32_e32 v32, 1.0, v32
	v_div_scale_f32 v33, s[8:9], v32, v32, 1.0
	v_rcp_f32_e32 v34, v33
	v_div_scale_f32 v35, vcc, 1.0, v32, 1.0
	v_fma_f32 v36, -v33, v34, 1.0
	v_fmac_f32_e32 v34, v36, v34
	v_mul_f32_e32 v36, v35, v34
; __device__ __forceinline__ bf16r f2bf(float f) {
;   unsigned u = __float_as_uint(f);
;   u += 0x7fffu + ((u >> 16) & 1u);
;   return (bf16r)(u >> 16);
; }
; __device__ __forceinline__ unsigned pack2(float a, float b) { return (unsigned)f2bf(a) | ((unsigned)f2bf(b) << 16); }
; __device__ __forceinline__ float lo16(unsigned v) { return __uint_as_float(v << 16); }
; __device__ __forceinline__ float hi16(unsigned v) { return __uint_as_float(v & 0xffff0000u); }
; __device__ __forceinline__ float siluf(float x) { return x / (1.f + __expf(-x)); }
; __device__ __forceinline__ float sigmf(float x) { return 1.f / (1.f + __expf(-x)); }
; __device__ __forceinline__ void inproj_epilogue(const Params& p, int layer, int mt, int ntile, int tid,
;                                                 f32x16 (&acc)[2][2], unsigned char* smem) {
;     ...
;     acc_foreach(tid, acc, [&](int row, int col, float v) {
;       int t = m0 + row;
;       float o = v;
;       if (mode == 1) o = (t >= NPADR) ? v : 0.f;
;       if (mode == 2) o = sigmf(v);
;       sT[row * 136 + col] = f2bf(o);
;     });
	v_fma_f32 v37, -v33, v36, v35
	v_fmac_f32_e32 v36, v37, v34
	v_fma_f32 v33, -v33, v36, v35
	v_div_fmas_f32 v33, v33, v34, v36
	v_div_fixup_f32 v32, v33, v32, 1.0
	v_bfe_u32 v33, v32, 16, 1
	v_add3_u32 v32, v32, v33, s79
	s_and_b64 vcc, exec, s[6:7]
	ds_write_b16_d16_hi v57, v32 offset:64
	v_mul_f32_e32 v32, 0xbfb8aa3b, v41
	v_exp_f32_e32 v32, v32
	s_nop 0
	v_add_f32_e32 v32, 1.0, v32
	v_div_scale_f32 v33, s[8:9], v32, v32, 1.0
	v_rcp_f32_e32 v34, v33
	v_div_scale_f32 v35, vcc, 1.0, v32, 1.0
	v_fma_f32 v36, -v33, v34, 1.0
	v_fmac_f32_e32 v34, v36, v34
	v_mul_f32_e32 v36, v35, v34
	v_fma_f32 v37, -v33, v36, v35
	v_fmac_f32_e32 v36, v37, v34
	v_fma_f32 v33, -v33, v36, v35
	v_div_fmas_f32 v33, v33, v34, v36
	v_div_fixup_f32 v32, v33, v32, 1.0
	v_bfe_u32 v33, v32, 16, 1
	v_add3_u32 v32, v32, v33, s79
	s_and_b64 vcc, exec, s[6:7]
	ds_write_b16_d16_hi v58, v32 offset:64
	v_mul_f32_e32 v32, 0xbfb8aa3b, v42
	v_exp_f32_e32 v32, v32
	s_nop 0
	v_add_f32_e32 v32, 1.0, v32
	v_div_scale_f32 v33, s[8:9], v32, v32, 1.0
	v_rcp_f32_e32 v34, v33
	v_div_scale_f32 v35, vcc, 1.0, v32, 1.0
	v_fma_f32 v36, -v33, v34, 1.0
	v_fmac_f32_e32 v34, v36, v34
	v_mul_f32_e32 v36, v35, v34
	v_fma_f32 v37, -v33, v36, v35
	v_fmac_f32_e32 v36, v37, v34
	v_fma_f32 v33, -v33, v36, v35
	v_div_fmas_f32 v33, v33, v34, v36
	v_div_fixup_f32 v32, v33, v32, 1.0
	v_bfe_u32 v33, v32, 16, 1
	v_add3_u32 v32, v32, v33, s79
	s_and_b64 vcc, exec, s[6:7]
	ds_write_b16_d16_hi v59, v32 offset:64
	v_mul_f32_e32 v32, 0xbfb8aa3b, v43
	v_exp_f32_e32 v32, v32
	s_nop 0
	v_add_f32_e32 v32, 1.0, v32
	v_div_scale_f32 v33, s[8:9], v32, v32, 1.0
	v_rcp_f32_e32 v34, v33
	v_div_scale_f32 v35, vcc, 1.0, v32, 1.0
	v_fma_f32 v36, -v33, v34, 1.0
	v_fmac_f32_e32 v34, v36, v34
	v_mul_f32_e32 v36, v35, v34
	v_fma_f32 v37, -v33, v36, v35
	v_fmac_f32_e32 v36, v37, v34
	v_fma_f32 v33, -v33, v36, v35
	v_div_fmas_f32 v33, v33, v34, v36
	v_div_fixup_f32 v32, v33, v32, 1.0
	v_bfe_u32 v33, v32, 16, 1
	v_add3_u32 v32, v32, v33, s79
	s_and_b64 vcc, exec, s[6:7]
	ds_write_b16_d16_hi v60, v32 offset:64
	v_mul_f32_e32 v32, 0xbfb8aa3b, v44
	v_exp_f32_e32 v32, v32
	s_nop 0
	v_add_f32_e32 v32, 1.0, v32
	v_div_scale_f32 v33, s[8:9], v32, v32, 1.0
	v_rcp_f32_e32 v34, v33
	v_div_scale_f32 v35, vcc, 1.0, v32, 1.0
	v_fma_f32 v36, -v33, v34, 1.0
	v_fmac_f32_e32 v34, v36, v34
	v_mul_f32_e32 v36, v35, v34
	v_fma_f32 v37, -v33, v36, v35
	v_fmac_f32_e32 v36, v37, v34
	v_fma_f32 v33, -v33, v36, v35
	v_div_fmas_f32 v33, v33, v34, v36
	v_div_fixup_f32 v32, v33, v32, 1.0
	v_bfe_u32 v33, v32, 16, 1
	v_add3_u32 v32, v32, v33, s79
	s_and_b64 vcc, exec, s[6:7]
	ds_write_b16_d16_hi v61, v32 offset:64
	v_mul_f32_e32 v32, 0xbfb8aa3b, v45
	v_exp_f32_e32 v32, v32
	s_nop 0
	v_add_f32_e32 v32, 1.0, v32
	v_div_scale_f32 v33, s[8:9], v32, v32, 1.0
	v_rcp_f32_e32 v34, v33
	v_div_scale_f32 v35, vcc, 1.0, v32, 1.0
	v_fma_f32 v36, -v33, v34, 1.0
	v_fmac_f32_e32 v34, v36, v34
	v_mul_f32_e32 v36, v35, v34
	v_fma_f32 v37, -v33, v36, v35
	v_fmac_f32_e32 v36, v37, v34
	v_fma_f32 v33, -v33, v36, v35
	v_div_fmas_f32 v33, v33, v34, v36
	v_div_fixup_f32 v32, v33, v32, 1.0
	v_bfe_u32 v33, v32, 16, 1
	v_add3_u32 v32, v32, v33, s79
	s_and_b64 vcc, exec, s[6:7]
	ds_write_b16_d16_hi v62, v32 offset:64
	v_mul_f32_e32 v32, 0xbfb8aa3b, v46
	v_exp_f32_e32 v32, v32
	s_nop 0
	v_add_f32_e32 v32, 1.0, v32
	v_div_scale_f32 v33, s[8:9], v32, v32, 1.0
	v_rcp_f32_e32 v34, v33
	v_div_scale_f32 v35, vcc, 1.0, v32, 1.0
	v_fma_f32 v36, -v33, v34, 1.0
	v_fmac_f32_e32 v34, v36, v34
	v_mul_f32_e32 v36, v35, v34
	v_fma_f32 v37, -v33, v36, v35
	v_fmac_f32_e32 v36, v37, v34
	v_fma_f32 v33, -v33, v36, v35
	v_div_fmas_f32 v33, v33, v34, v36
	v_div_fixup_f32 v32, v33, v32, 1.0
	v_bfe_u32 v33, v32, 16, 1
	v_add3_u32 v32, v32, v33, s79
	s_and_b64 vcc, exec, s[6:7]
	ds_write_b16_d16_hi v55, v32 offset:64
	v_mul_f32_e32 v32, 0xbfb8aa3b, v47
	v_exp_f32_e32 v32, v32
	s_nop 0
	v_add_f32_e32 v32, 1.0, v32
	v_div_scale_f32 v33, s[4:5], v32, v32, 1.0
	v_rcp_f32_e32 v34, v33
	v_div_scale_f32 v35, vcc, 1.0, v32, 1.0
	v_fma_f32 v36, -v33, v34, 1.0
	v_fmac_f32_e32 v34, v36, v34
	v_mul_f32_e32 v36, v35, v34
	v_fma_f32 v37, -v33, v36, v35
	v_fmac_f32_e32 v36, v37, v34
	v_fma_f32 v33, -v33, v36, v35
	v_div_fmas_f32 v33, v33, v34, v36
	v_div_fixup_f32 v32, v33, v32, 1.0
	s_branch .LBB0_3225

; __device__ __forceinline__ float sigmf(float x) { return 1.f / (1.f + __expf(-x)); }
; __device__ __forceinline__ bf16r f2bf(float f) {
;   unsigned u = __float_as_uint(f);
;   u += 0x7fffu + ((u >> 16) & 1u);
;   return (bf16r)(u >> 16);
; }
; __device__ __forceinline__ void inproj_epilogue(const Params& p, int layer, int mt, int ntile, int tid,
;                                                 f32x16 (&acc)[2][2], unsigned char* smem) {
;     ...
;     acc_foreach(tid, acc, [&](int row, int col, float v) {
;       int t = m0 + row;
;       float o = v;
;       if (mode == 1) o = (t >= NPADR) ? v : 0.f;
;       if (mode == 2) o = sigmf(v);
;       sT[row * 136 + col] = f2bf(o);
;     });
.LBB0_3370:
	v_bfe_u32 v110, v107, 16, 1
	v_and_b32_e32 v106, 0x5f, v106
	v_add3_u32 v111, v107, v110, s83
	v_mul_lo_u32 v110, v96, s90
	v_lshl_add_u32 v107, v106, 1, v110
	ds_write_b16_d16_hi v107, v111
	v_add3_u32 v111, s88, v96, 1
	v_cndmask_b32_e64 v112, 0, 1, s[10:11]
	v_cmp_ne_u32_e64 s[6:7], 1, v112
	v_cmp_lt_i32_e64 s[10:11], s81, v111
	s_nop 1

; __device__ __forceinline__ float sigmf(float x) { return 1.f / (1.f + __expf(-x)); }
; __device__ __forceinline__ bf16r f2bf(float f) {
;   unsigned u = __float_as_uint(f);
;   u += 0x7fffu + ((u >> 16) & 1u);
;   return (bf16r)(u >> 16);
; }
; __device__ __forceinline__ void inproj_epilogue(const Params& p, int layer, int mt, int ntile, int tid,
;                                                 f32x16 (&acc)[2][2], unsigned char* smem) {
;     ...
;     acc_foreach(tid, acc, [&](int row, int col, float v) {
;       int t = m0 + row;
;       float o = v;
;       if (mode == 1) o = (t >= NPADR) ? v : 0.f;
;       if (mode == 2) o = sigmf(v);
;       sT[row * 136 + col] = f2bf(o);
;     });
.LBB0_3373:
	v_bfe_u32 v112, v111, 16, 1
	v_add3_u32 v112, v111, v112, s83
	v_add_u32_e32 v111, 0x110, v110
	v_lshl_add_u32 v110, v106, 1, v111
	ds_write_b16_d16_hi v110, v112
	v_add3_u32 v112, s88, v96, 2
	v_cmp_lt_i32_e64 s[12:13], s81, v112
	s_nop 1

; __device__ __forceinline__ float sigmf(float x) { return 1.f / (1.f + __expf(-x)); }
; __device__ __forceinline__ bf16r f2bf(float f) {
;   unsigned u = __float_as_uint(f);
;   u += 0x7fffu + ((u >> 16) & 1u);
;   return (bf16r)(u >> 16);
; }
; __device__ __forceinline__ void inproj_epilogue(const Params& p, int layer, int mt, int ntile, int tid,
;                                                 f32x16 (&acc)[2][2], unsigned char* smem) {
;     ...
;     acc_foreach(tid, acc, [&](int row, int col, float v) {
;       int t = m0 + row;
;       float o = v;
;       if (mode == 1) o = (t >= NPADR) ? v : 0.f;
;       if (mode == 2) o = sigmf(v);
;       sT[row * 136 + col] = f2bf(o);
;     });
.LBB0_3376:
	v_bfe_u32 v113, v112, 16, 1
	v_add3_u32 v113, v112, v113, s83
	v_add_u32_e32 v112, 0x110, v111
	v_lshl_add_u32 v111, v106, 1, v112
	ds_write_b16_d16_hi v111, v113
	v_add3_u32 v113, s88, v96, 3
	v_cmp_lt_i32_e64 s[14:15], s81, v113
	s_nop 1

; __device__ __forceinline__ float sigmf(float x) { return 1.f / (1.f + __expf(-x)); }
; __device__ __forceinline__ bf16r f2bf(float f) {
;   unsigned u = __float_as_uint(f);
;   u += 0x7fffu + ((u >> 16) & 1u);
;   return (bf16r)(u >> 16);
; }
; __device__ __forceinline__ void inproj_epilogue(const Params& p, int layer, int mt, int ntile, int tid,
;                                                 f32x16 (&acc)[2][2], unsigned char* smem) {
;     ...
;     acc_foreach(tid, acc, [&](int row, int col, float v) {
;       int t = m0 + row;
;       float o = v;
;       if (mode == 1) o = (t >= NPADR) ? v : 0.f;
;       if (mode == 2) o = sigmf(v);
;       sT[row * 136 + col] = f2bf(o);
;     });
.LBB0_3379:
	v_bfe_u32 v114, v113, 16, 1
	v_add3_u32 v114, v113, v114, s83
	v_add_u32_e32 v113, 0x110, v112
	v_lshl_add_u32 v112, v106, 1, v113
	ds_write_b16_d16_hi v112, v114
	v_add3_u32 v114, s88, v96, 8
	v_cmp_lt_i32_e64 s[16:17], s81, v114
	s_nop 1

; __device__ __forceinline__ float sigmf(float x) { return 1.f / (1.f + __expf(-x)); }
; __device__ __forceinline__ bf16r f2bf(float f) {
;   unsigned u = __float_as_uint(f);
;   u += 0x7fffu + ((u >> 16) & 1u);
;   return (bf16r)(u >> 16);
; }
; __device__ __forceinline__ void inproj_epilogue(const Params& p, int layer, int mt, int ntile, int tid,
;                                                 f32x16 (&acc)[2][2], unsigned char* smem) {
;     ...
;     acc_foreach(tid, acc, [&](int row, int col, float v) {
;       int t = m0 + row;
;       float o = v;
;       if (mode == 1) o = (t >= NPADR) ? v : 0.f;
;       if (mode == 2) o = sigmf(v);
;       sT[row * 136 + col] = f2bf(o);
;     });
.LBB0_3382:
	v_bfe_u32 v115, v114, 16, 1
	v_add3_u32 v115, v114, v115, s83
	v_add_u32_e32 v114, 0x550, v113
	v_lshl_add_u32 v113, v106, 1, v114
	ds_write_b16_d16_hi v113, v115
	v_add3_u32 v115, s88, v96, 9
	v_cmp_lt_i32_e64 s[18:19], s81, v115
	s_nop 1

; __device__ __forceinline__ float sigmf(float x) { return 1.f / (1.f + __expf(-x)); }
; __device__ __forceinline__ bf16r f2bf(float f) {
;   unsigned u = __float_as_uint(f);
;   u += 0x7fffu + ((u >> 16) & 1u);
;   return (bf16r)(u >> 16);
; }
; __device__ __forceinline__ void inproj_epilogue(const Params& p, int layer, int mt, int ntile, int tid,
;                                                 f32x16 (&acc)[2][2], unsigned char* smem) {
;     ...
;     acc_foreach(tid, acc, [&](int row, int col, float v) {
;       int t = m0 + row;
;       float o = v;
;       if (mode == 1) o = (t >= NPADR) ? v : 0.f;
;       if (mode == 2) o = sigmf(v);
;       sT[row * 136 + col] = f2bf(o);
;     });
.LBB0_3385:
	v_bfe_u32 v116, v115, 16, 1
	v_add3_u32 v116, v115, v116, s83
	v_add_u32_e32 v115, 0x110, v114
	v_lshl_add_u32 v114, v106, 1, v115
	ds_write_b16_d16_hi v114, v116
	v_add3_u32 v116, s88, v96, 10
	v_cmp_lt_i32_e64 s[20:21], s81, v116
	s_nop 1

; __device__ __forceinline__ float sigmf(float x) { return 1.f / (1.f + __expf(-x)); }
; __device__ __forceinline__ bf16r f2bf(float f) {
;   unsigned u = __float_as_uint(f);
;   u += 0x7fffu + ((u >> 16) & 1u);
;   return (bf16r)(u >> 16);
; }
; __device__ __forceinline__ void inproj_epilogue(const Params& p, int layer, int mt, int ntile, int tid,
;                                                 f32x16 (&acc)[2][2], unsigned char* smem) {
;     ...
;     acc_foreach(tid, acc, [&](int row, int col, float v) {
;       int t = m0 + row;
;       float o = v;
;       if (mode == 1) o = (t >= NPADR) ? v : 0.f;
;       if (mode == 2) o = sigmf(v);
;       sT[row * 136 + col] = f2bf(o);
;     });
.LBB0_3388:
	v_bfe_u32 v117, v116, 16, 1
	v_add3_u32 v117, v116, v117, s83
	v_add_u32_e32 v116, 0x110, v115
	v_lshl_add_u32 v115, v106, 1, v116
	ds_write_b16_d16_hi v115, v117
	v_add3_u32 v117, s88, v96, 11
	v_cmp_lt_i32_e64 s[22:23], s81, v117
	s_nop 1

; __device__ __forceinline__ float sigmf(float x) { return 1.f / (1.f + __expf(-x)); }
; __device__ __forceinline__ bf16r f2bf(float f) {
;   unsigned u = __float_as_uint(f);
;   u += 0x7fffu + ((u >> 16) & 1u);
;   return (bf16r)(u >> 16);
; }
; __device__ __forceinline__ void inproj_epilogue(const Params& p, int layer, int mt, int ntile, int tid,
;                                                 f32x16 (&acc)[2][2], unsigned char* smem) {
;     ...
;     acc_foreach(tid, acc, [&](int row, int col, float v) {
;       int t = m0 + row;
;       float o = v;
;       if (mode == 1) o = (t >= NPADR) ? v : 0.f;
;       if (mode == 2) o = sigmf(v);
;       sT[row * 136 + col] = f2bf(o);
;     });
.LBB0_3391:
	v_bfe_u32 v118, v117, 16, 1
	v_add_u32_e32 v116, 0x110, v116
	v_add3_u32 v118, v117, v118, s83
	v_lshl_add_u32 v117, v106, 1, v116
	ds_write_b16_d16_hi v117, v118
	v_add3_u32 v118, s88, v96, 16
	v_cmp_lt_i32_e64 s[24:25], s81, v118
	s_nop 1

; __device__ __forceinline__ float sigmf(float x) { return 1.f / (1.f + __expf(-x)); }
; __device__ __forceinline__ bf16r f2bf(float f) {
;   unsigned u = __float_as_uint(f);
;   u += 0x7fffu + ((u >> 16) & 1u);
;   return (bf16r)(u >> 16);
; }
; __device__ __forceinline__ void inproj_epilogue(const Params& p, int layer, int mt, int ntile, int tid,
;                                                 f32x16 (&acc)[2][2], unsigned char* smem) {
;     ...
;     acc_foreach(tid, acc, [&](int row, int col, float v) {
;       int t = m0 + row;
;       float o = v;
;       if (mode == 1) o = (t >= NPADR) ? v : 0.f;
;       if (mode == 2) o = sigmf(v);
;       sT[row * 136 + col] = f2bf(o);
;     });
.LBB0_3394:
	v_bfe_u32 v119, v118, 16, 1
	v_add_u32_e32 v116, 0x550, v116
	v_add3_u32 v119, v118, v119, s83
	v_lshl_add_u32 v118, v106, 1, v116
	ds_write_b16_d16_hi v118, v119
	v_add3_u32 v119, s88, v96, 17
	v_cmp_lt_i32_e64 s[26:27], s81, v119
	s_nop 1

; __device__ __forceinline__ float sigmf(float x) { return 1.f / (1.f + __expf(-x)); }
; __device__ __forceinline__ bf16r f2bf(float f) {
;   unsigned u = __float_as_uint(f);
;   u += 0x7fffu + ((u >> 16) & 1u);
;   return (bf16r)(u >> 16);
; }
; __device__ __forceinline__ void inproj_epilogue(const Params& p, int layer, int mt, int ntile, int tid,
;                                                 f32x16 (&acc)[2][2], unsigned char* smem) {
;     ...
;     acc_foreach(tid, acc, [&](int row, int col, float v) {
;       int t = m0 + row;
;       float o = v;
;       if (mode == 1) o = (t >= NPADR) ? v : 0.f;
;       if (mode == 2) o = sigmf(v);
;       sT[row * 136 + col] = f2bf(o);
;     });
.LBB0_3397:
	v_bfe_u32 v120, v119, 16, 1
	v_add_u32_e32 v116, 0x110, v116
	v_add3_u32 v120, v119, v120, s83
	v_lshl_add_u32 v119, v106, 1, v116
	ds_write_b16_d16_hi v119, v120
	v_add3_u32 v120, s88, v96, 18
	v_cmp_lt_i32_e64 s[28:29], s81, v120
	s_nop 1

; __device__ __forceinline__ float sigmf(float x) { return 1.f / (1.f + __expf(-x)); }
; __device__ __forceinline__ bf16r f2bf(float f) {
;   unsigned u = __float_as_uint(f);
;   u += 0x7fffu + ((u >> 16) & 1u);
;   return (bf16r)(u >> 16);
; }
; __device__ __forceinline__ void inproj_epilogue(const Params& p, int layer, int mt, int ntile, int tid,
;                                                 f32x16 (&acc)[2][2], unsigned char* smem) {
;     ...
;     acc_foreach(tid, acc, [&](int row, int col, float v) {
;       int t = m0 + row;
;       float o = v;
;       if (mode == 1) o = (t >= NPADR) ? v : 0.f;
;       if (mode == 2) o = sigmf(v);
;       sT[row * 136 + col] = f2bf(o);
;     });
.LBB0_3400:
	v_bfe_u32 v121, v120, 16, 1
	v_add_u32_e32 v116, 0x110, v116
	v_add3_u32 v121, v120, v121, s83
	v_lshl_add_u32 v120, v106, 1, v116
	ds_write_b16_d16_hi v120, v121
	v_add3_u32 v121, s88, v96, 19
	v_cmp_lt_i32_e64 s[30:31], s81, v121
	s_nop 1

; __device__ __forceinline__ float sigmf(float x) { return 1.f / (1.f + __expf(-x)); }
; __device__ __forceinline__ bf16r f2bf(float f) {
;   unsigned u = __float_as_uint(f);
;   u += 0x7fffu + ((u >> 16) & 1u);
;   return (bf16r)(u >> 16);
; }
; __device__ __forceinline__ void inproj_epilogue(const Params& p, int layer, int mt, int ntile, int tid,
;                                                 f32x16 (&acc)[2][2], unsigned char* smem) {
;     ...
;     acc_foreach(tid, acc, [&](int row, int col, float v) {
;       int t = m0 + row;
;       float o = v;
;       if (mode == 1) o = (t >= NPADR) ? v : 0.f;
;       if (mode == 2) o = sigmf(v);
;       sT[row * 136 + col] = f2bf(o);
;     });
.LBB0_3403:
	v_bfe_u32 v122, v121, 16, 1
	v_add_u32_e32 v116, 0x110, v116
	v_add3_u32 v122, v121, v122, s83
	v_lshl_add_u32 v121, v106, 1, v116
	ds_write_b16_d16_hi v121, v122
	v_add3_u32 v122, s88, v96, 24
	v_cmp_lt_i32_e64 s[34:35], s81, v122
	s_nop 1

; __device__ __forceinline__ float sigmf(float x) { return 1.f / (1.f + __expf(-x)); }
; __device__ __forceinline__ bf16r f2bf(float f) {
;   unsigned u = __float_as_uint(f);
;   u += 0x7fffu + ((u >> 16) & 1u);
;   return (bf16r)(u >> 16);
; }
; __device__ __forceinline__ void inproj_epilogue(const Params& p, int layer, int mt, int ntile, int tid,
;                                                 f32x16 (&acc)[2][2], unsigned char* smem) {
;     ...
;     acc_foreach(tid, acc, [&](int row, int col, float v) {
;       int t = m0 + row;
;       float o = v;
;       if (mode == 1) o = (t >= NPADR) ? v : 0.f;
;       if (mode == 2) o = sigmf(v);
;       sT[row * 136 + col] = f2bf(o);
;     });
.LBB0_3406:
	v_bfe_u32 v123, v122, 16, 1
	v_add_u32_e32 v116, 0x550, v116
	v_add3_u32 v123, v122, v123, s83
	v_lshl_add_u32 v122, v106, 1, v116
	ds_write_b16_d16_hi v122, v123
	v_add3_u32 v123, s88, v96, 25
	v_cmp_lt_i32_e64 s[36:37], s81, v123
	s_nop 1

; __device__ __forceinline__ float sigmf(float x) { return 1.f / (1.f + __expf(-x)); }
; __device__ __forceinline__ bf16r f2bf(float f) {
;   unsigned u = __float_as_uint(f);
;   u += 0x7fffu + ((u >> 16) & 1u);
;   return (bf16r)(u >> 16);
; }
; __device__ __forceinline__ void inproj_epilogue(const Params& p, int layer, int mt, int ntile, int tid,
;                                                 f32x16 (&acc)[2][2], unsigned char* smem) {
;     ...
;     acc_foreach(tid, acc, [&](int row, int col, float v) {
;       int t = m0 + row;
;       float o = v;
;       if (mode == 1) o = (t >= NPADR) ? v : 0.f;
;       if (mode == 2) o = sigmf(v);
;       sT[row * 136 + col] = f2bf(o);
;     });
.LBB0_3409:
	v_bfe_u32 v124, v123, 16, 1
	v_add_u32_e32 v116, 0x110, v116
	v_add3_u32 v124, v123, v124, s83
	v_lshl_add_u32 v123, v106, 1, v116
	ds_write_b16_d16_hi v123, v124
	v_add3_u32 v124, s88, v96, 26
	v_cmp_lt_i32_e64 s[38:39], s81, v124
	s_nop 1

; __device__ __forceinline__ float sigmf(float x) { return 1.f / (1.f + __expf(-x)); }
; __device__ __forceinline__ bf16r f2bf(float f) {
;   unsigned u = __float_as_uint(f);
;   u += 0x7fffu + ((u >> 16) & 1u);
;   return (bf16r)(u >> 16);
; }
; __device__ __forceinline__ void inproj_epilogue(const Params& p, int layer, int mt, int ntile, int tid,
;                                                 f32x16 (&acc)[2][2], unsigned char* smem) {
;     ...
;     acc_foreach(tid, acc, [&](int row, int col, float v) {
;       int t = m0 + row;
;       float o = v;
;       if (mode == 1) o = (t >= NPADR) ? v : 0.f;
;       if (mode == 2) o = sigmf(v);
;       sT[row * 136 + col] = f2bf(o);
;     });
.LBB0_3412:
	v_bfe_u32 v125, v124, 16, 1
	v_add_u32_e32 v116, 0x110, v116
	v_add3_u32 v124, v124, v125, s83
	v_lshl_add_u32 v116, v106, 1, v116
	ds_write_b16_d16_hi v116, v124
	v_add3_u32 v124, s88, v96, 27
	v_cmp_lt_i32_e64 s[40:41], s81, v124
	s_nop 1

; __device__ __forceinline__ float sigmf(float x) { return 1.f / (1.f + __expf(-x)); }
; __device__ __forceinline__ bf16r f2bf(float f) {
;   unsigned u = __float_as_uint(f);
;   u += 0x7fffu + ((u >> 16) & 1u);
;   return (bf16r)(u >> 16);
; }
; __device__ __forceinline__ void inproj_epilogue(const Params& p, int layer, int mt, int ntile, int tid,
;                                                 f32x16 (&acc)[2][2], unsigned char* smem) {
;     ...
;     acc_foreach(tid, acc, [&](int row, int col, float v) {
;       int t = m0 + row;
;       float o = v;
;       if (mode == 1) o = (t >= NPADR) ? v : 0.f;
;       if (mode == 2) o = sigmf(v);
;       sT[row * 136 + col] = f2bf(o);
;     });
.LBB0_3415:
	v_bfe_u32 v125, v124, 16, 1
	v_add3_u32 v124, v124, v125, s83
	ds_write_b16_d16_hi v116, v124 offset:272
	s_nop 1

; __device__ __forceinline__ float sigmf(float x) { return 1.f / (1.f + __expf(-x)); }
; __device__ __forceinline__ bf16r f2bf(float f) {
;   unsigned u = __float_as_uint(f);
;   u += 0x7fffu + ((u >> 16) & 1u);
;   return (bf16r)(u >> 16);
; }
; __device__ __forceinline__ void inproj_epilogue(const Params& p, int layer, int mt, int ntile, int tid,
;                                                 f32x16 (&acc)[2][2], unsigned char* smem) {
;     ...
;     acc_foreach(tid, acc, [&](int row, int col, float v) {
;       int t = m0 + row;
;       float o = v;
;       if (mode == 1) o = (t >= NPADR) ? v : 0.f;
;       if (mode == 2) o = sigmf(v);
;       sT[row * 136 + col] = f2bf(o);
;     });
.LBB0_3418:
	v_bfe_u32 v124, v48, 16, 1
	v_add3_u32 v48, v48, v124, s83
	ds_write_b16_d16_hi v107, v48 offset:64
	s_nop 1

; __device__ __forceinline__ float sigmf(float x) { return 1.f / (1.f + __expf(-x)); }
; __device__ __forceinline__ bf16r f2bf(float f) {
;   unsigned u = __float_as_uint(f);
;   u += 0x7fffu + ((u >> 16) & 1u);
;   return (bf16r)(u >> 16);
; }
; __device__ __forceinline__ void inproj_epilogue(const Params& p, int layer, int mt, int ntile, int tid,
;                                                 f32x16 (&acc)[2][2], unsigned char* smem) {
;     ...
;     acc_foreach(tid, acc, [&](int row, int col, float v) {
;       int t = m0 + row;
;       float o = v;
;       if (mode == 1) o = (t >= NPADR) ? v : 0.f;
;       if (mode == 2) o = sigmf(v);
;       sT[row * 136 + col] = f2bf(o);
;     });
.LBB0_3421:
	v_bfe_u32 v49, v48, 16, 1
	v_add3_u32 v48, v48, v49, s83
	ds_write_b16_d16_hi v110, v48 offset:64
	s_nop 1

; __device__ __forceinline__ float sigmf(float x) { return 1.f / (1.f + __expf(-x)); }
; __device__ __forceinline__ bf16r f2bf(float f) {
;   unsigned u = __float_as_uint(f);
;   u += 0x7fffu + ((u >> 16) & 1u);
;   return (bf16r)(u >> 16);
; }
; __device__ __forceinline__ void inproj_epilogue(const Params& p, int layer, int mt, int ntile, int tid,
;                                                 f32x16 (&acc)[2][2], unsigned char* smem) {
;     ...
;     acc_foreach(tid, acc, [&](int row, int col, float v) {
;       int t = m0 + row;
;       float o = v;
;       if (mode == 1) o = (t >= NPADR) ? v : 0.f;
;       if (mode == 2) o = sigmf(v);
;       sT[row * 136 + col] = f2bf(o);
;     });
.LBB0_3424:
	v_bfe_u32 v49, v48, 16, 1
	v_add3_u32 v48, v48, v49, s83
	ds_write_b16_d16_hi v111, v48 offset:64
	s_nop 1

; __device__ __forceinline__ float sigmf(float x) { return 1.f / (1.f + __expf(-x)); }
; __device__ __forceinline__ bf16r f2bf(float f) {
;   unsigned u = __float_as_uint(f);
;   u += 0x7fffu + ((u >> 16) & 1u);
;   return (bf16r)(u >> 16);
; }
; __device__ __forceinline__ void inproj_epilogue(const Params& p, int layer, int mt, int ntile, int tid,
;                                                 f32x16 (&acc)[2][2], unsigned char* smem) {
;     ...
;     acc_foreach(tid, acc, [&](int row, int col, float v) {
;       int t = m0 + row;
;       float o = v;
;       if (mode == 1) o = (t >= NPADR) ? v : 0.f;
;       if (mode == 2) o = sigmf(v);
;       sT[row * 136 + col] = f2bf(o);
;     });
.LBB0_3427:
	v_bfe_u32 v49, v48, 16, 1
	v_add3_u32 v48, v48, v49, s83
	ds_write_b16_d16_hi v112, v48 offset:64
	s_nop 1

; __device__ __forceinline__ float sigmf(float x) { return 1.f / (1.f + __expf(-x)); }
; __device__ __forceinline__ bf16r f2bf(float f) {
;   unsigned u = __float_as_uint(f);
;   u += 0x7fffu + ((u >> 16) & 1u);
;   return (bf16r)(u >> 16);
; }
; __device__ __forceinline__ void inproj_epilogue(const Params& p, int layer, int mt, int ntile, int tid,
;                                                 f32x16 (&acc)[2][2], unsigned char* smem) {
;     ...
;     acc_foreach(tid, acc, [&](int row, int col, float v) {
;       int t = m0 + row;
;       float o = v;
;       if (mode == 1) o = (t >= NPADR) ? v : 0.f;
;       if (mode == 2) o = sigmf(v);
;       sT[row * 136 + col] = f2bf(o);
;     });
.LBB0_3430:
	v_bfe_u32 v49, v48, 16, 1
	v_add3_u32 v48, v48, v49, s83
	ds_write_b16_d16_hi v113, v48 offset:64
	s_nop 1

; __device__ __forceinline__ float sigmf(float x) { return 1.f / (1.f + __expf(-x)); }
; __device__ __forceinline__ bf16r f2bf(float f) {
;   unsigned u = __float_as_uint(f);
;   u += 0x7fffu + ((u >> 16) & 1u);
;   return (bf16r)(u >> 16);
; }
; __device__ __forceinline__ void inproj_epilogue(const Params& p, int layer, int mt, int ntile, int tid,
;                                                 f32x16 (&acc)[2][2], unsigned char* smem) {
;     ...
;     acc_foreach(tid, acc, [&](int row, int col, float v) {
;       int t = m0 + row;
;       float o = v;
;       if (mode == 1) o = (t >= NPADR) ? v : 0.f;
;       if (mode == 2) o = sigmf(v);
;       sT[row * 136 + col] = f2bf(o);
;     });
.LBB0_3433:
	v_bfe_u32 v49, v48, 16, 1
	v_add3_u32 v48, v48, v49, s83
	ds_write_b16_d16_hi v114, v48 offset:64
	s_nop 1

; __device__ __forceinline__ float sigmf(float x) { return 1.f / (1.f + __expf(-x)); }
; __device__ __forceinline__ bf16r f2bf(float f) {
;   unsigned u = __float_as_uint(f);
;   u += 0x7fffu + ((u >> 16) & 1u);
;   return (bf16r)(u >> 16);
; }
; __device__ __forceinline__ void inproj_epilogue(const Params& p, int layer, int mt, int ntile, int tid,
;                                                 f32x16 (&acc)[2][2], unsigned char* smem) {
;     ...
;     acc_foreach(tid, acc, [&](int row, int col, float v) {
;       int t = m0 + row;
;       float o = v;
;       if (mode == 1) o = (t >= NPADR) ? v : 0.f;
;       if (mode == 2) o = sigmf(v);
;       sT[row * 136 + col] = f2bf(o);
;     });
.LBB0_3436:
	v_bfe_u32 v49, v48, 16, 1
	v_add3_u32 v48, v48, v49, s83
	ds_write_b16_d16_hi v115, v48 offset:64
	s_nop 1

; __device__ __forceinline__ float sigmf(float x) { return 1.f / (1.f + __expf(-x)); }
; __device__ __forceinline__ bf16r f2bf(float f) {
;   unsigned u = __float_as_uint(f);
;   u += 0x7fffu + ((u >> 16) & 1u);
;   return (bf16r)(u >> 16);
; }
; __device__ __forceinline__ void inproj_epilogue(const Params& p, int layer, int mt, int ntile, int tid,
;                                                 f32x16 (&acc)[2][2], unsigned char* smem) {
;     ...
;     acc_foreach(tid, acc, [&](int row, int col, float v) {
;       int t = m0 + row;
;       float o = v;
;       if (mode == 1) o = (t >= NPADR) ? v : 0.f;
;       if (mode == 2) o = sigmf(v);
;       sT[row * 136 + col] = f2bf(o);
;     });
.LBB0_3439:
	v_bfe_u32 v49, v48, 16, 1
	v_add3_u32 v48, v48, v49, s83
	ds_write_b16_d16_hi v117, v48 offset:64
	s_nop 1

; __device__ __forceinline__ float sigmf(float x) { return 1.f / (1.f + __expf(-x)); }
; __device__ __forceinline__ bf16r f2bf(float f) {
;   unsigned u = __float_as_uint(f);
;   u += 0x7fffu + ((u >> 16) & 1u);
;   return (bf16r)(u >> 16);
; }
; __device__ __forceinline__ void inproj_epilogue(const Params& p, int layer, int mt, int ntile, int tid,
;                                                 f32x16 (&acc)[2][2], unsigned char* smem) {
;     ...
;     acc_foreach(tid, acc, [&](int row, int col, float v) {
;       int t = m0 + row;
;       float o = v;
;       if (mode == 1) o = (t >= NPADR) ? v : 0.f;
;       if (mode == 2) o = sigmf(v);
;       sT[row * 136 + col] = f2bf(o);
;     });
.LBB0_3442:
	v_bfe_u32 v49, v48, 16, 1
	v_add3_u32 v48, v48, v49, s83
	ds_write_b16_d16_hi v118, v48 offset:64
	s_nop 1

; __device__ __forceinline__ float sigmf(float x) { return 1.f / (1.f + __expf(-x)); }
; __device__ __forceinline__ bf16r f2bf(float f) {
;   unsigned u = __float_as_uint(f);
;   u += 0x7fffu + ((u >> 16) & 1u);
;   return (bf16r)(u >> 16);
; }
; __device__ __forceinline__ void inproj_epilogue(const Params& p, int layer, int mt, int ntile, int tid,
;                                                 f32x16 (&acc)[2][2], unsigned char* smem) {
;     ...
;     acc_foreach(tid, acc, [&](int row, int col, float v) {
;       int t = m0 + row;
;       float o = v;
;       if (mode == 1) o = (t >= NPADR) ? v : 0.f;
;       if (mode == 2) o = sigmf(v);
;       sT[row * 136 + col] = f2bf(o);
;     });
.LBB0_3445:
	v_bfe_u32 v49, v48, 16, 1
	v_add3_u32 v48, v48, v49, s83
	ds_write_b16_d16_hi v119, v48 offset:64
	s_nop 1

; __device__ __forceinline__ float sigmf(float x) { return 1.f / (1.f + __expf(-x)); }
; __device__ __forceinline__ bf16r f2bf(float f) {
;   unsigned u = __float_as_uint(f);
;   u += 0x7fffu + ((u >> 16) & 1u);
;   return (bf16r)(u >> 16);
; }
; __device__ __forceinline__ void inproj_epilogue(const Params& p, int layer, int mt, int ntile, int tid,
;                                                 f32x16 (&acc)[2][2], unsigned char* smem) {
;     ...
;     acc_foreach(tid, acc, [&](int row, int col, float v) {
;       int t = m0 + row;
;       float o = v;
;       if (mode == 1) o = (t >= NPADR) ? v : 0.f;
;       if (mode == 2) o = sigmf(v);
;       sT[row * 136 + col] = f2bf(o);
;     });
.LBB0_3448:
	v_bfe_u32 v49, v48, 16, 1
	v_add3_u32 v48, v48, v49, s83
	ds_write_b16_d16_hi v120, v48 offset:64
	s_nop 1

; __device__ __forceinline__ float sigmf(float x) { return 1.f / (1.f + __expf(-x)); }
; __device__ __forceinline__ bf16r f2bf(float f) {
;   unsigned u = __float_as_uint(f);
;   u += 0x7fffu + ((u >> 16) & 1u);
;   return (bf16r)(u >> 16);
; }
; __device__ __forceinline__ void inproj_epilogue(const Params& p, int layer, int mt, int ntile, int tid,
;                                                 f32x16 (&acc)[2][2], unsigned char* smem) {
;     ...
;     acc_foreach(tid, acc, [&](int row, int col, float v) {
;       int t = m0 + row;
;       float o = v;
;       if (mode == 1) o = (t >= NPADR) ? v : 0.f;
;       if (mode == 2) o = sigmf(v);
;       sT[row * 136 + col] = f2bf(o);
;     });
.LBB0_3451:
	v_bfe_u32 v49, v48, 16, 1
	v_add3_u32 v48, v48, v49, s83
	ds_write_b16_d16_hi v121, v48 offset:64
	s_nop 1

; __device__ __forceinline__ float sigmf(float x) { return 1.f / (1.f + __expf(-x)); }
; __device__ __forceinline__ bf16r f2bf(float f) {
;   unsigned u = __float_as_uint(f);
;   u += 0x7fffu + ((u >> 16) & 1u);
;   return (bf16r)(u >> 16);
; }
; __device__ __forceinline__ void inproj_epilogue(const Params& p, int layer, int mt, int ntile, int tid,
;                                                 f32x16 (&acc)[2][2], unsigned char* smem) {
;     ...
;     acc_foreach(tid, acc, [&](int row, int col, float v) {
;       int t = m0 + row;
;       float o = v;
;       if (mode == 1) o = (t >= NPADR) ? v : 0.f;
;       if (mode == 2) o = sigmf(v);
;       sT[row * 136 + col] = f2bf(o);
;     });
.LBB0_3454:
	v_bfe_u32 v49, v48, 16, 1
	v_add3_u32 v48, v48, v49, s83
	ds_write_b16_d16_hi v122, v48 offset:64
	s_nop 1

; __device__ __forceinline__ float sigmf(float x) { return 1.f / (1.f + __expf(-x)); }
; __device__ __forceinline__ bf16r f2bf(float f) {
;   unsigned u = __float_as_uint(f);
;   u += 0x7fffu + ((u >> 16) & 1u);
;   return (bf16r)(u >> 16);
; }
; __device__ __forceinline__ void inproj_epilogue(const Params& p, int layer, int mt, int ntile, int tid,
;                                                 f32x16 (&acc)[2][2], unsigned char* smem) {
;     ...
;     acc_foreach(tid, acc, [&](int row, int col, float v) {
;       int t = m0 + row;
;       float o = v;
;       if (mode == 1) o = (t >= NPADR) ? v : 0.f;
;       if (mode == 2) o = sigmf(v);
;       sT[row * 136 + col] = f2bf(o);
;     });
.LBB0_3457:
	v_bfe_u32 v49, v48, 16, 1
	v_add3_u32 v48, v48, v49, s83
	ds_write_b16_d16_hi v123, v48 offset:64
	s_nop 1

; __device__ __forceinline__ float sigmf(float x) { return 1.f / (1.f + __expf(-x)); }
; __device__ __forceinline__ bf16r f2bf(float f) {
;   unsigned u = __float_as_uint(f);
;   u += 0x7fffu + ((u >> 16) & 1u);
;   return (bf16r)(u >> 16);
; }
; __device__ __forceinline__ void inproj_epilogue(const Params& p, int layer, int mt, int ntile, int tid,
;                                                 f32x16 (&acc)[2][2], unsigned char* smem) {
;     ...
;     acc_foreach(tid, acc, [&](int row, int col, float v) {
;       int t = m0 + row;
;       float o = v;
;       if (mode == 1) o = (t >= NPADR) ? v : 0.f;
;       if (mode == 2) o = sigmf(v);
;       sT[row * 136 + col] = f2bf(o);
;     });
.LBB0_3460:
	v_bfe_u32 v49, v48, 16, 1
	v_add3_u32 v48, v48, v49, s83
	ds_write_b16_d16_hi v116, v48 offset:64
	s_nop 1

; __device__ __forceinline__ float sigmf(float x) { return 1.f / (1.f + __expf(-x)); }
; __device__ __forceinline__ bf16r f2bf(float f) {
;   unsigned u = __float_as_uint(f);
;   u += 0x7fffu + ((u >> 16) & 1u);
;   return (bf16r)(u >> 16);
; }
; __device__ __forceinline__ void inproj_epilogue(const Params& p, int layer, int mt, int ntile, int tid,
;                                                 f32x16 (&acc)[2][2], unsigned char* smem) {
;     ...
;     acc_foreach(tid, acc, [&](int row, int col, float v) {
;       int t = m0 + row;
;       float o = v;
;       if (mode == 1) o = (t >= NPADR) ? v : 0.f;
;       if (mode == 2) o = sigmf(v);
;       sT[row * 136 + col] = f2bf(o);
;     });
.LBB0_3463:
	v_bfe_u32 v50, v48, 16, 1
	v_add_u32_e32 v49, 0x110, v116
	v_add3_u32 v48, v48, v50, s83
	ds_write_b16_d16_hi v49, v48 offset:64
	v_or_b32_e32 v48, 32, v96
	v_add_u32_e32 v49, s88, v48
	v_cmp_lt_i32_e64 s[8:9], s81, v49
	s_nop 1

; __device__ __forceinline__ float sigmf(float x) { return 1.f / (1.f + __expf(-x)); }
; __device__ __forceinline__ bf16r f2bf(float f) {
;   unsigned u = __float_as_uint(f);
;   u += 0x7fffu + ((u >> 16) & 1u);
;   return (bf16r)(u >> 16);
; }
; __device__ __forceinline__ void inproj_epilogue(const Params& p, int layer, int mt, int ntile, int tid,
;                                                 f32x16 (&acc)[2][2], unsigned char* smem) {
;     ...
;     acc_foreach(tid, acc, [&](int row, int col, float v) {
;       int t = m0 + row;
;       float o = v;
;       if (mode == 1) o = (t >= NPADR) ? v : 0.f;
;       if (mode == 2) o = sigmf(v);
;       sT[row * 136 + col] = f2bf(o);
;     });
.LBB0_3466:
	v_bfe_u32 v50, v49, 16, 1
	v_add3_u32 v50, v49, v50, s83
	v_mul_lo_u32 v49, v48, s90
	v_lshl_add_u32 v48, v106, 1, v49
	ds_write_b16_d16_hi v48, v50
	v_add3_u32 v50, s88, v96, 33
	v_cmp_lt_i32_e64 s[10:11], s81, v50
	s_nop 1

; __device__ __forceinline__ float sigmf(float x) { return 1.f / (1.f + __expf(-x)); }
; __device__ __forceinline__ bf16r f2bf(float f) {
;   unsigned u = __float_as_uint(f);
;   u += 0x7fffu + ((u >> 16) & 1u);
;   return (bf16r)(u >> 16);
; }
; __device__ __forceinline__ void inproj_epilogue(const Params& p, int layer, int mt, int ntile, int tid,
;                                                 f32x16 (&acc)[2][2], unsigned char* smem) {
;     ...
;     acc_foreach(tid, acc, [&](int row, int col, float v) {
;       int t = m0 + row;
;       float o = v;
;       if (mode == 1) o = (t >= NPADR) ? v : 0.f;
;       if (mode == 2) o = sigmf(v);
;       sT[row * 136 + col] = f2bf(o);
;     });
.LBB0_3469:
	v_bfe_u32 v51, v50, 16, 1
	v_add3_u32 v51, v50, v51, s83
	v_add_u32_e32 v50, 0x110, v49
	v_lshl_add_u32 v49, v106, 1, v50
	ds_write_b16_d16_hi v49, v51
	v_add3_u32 v51, s88, v96, 34
	v_cmp_lt_i32_e64 s[12:13], s81, v51
	s_nop 1

; __device__ __forceinline__ float sigmf(float x) { return 1.f / (1.f + __expf(-x)); }
; __device__ __forceinline__ bf16r f2bf(float f) {
;   unsigned u = __float_as_uint(f);
;   u += 0x7fffu + ((u >> 16) & 1u);
;   return (bf16r)(u >> 16);
; }
; __device__ __forceinline__ void inproj_epilogue(const Params& p, int layer, int mt, int ntile, int tid,
;                                                 f32x16 (&acc)[2][2], unsigned char* smem) {
;     ...
;     acc_foreach(tid, acc, [&](int row, int col, float v) {
;       int t = m0 + row;
;       float o = v;
;       if (mode == 1) o = (t >= NPADR) ? v : 0.f;
;       if (mode == 2) o = sigmf(v);
;       sT[row * 136 + col] = f2bf(o);
;     });
.LBB0_3472:
	v_bfe_u32 v52, v51, 16, 1
	v_add3_u32 v52, v51, v52, s83
	v_add_u32_e32 v51, 0x110, v50
	v_lshl_add_u32 v50, v106, 1, v51
	ds_write_b16_d16_hi v50, v52
	v_add3_u32 v52, s88, v96, 35
	v_cmp_lt_i32_e64 s[14:15], s81, v52
	s_nop 1

; __device__ __forceinline__ float sigmf(float x) { return 1.f / (1.f + __expf(-x)); }
; __device__ __forceinline__ bf16r f2bf(float f) {
;   unsigned u = __float_as_uint(f);
;   u += 0x7fffu + ((u >> 16) & 1u);
;   return (bf16r)(u >> 16);
; }
; __device__ __forceinline__ void inproj_epilogue(const Params& p, int layer, int mt, int ntile, int tid,
;                                                 f32x16 (&acc)[2][2], unsigned char* smem) {
;     ...
;     acc_foreach(tid, acc, [&](int row, int col, float v) {
;       int t = m0 + row;
;       float o = v;
;       if (mode == 1) o = (t >= NPADR) ? v : 0.f;
;       if (mode == 2) o = sigmf(v);
;       sT[row * 136 + col] = f2bf(o);
;     });
.LBB0_3475:
	v_bfe_u32 v53, v52, 16, 1
	v_add3_u32 v53, v52, v53, s83
	v_add_u32_e32 v52, 0x110, v51
	v_lshl_add_u32 v51, v106, 1, v52
	ds_write_b16_d16_hi v51, v53
	v_add3_u32 v53, s88, v96, 40
	v_cmp_lt_i32_e64 s[16:17], s81, v53
	s_nop 1

; __device__ __forceinline__ float sigmf(float x) { return 1.f / (1.f + __expf(-x)); }
; __device__ __forceinline__ void inproj_epilogue(const Params& p, int layer, int mt, int ntile, int tid,
;                                                 f32x16 (&acc)[2][2], unsigned char* smem) {
;     ...
;     acc_foreach(tid, acc, [&](int row, int col, float v) {
;       int t = m0 + row;
;       float o = v;
;       if (mode == 1) o = (t >= NPADR) ? v : 0.f;
;       if (mode == 2) o = sigmf(v);
;       sT[row * 136 + col] = f2bf(o);
;     });
.LBB0_3478:
	v_bfe_u32 v54, v53, 16, 1
	v_add3_u32 v54, v53, v54, s83
	v_add_u32_e32 v53, 0x550, v52
	v_lshl_add_u32 v52, v106, 1, v53
	ds_write_b16_d16_hi v52, v54
	v_add3_u32 v54, s88, v96, 41
	v_cmp_lt_i32_e64 s[18:19], s81, v54
	s_nop 1

; __device__ __forceinline__ float sigmf(float x) { return 1.f / (1.f + __expf(-x)); }
; __device__ __forceinline__ void inproj_epilogue(const Params& p, int layer, int mt, int ntile, int tid,
;                                                 f32x16 (&acc)[2][2], unsigned char* smem) {
;     ...
;     acc_foreach(tid, acc, [&](int row, int col, float v) {
;       int t = m0 + row;
;       float o = v;
;       if (mode == 1) o = (t >= NPADR) ? v : 0.f;
;       if (mode == 2) o = sigmf(v);
;       sT[row * 136 + col] = f2bf(o);
;     });
.LBB0_3481:
	v_bfe_u32 v55, v54, 16, 1
	v_add3_u32 v55, v54, v55, s83
	v_add_u32_e32 v54, 0x110, v53
	v_lshl_add_u32 v53, v106, 1, v54
	ds_write_b16_d16_hi v53, v55
	v_add3_u32 v55, s88, v96, 42
	v_cmp_lt_i32_e64 s[20:21], s81, v55
	s_nop 1

; __device__ __forceinline__ float sigmf(float x) { return 1.f / (1.f + __expf(-x)); }
; __device__ __forceinline__ void inproj_epilogue(const Params& p, int layer, int mt, int ntile, int tid,
;                                                 f32x16 (&acc)[2][2], unsigned char* smem) {
;     ...
;     acc_foreach(tid, acc, [&](int row, int col, float v) {
;       int t = m0 + row;
;       float o = v;
;       if (mode == 1) o = (t >= NPADR) ? v : 0.f;
;       if (mode == 2) o = sigmf(v);
;       sT[row * 136 + col] = f2bf(o);
;     });
.LBB0_3484:
	v_bfe_u32 v56, v55, 16, 1
	v_add3_u32 v56, v55, v56, s83
	v_add_u32_e32 v55, 0x110, v54
	v_lshl_add_u32 v54, v106, 1, v55
	ds_write_b16_d16_hi v54, v56
	v_add3_u32 v56, s88, v96, 43
	v_cmp_lt_i32_e64 s[22:23], s81, v56
	s_nop 1

; __device__ __forceinline__ float sigmf(float x) { return 1.f / (1.f + __expf(-x)); }
; __device__ __forceinline__ void inproj_epilogue(const Params& p, int layer, int mt, int ntile, int tid,
;                                                 f32x16 (&acc)[2][2], unsigned char* smem) {
;     ...
;     acc_foreach(tid, acc, [&](int row, int col, float v) {
;       int t = m0 + row;
;       float o = v;
;       if (mode == 1) o = (t >= NPADR) ? v : 0.f;
;       if (mode == 2) o = sigmf(v);
;       sT[row * 136 + col] = f2bf(o);
;     });
.LBB0_3487:
	v_bfe_u32 v57, v56, 16, 1
	v_add_u32_e32 v55, 0x110, v55
	v_add3_u32 v57, v56, v57, s83
	v_lshl_add_u32 v56, v106, 1, v55
	ds_write_b16_d16_hi v56, v57
	v_add3_u32 v57, s88, v96, 48
	v_cmp_lt_i32_e64 s[24:25], s81, v57
	s_nop 1

; __device__ __forceinline__ float sigmf(float x) { return 1.f / (1.f + __expf(-x)); }
; __device__ __forceinline__ void inproj_epilogue(const Params& p, int layer, int mt, int ntile, int tid,
;                                                 f32x16 (&acc)[2][2], unsigned char* smem) {
;     ...
;     acc_foreach(tid, acc, [&](int row, int col, float v) {
;       int t = m0 + row;
;       float o = v;
;       if (mode == 1) o = (t >= NPADR) ? v : 0.f;
;       if (mode == 2) o = sigmf(v);
;       sT[row * 136 + col] = f2bf(o);
;     });
.LBB0_3490:
	v_bfe_u32 v58, v57, 16, 1
	v_add_u32_e32 v55, 0x550, v55
	v_add3_u32 v58, v57, v58, s83
	v_lshl_add_u32 v57, v106, 1, v55
	ds_write_b16_d16_hi v57, v58
	v_add3_u32 v58, s88, v96, 49
	v_cmp_lt_i32_e64 s[26:27], s81, v58
	s_nop 1

; __device__ __forceinline__ float sigmf(float x) { return 1.f / (1.f + __expf(-x)); }
; __device__ __forceinline__ void inproj_epilogue(const Params& p, int layer, int mt, int ntile, int tid,
;                                                 f32x16 (&acc)[2][2], unsigned char* smem) {
;     ...
;     acc_foreach(tid, acc, [&](int row, int col, float v) {
;       int t = m0 + row;
;       float o = v;
;       if (mode == 1) o = (t >= NPADR) ? v : 0.f;
;       if (mode == 2) o = sigmf(v);
;       sT[row * 136 + col] = f2bf(o);
;     });
.LBB0_3493:
	v_bfe_u32 v59, v58, 16, 1
	v_add_u32_e32 v55, 0x110, v55
	v_add3_u32 v59, v58, v59, s83
	v_lshl_add_u32 v58, v106, 1, v55
	ds_write_b16_d16_hi v58, v59
	v_add3_u32 v59, s88, v96, 50
	v_cmp_lt_i32_e64 s[28:29], s81, v59
	s_nop 1

; __device__ __forceinline__ float sigmf(float x) { return 1.f / (1.f + __expf(-x)); }
; __device__ __forceinline__ void inproj_epilogue(const Params& p, int layer, int mt, int ntile, int tid,
;                                                 f32x16 (&acc)[2][2], unsigned char* smem) {
;     ...
;     acc_foreach(tid, acc, [&](int row, int col, float v) {
;       int t = m0 + row;
;       float o = v;
;       if (mode == 1) o = (t >= NPADR) ? v : 0.f;
;       if (mode == 2) o = sigmf(v);
;       sT[row * 136 + col] = f2bf(o);
;     });
.LBB0_3496:
	v_bfe_u32 v60, v59, 16, 1
	v_add_u32_e32 v55, 0x110, v55
	v_add3_u32 v60, v59, v60, s83
	v_lshl_add_u32 v59, v106, 1, v55
	ds_write_b16_d16_hi v59, v60
	v_add3_u32 v60, s88, v96, 51
	v_cmp_lt_i32_e64 s[30:31], s81, v60
	s_nop 1

; __device__ __forceinline__ float sigmf(float x) { return 1.f / (1.f + __expf(-x)); }
; __device__ __forceinline__ void inproj_epilogue(const Params& p, int layer, int mt, int ntile, int tid,
;                                                 f32x16 (&acc)[2][2], unsigned char* smem) {
;     ...
;     acc_foreach(tid, acc, [&](int row, int col, float v) {
;       int t = m0 + row;
;       float o = v;
;       if (mode == 1) o = (t >= NPADR) ? v : 0.f;
;       if (mode == 2) o = sigmf(v);
;       sT[row * 136 + col] = f2bf(o);
;     });
.LBB0_3499:
	v_bfe_u32 v61, v60, 16, 1
	v_add_u32_e32 v55, 0x110, v55
	v_add3_u32 v61, v60, v61, s83
	v_lshl_add_u32 v60, v106, 1, v55
	ds_write_b16_d16_hi v60, v61
	v_add3_u32 v61, s88, v96, 56
	v_cmp_lt_i32_e64 s[34:35], s81, v61
	s_nop 1

; __device__ __forceinline__ float sigmf(float x) { return 1.f / (1.f + __expf(-x)); }
; __device__ __forceinline__ void inproj_epilogue(const Params& p, int layer, int mt, int ntile, int tid,
;                                                 f32x16 (&acc)[2][2], unsigned char* smem) {
;     ...
;     acc_foreach(tid, acc, [&](int row, int col, float v) {
;       int t = m0 + row;
;       float o = v;
;       if (mode == 1) o = (t >= NPADR) ? v : 0.f;
;       if (mode == 2) o = sigmf(v);
;       sT[row * 136 + col] = f2bf(o);
;     });
.LBB0_3502:
	v_bfe_u32 v62, v61, 16, 1
	v_add_u32_e32 v55, 0x550, v55
	v_add3_u32 v62, v61, v62, s83
	v_lshl_add_u32 v61, v106, 1, v55
	ds_write_b16_d16_hi v61, v62
	v_add3_u32 v62, s88, v96, 57
	v_cmp_lt_i32_e64 s[36:37], s81, v62
	s_nop 1

; __device__ __forceinline__ float sigmf(float x) { return 1.f / (1.f + __expf(-x)); }
; __device__ __forceinline__ void inproj_epilogue(const Params& p, int layer, int mt, int ntile, int tid,
;                                                 f32x16 (&acc)[2][2], unsigned char* smem) {
;     ...
;     acc_foreach(tid, acc, [&](int row, int col, float v) {
;       int t = m0 + row;
;       float o = v;
;       if (mode == 1) o = (t >= NPADR) ? v : 0.f;
;       if (mode == 2) o = sigmf(v);
;       sT[row * 136 + col] = f2bf(o);
;     });
.LBB0_3505:
	v_bfe_u32 v63, v62, 16, 1
	v_add_u32_e32 v55, 0x110, v55
	v_add3_u32 v63, v62, v63, s83
	v_lshl_add_u32 v62, v106, 1, v55
	ds_write_b16_d16_hi v62, v63
	v_add3_u32 v63, s88, v96, 58
	v_cmp_lt_i32_e64 s[38:39], s81, v63
	s_nop 1

; __device__ __forceinline__ float sigmf(float x) { return 1.f / (1.f + __expf(-x)); }
; __device__ __forceinline__ void inproj_epilogue(const Params& p, int layer, int mt, int ntile, int tid,
;                                                 f32x16 (&acc)[2][2], unsigned char* smem) {
;     ...
;     acc_foreach(tid, acc, [&](int row, int col, float v) {
;       int t = m0 + row;
;       float o = v;
;       if (mode == 1) o = (t >= NPADR) ? v : 0.f;
;       if (mode == 2) o = sigmf(v);
;       sT[row * 136 + col] = f2bf(o);
;     });
.LBB0_3508:
	v_bfe_u32 v107, v63, 16, 1
	v_add_u32_e32 v55, 0x110, v55
	v_add3_u32 v63, v63, v107, s83
	v_lshl_add_u32 v55, v106, 1, v55
	ds_write_b16_d16_hi v55, v63
	v_add3_u32 v63, s88, v96, 59
	v_cmp_lt_i32_e64 s[40:41], s81, v63
	s_nop 1

; __device__ __forceinline__ float sigmf(float x) { return 1.f / (1.f + __expf(-x)); }
; __device__ __forceinline__ void inproj_epilogue(const Params& p, int layer, int mt, int ntile, int tid,
;                                                 f32x16 (&acc)[2][2], unsigned char* smem) {
;     ...
;     acc_foreach(tid, acc, [&](int row, int col, float v) {
;       int t = m0 + row;
;       float o = v;
;       if (mode == 1) o = (t >= NPADR) ? v : 0.f;
;       if (mode == 2) o = sigmf(v);
;       sT[row * 136 + col] = f2bf(o);
;     });
.LBB0_3511:
	v_bfe_u32 v96, v63, 16, 1
	v_add3_u32 v63, v63, v96, s83
	ds_write_b16_d16_hi v55, v63 offset:272
	s_nop 1

; __device__ __forceinline__ float sigmf(float x) { return 1.f / (1.f + __expf(-x)); }
; __device__ __forceinline__ void inproj_epilogue(const Params& p, int layer, int mt, int ntile, int tid,
;                                                 f32x16 (&acc)[2][2], unsigned char* smem) {
;     ...
;     acc_foreach(tid, acc, [&](int row, int col, float v) {
;       int t = m0 + row;
;       float o = v;
;       if (mode == 1) o = (t >= NPADR) ? v : 0.f;
;       if (mode == 2) o = sigmf(v);
;       sT[row * 136 + col] = f2bf(o);
;     });
.LBB0_3514:
	v_bfe_u32 v63, v32, 16, 1
	v_add3_u32 v32, v32, v63, s83
	ds_write_b16_d16_hi v48, v32 offset:64
	s_nop 1

; __device__ __forceinline__ float sigmf(float x) { return 1.f / (1.f + __expf(-x)); }
; __device__ __forceinline__ void inproj_epilogue(const Params& p, int layer, int mt, int ntile, int tid,
;                                                 f32x16 (&acc)[2][2], unsigned char* smem) {
;     ...
;     acc_foreach(tid, acc, [&](int row, int col, float v) {
;       int t = m0 + row;
;       float o = v;
;       if (mode == 1) o = (t >= NPADR) ? v : 0.f;
;       if (mode == 2) o = sigmf(v);
;       sT[row * 136 + col] = f2bf(o);
;     });
.LBB0_3517:
	v_bfe_u32 v33, v32, 16, 1
	v_add3_u32 v32, v32, v33, s83
	ds_write_b16_d16_hi v49, v32 offset:64
	s_nop 1

; __device__ __forceinline__ float sigmf(float x) { return 1.f / (1.f + __expf(-x)); }
; __device__ __forceinline__ void inproj_epilogue(const Params& p, int layer, int mt, int ntile, int tid,
;                                                 f32x16 (&acc)[2][2], unsigned char* smem) {
;     ...
;     acc_foreach(tid, acc, [&](int row, int col, float v) {
;       int t = m0 + row;
;       float o = v;
;       if (mode == 1) o = (t >= NPADR) ? v : 0.f;
;       if (mode == 2) o = sigmf(v);
;       sT[row * 136 + col] = f2bf(o);
;     });
.LBB0_3520:
	v_bfe_u32 v33, v32, 16, 1
	v_add3_u32 v32, v32, v33, s83
	ds_write_b16_d16_hi v50, v32 offset:64
	s_nop 1

; __device__ __forceinline__ float sigmf(float x) { return 1.f / (1.f + __expf(-x)); }
; __device__ __forceinline__ void inproj_epilogue(const Params& p, int layer, int mt, int ntile, int tid,
;                                                 f32x16 (&acc)[2][2], unsigned char* smem) {
;     ...
;     acc_foreach(tid, acc, [&](int row, int col, float v) {
;       int t = m0 + row;
;       float o = v;
;       if (mode == 1) o = (t >= NPADR) ? v : 0.f;
;       if (mode == 2) o = sigmf(v);
;       sT[row * 136 + col] = f2bf(o);
;     });
.LBB0_3523:
	v_bfe_u32 v33, v32, 16, 1
	v_add3_u32 v32, v32, v33, s83
	ds_write_b16_d16_hi v51, v32 offset:64
	s_nop 1

; __device__ __forceinline__ float sigmf(float x) { return 1.f / (1.f + __expf(-x)); }
; __device__ __forceinline__ void inproj_epilogue(const Params& p, int layer, int mt, int ntile, int tid,
;                                                 f32x16 (&acc)[2][2], unsigned char* smem) {
;     ...
;     acc_foreach(tid, acc, [&](int row, int col, float v) {
;       int t = m0 + row;
;       float o = v;
;       if (mode == 1) o = (t >= NPADR) ? v : 0.f;
;       if (mode == 2) o = sigmf(v);
;       sT[row * 136 + col] = f2bf(o);
;     });
.LBB0_3526:
	v_bfe_u32 v33, v32, 16, 1
	v_add3_u32 v32, v32, v33, s83
	ds_write_b16_d16_hi v52, v32 offset:64
	s_nop 1

; __device__ __forceinline__ float sigmf(float x) { return 1.f / (1.f + __expf(-x)); }
; __device__ __forceinline__ void inproj_epilogue(const Params& p, int layer, int mt, int ntile, int tid,
;                                                 f32x16 (&acc)[2][2], unsigned char* smem) {
;     ...
;     acc_foreach(tid, acc, [&](int row, int col, float v) {
;       int t = m0 + row;
;       float o = v;
;       if (mode == 1) o = (t >= NPADR) ? v : 0.f;
;       if (mode == 2) o = sigmf(v);
;       sT[row * 136 + col] = f2bf(o);
;     });
.LBB0_3529:
	v_bfe_u32 v33, v32, 16, 1
	v_add3_u32 v32, v32, v33, s83
	ds_write_b16_d16_hi v53, v32 offset:64
	s_nop 1

; __device__ __forceinline__ float sigmf(float x) { return 1.f / (1.f + __expf(-x)); }
; __device__ __forceinline__ void inproj_epilogue(const Params& p, int layer, int mt, int ntile, int tid,
;                                                 f32x16 (&acc)[2][2], unsigned char* smem) {
;     ...
;     acc_foreach(tid, acc, [&](int row, int col, float v) {
;       int t = m0 + row;
;       float o = v;
;       if (mode == 1) o = (t >= NPADR) ? v : 0.f;
;       if (mode == 2) o = sigmf(v);
;       sT[row * 136 + col] = f2bf(o);
;     });
.LBB0_3532:
	v_bfe_u32 v33, v32, 16, 1
	v_add3_u32 v32, v32, v33, s83
	ds_write_b16_d16_hi v54, v32 offset:64
	s_nop 1

; __device__ __forceinline__ float sigmf(float x) { return 1.f / (1.f + __expf(-x)); }
; __device__ __forceinline__ void inproj_epilogue(const Params& p, int layer, int mt, int ntile, int tid,
;                                                 f32x16 (&acc)[2][2], unsigned char* smem) {
;     ...
;     acc_foreach(tid, acc, [&](int row, int col, float v) {
;       int t = m0 + row;
;       float o = v;
;       if (mode == 1) o = (t >= NPADR) ? v : 0.f;
;       if (mode == 2) o = sigmf(v);
;       sT[row * 136 + col] = f2bf(o);
;     });
.LBB0_3535:
	v_bfe_u32 v33, v32, 16, 1
	v_add3_u32 v32, v32, v33, s83
	ds_write_b16_d16_hi v56, v32 offset:64
	s_nop 1

; __device__ __forceinline__ float sigmf(float x) { return 1.f / (1.f + __expf(-x)); }
; __device__ __forceinline__ void inproj_epilogue(const Params& p, int layer, int mt, int ntile, int tid,
;                                                 f32x16 (&acc)[2][2], unsigned char* smem) {
;     ...
;     acc_foreach(tid, acc, [&](int row, int col, float v) {
;       int t = m0 + row;
;       float o = v;
;       if (mode == 1) o = (t >= NPADR) ? v : 0.f;
;       if (mode == 2) o = sigmf(v);
;       sT[row * 136 + col] = f2bf(o);
;     });
.LBB0_3538:
	v_bfe_u32 v33, v32, 16, 1
	v_add3_u32 v32, v32, v33, s83
	ds_write_b16_d16_hi v57, v32 offset:64
	s_nop 1

; __device__ __forceinline__ float sigmf(float x) { return 1.f / (1.f + __expf(-x)); }
; __device__ __forceinline__ void inproj_epilogue(const Params& p, int layer, int mt, int ntile, int tid,
;                                                 f32x16 (&acc)[2][2], unsigned char* smem) {
;     ...
;     acc_foreach(tid, acc, [&](int row, int col, float v) {
;       int t = m0 + row;
;       float o = v;
;       if (mode == 1) o = (t >= NPADR) ? v : 0.f;
;       if (mode == 2) o = sigmf(v);
;       sT[row * 136 + col] = f2bf(o);
;     });
.LBB0_3541:
	v_bfe_u32 v33, v32, 16, 1
	v_add3_u32 v32, v32, v33, s83
	ds_write_b16_d16_hi v58, v32 offset:64
	s_nop 1

; __device__ __forceinline__ float sigmf(float x) { return 1.f / (1.f + __expf(-x)); }
; __device__ __forceinline__ void inproj_epilogue(const Params& p, int layer, int mt, int ntile, int tid,
;                                                 f32x16 (&acc)[2][2], unsigned char* smem) {
;     ...
;     acc_foreach(tid, acc, [&](int row, int col, float v) {
;       int t = m0 + row;
;       float o = v;
;       if (mode == 1) o = (t >= NPADR) ? v : 0.f;
;       if (mode == 2) o = sigmf(v);
;       sT[row * 136 + col] = f2bf(o);
;     });
.LBB0_3544:
	v_bfe_u32 v33, v32, 16, 1
	v_add3_u32 v32, v32, v33, s83
	ds_write_b16_d16_hi v59, v32 offset:64
	s_nop 1

; __device__ __forceinline__ float sigmf(float x) { return 1.f / (1.f + __expf(-x)); }
; __device__ __forceinline__ void inproj_epilogue(const Params& p, int layer, int mt, int ntile, int tid,
;                                                 f32x16 (&acc)[2][2], unsigned char* smem) {
;     ...
;     acc_foreach(tid, acc, [&](int row, int col, float v) {
;       int t = m0 + row;
;       float o = v;
;       if (mode == 1) o = (t >= NPADR) ? v : 0.f;
;       if (mode == 2) o = sigmf(v);
;       sT[row * 136 + col] = f2bf(o);
;     });
.LBB0_3547:
	v_bfe_u32 v33, v32, 16, 1
	v_add3_u32 v32, v32, v33, s83
	ds_write_b16_d16_hi v60, v32 offset:64
	s_nop 1

; __device__ __forceinline__ float sigmf(float x) { return 1.f / (1.f + __expf(-x)); }
; __device__ __forceinline__ void inproj_epilogue(const Params& p, int layer, int mt, int ntile, int tid,
;                                                 f32x16 (&acc)[2][2], unsigned char* smem) {
;     ...
;     acc_foreach(tid, acc, [&](int row, int col, float v) {
;       int t = m0 + row;
;       float o = v;
;       if (mode == 1) o = (t >= NPADR) ? v : 0.f;
;       if (mode == 2) o = sigmf(v);
;       sT[row * 136 + col] = f2bf(o);
;     });
.LBB0_3550:
	v_bfe_u32 v33, v32, 16, 1
	v_add3_u32 v32, v32, v33, s83
	ds_write_b16_d16_hi v61, v32 offset:64
	s_nop 1

; __device__ __forceinline__ float sigmf(float x) { return 1.f / (1.f + __expf(-x)); }
; __device__ __forceinline__ void inproj_epilogue(const Params& p, int layer, int mt, int ntile, int tid,
;                                                 f32x16 (&acc)[2][2], unsigned char* smem) {
;     ...
;     acc_foreach(tid, acc, [&](int row, int col, float v) {
;       int t = m0 + row;
;       float o = v;
;       if (mode == 1) o = (t >= NPADR) ? v : 0.f;
;       if (mode == 2) o = sigmf(v);
;       sT[row * 136 + col] = f2bf(o);
;     });
.LBB0_3553:
	v_bfe_u32 v33, v32, 16, 1
	v_add3_u32 v32, v32, v33, s83
	ds_write_b16_d16_hi v62, v32 offset:64
	s_nop 1

; __device__ __forceinline__ float sigmf(float x) { return 1.f / (1.f + __expf(-x)); }
; __device__ __forceinline__ void inproj_epilogue(const Params& p, int layer, int mt, int ntile, int tid,
;                                                 f32x16 (&acc)[2][2], unsigned char* smem) {
;     ...
;     acc_foreach(tid, acc, [&](int row, int col, float v) {
;       int t = m0 + row;
;       float o = v;
;       if (mode == 1) o = (t >= NPADR) ? v : 0.f;
;       if (mode == 2) o = sigmf(v);
;       sT[row * 136 + col] = f2bf(o);
;     });
.LBB0_3556:
	v_bfe_u32 v33, v32, 16, 1
	v_add3_u32 v32, v32, v33, s83
	ds_write_b16_d16_hi v55, v32 offset:64
	s_nop 1

; __device__ __forceinline__ bf16r f2bf(float f) {
;   unsigned u = __float_as_uint(f);
;   u += 0x7fffu + ((u >> 16) & 1u);
;   return (bf16r)(u >> 16);
; }
; __device__ __forceinline__ float sigmf(float x) { return 1.f / (1.f + __expf(-x)); }
; __device__ __forceinline__ void inproj_epilogue(const Params& p, int layer, int mt, int ntile, int tid,
;                                                 f32x16 (&acc)[2][2], unsigned char* smem) {
;     ...
;       if (mode == 2) o = sigmf(v);
;       sT[row * 136 + col] = f2bf(o);
.Lgv_7:
	v_mul_f32_e32 v107, 0xbfb8aa3b, v16
	v_exp_f32_e32 v107, v107
	s_nop 0
	v_add_f32_e32 v107, 1.0, v107
	v_div_scale_f32 v110, s[6:7], v107, v107, 1.0
	v_rcp_f32_e32 v111, v110
	v_div_scale_f32 v112, vcc, 1.0, v107, 1.0
	v_fma_f32 v113, -v110, v111, 1.0
	v_fmac_f32_e32 v111, v113, v111
	v_mul_f32_e32 v113, v112, v111
	v_fma_f32 v114, -v110, v113, v112
	v_fmac_f32_e32 v113, v114, v111
	v_fma_f32 v110, -v110, v113, v112
	v_div_fmas_f32 v110, v110, v111, v113
	v_div_fixup_f32 v107, v110, v107, 1.0
	v_bfe_u32 v110, v107, 16, 1
	v_and_b32_e32 v106, 0x5f, v106
	v_add3_u32 v111, v107, v110, s83
	v_mul_lo_u32 v110, v96, s90
	v_lshl_add_u32 v107, v106, 1, v110
	ds_write_b16_d16_hi v107, v111
	v_add3_u32 v111, s88, v96, 1
	v_cndmask_b32_e64 v112, 0, 1, s[10:11]
	v_cmp_ne_u32_e64 s[6:7], 1, v112
	s_andn2_b64 vcc, exec, s[10:11]
	v_cmp_lt_i32_e64 s[10:11], s81, v111
	v_mul_f32_e32 v111, 0xbfb8aa3b, v17
	v_exp_f32_e32 v111, v111
	s_nop 0
	v_add_f32_e32 v111, 1.0, v111
	v_div_scale_f32 v112, s[12:13], v111, v111, 1.0
	v_rcp_f32_e32 v113, v112
	v_div_scale_f32 v114, vcc, 1.0, v111, 1.0
	v_fma_f32 v115, -v112, v113, 1.0
	v_fmac_f32_e32 v113, v115, v113
	v_mul_f32_e32 v115, v114, v113
	v_fma_f32 v116, -v112, v115, v114
	v_fmac_f32_e32 v115, v116, v113
	v_fma_f32 v112, -v112, v115, v114
	v_div_fmas_f32 v112, v112, v113, v115
	v_div_fixup_f32 v111, v112, v111, 1.0
	v_bfe_u32 v112, v111, 16, 1
	v_add3_u32 v112, v111, v112, s83
	v_add_u32_e32 v111, 0x110, v110
	v_lshl_add_u32 v110, v106, 1, v111
	ds_write_b16_d16_hi v110, v112
	v_add3_u32 v112, s88, v96, 2
	s_and_b64 vcc, exec, s[6:7]
	v_cmp_lt_i32_e64 s[12:13], s81, v112
	v_mul_f32_e32 v112, 0xbfb8aa3b, v18
	v_exp_f32_e32 v112, v112
	s_nop 0
	v_add_f32_e32 v112, 1.0, v112
	v_div_scale_f32 v113, s[14:15], v112, v112, 1.0
	v_rcp_f32_e32 v114, v113
	v_div_scale_f32 v115, vcc, 1.0, v112, 1.0
	v_fma_f32 v116, -v113, v114, 1.0
	v_fmac_f32_e32 v114, v116, v114
	v_mul_f32_e32 v116, v115, v114
	v_fma_f32 v117, -v113, v116, v115
	v_fmac_f32_e32 v116, v117, v114
	v_fma_f32 v113, -v113, v116, v115
	v_div_fmas_f32 v113, v113, v114, v116
	v_div_fixup_f32 v112, v113, v112, 1.0
	v_bfe_u32 v113, v112, 16, 1
	v_add3_u32 v113, v112, v113, s83
	v_add_u32_e32 v112, 0x110, v111
	v_lshl_add_u32 v111, v106, 1, v112
	ds_write_b16_d16_hi v111, v113
	v_add3_u32 v113, s88, v96, 3
	s_and_b64 vcc, exec, s[6:7]
	v_cmp_lt_i32_e64 s[14:15], s81, v113
	v_mul_f32_e32 v113, 0xbfb8aa3b, v19
	v_exp_f32_e32 v113, v113
	s_nop 0
	v_add_f32_e32 v113, 1.0, v113
	v_div_scale_f32 v114, s[16:17], v113, v113, 1.0
	v_rcp_f32_e32 v115, v114
	v_div_scale_f32 v116, vcc, 1.0, v113, 1.0
	v_fma_f32 v117, -v114, v115, 1.0
	v_fmac_f32_e32 v115, v117, v115
	v_mul_f32_e32 v117, v116, v115
	v_fma_f32 v118, -v114, v117, v116
	v_fmac_f32_e32 v117, v118, v115
	v_fma_f32 v114, -v114, v117, v116
	v_div_fmas_f32 v114, v114, v115, v117
	v_div_fixup_f32 v113, v114, v113, 1.0
	v_bfe_u32 v114, v113, 16, 1
	v_add3_u32 v114, v113, v114, s83
	v_add_u32_e32 v113, 0x110, v112
	v_lshl_add_u32 v112, v106, 1, v113
	ds_write_b16_d16_hi v112, v114
	v_add3_u32 v114, s88, v96, 8
	s_and_b64 vcc, exec, s[6:7]
	v_cmp_lt_i32_e64 s[16:17], s81, v114
	v_mul_f32_e32 v114, 0xbfb8aa3b, v20
	v_exp_f32_e32 v114, v114
	s_nop 0
	v_add_f32_e32 v114, 1.0, v114
	v_div_scale_f32 v115, s[18:19], v114, v114, 1.0
	v_rcp_f32_e32 v116, v115
	v_div_scale_f32 v117, vcc, 1.0, v114, 1.0
	v_fma_f32 v118, -v115, v116, 1.0
	v_fmac_f32_e32 v116, v118, v116
	v_mul_f32_e32 v118, v117, v116
	v_fma_f32 v119, -v115, v118, v117
	v_fmac_f32_e32 v118, v119, v116
	v_fma_f32 v115, -v115, v118, v117
	v_div_fmas_f32 v115, v115, v116, v118
	v_div_fixup_f32 v114, v115, v114, 1.0
	v_bfe_u32 v115, v114, 16, 1
	v_add3_u32 v115, v114, v115, s83
	v_add_u32_e32 v114, 0x550, v113
	v_lshl_add_u32 v113, v106, 1, v114
	ds_write_b16_d16_hi v113, v115
	v_add3_u32 v115, s88, v96, 9
	s_and_b64 vcc, exec, s[6:7]
	v_cmp_lt_i32_e64 s[18:19], s81, v115
	v_mul_f32_e32 v115, 0xbfb8aa3b, v21
	v_exp_f32_e32 v115, v115
	s_nop 0
	v_add_f32_e32 v115, 1.0, v115
	v_div_scale_f32 v116, s[20:21], v115, v115, 1.0
	v_rcp_f32_e32 v117, v116
	v_div_scale_f32 v118, vcc, 1.0, v115, 1.0
	v_fma_f32 v119, -v116, v117, 1.0
	v_fmac_f32_e32 v117, v119, v117
	v_mul_f32_e32 v119, v118, v117
	v_fma_f32 v120, -v116, v119, v118
	v_fmac_f32_e32 v119, v120, v117
	v_fma_f32 v116, -v116, v119, v118
	v_div_fmas_f32 v116, v116, v117, v119
	v_div_fixup_f32 v115, v116, v115, 1.0
	v_bfe_u32 v116, v115, 16, 1
	v_add3_u32 v116, v115, v116, s83
	v_add_u32_e32 v115, 0x110, v114
	v_lshl_add_u32 v114, v106, 1, v115
	ds_write_b16_d16_hi v114, v116
	v_add3_u32 v116, s88, v96, 10
	s_and_b64 vcc, exec, s[6:7]
	v_cmp_lt_i32_e64 s[20:21], s81, v116
	v_mul_f32_e32 v116, 0xbfb8aa3b, v22
	v_exp_f32_e32 v116, v116
	s_nop 0
	v_add_f32_e32 v116, 1.0, v116
	v_div_scale_f32 v117, s[22:23], v116, v116, 1.0
	v_rcp_f32_e32 v118, v117
	v_div_scale_f32 v119, vcc, 1.0, v116, 1.0
	v_fma_f32 v120, -v117, v118, 1.0
	v_fmac_f32_e32 v118, v120, v118
	v_mul_f32_e32 v120, v119, v118
	v_fma_f32 v121, -v117, v120, v119
	v_fmac_f32_e32 v120, v121, v118
	v_fma_f32 v117, -v117, v120, v119
	v_div_fmas_f32 v117, v117, v118, v120
	v_div_fixup_f32 v116, v117, v116, 1.0
	v_bfe_u32 v117, v116, 16, 1
	v_add3_u32 v117, v116, v117, s83
	v_add_u32_e32 v116, 0x110, v115
	v_lshl_add_u32 v115, v106, 1, v116
	ds_write_b16_d16_hi v115, v117
	v_add3_u32 v117, s88, v96, 11
	s_and_b64 vcc, exec, s[6:7]
	v_cmp_lt_i32_e64 s[22:23], s81, v117
	v_mul_f32_e32 v117, 0xbfb8aa3b, v23
	v_exp_f32_e32 v117, v117
	s_nop 0
	v_add_f32_e32 v117, 1.0, v117
	v_div_scale_f32 v118, s[24:25], v117, v117, 1.0
	v_rcp_f32_e32 v119, v118
; __device__ __forceinline__ bf16r f2bf(float f) {
;   unsigned u = __float_as_uint(f);
;   u += 0x7fffu + ((u >> 16) & 1u);
;   return (bf16r)(u >> 16);
; }
; __device__ __forceinline__ float sigmf(float x) { return 1.f / (1.f + __expf(-x)); }
; __device__ __forceinline__ void inproj_epilogue(const Params& p, int layer, int mt, int ntile, int tid,
;                                                 f32x16 (&acc)[2][2], unsigned char* smem) {
;     ...
;       if (mode == 2) o = sigmf(v);
;       sT[row * 136 + col] = f2bf(o);
	v_div_scale_f32 v120, vcc, 1.0, v117, 1.0
	v_fma_f32 v121, -v118, v119, 1.0
	v_fmac_f32_e32 v119, v121, v119
	v_mul_f32_e32 v121, v120, v119
	v_fma_f32 v122, -v118, v121, v120
	v_fmac_f32_e32 v121, v122, v119
	v_fma_f32 v118, -v118, v121, v120
	v_div_fmas_f32 v118, v118, v119, v121
	v_div_fixup_f32 v117, v118, v117, 1.0
	v_bfe_u32 v118, v117, 16, 1
	v_add_u32_e32 v116, 0x110, v116
	v_add3_u32 v118, v117, v118, s83
	v_lshl_add_u32 v117, v106, 1, v116
	ds_write_b16_d16_hi v117, v118
	v_add3_u32 v118, s88, v96, 16
	s_and_b64 vcc, exec, s[6:7]
	v_cmp_lt_i32_e64 s[24:25], s81, v118
	v_mul_f32_e32 v118, 0xbfb8aa3b, v24
	v_exp_f32_e32 v118, v118
	s_nop 0
	v_add_f32_e32 v118, 1.0, v118
	v_div_scale_f32 v119, s[26:27], v118, v118, 1.0
	v_rcp_f32_e32 v120, v119
	v_div_scale_f32 v121, vcc, 1.0, v118, 1.0
	v_fma_f32 v122, -v119, v120, 1.0
	v_fmac_f32_e32 v120, v122, v120
	v_mul_f32_e32 v122, v121, v120
	v_fma_f32 v123, -v119, v122, v121
	v_fmac_f32_e32 v122, v123, v120
	v_fma_f32 v119, -v119, v122, v121
	v_div_fmas_f32 v119, v119, v120, v122
	v_div_fixup_f32 v118, v119, v118, 1.0
	v_bfe_u32 v119, v118, 16, 1
	v_add_u32_e32 v116, 0x550, v116
	v_add3_u32 v119, v118, v119, s83
	v_lshl_add_u32 v118, v106, 1, v116
	ds_write_b16_d16_hi v118, v119
	v_add3_u32 v119, s88, v96, 17
	s_and_b64 vcc, exec, s[6:7]
	v_cmp_lt_i32_e64 s[26:27], s81, v119
	v_mul_f32_e32 v119, 0xbfb8aa3b, v25
	v_exp_f32_e32 v119, v119
	s_nop 0
	v_add_f32_e32 v119, 1.0, v119
	v_div_scale_f32 v120, s[28:29], v119, v119, 1.0
	v_rcp_f32_e32 v121, v120
	v_div_scale_f32 v122, vcc, 1.0, v119, 1.0
	v_fma_f32 v123, -v120, v121, 1.0
	v_fmac_f32_e32 v121, v123, v121
	v_mul_f32_e32 v123, v122, v121
	v_fma_f32 v124, -v120, v123, v122
	v_fmac_f32_e32 v123, v124, v121
	v_fma_f32 v120, -v120, v123, v122
	v_div_fmas_f32 v120, v120, v121, v123
	v_div_fixup_f32 v119, v120, v119, 1.0
	v_bfe_u32 v120, v119, 16, 1
	v_add_u32_e32 v116, 0x110, v116
	v_add3_u32 v120, v119, v120, s83
	v_lshl_add_u32 v119, v106, 1, v116
	ds_write_b16_d16_hi v119, v120
	v_add3_u32 v120, s88, v96, 18
	s_and_b64 vcc, exec, s[6:7]
	v_cmp_lt_i32_e64 s[28:29], s81, v120
	v_mul_f32_e32 v120, 0xbfb8aa3b, v26
	v_exp_f32_e32 v120, v120
	s_nop 0
	v_add_f32_e32 v120, 1.0, v120
	v_div_scale_f32 v121, s[30:31], v120, v120, 1.0
	v_rcp_f32_e32 v122, v121
	v_div_scale_f32 v123, vcc, 1.0, v120, 1.0
	v_fma_f32 v124, -v121, v122, 1.0
	v_fmac_f32_e32 v122, v124, v122
	v_mul_f32_e32 v124, v123, v122
	v_fma_f32 v125, -v121, v124, v123
	v_fmac_f32_e32 v124, v125, v122
	v_fma_f32 v121, -v121, v124, v123
	v_div_fmas_f32 v121, v121, v122, v124
	v_div_fixup_f32 v120, v121, v120, 1.0
	v_bfe_u32 v121, v120, 16, 1
	v_add_u32_e32 v116, 0x110, v116
	v_add3_u32 v121, v120, v121, s83
	v_lshl_add_u32 v120, v106, 1, v116
	ds_write_b16_d16_hi v120, v121
	v_add3_u32 v121, s88, v96, 19
	s_and_b64 vcc, exec, s[6:7]
	v_cmp_lt_i32_e64 s[30:31], s81, v121
	v_mul_f32_e32 v121, 0xbfb8aa3b, v27
	v_exp_f32_e32 v121, v121
	s_nop 0
	v_add_f32_e32 v121, 1.0, v121
	v_div_scale_f32 v122, s[34:35], v121, v121, 1.0
	v_rcp_f32_e32 v123, v122
	v_div_scale_f32 v124, vcc, 1.0, v121, 1.0
	v_fma_f32 v125, -v122, v123, 1.0
	v_fmac_f32_e32 v123, v125, v123
	v_mul_f32_e32 v125, v124, v123
	v_fma_f32 v126, -v122, v125, v124
	v_fmac_f32_e32 v125, v126, v123
	v_fma_f32 v122, -v122, v125, v124
	v_div_fmas_f32 v122, v122, v123, v125
	v_div_fixup_f32 v121, v122, v121, 1.0
	v_bfe_u32 v122, v121, 16, 1
	v_add_u32_e32 v116, 0x110, v116
	v_add3_u32 v122, v121, v122, s83
	v_lshl_add_u32 v121, v106, 1, v116
	ds_write_b16_d16_hi v121, v122
	v_add3_u32 v122, s88, v96, 24
	s_and_b64 vcc, exec, s[6:7]
	v_cmp_lt_i32_e64 s[34:35], s81, v122
	v_mul_f32_e32 v122, 0xbfb8aa3b, v28
	v_exp_f32_e32 v122, v122
	s_nop 0
	v_add_f32_e32 v122, 1.0, v122
	v_div_scale_f32 v123, s[36:37], v122, v122, 1.0
	v_rcp_f32_e32 v124, v123
	v_div_scale_f32 v125, vcc, 1.0, v122, 1.0
	v_fma_f32 v126, -v123, v124, 1.0
	v_fmac_f32_e32 v124, v126, v124
	v_mul_f32_e32 v126, v125, v124
	v_fma_f32 v127, -v123, v126, v125
	v_fmac_f32_e32 v126, v127, v124
	v_fma_f32 v123, -v123, v126, v125
	v_div_fmas_f32 v123, v123, v124, v126
	v_div_fixup_f32 v122, v123, v122, 1.0
	v_bfe_u32 v123, v122, 16, 1
	v_add_u32_e32 v116, 0x550, v116
	v_add3_u32 v123, v122, v123, s83
	v_lshl_add_u32 v122, v106, 1, v116
	ds_write_b16_d16_hi v122, v123
	v_add3_u32 v123, s88, v96, 25
	s_and_b64 vcc, exec, s[6:7]
	v_cmp_lt_i32_e64 s[36:37], s81, v123
	v_mul_f32_e32 v123, 0xbfb8aa3b, v29
	v_exp_f32_e32 v123, v123
	s_nop 0
	v_add_f32_e32 v123, 1.0, v123
	v_div_scale_f32 v124, s[38:39], v123, v123, 1.0
	v_rcp_f32_e32 v125, v124
	v_div_scale_f32 v126, vcc, 1.0, v123, 1.0
	v_fma_f32 v127, -v124, v125, 1.0
	v_fmac_f32_e32 v125, v127, v125
	v_mul_f32_e32 v127, v126, v125
	v_fma_f32 v128, -v124, v127, v126
	v_fmac_f32_e32 v127, v128, v125
	v_fma_f32 v124, -v124, v127, v126
	v_div_fmas_f32 v124, v124, v125, v127
	v_div_fixup_f32 v123, v124, v123, 1.0
	v_bfe_u32 v124, v123, 16, 1
	v_add_u32_e32 v116, 0x110, v116
	v_add3_u32 v124, v123, v124, s83
	v_lshl_add_u32 v123, v106, 1, v116
	ds_write_b16_d16_hi v123, v124
	v_add3_u32 v124, s88, v96, 26
	s_and_b64 vcc, exec, s[6:7]
	v_cmp_lt_i32_e64 s[38:39], s81, v124
	v_mul_f32_e32 v124, 0xbfb8aa3b, v30
	v_exp_f32_e32 v124, v124
	s_nop 0
	v_add_f32_e32 v124, 1.0, v124
	v_div_scale_f32 v125, s[40:41], v124, v124, 1.0
	v_rcp_f32_e32 v126, v125
	v_div_scale_f32 v127, vcc, 1.0, v124, 1.0
	v_fma_f32 v128, -v125, v126, 1.0
	v_fmac_f32_e32 v126, v128, v126
	v_mul_f32_e32 v128, v127, v126
	v_fma_f32 v129, -v125, v128, v127
	v_fmac_f32_e32 v128, v129, v126
	v_fma_f32 v125, -v125, v128, v127
	v_div_fmas_f32 v125, v125, v126, v128
; __device__ __forceinline__ bf16r f2bf(float f) {
;   unsigned u = __float_as_uint(f);
;   u += 0x7fffu + ((u >> 16) & 1u);
;   return (bf16r)(u >> 16);
; }
; __device__ __forceinline__ float sigmf(float x) { return 1.f / (1.f + __expf(-x)); }
; __device__ __forceinline__ void inproj_epilogue(const Params& p, int layer, int mt, int ntile, int tid,
;                                                 f32x16 (&acc)[2][2], unsigned char* smem) {
;     ...
;       if (mode == 2) o = sigmf(v);
;       sT[row * 136 + col] = f2bf(o);
	v_div_fixup_f32 v124, v125, v124, 1.0
	v_bfe_u32 v125, v124, 16, 1
	v_add_u32_e32 v116, 0x110, v116
	v_add3_u32 v124, v124, v125, s83
	v_lshl_add_u32 v116, v106, 1, v116
	ds_write_b16_d16_hi v116, v124
	v_add3_u32 v124, s88, v96, 27
	s_and_b64 vcc, exec, s[6:7]
	v_cmp_lt_i32_e64 s[40:41], s81, v124
	v_mul_f32_e32 v124, 0xbfb8aa3b, v31
	v_exp_f32_e32 v124, v124
	s_nop 0
	v_add_f32_e32 v124, 1.0, v124
	v_div_scale_f32 v125, s[96:97], v124, v124, 1.0
	v_rcp_f32_e32 v126, v125
	v_div_scale_f32 v127, vcc, 1.0, v124, 1.0
	v_fma_f32 v128, -v125, v126, 1.0
	v_fmac_f32_e32 v126, v128, v126
	v_mul_f32_e32 v128, v127, v126
	v_fma_f32 v129, -v125, v128, v127
	v_fmac_f32_e32 v128, v129, v126
	v_fma_f32 v125, -v125, v128, v127
	v_div_fmas_f32 v125, v125, v126, v128
	v_div_fixup_f32 v124, v125, v124, 1.0
	v_bfe_u32 v125, v124, 16, 1
	v_add3_u32 v124, v124, v125, s83
	ds_write_b16_d16_hi v116, v124 offset:272
	s_and_b64 vcc, exec, s[6:7]
	v_mul_f32_e32 v48, 0xbfb8aa3b, v48
	v_exp_f32_e32 v48, v48
	s_nop 0
	v_add_f32_e32 v48, 1.0, v48
	v_div_scale_f32 v124, s[8:9], v48, v48, 1.0
	v_rcp_f32_e32 v125, v124
	v_div_scale_f32 v126, vcc, 1.0, v48, 1.0
	v_fma_f32 v127, -v124, v125, 1.0
	v_fmac_f32_e32 v125, v127, v125
	v_mul_f32_e32 v127, v126, v125
	v_fma_f32 v128, -v124, v127, v126
	v_fmac_f32_e32 v127, v128, v125
	v_fma_f32 v124, -v124, v127, v126
	v_div_fmas_f32 v124, v124, v125, v127
	v_div_fixup_f32 v48, v124, v48, 1.0
	v_bfe_u32 v124, v48, 16, 1
	v_add3_u32 v48, v48, v124, s83
	s_and_b64 vcc, exec, s[6:7]
	ds_write_b16_d16_hi v107, v48 offset:64
	v_mul_f32_e32 v48, 0xbfb8aa3b, v49
	v_exp_f32_e32 v48, v48
	s_nop 0
	v_add_f32_e32 v48, 1.0, v48
	v_div_scale_f32 v49, s[8:9], v48, v48, 1.0
	v_rcp_f32_e32 v107, v49
	v_div_scale_f32 v124, vcc, 1.0, v48, 1.0
	v_fma_f32 v125, -v49, v107, 1.0
	v_fmac_f32_e32 v107, v125, v107
	v_mul_f32_e32 v125, v124, v107
	v_fma_f32 v126, -v49, v125, v124
	v_fmac_f32_e32 v125, v126, v107
	v_fma_f32 v49, -v49, v125, v124
	v_div_fmas_f32 v49, v49, v107, v125
	v_div_fixup_f32 v48, v49, v48, 1.0
	v_bfe_u32 v49, v48, 16, 1
	v_add3_u32 v48, v48, v49, s83
	s_and_b64 vcc, exec, s[6:7]
	ds_write_b16_d16_hi v110, v48 offset:64
	v_mul_f32_e32 v48, 0xbfb8aa3b, v50
	v_exp_f32_e32 v48, v48
	s_nop 0
	v_add_f32_e32 v48, 1.0, v48
	v_div_scale_f32 v49, s[8:9], v48, v48, 1.0
	v_rcp_f32_e32 v50, v49
	v_div_scale_f32 v107, vcc, 1.0, v48, 1.0
	v_fma_f32 v110, -v49, v50, 1.0
	v_fmac_f32_e32 v50, v110, v50
	v_mul_f32_e32 v110, v107, v50
	v_fma_f32 v124, -v49, v110, v107
	v_fmac_f32_e32 v110, v124, v50
	v_fma_f32 v49, -v49, v110, v107
	v_div_fmas_f32 v49, v49, v50, v110
	v_div_fixup_f32 v48, v49, v48, 1.0
	v_bfe_u32 v49, v48, 16, 1
	v_add3_u32 v48, v48, v49, s83
	s_and_b64 vcc, exec, s[6:7]
	ds_write_b16_d16_hi v111, v48 offset:64
	v_mul_f32_e32 v48, 0xbfb8aa3b, v51
	v_exp_f32_e32 v48, v48
	s_nop 0
	v_add_f32_e32 v48, 1.0, v48
	v_div_scale_f32 v49, s[8:9], v48, v48, 1.0
	v_rcp_f32_e32 v50, v49
	v_div_scale_f32 v51, vcc, 1.0, v48, 1.0
	v_fma_f32 v107, -v49, v50, 1.0
	v_fmac_f32_e32 v50, v107, v50
	v_mul_f32_e32 v107, v51, v50
	v_fma_f32 v110, -v49, v107, v51
	v_fmac_f32_e32 v107, v110, v50
	v_fma_f32 v49, -v49, v107, v51
	v_div_fmas_f32 v49, v49, v50, v107
	v_div_fixup_f32 v48, v49, v48, 1.0
	v_bfe_u32 v49, v48, 16, 1
	v_add3_u32 v48, v48, v49, s83
	s_and_b64 vcc, exec, s[6:7]
	ds_write_b16_d16_hi v112, v48 offset:64
	v_mul_f32_e32 v48, 0xbfb8aa3b, v52
	v_exp_f32_e32 v48, v48
	s_nop 0
	v_add_f32_e32 v48, 1.0, v48
	v_div_scale_f32 v49, s[8:9], v48, v48, 1.0
	v_rcp_f32_e32 v50, v49
	v_div_scale_f32 v51, vcc, 1.0, v48, 1.0
	v_fma_f32 v52, -v49, v50, 1.0
	v_fmac_f32_e32 v50, v52, v50
	v_mul_f32_e32 v52, v51, v50
	v_fma_f32 v107, -v49, v52, v51
	v_fmac_f32_e32 v52, v107, v50
	v_fma_f32 v49, -v49, v52, v51
	v_div_fmas_f32 v49, v49, v50, v52
	v_div_fixup_f32 v48, v49, v48, 1.0
	v_bfe_u32 v49, v48, 16, 1
	v_add3_u32 v48, v48, v49, s83
	s_and_b64 vcc, exec, s[6:7]
	ds_write_b16_d16_hi v113, v48 offset:64
	v_mul_f32_e32 v48, 0xbfb8aa3b, v53
	v_exp_f32_e32 v48, v48
	s_nop 0
	v_add_f32_e32 v48, 1.0, v48
	v_div_scale_f32 v49, s[8:9], v48, v48, 1.0
	v_rcp_f32_e32 v50, v49
	v_div_scale_f32 v51, vcc, 1.0, v48, 1.0
	v_fma_f32 v52, -v49, v50, 1.0
	v_fmac_f32_e32 v50, v52, v50
	v_mul_f32_e32 v52, v51, v50
	v_fma_f32 v53, -v49, v52, v51
	v_fmac_f32_e32 v52, v53, v50
	v_fma_f32 v49, -v49, v52, v51
	v_div_fmas_f32 v49, v49, v50, v52
	v_div_fixup_f32 v48, v49, v48, 1.0
	v_bfe_u32 v49, v48, 16, 1
	v_add3_u32 v48, v48, v49, s83
	s_and_b64 vcc, exec, s[6:7]
	ds_write_b16_d16_hi v114, v48 offset:64
	v_mul_f32_e32 v48, 0xbfb8aa3b, v54
	v_exp_f32_e32 v48, v48
	s_nop 0
	v_add_f32_e32 v48, 1.0, v48
	v_div_scale_f32 v49, s[8:9], v48, v48, 1.0
	v_rcp_f32_e32 v50, v49
	v_div_scale_f32 v51, vcc, 1.0, v48, 1.0
	v_fma_f32 v52, -v49, v50, 1.0
	v_fmac_f32_e32 v50, v52, v50
	v_mul_f32_e32 v52, v51, v50
	v_fma_f32 v53, -v49, v52, v51
	v_fmac_f32_e32 v52, v53, v50
	v_fma_f32 v49, -v49, v52, v51
	v_div_fmas_f32 v49, v49, v50, v52
	v_div_fixup_f32 v48, v49, v48, 1.0
	v_bfe_u32 v49, v48, 16, 1
	v_add3_u32 v48, v48, v49, s83
	s_and_b64 vcc, exec, s[6:7]
	ds_write_b16_d16_hi v115, v48 offset:64
	v_mul_f32_e32 v48, 0xbfb8aa3b, v55
	v_exp_f32_e32 v48, v48
	s_nop 0
	v_add_f32_e32 v48, 1.0, v48
	v_div_scale_f32 v49, s[8:9], v48, v48, 1.0
	v_rcp_f32_e32 v50, v49
	v_div_scale_f32 v51, vcc, 1.0, v48, 1.0
	v_fma_f32 v52, -v49, v50, 1.0
	v_fmac_f32_e32 v50, v52, v50
	v_mul_f32_e32 v52, v51, v50
	v_fma_f32 v53, -v49, v52, v51
	v_fmac_f32_e32 v52, v53, v50
	v_fma_f32 v49, -v49, v52, v51
	v_div_fmas_f32 v49, v49, v50, v52
	v_div_fixup_f32 v48, v49, v48, 1.0
	v_bfe_u32 v49, v48, 16, 1
	v_add3_u32 v48, v48, v49, s83
; __device__ __forceinline__ bf16r f2bf(float f) {
;   unsigned u = __float_as_uint(f);
;   u += 0x7fffu + ((u >> 16) & 1u);
;   return (bf16r)(u >> 16);
; }
; __device__ __forceinline__ float sigmf(float x) { return 1.f / (1.f + __expf(-x)); }
; __device__ __forceinline__ void inproj_epilogue(const Params& p, int layer, int mt, int ntile, int tid,
;                                                 f32x16 (&acc)[2][2], unsigned char* smem) {
;     ...
;       if (mode == 2) o = sigmf(v);
;       sT[row * 136 + col] = f2bf(o);
	s_and_b64 vcc, exec, s[6:7]
	ds_write_b16_d16_hi v117, v48 offset:64
	v_mul_f32_e32 v48, 0xbfb8aa3b, v56
	v_exp_f32_e32 v48, v48
	s_nop 0
	v_add_f32_e32 v48, 1.0, v48
	v_div_scale_f32 v49, s[8:9], v48, v48, 1.0
	v_rcp_f32_e32 v50, v49
	v_div_scale_f32 v51, vcc, 1.0, v48, 1.0
	v_fma_f32 v52, -v49, v50, 1.0
	v_fmac_f32_e32 v50, v52, v50
	v_mul_f32_e32 v52, v51, v50
	v_fma_f32 v53, -v49, v52, v51
	v_fmac_f32_e32 v52, v53, v50
	v_fma_f32 v49, -v49, v52, v51
	v_div_fmas_f32 v49, v49, v50, v52
	v_div_fixup_f32 v48, v49, v48, 1.0
	v_bfe_u32 v49, v48, 16, 1
	v_add3_u32 v48, v48, v49, s83
	s_and_b64 vcc, exec, s[6:7]
	ds_write_b16_d16_hi v118, v48 offset:64
	v_mul_f32_e32 v48, 0xbfb8aa3b, v57
	v_exp_f32_e32 v48, v48
	s_nop 0
	v_add_f32_e32 v48, 1.0, v48
	v_div_scale_f32 v49, s[8:9], v48, v48, 1.0
	v_rcp_f32_e32 v50, v49
	v_div_scale_f32 v51, vcc, 1.0, v48, 1.0
	v_fma_f32 v52, -v49, v50, 1.0
	v_fmac_f32_e32 v50, v52, v50
	v_mul_f32_e32 v52, v51, v50
	v_fma_f32 v53, -v49, v52, v51
	v_fmac_f32_e32 v52, v53, v50
	v_fma_f32 v49, -v49, v52, v51
	v_div_fmas_f32 v49, v49, v50, v52
	v_div_fixup_f32 v48, v49, v48, 1.0
	v_bfe_u32 v49, v48, 16, 1
	v_add3_u32 v48, v48, v49, s83
	s_and_b64 vcc, exec, s[6:7]
	ds_write_b16_d16_hi v119, v48 offset:64
	v_mul_f32_e32 v48, 0xbfb8aa3b, v58
	v_exp_f32_e32 v48, v48
	s_nop 0
	v_add_f32_e32 v48, 1.0, v48
	v_div_scale_f32 v49, s[8:9], v48, v48, 1.0
	v_rcp_f32_e32 v50, v49
	v_div_scale_f32 v51, vcc, 1.0, v48, 1.0
	v_fma_f32 v52, -v49, v50, 1.0
	v_fmac_f32_e32 v50, v52, v50
	v_mul_f32_e32 v52, v51, v50
	v_fma_f32 v53, -v49, v52, v51
	v_fmac_f32_e32 v52, v53, v50
	v_fma_f32 v49, -v49, v52, v51
	v_div_fmas_f32 v49, v49, v50, v52
	v_div_fixup_f32 v48, v49, v48, 1.0
	v_bfe_u32 v49, v48, 16, 1
	v_add3_u32 v48, v48, v49, s83
	s_and_b64 vcc, exec, s[6:7]
	ds_write_b16_d16_hi v120, v48 offset:64
	v_mul_f32_e32 v48, 0xbfb8aa3b, v59
	v_exp_f32_e32 v48, v48
	s_nop 0
	v_add_f32_e32 v48, 1.0, v48
	v_div_scale_f32 v49, s[8:9], v48, v48, 1.0
	v_rcp_f32_e32 v50, v49
	v_div_scale_f32 v51, vcc, 1.0, v48, 1.0
	v_fma_f32 v52, -v49, v50, 1.0
	v_fmac_f32_e32 v50, v52, v50
	v_mul_f32_e32 v52, v51, v50
	v_fma_f32 v53, -v49, v52, v51
	v_fmac_f32_e32 v52, v53, v50
	v_fma_f32 v49, -v49, v52, v51
	v_div_fmas_f32 v49, v49, v50, v52
	v_div_fixup_f32 v48, v49, v48, 1.0
	v_bfe_u32 v49, v48, 16, 1
	v_add3_u32 v48, v48, v49, s83
	s_and_b64 vcc, exec, s[6:7]
	ds_write_b16_d16_hi v121, v48 offset:64
	v_mul_f32_e32 v48, 0xbfb8aa3b, v60
	v_exp_f32_e32 v48, v48
	s_nop 0
	v_add_f32_e32 v48, 1.0, v48
	v_div_scale_f32 v49, s[8:9], v48, v48, 1.0
	v_rcp_f32_e32 v50, v49
	v_div_scale_f32 v51, vcc, 1.0, v48, 1.0
	v_fma_f32 v52, -v49, v50, 1.0
	v_fmac_f32_e32 v50, v52, v50
	v_mul_f32_e32 v52, v51, v50
	v_fma_f32 v53, -v49, v52, v51
	v_fmac_f32_e32 v52, v53, v50
	v_fma_f32 v49, -v49, v52, v51
	v_div_fmas_f32 v49, v49, v50, v52
	v_div_fixup_f32 v48, v49, v48, 1.0
	v_bfe_u32 v49, v48, 16, 1
	v_add3_u32 v48, v48, v49, s83
	s_and_b64 vcc, exec, s[6:7]
	ds_write_b16_d16_hi v122, v48 offset:64
	v_mul_f32_e32 v48, 0xbfb8aa3b, v61
	v_exp_f32_e32 v48, v48
	s_nop 0
	v_add_f32_e32 v48, 1.0, v48
	v_div_scale_f32 v49, s[8:9], v48, v48, 1.0
	v_rcp_f32_e32 v50, v49
	v_div_scale_f32 v51, vcc, 1.0, v48, 1.0
	v_fma_f32 v52, -v49, v50, 1.0
	v_fmac_f32_e32 v50, v52, v50
	v_mul_f32_e32 v52, v51, v50
	v_fma_f32 v53, -v49, v52, v51
	v_fmac_f32_e32 v52, v53, v50
	v_fma_f32 v49, -v49, v52, v51
	v_div_fmas_f32 v49, v49, v50, v52
	v_div_fixup_f32 v48, v49, v48, 1.0
	v_bfe_u32 v49, v48, 16, 1
	v_add3_u32 v48, v48, v49, s83
	s_and_b64 vcc, exec, s[6:7]
	ds_write_b16_d16_hi v123, v48 offset:64
	v_mul_f32_e32 v48, 0xbfb8aa3b, v62
	v_exp_f32_e32 v48, v48
	s_nop 0
	v_add_f32_e32 v48, 1.0, v48
	v_div_scale_f32 v49, s[8:9], v48, v48, 1.0
	v_rcp_f32_e32 v50, v49
	v_div_scale_f32 v51, vcc, 1.0, v48, 1.0
	v_fma_f32 v52, -v49, v50, 1.0
	v_fmac_f32_e32 v50, v52, v50
	v_mul_f32_e32 v52, v51, v50
	v_fma_f32 v53, -v49, v52, v51
	v_fmac_f32_e32 v52, v53, v50
	v_fma_f32 v49, -v49, v52, v51
	v_div_fmas_f32 v49, v49, v50, v52
	v_div_fixup_f32 v48, v49, v48, 1.0
	v_bfe_u32 v49, v48, 16, 1
	v_add3_u32 v48, v48, v49, s83
	s_and_b64 vcc, exec, s[6:7]
	ds_write_b16_d16_hi v116, v48 offset:64
	v_mul_f32_e32 v48, 0xbfb8aa3b, v63
	v_exp_f32_e32 v48, v48
	s_nop 0
	v_add_f32_e32 v48, 1.0, v48
	v_div_scale_f32 v49, s[8:9], v48, v48, 1.0
	v_rcp_f32_e32 v50, v49
	v_div_scale_f32 v51, vcc, 1.0, v48, 1.0
	v_fma_f32 v52, -v49, v50, 1.0
	v_fmac_f32_e32 v50, v52, v50
	v_mul_f32_e32 v52, v51, v50
	v_fma_f32 v53, -v49, v52, v51
	v_fmac_f32_e32 v52, v53, v50
	v_fma_f32 v49, -v49, v52, v51
	v_div_fmas_f32 v49, v49, v50, v52
	v_div_fixup_f32 v48, v49, v48, 1.0
	v_bfe_u32 v50, v48, 16, 1
	v_add_u32_e32 v49, 0x110, v116
	v_add3_u32 v48, v48, v50, s83
	ds_write_b16_d16_hi v49, v48 offset:64
	v_or_b32_e32 v48, 32, v96
	v_add_u32_e32 v49, s88, v48
	s_and_b64 vcc, exec, s[6:7]
	v_cmp_lt_i32_e64 s[8:9], s81, v49
	v_mul_f32_e32 v49, 0xbfb8aa3b, v0
	v_exp_f32_e32 v49, v49
	s_nop 0
	v_add_f32_e32 v49, 1.0, v49
	v_div_scale_f32 v50, s[10:11], v49, v49, 1.0
	v_rcp_f32_e32 v51, v50
	v_div_scale_f32 v52, vcc, 1.0, v49, 1.0
	v_fma_f32 v53, -v50, v51, 1.0
	v_fmac_f32_e32 v51, v53, v51
	v_mul_f32_e32 v53, v52, v51
	v_fma_f32 v54, -v50, v53, v52
	v_fmac_f32_e32 v53, v54, v51
	v_fma_f32 v50, -v50, v53, v52
	v_div_fmas_f32 v50, v50, v51, v53
	v_div_fixup_f32 v49, v50, v49, 1.0
	v_bfe_u32 v50, v49, 16, 1
	v_add3_u32 v50, v49, v50, s83
	v_mul_lo_u32 v49, v48, s90
	v_lshl_add_u32 v48, v106, 1, v49
	ds_write_b16_d16_hi v48, v50
	v_add3_u32 v50, s88, v96, 33
	s_and_b64 vcc, exec, s[6:7]
	v_cmp_lt_i32_e64 s[10:11], s81, v50
	v_mul_f32_e32 v50, 0xbfb8aa3b, v1
; __device__ __forceinline__ bf16r f2bf(float f) {
;   unsigned u = __float_as_uint(f);
;   u += 0x7fffu + ((u >> 16) & 1u);
;   return (bf16r)(u >> 16);
; }
; __device__ __forceinline__ float sigmf(float x) { return 1.f / (1.f + __expf(-x)); }
; __device__ __forceinline__ void inproj_epilogue(const Params& p, int layer, int mt, int ntile, int tid,
;                                                 f32x16 (&acc)[2][2], unsigned char* smem) {
;     ...
;       if (mode == 2) o = sigmf(v);
;       sT[row * 136 + col] = f2bf(o);
	v_exp_f32_e32 v50, v50
	s_nop 0
	v_add_f32_e32 v50, 1.0, v50
	v_div_scale_f32 v51, s[12:13], v50, v50, 1.0
	v_rcp_f32_e32 v52, v51
	v_div_scale_f32 v53, vcc, 1.0, v50, 1.0
	v_fma_f32 v54, -v51, v52, 1.0
	v_fmac_f32_e32 v52, v54, v52
	v_mul_f32_e32 v54, v53, v52
	v_fma_f32 v55, -v51, v54, v53
	v_fmac_f32_e32 v54, v55, v52
	v_fma_f32 v51, -v51, v54, v53
	v_div_fmas_f32 v51, v51, v52, v54
	v_div_fixup_f32 v50, v51, v50, 1.0
	v_bfe_u32 v51, v50, 16, 1
	v_add3_u32 v51, v50, v51, s83
	v_add_u32_e32 v50, 0x110, v49
	v_lshl_add_u32 v49, v106, 1, v50
	ds_write_b16_d16_hi v49, v51
	v_add3_u32 v51, s88, v96, 34
	s_and_b64 vcc, exec, s[6:7]
	v_cmp_lt_i32_e64 s[12:13], s81, v51
	v_mul_f32_e32 v51, 0xbfb8aa3b, v2
	v_exp_f32_e32 v51, v51
	s_nop 0
	v_add_f32_e32 v51, 1.0, v51
	v_div_scale_f32 v52, s[14:15], v51, v51, 1.0
	v_rcp_f32_e32 v53, v52
	v_div_scale_f32 v54, vcc, 1.0, v51, 1.0
	v_fma_f32 v55, -v52, v53, 1.0
	v_fmac_f32_e32 v53, v55, v53
	v_mul_f32_e32 v55, v54, v53
	v_fma_f32 v56, -v52, v55, v54
	v_fmac_f32_e32 v55, v56, v53
	v_fma_f32 v52, -v52, v55, v54
	v_div_fmas_f32 v52, v52, v53, v55
	v_div_fixup_f32 v51, v52, v51, 1.0
	v_bfe_u32 v52, v51, 16, 1
	v_add3_u32 v52, v51, v52, s83
	v_add_u32_e32 v51, 0x110, v50
	v_lshl_add_u32 v50, v106, 1, v51
	ds_write_b16_d16_hi v50, v52
	v_add3_u32 v52, s88, v96, 35
	s_and_b64 vcc, exec, s[6:7]
	v_cmp_lt_i32_e64 s[14:15], s81, v52
	v_mul_f32_e32 v52, 0xbfb8aa3b, v3
	v_exp_f32_e32 v52, v52
	s_nop 0
	v_add_f32_e32 v52, 1.0, v52
	v_div_scale_f32 v53, s[16:17], v52, v52, 1.0
	v_rcp_f32_e32 v54, v53
	v_div_scale_f32 v55, vcc, 1.0, v52, 1.0
	v_fma_f32 v56, -v53, v54, 1.0
	v_fmac_f32_e32 v54, v56, v54
	v_mul_f32_e32 v56, v55, v54
	v_fma_f32 v57, -v53, v56, v55
	v_fmac_f32_e32 v56, v57, v54
	v_fma_f32 v53, -v53, v56, v55
	v_div_fmas_f32 v53, v53, v54, v56
	v_div_fixup_f32 v52, v53, v52, 1.0
	v_bfe_u32 v53, v52, 16, 1
	v_add3_u32 v53, v52, v53, s83
	v_add_u32_e32 v52, 0x110, v51
	v_lshl_add_u32 v51, v106, 1, v52
	ds_write_b16_d16_hi v51, v53
	v_add3_u32 v53, s88, v96, 40
	s_and_b64 vcc, exec, s[6:7]
	v_cmp_lt_i32_e64 s[16:17], s81, v53
	v_mul_f32_e32 v53, 0xbfb8aa3b, v4
	v_exp_f32_e32 v53, v53
	s_nop 0
	v_add_f32_e32 v53, 1.0, v53
	v_div_scale_f32 v54, s[18:19], v53, v53, 1.0
	v_rcp_f32_e32 v55, v54
	v_div_scale_f32 v56, vcc, 1.0, v53, 1.0
	v_fma_f32 v57, -v54, v55, 1.0
	v_fmac_f32_e32 v55, v57, v55
	v_mul_f32_e32 v57, v56, v55
	v_fma_f32 v58, -v54, v57, v56
	v_fmac_f32_e32 v57, v58, v55
	v_fma_f32 v54, -v54, v57, v56
	v_div_fmas_f32 v54, v54, v55, v57
	v_div_fixup_f32 v53, v54, v53, 1.0
	v_bfe_u32 v54, v53, 16, 1
	v_add3_u32 v54, v53, v54, s83
	v_add_u32_e32 v53, 0x550, v52
	v_lshl_add_u32 v52, v106, 1, v53
	ds_write_b16_d16_hi v52, v54
	v_add3_u32 v54, s88, v96, 41
	s_and_b64 vcc, exec, s[6:7]
	v_cmp_lt_i32_e64 s[18:19], s81, v54
	v_mul_f32_e32 v54, 0xbfb8aa3b, v5
	v_exp_f32_e32 v54, v54
	s_nop 0
	v_add_f32_e32 v54, 1.0, v54
	v_div_scale_f32 v55, s[20:21], v54, v54, 1.0
	v_rcp_f32_e32 v56, v55
	v_div_scale_f32 v57, vcc, 1.0, v54, 1.0
	v_fma_f32 v58, -v55, v56, 1.0
	v_fmac_f32_e32 v56, v58, v56
	v_mul_f32_e32 v58, v57, v56
	v_fma_f32 v59, -v55, v58, v57
	v_fmac_f32_e32 v58, v59, v56
	v_fma_f32 v55, -v55, v58, v57
	v_div_fmas_f32 v55, v55, v56, v58
	v_div_fixup_f32 v54, v55, v54, 1.0
	v_bfe_u32 v55, v54, 16, 1
	v_add3_u32 v55, v54, v55, s83
	v_add_u32_e32 v54, 0x110, v53
	v_lshl_add_u32 v53, v106, 1, v54
	ds_write_b16_d16_hi v53, v55
	v_add3_u32 v55, s88, v96, 42
	s_and_b64 vcc, exec, s[6:7]
	v_cmp_lt_i32_e64 s[20:21], s81, v55
	v_mul_f32_e32 v55, 0xbfb8aa3b, v6
	v_exp_f32_e32 v55, v55
	s_nop 0
	v_add_f32_e32 v55, 1.0, v55
	v_div_scale_f32 v56, s[22:23], v55, v55, 1.0
	v_rcp_f32_e32 v57, v56
	v_div_scale_f32 v58, vcc, 1.0, v55, 1.0
	v_fma_f32 v59, -v56, v57, 1.0
	v_fmac_f32_e32 v57, v59, v57
	v_mul_f32_e32 v59, v58, v57
	v_fma_f32 v60, -v56, v59, v58
	v_fmac_f32_e32 v59, v60, v57
	v_fma_f32 v56, -v56, v59, v58
	v_div_fmas_f32 v56, v56, v57, v59
	v_div_fixup_f32 v55, v56, v55, 1.0
	v_bfe_u32 v56, v55, 16, 1
	v_add3_u32 v56, v55, v56, s83
	v_add_u32_e32 v55, 0x110, v54
	v_lshl_add_u32 v54, v106, 1, v55
	ds_write_b16_d16_hi v54, v56
	v_add3_u32 v56, s88, v96, 43
	s_and_b64 vcc, exec, s[6:7]
	v_cmp_lt_i32_e64 s[22:23], s81, v56
	v_mul_f32_e32 v56, 0xbfb8aa3b, v7
	v_exp_f32_e32 v56, v56
	s_nop 0
	v_add_f32_e32 v56, 1.0, v56
	v_div_scale_f32 v57, s[24:25], v56, v56, 1.0
	v_rcp_f32_e32 v58, v57
	v_div_scale_f32 v59, vcc, 1.0, v56, 1.0
	v_fma_f32 v60, -v57, v58, 1.0
	v_fmac_f32_e32 v58, v60, v58
	v_mul_f32_e32 v60, v59, v58
	v_fma_f32 v61, -v57, v60, v59
	v_fmac_f32_e32 v60, v61, v58
	v_fma_f32 v57, -v57, v60, v59
	v_div_fmas_f32 v57, v57, v58, v60
	v_div_fixup_f32 v56, v57, v56, 1.0
	v_bfe_u32 v57, v56, 16, 1
	v_add_u32_e32 v55, 0x110, v55
	v_add3_u32 v57, v56, v57, s83
	v_lshl_add_u32 v56, v106, 1, v55
	ds_write_b16_d16_hi v56, v57
	v_add3_u32 v57, s88, v96, 48
	s_and_b64 vcc, exec, s[6:7]
	v_cmp_lt_i32_e64 s[24:25], s81, v57
	v_mul_f32_e32 v57, 0xbfb8aa3b, v8
	v_exp_f32_e32 v57, v57
	s_nop 0
	v_add_f32_e32 v57, 1.0, v57
	v_div_scale_f32 v58, s[26:27], v57, v57, 1.0
	v_rcp_f32_e32 v59, v58
	v_div_scale_f32 v60, vcc, 1.0, v57, 1.0
	v_fma_f32 v61, -v58, v59, 1.0
	v_fmac_f32_e32 v59, v61, v59
	v_mul_f32_e32 v61, v60, v59
	v_fma_f32 v62, -v58, v61, v60
	v_fmac_f32_e32 v61, v62, v59
	v_fma_f32 v58, -v58, v61, v60
	v_div_fmas_f32 v58, v58, v59, v61
	v_div_fixup_f32 v57, v58, v57, 1.0
	v_bfe_u32 v58, v57, 16, 1
	v_add_u32_e32 v55, 0x550, v55
	v_add3_u32 v58, v57, v58, s83
	v_lshl_add_u32 v57, v106, 1, v55
	ds_write_b16_d16_hi v57, v58
	v_add3_u32 v58, s88, v96, 49
	s_and_b64 vcc, exec, s[6:7]
	v_cmp_lt_i32_e64 s[26:27], s81, v58
; __device__ __forceinline__ bf16r f2bf(float f) {
;   unsigned u = __float_as_uint(f);
;   u += 0x7fffu + ((u >> 16) & 1u);
;   return (bf16r)(u >> 16);
; }
; __device__ __forceinline__ float sigmf(float x) { return 1.f / (1.f + __expf(-x)); }
; __device__ __forceinline__ void inproj_epilogue(const Params& p, int layer, int mt, int ntile, int tid,
;                                                 f32x16 (&acc)[2][2], unsigned char* smem) {
;     ...
;       if (mode == 2) o = sigmf(v);
;       sT[row * 136 + col] = f2bf(o);
	v_mul_f32_e32 v58, 0xbfb8aa3b, v9
	v_exp_f32_e32 v58, v58
	s_nop 0
	v_add_f32_e32 v58, 1.0, v58
	v_div_scale_f32 v59, s[28:29], v58, v58, 1.0
	v_rcp_f32_e32 v60, v59
	v_div_scale_f32 v61, vcc, 1.0, v58, 1.0
	v_fma_f32 v62, -v59, v60, 1.0
	v_fmac_f32_e32 v60, v62, v60
	v_mul_f32_e32 v62, v61, v60
	v_fma_f32 v63, -v59, v62, v61
	v_fmac_f32_e32 v62, v63, v60
	v_fma_f32 v59, -v59, v62, v61
	v_div_fmas_f32 v59, v59, v60, v62
	v_div_fixup_f32 v58, v59, v58, 1.0
	v_bfe_u32 v59, v58, 16, 1
	v_add_u32_e32 v55, 0x110, v55
	v_add3_u32 v59, v58, v59, s83
	v_lshl_add_u32 v58, v106, 1, v55
	ds_write_b16_d16_hi v58, v59
	v_add3_u32 v59, s88, v96, 50
	s_and_b64 vcc, exec, s[6:7]
	v_cmp_lt_i32_e64 s[28:29], s81, v59
	v_mul_f32_e32 v59, 0xbfb8aa3b, v10
	v_exp_f32_e32 v59, v59
	s_nop 0
	v_add_f32_e32 v59, 1.0, v59
	v_div_scale_f32 v60, s[30:31], v59, v59, 1.0
	v_rcp_f32_e32 v61, v60
	v_div_scale_f32 v62, vcc, 1.0, v59, 1.0
	v_fma_f32 v63, -v60, v61, 1.0
	v_fmac_f32_e32 v61, v63, v61
	v_mul_f32_e32 v63, v62, v61
	v_fma_f32 v107, -v60, v63, v62
	v_fmac_f32_e32 v63, v107, v61
	v_fma_f32 v60, -v60, v63, v62
	v_div_fmas_f32 v60, v60, v61, v63
	v_div_fixup_f32 v59, v60, v59, 1.0
	v_bfe_u32 v60, v59, 16, 1
	v_add_u32_e32 v55, 0x110, v55
	v_add3_u32 v60, v59, v60, s83
	v_lshl_add_u32 v59, v106, 1, v55
	ds_write_b16_d16_hi v59, v60
	v_add3_u32 v60, s88, v96, 51
	s_and_b64 vcc, exec, s[6:7]
	v_cmp_lt_i32_e64 s[30:31], s81, v60
	v_mul_f32_e32 v60, 0xbfb8aa3b, v11
	v_exp_f32_e32 v60, v60
	s_nop 0
	v_add_f32_e32 v60, 1.0, v60
	v_div_scale_f32 v61, s[34:35], v60, v60, 1.0
	v_rcp_f32_e32 v62, v61
	v_div_scale_f32 v63, vcc, 1.0, v60, 1.0
	v_fma_f32 v107, -v61, v62, 1.0
	v_fmac_f32_e32 v62, v107, v62
	v_mul_f32_e32 v107, v63, v62
	v_fma_f32 v110, -v61, v107, v63
	v_fmac_f32_e32 v107, v110, v62
	v_fma_f32 v61, -v61, v107, v63
	v_div_fmas_f32 v61, v61, v62, v107
	v_div_fixup_f32 v60, v61, v60, 1.0
	v_bfe_u32 v61, v60, 16, 1
	v_add_u32_e32 v55, 0x110, v55
	v_add3_u32 v61, v60, v61, s83
	v_lshl_add_u32 v60, v106, 1, v55
	ds_write_b16_d16_hi v60, v61
	v_add3_u32 v61, s88, v96, 56
	s_and_b64 vcc, exec, s[6:7]
	v_cmp_lt_i32_e64 s[34:35], s81, v61
	v_mul_f32_e32 v61, 0xbfb8aa3b, v12
	v_exp_f32_e32 v61, v61
	s_nop 0
	v_add_f32_e32 v61, 1.0, v61
	v_div_scale_f32 v62, s[36:37], v61, v61, 1.0
	v_rcp_f32_e32 v63, v62
	v_div_scale_f32 v107, vcc, 1.0, v61, 1.0
	v_fma_f32 v110, -v62, v63, 1.0
	v_fmac_f32_e32 v63, v110, v63
	v_mul_f32_e32 v110, v107, v63
	v_fma_f32 v111, -v62, v110, v107
	v_fmac_f32_e32 v110, v111, v63
	v_fma_f32 v62, -v62, v110, v107
	v_div_fmas_f32 v62, v62, v63, v110
	v_div_fixup_f32 v61, v62, v61, 1.0
	v_bfe_u32 v62, v61, 16, 1
	v_add_u32_e32 v55, 0x550, v55
	v_add3_u32 v62, v61, v62, s83
	v_lshl_add_u32 v61, v106, 1, v55
	ds_write_b16_d16_hi v61, v62
	v_add3_u32 v62, s88, v96, 57
	s_and_b64 vcc, exec, s[6:7]
	v_cmp_lt_i32_e64 s[36:37], s81, v62
	v_mul_f32_e32 v62, 0xbfb8aa3b, v13
	v_exp_f32_e32 v62, v62
	s_nop 0
	v_add_f32_e32 v62, 1.0, v62
	v_div_scale_f32 v63, s[38:39], v62, v62, 1.0
	v_rcp_f32_e32 v107, v63
	v_div_scale_f32 v110, vcc, 1.0, v62, 1.0
	v_fma_f32 v111, -v63, v107, 1.0
	v_fmac_f32_e32 v107, v111, v107
	v_mul_f32_e32 v111, v110, v107
	v_fma_f32 v112, -v63, v111, v110
	v_fmac_f32_e32 v111, v112, v107
	v_fma_f32 v63, -v63, v111, v110
	v_div_fmas_f32 v63, v63, v107, v111
	v_div_fixup_f32 v62, v63, v62, 1.0
	v_bfe_u32 v63, v62, 16, 1
	v_add_u32_e32 v55, 0x110, v55
	v_add3_u32 v63, v62, v63, s83
	v_lshl_add_u32 v62, v106, 1, v55
	ds_write_b16_d16_hi v62, v63
	v_add3_u32 v63, s88, v96, 58
	s_and_b64 vcc, exec, s[6:7]
	v_cmp_lt_i32_e64 s[38:39], s81, v63
	v_mul_f32_e32 v63, 0xbfb8aa3b, v14
	v_exp_f32_e32 v63, v63
	s_nop 0
	v_add_f32_e32 v63, 1.0, v63
	v_div_scale_f32 v107, s[40:41], v63, v63, 1.0
	v_rcp_f32_e32 v110, v107
	v_div_scale_f32 v111, vcc, 1.0, v63, 1.0
	v_fma_f32 v112, -v107, v110, 1.0
	v_fmac_f32_e32 v110, v112, v110
	v_mul_f32_e32 v112, v111, v110
	v_fma_f32 v113, -v107, v112, v111
	v_fmac_f32_e32 v112, v113, v110
	v_fma_f32 v107, -v107, v112, v111
	v_div_fmas_f32 v107, v107, v110, v112
	v_div_fixup_f32 v63, v107, v63, 1.0
	v_bfe_u32 v107, v63, 16, 1
	v_add_u32_e32 v55, 0x110, v55
	v_add3_u32 v63, v63, v107, s83
	v_lshl_add_u32 v55, v106, 1, v55
	ds_write_b16_d16_hi v55, v63
	v_add3_u32 v63, s88, v96, 59
	s_and_b64 vcc, exec, s[6:7]
	v_cmp_lt_i32_e64 s[40:41], s81, v63
	v_mul_f32_e32 v63, 0xbfb8aa3b, v15
	v_exp_f32_e32 v63, v63
	s_nop 0
	v_add_f32_e32 v63, 1.0, v63
	v_div_scale_f32 v96, s[96:97], v63, v63, 1.0
	v_rcp_f32_e32 v106, v96
	v_div_scale_f32 v107, vcc, 1.0, v63, 1.0
	v_fma_f32 v110, -v96, v106, 1.0
	v_fmac_f32_e32 v106, v110, v106
	v_mul_f32_e32 v110, v107, v106
	v_fma_f32 v111, -v96, v110, v107
	v_fmac_f32_e32 v110, v111, v106
	v_fma_f32 v96, -v96, v110, v107
	v_div_fmas_f32 v96, v96, v106, v110
	v_div_fixup_f32 v63, v96, v63, 1.0
	v_bfe_u32 v96, v63, 16, 1
	v_add3_u32 v63, v63, v96, s83
	ds_write_b16_d16_hi v55, v63 offset:272
	s_and_b64 vcc, exec, s[6:7]
	v_mul_f32_e32 v32, 0xbfb8aa3b, v32
	v_exp_f32_e32 v32, v32
	s_nop 0
	v_add_f32_e32 v32, 1.0, v32
	v_div_scale_f32 v63, s[8:9], v32, v32, 1.0
	v_rcp_f32_e32 v96, v63
	v_div_scale_f32 v106, vcc, 1.0, v32, 1.0
	v_fma_f32 v107, -v63, v96, 1.0
	v_fmac_f32_e32 v96, v107, v96
	v_mul_f32_e32 v107, v106, v96
	v_fma_f32 v110, -v63, v107, v106
	v_fmac_f32_e32 v107, v110, v96
	v_fma_f32 v63, -v63, v107, v106
	v_div_fmas_f32 v63, v63, v96, v107
	v_div_fixup_f32 v32, v63, v32, 1.0
	v_bfe_u32 v63, v32, 16, 1
	v_add3_u32 v32, v32, v63, s83
	s_and_b64 vcc, exec, s[6:7]
	ds_write_b16_d16_hi v48, v32 offset:64
	v_mul_f32_e32 v32, 0xbfb8aa3b, v33
	v_exp_f32_e32 v32, v32
	s_nop 0
	v_add_f32_e32 v32, 1.0, v32
; __device__ __forceinline__ bf16r f2bf(float f) {
;   unsigned u = __float_as_uint(f);
;   u += 0x7fffu + ((u >> 16) & 1u);
;   return (bf16r)(u >> 16);
; }
; __device__ __forceinline__ float sigmf(float x) { return 1.f / (1.f + __expf(-x)); }
; __device__ __forceinline__ void inproj_epilogue(const Params& p, int layer, int mt, int ntile, int tid,
;                                                 f32x16 (&acc)[2][2], unsigned char* smem) {
;     ...
;       if (mode == 2) o = sigmf(v);
;       sT[row * 136 + col] = f2bf(o);
	v_div_scale_f32 v33, s[8:9], v32, v32, 1.0
	v_rcp_f32_e32 v48, v33
	v_div_scale_f32 v63, vcc, 1.0, v32, 1.0
	v_fma_f32 v96, -v33, v48, 1.0
	v_fmac_f32_e32 v48, v96, v48
	v_mul_f32_e32 v96, v63, v48
	v_fma_f32 v106, -v33, v96, v63
	v_fmac_f32_e32 v96, v106, v48
	v_fma_f32 v33, -v33, v96, v63
	v_div_fmas_f32 v33, v33, v48, v96
	v_div_fixup_f32 v32, v33, v32, 1.0
	v_bfe_u32 v33, v32, 16, 1
	v_add3_u32 v32, v32, v33, s83
	s_and_b64 vcc, exec, s[6:7]
	ds_write_b16_d16_hi v49, v32 offset:64
	v_mul_f32_e32 v32, 0xbfb8aa3b, v34
	v_exp_f32_e32 v32, v32
	s_nop 0
	v_add_f32_e32 v32, 1.0, v32
	v_div_scale_f32 v33, s[8:9], v32, v32, 1.0
	v_rcp_f32_e32 v34, v33
	v_div_scale_f32 v48, vcc, 1.0, v32, 1.0
	v_fma_f32 v49, -v33, v34, 1.0
	v_fmac_f32_e32 v34, v49, v34
	v_mul_f32_e32 v49, v48, v34
	v_fma_f32 v63, -v33, v49, v48
	v_fmac_f32_e32 v49, v63, v34
	v_fma_f32 v33, -v33, v49, v48
	v_div_fmas_f32 v33, v33, v34, v49
	v_div_fixup_f32 v32, v33, v32, 1.0
	v_bfe_u32 v33, v32, 16, 1
	v_add3_u32 v32, v32, v33, s83
	s_and_b64 vcc, exec, s[6:7]
	ds_write_b16_d16_hi v50, v32 offset:64
	v_mul_f32_e32 v32, 0xbfb8aa3b, v35
	v_exp_f32_e32 v32, v32
	s_nop 0
	v_add_f32_e32 v32, 1.0, v32
	v_div_scale_f32 v33, s[8:9], v32, v32, 1.0
	v_rcp_f32_e32 v34, v33
	v_div_scale_f32 v35, vcc, 1.0, v32, 1.0
	v_fma_f32 v48, -v33, v34, 1.0
	v_fmac_f32_e32 v34, v48, v34
	v_mul_f32_e32 v48, v35, v34
	v_fma_f32 v49, -v33, v48, v35
	v_fmac_f32_e32 v48, v49, v34
	v_fma_f32 v33, -v33, v48, v35
	v_div_fmas_f32 v33, v33, v34, v48
	v_div_fixup_f32 v32, v33, v32, 1.0
	v_bfe_u32 v33, v32, 16, 1
	v_add3_u32 v32, v32, v33, s83
	s_and_b64 vcc, exec, s[6:7]
	ds_write_b16_d16_hi v51, v32 offset:64
	v_mul_f32_e32 v32, 0xbfb8aa3b, v36
	v_exp_f32_e32 v32, v32
	s_nop 0
	v_add_f32_e32 v32, 1.0, v32
	v_div_scale_f32 v33, s[8:9], v32, v32, 1.0
	v_rcp_f32_e32 v34, v33
	v_div_scale_f32 v35, vcc, 1.0, v32, 1.0
	v_fma_f32 v36, -v33, v34, 1.0
	v_fmac_f32_e32 v34, v36, v34
	v_mul_f32_e32 v36, v35, v34
	v_fma_f32 v48, -v33, v36, v35
	v_fmac_f32_e32 v36, v48, v34
	v_fma_f32 v33, -v33, v36, v35
	v_div_fmas_f32 v33, v33, v34, v36
	v_div_fixup_f32 v32, v33, v32, 1.0
	v_bfe_u32 v33, v32, 16, 1
	v_add3_u32 v32, v32, v33, s83
	s_and_b64 vcc, exec, s[6:7]
	ds_write_b16_d16_hi v52, v32 offset:64
	v_mul_f32_e32 v32, 0xbfb8aa3b, v37
	v_exp_f32_e32 v32, v32
	s_nop 0
	v_add_f32_e32 v32, 1.0, v32
	v_div_scale_f32 v33, s[8:9], v32, v32, 1.0
	v_rcp_f32_e32 v34, v33
	v_div_scale_f32 v35, vcc, 1.0, v32, 1.0
	v_fma_f32 v36, -v33, v34, 1.0
	v_fmac_f32_e32 v34, v36, v34
	v_mul_f32_e32 v36, v35, v34
	v_fma_f32 v37, -v33, v36, v35
	v_fmac_f32_e32 v36, v37, v34
	v_fma_f32 v33, -v33, v36, v35
	v_div_fmas_f32 v33, v33, v34, v36
	v_div_fixup_f32 v32, v33, v32, 1.0
	v_bfe_u32 v33, v32, 16, 1
	v_add3_u32 v32, v32, v33, s83
	s_and_b64 vcc, exec, s[6:7]
	ds_write_b16_d16_hi v53, v32 offset:64
	v_mul_f32_e32 v32, 0xbfb8aa3b, v38
	v_exp_f32_e32 v32, v32
	s_nop 0
	v_add_f32_e32 v32, 1.0, v32
	v_div_scale_f32 v33, s[8:9], v32, v32, 1.0
	v_rcp_f32_e32 v34, v33
	v_div_scale_f32 v35, vcc, 1.0, v32, 1.0
	v_fma_f32 v36, -v33, v34, 1.0
	v_fmac_f32_e32 v34, v36, v34
	v_mul_f32_e32 v36, v35, v34
	v_fma_f32 v37, -v33, v36, v35
	v_fmac_f32_e32 v36, v37, v34
	v_fma_f32 v33, -v33, v36, v35
	v_div_fmas_f32 v33, v33, v34, v36
	v_div_fixup_f32 v32, v33, v32, 1.0
	v_bfe_u32 v33, v32, 16, 1
	v_add3_u32 v32, v32, v33, s83
	s_and_b64 vcc, exec, s[6:7]
	ds_write_b16_d16_hi v54, v32 offset:64
	v_mul_f32_e32 v32, 0xbfb8aa3b, v39
	v_exp_f32_e32 v32, v32
	s_nop 0
	v_add_f32_e32 v32, 1.0, v32
	v_div_scale_f32 v33, s[8:9], v32, v32, 1.0
	v_rcp_f32_e32 v34, v33
	v_div_scale_f32 v35, vcc, 1.0, v32, 1.0
	v_fma_f32 v36, -v33, v34, 1.0
	v_fmac_f32_e32 v34, v36, v34
	v_mul_f32_e32 v36, v35, v34
	v_fma_f32 v37, -v33, v36, v35
	v_fmac_f32_e32 v36, v37, v34
	v_fma_f32 v33, -v33, v36, v35
	v_div_fmas_f32 v33, v33, v34, v36
	v_div_fixup_f32 v32, v33, v32, 1.0
	v_bfe_u32 v33, v32, 16, 1
	v_add3_u32 v32, v32, v33, s83
	s_and_b64 vcc, exec, s[6:7]
	ds_write_b16_d16_hi v56, v32 offset:64
	v_mul_f32_e32 v32, 0xbfb8aa3b, v40
	v_exp_f32_e32 v32, v32
	s_nop 0
	v_add_f32_e32 v32, 1.0, v32
	v_div_scale_f32 v33, s[8:9], v32, v32, 1.0
	v_rcp_f32_e32 v34, v33
	v_div_scale_f32 v35, vcc, 1.0, v32, 1.0
	v_fma_f32 v36, -v33, v34, 1.0
	v_fmac_f32_e32 v34, v36, v34
	v_mul_f32_e32 v36, v35, v34
; __device__ __forceinline__ bf16r f2bf(float f) {
;   unsigned u = __float_as_uint(f);
;   u += 0x7fffu + ((u >> 16) & 1u);
;   return (bf16r)(u >> 16);
; }
; __device__ __forceinline__ float sigmf(float x) { return 1.f / (1.f + __expf(-x)); }
; __device__ __forceinline__ void inproj_epilogue(const Params& p, int layer, int mt, int ntile, int tid,
;                                                 f32x16 (&acc)[2][2], unsigned char* smem) {
;     ...
;       if (mode == 2) o = sigmf(v);
;       sT[row * 136 + col] = f2bf(o);
	v_fma_f32 v37, -v33, v36, v35
	v_fmac_f32_e32 v36, v37, v34
	v_fma_f32 v33, -v33, v36, v35
	v_div_fmas_f32 v33, v33, v34, v36
	v_div_fixup_f32 v32, v33, v32, 1.0
	v_bfe_u32 v33, v32, 16, 1
	v_add3_u32 v32, v32, v33, s83
	s_and_b64 vcc, exec, s[6:7]
	ds_write_b16_d16_hi v57, v32 offset:64
	v_mul_f32_e32 v32, 0xbfb8aa3b, v41
	v_exp_f32_e32 v32, v32
	s_nop 0
	v_add_f32_e32 v32, 1.0, v32
	v_div_scale_f32 v33, s[8:9], v32, v32, 1.0
	v_rcp_f32_e32 v34, v33
	v_div_scale_f32 v35, vcc, 1.0, v32, 1.0
	v_fma_f32 v36, -v33, v34, 1.0
	v_fmac_f32_e32 v34, v36, v34
	v_mul_f32_e32 v36, v35, v34
	v_fma_f32 v37, -v33, v36, v35
	v_fmac_f32_e32 v36, v37, v34
	v_fma_f32 v33, -v33, v36, v35
	v_div_fmas_f32 v33, v33, v34, v36
	v_div_fixup_f32 v32, v33, v32, 1.0
	v_bfe_u32 v33, v32, 16, 1
	v_add3_u32 v32, v32, v33, s83
	s_and_b64 vcc, exec, s[6:7]
	ds_write_b16_d16_hi v58, v32 offset:64
	v_mul_f32_e32 v32, 0xbfb8aa3b, v42
	v_exp_f32_e32 v32, v32
	s_nop 0
	v_add_f32_e32 v32, 1.0, v32
	v_div_scale_f32 v33, s[8:9], v32, v32, 1.0
	v_rcp_f32_e32 v34, v33
	v_div_scale_f32 v35, vcc, 1.0, v32, 1.0
	v_fma_f32 v36, -v33, v34, 1.0
	v_fmac_f32_e32 v34, v36, v34
	v_mul_f32_e32 v36, v35, v34
	v_fma_f32 v37, -v33, v36, v35
	v_fmac_f32_e32 v36, v37, v34
	v_fma_f32 v33, -v33, v36, v35
	v_div_fmas_f32 v33, v33, v34, v36
	v_div_fixup_f32 v32, v33, v32, 1.0
	v_bfe_u32 v33, v32, 16, 1
	v_add3_u32 v32, v32, v33, s83
	s_and_b64 vcc, exec, s[6:7]
	ds_write_b16_d16_hi v59, v32 offset:64
	v_mul_f32_e32 v32, 0xbfb8aa3b, v43
	v_exp_f32_e32 v32, v32
	s_nop 0
	v_add_f32_e32 v32, 1.0, v32
	v_div_scale_f32 v33, s[8:9], v32, v32, 1.0
	v_rcp_f32_e32 v34, v33
	v_div_scale_f32 v35, vcc, 1.0, v32, 1.0
	v_fma_f32 v36, -v33, v34, 1.0
	v_fmac_f32_e32 v34, v36, v34
	v_mul_f32_e32 v36, v35, v34
	v_fma_f32 v37, -v33, v36, v35
	v_fmac_f32_e32 v36, v37, v34
	v_fma_f32 v33, -v33, v36, v35
	v_div_fmas_f32 v33, v33, v34, v36
	v_div_fixup_f32 v32, v33, v32, 1.0
	v_bfe_u32 v33, v32, 16, 1
	v_add3_u32 v32, v32, v33, s83
	s_and_b64 vcc, exec, s[6:7]
	ds_write_b16_d16_hi v60, v32 offset:64
	v_mul_f32_e32 v32, 0xbfb8aa3b, v44
	v_exp_f32_e32 v32, v32
	s_nop 0
	v_add_f32_e32 v32, 1.0, v32
	v_div_scale_f32 v33, s[8:9], v32, v32, 1.0
	v_rcp_f32_e32 v34, v33
	v_div_scale_f32 v35, vcc, 1.0, v32, 1.0
	v_fma_f32 v36, -v33, v34, 1.0
	v_fmac_f32_e32 v34, v36, v34
	v_mul_f32_e32 v36, v35, v34
	v_fma_f32 v37, -v33, v36, v35
	v_fmac_f32_e32 v36, v37, v34
	v_fma_f32 v33, -v33, v36, v35
	v_div_fmas_f32 v33, v33, v34, v36
	v_div_fixup_f32 v32, v33, v32, 1.0
	v_bfe_u32 v33, v32, 16, 1
	v_add3_u32 v32, v32, v33, s83
	s_and_b64 vcc, exec, s[6:7]
	ds_write_b16_d16_hi v61, v32 offset:64
	v_mul_f32_e32 v32, 0xbfb8aa3b, v45
	v_exp_f32_e32 v32, v32
	s_nop 0
	v_add_f32_e32 v32, 1.0, v32
	v_div_scale_f32 v33, s[8:9], v32, v32, 1.0
	v_rcp_f32_e32 v34, v33
	v_div_scale_f32 v35, vcc, 1.0, v32, 1.0
	v_fma_f32 v36, -v33, v34, 1.0
	v_fmac_f32_e32 v34, v36, v34
	v_mul_f32_e32 v36, v35, v34
	v_fma_f32 v37, -v33, v36, v35
	v_fmac_f32_e32 v36, v37, v34
	v_fma_f32 v33, -v33, v36, v35
	v_div_fmas_f32 v33, v33, v34, v36
	v_div_fixup_f32 v32, v33, v32, 1.0
	v_bfe_u32 v33, v32, 16, 1
	v_add3_u32 v32, v32, v33, s83
	s_and_b64 vcc, exec, s[6:7]
	ds_write_b16_d16_hi v62, v32 offset:64
	v_mul_f32_e32 v32, 0xbfb8aa3b, v46
	v_exp_f32_e32 v32, v32
	s_nop 0
	v_add_f32_e32 v32, 1.0, v32
	v_div_scale_f32 v33, s[8:9], v32, v32, 1.0
	v_rcp_f32_e32 v34, v33
	v_div_scale_f32 v35, vcc, 1.0, v32, 1.0
	v_fma_f32 v36, -v33, v34, 1.0
	v_fmac_f32_e32 v34, v36, v34
	v_mul_f32_e32 v36, v35, v34
	v_fma_f32 v37, -v33, v36, v35
	v_fmac_f32_e32 v36, v37, v34
	v_fma_f32 v33, -v33, v36, v35
	v_div_fmas_f32 v33, v33, v34, v36
	v_div_fixup_f32 v32, v33, v32, 1.0
	v_bfe_u32 v33, v32, 16, 1
	v_add3_u32 v32, v32, v33, s83
	s_and_b64 vcc, exec, s[6:7]
	ds_write_b16_d16_hi v55, v32 offset:64
	v_mul_f32_e32 v32, 0xbfb8aa3b, v47
	v_exp_f32_e32 v32, v32
	s_nop 0
	v_add_f32_e32 v32, 1.0, v32
	v_div_scale_f32 v33, s[4:5], v32, v32, 1.0
	v_rcp_f32_e32 v34, v33
	v_div_scale_f32 v35, vcc, 1.0, v32, 1.0
	v_fma_f32 v36, -v33, v34, 1.0
	v_fmac_f32_e32 v34, v36, v34
	v_mul_f32_e32 v36, v35, v34
	v_fma_f32 v37, -v33, v36, v35
	v_fmac_f32_e32 v36, v37, v34
	v_fma_f32 v33, -v33, v36, v35
	v_div_fmas_f32 v33, v33, v34, v36
	v_div_fixup_f32 v32, v33, v32, 1.0
	s_branch .LBB0_3559

; __device__ __forceinline__ float sigmf(float x) { return 1.f / (1.f + __expf(-x)); }
; __device__ __forceinline__ void inproj_epilogue(const Params& p, int layer, int mt, int ntile, int tid,
;                                                 f32x16 (&acc)[2][2], unsigned char* smem) {
;     ...
;     acc_foreach(tid, acc, [&](int row, int col, float v) {
;       int t = m0 + row;
;       float o = v;
;       if (mode == 1) o = (t >= NPADR) ? v : 0.f;
;       if (mode == 2) o = sigmf(v);
;       sT[row * 136 + col] = f2bf(o);
;     });
.LBB0_4154:
	v_bfe_u32 v110, v107, 16, 1
	v_and_b32_e32 v106, 0x5f, v106
	v_add3_u32 v111, v107, v110, s80
	v_mul_lo_u32 v110, v96, s81
	v_lshl_add_u32 v107, v106, 1, v110
	ds_write_b16_d16_hi v107, v111
	v_add3_u32 v111, s74, v96, 1
	v_cndmask_b32_e64 v112, 0, 1, s[10:11]
	v_cmp_ne_u32_e64 s[6:7], 1, v112
	v_cmp_lt_i32_e64 s[10:11], s78, v111
	s_nop 1

; __device__ __forceinline__ float sigmf(float x) { return 1.f / (1.f + __expf(-x)); }
; __device__ __forceinline__ void inproj_epilogue(const Params& p, int layer, int mt, int ntile, int tid,
;                                                 f32x16 (&acc)[2][2], unsigned char* smem) {
;     ...
;     acc_foreach(tid, acc, [&](int row, int col, float v) {
;       int t = m0 + row;
;       float o = v;
;       if (mode == 1) o = (t >= NPADR) ? v : 0.f;
;       if (mode == 2) o = sigmf(v);
;       sT[row * 136 + col] = f2bf(o);
;     });
.LBB0_4157:
	v_bfe_u32 v112, v111, 16, 1
	v_add3_u32 v112, v111, v112, s80
	v_add_u32_e32 v111, 0x110, v110
	v_lshl_add_u32 v110, v106, 1, v111
	ds_write_b16_d16_hi v110, v112
	v_add3_u32 v112, s74, v96, 2
	v_cmp_lt_i32_e64 s[12:13], s78, v112
	s_nop 1

; __device__ __forceinline__ float sigmf(float x) { return 1.f / (1.f + __expf(-x)); }
; __device__ __forceinline__ void inproj_epilogue(const Params& p, int layer, int mt, int ntile, int tid,
;                                                 f32x16 (&acc)[2][2], unsigned char* smem) {
;     ...
;     acc_foreach(tid, acc, [&](int row, int col, float v) {
;       int t = m0 + row;
;       float o = v;
;       if (mode == 1) o = (t >= NPADR) ? v : 0.f;
;       if (mode == 2) o = sigmf(v);
;       sT[row * 136 + col] = f2bf(o);
;     });
.LBB0_4160:
	v_bfe_u32 v113, v112, 16, 1
	v_add3_u32 v113, v112, v113, s80
	v_add_u32_e32 v112, 0x110, v111
	v_lshl_add_u32 v111, v106, 1, v112
	ds_write_b16_d16_hi v111, v113
	v_add3_u32 v113, s74, v96, 3
	v_cmp_lt_i32_e64 s[14:15], s78, v113
	s_nop 1

; __device__ __forceinline__ float sigmf(float x) { return 1.f / (1.f + __expf(-x)); }
; __device__ __forceinline__ void inproj_epilogue(const Params& p, int layer, int mt, int ntile, int tid,
;                                                 f32x16 (&acc)[2][2], unsigned char* smem) {
;     ...
;     acc_foreach(tid, acc, [&](int row, int col, float v) {
;       int t = m0 + row;
;       float o = v;
;       if (mode == 1) o = (t >= NPADR) ? v : 0.f;
;       if (mode == 2) o = sigmf(v);
;       sT[row * 136 + col] = f2bf(o);
;     });
.LBB0_4163:
	v_bfe_u32 v114, v113, 16, 1
	v_add3_u32 v114, v113, v114, s80
	v_add_u32_e32 v113, 0x110, v112
	v_lshl_add_u32 v112, v106, 1, v113
	ds_write_b16_d16_hi v112, v114
	v_add3_u32 v114, s74, v96, 8
	v_cmp_lt_i32_e64 s[16:17], s78, v114
	s_nop 1

; __device__ __forceinline__ float sigmf(float x) { return 1.f / (1.f + __expf(-x)); }
; __device__ __forceinline__ void inproj_epilogue(const Params& p, int layer, int mt, int ntile, int tid,
;                                                 f32x16 (&acc)[2][2], unsigned char* smem) {
;     ...
;     acc_foreach(tid, acc, [&](int row, int col, float v) {
;       int t = m0 + row;
;       float o = v;
;       if (mode == 1) o = (t >= NPADR) ? v : 0.f;
;       if (mode == 2) o = sigmf(v);
;       sT[row * 136 + col] = f2bf(o);
;     });
.LBB0_4166:
	v_bfe_u32 v115, v114, 16, 1
	v_add3_u32 v115, v114, v115, s80
	v_add_u32_e32 v114, 0x550, v113
	v_lshl_add_u32 v113, v106, 1, v114
	ds_write_b16_d16_hi v113, v115
	v_add3_u32 v115, s74, v96, 9
	v_cmp_lt_i32_e64 s[18:19], s78, v115
	s_nop 1

; __device__ __forceinline__ float sigmf(float x) { return 1.f / (1.f + __expf(-x)); }
; __device__ __forceinline__ void inproj_epilogue(const Params& p, int layer, int mt, int ntile, int tid,
;                                                 f32x16 (&acc)[2][2], unsigned char* smem) {
;     ...
;     acc_foreach(tid, acc, [&](int row, int col, float v) {
;       int t = m0 + row;
;       float o = v;
;       if (mode == 1) o = (t >= NPADR) ? v : 0.f;
;       if (mode == 2) o = sigmf(v);
;       sT[row * 136 + col] = f2bf(o);
;     });
.LBB0_4169:
	v_bfe_u32 v116, v115, 16, 1
	v_add3_u32 v116, v115, v116, s80
	v_add_u32_e32 v115, 0x110, v114
	v_lshl_add_u32 v114, v106, 1, v115
	ds_write_b16_d16_hi v114, v116
	v_add3_u32 v116, s74, v96, 10
	v_cmp_lt_i32_e64 s[20:21], s78, v116
	s_nop 1

; __device__ __forceinline__ float sigmf(float x) { return 1.f / (1.f + __expf(-x)); }
; __device__ __forceinline__ void inproj_epilogue(const Params& p, int layer, int mt, int ntile, int tid,
;                                                 f32x16 (&acc)[2][2], unsigned char* smem) {
;     ...
;     acc_foreach(tid, acc, [&](int row, int col, float v) {
;       int t = m0 + row;
;       float o = v;
;       if (mode == 1) o = (t >= NPADR) ? v : 0.f;
;       if (mode == 2) o = sigmf(v);
;       sT[row * 136 + col] = f2bf(o);
;     });
.LBB0_4172:
	v_bfe_u32 v117, v116, 16, 1
	v_add3_u32 v117, v116, v117, s80
	v_add_u32_e32 v116, 0x110, v115
	v_lshl_add_u32 v115, v106, 1, v116
	ds_write_b16_d16_hi v115, v117
	v_add3_u32 v117, s74, v96, 11
	v_cmp_lt_i32_e64 s[22:23], s78, v117
	s_nop 1

; __device__ __forceinline__ float sigmf(float x) { return 1.f / (1.f + __expf(-x)); }
; __device__ __forceinline__ void inproj_epilogue(const Params& p, int layer, int mt, int ntile, int tid,
;                                                 f32x16 (&acc)[2][2], unsigned char* smem) {
;     ...
;     acc_foreach(tid, acc, [&](int row, int col, float v) {
;       int t = m0 + row;
;       float o = v;
;       if (mode == 1) o = (t >= NPADR) ? v : 0.f;
;       if (mode == 2) o = sigmf(v);
;       sT[row * 136 + col] = f2bf(o);
;     });
.LBB0_4175:
	v_bfe_u32 v118, v117, 16, 1
	v_add_u32_e32 v116, 0x110, v116
	v_add3_u32 v118, v117, v118, s80
	v_lshl_add_u32 v117, v106, 1, v116
	ds_write_b16_d16_hi v117, v118
	v_add3_u32 v118, s74, v96, 16
	v_cmp_lt_i32_e64 s[24:25], s78, v118
	s_nop 1

; __device__ __forceinline__ float sigmf(float x) { return 1.f / (1.f + __expf(-x)); }
; __device__ __forceinline__ void inproj_epilogue(const Params& p, int layer, int mt, int ntile, int tid,
;                                                 f32x16 (&acc)[2][2], unsigned char* smem) {
;     ...
;     acc_foreach(tid, acc, [&](int row, int col, float v) {
;       int t = m0 + row;
;       float o = v;
;       if (mode == 1) o = (t >= NPADR) ? v : 0.f;
;       if (mode == 2) o = sigmf(v);
;       sT[row * 136 + col] = f2bf(o);
;     });
.LBB0_4178:
	v_bfe_u32 v119, v118, 16, 1
	v_add_u32_e32 v116, 0x550, v116
	v_add3_u32 v119, v118, v119, s80
	v_lshl_add_u32 v118, v106, 1, v116
	ds_write_b16_d16_hi v118, v119
	v_add3_u32 v119, s74, v96, 17
	v_cmp_lt_i32_e64 s[26:27], s78, v119
	s_nop 1

; __device__ __forceinline__ float sigmf(float x) { return 1.f / (1.f + __expf(-x)); }
; __device__ __forceinline__ void inproj_epilogue(const Params& p, int layer, int mt, int ntile, int tid,
;                                                 f32x16 (&acc)[2][2], unsigned char* smem) {
;     ...
;     acc_foreach(tid, acc, [&](int row, int col, float v) {
;       int t = m0 + row;
;       float o = v;
;       if (mode == 1) o = (t >= NPADR) ? v : 0.f;
;       if (mode == 2) o = sigmf(v);
;       sT[row * 136 + col] = f2bf(o);
;     });
.LBB0_4181:
	v_bfe_u32 v120, v119, 16, 1
	v_add_u32_e32 v116, 0x110, v116
	v_add3_u32 v120, v119, v120, s80
	v_lshl_add_u32 v119, v106, 1, v116
	ds_write_b16_d16_hi v119, v120
	v_add3_u32 v120, s74, v96, 18
	v_cmp_lt_i32_e64 s[28:29], s78, v120
	s_nop 1

; __device__ __forceinline__ float sigmf(float x) { return 1.f / (1.f + __expf(-x)); }
; __device__ __forceinline__ void inproj_epilogue(const Params& p, int layer, int mt, int ntile, int tid,
;                                                 f32x16 (&acc)[2][2], unsigned char* smem) {
;     ...
;     acc_foreach(tid, acc, [&](int row, int col, float v) {
;       int t = m0 + row;
;       float o = v;
;       if (mode == 1) o = (t >= NPADR) ? v : 0.f;
;       if (mode == 2) o = sigmf(v);
;       sT[row * 136 + col] = f2bf(o);
;     });
.LBB0_4184:
	v_bfe_u32 v121, v120, 16, 1
	v_add_u32_e32 v116, 0x110, v116
	v_add3_u32 v121, v120, v121, s80
	v_lshl_add_u32 v120, v106, 1, v116
	ds_write_b16_d16_hi v120, v121
	v_add3_u32 v121, s74, v96, 19
	v_cmp_lt_i32_e64 s[30:31], s78, v121
	s_nop 1

; __device__ __forceinline__ float sigmf(float x) { return 1.f / (1.f + __expf(-x)); }
; __device__ __forceinline__ void inproj_epilogue(const Params& p, int layer, int mt, int ntile, int tid,
;                                                 f32x16 (&acc)[2][2], unsigned char* smem) {
;     ...
;     acc_foreach(tid, acc, [&](int row, int col, float v) {
;       int t = m0 + row;
;       float o = v;
;       if (mode == 1) o = (t >= NPADR) ? v : 0.f;
;       if (mode == 2) o = sigmf(v);
;       sT[row * 136 + col] = f2bf(o);
;     });
.LBB0_4187:
	v_bfe_u32 v122, v121, 16, 1
	v_add_u32_e32 v116, 0x110, v116
	v_add3_u32 v122, v121, v122, s80
	v_lshl_add_u32 v121, v106, 1, v116
	ds_write_b16_d16_hi v121, v122
	v_add3_u32 v122, s74, v96, 24
	v_cmp_lt_i32_e64 s[34:35], s78, v122
	s_nop 1

; __device__ __forceinline__ float sigmf(float x) { return 1.f / (1.f + __expf(-x)); }
; __device__ __forceinline__ void inproj_epilogue(const Params& p, int layer, int mt, int ntile, int tid,
;                                                 f32x16 (&acc)[2][2], unsigned char* smem) {
;     ...
;     acc_foreach(tid, acc, [&](int row, int col, float v) {
;       int t = m0 + row;
;       float o = v;
;       if (mode == 1) o = (t >= NPADR) ? v : 0.f;
;       if (mode == 2) o = sigmf(v);
;       sT[row * 136 + col] = f2bf(o);
;     });
.LBB0_4190:
	v_bfe_u32 v123, v122, 16, 1
	v_add_u32_e32 v116, 0x550, v116
	v_add3_u32 v123, v122, v123, s80
	v_lshl_add_u32 v122, v106, 1, v116
	ds_write_b16_d16_hi v122, v123
	v_add3_u32 v123, s74, v96, 25
	v_cmp_lt_i32_e64 s[36:37], s78, v123
	s_nop 1

; __device__ __forceinline__ float sigmf(float x) { return 1.f / (1.f + __expf(-x)); }
; __device__ __forceinline__ void inproj_epilogue(const Params& p, int layer, int mt, int ntile, int tid,
;                                                 f32x16 (&acc)[2][2], unsigned char* smem) {
;     ...
;     acc_foreach(tid, acc, [&](int row, int col, float v) {
;       int t = m0 + row;
;       float o = v;
;       if (mode == 1) o = (t >= NPADR) ? v : 0.f;
;       if (mode == 2) o = sigmf(v);
;       sT[row * 136 + col] = f2bf(o);
;     });
.LBB0_4193:
	v_bfe_u32 v124, v123, 16, 1
	v_add_u32_e32 v116, 0x110, v116
	v_add3_u32 v124, v123, v124, s80
	v_lshl_add_u32 v123, v106, 1, v116
	ds_write_b16_d16_hi v123, v124
	v_add3_u32 v124, s74, v96, 26
	v_cmp_lt_i32_e64 s[38:39], s78, v124
	s_nop 1

; __device__ __forceinline__ float sigmf(float x) { return 1.f / (1.f + __expf(-x)); }
; __device__ __forceinline__ void inproj_epilogue(const Params& p, int layer, int mt, int ntile, int tid,
;                                                 f32x16 (&acc)[2][2], unsigned char* smem) {
;     ...
;     acc_foreach(tid, acc, [&](int row, int col, float v) {
;       int t = m0 + row;
;       float o = v;
;       if (mode == 1) o = (t >= NPADR) ? v : 0.f;
;       if (mode == 2) o = sigmf(v);
;       sT[row * 136 + col] = f2bf(o);
;     });
.LBB0_4196:
	v_bfe_u32 v125, v124, 16, 1
	v_add_u32_e32 v116, 0x110, v116
	v_add3_u32 v124, v124, v125, s80
	v_lshl_add_u32 v116, v106, 1, v116
	ds_write_b16_d16_hi v116, v124
	v_add3_u32 v124, s74, v96, 27
	v_cmp_lt_i32_e64 s[40:41], s78, v124
	s_nop 1

; __device__ __forceinline__ float sigmf(float x) { return 1.f / (1.f + __expf(-x)); }
; __device__ __forceinline__ void inproj_epilogue(const Params& p, int layer, int mt, int ntile, int tid,
;                                                 f32x16 (&acc)[2][2], unsigned char* smem) {
;     ...
;     acc_foreach(tid, acc, [&](int row, int col, float v) {
;       int t = m0 + row;
;       float o = v;
;       if (mode == 1) o = (t >= NPADR) ? v : 0.f;
;       if (mode == 2) o = sigmf(v);
;       sT[row * 136 + col] = f2bf(o);
;     });
.LBB0_4199:
	v_bfe_u32 v125, v124, 16, 1
	v_add3_u32 v124, v124, v125, s80
	ds_write_b16_d16_hi v116, v124 offset:272
	s_nop 1

; __device__ __forceinline__ float sigmf(float x) { return 1.f / (1.f + __expf(-x)); }
; __device__ __forceinline__ void inproj_epilogue(const Params& p, int layer, int mt, int ntile, int tid,
;                                                 f32x16 (&acc)[2][2], unsigned char* smem) {
;     ...
;     acc_foreach(tid, acc, [&](int row, int col, float v) {
;       int t = m0 + row;
;       float o = v;
;       if (mode == 1) o = (t >= NPADR) ? v : 0.f;
;       if (mode == 2) o = sigmf(v);
;       sT[row * 136 + col] = f2bf(o);
;     });
.LBB0_4202:
	v_bfe_u32 v124, v48, 16, 1
	v_add3_u32 v48, v48, v124, s80
	ds_write_b16_d16_hi v107, v48 offset:64
	s_nop 1

; __device__ __forceinline__ float sigmf(float x) { return 1.f / (1.f + __expf(-x)); }
; __device__ __forceinline__ void inproj_epilogue(const Params& p, int layer, int mt, int ntile, int tid,
;                                                 f32x16 (&acc)[2][2], unsigned char* smem) {
;     ...
;     acc_foreach(tid, acc, [&](int row, int col, float v) {
;       int t = m0 + row;
;       float o = v;
;       if (mode == 1) o = (t >= NPADR) ? v : 0.f;
;       if (mode == 2) o = sigmf(v);
;       sT[row * 136 + col] = f2bf(o);
;     });
.LBB0_4205:
	v_bfe_u32 v49, v48, 16, 1
	v_add3_u32 v48, v48, v49, s80
	ds_write_b16_d16_hi v110, v48 offset:64
	s_nop 1

; __device__ __forceinline__ float sigmf(float x) { return 1.f / (1.f + __expf(-x)); }
; __device__ __forceinline__ void inproj_epilogue(const Params& p, int layer, int mt, int ntile, int tid,
;                                                 f32x16 (&acc)[2][2], unsigned char* smem) {
;     ...
;     acc_foreach(tid, acc, [&](int row, int col, float v) {
;       int t = m0 + row;
;       float o = v;
;       if (mode == 1) o = (t >= NPADR) ? v : 0.f;
;       if (mode == 2) o = sigmf(v);
;       sT[row * 136 + col] = f2bf(o);
;     });
.LBB0_4208:
	v_bfe_u32 v49, v48, 16, 1
	v_add3_u32 v48, v48, v49, s80
	ds_write_b16_d16_hi v111, v48 offset:64
	s_nop 1

; __device__ __forceinline__ float sigmf(float x) { return 1.f / (1.f + __expf(-x)); }
; __device__ __forceinline__ void inproj_epilogue(const Params& p, int layer, int mt, int ntile, int tid,
;                                                 f32x16 (&acc)[2][2], unsigned char* smem) {
;     ...
;     acc_foreach(tid, acc, [&](int row, int col, float v) {
;       int t = m0 + row;
;       float o = v;
;       if (mode == 1) o = (t >= NPADR) ? v : 0.f;
;       if (mode == 2) o = sigmf(v);
;       sT[row * 136 + col] = f2bf(o);
;     });
.LBB0_4211:
	v_bfe_u32 v49, v48, 16, 1
	v_add3_u32 v48, v48, v49, s80
	ds_write_b16_d16_hi v112, v48 offset:64
	s_nop 1

; __device__ __forceinline__ float sigmf(float x) { return 1.f / (1.f + __expf(-x)); }
; __device__ __forceinline__ void inproj_epilogue(const Params& p, int layer, int mt, int ntile, int tid,
;                                                 f32x16 (&acc)[2][2], unsigned char* smem) {
;     ...
;     acc_foreach(tid, acc, [&](int row, int col, float v) {
;       int t = m0 + row;
;       float o = v;
;       if (mode == 1) o = (t >= NPADR) ? v : 0.f;
;       if (mode == 2) o = sigmf(v);
;       sT[row * 136 + col] = f2bf(o);
;     });
.LBB0_4214:
	v_bfe_u32 v49, v48, 16, 1
	v_add3_u32 v48, v48, v49, s80
	ds_write_b16_d16_hi v113, v48 offset:64
	s_nop 1

; __device__ __forceinline__ float sigmf(float x) { return 1.f / (1.f + __expf(-x)); }
; __device__ __forceinline__ void inproj_epilogue(const Params& p, int layer, int mt, int ntile, int tid,
;                                                 f32x16 (&acc)[2][2], unsigned char* smem) {
;     ...
;     acc_foreach(tid, acc, [&](int row, int col, float v) {
;       int t = m0 + row;
;       float o = v;
;       if (mode == 1) o = (t >= NPADR) ? v : 0.f;
;       if (mode == 2) o = sigmf(v);
;       sT[row * 136 + col] = f2bf(o);
;     });
.LBB0_4217:
	v_bfe_u32 v49, v48, 16, 1
	v_add3_u32 v48, v48, v49, s80
	ds_write_b16_d16_hi v114, v48 offset:64
	s_nop 1

; __device__ __forceinline__ float sigmf(float x) { return 1.f / (1.f + __expf(-x)); }
; __device__ __forceinline__ void inproj_epilogue(const Params& p, int layer, int mt, int ntile, int tid,
;                                                 f32x16 (&acc)[2][2], unsigned char* smem) {
;     ...
;     acc_foreach(tid, acc, [&](int row, int col, float v) {
;       int t = m0 + row;
;       float o = v;
;       if (mode == 1) o = (t >= NPADR) ? v : 0.f;
;       if (mode == 2) o = sigmf(v);
;       sT[row * 136 + col] = f2bf(o);
;     });
.LBB0_4220:
	v_bfe_u32 v49, v48, 16, 1
	v_add3_u32 v48, v48, v49, s80
	ds_write_b16_d16_hi v115, v48 offset:64
	s_nop 1

; __device__ __forceinline__ float sigmf(float x) { return 1.f / (1.f + __expf(-x)); }
; __device__ __forceinline__ void inproj_epilogue(const Params& p, int layer, int mt, int ntile, int tid,
;                                                 f32x16 (&acc)[2][2], unsigned char* smem) {
;     ...
;     acc_foreach(tid, acc, [&](int row, int col, float v) {
;       int t = m0 + row;
;       float o = v;
;       if (mode == 1) o = (t >= NPADR) ? v : 0.f;
;       if (mode == 2) o = sigmf(v);
;       sT[row * 136 + col] = f2bf(o);
;     });
.LBB0_4223:
	v_bfe_u32 v49, v48, 16, 1
	v_add3_u32 v48, v48, v49, s80
	ds_write_b16_d16_hi v117, v48 offset:64
	s_nop 1

; __device__ __forceinline__ float sigmf(float x) { return 1.f / (1.f + __expf(-x)); }
; __device__ __forceinline__ void inproj_epilogue(const Params& p, int layer, int mt, int ntile, int tid,
;                                                 f32x16 (&acc)[2][2], unsigned char* smem) {
;     ...
;     acc_foreach(tid, acc, [&](int row, int col, float v) {
;       int t = m0 + row;
;       float o = v;
;       if (mode == 1) o = (t >= NPADR) ? v : 0.f;
;       if (mode == 2) o = sigmf(v);
;       sT[row * 136 + col] = f2bf(o);
;     });
.LBB0_4226:
	v_bfe_u32 v49, v48, 16, 1
	v_add3_u32 v48, v48, v49, s80
	ds_write_b16_d16_hi v118, v48 offset:64
	s_nop 1

; __device__ __forceinline__ float sigmf(float x) { return 1.f / (1.f + __expf(-x)); }
; __device__ __forceinline__ bf16r f2bf(float f) {
;   unsigned u = __float_as_uint(f);
;   u += 0x7fffu + ((u >> 16) & 1u);
;   return (bf16r)(u >> 16);
; }
; __device__ __forceinline__ void inproj_epilogue(const Params& p, int layer, int mt, int ntile, int tid,
;                                                 f32x16 (&acc)[2][2], unsigned char* smem) {
;     ...
;     acc_foreach(tid, acc, [&](int row, int col, float v) {
;       int t = m0 + row;
;       float o = v;
;       if (mode == 1) o = (t >= NPADR) ? v : 0.f;
;       if (mode == 2) o = sigmf(v);
;       sT[row * 136 + col] = f2bf(o);
;     });
.LBB0_4229:
	v_bfe_u32 v49, v48, 16, 1
	v_add3_u32 v48, v48, v49, s80
	ds_write_b16_d16_hi v119, v48 offset:64
	s_nop 1

; __device__ __forceinline__ float sigmf(float x) { return 1.f / (1.f + __expf(-x)); }
; __device__ __forceinline__ bf16r f2bf(float f) {
;   unsigned u = __float_as_uint(f);
;   u += 0x7fffu + ((u >> 16) & 1u);
;   return (bf16r)(u >> 16);
; }
; __device__ __forceinline__ void inproj_epilogue(const Params& p, int layer, int mt, int ntile, int tid,
;                                                 f32x16 (&acc)[2][2], unsigned char* smem) {
;     ...
;     acc_foreach(tid, acc, [&](int row, int col, float v) {
;       int t = m0 + row;
;       float o = v;
;       if (mode == 1) o = (t >= NPADR) ? v : 0.f;
;       if (mode == 2) o = sigmf(v);
;       sT[row * 136 + col] = f2bf(o);
;     });
.LBB0_4232:
	v_bfe_u32 v49, v48, 16, 1
	v_add3_u32 v48, v48, v49, s80
	ds_write_b16_d16_hi v120, v48 offset:64
	s_nop 1

; __device__ __forceinline__ float sigmf(float x) { return 1.f / (1.f + __expf(-x)); }
; __device__ __forceinline__ bf16r f2bf(float f) {
;   unsigned u = __float_as_uint(f);
;   u += 0x7fffu + ((u >> 16) & 1u);
;   return (bf16r)(u >> 16);
; }
; __device__ __forceinline__ void inproj_epilogue(const Params& p, int layer, int mt, int ntile, int tid,
;                                                 f32x16 (&acc)[2][2], unsigned char* smem) {
;     ...
;     acc_foreach(tid, acc, [&](int row, int col, float v) {
;       int t = m0 + row;
;       float o = v;
;       if (mode == 1) o = (t >= NPADR) ? v : 0.f;
;       if (mode == 2) o = sigmf(v);
;       sT[row * 136 + col] = f2bf(o);
;     });
.LBB0_4235:
	v_bfe_u32 v49, v48, 16, 1
	v_add3_u32 v48, v48, v49, s80
	ds_write_b16_d16_hi v121, v48 offset:64
	s_nop 1

; __device__ __forceinline__ float sigmf(float x) { return 1.f / (1.f + __expf(-x)); }
; __device__ __forceinline__ bf16r f2bf(float f) {
;   unsigned u = __float_as_uint(f);
;   u += 0x7fffu + ((u >> 16) & 1u);
;   return (bf16r)(u >> 16);
; }
; __device__ __forceinline__ void inproj_epilogue(const Params& p, int layer, int mt, int ntile, int tid,
;                                                 f32x16 (&acc)[2][2], unsigned char* smem) {
;     ...
;     acc_foreach(tid, acc, [&](int row, int col, float v) {
;       int t = m0 + row;
;       float o = v;
;       if (mode == 1) o = (t >= NPADR) ? v : 0.f;
;       if (mode == 2) o = sigmf(v);
;       sT[row * 136 + col] = f2bf(o);
;     });
.LBB0_4238:
	v_bfe_u32 v49, v48, 16, 1
	v_add3_u32 v48, v48, v49, s80
	ds_write_b16_d16_hi v122, v48 offset:64
	s_nop 1

; __device__ __forceinline__ float sigmf(float x) { return 1.f / (1.f + __expf(-x)); }
; __device__ __forceinline__ bf16r f2bf(float f) {
;   unsigned u = __float_as_uint(f);
;   u += 0x7fffu + ((u >> 16) & 1u);
;   return (bf16r)(u >> 16);
; }
; __device__ __forceinline__ void inproj_epilogue(const Params& p, int layer, int mt, int ntile, int tid,
;                                                 f32x16 (&acc)[2][2], unsigned char* smem) {
;     ...
;     acc_foreach(tid, acc, [&](int row, int col, float v) {
;       int t = m0 + row;
;       float o = v;
;       if (mode == 1) o = (t >= NPADR) ? v : 0.f;
;       if (mode == 2) o = sigmf(v);
;       sT[row * 136 + col] = f2bf(o);
;     });
.LBB0_4241:
	v_bfe_u32 v49, v48, 16, 1
	v_add3_u32 v48, v48, v49, s80
	ds_write_b16_d16_hi v123, v48 offset:64
	s_nop 1

; __device__ __forceinline__ float sigmf(float x) { return 1.f / (1.f + __expf(-x)); }
; __device__ __forceinline__ bf16r f2bf(float f) {
;   unsigned u = __float_as_uint(f);
;   u += 0x7fffu + ((u >> 16) & 1u);
;   return (bf16r)(u >> 16);
; }
; __device__ __forceinline__ void inproj_epilogue(const Params& p, int layer, int mt, int ntile, int tid,
;                                                 f32x16 (&acc)[2][2], unsigned char* smem) {
;     ...
;     acc_foreach(tid, acc, [&](int row, int col, float v) {
;       int t = m0 + row;
;       float o = v;
;       if (mode == 1) o = (t >= NPADR) ? v : 0.f;
;       if (mode == 2) o = sigmf(v);
;       sT[row * 136 + col] = f2bf(o);
;     });
.LBB0_4244:
	v_bfe_u32 v49, v48, 16, 1
	v_add3_u32 v48, v48, v49, s80
	ds_write_b16_d16_hi v116, v48 offset:64
	s_nop 1

; __device__ __forceinline__ float sigmf(float x) { return 1.f / (1.f + __expf(-x)); }
; template <int MT, int NT, class F>
; __device__ __forceinline__ void acc_foreach(int tid, f32x16 (&acc)[MT][NT], F f) {
;     ...
;   const int wm = w >> 1, wn = w & 1, hi = lane >> 5, c = lane & 31;
; #pragma unroll
;   for (int mt = 0; mt < MT; mt++)
; #pragma unroll
;     for (int nt = 0; nt < NT; nt++)
; #pragma unroll
;       for (int i = 0; i < 16; i++) {
;         int row = wm * (MT * 32) + mt * 32 + (i & 3) + 8 * (i >> 2) + 4 * hi;
;         int col = wn * (NT * 32) + nt * 32 + c;
;         f(row, col, acc[mt][nt][i]);
; __device__ __forceinline__ void inproj_epilogue(const Params& p, int layer, int mt, int ntile, int tid,
;                                                 f32x16 (&acc)[2][2], unsigned char* smem) {
;     ...
;     acc_foreach(tid, acc, [&](int row, int col, float v) {
;       int t = m0 + row;
;       float o = v;
;       if (mode == 1) o = (t >= NPADR) ? v : 0.f;
;       if (mode == 2) o = sigmf(v);
;       sT[row * 136 + col] = f2bf(o);
;     });
.LBB0_4247:
	v_bfe_u32 v50, v48, 16, 1
	v_add_u32_e32 v49, 0x110, v116
	v_add3_u32 v48, v48, v50, s80
	ds_write_b16_d16_hi v49, v48 offset:64
	v_or_b32_e32 v48, 32, v96
	v_add_u32_e32 v49, s74, v48
	v_cmp_lt_i32_e64 s[8:9], s78, v49
	s_nop 1

; __device__ __forceinline__ float sigmf(float x) { return 1.f / (1.f + __expf(-x)); }
; template <int MT, int NT, class F>
; __device__ __forceinline__ void acc_foreach(int tid, f32x16 (&acc)[MT][NT], F f) {
;     ...
;   const int wm = w >> 1, wn = w & 1, hi = lane >> 5, c = lane & 31;
; #pragma unroll
;   for (int mt = 0; mt < MT; mt++)
; #pragma unroll
;     for (int nt = 0; nt < NT; nt++)
; #pragma unroll
;       for (int i = 0; i < 16; i++) {
;         int row = wm * (MT * 32) + mt * 32 + (i & 3) + 8 * (i >> 2) + 4 * hi;
;         int col = wn * (NT * 32) + nt * 32 + c;
;         f(row, col, acc[mt][nt][i]);
; __device__ __forceinline__ void inproj_epilogue(const Params& p, int layer, int mt, int ntile, int tid,
;                                                 f32x16 (&acc)[2][2], unsigned char* smem) {
;     ...
;     acc_foreach(tid, acc, [&](int row, int col, float v) {
;       int t = m0 + row;
;       float o = v;
;       if (mode == 1) o = (t >= NPADR) ? v : 0.f;
;       if (mode == 2) o = sigmf(v);
;       sT[row * 136 + col] = f2bf(o);
;     });
.LBB0_4250:
	v_bfe_u32 v50, v49, 16, 1
	v_add3_u32 v50, v49, v50, s80
	v_mul_lo_u32 v49, v48, s81
	v_lshl_add_u32 v48, v106, 1, v49
	ds_write_b16_d16_hi v48, v50
	v_add3_u32 v50, s74, v96, 33
	v_cmp_lt_i32_e64 s[10:11], s78, v50
	s_nop 1

; __device__ __forceinline__ float sigmf(float x) { return 1.f / (1.f + __expf(-x)); }
; __device__ __forceinline__ bf16r f2bf(float f) {
;   unsigned u = __float_as_uint(f);
;   u += 0x7fffu + ((u >> 16) & 1u);
;   return (bf16r)(u >> 16);
; }
; __device__ __forceinline__ void inproj_epilogue(const Params& p, int layer, int mt, int ntile, int tid,
;                                                 f32x16 (&acc)[2][2], unsigned char* smem) {
;     ...
;     acc_foreach(tid, acc, [&](int row, int col, float v) {
;       int t = m0 + row;
;       float o = v;
;       if (mode == 1) o = (t >= NPADR) ? v : 0.f;
;       if (mode == 2) o = sigmf(v);
;       sT[row * 136 + col] = f2bf(o);
;     });
.LBB0_4253:
	v_bfe_u32 v51, v50, 16, 1
	v_add3_u32 v51, v50, v51, s80
	v_add_u32_e32 v50, 0x110, v49
	v_lshl_add_u32 v49, v106, 1, v50
	ds_write_b16_d16_hi v49, v51
	v_add3_u32 v51, s74, v96, 34
	v_cmp_lt_i32_e64 s[12:13], s78, v51
	s_nop 1

; __device__ __forceinline__ float sigmf(float x) { return 1.f / (1.f + __expf(-x)); }
; __device__ __forceinline__ bf16r f2bf(float f) {
;   unsigned u = __float_as_uint(f);
;   u += 0x7fffu + ((u >> 16) & 1u);
;   return (bf16r)(u >> 16);
; }
; __device__ __forceinline__ void inproj_epilogue(const Params& p, int layer, int mt, int ntile, int tid,
;                                                 f32x16 (&acc)[2][2], unsigned char* smem) {
;     ...
;     acc_foreach(tid, acc, [&](int row, int col, float v) {
;       int t = m0 + row;
;       float o = v;
;       if (mode == 1) o = (t >= NPADR) ? v : 0.f;
;       if (mode == 2) o = sigmf(v);
;       sT[row * 136 + col] = f2bf(o);
;     });
.LBB0_4256:
	v_bfe_u32 v52, v51, 16, 1
	v_add3_u32 v52, v51, v52, s80
	v_add_u32_e32 v51, 0x110, v50
	v_lshl_add_u32 v50, v106, 1, v51
	ds_write_b16_d16_hi v50, v52
	v_add3_u32 v52, s74, v96, 35
	v_cmp_lt_i32_e64 s[14:15], s78, v52
	s_nop 1

; __device__ __forceinline__ float sigmf(float x) { return 1.f / (1.f + __expf(-x)); }
; __device__ __forceinline__ bf16r f2bf(float f) {
;   unsigned u = __float_as_uint(f);
;   u += 0x7fffu + ((u >> 16) & 1u);
;   return (bf16r)(u >> 16);
; }
; __device__ __forceinline__ void inproj_epilogue(const Params& p, int layer, int mt, int ntile, int tid,
;                                                 f32x16 (&acc)[2][2], unsigned char* smem) {
;     ...
;     acc_foreach(tid, acc, [&](int row, int col, float v) {
;       int t = m0 + row;
;       float o = v;
;       if (mode == 1) o = (t >= NPADR) ? v : 0.f;
;       if (mode == 2) o = sigmf(v);
;       sT[row * 136 + col] = f2bf(o);
;     });
.LBB0_4259:
	v_bfe_u32 v53, v52, 16, 1
	v_add3_u32 v53, v52, v53, s80
	v_add_u32_e32 v52, 0x110, v51
	v_lshl_add_u32 v51, v106, 1, v52
	ds_write_b16_d16_hi v51, v53
	v_add3_u32 v53, s74, v96, 40
	v_cmp_lt_i32_e64 s[16:17], s78, v53
	s_nop 1

; __device__ __forceinline__ float sigmf(float x) { return 1.f / (1.f + __expf(-x)); }
; __device__ __forceinline__ bf16r f2bf(float f) {
;   unsigned u = __float_as_uint(f);
;   u += 0x7fffu + ((u >> 16) & 1u);
;   return (bf16r)(u >> 16);
; }
; __device__ __forceinline__ void inproj_epilogue(const Params& p, int layer, int mt, int ntile, int tid,
;                                                 f32x16 (&acc)[2][2], unsigned char* smem) {
;     ...
;     acc_foreach(tid, acc, [&](int row, int col, float v) {
;       int t = m0 + row;
;       float o = v;
;       if (mode == 1) o = (t >= NPADR) ? v : 0.f;
;       if (mode == 2) o = sigmf(v);
;       sT[row * 136 + col] = f2bf(o);
;     });
.LBB0_4262:
	v_bfe_u32 v54, v53, 16, 1
	v_add3_u32 v54, v53, v54, s80
	v_add_u32_e32 v53, 0x550, v52
	v_lshl_add_u32 v52, v106, 1, v53
	ds_write_b16_d16_hi v52, v54
	v_add3_u32 v54, s74, v96, 41
	v_cmp_lt_i32_e64 s[18:19], s78, v54
	s_nop 1

; __device__ __forceinline__ float sigmf(float x) { return 1.f / (1.f + __expf(-x)); }
; __device__ __forceinline__ bf16r f2bf(float f) {
;   unsigned u = __float_as_uint(f);
;   u += 0x7fffu + ((u >> 16) & 1u);
;   return (bf16r)(u >> 16);
; }
; __device__ __forceinline__ void inproj_epilogue(const Params& p, int layer, int mt, int ntile, int tid,
;                                                 f32x16 (&acc)[2][2], unsigned char* smem) {
;     ...
;     acc_foreach(tid, acc, [&](int row, int col, float v) {
;       int t = m0 + row;
;       float o = v;
;       if (mode == 1) o = (t >= NPADR) ? v : 0.f;
;       if (mode == 2) o = sigmf(v);
;       sT[row * 136 + col] = f2bf(o);
;     });
.LBB0_4265:
	v_bfe_u32 v55, v54, 16, 1
	v_add3_u32 v55, v54, v55, s80
	v_add_u32_e32 v54, 0x110, v53
	v_lshl_add_u32 v53, v106, 1, v54
	ds_write_b16_d16_hi v53, v55
	v_add3_u32 v55, s74, v96, 42
	v_cmp_lt_i32_e64 s[20:21], s78, v55
	s_nop 1

; __device__ __forceinline__ float sigmf(float x) { return 1.f / (1.f + __expf(-x)); }
; __device__ __forceinline__ bf16r f2bf(float f) {
;   unsigned u = __float_as_uint(f);
;   u += 0x7fffu + ((u >> 16) & 1u);
;   return (bf16r)(u >> 16);
; }
; __device__ __forceinline__ void inproj_epilogue(const Params& p, int layer, int mt, int ntile, int tid,
;                                                 f32x16 (&acc)[2][2], unsigned char* smem) {
;     ...
;     acc_foreach(tid, acc, [&](int row, int col, float v) {
;       int t = m0 + row;
;       float o = v;
;       if (mode == 1) o = (t >= NPADR) ? v : 0.f;
;       if (mode == 2) o = sigmf(v);
;       sT[row * 136 + col] = f2bf(o);
;     });
.LBB0_4268:
	v_bfe_u32 v56, v55, 16, 1
	v_add3_u32 v56, v55, v56, s80
	v_add_u32_e32 v55, 0x110, v54
	v_lshl_add_u32 v54, v106, 1, v55
	ds_write_b16_d16_hi v54, v56
	v_add3_u32 v56, s74, v96, 43
	v_cmp_lt_i32_e64 s[22:23], s78, v56
	s_nop 1

; __device__ __forceinline__ float sigmf(float x) { return 1.f / (1.f + __expf(-x)); }
; __device__ __forceinline__ bf16r f2bf(float f) {
;   unsigned u = __float_as_uint(f);
;   u += 0x7fffu + ((u >> 16) & 1u);
;   return (bf16r)(u >> 16);
; }
; __device__ __forceinline__ void inproj_epilogue(const Params& p, int layer, int mt, int ntile, int tid,
;                                                 f32x16 (&acc)[2][2], unsigned char* smem) {
;     ...
;     acc_foreach(tid, acc, [&](int row, int col, float v) {
;       int t = m0 + row;
;       float o = v;
;       if (mode == 1) o = (t >= NPADR) ? v : 0.f;
;       if (mode == 2) o = sigmf(v);
;       sT[row * 136 + col] = f2bf(o);
;     });
.LBB0_4271:
	v_bfe_u32 v57, v56, 16, 1
	v_add_u32_e32 v55, 0x110, v55
	v_add3_u32 v57, v56, v57, s80
	v_lshl_add_u32 v56, v106, 1, v55
	ds_write_b16_d16_hi v56, v57
	v_add3_u32 v57, s74, v96, 48
	v_cmp_lt_i32_e64 s[24:25], s78, v57
	s_nop 1

; __device__ __forceinline__ float sigmf(float x) { return 1.f / (1.f + __expf(-x)); }
; __device__ __forceinline__ bf16r f2bf(float f) {
;   unsigned u = __float_as_uint(f);
;   u += 0x7fffu + ((u >> 16) & 1u);
;   return (bf16r)(u >> 16);
; }
; __device__ __forceinline__ void inproj_epilogue(const Params& p, int layer, int mt, int ntile, int tid,
;                                                 f32x16 (&acc)[2][2], unsigned char* smem) {
;     ...
;     acc_foreach(tid, acc, [&](int row, int col, float v) {
;       int t = m0 + row;
;       float o = v;
;       if (mode == 1) o = (t >= NPADR) ? v : 0.f;
;       if (mode == 2) o = sigmf(v);
;       sT[row * 136 + col] = f2bf(o);
;     });
.LBB0_4274:
	v_bfe_u32 v58, v57, 16, 1
	v_add_u32_e32 v55, 0x550, v55
	v_add3_u32 v58, v57, v58, s80
	v_lshl_add_u32 v57, v106, 1, v55
	ds_write_b16_d16_hi v57, v58
	v_add3_u32 v58, s74, v96, 49
	v_cmp_lt_i32_e64 s[26:27], s78, v58
	s_nop 1

; __device__ __forceinline__ float sigmf(float x) { return 1.f / (1.f + __expf(-x)); }
; __device__ __forceinline__ bf16r f2bf(float f) {
;   unsigned u = __float_as_uint(f);
;   u += 0x7fffu + ((u >> 16) & 1u);
;   return (bf16r)(u >> 16);
; }
; __device__ __forceinline__ void inproj_epilogue(const Params& p, int layer, int mt, int ntile, int tid,
;                                                 f32x16 (&acc)[2][2], unsigned char* smem) {
;     ...
;     acc_foreach(tid, acc, [&](int row, int col, float v) {
;       int t = m0 + row;
;       float o = v;
;       if (mode == 1) o = (t >= NPADR) ? v : 0.f;
;       if (mode == 2) o = sigmf(v);
;       sT[row * 136 + col] = f2bf(o);
;     });
.LBB0_4277:
	v_bfe_u32 v59, v58, 16, 1
	v_add_u32_e32 v55, 0x110, v55
	v_add3_u32 v59, v58, v59, s80
	v_lshl_add_u32 v58, v106, 1, v55
	ds_write_b16_d16_hi v58, v59
	v_add3_u32 v59, s74, v96, 50
	v_cmp_lt_i32_e64 s[28:29], s78, v59
	s_nop 1

; __device__ __forceinline__ float sigmf(float x) { return 1.f / (1.f + __expf(-x)); }
; __device__ __forceinline__ bf16r f2bf(float f) {
;   unsigned u = __float_as_uint(f);
;   u += 0x7fffu + ((u >> 16) & 1u);
;   return (bf16r)(u >> 16);
; }
; __device__ __forceinline__ void inproj_epilogue(const Params& p, int layer, int mt, int ntile, int tid,
;                                                 f32x16 (&acc)[2][2], unsigned char* smem) {
;     ...
;     acc_foreach(tid, acc, [&](int row, int col, float v) {
;       int t = m0 + row;
;       float o = v;
;       if (mode == 1) o = (t >= NPADR) ? v : 0.f;
;       if (mode == 2) o = sigmf(v);
;       sT[row * 136 + col] = f2bf(o);
;     });
.LBB0_4280:
	v_bfe_u32 v60, v59, 16, 1
	v_add_u32_e32 v55, 0x110, v55
	v_add3_u32 v60, v59, v60, s80
	v_lshl_add_u32 v59, v106, 1, v55
	ds_write_b16_d16_hi v59, v60
	v_add3_u32 v60, s74, v96, 51
	v_cmp_lt_i32_e64 s[30:31], s78, v60
	s_nop 1

; __device__ __forceinline__ float sigmf(float x) { return 1.f / (1.f + __expf(-x)); }
; __device__ __forceinline__ bf16r f2bf(float f) {
;   unsigned u = __float_as_uint(f);
;   u += 0x7fffu + ((u >> 16) & 1u);
;   return (bf16r)(u >> 16);
; }
; __device__ __forceinline__ void inproj_epilogue(const Params& p, int layer, int mt, int ntile, int tid,
;                                                 f32x16 (&acc)[2][2], unsigned char* smem) {
;     ...
;     acc_foreach(tid, acc, [&](int row, int col, float v) {
;       int t = m0 + row;
;       float o = v;
;       if (mode == 1) o = (t >= NPADR) ? v : 0.f;
;       if (mode == 2) o = sigmf(v);
;       sT[row * 136 + col] = f2bf(o);
;     });
.LBB0_4283:
	v_bfe_u32 v61, v60, 16, 1
	v_add_u32_e32 v55, 0x110, v55
	v_add3_u32 v61, v60, v61, s80
	v_lshl_add_u32 v60, v106, 1, v55
	ds_write_b16_d16_hi v60, v61
	v_add3_u32 v61, s74, v96, 56
	v_cmp_lt_i32_e64 s[34:35], s78, v61
	s_nop 1

; __device__ __forceinline__ float sigmf(float x) { return 1.f / (1.f + __expf(-x)); }
; __device__ __forceinline__ bf16r f2bf(float f) {
;   unsigned u = __float_as_uint(f);
;   u += 0x7fffu + ((u >> 16) & 1u);
;   return (bf16r)(u >> 16);
; }
; __device__ __forceinline__ void inproj_epilogue(const Params& p, int layer, int mt, int ntile, int tid,
;                                                 f32x16 (&acc)[2][2], unsigned char* smem) {
;     ...
;     acc_foreach(tid, acc, [&](int row, int col, float v) {
;       int t = m0 + row;
;       float o = v;
;       if (mode == 1) o = (t >= NPADR) ? v : 0.f;
;       if (mode == 2) o = sigmf(v);
;       sT[row * 136 + col] = f2bf(o);
;     });
.LBB0_4286:
	v_bfe_u32 v62, v61, 16, 1
	v_add_u32_e32 v55, 0x550, v55
	v_add3_u32 v62, v61, v62, s80
	v_lshl_add_u32 v61, v106, 1, v55
	ds_write_b16_d16_hi v61, v62
	v_add3_u32 v62, s74, v96, 57
	v_cmp_lt_i32_e64 s[36:37], s78, v62
	s_nop 1

; __device__ __forceinline__ float sigmf(float x) { return 1.f / (1.f + __expf(-x)); }
; __device__ __forceinline__ bf16r f2bf(float f) {
;   unsigned u = __float_as_uint(f);
;   u += 0x7fffu + ((u >> 16) & 1u);
;   return (bf16r)(u >> 16);
; }
; __device__ __forceinline__ void inproj_epilogue(const Params& p, int layer, int mt, int ntile, int tid,
;                                                 f32x16 (&acc)[2][2], unsigned char* smem) {
;     ...
;     acc_foreach(tid, acc, [&](int row, int col, float v) {
;       int t = m0 + row;
;       float o = v;
;       if (mode == 1) o = (t >= NPADR) ? v : 0.f;
;       if (mode == 2) o = sigmf(v);
;       sT[row * 136 + col] = f2bf(o);
;     });
.LBB0_4289:
	v_bfe_u32 v63, v62, 16, 1
	v_add_u32_e32 v55, 0x110, v55
	v_add3_u32 v63, v62, v63, s80
	v_lshl_add_u32 v62, v106, 1, v55
	ds_write_b16_d16_hi v62, v63
	v_add3_u32 v63, s74, v96, 58
	v_cmp_lt_i32_e64 s[38:39], s78, v63
	s_nop 1

; __device__ __forceinline__ float sigmf(float x) { return 1.f / (1.f + __expf(-x)); }
; __device__ __forceinline__ bf16r f2bf(float f) {
;   unsigned u = __float_as_uint(f);
;   u += 0x7fffu + ((u >> 16) & 1u);
;   return (bf16r)(u >> 16);
; }
; __device__ __forceinline__ void inproj_epilogue(const Params& p, int layer, int mt, int ntile, int tid,
;                                                 f32x16 (&acc)[2][2], unsigned char* smem) {
;     ...
;     acc_foreach(tid, acc, [&](int row, int col, float v) {
;       int t = m0 + row;
;       float o = v;
;       if (mode == 1) o = (t >= NPADR) ? v : 0.f;
;       if (mode == 2) o = sigmf(v);
;       sT[row * 136 + col] = f2bf(o);
;     });
.LBB0_4292:
	v_bfe_u32 v107, v63, 16, 1
	v_add_u32_e32 v55, 0x110, v55
	v_add3_u32 v63, v63, v107, s80
	v_lshl_add_u32 v55, v106, 1, v55
	ds_write_b16_d16_hi v55, v63
	v_add3_u32 v63, s74, v96, 59
	v_cmp_lt_i32_e64 s[40:41], s78, v63
	s_nop 1

; __device__ __forceinline__ float sigmf(float x) { return 1.f / (1.f + __expf(-x)); }
; __device__ __forceinline__ bf16r f2bf(float f) {
;   unsigned u = __float_as_uint(f);
;   u += 0x7fffu + ((u >> 16) & 1u);
;   return (bf16r)(u >> 16);
; }
; __device__ __forceinline__ void inproj_epilogue(const Params& p, int layer, int mt, int ntile, int tid,
;                                                 f32x16 (&acc)[2][2], unsigned char* smem) {
;     ...
;     acc_foreach(tid, acc, [&](int row, int col, float v) {
;       int t = m0 + row;
;       float o = v;
;       if (mode == 1) o = (t >= NPADR) ? v : 0.f;
;       if (mode == 2) o = sigmf(v);
;       sT[row * 136 + col] = f2bf(o);
;     });
.LBB0_4295:
	v_bfe_u32 v96, v63, 16, 1
	v_add3_u32 v63, v63, v96, s80
	ds_write_b16_d16_hi v55, v63 offset:272
	s_nop 1

; __device__ __forceinline__ float sigmf(float x) { return 1.f / (1.f + __expf(-x)); }
; __device__ __forceinline__ bf16r f2bf(float f) {
;   unsigned u = __float_as_uint(f);
;   u += 0x7fffu + ((u >> 16) & 1u);
;   return (bf16r)(u >> 16);
; }
; __device__ __forceinline__ void inproj_epilogue(const Params& p, int layer, int mt, int ntile, int tid,
;                                                 f32x16 (&acc)[2][2], unsigned char* smem) {
;     ...
;     acc_foreach(tid, acc, [&](int row, int col, float v) {
;       int t = m0 + row;
;       float o = v;
;       if (mode == 1) o = (t >= NPADR) ? v : 0.f;
;       if (mode == 2) o = sigmf(v);
;       sT[row * 136 + col] = f2bf(o);
;     });
.LBB0_4298:
	v_bfe_u32 v63, v32, 16, 1
	v_add3_u32 v32, v32, v63, s80
	ds_write_b16_d16_hi v48, v32 offset:64
	s_nop 1

; __device__ __forceinline__ float sigmf(float x) { return 1.f / (1.f + __expf(-x)); }
; __device__ __forceinline__ bf16r f2bf(float f) {
;   unsigned u = __float_as_uint(f);
;   u += 0x7fffu + ((u >> 16) & 1u);
;   return (bf16r)(u >> 16);
; }
; __device__ __forceinline__ void inproj_epilogue(const Params& p, int layer, int mt, int ntile, int tid,
;                                                 f32x16 (&acc)[2][2], unsigned char* smem) {
;     ...
;     acc_foreach(tid, acc, [&](int row, int col, float v) {
;       int t = m0 + row;
;       float o = v;
;       if (mode == 1) o = (t >= NPADR) ? v : 0.f;
;       if (mode == 2) o = sigmf(v);
;       sT[row * 136 + col] = f2bf(o);
;     });
.LBB0_4301:
	v_bfe_u32 v33, v32, 16, 1
	v_add3_u32 v32, v32, v33, s80
	ds_write_b16_d16_hi v49, v32 offset:64
	s_nop 1

; __device__ __forceinline__ float sigmf(float x) { return 1.f / (1.f + __expf(-x)); }
; __device__ __forceinline__ bf16r f2bf(float f) {
;   unsigned u = __float_as_uint(f);
;   u += 0x7fffu + ((u >> 16) & 1u);
;   return (bf16r)(u >> 16);
; }
; __device__ __forceinline__ void inproj_epilogue(const Params& p, int layer, int mt, int ntile, int tid,
;                                                 f32x16 (&acc)[2][2], unsigned char* smem) {
;     ...
;     acc_foreach(tid, acc, [&](int row, int col, float v) {
;       int t = m0 + row;
;       float o = v;
;       if (mode == 1) o = (t >= NPADR) ? v : 0.f;
;       if (mode == 2) o = sigmf(v);
;       sT[row * 136 + col] = f2bf(o);
;     });
.LBB0_4304:
	v_bfe_u32 v33, v32, 16, 1
	v_add3_u32 v32, v32, v33, s80
	ds_write_b16_d16_hi v50, v32 offset:64
	s_nop 1

; __device__ __forceinline__ float sigmf(float x) { return 1.f / (1.f + __expf(-x)); }
; __device__ __forceinline__ bf16r f2bf(float f) {
;   unsigned u = __float_as_uint(f);
;   u += 0x7fffu + ((u >> 16) & 1u);
;   return (bf16r)(u >> 16);
; }
; __device__ __forceinline__ void inproj_epilogue(const Params& p, int layer, int mt, int ntile, int tid,
;                                                 f32x16 (&acc)[2][2], unsigned char* smem) {
;     ...
;     acc_foreach(tid, acc, [&](int row, int col, float v) {
;       int t = m0 + row;
;       float o = v;
;       if (mode == 1) o = (t >= NPADR) ? v : 0.f;
;       if (mode == 2) o = sigmf(v);
;       sT[row * 136 + col] = f2bf(o);
;     });
.LBB0_4307:
	v_bfe_u32 v33, v32, 16, 1
	v_add3_u32 v32, v32, v33, s80
	ds_write_b16_d16_hi v51, v32 offset:64
	s_nop 1

; __device__ __forceinline__ float sigmf(float x) { return 1.f / (1.f + __expf(-x)); }
; __device__ __forceinline__ bf16r f2bf(float f) {
;   unsigned u = __float_as_uint(f);
;   u += 0x7fffu + ((u >> 16) & 1u);
;   return (bf16r)(u >> 16);
; }
; __device__ __forceinline__ void inproj_epilogue(const Params& p, int layer, int mt, int ntile, int tid,
;                                                 f32x16 (&acc)[2][2], unsigned char* smem) {
;     ...
;     acc_foreach(tid, acc, [&](int row, int col, float v) {
;       int t = m0 + row;
;       float o = v;
;       if (mode == 1) o = (t >= NPADR) ? v : 0.f;
;       if (mode == 2) o = sigmf(v);
;       sT[row * 136 + col] = f2bf(o);
;     });
.LBB0_4310:
	v_bfe_u32 v33, v32, 16, 1
	v_add3_u32 v32, v32, v33, s80
	ds_write_b16_d16_hi v52, v32 offset:64
	s_nop 1

; __device__ __forceinline__ float sigmf(float x) { return 1.f / (1.f + __expf(-x)); }
; __device__ __forceinline__ bf16r f2bf(float f) {
;   unsigned u = __float_as_uint(f);
;   u += 0x7fffu + ((u >> 16) & 1u);
;   return (bf16r)(u >> 16);
; }
; __device__ __forceinline__ void inproj_epilogue(const Params& p, int layer, int mt, int ntile, int tid,
;                                                 f32x16 (&acc)[2][2], unsigned char* smem) {
;     ...
;     acc_foreach(tid, acc, [&](int row, int col, float v) {
;       int t = m0 + row;
;       float o = v;
;       if (mode == 1) o = (t >= NPADR) ? v : 0.f;
;       if (mode == 2) o = sigmf(v);
;       sT[row * 136 + col] = f2bf(o);
;     });
.LBB0_4313:
	v_bfe_u32 v33, v32, 16, 1
	v_add3_u32 v32, v32, v33, s80
	ds_write_b16_d16_hi v53, v32 offset:64
	s_nop 1

; __device__ __forceinline__ float sigmf(float x) { return 1.f / (1.f + __expf(-x)); }
; __device__ __forceinline__ bf16r f2bf(float f) {
;   unsigned u = __float_as_uint(f);
;   u += 0x7fffu + ((u >> 16) & 1u);
;   return (bf16r)(u >> 16);
; }
; __device__ __forceinline__ void inproj_epilogue(const Params& p, int layer, int mt, int ntile, int tid,
;                                                 f32x16 (&acc)[2][2], unsigned char* smem) {
;     ...
;     acc_foreach(tid, acc, [&](int row, int col, float v) {
;       int t = m0 + row;
;       float o = v;
;       if (mode == 1) o = (t >= NPADR) ? v : 0.f;
;       if (mode == 2) o = sigmf(v);
;       sT[row * 136 + col] = f2bf(o);
;     });
.LBB0_4316:
	v_bfe_u32 v33, v32, 16, 1
	v_add3_u32 v32, v32, v33, s80
	ds_write_b16_d16_hi v54, v32 offset:64
	s_nop 1

; __device__ __forceinline__ float sigmf(float x) { return 1.f / (1.f + __expf(-x)); }
; __device__ __forceinline__ bf16r f2bf(float f) {
;   unsigned u = __float_as_uint(f);
;   u += 0x7fffu + ((u >> 16) & 1u);
;   return (bf16r)(u >> 16);
; }
; __device__ __forceinline__ void inproj_epilogue(const Params& p, int layer, int mt, int ntile, int tid,
;                                                 f32x16 (&acc)[2][2], unsigned char* smem) {
;     ...
;     acc_foreach(tid, acc, [&](int row, int col, float v) {
;       int t = m0 + row;
;       float o = v;
;       if (mode == 1) o = (t >= NPADR) ? v : 0.f;
;       if (mode == 2) o = sigmf(v);
;       sT[row * 136 + col] = f2bf(o);
;     });
.LBB0_4319:
	v_bfe_u32 v33, v32, 16, 1
	v_add3_u32 v32, v32, v33, s80
	ds_write_b16_d16_hi v56, v32 offset:64
	s_nop 1

; __device__ __forceinline__ float sigmf(float x) { return 1.f / (1.f + __expf(-x)); }
; __device__ __forceinline__ bf16r f2bf(float f) {
;   unsigned u = __float_as_uint(f);
;   u += 0x7fffu + ((u >> 16) & 1u);
;   return (bf16r)(u >> 16);
; }
; __device__ __forceinline__ void inproj_epilogue(const Params& p, int layer, int mt, int ntile, int tid,
;                                                 f32x16 (&acc)[2][2], unsigned char* smem) {
;     ...
;     acc_foreach(tid, acc, [&](int row, int col, float v) {
;       int t = m0 + row;
;       float o = v;
;       if (mode == 1) o = (t >= NPADR) ? v : 0.f;
;       if (mode == 2) o = sigmf(v);
;       sT[row * 136 + col] = f2bf(o);
;     });
.LBB0_4322:
	v_bfe_u32 v33, v32, 16, 1
	v_add3_u32 v32, v32, v33, s80
	ds_write_b16_d16_hi v57, v32 offset:64
	s_nop 1

; __device__ __forceinline__ float sigmf(float x) { return 1.f / (1.f + __expf(-x)); }
; __device__ __forceinline__ bf16r f2bf(float f) {
;   unsigned u = __float_as_uint(f);
;   u += 0x7fffu + ((u >> 16) & 1u);
;   return (bf16r)(u >> 16);
; }
; __device__ __forceinline__ void inproj_epilogue(const Params& p, int layer, int mt, int ntile, int tid,
;                                                 f32x16 (&acc)[2][2], unsigned char* smem) {
;     ...
;     acc_foreach(tid, acc, [&](int row, int col, float v) {
;       int t = m0 + row;
;       float o = v;
;       if (mode == 1) o = (t >= NPADR) ? v : 0.f;
;       if (mode == 2) o = sigmf(v);
;       sT[row * 136 + col] = f2bf(o);
;     });
.LBB0_4325:
	v_bfe_u32 v33, v32, 16, 1
	v_add3_u32 v32, v32, v33, s80
	ds_write_b16_d16_hi v58, v32 offset:64
	s_nop 1

; __device__ __forceinline__ float sigmf(float x) { return 1.f / (1.f + __expf(-x)); }
; __device__ __forceinline__ bf16r f2bf(float f) {
;   unsigned u = __float_as_uint(f);
;   u += 0x7fffu + ((u >> 16) & 1u);
;   return (bf16r)(u >> 16);
; }
; __device__ __forceinline__ void inproj_epilogue(const Params& p, int layer, int mt, int ntile, int tid,
;                                                 f32x16 (&acc)[2][2], unsigned char* smem) {
;     ...
;     acc_foreach(tid, acc, [&](int row, int col, float v) {
;       int t = m0 + row;
;       float o = v;
;       if (mode == 1) o = (t >= NPADR) ? v : 0.f;
;       if (mode == 2) o = sigmf(v);
;       sT[row * 136 + col] = f2bf(o);
;     });
.LBB0_4328:
	v_bfe_u32 v33, v32, 16, 1
	v_add3_u32 v32, v32, v33, s80
	ds_write_b16_d16_hi v59, v32 offset:64
	s_nop 1

; __device__ __forceinline__ float sigmf(float x) { return 1.f / (1.f + __expf(-x)); }
; __device__ __forceinline__ bf16r f2bf(float f) {
;   unsigned u = __float_as_uint(f);
;   u += 0x7fffu + ((u >> 16) & 1u);
;   return (bf16r)(u >> 16);
; }
; __device__ __forceinline__ void inproj_epilogue(const Params& p, int layer, int mt, int ntile, int tid,
;                                                 f32x16 (&acc)[2][2], unsigned char* smem) {
;     ...
;     acc_foreach(tid, acc, [&](int row, int col, float v) {
;       int t = m0 + row;
;       float o = v;
;       if (mode == 1) o = (t >= NPADR) ? v : 0.f;
;       if (mode == 2) o = sigmf(v);
;       sT[row * 136 + col] = f2bf(o);
;     });
.LBB0_4331:
	v_bfe_u32 v33, v32, 16, 1
	v_add3_u32 v32, v32, v33, s80
	ds_write_b16_d16_hi v60, v32 offset:64
	s_nop 1

; __device__ __forceinline__ float sigmf(float x) { return 1.f / (1.f + __expf(-x)); }
; __device__ __forceinline__ bf16r f2bf(float f) {
;   unsigned u = __float_as_uint(f);
;   u += 0x7fffu + ((u >> 16) & 1u);
;   return (bf16r)(u >> 16);
; }
; __device__ __forceinline__ void inproj_epilogue(const Params& p, int layer, int mt, int ntile, int tid,
;                                                 f32x16 (&acc)[2][2], unsigned char* smem) {
;     ...
;     acc_foreach(tid, acc, [&](int row, int col, float v) {
;       int t = m0 + row;
;       float o = v;
;       if (mode == 1) o = (t >= NPADR) ? v : 0.f;
;       if (mode == 2) o = sigmf(v);
;       sT[row * 136 + col] = f2bf(o);
;     });
.LBB0_4334:
	v_bfe_u32 v33, v32, 16, 1
	v_add3_u32 v32, v32, v33, s80
	ds_write_b16_d16_hi v61, v32 offset:64
	s_nop 1

; __device__ __forceinline__ float sigmf(float x) { return 1.f / (1.f + __expf(-x)); }
; __device__ __forceinline__ bf16r f2bf(float f) {
;   unsigned u = __float_as_uint(f);
;   u += 0x7fffu + ((u >> 16) & 1u);
;   return (bf16r)(u >> 16);
; }
; __device__ __forceinline__ void inproj_epilogue(const Params& p, int layer, int mt, int ntile, int tid,
;                                                 f32x16 (&acc)[2][2], unsigned char* smem) {
;     ...
;     acc_foreach(tid, acc, [&](int row, int col, float v) {
;       int t = m0 + row;
;       float o = v;
;       if (mode == 1) o = (t >= NPADR) ? v : 0.f;
;       if (mode == 2) o = sigmf(v);
;       sT[row * 136 + col] = f2bf(o);
;     });
.LBB0_4337:
	v_bfe_u32 v33, v32, 16, 1
	v_add3_u32 v32, v32, v33, s80
	ds_write_b16_d16_hi v62, v32 offset:64
	s_nop 1

; __device__ __forceinline__ float sigmf(float x) { return 1.f / (1.f + __expf(-x)); }
; __device__ __forceinline__ bf16r f2bf(float f) {
;   unsigned u = __float_as_uint(f);
;   u += 0x7fffu + ((u >> 16) & 1u);
;   return (bf16r)(u >> 16);
; }
; __device__ __forceinline__ void inproj_epilogue(const Params& p, int layer, int mt, int ntile, int tid,
;                                                 f32x16 (&acc)[2][2], unsigned char* smem) {
;     ...
;     acc_foreach(tid, acc, [&](int row, int col, float v) {
;       int t = m0 + row;
;       float o = v;
;       if (mode == 1) o = (t >= NPADR) ? v : 0.f;
;       if (mode == 2) o = sigmf(v);
;       sT[row * 136 + col] = f2bf(o);
;     });
.LBB0_4340:
	v_bfe_u32 v33, v32, 16, 1
	v_add3_u32 v32, v32, v33, s80
	ds_write_b16_d16_hi v55, v32 offset:64
	s_nop 1

; __device__ __forceinline__ bf16r f2bf(float f) {
;   unsigned u = __float_as_uint(f);
;   u += 0x7fffu + ((u >> 16) & 1u);
;   return (bf16r)(u >> 16);
; }
; __device__ __forceinline__ unsigned pack2(float a, float b) { return (unsigned)f2bf(a) | ((unsigned)f2bf(b) << 16); }
; __device__ __forceinline__ float lo16(unsigned v) { return __uint_as_float(v << 16); }
; __device__ __forceinline__ float hi16(unsigned v) { return __uint_as_float(v & 0xffff0000u); }
; __device__ __forceinline__ float siluf(float x) { return x / (1.f + __expf(-x)); }
; __device__ __forceinline__ float sigmf(float x) { return 1.f / (1.f + __expf(-x)); }
; __device__ __forceinline__ void inproj_epilogue(const Params& p, int layer, int mt, int ntile, int tid,
;                                                 f32x16 (&acc)[2][2], unsigned char* smem) {
;     ...
;       float o = v;
;       if (mode == 1) o = (t >= NPADR) ? v : 0.f;
;       if (mode == 2) o = sigmf(v);
;       sT[row * 136 + col] = f2bf(o);
.Lgv_8:
	v_mul_f32_e32 v107, 0xbfb8aa3b, v16
	v_exp_f32_e32 v107, v107
	s_nop 0
	v_add_f32_e32 v107, 1.0, v107
	v_div_scale_f32 v110, s[6:7], v107, v107, 1.0
	v_rcp_f32_e32 v111, v110
	v_div_scale_f32 v112, vcc, 1.0, v107, 1.0
	v_fma_f32 v113, -v110, v111, 1.0
	v_fmac_f32_e32 v111, v113, v111
	v_mul_f32_e32 v113, v112, v111
	v_fma_f32 v114, -v110, v113, v112
	v_fmac_f32_e32 v113, v114, v111
	v_fma_f32 v110, -v110, v113, v112
	v_div_fmas_f32 v110, v110, v111, v113
	v_div_fixup_f32 v107, v110, v107, 1.0
	v_bfe_u32 v110, v107, 16, 1
	v_and_b32_e32 v106, 0x5f, v106
	v_add3_u32 v111, v107, v110, s80
	v_mul_lo_u32 v110, v96, s81
	v_lshl_add_u32 v107, v106, 1, v110
	ds_write_b16_d16_hi v107, v111
	v_add3_u32 v111, s74, v96, 1
	v_cndmask_b32_e64 v112, 0, 1, s[10:11]
	v_cmp_ne_u32_e64 s[6:7], 1, v112
	s_andn2_b64 vcc, exec, s[10:11]
	v_cmp_lt_i32_e64 s[10:11], s78, v111
	v_mul_f32_e32 v111, 0xbfb8aa3b, v17
	v_exp_f32_e32 v111, v111
	s_nop 0
	v_add_f32_e32 v111, 1.0, v111
	v_div_scale_f32 v112, s[12:13], v111, v111, 1.0
	v_rcp_f32_e32 v113, v112
	v_div_scale_f32 v114, vcc, 1.0, v111, 1.0
	v_fma_f32 v115, -v112, v113, 1.0
	v_fmac_f32_e32 v113, v115, v113
	v_mul_f32_e32 v115, v114, v113
	v_fma_f32 v116, -v112, v115, v114
	v_fmac_f32_e32 v115, v116, v113
	v_fma_f32 v112, -v112, v115, v114
	v_div_fmas_f32 v112, v112, v113, v115
	v_div_fixup_f32 v111, v112, v111, 1.0
	v_bfe_u32 v112, v111, 16, 1
	v_add3_u32 v112, v111, v112, s80
	v_add_u32_e32 v111, 0x110, v110
	v_lshl_add_u32 v110, v106, 1, v111
	ds_write_b16_d16_hi v110, v112
	v_add3_u32 v112, s74, v96, 2
	s_and_b64 vcc, exec, s[6:7]
	v_cmp_lt_i32_e64 s[12:13], s78, v112
	v_mul_f32_e32 v112, 0xbfb8aa3b, v18
	v_exp_f32_e32 v112, v112
	s_nop 0
	v_add_f32_e32 v112, 1.0, v112
	v_div_scale_f32 v113, s[14:15], v112, v112, 1.0
	v_rcp_f32_e32 v114, v113
	v_div_scale_f32 v115, vcc, 1.0, v112, 1.0
	v_fma_f32 v116, -v113, v114, 1.0
	v_fmac_f32_e32 v114, v116, v114
	v_mul_f32_e32 v116, v115, v114
	v_fma_f32 v117, -v113, v116, v115
	v_fmac_f32_e32 v116, v117, v114
	v_fma_f32 v113, -v113, v116, v115
	v_div_fmas_f32 v113, v113, v114, v116
	v_div_fixup_f32 v112, v113, v112, 1.0
	v_bfe_u32 v113, v112, 16, 1
	v_add3_u32 v113, v112, v113, s80
	v_add_u32_e32 v112, 0x110, v111
	v_lshl_add_u32 v111, v106, 1, v112
	ds_write_b16_d16_hi v111, v113
	v_add3_u32 v113, s74, v96, 3
	s_and_b64 vcc, exec, s[6:7]
	v_cmp_lt_i32_e64 s[14:15], s78, v113
	v_mul_f32_e32 v113, 0xbfb8aa3b, v19
	v_exp_f32_e32 v113, v113
	s_nop 0
	v_add_f32_e32 v113, 1.0, v113
	v_div_scale_f32 v114, s[16:17], v113, v113, 1.0
	v_rcp_f32_e32 v115, v114
	v_div_scale_f32 v116, vcc, 1.0, v113, 1.0
	v_fma_f32 v117, -v114, v115, 1.0
	v_fmac_f32_e32 v115, v117, v115
	v_mul_f32_e32 v117, v116, v115
	v_fma_f32 v118, -v114, v117, v116
	v_fmac_f32_e32 v117, v118, v115
	v_fma_f32 v114, -v114, v117, v116
	v_div_fmas_f32 v114, v114, v115, v117
	v_div_fixup_f32 v113, v114, v113, 1.0
	v_bfe_u32 v114, v113, 16, 1
	v_add3_u32 v114, v113, v114, s80
	v_add_u32_e32 v113, 0x110, v112
	v_lshl_add_u32 v112, v106, 1, v113
	ds_write_b16_d16_hi v112, v114
	v_add3_u32 v114, s74, v96, 8
	s_and_b64 vcc, exec, s[6:7]
	v_cmp_lt_i32_e64 s[16:17], s78, v114
	v_mul_f32_e32 v114, 0xbfb8aa3b, v20
	v_exp_f32_e32 v114, v114
	s_nop 0
	v_add_f32_e32 v114, 1.0, v114
	v_div_scale_f32 v115, s[18:19], v114, v114, 1.0
	v_rcp_f32_e32 v116, v115
	v_div_scale_f32 v117, vcc, 1.0, v114, 1.0
	v_fma_f32 v118, -v115, v116, 1.0
	v_fmac_f32_e32 v116, v118, v116
	v_mul_f32_e32 v118, v117, v116
	v_fma_f32 v119, -v115, v118, v117
	v_fmac_f32_e32 v118, v119, v116
	v_fma_f32 v115, -v115, v118, v117
	v_div_fmas_f32 v115, v115, v116, v118
	v_div_fixup_f32 v114, v115, v114, 1.0
	v_bfe_u32 v115, v114, 16, 1
	v_add3_u32 v115, v114, v115, s80
	v_add_u32_e32 v114, 0x550, v113
	v_lshl_add_u32 v113, v106, 1, v114
	ds_write_b16_d16_hi v113, v115
	v_add3_u32 v115, s74, v96, 9
	s_and_b64 vcc, exec, s[6:7]
	v_cmp_lt_i32_e64 s[18:19], s78, v115
	v_mul_f32_e32 v115, 0xbfb8aa3b, v21
	v_exp_f32_e32 v115, v115
	s_nop 0
	v_add_f32_e32 v115, 1.0, v115
	v_div_scale_f32 v116, s[20:21], v115, v115, 1.0
	v_rcp_f32_e32 v117, v116
	v_div_scale_f32 v118, vcc, 1.0, v115, 1.0
	v_fma_f32 v119, -v116, v117, 1.0
	v_fmac_f32_e32 v117, v119, v117
	v_mul_f32_e32 v119, v118, v117
	v_fma_f32 v120, -v116, v119, v118
	v_fmac_f32_e32 v119, v120, v117
	v_fma_f32 v116, -v116, v119, v118
	v_div_fmas_f32 v116, v116, v117, v119
	v_div_fixup_f32 v115, v116, v115, 1.0
	v_bfe_u32 v116, v115, 16, 1
	v_add3_u32 v116, v115, v116, s80
	v_add_u32_e32 v115, 0x110, v114
	v_lshl_add_u32 v114, v106, 1, v115
	ds_write_b16_d16_hi v114, v116
	v_add3_u32 v116, s74, v96, 10
	s_and_b64 vcc, exec, s[6:7]
	v_cmp_lt_i32_e64 s[20:21], s78, v116
	v_mul_f32_e32 v116, 0xbfb8aa3b, v22
	v_exp_f32_e32 v116, v116
	s_nop 0
	v_add_f32_e32 v116, 1.0, v116
	v_div_scale_f32 v117, s[22:23], v116, v116, 1.0
	v_rcp_f32_e32 v118, v117
	v_div_scale_f32 v119, vcc, 1.0, v116, 1.0
	v_fma_f32 v120, -v117, v118, 1.0
	v_fmac_f32_e32 v118, v120, v118
	v_mul_f32_e32 v120, v119, v118
	v_fma_f32 v121, -v117, v120, v119
	v_fmac_f32_e32 v120, v121, v118
	v_fma_f32 v117, -v117, v120, v119
	v_div_fmas_f32 v117, v117, v118, v120
	v_div_fixup_f32 v116, v117, v116, 1.0
	v_bfe_u32 v117, v116, 16, 1
	v_add3_u32 v117, v116, v117, s80
	v_add_u32_e32 v116, 0x110, v115
	v_lshl_add_u32 v115, v106, 1, v116
	ds_write_b16_d16_hi v115, v117
	v_add3_u32 v117, s74, v96, 11
	s_and_b64 vcc, exec, s[6:7]
	v_cmp_lt_i32_e64 s[22:23], s78, v117
	v_mul_f32_e32 v117, 0xbfb8aa3b, v23
	v_exp_f32_e32 v117, v117
	s_nop 0
	v_add_f32_e32 v117, 1.0, v117
	v_div_scale_f32 v118, s[24:25], v117, v117, 1.0
	v_rcp_f32_e32 v119, v118
; __device__ __forceinline__ bf16r f2bf(float f) {
;   unsigned u = __float_as_uint(f);
;   u += 0x7fffu + ((u >> 16) & 1u);
;   return (bf16r)(u >> 16);
; }
; __device__ __forceinline__ unsigned pack2(float a, float b) { return (unsigned)f2bf(a) | ((unsigned)f2bf(b) << 16); }
; __device__ __forceinline__ float lo16(unsigned v) { return __uint_as_float(v << 16); }
; __device__ __forceinline__ float hi16(unsigned v) { return __uint_as_float(v & 0xffff0000u); }
; __device__ __forceinline__ float siluf(float x) { return x / (1.f + __expf(-x)); }
; __device__ __forceinline__ float sigmf(float x) { return 1.f / (1.f + __expf(-x)); }
; __device__ __forceinline__ void inproj_epilogue(const Params& p, int layer, int mt, int ntile, int tid,
;                                                 f32x16 (&acc)[2][2], unsigned char* smem) {
;     ...
;       float o = v;
;       if (mode == 1) o = (t >= NPADR) ? v : 0.f;
;       if (mode == 2) o = sigmf(v);
;       sT[row * 136 + col] = f2bf(o);
	v_div_scale_f32 v120, vcc, 1.0, v117, 1.0
	v_fma_f32 v121, -v118, v119, 1.0
	v_fmac_f32_e32 v119, v121, v119
	v_mul_f32_e32 v121, v120, v119
	v_fma_f32 v122, -v118, v121, v120
	v_fmac_f32_e32 v121, v122, v119
	v_fma_f32 v118, -v118, v121, v120
	v_div_fmas_f32 v118, v118, v119, v121
	v_div_fixup_f32 v117, v118, v117, 1.0
	v_bfe_u32 v118, v117, 16, 1
	v_add_u32_e32 v116, 0x110, v116
	v_add3_u32 v118, v117, v118, s80
	v_lshl_add_u32 v117, v106, 1, v116
	ds_write_b16_d16_hi v117, v118
	v_add3_u32 v118, s74, v96, 16
	s_and_b64 vcc, exec, s[6:7]
	v_cmp_lt_i32_e64 s[24:25], s78, v118
	v_mul_f32_e32 v118, 0xbfb8aa3b, v24
	v_exp_f32_e32 v118, v118
	s_nop 0
	v_add_f32_e32 v118, 1.0, v118
	v_div_scale_f32 v119, s[26:27], v118, v118, 1.0
	v_rcp_f32_e32 v120, v119
	v_div_scale_f32 v121, vcc, 1.0, v118, 1.0
	v_fma_f32 v122, -v119, v120, 1.0
	v_fmac_f32_e32 v120, v122, v120
	v_mul_f32_e32 v122, v121, v120
	v_fma_f32 v123, -v119, v122, v121
	v_fmac_f32_e32 v122, v123, v120
	v_fma_f32 v119, -v119, v122, v121
	v_div_fmas_f32 v119, v119, v120, v122
	v_div_fixup_f32 v118, v119, v118, 1.0
	v_bfe_u32 v119, v118, 16, 1
	v_add_u32_e32 v116, 0x550, v116
	v_add3_u32 v119, v118, v119, s80
	v_lshl_add_u32 v118, v106, 1, v116
	ds_write_b16_d16_hi v118, v119
	v_add3_u32 v119, s74, v96, 17
	s_and_b64 vcc, exec, s[6:7]
	v_cmp_lt_i32_e64 s[26:27], s78, v119
	v_mul_f32_e32 v119, 0xbfb8aa3b, v25
	v_exp_f32_e32 v119, v119
	s_nop 0
	v_add_f32_e32 v119, 1.0, v119
	v_div_scale_f32 v120, s[28:29], v119, v119, 1.0
	v_rcp_f32_e32 v121, v120
	v_div_scale_f32 v122, vcc, 1.0, v119, 1.0
	v_fma_f32 v123, -v120, v121, 1.0
	v_fmac_f32_e32 v121, v123, v121
	v_mul_f32_e32 v123, v122, v121
	v_fma_f32 v124, -v120, v123, v122
	v_fmac_f32_e32 v123, v124, v121
	v_fma_f32 v120, -v120, v123, v122
	v_div_fmas_f32 v120, v120, v121, v123
	v_div_fixup_f32 v119, v120, v119, 1.0
	v_bfe_u32 v120, v119, 16, 1
	v_add_u32_e32 v116, 0x110, v116
	v_add3_u32 v120, v119, v120, s80
	v_lshl_add_u32 v119, v106, 1, v116
	ds_write_b16_d16_hi v119, v120
	v_add3_u32 v120, s74, v96, 18
	s_and_b64 vcc, exec, s[6:7]
	v_cmp_lt_i32_e64 s[28:29], s78, v120
	v_mul_f32_e32 v120, 0xbfb8aa3b, v26
	v_exp_f32_e32 v120, v120
	s_nop 0
	v_add_f32_e32 v120, 1.0, v120
	v_div_scale_f32 v121, s[30:31], v120, v120, 1.0
	v_rcp_f32_e32 v122, v121
	v_div_scale_f32 v123, vcc, 1.0, v120, 1.0
	v_fma_f32 v124, -v121, v122, 1.0
	v_fmac_f32_e32 v122, v124, v122
	v_mul_f32_e32 v124, v123, v122
	v_fma_f32 v125, -v121, v124, v123
	v_fmac_f32_e32 v124, v125, v122
	v_fma_f32 v121, -v121, v124, v123
	v_div_fmas_f32 v121, v121, v122, v124
	v_div_fixup_f32 v120, v121, v120, 1.0
	v_bfe_u32 v121, v120, 16, 1
	v_add_u32_e32 v116, 0x110, v116
	v_add3_u32 v121, v120, v121, s80
	v_lshl_add_u32 v120, v106, 1, v116
	ds_write_b16_d16_hi v120, v121
	v_add3_u32 v121, s74, v96, 19
	s_and_b64 vcc, exec, s[6:7]
	v_cmp_lt_i32_e64 s[30:31], s78, v121
	v_mul_f32_e32 v121, 0xbfb8aa3b, v27
	v_exp_f32_e32 v121, v121
	s_nop 0
	v_add_f32_e32 v121, 1.0, v121
	v_div_scale_f32 v122, s[34:35], v121, v121, 1.0
	v_rcp_f32_e32 v123, v122
	v_div_scale_f32 v124, vcc, 1.0, v121, 1.0
	v_fma_f32 v125, -v122, v123, 1.0
	v_fmac_f32_e32 v123, v125, v123
	v_mul_f32_e32 v125, v124, v123
	v_fma_f32 v126, -v122, v125, v124
	v_fmac_f32_e32 v125, v126, v123
	v_fma_f32 v122, -v122, v125, v124
	v_div_fmas_f32 v122, v122, v123, v125
	v_div_fixup_f32 v121, v122, v121, 1.0
	v_bfe_u32 v122, v121, 16, 1
	v_add_u32_e32 v116, 0x110, v116
	v_add3_u32 v122, v121, v122, s80
	v_lshl_add_u32 v121, v106, 1, v116
	ds_write_b16_d16_hi v121, v122
	v_add3_u32 v122, s74, v96, 24
	s_and_b64 vcc, exec, s[6:7]
	v_cmp_lt_i32_e64 s[34:35], s78, v122
	v_mul_f32_e32 v122, 0xbfb8aa3b, v28
	v_exp_f32_e32 v122, v122
	s_nop 0
	v_add_f32_e32 v122, 1.0, v122
	v_div_scale_f32 v123, s[36:37], v122, v122, 1.0
	v_rcp_f32_e32 v124, v123
	v_div_scale_f32 v125, vcc, 1.0, v122, 1.0
	v_fma_f32 v126, -v123, v124, 1.0
	v_fmac_f32_e32 v124, v126, v124
	v_mul_f32_e32 v126, v125, v124
	v_fma_f32 v127, -v123, v126, v125
	v_fmac_f32_e32 v126, v127, v124
	v_fma_f32 v123, -v123, v126, v125
	v_div_fmas_f32 v123, v123, v124, v126
	v_div_fixup_f32 v122, v123, v122, 1.0
	v_bfe_u32 v123, v122, 16, 1
	v_add_u32_e32 v116, 0x550, v116
	v_add3_u32 v123, v122, v123, s80
	v_lshl_add_u32 v122, v106, 1, v116
	ds_write_b16_d16_hi v122, v123
	v_add3_u32 v123, s74, v96, 25
	s_and_b64 vcc, exec, s[6:7]
	v_cmp_lt_i32_e64 s[36:37], s78, v123
	v_mul_f32_e32 v123, 0xbfb8aa3b, v29
	v_exp_f32_e32 v123, v123
	s_nop 0
	v_add_f32_e32 v123, 1.0, v123
	v_div_scale_f32 v124, s[38:39], v123, v123, 1.0
	v_rcp_f32_e32 v125, v124
	v_div_scale_f32 v126, vcc, 1.0, v123, 1.0
	v_fma_f32 v127, -v124, v125, 1.0
	v_fmac_f32_e32 v125, v127, v125
	v_mul_f32_e32 v127, v126, v125
	v_fma_f32 v128, -v124, v127, v126
	v_fmac_f32_e32 v127, v128, v125
	v_fma_f32 v124, -v124, v127, v126
	v_div_fmas_f32 v124, v124, v125, v127
	v_div_fixup_f32 v123, v124, v123, 1.0
	v_bfe_u32 v124, v123, 16, 1
	v_add_u32_e32 v116, 0x110, v116
	v_add3_u32 v124, v123, v124, s80
	v_lshl_add_u32 v123, v106, 1, v116
	ds_write_b16_d16_hi v123, v124
	v_add3_u32 v124, s74, v96, 26
	s_and_b64 vcc, exec, s[6:7]
	v_cmp_lt_i32_e64 s[38:39], s78, v124
	v_mul_f32_e32 v124, 0xbfb8aa3b, v30
	v_exp_f32_e32 v124, v124
	s_nop 0
	v_add_f32_e32 v124, 1.0, v124
	v_div_scale_f32 v125, s[40:41], v124, v124, 1.0
	v_rcp_f32_e32 v126, v125
	v_div_scale_f32 v127, vcc, 1.0, v124, 1.0
	v_fma_f32 v128, -v125, v126, 1.0
	v_fmac_f32_e32 v126, v128, v126
	v_mul_f32_e32 v128, v127, v126
	v_fma_f32 v129, -v125, v128, v127
	v_fmac_f32_e32 v128, v129, v126
	v_fma_f32 v125, -v125, v128, v127
	v_div_fmas_f32 v125, v125, v126, v128
; __device__ __forceinline__ bf16r f2bf(float f) {
;   unsigned u = __float_as_uint(f);
;   u += 0x7fffu + ((u >> 16) & 1u);
;   return (bf16r)(u >> 16);
; }
; __device__ __forceinline__ unsigned pack2(float a, float b) { return (unsigned)f2bf(a) | ((unsigned)f2bf(b) << 16); }
; __device__ __forceinline__ float lo16(unsigned v) { return __uint_as_float(v << 16); }
; __device__ __forceinline__ float hi16(unsigned v) { return __uint_as_float(v & 0xffff0000u); }
; __device__ __forceinline__ float siluf(float x) { return x / (1.f + __expf(-x)); }
; __device__ __forceinline__ float sigmf(float x) { return 1.f / (1.f + __expf(-x)); }
; __device__ __forceinline__ void inproj_epilogue(const Params& p, int layer, int mt, int ntile, int tid,
;                                                 f32x16 (&acc)[2][2], unsigned char* smem) {
;     ...
;       float o = v;
;       if (mode == 1) o = (t >= NPADR) ? v : 0.f;
;       if (mode == 2) o = sigmf(v);
;       sT[row * 136 + col] = f2bf(o);
	v_div_fixup_f32 v124, v125, v124, 1.0
	v_bfe_u32 v125, v124, 16, 1
	v_add_u32_e32 v116, 0x110, v116
	v_add3_u32 v124, v124, v125, s80
	v_lshl_add_u32 v116, v106, 1, v116
	ds_write_b16_d16_hi v116, v124
	v_add3_u32 v124, s74, v96, 27
	s_and_b64 vcc, exec, s[6:7]
	v_cmp_lt_i32_e64 s[40:41], s78, v124
	v_mul_f32_e32 v124, 0xbfb8aa3b, v31
	v_exp_f32_e32 v124, v124
	s_nop 0
	v_add_f32_e32 v124, 1.0, v124
	v_div_scale_f32 v125, s[92:93], v124, v124, 1.0
	v_rcp_f32_e32 v126, v125
	v_div_scale_f32 v127, vcc, 1.0, v124, 1.0
	v_fma_f32 v128, -v125, v126, 1.0
	v_fmac_f32_e32 v126, v128, v126
	v_mul_f32_e32 v128, v127, v126
	v_fma_f32 v129, -v125, v128, v127
	v_fmac_f32_e32 v128, v129, v126
	v_fma_f32 v125, -v125, v128, v127
	v_div_fmas_f32 v125, v125, v126, v128
	v_div_fixup_f32 v124, v125, v124, 1.0
	v_bfe_u32 v125, v124, 16, 1
	v_add3_u32 v124, v124, v125, s80
	ds_write_b16_d16_hi v116, v124 offset:272
	s_and_b64 vcc, exec, s[6:7]
	v_mul_f32_e32 v48, 0xbfb8aa3b, v48
	v_exp_f32_e32 v48, v48
	s_nop 0
	v_add_f32_e32 v48, 1.0, v48
	v_div_scale_f32 v124, s[8:9], v48, v48, 1.0
	v_rcp_f32_e32 v125, v124
	v_div_scale_f32 v126, vcc, 1.0, v48, 1.0
	v_fma_f32 v127, -v124, v125, 1.0
	v_fmac_f32_e32 v125, v127, v125
	v_mul_f32_e32 v127, v126, v125
	v_fma_f32 v128, -v124, v127, v126
	v_fmac_f32_e32 v127, v128, v125
	v_fma_f32 v124, -v124, v127, v126
	v_div_fmas_f32 v124, v124, v125, v127
	v_div_fixup_f32 v48, v124, v48, 1.0
	v_bfe_u32 v124, v48, 16, 1
	v_add3_u32 v48, v48, v124, s80
	s_and_b64 vcc, exec, s[6:7]
	ds_write_b16_d16_hi v107, v48 offset:64
	v_mul_f32_e32 v48, 0xbfb8aa3b, v49
	v_exp_f32_e32 v48, v48
	s_nop 0
	v_add_f32_e32 v48, 1.0, v48
	v_div_scale_f32 v49, s[8:9], v48, v48, 1.0
	v_rcp_f32_e32 v107, v49
	v_div_scale_f32 v124, vcc, 1.0, v48, 1.0
	v_fma_f32 v125, -v49, v107, 1.0
	v_fmac_f32_e32 v107, v125, v107
	v_mul_f32_e32 v125, v124, v107
	v_fma_f32 v126, -v49, v125, v124
	v_fmac_f32_e32 v125, v126, v107
	v_fma_f32 v49, -v49, v125, v124
	v_div_fmas_f32 v49, v49, v107, v125
	v_div_fixup_f32 v48, v49, v48, 1.0
	v_bfe_u32 v49, v48, 16, 1
	v_add3_u32 v48, v48, v49, s80
	s_and_b64 vcc, exec, s[6:7]
	ds_write_b16_d16_hi v110, v48 offset:64
	v_mul_f32_e32 v48, 0xbfb8aa3b, v50
	v_exp_f32_e32 v48, v48
	s_nop 0
	v_add_f32_e32 v48, 1.0, v48
	v_div_scale_f32 v49, s[8:9], v48, v48, 1.0
	v_rcp_f32_e32 v50, v49
	v_div_scale_f32 v107, vcc, 1.0, v48, 1.0
	v_fma_f32 v110, -v49, v50, 1.0
	v_fmac_f32_e32 v50, v110, v50
	v_mul_f32_e32 v110, v107, v50
	v_fma_f32 v124, -v49, v110, v107
	v_fmac_f32_e32 v110, v124, v50
	v_fma_f32 v49, -v49, v110, v107
	v_div_fmas_f32 v49, v49, v50, v110
	v_div_fixup_f32 v48, v49, v48, 1.0
	v_bfe_u32 v49, v48, 16, 1
	v_add3_u32 v48, v48, v49, s80
	s_and_b64 vcc, exec, s[6:7]
	ds_write_b16_d16_hi v111, v48 offset:64
	v_mul_f32_e32 v48, 0xbfb8aa3b, v51
	v_exp_f32_e32 v48, v48
	s_nop 0
	v_add_f32_e32 v48, 1.0, v48
	v_div_scale_f32 v49, s[8:9], v48, v48, 1.0
	v_rcp_f32_e32 v50, v49
	v_div_scale_f32 v51, vcc, 1.0, v48, 1.0
	v_fma_f32 v107, -v49, v50, 1.0
	v_fmac_f32_e32 v50, v107, v50
	v_mul_f32_e32 v107, v51, v50
	v_fma_f32 v110, -v49, v107, v51
	v_fmac_f32_e32 v107, v110, v50
	v_fma_f32 v49, -v49, v107, v51
	v_div_fmas_f32 v49, v49, v50, v107
	v_div_fixup_f32 v48, v49, v48, 1.0
	v_bfe_u32 v49, v48, 16, 1
	v_add3_u32 v48, v48, v49, s80
	s_and_b64 vcc, exec, s[6:7]
	ds_write_b16_d16_hi v112, v48 offset:64
	v_mul_f32_e32 v48, 0xbfb8aa3b, v52
	v_exp_f32_e32 v48, v48
	s_nop 0
	v_add_f32_e32 v48, 1.0, v48
	v_div_scale_f32 v49, s[8:9], v48, v48, 1.0
	v_rcp_f32_e32 v50, v49
	v_div_scale_f32 v51, vcc, 1.0, v48, 1.0
	v_fma_f32 v52, -v49, v50, 1.0
	v_fmac_f32_e32 v50, v52, v50
	v_mul_f32_e32 v52, v51, v50
	v_fma_f32 v107, -v49, v52, v51
	v_fmac_f32_e32 v52, v107, v50
	v_fma_f32 v49, -v49, v52, v51
	v_div_fmas_f32 v49, v49, v50, v52
	v_div_fixup_f32 v48, v49, v48, 1.0
	v_bfe_u32 v49, v48, 16, 1
	v_add3_u32 v48, v48, v49, s80
	s_and_b64 vcc, exec, s[6:7]
	ds_write_b16_d16_hi v113, v48 offset:64
	v_mul_f32_e32 v48, 0xbfb8aa3b, v53
	v_exp_f32_e32 v48, v48
	s_nop 0
	v_add_f32_e32 v48, 1.0, v48
	v_div_scale_f32 v49, s[8:9], v48, v48, 1.0
	v_rcp_f32_e32 v50, v49
	v_div_scale_f32 v51, vcc, 1.0, v48, 1.0
	v_fma_f32 v52, -v49, v50, 1.0
	v_fmac_f32_e32 v50, v52, v50
	v_mul_f32_e32 v52, v51, v50
	v_fma_f32 v53, -v49, v52, v51
	v_fmac_f32_e32 v52, v53, v50
	v_fma_f32 v49, -v49, v52, v51
	v_div_fmas_f32 v49, v49, v50, v52
	v_div_fixup_f32 v48, v49, v48, 1.0
	v_bfe_u32 v49, v48, 16, 1
	v_add3_u32 v48, v48, v49, s80
	s_and_b64 vcc, exec, s[6:7]
	ds_write_b16_d16_hi v114, v48 offset:64
	v_mul_f32_e32 v48, 0xbfb8aa3b, v54
	v_exp_f32_e32 v48, v48
	s_nop 0
	v_add_f32_e32 v48, 1.0, v48
	v_div_scale_f32 v49, s[8:9], v48, v48, 1.0
	v_rcp_f32_e32 v50, v49
	v_div_scale_f32 v51, vcc, 1.0, v48, 1.0
	v_fma_f32 v52, -v49, v50, 1.0
	v_fmac_f32_e32 v50, v52, v50
	v_mul_f32_e32 v52, v51, v50
	v_fma_f32 v53, -v49, v52, v51
	v_fmac_f32_e32 v52, v53, v50
	v_fma_f32 v49, -v49, v52, v51
	v_div_fmas_f32 v49, v49, v50, v52
	v_div_fixup_f32 v48, v49, v48, 1.0
	v_bfe_u32 v49, v48, 16, 1
	v_add3_u32 v48, v48, v49, s80
	s_and_b64 vcc, exec, s[6:7]
	ds_write_b16_d16_hi v115, v48 offset:64
	v_mul_f32_e32 v48, 0xbfb8aa3b, v55
	v_exp_f32_e32 v48, v48
	s_nop 0
	v_add_f32_e32 v48, 1.0, v48
	v_div_scale_f32 v49, s[8:9], v48, v48, 1.0
	v_rcp_f32_e32 v50, v49
	v_div_scale_f32 v51, vcc, 1.0, v48, 1.0
	v_fma_f32 v52, -v49, v50, 1.0
	v_fmac_f32_e32 v50, v52, v50
	v_mul_f32_e32 v52, v51, v50
	v_fma_f32 v53, -v49, v52, v51
	v_fmac_f32_e32 v52, v53, v50
	v_fma_f32 v49, -v49, v52, v51
	v_div_fmas_f32 v49, v49, v50, v52
	v_div_fixup_f32 v48, v49, v48, 1.0
	v_bfe_u32 v49, v48, 16, 1
	v_add3_u32 v48, v48, v49, s80
; __device__ __forceinline__ bf16r f2bf(float f) {
;   unsigned u = __float_as_uint(f);
;   u += 0x7fffu + ((u >> 16) & 1u);
;   return (bf16r)(u >> 16);
; }
; __device__ __forceinline__ unsigned pack2(float a, float b) { return (unsigned)f2bf(a) | ((unsigned)f2bf(b) << 16); }
; __device__ __forceinline__ float lo16(unsigned v) { return __uint_as_float(v << 16); }
; __device__ __forceinline__ float hi16(unsigned v) { return __uint_as_float(v & 0xffff0000u); }
; __device__ __forceinline__ float siluf(float x) { return x / (1.f + __expf(-x)); }
; __device__ __forceinline__ float sigmf(float x) { return 1.f / (1.f + __expf(-x)); }
; __device__ __forceinline__ void inproj_epilogue(const Params& p, int layer, int mt, int ntile, int tid,
;                                                 f32x16 (&acc)[2][2], unsigned char* smem) {
;     ...
;       float o = v;
;       if (mode == 1) o = (t >= NPADR) ? v : 0.f;
;       if (mode == 2) o = sigmf(v);
;       sT[row * 136 + col] = f2bf(o);
	s_and_b64 vcc, exec, s[6:7]
	ds_write_b16_d16_hi v117, v48 offset:64
	v_mul_f32_e32 v48, 0xbfb8aa3b, v56
	v_exp_f32_e32 v48, v48
	s_nop 0
	v_add_f32_e32 v48, 1.0, v48
	v_div_scale_f32 v49, s[8:9], v48, v48, 1.0
	v_rcp_f32_e32 v50, v49
	v_div_scale_f32 v51, vcc, 1.0, v48, 1.0
	v_fma_f32 v52, -v49, v50, 1.0
	v_fmac_f32_e32 v50, v52, v50
	v_mul_f32_e32 v52, v51, v50
	v_fma_f32 v53, -v49, v52, v51
	v_fmac_f32_e32 v52, v53, v50
	v_fma_f32 v49, -v49, v52, v51
	v_div_fmas_f32 v49, v49, v50, v52
	v_div_fixup_f32 v48, v49, v48, 1.0
	v_bfe_u32 v49, v48, 16, 1
	v_add3_u32 v48, v48, v49, s80
	s_and_b64 vcc, exec, s[6:7]
	ds_write_b16_d16_hi v118, v48 offset:64
	v_mul_f32_e32 v48, 0xbfb8aa3b, v57
	v_exp_f32_e32 v48, v48
	s_nop 0
	v_add_f32_e32 v48, 1.0, v48
	v_div_scale_f32 v49, s[8:9], v48, v48, 1.0
	v_rcp_f32_e32 v50, v49
	v_div_scale_f32 v51, vcc, 1.0, v48, 1.0
	v_fma_f32 v52, -v49, v50, 1.0
	v_fmac_f32_e32 v50, v52, v50
	v_mul_f32_e32 v52, v51, v50
	v_fma_f32 v53, -v49, v52, v51
	v_fmac_f32_e32 v52, v53, v50
	v_fma_f32 v49, -v49, v52, v51
	v_div_fmas_f32 v49, v49, v50, v52
	v_div_fixup_f32 v48, v49, v48, 1.0
	v_bfe_u32 v49, v48, 16, 1
	v_add3_u32 v48, v48, v49, s80
	s_and_b64 vcc, exec, s[6:7]
	ds_write_b16_d16_hi v119, v48 offset:64
	v_mul_f32_e32 v48, 0xbfb8aa3b, v58
	v_exp_f32_e32 v48, v48
	s_nop 0
	v_add_f32_e32 v48, 1.0, v48
	v_div_scale_f32 v49, s[8:9], v48, v48, 1.0
	v_rcp_f32_e32 v50, v49
	v_div_scale_f32 v51, vcc, 1.0, v48, 1.0
	v_fma_f32 v52, -v49, v50, 1.0
	v_fmac_f32_e32 v50, v52, v50
	v_mul_f32_e32 v52, v51, v50
	v_fma_f32 v53, -v49, v52, v51
	v_fmac_f32_e32 v52, v53, v50
	v_fma_f32 v49, -v49, v52, v51
	v_div_fmas_f32 v49, v49, v50, v52
	v_div_fixup_f32 v48, v49, v48, 1.0
	v_bfe_u32 v49, v48, 16, 1
	v_add3_u32 v48, v48, v49, s80
	s_and_b64 vcc, exec, s[6:7]
	ds_write_b16_d16_hi v120, v48 offset:64
	v_mul_f32_e32 v48, 0xbfb8aa3b, v59
	v_exp_f32_e32 v48, v48
	s_nop 0
	v_add_f32_e32 v48, 1.0, v48
	v_div_scale_f32 v49, s[8:9], v48, v48, 1.0
	v_rcp_f32_e32 v50, v49
	v_div_scale_f32 v51, vcc, 1.0, v48, 1.0
	v_fma_f32 v52, -v49, v50, 1.0
	v_fmac_f32_e32 v50, v52, v50
	v_mul_f32_e32 v52, v51, v50
	v_fma_f32 v53, -v49, v52, v51
	v_fmac_f32_e32 v52, v53, v50
	v_fma_f32 v49, -v49, v52, v51
	v_div_fmas_f32 v49, v49, v50, v52
	v_div_fixup_f32 v48, v49, v48, 1.0
	v_bfe_u32 v49, v48, 16, 1
	v_add3_u32 v48, v48, v49, s80
	s_and_b64 vcc, exec, s[6:7]
	ds_write_b16_d16_hi v121, v48 offset:64
	v_mul_f32_e32 v48, 0xbfb8aa3b, v60
	v_exp_f32_e32 v48, v48
	s_nop 0
	v_add_f32_e32 v48, 1.0, v48
	v_div_scale_f32 v49, s[8:9], v48, v48, 1.0
	v_rcp_f32_e32 v50, v49
	v_div_scale_f32 v51, vcc, 1.0, v48, 1.0
	v_fma_f32 v52, -v49, v50, 1.0
	v_fmac_f32_e32 v50, v52, v50
	v_mul_f32_e32 v52, v51, v50
	v_fma_f32 v53, -v49, v52, v51
	v_fmac_f32_e32 v52, v53, v50
	v_fma_f32 v49, -v49, v52, v51
	v_div_fmas_f32 v49, v49, v50, v52
	v_div_fixup_f32 v48, v49, v48, 1.0
	v_bfe_u32 v49, v48, 16, 1
	v_add3_u32 v48, v48, v49, s80
	s_and_b64 vcc, exec, s[6:7]
	ds_write_b16_d16_hi v122, v48 offset:64
	v_mul_f32_e32 v48, 0xbfb8aa3b, v61
	v_exp_f32_e32 v48, v48
	s_nop 0
	v_add_f32_e32 v48, 1.0, v48
	v_div_scale_f32 v49, s[8:9], v48, v48, 1.0
	v_rcp_f32_e32 v50, v49
	v_div_scale_f32 v51, vcc, 1.0, v48, 1.0
	v_fma_f32 v52, -v49, v50, 1.0
	v_fmac_f32_e32 v50, v52, v50
	v_mul_f32_e32 v52, v51, v50
	v_fma_f32 v53, -v49, v52, v51
	v_fmac_f32_e32 v52, v53, v50
	v_fma_f32 v49, -v49, v52, v51
	v_div_fmas_f32 v49, v49, v50, v52
	v_div_fixup_f32 v48, v49, v48, 1.0
	v_bfe_u32 v49, v48, 16, 1
	v_add3_u32 v48, v48, v49, s80
	s_and_b64 vcc, exec, s[6:7]
	ds_write_b16_d16_hi v123, v48 offset:64
	v_mul_f32_e32 v48, 0xbfb8aa3b, v62
	v_exp_f32_e32 v48, v48
	s_nop 0
	v_add_f32_e32 v48, 1.0, v48
	v_div_scale_f32 v49, s[8:9], v48, v48, 1.0
	v_rcp_f32_e32 v50, v49
	v_div_scale_f32 v51, vcc, 1.0, v48, 1.0
	v_fma_f32 v52, -v49, v50, 1.0
	v_fmac_f32_e32 v50, v52, v50
	v_mul_f32_e32 v52, v51, v50
	v_fma_f32 v53, -v49, v52, v51
	v_fmac_f32_e32 v52, v53, v50
	v_fma_f32 v49, -v49, v52, v51
	v_div_fmas_f32 v49, v49, v50, v52
	v_div_fixup_f32 v48, v49, v48, 1.0
	v_bfe_u32 v49, v48, 16, 1
	v_add3_u32 v48, v48, v49, s80
	s_and_b64 vcc, exec, s[6:7]
	ds_write_b16_d16_hi v116, v48 offset:64
	v_mul_f32_e32 v48, 0xbfb8aa3b, v63
	v_exp_f32_e32 v48, v48
	s_nop 0
	v_add_f32_e32 v48, 1.0, v48
	v_div_scale_f32 v49, s[8:9], v48, v48, 1.0
	v_rcp_f32_e32 v50, v49
	v_div_scale_f32 v51, vcc, 1.0, v48, 1.0
	v_fma_f32 v52, -v49, v50, 1.0
	v_fmac_f32_e32 v50, v52, v50
	v_mul_f32_e32 v52, v51, v50
	v_fma_f32 v53, -v49, v52, v51
	v_fmac_f32_e32 v52, v53, v50
	v_fma_f32 v49, -v49, v52, v51
	v_div_fmas_f32 v49, v49, v50, v52
	v_div_fixup_f32 v48, v49, v48, 1.0
	v_bfe_u32 v50, v48, 16, 1
	v_add_u32_e32 v49, 0x110, v116
	v_add3_u32 v48, v48, v50, s80
	ds_write_b16_d16_hi v49, v48 offset:64
	v_or_b32_e32 v48, 32, v96
	v_add_u32_e32 v49, s74, v48
	s_and_b64 vcc, exec, s[6:7]
	v_cmp_lt_i32_e64 s[8:9], s78, v49
	v_mul_f32_e32 v49, 0xbfb8aa3b, v0
	v_exp_f32_e32 v49, v49
	s_nop 0
	v_add_f32_e32 v49, 1.0, v49
	v_div_scale_f32 v50, s[10:11], v49, v49, 1.0
	v_rcp_f32_e32 v51, v50
	v_div_scale_f32 v52, vcc, 1.0, v49, 1.0
	v_fma_f32 v53, -v50, v51, 1.0
	v_fmac_f32_e32 v51, v53, v51
	v_mul_f32_e32 v53, v52, v51
	v_fma_f32 v54, -v50, v53, v52
	v_fmac_f32_e32 v53, v54, v51
	v_fma_f32 v50, -v50, v53, v52
	v_div_fmas_f32 v50, v50, v51, v53
	v_div_fixup_f32 v49, v50, v49, 1.0
	v_bfe_u32 v50, v49, 16, 1
	v_add3_u32 v50, v49, v50, s80
	v_mul_lo_u32 v49, v48, s81
	v_lshl_add_u32 v48, v106, 1, v49
	ds_write_b16_d16_hi v48, v50
	v_add3_u32 v50, s74, v96, 33
	s_and_b64 vcc, exec, s[6:7]
	v_cmp_lt_i32_e64 s[10:11], s78, v50
	v_mul_f32_e32 v50, 0xbfb8aa3b, v1
; __device__ __forceinline__ bf16r f2bf(float f) {
;   unsigned u = __float_as_uint(f);
;   u += 0x7fffu + ((u >> 16) & 1u);
;   return (bf16r)(u >> 16);
; }
; __device__ __forceinline__ unsigned pack2(float a, float b) { return (unsigned)f2bf(a) | ((unsigned)f2bf(b) << 16); }
; __device__ __forceinline__ float lo16(unsigned v) { return __uint_as_float(v << 16); }
; __device__ __forceinline__ float hi16(unsigned v) { return __uint_as_float(v & 0xffff0000u); }
; __device__ __forceinline__ float siluf(float x) { return x / (1.f + __expf(-x)); }
; __device__ __forceinline__ float sigmf(float x) { return 1.f / (1.f + __expf(-x)); }
; __device__ __forceinline__ void inproj_epilogue(const Params& p, int layer, int mt, int ntile, int tid,
;                                                 f32x16 (&acc)[2][2], unsigned char* smem) {
;     ...
;       float o = v;
;       if (mode == 1) o = (t >= NPADR) ? v : 0.f;
;       if (mode == 2) o = sigmf(v);
;       sT[row * 136 + col] = f2bf(o);
	v_exp_f32_e32 v50, v50
	s_nop 0
	v_add_f32_e32 v50, 1.0, v50
	v_div_scale_f32 v51, s[12:13], v50, v50, 1.0
	v_rcp_f32_e32 v52, v51
	v_div_scale_f32 v53, vcc, 1.0, v50, 1.0
	v_fma_f32 v54, -v51, v52, 1.0
	v_fmac_f32_e32 v52, v54, v52
	v_mul_f32_e32 v54, v53, v52
	v_fma_f32 v55, -v51, v54, v53
	v_fmac_f32_e32 v54, v55, v52
	v_fma_f32 v51, -v51, v54, v53
	v_div_fmas_f32 v51, v51, v52, v54
	v_div_fixup_f32 v50, v51, v50, 1.0
	v_bfe_u32 v51, v50, 16, 1
	v_add3_u32 v51, v50, v51, s80
	v_add_u32_e32 v50, 0x110, v49
	v_lshl_add_u32 v49, v106, 1, v50
	ds_write_b16_d16_hi v49, v51
	v_add3_u32 v51, s74, v96, 34
	s_and_b64 vcc, exec, s[6:7]
	v_cmp_lt_i32_e64 s[12:13], s78, v51
	v_mul_f32_e32 v51, 0xbfb8aa3b, v2
	v_exp_f32_e32 v51, v51
	s_nop 0
	v_add_f32_e32 v51, 1.0, v51
	v_div_scale_f32 v52, s[14:15], v51, v51, 1.0
	v_rcp_f32_e32 v53, v52
	v_div_scale_f32 v54, vcc, 1.0, v51, 1.0
	v_fma_f32 v55, -v52, v53, 1.0
	v_fmac_f32_e32 v53, v55, v53
	v_mul_f32_e32 v55, v54, v53
	v_fma_f32 v56, -v52, v55, v54
	v_fmac_f32_e32 v55, v56, v53
	v_fma_f32 v52, -v52, v55, v54
	v_div_fmas_f32 v52, v52, v53, v55
	v_div_fixup_f32 v51, v52, v51, 1.0
	v_bfe_u32 v52, v51, 16, 1
	v_add3_u32 v52, v51, v52, s80
	v_add_u32_e32 v51, 0x110, v50
	v_lshl_add_u32 v50, v106, 1, v51
	ds_write_b16_d16_hi v50, v52
	v_add3_u32 v52, s74, v96, 35
	s_and_b64 vcc, exec, s[6:7]
	v_cmp_lt_i32_e64 s[14:15], s78, v52
	v_mul_f32_e32 v52, 0xbfb8aa3b, v3
	v_exp_f32_e32 v52, v52
	s_nop 0
	v_add_f32_e32 v52, 1.0, v52
	v_div_scale_f32 v53, s[16:17], v52, v52, 1.0
	v_rcp_f32_e32 v54, v53
	v_div_scale_f32 v55, vcc, 1.0, v52, 1.0
	v_fma_f32 v56, -v53, v54, 1.0
	v_fmac_f32_e32 v54, v56, v54
	v_mul_f32_e32 v56, v55, v54
	v_fma_f32 v57, -v53, v56, v55
	v_fmac_f32_e32 v56, v57, v54
	v_fma_f32 v53, -v53, v56, v55
	v_div_fmas_f32 v53, v53, v54, v56
	v_div_fixup_f32 v52, v53, v52, 1.0
	v_bfe_u32 v53, v52, 16, 1
	v_add3_u32 v53, v52, v53, s80
	v_add_u32_e32 v52, 0x110, v51
	v_lshl_add_u32 v51, v106, 1, v52
	ds_write_b16_d16_hi v51, v53
	v_add3_u32 v53, s74, v96, 40
	s_and_b64 vcc, exec, s[6:7]
	v_cmp_lt_i32_e64 s[16:17], s78, v53
	v_mul_f32_e32 v53, 0xbfb8aa3b, v4
	v_exp_f32_e32 v53, v53
	s_nop 0
	v_add_f32_e32 v53, 1.0, v53
	v_div_scale_f32 v54, s[18:19], v53, v53, 1.0
	v_rcp_f32_e32 v55, v54
	v_div_scale_f32 v56, vcc, 1.0, v53, 1.0
	v_fma_f32 v57, -v54, v55, 1.0
	v_fmac_f32_e32 v55, v57, v55
	v_mul_f32_e32 v57, v56, v55
	v_fma_f32 v58, -v54, v57, v56
	v_fmac_f32_e32 v57, v58, v55
	v_fma_f32 v54, -v54, v57, v56
	v_div_fmas_f32 v54, v54, v55, v57
	v_div_fixup_f32 v53, v54, v53, 1.0
	v_bfe_u32 v54, v53, 16, 1
	v_add3_u32 v54, v53, v54, s80
	v_add_u32_e32 v53, 0x550, v52
	v_lshl_add_u32 v52, v106, 1, v53
	ds_write_b16_d16_hi v52, v54
	v_add3_u32 v54, s74, v96, 41
	s_and_b64 vcc, exec, s[6:7]
	v_cmp_lt_i32_e64 s[18:19], s78, v54
	v_mul_f32_e32 v54, 0xbfb8aa3b, v5
	v_exp_f32_e32 v54, v54
	s_nop 0
	v_add_f32_e32 v54, 1.0, v54
	v_div_scale_f32 v55, s[20:21], v54, v54, 1.0
	v_rcp_f32_e32 v56, v55
	v_div_scale_f32 v57, vcc, 1.0, v54, 1.0
	v_fma_f32 v58, -v55, v56, 1.0
	v_fmac_f32_e32 v56, v58, v56
	v_mul_f32_e32 v58, v57, v56
	v_fma_f32 v59, -v55, v58, v57
	v_fmac_f32_e32 v58, v59, v56
	v_fma_f32 v55, -v55, v58, v57
	v_div_fmas_f32 v55, v55, v56, v58
	v_div_fixup_f32 v54, v55, v54, 1.0
	v_bfe_u32 v55, v54, 16, 1
	v_add3_u32 v55, v54, v55, s80
	v_add_u32_e32 v54, 0x110, v53
	v_lshl_add_u32 v53, v106, 1, v54
	ds_write_b16_d16_hi v53, v55
	v_add3_u32 v55, s74, v96, 42
	s_and_b64 vcc, exec, s[6:7]
	v_cmp_lt_i32_e64 s[20:21], s78, v55
	v_mul_f32_e32 v55, 0xbfb8aa3b, v6
	v_exp_f32_e32 v55, v55
	s_nop 0
	v_add_f32_e32 v55, 1.0, v55
	v_div_scale_f32 v56, s[22:23], v55, v55, 1.0
	v_rcp_f32_e32 v57, v56
	v_div_scale_f32 v58, vcc, 1.0, v55, 1.0
	v_fma_f32 v59, -v56, v57, 1.0
	v_fmac_f32_e32 v57, v59, v57
	v_mul_f32_e32 v59, v58, v57
	v_fma_f32 v60, -v56, v59, v58
	v_fmac_f32_e32 v59, v60, v57
	v_fma_f32 v56, -v56, v59, v58
	v_div_fmas_f32 v56, v56, v57, v59
	v_div_fixup_f32 v55, v56, v55, 1.0
	v_bfe_u32 v56, v55, 16, 1
	v_add3_u32 v56, v55, v56, s80
	v_add_u32_e32 v55, 0x110, v54
	v_lshl_add_u32 v54, v106, 1, v55
	ds_write_b16_d16_hi v54, v56
	v_add3_u32 v56, s74, v96, 43
	s_and_b64 vcc, exec, s[6:7]
	v_cmp_lt_i32_e64 s[22:23], s78, v56
	v_mul_f32_e32 v56, 0xbfb8aa3b, v7
	v_exp_f32_e32 v56, v56
	s_nop 0
	v_add_f32_e32 v56, 1.0, v56
	v_div_scale_f32 v57, s[24:25], v56, v56, 1.0
	v_rcp_f32_e32 v58, v57
	v_div_scale_f32 v59, vcc, 1.0, v56, 1.0
	v_fma_f32 v60, -v57, v58, 1.0
	v_fmac_f32_e32 v58, v60, v58
	v_mul_f32_e32 v60, v59, v58
	v_fma_f32 v61, -v57, v60, v59
	v_fmac_f32_e32 v60, v61, v58
	v_fma_f32 v57, -v57, v60, v59
	v_div_fmas_f32 v57, v57, v58, v60
	v_div_fixup_f32 v56, v57, v56, 1.0
	v_bfe_u32 v57, v56, 16, 1
	v_add_u32_e32 v55, 0x110, v55
	v_add3_u32 v57, v56, v57, s80
	v_lshl_add_u32 v56, v106, 1, v55
	ds_write_b16_d16_hi v56, v57
	v_add3_u32 v57, s74, v96, 48
	s_and_b64 vcc, exec, s[6:7]
	v_cmp_lt_i32_e64 s[24:25], s78, v57
	v_mul_f32_e32 v57, 0xbfb8aa3b, v8
	v_exp_f32_e32 v57, v57
	s_nop 0
	v_add_f32_e32 v57, 1.0, v57
	v_div_scale_f32 v58, s[26:27], v57, v57, 1.0
	v_rcp_f32_e32 v59, v58
	v_div_scale_f32 v60, vcc, 1.0, v57, 1.0
	v_fma_f32 v61, -v58, v59, 1.0
	v_fmac_f32_e32 v59, v61, v59
	v_mul_f32_e32 v61, v60, v59
	v_fma_f32 v62, -v58, v61, v60
	v_fmac_f32_e32 v61, v62, v59
	v_fma_f32 v58, -v58, v61, v60
	v_div_fmas_f32 v58, v58, v59, v61
	v_div_fixup_f32 v57, v58, v57, 1.0
	v_bfe_u32 v58, v57, 16, 1
	v_add_u32_e32 v55, 0x550, v55
	v_add3_u32 v58, v57, v58, s80
	v_lshl_add_u32 v57, v106, 1, v55
	ds_write_b16_d16_hi v57, v58
	v_add3_u32 v58, s74, v96, 49
	s_and_b64 vcc, exec, s[6:7]
	v_cmp_lt_i32_e64 s[26:27], s78, v58
; __device__ __forceinline__ bf16r f2bf(float f) {
;   unsigned u = __float_as_uint(f);
;   u += 0x7fffu + ((u >> 16) & 1u);
;   return (bf16r)(u >> 16);
; }
; __device__ __forceinline__ unsigned pack2(float a, float b) { return (unsigned)f2bf(a) | ((unsigned)f2bf(b) << 16); }
; __device__ __forceinline__ float lo16(unsigned v) { return __uint_as_float(v << 16); }
; __device__ __forceinline__ float hi16(unsigned v) { return __uint_as_float(v & 0xffff0000u); }
; __device__ __forceinline__ float siluf(float x) { return x / (1.f + __expf(-x)); }
; __device__ __forceinline__ float sigmf(float x) { return 1.f / (1.f + __expf(-x)); }
; __device__ __forceinline__ void inproj_epilogue(const Params& p, int layer, int mt, int ntile, int tid,
;                                                 f32x16 (&acc)[2][2], unsigned char* smem) {
;     ...
;       float o = v;
;       if (mode == 1) o = (t >= NPADR) ? v : 0.f;
;       if (mode == 2) o = sigmf(v);
;       sT[row * 136 + col] = f2bf(o);
	v_mul_f32_e32 v58, 0xbfb8aa3b, v9
	v_exp_f32_e32 v58, v58
	s_nop 0
	v_add_f32_e32 v58, 1.0, v58
	v_div_scale_f32 v59, s[28:29], v58, v58, 1.0
	v_rcp_f32_e32 v60, v59
	v_div_scale_f32 v61, vcc, 1.0, v58, 1.0
	v_fma_f32 v62, -v59, v60, 1.0
	v_fmac_f32_e32 v60, v62, v60
	v_mul_f32_e32 v62, v61, v60
	v_fma_f32 v63, -v59, v62, v61
	v_fmac_f32_e32 v62, v63, v60
	v_fma_f32 v59, -v59, v62, v61
	v_div_fmas_f32 v59, v59, v60, v62
	v_div_fixup_f32 v58, v59, v58, 1.0
	v_bfe_u32 v59, v58, 16, 1
	v_add_u32_e32 v55, 0x110, v55
	v_add3_u32 v59, v58, v59, s80
	v_lshl_add_u32 v58, v106, 1, v55
	ds_write_b16_d16_hi v58, v59
	v_add3_u32 v59, s74, v96, 50
	s_and_b64 vcc, exec, s[6:7]
	v_cmp_lt_i32_e64 s[28:29], s78, v59
	v_mul_f32_e32 v59, 0xbfb8aa3b, v10
	v_exp_f32_e32 v59, v59
	s_nop 0
	v_add_f32_e32 v59, 1.0, v59
	v_div_scale_f32 v60, s[30:31], v59, v59, 1.0
	v_rcp_f32_e32 v61, v60
	v_div_scale_f32 v62, vcc, 1.0, v59, 1.0
	v_fma_f32 v63, -v60, v61, 1.0
	v_fmac_f32_e32 v61, v63, v61
	v_mul_f32_e32 v63, v62, v61
	v_fma_f32 v107, -v60, v63, v62
	v_fmac_f32_e32 v63, v107, v61
	v_fma_f32 v60, -v60, v63, v62
	v_div_fmas_f32 v60, v60, v61, v63
	v_div_fixup_f32 v59, v60, v59, 1.0
	v_bfe_u32 v60, v59, 16, 1
	v_add_u32_e32 v55, 0x110, v55
	v_add3_u32 v60, v59, v60, s80
	v_lshl_add_u32 v59, v106, 1, v55
	ds_write_b16_d16_hi v59, v60
	v_add3_u32 v60, s74, v96, 51
	s_and_b64 vcc, exec, s[6:7]
	v_cmp_lt_i32_e64 s[30:31], s78, v60
	v_mul_f32_e32 v60, 0xbfb8aa3b, v11
	v_exp_f32_e32 v60, v60
	s_nop 0
	v_add_f32_e32 v60, 1.0, v60
	v_div_scale_f32 v61, s[34:35], v60, v60, 1.0
	v_rcp_f32_e32 v62, v61
	v_div_scale_f32 v63, vcc, 1.0, v60, 1.0
	v_fma_f32 v107, -v61, v62, 1.0
	v_fmac_f32_e32 v62, v107, v62
	v_mul_f32_e32 v107, v63, v62
	v_fma_f32 v110, -v61, v107, v63
	v_fmac_f32_e32 v107, v110, v62
	v_fma_f32 v61, -v61, v107, v63
	v_div_fmas_f32 v61, v61, v62, v107
	v_div_fixup_f32 v60, v61, v60, 1.0
	v_bfe_u32 v61, v60, 16, 1
	v_add_u32_e32 v55, 0x110, v55
	v_add3_u32 v61, v60, v61, s80
	v_lshl_add_u32 v60, v106, 1, v55
	ds_write_b16_d16_hi v60, v61
	v_add3_u32 v61, s74, v96, 56
	s_and_b64 vcc, exec, s[6:7]
	v_cmp_lt_i32_e64 s[34:35], s78, v61
	v_mul_f32_e32 v61, 0xbfb8aa3b, v12
	v_exp_f32_e32 v61, v61
	s_nop 0
	v_add_f32_e32 v61, 1.0, v61
	v_div_scale_f32 v62, s[36:37], v61, v61, 1.0
	v_rcp_f32_e32 v63, v62
	v_div_scale_f32 v107, vcc, 1.0, v61, 1.0
	v_fma_f32 v110, -v62, v63, 1.0
	v_fmac_f32_e32 v63, v110, v63
	v_mul_f32_e32 v110, v107, v63
	v_fma_f32 v111, -v62, v110, v107
	v_fmac_f32_e32 v110, v111, v63
	v_fma_f32 v62, -v62, v110, v107
	v_div_fmas_f32 v62, v62, v63, v110
	v_div_fixup_f32 v61, v62, v61, 1.0
	v_bfe_u32 v62, v61, 16, 1
	v_add_u32_e32 v55, 0x550, v55
	v_add3_u32 v62, v61, v62, s80
	v_lshl_add_u32 v61, v106, 1, v55
	ds_write_b16_d16_hi v61, v62
	v_add3_u32 v62, s74, v96, 57
	s_and_b64 vcc, exec, s[6:7]
	v_cmp_lt_i32_e64 s[36:37], s78, v62
	v_mul_f32_e32 v62, 0xbfb8aa3b, v13
	v_exp_f32_e32 v62, v62
	s_nop 0
	v_add_f32_e32 v62, 1.0, v62
	v_div_scale_f32 v63, s[38:39], v62, v62, 1.0
	v_rcp_f32_e32 v107, v63
	v_div_scale_f32 v110, vcc, 1.0, v62, 1.0
	v_fma_f32 v111, -v63, v107, 1.0
	v_fmac_f32_e32 v107, v111, v107
	v_mul_f32_e32 v111, v110, v107
	v_fma_f32 v112, -v63, v111, v110
	v_fmac_f32_e32 v111, v112, v107
	v_fma_f32 v63, -v63, v111, v110
	v_div_fmas_f32 v63, v63, v107, v111
	v_div_fixup_f32 v62, v63, v62, 1.0
	v_bfe_u32 v63, v62, 16, 1
	v_add_u32_e32 v55, 0x110, v55
	v_add3_u32 v63, v62, v63, s80
	v_lshl_add_u32 v62, v106, 1, v55
	ds_write_b16_d16_hi v62, v63
	v_add3_u32 v63, s74, v96, 58
	s_and_b64 vcc, exec, s[6:7]
	v_cmp_lt_i32_e64 s[38:39], s78, v63
	v_mul_f32_e32 v63, 0xbfb8aa3b, v14
	v_exp_f32_e32 v63, v63
	s_nop 0
	v_add_f32_e32 v63, 1.0, v63
	v_div_scale_f32 v107, s[40:41], v63, v63, 1.0
	v_rcp_f32_e32 v110, v107
	v_div_scale_f32 v111, vcc, 1.0, v63, 1.0
	v_fma_f32 v112, -v107, v110, 1.0
	v_fmac_f32_e32 v110, v112, v110
	v_mul_f32_e32 v112, v111, v110
	v_fma_f32 v113, -v107, v112, v111
	v_fmac_f32_e32 v112, v113, v110
	v_fma_f32 v107, -v107, v112, v111
	v_div_fmas_f32 v107, v107, v110, v112
	v_div_fixup_f32 v63, v107, v63, 1.0
	v_bfe_u32 v107, v63, 16, 1
	v_add_u32_e32 v55, 0x110, v55
	v_add3_u32 v63, v63, v107, s80
	v_lshl_add_u32 v55, v106, 1, v55
	ds_write_b16_d16_hi v55, v63
	v_add3_u32 v63, s74, v96, 59
	s_and_b64 vcc, exec, s[6:7]
	v_cmp_lt_i32_e64 s[40:41], s78, v63
	v_mul_f32_e32 v63, 0xbfb8aa3b, v15
	v_exp_f32_e32 v63, v63
	s_nop 0
	v_add_f32_e32 v63, 1.0, v63
	v_div_scale_f32 v96, s[92:93], v63, v63, 1.0
	v_rcp_f32_e32 v106, v96
	v_div_scale_f32 v107, vcc, 1.0, v63, 1.0
	v_fma_f32 v110, -v96, v106, 1.0
	v_fmac_f32_e32 v106, v110, v106
	v_mul_f32_e32 v110, v107, v106
	v_fma_f32 v111, -v96, v110, v107
	v_fmac_f32_e32 v110, v111, v106
	v_fma_f32 v96, -v96, v110, v107
	v_div_fmas_f32 v96, v96, v106, v110
	v_div_fixup_f32 v63, v96, v63, 1.0
	v_bfe_u32 v96, v63, 16, 1
	v_add3_u32 v63, v63, v96, s80
	ds_write_b16_d16_hi v55, v63 offset:272
	s_and_b64 vcc, exec, s[6:7]
	v_mul_f32_e32 v32, 0xbfb8aa3b, v32
	v_exp_f32_e32 v32, v32
	s_nop 0
	v_add_f32_e32 v32, 1.0, v32
	v_div_scale_f32 v63, s[8:9], v32, v32, 1.0
	v_rcp_f32_e32 v96, v63
	v_div_scale_f32 v106, vcc, 1.0, v32, 1.0
	v_fma_f32 v107, -v63, v96, 1.0
	v_fmac_f32_e32 v96, v107, v96
	v_mul_f32_e32 v107, v106, v96
	v_fma_f32 v110, -v63, v107, v106
	v_fmac_f32_e32 v107, v110, v96
	v_fma_f32 v63, -v63, v107, v106
	v_div_fmas_f32 v63, v63, v96, v107
	v_div_fixup_f32 v32, v63, v32, 1.0
	v_bfe_u32 v63, v32, 16, 1
	v_add3_u32 v32, v32, v63, s80
	s_and_b64 vcc, exec, s[6:7]
	ds_write_b16_d16_hi v48, v32 offset:64
	v_mul_f32_e32 v32, 0xbfb8aa3b, v33
	v_exp_f32_e32 v32, v32
	s_nop 0
	v_add_f32_e32 v32, 1.0, v32
; __device__ __forceinline__ bf16r f2bf(float f) {
;   unsigned u = __float_as_uint(f);
;   u += 0x7fffu + ((u >> 16) & 1u);
;   return (bf16r)(u >> 16);
; }
; __device__ __forceinline__ unsigned pack2(float a, float b) { return (unsigned)f2bf(a) | ((unsigned)f2bf(b) << 16); }
; __device__ __forceinline__ float lo16(unsigned v) { return __uint_as_float(v << 16); }
; __device__ __forceinline__ float hi16(unsigned v) { return __uint_as_float(v & 0xffff0000u); }
; __device__ __forceinline__ float siluf(float x) { return x / (1.f + __expf(-x)); }
; __device__ __forceinline__ float sigmf(float x) { return 1.f / (1.f + __expf(-x)); }
; __device__ __forceinline__ void inproj_epilogue(const Params& p, int layer, int mt, int ntile, int tid,
;                                                 f32x16 (&acc)[2][2], unsigned char* smem) {
;     ...
;       float o = v;
;       if (mode == 1) o = (t >= NPADR) ? v : 0.f;
;       if (mode == 2) o = sigmf(v);
;       sT[row * 136 + col] = f2bf(o);
	v_div_scale_f32 v33, s[8:9], v32, v32, 1.0
	v_rcp_f32_e32 v48, v33
	v_div_scale_f32 v63, vcc, 1.0, v32, 1.0
	v_fma_f32 v96, -v33, v48, 1.0
	v_fmac_f32_e32 v48, v96, v48
	v_mul_f32_e32 v96, v63, v48
	v_fma_f32 v106, -v33, v96, v63
	v_fmac_f32_e32 v96, v106, v48
	v_fma_f32 v33, -v33, v96, v63
	v_div_fmas_f32 v33, v33, v48, v96
	v_div_fixup_f32 v32, v33, v32, 1.0
	v_bfe_u32 v33, v32, 16, 1
	v_add3_u32 v32, v32, v33, s80
	s_and_b64 vcc, exec, s[6:7]
	ds_write_b16_d16_hi v49, v32 offset:64
	v_mul_f32_e32 v32, 0xbfb8aa3b, v34
	v_exp_f32_e32 v32, v32
	s_nop 0
	v_add_f32_e32 v32, 1.0, v32
	v_div_scale_f32 v33, s[8:9], v32, v32, 1.0
	v_rcp_f32_e32 v34, v33
	v_div_scale_f32 v48, vcc, 1.0, v32, 1.0
	v_fma_f32 v49, -v33, v34, 1.0
	v_fmac_f32_e32 v34, v49, v34
	v_mul_f32_e32 v49, v48, v34
	v_fma_f32 v63, -v33, v49, v48
	v_fmac_f32_e32 v49, v63, v34
	v_fma_f32 v33, -v33, v49, v48
	v_div_fmas_f32 v33, v33, v34, v49
	v_div_fixup_f32 v32, v33, v32, 1.0
	v_bfe_u32 v33, v32, 16, 1
	v_add3_u32 v32, v32, v33, s80
	s_and_b64 vcc, exec, s[6:7]
	ds_write_b16_d16_hi v50, v32 offset:64
	v_mul_f32_e32 v32, 0xbfb8aa3b, v35
	v_exp_f32_e32 v32, v32
	s_nop 0
	v_add_f32_e32 v32, 1.0, v32
	v_div_scale_f32 v33, s[8:9], v32, v32, 1.0
	v_rcp_f32_e32 v34, v33
	v_div_scale_f32 v35, vcc, 1.0, v32, 1.0
	v_fma_f32 v48, -v33, v34, 1.0
	v_fmac_f32_e32 v34, v48, v34
	v_mul_f32_e32 v48, v35, v34
	v_fma_f32 v49, -v33, v48, v35
	v_fmac_f32_e32 v48, v49, v34
	v_fma_f32 v33, -v33, v48, v35
	v_div_fmas_f32 v33, v33, v34, v48
	v_div_fixup_f32 v32, v33, v32, 1.0
	v_bfe_u32 v33, v32, 16, 1
	v_add3_u32 v32, v32, v33, s80
	s_and_b64 vcc, exec, s[6:7]
	ds_write_b16_d16_hi v51, v32 offset:64
	v_mul_f32_e32 v32, 0xbfb8aa3b, v36
	v_exp_f32_e32 v32, v32
	s_nop 0
	v_add_f32_e32 v32, 1.0, v32
	v_div_scale_f32 v33, s[8:9], v32, v32, 1.0
	v_rcp_f32_e32 v34, v33
	v_div_scale_f32 v35, vcc, 1.0, v32, 1.0
	v_fma_f32 v36, -v33, v34, 1.0
	v_fmac_f32_e32 v34, v36, v34
	v_mul_f32_e32 v36, v35, v34
	v_fma_f32 v48, -v33, v36, v35
	v_fmac_f32_e32 v36, v48, v34
	v_fma_f32 v33, -v33, v36, v35
	v_div_fmas_f32 v33, v33, v34, v36
	v_div_fixup_f32 v32, v33, v32, 1.0
	v_bfe_u32 v33, v32, 16, 1
	v_add3_u32 v32, v32, v33, s80
	s_and_b64 vcc, exec, s[6:7]
	ds_write_b16_d16_hi v52, v32 offset:64
	v_mul_f32_e32 v32, 0xbfb8aa3b, v37
	v_exp_f32_e32 v32, v32
	s_nop 0
	v_add_f32_e32 v32, 1.0, v32
	v_div_scale_f32 v33, s[8:9], v32, v32, 1.0
	v_rcp_f32_e32 v34, v33
	v_div_scale_f32 v35, vcc, 1.0, v32, 1.0
	v_fma_f32 v36, -v33, v34, 1.0
	v_fmac_f32_e32 v34, v36, v34
	v_mul_f32_e32 v36, v35, v34
	v_fma_f32 v37, -v33, v36, v35
	v_fmac_f32_e32 v36, v37, v34
	v_fma_f32 v33, -v33, v36, v35
	v_div_fmas_f32 v33, v33, v34, v36
	v_div_fixup_f32 v32, v33, v32, 1.0
	v_bfe_u32 v33, v32, 16, 1
	v_add3_u32 v32, v32, v33, s80
	s_and_b64 vcc, exec, s[6:7]
	ds_write_b16_d16_hi v53, v32 offset:64
	v_mul_f32_e32 v32, 0xbfb8aa3b, v38
	v_exp_f32_e32 v32, v32
	s_nop 0
	v_add_f32_e32 v32, 1.0, v32
	v_div_scale_f32 v33, s[8:9], v32, v32, 1.0
	v_rcp_f32_e32 v34, v33
	v_div_scale_f32 v35, vcc, 1.0, v32, 1.0
	v_fma_f32 v36, -v33, v34, 1.0
	v_fmac_f32_e32 v34, v36, v34
	v_mul_f32_e32 v36, v35, v34
	v_fma_f32 v37, -v33, v36, v35
	v_fmac_f32_e32 v36, v37, v34
	v_fma_f32 v33, -v33, v36, v35
	v_div_fmas_f32 v33, v33, v34, v36
	v_div_fixup_f32 v32, v33, v32, 1.0
	v_bfe_u32 v33, v32, 16, 1
	v_add3_u32 v32, v32, v33, s80
	s_and_b64 vcc, exec, s[6:7]
	ds_write_b16_d16_hi v54, v32 offset:64
	v_mul_f32_e32 v32, 0xbfb8aa3b, v39
	v_exp_f32_e32 v32, v32
	s_nop 0
	v_add_f32_e32 v32, 1.0, v32
	v_div_scale_f32 v33, s[8:9], v32, v32, 1.0
	v_rcp_f32_e32 v34, v33
	v_div_scale_f32 v35, vcc, 1.0, v32, 1.0
	v_fma_f32 v36, -v33, v34, 1.0
	v_fmac_f32_e32 v34, v36, v34
	v_mul_f32_e32 v36, v35, v34
	v_fma_f32 v37, -v33, v36, v35
	v_fmac_f32_e32 v36, v37, v34
	v_fma_f32 v33, -v33, v36, v35
	v_div_fmas_f32 v33, v33, v34, v36
	v_div_fixup_f32 v32, v33, v32, 1.0
	v_bfe_u32 v33, v32, 16, 1
	v_add3_u32 v32, v32, v33, s80
	s_and_b64 vcc, exec, s[6:7]
	ds_write_b16_d16_hi v56, v32 offset:64
	v_mul_f32_e32 v32, 0xbfb8aa3b, v40
	v_exp_f32_e32 v32, v32
	s_nop 0
	v_add_f32_e32 v32, 1.0, v32
	v_div_scale_f32 v33, s[8:9], v32, v32, 1.0
	v_rcp_f32_e32 v34, v33
	v_div_scale_f32 v35, vcc, 1.0, v32, 1.0
	v_fma_f32 v36, -v33, v34, 1.0
	v_fmac_f32_e32 v34, v36, v34
	v_mul_f32_e32 v36, v35, v34
; __device__ __forceinline__ bf16r f2bf(float f) {
;   unsigned u = __float_as_uint(f);
;   u += 0x7fffu + ((u >> 16) & 1u);
;   return (bf16r)(u >> 16);
; }
; __device__ __forceinline__ unsigned pack2(float a, float b) { return (unsigned)f2bf(a) | ((unsigned)f2bf(b) << 16); }
; __device__ __forceinline__ float lo16(unsigned v) { return __uint_as_float(v << 16); }
; __device__ __forceinline__ float hi16(unsigned v) { return __uint_as_float(v & 0xffff0000u); }
; __device__ __forceinline__ float siluf(float x) { return x / (1.f + __expf(-x)); }
; __device__ __forceinline__ float sigmf(float x) { return 1.f / (1.f + __expf(-x)); }
; __device__ __forceinline__ void inproj_epilogue(const Params& p, int layer, int mt, int ntile, int tid,
;                                                 f32x16 (&acc)[2][2], unsigned char* smem) {
;     ...
;       float o = v;
;       if (mode == 1) o = (t >= NPADR) ? v : 0.f;
;       if (mode == 2) o = sigmf(v);
;       sT[row * 136 + col] = f2bf(o);
	v_fma_f32 v37, -v33, v36, v35
	v_fmac_f32_e32 v36, v37, v34
	v_fma_f32 v33, -v33, v36, v35
	v_div_fmas_f32 v33, v33, v34, v36
	v_div_fixup_f32 v32, v33, v32, 1.0
	v_bfe_u32 v33, v32, 16, 1
	v_add3_u32 v32, v32, v33, s80
	s_and_b64 vcc, exec, s[6:7]
	ds_write_b16_d16_hi v57, v32 offset:64
	v_mul_f32_e32 v32, 0xbfb8aa3b, v41
	v_exp_f32_e32 v32, v32
	s_nop 0
	v_add_f32_e32 v32, 1.0, v32
	v_div_scale_f32 v33, s[8:9], v32, v32, 1.0
	v_rcp_f32_e32 v34, v33
	v_div_scale_f32 v35, vcc, 1.0, v32, 1.0
	v_fma_f32 v36, -v33, v34, 1.0
	v_fmac_f32_e32 v34, v36, v34
	v_mul_f32_e32 v36, v35, v34
	v_fma_f32 v37, -v33, v36, v35
	v_fmac_f32_e32 v36, v37, v34
	v_fma_f32 v33, -v33, v36, v35
	v_div_fmas_f32 v33, v33, v34, v36
	v_div_fixup_f32 v32, v33, v32, 1.0
	v_bfe_u32 v33, v32, 16, 1
	v_add3_u32 v32, v32, v33, s80
	s_and_b64 vcc, exec, s[6:7]
	ds_write_b16_d16_hi v58, v32 offset:64
	v_mul_f32_e32 v32, 0xbfb8aa3b, v42
	v_exp_f32_e32 v32, v32
	s_nop 0
	v_add_f32_e32 v32, 1.0, v32
	v_div_scale_f32 v33, s[8:9], v32, v32, 1.0
	v_rcp_f32_e32 v34, v33
	v_div_scale_f32 v35, vcc, 1.0, v32, 1.0
	v_fma_f32 v36, -v33, v34, 1.0
	v_fmac_f32_e32 v34, v36, v34
	v_mul_f32_e32 v36, v35, v34
	v_fma_f32 v37, -v33, v36, v35
	v_fmac_f32_e32 v36, v37, v34
	v_fma_f32 v33, -v33, v36, v35
	v_div_fmas_f32 v33, v33, v34, v36
	v_div_fixup_f32 v32, v33, v32, 1.0
	v_bfe_u32 v33, v32, 16, 1
	v_add3_u32 v32, v32, v33, s80
	s_and_b64 vcc, exec, s[6:7]
	ds_write_b16_d16_hi v59, v32 offset:64
	v_mul_f32_e32 v32, 0xbfb8aa3b, v43
	v_exp_f32_e32 v32, v32
	s_nop 0
	v_add_f32_e32 v32, 1.0, v32
	v_div_scale_f32 v33, s[8:9], v32, v32, 1.0
	v_rcp_f32_e32 v34, v33
	v_div_scale_f32 v35, vcc, 1.0, v32, 1.0
	v_fma_f32 v36, -v33, v34, 1.0
	v_fmac_f32_e32 v34, v36, v34
	v_mul_f32_e32 v36, v35, v34
	v_fma_f32 v37, -v33, v36, v35
	v_fmac_f32_e32 v36, v37, v34
	v_fma_f32 v33, -v33, v36, v35
	v_div_fmas_f32 v33, v33, v34, v36
	v_div_fixup_f32 v32, v33, v32, 1.0
	v_bfe_u32 v33, v32, 16, 1
	v_add3_u32 v32, v32, v33, s80
	s_and_b64 vcc, exec, s[6:7]
	ds_write_b16_d16_hi v60, v32 offset:64
	v_mul_f32_e32 v32, 0xbfb8aa3b, v44
	v_exp_f32_e32 v32, v32
	s_nop 0
	v_add_f32_e32 v32, 1.0, v32
	v_div_scale_f32 v33, s[8:9], v32, v32, 1.0
	v_rcp_f32_e32 v34, v33
	v_div_scale_f32 v35, vcc, 1.0, v32, 1.0
	v_fma_f32 v36, -v33, v34, 1.0
	v_fmac_f32_e32 v34, v36, v34
	v_mul_f32_e32 v36, v35, v34
	v_fma_f32 v37, -v33, v36, v35
	v_fmac_f32_e32 v36, v37, v34
	v_fma_f32 v33, -v33, v36, v35
	v_div_fmas_f32 v33, v33, v34, v36
	v_div_fixup_f32 v32, v33, v32, 1.0
	v_bfe_u32 v33, v32, 16, 1
	v_add3_u32 v32, v32, v33, s80
	s_and_b64 vcc, exec, s[6:7]
	ds_write_b16_d16_hi v61, v32 offset:64
	v_mul_f32_e32 v32, 0xbfb8aa3b, v45
	v_exp_f32_e32 v32, v32
	s_nop 0
	v_add_f32_e32 v32, 1.0, v32
	v_div_scale_f32 v33, s[8:9], v32, v32, 1.0
	v_rcp_f32_e32 v34, v33
	v_div_scale_f32 v35, vcc, 1.0, v32, 1.0
	v_fma_f32 v36, -v33, v34, 1.0
	v_fmac_f32_e32 v34, v36, v34
	v_mul_f32_e32 v36, v35, v34
	v_fma_f32 v37, -v33, v36, v35
	v_fmac_f32_e32 v36, v37, v34
	v_fma_f32 v33, -v33, v36, v35
	v_div_fmas_f32 v33, v33, v34, v36
	v_div_fixup_f32 v32, v33, v32, 1.0
	v_bfe_u32 v33, v32, 16, 1
	v_add3_u32 v32, v32, v33, s80
	s_and_b64 vcc, exec, s[6:7]
	ds_write_b16_d16_hi v62, v32 offset:64
	v_mul_f32_e32 v32, 0xbfb8aa3b, v46
	v_exp_f32_e32 v32, v32
	s_nop 0
	v_add_f32_e32 v32, 1.0, v32
	v_div_scale_f32 v33, s[8:9], v32, v32, 1.0
	v_rcp_f32_e32 v34, v33
	v_div_scale_f32 v35, vcc, 1.0, v32, 1.0
	v_fma_f32 v36, -v33, v34, 1.0
	v_fmac_f32_e32 v34, v36, v34
	v_mul_f32_e32 v36, v35, v34
	v_fma_f32 v37, -v33, v36, v35
	v_fmac_f32_e32 v36, v37, v34
	v_fma_f32 v33, -v33, v36, v35
	v_div_fmas_f32 v33, v33, v34, v36
	v_div_fixup_f32 v32, v33, v32, 1.0
	v_bfe_u32 v33, v32, 16, 1
	v_add3_u32 v32, v32, v33, s80
	s_and_b64 vcc, exec, s[6:7]
	ds_write_b16_d16_hi v55, v32 offset:64
	v_mul_f32_e32 v32, 0xbfb8aa3b, v47
	v_exp_f32_e32 v32, v32
	s_nop 0
	v_add_f32_e32 v32, 1.0, v32
	v_div_scale_f32 v33, s[4:5], v32, v32, 1.0
	v_rcp_f32_e32 v34, v33
	v_div_scale_f32 v35, vcc, 1.0, v32, 1.0
	v_fma_f32 v36, -v33, v34, 1.0
	v_fmac_f32_e32 v34, v36, v34
	v_mul_f32_e32 v36, v35, v34
	v_fma_f32 v37, -v33, v36, v35
	v_fmac_f32_e32 v36, v37, v34
	v_fma_f32 v33, -v33, v36, v35
	v_div_fmas_f32 v33, v33, v34, v36
	v_div_fixup_f32 v32, v33, v32, 1.0
	s_branch .LBB0_4343

; __device__ __forceinline__ float sigmf(float x) { return 1.f / (1.f + __expf(-x)); }
; template <int MT, int NT, class F>
; __device__ __forceinline__ void acc_foreach(int tid, f32x16 (&acc)[MT][NT], F f) {
;     ...
;   const int wm = w >> 1, wn = w & 1, hi = lane >> 5, c = lane & 31;
; #pragma unroll
;   for (int mt = 0; mt < MT; mt++)
; #pragma unroll
;     for (int nt = 0; nt < NT; nt++)
; #pragma unroll
;       for (int i = 0; i < 16; i++) {
;         int row = wm * (MT * 32) + mt * 32 + (i & 3) + 8 * (i >> 2) + 4 * hi;
;         int col = wn * (NT * 32) + nt * 32 + c;
;         f(row, col, acc[mt][nt][i]);
; __device__ __forceinline__ void inproj_epilogue(const Params& p, int layer, int mt, int ntile, int tid,
;                                                 f32x16 (&acc)[2][2], unsigned char* smem) {
;     ...
;     acc_foreach(tid, acc, [&](int row, int col, float v) {
;       int t = m0 + row;
;       float o = v;
;       if (mode == 1) o = (t >= NPADR) ? v : 0.f;
;       if (mode == 2) o = sigmf(v);
;       sT[row * 136 + col] = f2bf(o);
;     });
.LBB0_4545:
	v_bfe_u32 v110, v107, 16, 1
	v_and_b32_e32 v106, 0x5f, v106
	v_add3_u32 v111, v107, v110, s83
	v_mul_lo_u32 v110, v96, s86
	v_lshl_add_u32 v107, v106, 1, v110
	ds_write_b16_d16_hi v107, v111
	v_add3_u32 v111, s74, v96, 1
	v_cndmask_b32_e64 v112, 0, 1, s[10:11]
	v_cmp_ne_u32_e64 s[6:7], 1, v112
	v_cmp_lt_i32_e64 s[10:11], s81, v111
	s_nop 1

; __device__ __forceinline__ float sigmf(float x) { return 1.f / (1.f + __expf(-x)); }
; __device__ __forceinline__ bf16r f2bf(float f) {
;   unsigned u = __float_as_uint(f);
;   u += 0x7fffu + ((u >> 16) & 1u);
;   return (bf16r)(u >> 16);
; }
; __device__ __forceinline__ void inproj_epilogue(const Params& p, int layer, int mt, int ntile, int tid,
;                                                 f32x16 (&acc)[2][2], unsigned char* smem) {
;     ...
;     acc_foreach(tid, acc, [&](int row, int col, float v) {
;       int t = m0 + row;
;       float o = v;
;       if (mode == 1) o = (t >= NPADR) ? v : 0.f;
;       if (mode == 2) o = sigmf(v);
;       sT[row * 136 + col] = f2bf(o);
;     });
.LBB0_4548:
	v_bfe_u32 v112, v111, 16, 1
	v_add3_u32 v112, v111, v112, s83
	v_add_u32_e32 v111, 0x110, v110
	v_lshl_add_u32 v110, v106, 1, v111
	ds_write_b16_d16_hi v110, v112
	v_add3_u32 v112, s74, v96, 2
	v_cmp_lt_i32_e64 s[12:13], s81, v112
	s_nop 1

; __device__ __forceinline__ float sigmf(float x) { return 1.f / (1.f + __expf(-x)); }
; __device__ __forceinline__ bf16r f2bf(float f) {
;   unsigned u = __float_as_uint(f);
;   u += 0x7fffu + ((u >> 16) & 1u);
;   return (bf16r)(u >> 16);
; }
; __device__ __forceinline__ void inproj_epilogue(const Params& p, int layer, int mt, int ntile, int tid,
;                                                 f32x16 (&acc)[2][2], unsigned char* smem) {
;     ...
;     acc_foreach(tid, acc, [&](int row, int col, float v) {
;       int t = m0 + row;
;       float o = v;
;       if (mode == 1) o = (t >= NPADR) ? v : 0.f;
;       if (mode == 2) o = sigmf(v);
;       sT[row * 136 + col] = f2bf(o);
;     });
.LBB0_4551:
	v_bfe_u32 v113, v112, 16, 1
	v_add3_u32 v113, v112, v113, s83
	v_add_u32_e32 v112, 0x110, v111
	v_lshl_add_u32 v111, v106, 1, v112
	ds_write_b16_d16_hi v111, v113
	v_add3_u32 v113, s74, v96, 3
	v_cmp_lt_i32_e64 s[14:15], s81, v113
	s_nop 1

; __device__ __forceinline__ float sigmf(float x) { return 1.f / (1.f + __expf(-x)); }
; __device__ __forceinline__ bf16r f2bf(float f) {
;   unsigned u = __float_as_uint(f);
;   u += 0x7fffu + ((u >> 16) & 1u);
;   return (bf16r)(u >> 16);
; }
; __device__ __forceinline__ void inproj_epilogue(const Params& p, int layer, int mt, int ntile, int tid,
;                                                 f32x16 (&acc)[2][2], unsigned char* smem) {
;     ...
;     acc_foreach(tid, acc, [&](int row, int col, float v) {
;       int t = m0 + row;
;       float o = v;
;       if (mode == 1) o = (t >= NPADR) ? v : 0.f;
;       if (mode == 2) o = sigmf(v);
;       sT[row * 136 + col] = f2bf(o);
;     });
.LBB0_4554:
	v_bfe_u32 v114, v113, 16, 1
	v_add3_u32 v114, v113, v114, s83
	v_add_u32_e32 v113, 0x110, v112
	v_lshl_add_u32 v112, v106, 1, v113
	ds_write_b16_d16_hi v112, v114
	v_add3_u32 v114, s74, v96, 8
	v_cmp_lt_i32_e64 s[16:17], s81, v114
	s_nop 1

; __device__ __forceinline__ float sigmf(float x) { return 1.f / (1.f + __expf(-x)); }
; __device__ __forceinline__ bf16r f2bf(float f) {
;   unsigned u = __float_as_uint(f);
;   u += 0x7fffu + ((u >> 16) & 1u);
;   return (bf16r)(u >> 16);
; }
; __device__ __forceinline__ void inproj_epilogue(const Params& p, int layer, int mt, int ntile, int tid,
;                                                 f32x16 (&acc)[2][2], unsigned char* smem) {
;     ...
;     acc_foreach(tid, acc, [&](int row, int col, float v) {
;       int t = m0 + row;
;       float o = v;
;       if (mode == 1) o = (t >= NPADR) ? v : 0.f;
;       if (mode == 2) o = sigmf(v);
;       sT[row * 136 + col] = f2bf(o);
;     });
.LBB0_4557:
	v_bfe_u32 v115, v114, 16, 1
	v_add3_u32 v115, v114, v115, s83
	v_add_u32_e32 v114, 0x550, v113
	v_lshl_add_u32 v113, v106, 1, v114
	ds_write_b16_d16_hi v113, v115
	v_add3_u32 v115, s74, v96, 9
	v_cmp_lt_i32_e64 s[18:19], s81, v115
	s_nop 1

; __device__ __forceinline__ float sigmf(float x) { return 1.f / (1.f + __expf(-x)); }
; __device__ __forceinline__ bf16r f2bf(float f) {
;   unsigned u = __float_as_uint(f);
;   u += 0x7fffu + ((u >> 16) & 1u);
;   return (bf16r)(u >> 16);
; }
; __device__ __forceinline__ void inproj_epilogue(const Params& p, int layer, int mt, int ntile, int tid,
;                                                 f32x16 (&acc)[2][2], unsigned char* smem) {
;     ...
;     acc_foreach(tid, acc, [&](int row, int col, float v) {
;       int t = m0 + row;
;       float o = v;
;       if (mode == 1) o = (t >= NPADR) ? v : 0.f;
;       if (mode == 2) o = sigmf(v);
;       sT[row * 136 + col] = f2bf(o);
;     });
.LBB0_4560:
	v_bfe_u32 v116, v115, 16, 1
	v_add3_u32 v116, v115, v116, s83
	v_add_u32_e32 v115, 0x110, v114
	v_lshl_add_u32 v114, v106, 1, v115
	ds_write_b16_d16_hi v114, v116
	v_add3_u32 v116, s74, v96, 10
	v_cmp_lt_i32_e64 s[20:21], s81, v116
	s_nop 1

; __device__ __forceinline__ float sigmf(float x) { return 1.f / (1.f + __expf(-x)); }
; __device__ __forceinline__ bf16r f2bf(float f) {
;   unsigned u = __float_as_uint(f);
;   u += 0x7fffu + ((u >> 16) & 1u);
;   return (bf16r)(u >> 16);
; }
; __device__ __forceinline__ void inproj_epilogue(const Params& p, int layer, int mt, int ntile, int tid,
;                                                 f32x16 (&acc)[2][2], unsigned char* smem) {
;     ...
;     acc_foreach(tid, acc, [&](int row, int col, float v) {
;       int t = m0 + row;
;       float o = v;
;       if (mode == 1) o = (t >= NPADR) ? v : 0.f;
;       if (mode == 2) o = sigmf(v);
;       sT[row * 136 + col] = f2bf(o);
;     });
.LBB0_4563:
	v_bfe_u32 v117, v116, 16, 1
	v_add3_u32 v117, v116, v117, s83
	v_add_u32_e32 v116, 0x110, v115
	v_lshl_add_u32 v115, v106, 1, v116
	ds_write_b16_d16_hi v115, v117
	v_add3_u32 v117, s74, v96, 11
	v_cmp_lt_i32_e64 s[22:23], s81, v117
	s_nop 1

; __device__ __forceinline__ float sigmf(float x) { return 1.f / (1.f + __expf(-x)); }
; __device__ __forceinline__ bf16r f2bf(float f) {
;   unsigned u = __float_as_uint(f);
;   u += 0x7fffu + ((u >> 16) & 1u);
;   return (bf16r)(u >> 16);
; }
; __device__ __forceinline__ void inproj_epilogue(const Params& p, int layer, int mt, int ntile, int tid,
;                                                 f32x16 (&acc)[2][2], unsigned char* smem) {
;     ...
;     acc_foreach(tid, acc, [&](int row, int col, float v) {
;       int t = m0 + row;
;       float o = v;
;       if (mode == 1) o = (t >= NPADR) ? v : 0.f;
;       if (mode == 2) o = sigmf(v);
;       sT[row * 136 + col] = f2bf(o);
;     });
.LBB0_4566:
	v_bfe_u32 v118, v117, 16, 1
	v_add_u32_e32 v116, 0x110, v116
	v_add3_u32 v118, v117, v118, s83
	v_lshl_add_u32 v117, v106, 1, v116
	ds_write_b16_d16_hi v117, v118
	v_add3_u32 v118, s74, v96, 16
	v_cmp_lt_i32_e64 s[24:25], s81, v118
	s_nop 1

; __device__ __forceinline__ float sigmf(float x) { return 1.f / (1.f + __expf(-x)); }
; __device__ __forceinline__ bf16r f2bf(float f) {
;   unsigned u = __float_as_uint(f);
;   u += 0x7fffu + ((u >> 16) & 1u);
;   return (bf16r)(u >> 16);
; }
; __device__ __forceinline__ void inproj_epilogue(const Params& p, int layer, int mt, int ntile, int tid,
;                                                 f32x16 (&acc)[2][2], unsigned char* smem) {
;     ...
;     acc_foreach(tid, acc, [&](int row, int col, float v) {
;       int t = m0 + row;
;       float o = v;
;       if (mode == 1) o = (t >= NPADR) ? v : 0.f;
;       if (mode == 2) o = sigmf(v);
;       sT[row * 136 + col] = f2bf(o);
;     });
.LBB0_4569:
	v_bfe_u32 v119, v118, 16, 1
	v_add_u32_e32 v116, 0x550, v116
	v_add3_u32 v119, v118, v119, s83
	v_lshl_add_u32 v118, v106, 1, v116
	ds_write_b16_d16_hi v118, v119
	v_add3_u32 v119, s74, v96, 17
	v_cmp_lt_i32_e64 s[26:27], s81, v119
	s_nop 1

; __device__ __forceinline__ float sigmf(float x) { return 1.f / (1.f + __expf(-x)); }
; __device__ __forceinline__ bf16r f2bf(float f) {
;   unsigned u = __float_as_uint(f);
;   u += 0x7fffu + ((u >> 16) & 1u);
;   return (bf16r)(u >> 16);
; }
; __device__ __forceinline__ void inproj_epilogue(const Params& p, int layer, int mt, int ntile, int tid,
;                                                 f32x16 (&acc)[2][2], unsigned char* smem) {
;     ...
;     acc_foreach(tid, acc, [&](int row, int col, float v) {
;       int t = m0 + row;
;       float o = v;
;       if (mode == 1) o = (t >= NPADR) ? v : 0.f;
;       if (mode == 2) o = sigmf(v);
;       sT[row * 136 + col] = f2bf(o);
;     });
.LBB0_4572:
	v_bfe_u32 v120, v119, 16, 1
	v_add_u32_e32 v116, 0x110, v116
	v_add3_u32 v120, v119, v120, s83
	v_lshl_add_u32 v119, v106, 1, v116
	ds_write_b16_d16_hi v119, v120
	v_add3_u32 v120, s74, v96, 18
	v_cmp_lt_i32_e64 s[28:29], s81, v120
	s_nop 1

; __device__ __forceinline__ float sigmf(float x) { return 1.f / (1.f + __expf(-x)); }
; __device__ __forceinline__ bf16r f2bf(float f) {
;   unsigned u = __float_as_uint(f);
;   u += 0x7fffu + ((u >> 16) & 1u);
;   return (bf16r)(u >> 16);
; }
; __device__ __forceinline__ void inproj_epilogue(const Params& p, int layer, int mt, int ntile, int tid,
;                                                 f32x16 (&acc)[2][2], unsigned char* smem) {
;     ...
;     acc_foreach(tid, acc, [&](int row, int col, float v) {
;       int t = m0 + row;
;       float o = v;
;       if (mode == 1) o = (t >= NPADR) ? v : 0.f;
;       if (mode == 2) o = sigmf(v);
;       sT[row * 136 + col] = f2bf(o);
;     });
.LBB0_4575:
	v_bfe_u32 v121, v120, 16, 1
	v_add_u32_e32 v116, 0x110, v116
	v_add3_u32 v121, v120, v121, s83
	v_lshl_add_u32 v120, v106, 1, v116
	ds_write_b16_d16_hi v120, v121
	v_add3_u32 v121, s74, v96, 19
	v_cmp_lt_i32_e64 s[30:31], s81, v121
	s_nop 1

; __device__ __forceinline__ float sigmf(float x) { return 1.f / (1.f + __expf(-x)); }
; __device__ __forceinline__ bf16r f2bf(float f) {
;   unsigned u = __float_as_uint(f);
;   u += 0x7fffu + ((u >> 16) & 1u);
;   return (bf16r)(u >> 16);
; }
; __device__ __forceinline__ void inproj_epilogue(const Params& p, int layer, int mt, int ntile, int tid,
;                                                 f32x16 (&acc)[2][2], unsigned char* smem) {
;     ...
;     acc_foreach(tid, acc, [&](int row, int col, float v) {
;       int t = m0 + row;
;       float o = v;
;       if (mode == 1) o = (t >= NPADR) ? v : 0.f;
;       if (mode == 2) o = sigmf(v);
;       sT[row * 136 + col] = f2bf(o);
;     });
.LBB0_4578:
	v_bfe_u32 v122, v121, 16, 1
	v_add_u32_e32 v116, 0x110, v116
	v_add3_u32 v122, v121, v122, s83
	v_lshl_add_u32 v121, v106, 1, v116
	ds_write_b16_d16_hi v121, v122
	v_add3_u32 v122, s74, v96, 24
	v_cmp_lt_i32_e64 s[34:35], s81, v122
	s_nop 1

; __device__ __forceinline__ float sigmf(float x) { return 1.f / (1.f + __expf(-x)); }
; __device__ __forceinline__ bf16r f2bf(float f) {
;   unsigned u = __float_as_uint(f);
;   u += 0x7fffu + ((u >> 16) & 1u);
;   return (bf16r)(u >> 16);
; }
; __device__ __forceinline__ void inproj_epilogue(const Params& p, int layer, int mt, int ntile, int tid,
;                                                 f32x16 (&acc)[2][2], unsigned char* smem) {
;     ...
;     acc_foreach(tid, acc, [&](int row, int col, float v) {
;       int t = m0 + row;
;       float o = v;
;       if (mode == 1) o = (t >= NPADR) ? v : 0.f;
;       if (mode == 2) o = sigmf(v);
;       sT[row * 136 + col] = f2bf(o);
;     });
.LBB0_4581:
	v_bfe_u32 v123, v122, 16, 1
	v_add_u32_e32 v116, 0x550, v116
	v_add3_u32 v123, v122, v123, s83
	v_lshl_add_u32 v122, v106, 1, v116
	ds_write_b16_d16_hi v122, v123
	v_add3_u32 v123, s74, v96, 25
	v_cmp_lt_i32_e64 s[36:37], s81, v123
	s_nop 1

; __device__ __forceinline__ float sigmf(float x) { return 1.f / (1.f + __expf(-x)); }
; __device__ __forceinline__ bf16r f2bf(float f) {
;   unsigned u = __float_as_uint(f);
;   u += 0x7fffu + ((u >> 16) & 1u);
;   return (bf16r)(u >> 16);
; }
; __device__ __forceinline__ void inproj_epilogue(const Params& p, int layer, int mt, int ntile, int tid,
;                                                 f32x16 (&acc)[2][2], unsigned char* smem) {
;     ...
;     acc_foreach(tid, acc, [&](int row, int col, float v) {
;       int t = m0 + row;
;       float o = v;
;       if (mode == 1) o = (t >= NPADR) ? v : 0.f;
;       if (mode == 2) o = sigmf(v);
;       sT[row * 136 + col] = f2bf(o);
;     });
.LBB0_4584:
	v_bfe_u32 v124, v123, 16, 1
	v_add_u32_e32 v116, 0x110, v116
	v_add3_u32 v124, v123, v124, s83
	v_lshl_add_u32 v123, v106, 1, v116
	ds_write_b16_d16_hi v123, v124
	v_add3_u32 v124, s74, v96, 26
	v_cmp_lt_i32_e64 s[38:39], s81, v124
	s_nop 1

; __device__ __forceinline__ float sigmf(float x) { return 1.f / (1.f + __expf(-x)); }
; __device__ __forceinline__ void inproj_epilogue(const Params& p, int layer, int mt, int ntile, int tid,
;                                                 f32x16 (&acc)[2][2], unsigned char* smem) {
;     ...
;     acc_foreach(tid, acc, [&](int row, int col, float v) {
;       int t = m0 + row;
;       float o = v;
;       if (mode == 1) o = (t >= NPADR) ? v : 0.f;
;       if (mode == 2) o = sigmf(v);
;       sT[row * 136 + col] = f2bf(o);
;     });
.LBB0_4587:
	v_bfe_u32 v125, v124, 16, 1
	v_add_u32_e32 v116, 0x110, v116
	v_add3_u32 v124, v124, v125, s83
	v_lshl_add_u32 v116, v106, 1, v116
	ds_write_b16_d16_hi v116, v124
	v_add3_u32 v124, s74, v96, 27
	v_cmp_lt_i32_e64 s[40:41], s81, v124
	s_nop 1

; __device__ __forceinline__ float sigmf(float x) { return 1.f / (1.f + __expf(-x)); }
; __device__ __forceinline__ void inproj_epilogue(const Params& p, int layer, int mt, int ntile, int tid,
;                                                 f32x16 (&acc)[2][2], unsigned char* smem) {
;     ...
;     acc_foreach(tid, acc, [&](int row, int col, float v) {
;       int t = m0 + row;
;       float o = v;
;       if (mode == 1) o = (t >= NPADR) ? v : 0.f;
;       if (mode == 2) o = sigmf(v);
;       sT[row * 136 + col] = f2bf(o);
;     });
.LBB0_4638:
	v_bfe_u32 v50, v48, 16, 1
	v_add_u32_e32 v49, 0x110, v116
	v_add3_u32 v48, v48, v50, s83
	ds_write_b16_d16_hi v49, v48 offset:64
	v_or_b32_e32 v48, 32, v96
	v_add_u32_e32 v49, s74, v48
	v_cmp_lt_i32_e64 s[8:9], s81, v49
	s_nop 1

; __device__ __forceinline__ float sigmf(float x) { return 1.f / (1.f + __expf(-x)); }
; __device__ __forceinline__ void inproj_epilogue(const Params& p, int layer, int mt, int ntile, int tid,
;                                                 f32x16 (&acc)[2][2], unsigned char* smem) {
;     ...
;     acc_foreach(tid, acc, [&](int row, int col, float v) {
;       int t = m0 + row;
;       float o = v;
;       if (mode == 1) o = (t >= NPADR) ? v : 0.f;
;       if (mode == 2) o = sigmf(v);
;       sT[row * 136 + col] = f2bf(o);
;     });
.LBB0_4641:
	v_bfe_u32 v50, v49, 16, 1
	v_add3_u32 v50, v49, v50, s83
	v_mul_lo_u32 v49, v48, s86
	v_lshl_add_u32 v48, v106, 1, v49
	ds_write_b16_d16_hi v48, v50
	v_add3_u32 v50, s74, v96, 33
	v_cmp_lt_i32_e64 s[10:11], s81, v50
	s_nop 1

; __device__ __forceinline__ float sigmf(float x) { return 1.f / (1.f + __expf(-x)); }
; __device__ __forceinline__ void inproj_epilogue(const Params& p, int layer, int mt, int ntile, int tid,
;                                                 f32x16 (&acc)[2][2], unsigned char* smem) {
;     ...
;     acc_foreach(tid, acc, [&](int row, int col, float v) {
;       int t = m0 + row;
;       float o = v;
;       if (mode == 1) o = (t >= NPADR) ? v : 0.f;
;       if (mode == 2) o = sigmf(v);
;       sT[row * 136 + col] = f2bf(o);
;     });
.LBB0_4644:
	v_bfe_u32 v51, v50, 16, 1
	v_add3_u32 v51, v50, v51, s83
	v_add_u32_e32 v50, 0x110, v49
	v_lshl_add_u32 v49, v106, 1, v50
	ds_write_b16_d16_hi v49, v51
	v_add3_u32 v51, s74, v96, 34
	v_cmp_lt_i32_e64 s[12:13], s81, v51
	s_nop 1

; __device__ __forceinline__ float sigmf(float x) { return 1.f / (1.f + __expf(-x)); }
; __device__ __forceinline__ void inproj_epilogue(const Params& p, int layer, int mt, int ntile, int tid,
;                                                 f32x16 (&acc)[2][2], unsigned char* smem) {
;     ...
;     acc_foreach(tid, acc, [&](int row, int col, float v) {
;       int t = m0 + row;
;       float o = v;
;       if (mode == 1) o = (t >= NPADR) ? v : 0.f;
;       if (mode == 2) o = sigmf(v);
;       sT[row * 136 + col] = f2bf(o);
;     });
.LBB0_4647:
	v_bfe_u32 v52, v51, 16, 1
	v_add3_u32 v52, v51, v52, s83
	v_add_u32_e32 v51, 0x110, v50
	v_lshl_add_u32 v50, v106, 1, v51
	ds_write_b16_d16_hi v50, v52
	v_add3_u32 v52, s74, v96, 35
	v_cmp_lt_i32_e64 s[14:15], s81, v52
	s_nop 1

; __device__ __forceinline__ float sigmf(float x) { return 1.f / (1.f + __expf(-x)); }
; __device__ __forceinline__ void inproj_epilogue(const Params& p, int layer, int mt, int ntile, int tid,
;                                                 f32x16 (&acc)[2][2], unsigned char* smem) {
;     ...
;     acc_foreach(tid, acc, [&](int row, int col, float v) {
;       int t = m0 + row;
;       float o = v;
;       if (mode == 1) o = (t >= NPADR) ? v : 0.f;
;       if (mode == 2) o = sigmf(v);
;       sT[row * 136 + col] = f2bf(o);
;     });
.LBB0_4650:
	v_bfe_u32 v53, v52, 16, 1
	v_add3_u32 v53, v52, v53, s83
	v_add_u32_e32 v52, 0x110, v51
	v_lshl_add_u32 v51, v106, 1, v52
	ds_write_b16_d16_hi v51, v53
	v_add3_u32 v53, s74, v96, 40
	v_cmp_lt_i32_e64 s[16:17], s81, v53
	s_nop 1

; __device__ __forceinline__ float sigmf(float x) { return 1.f / (1.f + __expf(-x)); }
; __device__ __forceinline__ void inproj_epilogue(const Params& p, int layer, int mt, int ntile, int tid,
;                                                 f32x16 (&acc)[2][2], unsigned char* smem) {
;     ...
;     acc_foreach(tid, acc, [&](int row, int col, float v) {
;       int t = m0 + row;
;       float o = v;
;       if (mode == 1) o = (t >= NPADR) ? v : 0.f;
;       if (mode == 2) o = sigmf(v);
;       sT[row * 136 + col] = f2bf(o);
;     });
.LBB0_4653:
	v_bfe_u32 v54, v53, 16, 1
	v_add3_u32 v54, v53, v54, s83
	v_add_u32_e32 v53, 0x550, v52
	v_lshl_add_u32 v52, v106, 1, v53
	ds_write_b16_d16_hi v52, v54
	v_add3_u32 v54, s74, v96, 41
	v_cmp_lt_i32_e64 s[18:19], s81, v54
	s_nop 1

; __device__ __forceinline__ float sigmf(float x) { return 1.f / (1.f + __expf(-x)); }
; __device__ __forceinline__ void inproj_epilogue(const Params& p, int layer, int mt, int ntile, int tid,
;                                                 f32x16 (&acc)[2][2], unsigned char* smem) {
;     ...
;     acc_foreach(tid, acc, [&](int row, int col, float v) {
;       int t = m0 + row;
;       float o = v;
;       if (mode == 1) o = (t >= NPADR) ? v : 0.f;
;       if (mode == 2) o = sigmf(v);
;       sT[row * 136 + col] = f2bf(o);
;     });
.LBB0_4656:
	v_bfe_u32 v55, v54, 16, 1
	v_add3_u32 v55, v54, v55, s83
	v_add_u32_e32 v54, 0x110, v53
	v_lshl_add_u32 v53, v106, 1, v54
	ds_write_b16_d16_hi v53, v55
	v_add3_u32 v55, s74, v96, 42
	v_cmp_lt_i32_e64 s[20:21], s81, v55
	s_nop 1

; __device__ __forceinline__ float sigmf(float x) { return 1.f / (1.f + __expf(-x)); }
; __device__ __forceinline__ void inproj_epilogue(const Params& p, int layer, int mt, int ntile, int tid,
;                                                 f32x16 (&acc)[2][2], unsigned char* smem) {
;     ...
;     acc_foreach(tid, acc, [&](int row, int col, float v) {
;       int t = m0 + row;
;       float o = v;
;       if (mode == 1) o = (t >= NPADR) ? v : 0.f;
;       if (mode == 2) o = sigmf(v);
;       sT[row * 136 + col] = f2bf(o);
;     });
.LBB0_4659:
	v_bfe_u32 v56, v55, 16, 1
	v_add3_u32 v56, v55, v56, s83
	v_add_u32_e32 v55, 0x110, v54
	v_lshl_add_u32 v54, v106, 1, v55
	ds_write_b16_d16_hi v54, v56
	v_add3_u32 v56, s74, v96, 43
	v_cmp_lt_i32_e64 s[22:23], s81, v56
	s_nop 1

; __device__ __forceinline__ float sigmf(float x) { return 1.f / (1.f + __expf(-x)); }
; __device__ __forceinline__ void inproj_epilogue(const Params& p, int layer, int mt, int ntile, int tid,
;                                                 f32x16 (&acc)[2][2], unsigned char* smem) {
;     ...
;     acc_foreach(tid, acc, [&](int row, int col, float v) {
;       int t = m0 + row;
;       float o = v;
;       if (mode == 1) o = (t >= NPADR) ? v : 0.f;
;       if (mode == 2) o = sigmf(v);
;       sT[row * 136 + col] = f2bf(o);
;     });
.LBB0_4662:
	v_bfe_u32 v57, v56, 16, 1
	v_add_u32_e32 v55, 0x110, v55
	v_add3_u32 v57, v56, v57, s83
	v_lshl_add_u32 v56, v106, 1, v55
	ds_write_b16_d16_hi v56, v57
	v_add3_u32 v57, s74, v96, 48
	v_cmp_lt_i32_e64 s[24:25], s81, v57
	s_nop 1

; __device__ __forceinline__ float sigmf(float x) { return 1.f / (1.f + __expf(-x)); }
; __device__ __forceinline__ void inproj_epilogue(const Params& p, int layer, int mt, int ntile, int tid,
;                                                 f32x16 (&acc)[2][2], unsigned char* smem) {
;     ...
;     acc_foreach(tid, acc, [&](int row, int col, float v) {
;       int t = m0 + row;
;       float o = v;
;       if (mode == 1) o = (t >= NPADR) ? v : 0.f;
;       if (mode == 2) o = sigmf(v);
;       sT[row * 136 + col] = f2bf(o);
;     });
.LBB0_4665:
	v_bfe_u32 v58, v57, 16, 1
	v_add_u32_e32 v55, 0x550, v55
	v_add3_u32 v58, v57, v58, s83
	v_lshl_add_u32 v57, v106, 1, v55
	ds_write_b16_d16_hi v57, v58
	v_add3_u32 v58, s74, v96, 49
	v_cmp_lt_i32_e64 s[26:27], s81, v58
	s_nop 1

; __device__ __forceinline__ float sigmf(float x) { return 1.f / (1.f + __expf(-x)); }
; __device__ __forceinline__ void inproj_epilogue(const Params& p, int layer, int mt, int ntile, int tid,
;                                                 f32x16 (&acc)[2][2], unsigned char* smem) {
;     ...
;     acc_foreach(tid, acc, [&](int row, int col, float v) {
;       int t = m0 + row;
;       float o = v;
;       if (mode == 1) o = (t >= NPADR) ? v : 0.f;
;       if (mode == 2) o = sigmf(v);
;       sT[row * 136 + col] = f2bf(o);
;     });
.LBB0_4668:
	v_bfe_u32 v59, v58, 16, 1
	v_add_u32_e32 v55, 0x110, v55
	v_add3_u32 v59, v58, v59, s83
	v_lshl_add_u32 v58, v106, 1, v55
	ds_write_b16_d16_hi v58, v59
	v_add3_u32 v59, s74, v96, 50
	v_cmp_lt_i32_e64 s[28:29], s81, v59
	s_nop 1

; __device__ __forceinline__ float sigmf(float x) { return 1.f / (1.f + __expf(-x)); }
; __device__ __forceinline__ void inproj_epilogue(const Params& p, int layer, int mt, int ntile, int tid,
;                                                 f32x16 (&acc)[2][2], unsigned char* smem) {
;     ...
;     acc_foreach(tid, acc, [&](int row, int col, float v) {
;       int t = m0 + row;
;       float o = v;
;       if (mode == 1) o = (t >= NPADR) ? v : 0.f;
;       if (mode == 2) o = sigmf(v);
;       sT[row * 136 + col] = f2bf(o);
;     });
.LBB0_4671:
	v_bfe_u32 v60, v59, 16, 1
	v_add_u32_e32 v55, 0x110, v55
	v_add3_u32 v60, v59, v60, s83
	v_lshl_add_u32 v59, v106, 1, v55
	ds_write_b16_d16_hi v59, v60
	v_add3_u32 v60, s74, v96, 51
	v_cmp_lt_i32_e64 s[30:31], s81, v60
	s_nop 1

; __device__ __forceinline__ float sigmf(float x) { return 1.f / (1.f + __expf(-x)); }
; __device__ __forceinline__ void inproj_epilogue(const Params& p, int layer, int mt, int ntile, int tid,
;                                                 f32x16 (&acc)[2][2], unsigned char* smem) {
;     ...
;     acc_foreach(tid, acc, [&](int row, int col, float v) {
;       int t = m0 + row;
;       float o = v;
;       if (mode == 1) o = (t >= NPADR) ? v : 0.f;
;       if (mode == 2) o = sigmf(v);
;       sT[row * 136 + col] = f2bf(o);
;     });
.LBB0_4674:
	v_bfe_u32 v61, v60, 16, 1
	v_add_u32_e32 v55, 0x110, v55
	v_add3_u32 v61, v60, v61, s83
	v_lshl_add_u32 v60, v106, 1, v55
	ds_write_b16_d16_hi v60, v61
	v_add3_u32 v61, s74, v96, 56
	v_cmp_lt_i32_e64 s[34:35], s81, v61
	s_nop 1

; __device__ __forceinline__ float sigmf(float x) { return 1.f / (1.f + __expf(-x)); }
; __device__ __forceinline__ void inproj_epilogue(const Params& p, int layer, int mt, int ntile, int tid,
;                                                 f32x16 (&acc)[2][2], unsigned char* smem) {
;     ...
;     acc_foreach(tid, acc, [&](int row, int col, float v) {
;       int t = m0 + row;
;       float o = v;
;       if (mode == 1) o = (t >= NPADR) ? v : 0.f;
;       if (mode == 2) o = sigmf(v);
;       sT[row * 136 + col] = f2bf(o);
;     });
.LBB0_4677:
	v_bfe_u32 v62, v61, 16, 1
	v_add_u32_e32 v55, 0x550, v55
	v_add3_u32 v62, v61, v62, s83
	v_lshl_add_u32 v61, v106, 1, v55
	ds_write_b16_d16_hi v61, v62
	v_add3_u32 v62, s74, v96, 57
	v_cmp_lt_i32_e64 s[36:37], s81, v62
	s_nop 1

; __device__ __forceinline__ float sigmf(float x) { return 1.f / (1.f + __expf(-x)); }
; __device__ __forceinline__ void inproj_epilogue(const Params& p, int layer, int mt, int ntile, int tid,
;                                                 f32x16 (&acc)[2][2], unsigned char* smem) {
;     ...
;     acc_foreach(tid, acc, [&](int row, int col, float v) {
;       int t = m0 + row;
;       float o = v;
;       if (mode == 1) o = (t >= NPADR) ? v : 0.f;
;       if (mode == 2) o = sigmf(v);
;       sT[row * 136 + col] = f2bf(o);
;     });
.LBB0_4680:
	v_bfe_u32 v63, v62, 16, 1
	v_add_u32_e32 v55, 0x110, v55
	v_add3_u32 v63, v62, v63, s83
	v_lshl_add_u32 v62, v106, 1, v55
	ds_write_b16_d16_hi v62, v63
	v_add3_u32 v63, s74, v96, 58
	v_cmp_lt_i32_e64 s[38:39], s81, v63
	s_nop 1

; __device__ __forceinline__ float sigmf(float x) { return 1.f / (1.f + __expf(-x)); }
; __device__ __forceinline__ void inproj_epilogue(const Params& p, int layer, int mt, int ntile, int tid,
;                                                 f32x16 (&acc)[2][2], unsigned char* smem) {
;     ...
;     acc_foreach(tid, acc, [&](int row, int col, float v) {
;       int t = m0 + row;
;       float o = v;
;       if (mode == 1) o = (t >= NPADR) ? v : 0.f;
;       if (mode == 2) o = sigmf(v);
;       sT[row * 136 + col] = f2bf(o);
;     });
.LBB0_4683:
	v_bfe_u32 v107, v63, 16, 1
	v_add_u32_e32 v55, 0x110, v55
	v_add3_u32 v63, v63, v107, s83
	v_lshl_add_u32 v55, v106, 1, v55
	ds_write_b16_d16_hi v55, v63
	v_add3_u32 v63, s74, v96, 59
	v_cmp_lt_i32_e64 s[40:41], s81, v63
	s_nop 1

; __device__ __forceinline__ bf16r f2bf(float f) {
;   unsigned u = __float_as_uint(f);
;   u += 0x7fffu + ((u >> 16) & 1u);
;   return (bf16r)(u >> 16);
; }
; __device__ __forceinline__ unsigned pack2(float a, float b) { return (unsigned)f2bf(a) | ((unsigned)f2bf(b) << 16); }
; __device__ __forceinline__ float lo16(unsigned v) { return __uint_as_float(v << 16); }
; __device__ __forceinline__ float hi16(unsigned v) { return __uint_as_float(v & 0xffff0000u); }
; __device__ __forceinline__ float siluf(float x) { return x / (1.f + __expf(-x)); }
; __device__ __forceinline__ float sigmf(float x) { return 1.f / (1.f + __expf(-x)); }
; __device__ __forceinline__ void inproj_epilogue(const Params& p, int layer, int mt, int ntile, int tid,
;                                                 f32x16 (&acc)[2][2], unsigned char* smem) {
;     ...
;     acc_foreach(tid, acc, [&](int row, int col, float v) {
;       int t = m0 + row;
;       float o = v;
;       if (mode == 1) o = (t >= NPADR) ? v : 0.f;
;       if (mode == 2) o = sigmf(v);
;       sT[row * 136 + col] = f2bf(o);
;     });
.Lgv_9:
	v_mul_f32_e32 v107, 0xbfb8aa3b, v16
	v_exp_f32_e32 v107, v107
	s_nop 0
	v_add_f32_e32 v107, 1.0, v107
	v_div_scale_f32 v110, s[6:7], v107, v107, 1.0
	v_rcp_f32_e32 v111, v110
	v_div_scale_f32 v112, vcc, 1.0, v107, 1.0
	v_fma_f32 v113, -v110, v111, 1.0
	v_fmac_f32_e32 v111, v113, v111
	v_mul_f32_e32 v113, v112, v111
	v_fma_f32 v114, -v110, v113, v112
	v_fmac_f32_e32 v113, v114, v111
	v_fma_f32 v110, -v110, v113, v112
	v_div_fmas_f32 v110, v110, v111, v113
	v_div_fixup_f32 v107, v110, v107, 1.0
	v_bfe_u32 v110, v107, 16, 1
	v_and_b32_e32 v106, 0x5f, v106
	v_add3_u32 v111, v107, v110, s83
	v_mul_lo_u32 v110, v96, s86
	v_lshl_add_u32 v107, v106, 1, v110
	ds_write_b16_d16_hi v107, v111
	v_add3_u32 v111, s74, v96, 1
	v_cndmask_b32_e64 v112, 0, 1, s[10:11]
	v_cmp_ne_u32_e64 s[6:7], 1, v112
	s_andn2_b64 vcc, exec, s[10:11]
	v_cmp_lt_i32_e64 s[10:11], s81, v111
	v_mul_f32_e32 v111, 0xbfb8aa3b, v17
	v_exp_f32_e32 v111, v111
	s_nop 0
	v_add_f32_e32 v111, 1.0, v111
	v_div_scale_f32 v112, s[12:13], v111, v111, 1.0
	v_rcp_f32_e32 v113, v112
	v_div_scale_f32 v114, vcc, 1.0, v111, 1.0
	v_fma_f32 v115, -v112, v113, 1.0
	v_fmac_f32_e32 v113, v115, v113
	v_mul_f32_e32 v115, v114, v113
	v_fma_f32 v116, -v112, v115, v114
	v_fmac_f32_e32 v115, v116, v113
	v_fma_f32 v112, -v112, v115, v114
	v_div_fmas_f32 v112, v112, v113, v115
	v_div_fixup_f32 v111, v112, v111, 1.0
	v_bfe_u32 v112, v111, 16, 1
	v_add3_u32 v112, v111, v112, s83
	v_add_u32_e32 v111, 0x110, v110
	v_lshl_add_u32 v110, v106, 1, v111
	ds_write_b16_d16_hi v110, v112
	v_add3_u32 v112, s74, v96, 2
	s_and_b64 vcc, exec, s[6:7]
	v_cmp_lt_i32_e64 s[12:13], s81, v112
	v_mul_f32_e32 v112, 0xbfb8aa3b, v18
	v_exp_f32_e32 v112, v112
	s_nop 0
	v_add_f32_e32 v112, 1.0, v112
	v_div_scale_f32 v113, s[14:15], v112, v112, 1.0
	v_rcp_f32_e32 v114, v113
	v_div_scale_f32 v115, vcc, 1.0, v112, 1.0
	v_fma_f32 v116, -v113, v114, 1.0
	v_fmac_f32_e32 v114, v116, v114
	v_mul_f32_e32 v116, v115, v114
	v_fma_f32 v117, -v113, v116, v115
	v_fmac_f32_e32 v116, v117, v114
	v_fma_f32 v113, -v113, v116, v115
	v_div_fmas_f32 v113, v113, v114, v116
	v_div_fixup_f32 v112, v113, v112, 1.0
	v_bfe_u32 v113, v112, 16, 1
	v_add3_u32 v113, v112, v113, s83
	v_add_u32_e32 v112, 0x110, v111
	v_lshl_add_u32 v111, v106, 1, v112
	ds_write_b16_d16_hi v111, v113
	v_add3_u32 v113, s74, v96, 3
	s_and_b64 vcc, exec, s[6:7]
	v_cmp_lt_i32_e64 s[14:15], s81, v113
	v_mul_f32_e32 v113, 0xbfb8aa3b, v19
	v_exp_f32_e32 v113, v113
	s_nop 0
	v_add_f32_e32 v113, 1.0, v113
	v_div_scale_f32 v114, s[16:17], v113, v113, 1.0
	v_rcp_f32_e32 v115, v114
	v_div_scale_f32 v116, vcc, 1.0, v113, 1.0
	v_fma_f32 v117, -v114, v115, 1.0
	v_fmac_f32_e32 v115, v117, v115
	v_mul_f32_e32 v117, v116, v115
	v_fma_f32 v118, -v114, v117, v116
	v_fmac_f32_e32 v117, v118, v115
	v_fma_f32 v114, -v114, v117, v116
	v_div_fmas_f32 v114, v114, v115, v117
	v_div_fixup_f32 v113, v114, v113, 1.0
	v_bfe_u32 v114, v113, 16, 1
	v_add3_u32 v114, v113, v114, s83
	v_add_u32_e32 v113, 0x110, v112
	v_lshl_add_u32 v112, v106, 1, v113
	ds_write_b16_d16_hi v112, v114
	v_add3_u32 v114, s74, v96, 8
	s_and_b64 vcc, exec, s[6:7]
	v_cmp_lt_i32_e64 s[16:17], s81, v114
	v_mul_f32_e32 v114, 0xbfb8aa3b, v20
	v_exp_f32_e32 v114, v114
	s_nop 0
	v_add_f32_e32 v114, 1.0, v114
	v_div_scale_f32 v115, s[18:19], v114, v114, 1.0
	v_rcp_f32_e32 v116, v115
	v_div_scale_f32 v117, vcc, 1.0, v114, 1.0
	v_fma_f32 v118, -v115, v116, 1.0
	v_fmac_f32_e32 v116, v118, v116
	v_mul_f32_e32 v118, v117, v116
	v_fma_f32 v119, -v115, v118, v117
	v_fmac_f32_e32 v118, v119, v116
	v_fma_f32 v115, -v115, v118, v117
	v_div_fmas_f32 v115, v115, v116, v118
	v_div_fixup_f32 v114, v115, v114, 1.0
	v_bfe_u32 v115, v114, 16, 1
	v_add3_u32 v115, v114, v115, s83
	v_add_u32_e32 v114, 0x550, v113
	v_lshl_add_u32 v113, v106, 1, v114
	ds_write_b16_d16_hi v113, v115
	v_add3_u32 v115, s74, v96, 9
	s_and_b64 vcc, exec, s[6:7]
	v_cmp_lt_i32_e64 s[18:19], s81, v115
	v_mul_f32_e32 v115, 0xbfb8aa3b, v21
	v_exp_f32_e32 v115, v115
	s_nop 0
	v_add_f32_e32 v115, 1.0, v115
	v_div_scale_f32 v116, s[20:21], v115, v115, 1.0
	v_rcp_f32_e32 v117, v116
	v_div_scale_f32 v118, vcc, 1.0, v115, 1.0
	v_fma_f32 v119, -v116, v117, 1.0
	v_fmac_f32_e32 v117, v119, v117
	v_mul_f32_e32 v119, v118, v117
	v_fma_f32 v120, -v116, v119, v118
	v_fmac_f32_e32 v119, v120, v117
	v_fma_f32 v116, -v116, v119, v118
	v_div_fmas_f32 v116, v116, v117, v119
	v_div_fixup_f32 v115, v116, v115, 1.0
	v_bfe_u32 v116, v115, 16, 1
	v_add3_u32 v116, v115, v116, s83
	v_add_u32_e32 v115, 0x110, v114
	v_lshl_add_u32 v114, v106, 1, v115
	ds_write_b16_d16_hi v114, v116
	v_add3_u32 v116, s74, v96, 10
	s_and_b64 vcc, exec, s[6:7]
	v_cmp_lt_i32_e64 s[20:21], s81, v116
	v_mul_f32_e32 v116, 0xbfb8aa3b, v22
	v_exp_f32_e32 v116, v116
	s_nop 0
	v_add_f32_e32 v116, 1.0, v116
	v_div_scale_f32 v117, s[22:23], v116, v116, 1.0
	v_rcp_f32_e32 v118, v117
	v_div_scale_f32 v119, vcc, 1.0, v116, 1.0
	v_fma_f32 v120, -v117, v118, 1.0
	v_fmac_f32_e32 v118, v120, v118
	v_mul_f32_e32 v120, v119, v118
	v_fma_f32 v121, -v117, v120, v119
	v_fmac_f32_e32 v120, v121, v118
	v_fma_f32 v117, -v117, v120, v119
	v_div_fmas_f32 v117, v117, v118, v120
	v_div_fixup_f32 v116, v117, v116, 1.0
	v_bfe_u32 v117, v116, 16, 1
	v_add3_u32 v117, v116, v117, s83
	v_add_u32_e32 v116, 0x110, v115
	v_lshl_add_u32 v115, v106, 1, v116
	ds_write_b16_d16_hi v115, v117
	v_add3_u32 v117, s74, v96, 11
	s_and_b64 vcc, exec, s[6:7]
	v_cmp_lt_i32_e64 s[22:23], s81, v117
	v_mul_f32_e32 v117, 0xbfb8aa3b, v23
	v_exp_f32_e32 v117, v117
	s_nop 0
	v_add_f32_e32 v117, 1.0, v117
	v_div_scale_f32 v118, s[24:25], v117, v117, 1.0
	v_rcp_f32_e32 v119, v118
; __device__ __forceinline__ bf16r f2bf(float f) {
;   unsigned u = __float_as_uint(f);
;   u += 0x7fffu + ((u >> 16) & 1u);
;   return (bf16r)(u >> 16);
; }
; __device__ __forceinline__ unsigned pack2(float a, float b) { return (unsigned)f2bf(a) | ((unsigned)f2bf(b) << 16); }
; __device__ __forceinline__ float lo16(unsigned v) { return __uint_as_float(v << 16); }
; __device__ __forceinline__ float hi16(unsigned v) { return __uint_as_float(v & 0xffff0000u); }
; __device__ __forceinline__ float siluf(float x) { return x / (1.f + __expf(-x)); }
; __device__ __forceinline__ float sigmf(float x) { return 1.f / (1.f + __expf(-x)); }
; __device__ __forceinline__ void inproj_epilogue(const Params& p, int layer, int mt, int ntile, int tid,
;                                                 f32x16 (&acc)[2][2], unsigned char* smem) {
;     ...
;     acc_foreach(tid, acc, [&](int row, int col, float v) {
;       int t = m0 + row;
;       float o = v;
;       if (mode == 1) o = (t >= NPADR) ? v : 0.f;
;       if (mode == 2) o = sigmf(v);
;       sT[row * 136 + col] = f2bf(o);
;     });
	v_div_scale_f32 v120, vcc, 1.0, v117, 1.0
	v_fma_f32 v121, -v118, v119, 1.0
	v_fmac_f32_e32 v119, v121, v119
	v_mul_f32_e32 v121, v120, v119
	v_fma_f32 v122, -v118, v121, v120
	v_fmac_f32_e32 v121, v122, v119
	v_fma_f32 v118, -v118, v121, v120
	v_div_fmas_f32 v118, v118, v119, v121
	v_div_fixup_f32 v117, v118, v117, 1.0
	v_bfe_u32 v118, v117, 16, 1
	v_add_u32_e32 v116, 0x110, v116
	v_add3_u32 v118, v117, v118, s83
	v_lshl_add_u32 v117, v106, 1, v116
	ds_write_b16_d16_hi v117, v118
	v_add3_u32 v118, s74, v96, 16
	s_and_b64 vcc, exec, s[6:7]
	v_cmp_lt_i32_e64 s[24:25], s81, v118
	v_mul_f32_e32 v118, 0xbfb8aa3b, v24
	v_exp_f32_e32 v118, v118
	s_nop 0
	v_add_f32_e32 v118, 1.0, v118
	v_div_scale_f32 v119, s[26:27], v118, v118, 1.0
	v_rcp_f32_e32 v120, v119
	v_div_scale_f32 v121, vcc, 1.0, v118, 1.0
	v_fma_f32 v122, -v119, v120, 1.0
	v_fmac_f32_e32 v120, v122, v120
	v_mul_f32_e32 v122, v121, v120
	v_fma_f32 v123, -v119, v122, v121
	v_fmac_f32_e32 v122, v123, v120
	v_fma_f32 v119, -v119, v122, v121
	v_div_fmas_f32 v119, v119, v120, v122
	v_div_fixup_f32 v118, v119, v118, 1.0
	v_bfe_u32 v119, v118, 16, 1
	v_add_u32_e32 v116, 0x550, v116
	v_add3_u32 v119, v118, v119, s83
	v_lshl_add_u32 v118, v106, 1, v116
	ds_write_b16_d16_hi v118, v119
	v_add3_u32 v119, s74, v96, 17
	s_and_b64 vcc, exec, s[6:7]
	v_cmp_lt_i32_e64 s[26:27], s81, v119
	v_mul_f32_e32 v119, 0xbfb8aa3b, v25
	v_exp_f32_e32 v119, v119
	s_nop 0
	v_add_f32_e32 v119, 1.0, v119
	v_div_scale_f32 v120, s[28:29], v119, v119, 1.0
	v_rcp_f32_e32 v121, v120
	v_div_scale_f32 v122, vcc, 1.0, v119, 1.0
	v_fma_f32 v123, -v120, v121, 1.0
	v_fmac_f32_e32 v121, v123, v121
	v_mul_f32_e32 v123, v122, v121
	v_fma_f32 v124, -v120, v123, v122
	v_fmac_f32_e32 v123, v124, v121
	v_fma_f32 v120, -v120, v123, v122
	v_div_fmas_f32 v120, v120, v121, v123
	v_div_fixup_f32 v119, v120, v119, 1.0
	v_bfe_u32 v120, v119, 16, 1
	v_add_u32_e32 v116, 0x110, v116
	v_add3_u32 v120, v119, v120, s83
	v_lshl_add_u32 v119, v106, 1, v116
	ds_write_b16_d16_hi v119, v120
	v_add3_u32 v120, s74, v96, 18
	s_and_b64 vcc, exec, s[6:7]
	v_cmp_lt_i32_e64 s[28:29], s81, v120
	v_mul_f32_e32 v120, 0xbfb8aa3b, v26
	v_exp_f32_e32 v120, v120
	s_nop 0
	v_add_f32_e32 v120, 1.0, v120
	v_div_scale_f32 v121, s[30:31], v120, v120, 1.0
	v_rcp_f32_e32 v122, v121
	v_div_scale_f32 v123, vcc, 1.0, v120, 1.0
	v_fma_f32 v124, -v121, v122, 1.0
	v_fmac_f32_e32 v122, v124, v122
	v_mul_f32_e32 v124, v123, v122
	v_fma_f32 v125, -v121, v124, v123
	v_fmac_f32_e32 v124, v125, v122
	v_fma_f32 v121, -v121, v124, v123
	v_div_fmas_f32 v121, v121, v122, v124
	v_div_fixup_f32 v120, v121, v120, 1.0
	v_bfe_u32 v121, v120, 16, 1
	v_add_u32_e32 v116, 0x110, v116
	v_add3_u32 v121, v120, v121, s83
	v_lshl_add_u32 v120, v106, 1, v116
	ds_write_b16_d16_hi v120, v121
	v_add3_u32 v121, s74, v96, 19
	s_and_b64 vcc, exec, s[6:7]
	v_cmp_lt_i32_e64 s[30:31], s81, v121
	v_mul_f32_e32 v121, 0xbfb8aa3b, v27
	v_exp_f32_e32 v121, v121
	s_nop 0
	v_add_f32_e32 v121, 1.0, v121
	v_div_scale_f32 v122, s[34:35], v121, v121, 1.0
	v_rcp_f32_e32 v123, v122
	v_div_scale_f32 v124, vcc, 1.0, v121, 1.0
	v_fma_f32 v125, -v122, v123, 1.0
	v_fmac_f32_e32 v123, v125, v123
	v_mul_f32_e32 v125, v124, v123
	v_fma_f32 v126, -v122, v125, v124
	v_fmac_f32_e32 v125, v126, v123
	v_fma_f32 v122, -v122, v125, v124
	v_div_fmas_f32 v122, v122, v123, v125
	v_div_fixup_f32 v121, v122, v121, 1.0
	v_bfe_u32 v122, v121, 16, 1
	v_add_u32_e32 v116, 0x110, v116
	v_add3_u32 v122, v121, v122, s83
	v_lshl_add_u32 v121, v106, 1, v116
	ds_write_b16_d16_hi v121, v122
	v_add3_u32 v122, s74, v96, 24
	s_and_b64 vcc, exec, s[6:7]
	v_cmp_lt_i32_e64 s[34:35], s81, v122
	v_mul_f32_e32 v122, 0xbfb8aa3b, v28
	v_exp_f32_e32 v122, v122
	s_nop 0
	v_add_f32_e32 v122, 1.0, v122
	v_div_scale_f32 v123, s[36:37], v122, v122, 1.0
	v_rcp_f32_e32 v124, v123
	v_div_scale_f32 v125, vcc, 1.0, v122, 1.0
	v_fma_f32 v126, -v123, v124, 1.0
	v_fmac_f32_e32 v124, v126, v124
	v_mul_f32_e32 v126, v125, v124
	v_fma_f32 v127, -v123, v126, v125
	v_fmac_f32_e32 v126, v127, v124
	v_fma_f32 v123, -v123, v126, v125
	v_div_fmas_f32 v123, v123, v124, v126
	v_div_fixup_f32 v122, v123, v122, 1.0
	v_bfe_u32 v123, v122, 16, 1
	v_add_u32_e32 v116, 0x550, v116
	v_add3_u32 v123, v122, v123, s83
	v_lshl_add_u32 v122, v106, 1, v116
	ds_write_b16_d16_hi v122, v123
	v_add3_u32 v123, s74, v96, 25
	s_and_b64 vcc, exec, s[6:7]
	v_cmp_lt_i32_e64 s[36:37], s81, v123
	v_mul_f32_e32 v123, 0xbfb8aa3b, v29
	v_exp_f32_e32 v123, v123
	s_nop 0
	v_add_f32_e32 v123, 1.0, v123
	v_div_scale_f32 v124, s[38:39], v123, v123, 1.0
	v_rcp_f32_e32 v125, v124
	v_div_scale_f32 v126, vcc, 1.0, v123, 1.0
	v_fma_f32 v127, -v124, v125, 1.0
	v_fmac_f32_e32 v125, v127, v125
	v_mul_f32_e32 v127, v126, v125
	v_fma_f32 v128, -v124, v127, v126
	v_fmac_f32_e32 v127, v128, v125
	v_fma_f32 v124, -v124, v127, v126
	v_div_fmas_f32 v124, v124, v125, v127
	v_div_fixup_f32 v123, v124, v123, 1.0
	v_bfe_u32 v124, v123, 16, 1
	v_add_u32_e32 v116, 0x110, v116
	v_add3_u32 v124, v123, v124, s83
	v_lshl_add_u32 v123, v106, 1, v116
	ds_write_b16_d16_hi v123, v124
	v_add3_u32 v124, s74, v96, 26
	s_and_b64 vcc, exec, s[6:7]
	v_cmp_lt_i32_e64 s[38:39], s81, v124
	v_mul_f32_e32 v124, 0xbfb8aa3b, v30
	v_exp_f32_e32 v124, v124
	s_nop 0
	v_add_f32_e32 v124, 1.0, v124
	v_div_scale_f32 v125, s[40:41], v124, v124, 1.0
	v_rcp_f32_e32 v126, v125
	v_div_scale_f32 v127, vcc, 1.0, v124, 1.0
	v_fma_f32 v128, -v125, v126, 1.0
	v_fmac_f32_e32 v126, v128, v126
	v_mul_f32_e32 v128, v127, v126
	v_fma_f32 v129, -v125, v128, v127
	v_fmac_f32_e32 v128, v129, v126
	v_fma_f32 v125, -v125, v128, v127
	v_div_fmas_f32 v125, v125, v126, v128
; __device__ __forceinline__ bf16r f2bf(float f) {
;   unsigned u = __float_as_uint(f);
;   u += 0x7fffu + ((u >> 16) & 1u);
;   return (bf16r)(u >> 16);
; }
; __device__ __forceinline__ unsigned pack2(float a, float b) { return (unsigned)f2bf(a) | ((unsigned)f2bf(b) << 16); }
; __device__ __forceinline__ float lo16(unsigned v) { return __uint_as_float(v << 16); }
; __device__ __forceinline__ float hi16(unsigned v) { return __uint_as_float(v & 0xffff0000u); }
; __device__ __forceinline__ float siluf(float x) { return x / (1.f + __expf(-x)); }
; __device__ __forceinline__ float sigmf(float x) { return 1.f / (1.f + __expf(-x)); }
; __device__ __forceinline__ void inproj_epilogue(const Params& p, int layer, int mt, int ntile, int tid,
;                                                 f32x16 (&acc)[2][2], unsigned char* smem) {
;     ...
;     acc_foreach(tid, acc, [&](int row, int col, float v) {
;       int t = m0 + row;
;       float o = v;
;       if (mode == 1) o = (t >= NPADR) ? v : 0.f;
;       if (mode == 2) o = sigmf(v);
;       sT[row * 136 + col] = f2bf(o);
;     });
	v_div_fixup_f32 v124, v125, v124, 1.0
	v_bfe_u32 v125, v124, 16, 1
	v_add_u32_e32 v116, 0x110, v116
	v_add3_u32 v124, v124, v125, s83
	v_lshl_add_u32 v116, v106, 1, v116
	ds_write_b16_d16_hi v116, v124
	v_add3_u32 v124, s74, v96, 27
	s_and_b64 vcc, exec, s[6:7]
	v_cmp_lt_i32_e64 s[40:41], s81, v124
	v_mul_f32_e32 v124, 0xbfb8aa3b, v31
	v_exp_f32_e32 v124, v124
	s_nop 0
	v_add_f32_e32 v124, 1.0, v124
	v_div_scale_f32 v125, s[92:93], v124, v124, 1.0
	v_rcp_f32_e32 v126, v125
	v_div_scale_f32 v127, vcc, 1.0, v124, 1.0
	v_fma_f32 v128, -v125, v126, 1.0
	v_fmac_f32_e32 v126, v128, v126
	v_mul_f32_e32 v128, v127, v126
	v_fma_f32 v129, -v125, v128, v127
	v_fmac_f32_e32 v128, v129, v126
	v_fma_f32 v125, -v125, v128, v127
	v_div_fmas_f32 v125, v125, v126, v128
	v_div_fixup_f32 v124, v125, v124, 1.0
	v_bfe_u32 v125, v124, 16, 1
	v_add3_u32 v124, v124, v125, s83
	ds_write_b16_d16_hi v116, v124 offset:272
	s_and_b64 vcc, exec, s[6:7]
	v_mul_f32_e32 v48, 0xbfb8aa3b, v48
	v_exp_f32_e32 v48, v48
	s_nop 0
	v_add_f32_e32 v48, 1.0, v48
	v_div_scale_f32 v124, s[8:9], v48, v48, 1.0
	v_rcp_f32_e32 v125, v124
	v_div_scale_f32 v126, vcc, 1.0, v48, 1.0
	v_fma_f32 v127, -v124, v125, 1.0
	v_fmac_f32_e32 v125, v127, v125
	v_mul_f32_e32 v127, v126, v125
	v_fma_f32 v128, -v124, v127, v126
	v_fmac_f32_e32 v127, v128, v125
	v_fma_f32 v124, -v124, v127, v126
	v_div_fmas_f32 v124, v124, v125, v127
	v_div_fixup_f32 v48, v124, v48, 1.0
	v_bfe_u32 v124, v48, 16, 1
	v_add3_u32 v48, v48, v124, s83
	s_and_b64 vcc, exec, s[6:7]
	ds_write_b16_d16_hi v107, v48 offset:64
	v_mul_f32_e32 v48, 0xbfb8aa3b, v49
	v_exp_f32_e32 v48, v48
	s_nop 0
	v_add_f32_e32 v48, 1.0, v48
	v_div_scale_f32 v49, s[8:9], v48, v48, 1.0
	v_rcp_f32_e32 v107, v49
	v_div_scale_f32 v124, vcc, 1.0, v48, 1.0
	v_fma_f32 v125, -v49, v107, 1.0
	v_fmac_f32_e32 v107, v125, v107
	v_mul_f32_e32 v125, v124, v107
	v_fma_f32 v126, -v49, v125, v124
	v_fmac_f32_e32 v125, v126, v107
	v_fma_f32 v49, -v49, v125, v124
	v_div_fmas_f32 v49, v49, v107, v125
	v_div_fixup_f32 v48, v49, v48, 1.0
	v_bfe_u32 v49, v48, 16, 1
	v_add3_u32 v48, v48, v49, s83
	s_and_b64 vcc, exec, s[6:7]
	ds_write_b16_d16_hi v110, v48 offset:64
	v_mul_f32_e32 v48, 0xbfb8aa3b, v50
	v_exp_f32_e32 v48, v48
	s_nop 0
	v_add_f32_e32 v48, 1.0, v48
	v_div_scale_f32 v49, s[8:9], v48, v48, 1.0
	v_rcp_f32_e32 v50, v49
	v_div_scale_f32 v107, vcc, 1.0, v48, 1.0
	v_fma_f32 v110, -v49, v50, 1.0
	v_fmac_f32_e32 v50, v110, v50
	v_mul_f32_e32 v110, v107, v50
	v_fma_f32 v124, -v49, v110, v107
	v_fmac_f32_e32 v110, v124, v50
	v_fma_f32 v49, -v49, v110, v107
	v_div_fmas_f32 v49, v49, v50, v110
	v_div_fixup_f32 v48, v49, v48, 1.0
	v_bfe_u32 v49, v48, 16, 1
	v_add3_u32 v48, v48, v49, s83
	s_and_b64 vcc, exec, s[6:7]
	ds_write_b16_d16_hi v111, v48 offset:64
	v_mul_f32_e32 v48, 0xbfb8aa3b, v51
	v_exp_f32_e32 v48, v48
	s_nop 0
	v_add_f32_e32 v48, 1.0, v48
	v_div_scale_f32 v49, s[8:9], v48, v48, 1.0
	v_rcp_f32_e32 v50, v49
	v_div_scale_f32 v51, vcc, 1.0, v48, 1.0
	v_fma_f32 v107, -v49, v50, 1.0
	v_fmac_f32_e32 v50, v107, v50
	v_mul_f32_e32 v107, v51, v50
	v_fma_f32 v110, -v49, v107, v51
	v_fmac_f32_e32 v107, v110, v50
	v_fma_f32 v49, -v49, v107, v51
	v_div_fmas_f32 v49, v49, v50, v107
	v_div_fixup_f32 v48, v49, v48, 1.0
	v_bfe_u32 v49, v48, 16, 1
	v_add3_u32 v48, v48, v49, s83
	s_and_b64 vcc, exec, s[6:7]
	ds_write_b16_d16_hi v112, v48 offset:64
	v_mul_f32_e32 v48, 0xbfb8aa3b, v52
	v_exp_f32_e32 v48, v48
	s_nop 0
	v_add_f32_e32 v48, 1.0, v48
	v_div_scale_f32 v49, s[8:9], v48, v48, 1.0
	v_rcp_f32_e32 v50, v49
	v_div_scale_f32 v51, vcc, 1.0, v48, 1.0
	v_fma_f32 v52, -v49, v50, 1.0
	v_fmac_f32_e32 v50, v52, v50
	v_mul_f32_e32 v52, v51, v50
	v_fma_f32 v107, -v49, v52, v51
	v_fmac_f32_e32 v52, v107, v50
	v_fma_f32 v49, -v49, v52, v51
	v_div_fmas_f32 v49, v49, v50, v52
	v_div_fixup_f32 v48, v49, v48, 1.0
	v_bfe_u32 v49, v48, 16, 1
	v_add3_u32 v48, v48, v49, s83
	s_and_b64 vcc, exec, s[6:7]
	ds_write_b16_d16_hi v113, v48 offset:64
	v_mul_f32_e32 v48, 0xbfb8aa3b, v53
	v_exp_f32_e32 v48, v48
	s_nop 0
	v_add_f32_e32 v48, 1.0, v48
	v_div_scale_f32 v49, s[8:9], v48, v48, 1.0
	v_rcp_f32_e32 v50, v49
	v_div_scale_f32 v51, vcc, 1.0, v48, 1.0
	v_fma_f32 v52, -v49, v50, 1.0
	v_fmac_f32_e32 v50, v52, v50
	v_mul_f32_e32 v52, v51, v50
	v_fma_f32 v53, -v49, v52, v51
	v_fmac_f32_e32 v52, v53, v50
	v_fma_f32 v49, -v49, v52, v51
	v_div_fmas_f32 v49, v49, v50, v52
	v_div_fixup_f32 v48, v49, v48, 1.0
	v_bfe_u32 v49, v48, 16, 1
	v_add3_u32 v48, v48, v49, s83
	s_and_b64 vcc, exec, s[6:7]
	ds_write_b16_d16_hi v114, v48 offset:64
	v_mul_f32_e32 v48, 0xbfb8aa3b, v54
	v_exp_f32_e32 v48, v48
	s_nop 0
	v_add_f32_e32 v48, 1.0, v48
	v_div_scale_f32 v49, s[8:9], v48, v48, 1.0
	v_rcp_f32_e32 v50, v49
	v_div_scale_f32 v51, vcc, 1.0, v48, 1.0
	v_fma_f32 v52, -v49, v50, 1.0
	v_fmac_f32_e32 v50, v52, v50
	v_mul_f32_e32 v52, v51, v50
	v_fma_f32 v53, -v49, v52, v51
	v_fmac_f32_e32 v52, v53, v50
	v_fma_f32 v49, -v49, v52, v51
	v_div_fmas_f32 v49, v49, v50, v52
	v_div_fixup_f32 v48, v49, v48, 1.0
	v_bfe_u32 v49, v48, 16, 1
	v_add3_u32 v48, v48, v49, s83
	s_and_b64 vcc, exec, s[6:7]
	ds_write_b16_d16_hi v115, v48 offset:64
	v_mul_f32_e32 v48, 0xbfb8aa3b, v55
	v_exp_f32_e32 v48, v48
	s_nop 0
	v_add_f32_e32 v48, 1.0, v48
	v_div_scale_f32 v49, s[8:9], v48, v48, 1.0
	v_rcp_f32_e32 v50, v49
	v_div_scale_f32 v51, vcc, 1.0, v48, 1.0
	v_fma_f32 v52, -v49, v50, 1.0
	v_fmac_f32_e32 v50, v52, v50
	v_mul_f32_e32 v52, v51, v50
	v_fma_f32 v53, -v49, v52, v51
	v_fmac_f32_e32 v52, v53, v50
	v_fma_f32 v49, -v49, v52, v51
	v_div_fmas_f32 v49, v49, v50, v52
	v_div_fixup_f32 v48, v49, v48, 1.0
	v_bfe_u32 v49, v48, 16, 1
	v_add3_u32 v48, v48, v49, s83
; __device__ __forceinline__ bf16r f2bf(float f) {
;   unsigned u = __float_as_uint(f);
;   u += 0x7fffu + ((u >> 16) & 1u);
;   return (bf16r)(u >> 16);
; }
; __device__ __forceinline__ unsigned pack2(float a, float b) { return (unsigned)f2bf(a) | ((unsigned)f2bf(b) << 16); }
; __device__ __forceinline__ float lo16(unsigned v) { return __uint_as_float(v << 16); }
; __device__ __forceinline__ float hi16(unsigned v) { return __uint_as_float(v & 0xffff0000u); }
; __device__ __forceinline__ float siluf(float x) { return x / (1.f + __expf(-x)); }
; __device__ __forceinline__ float sigmf(float x) { return 1.f / (1.f + __expf(-x)); }
; __device__ __forceinline__ void inproj_epilogue(const Params& p, int layer, int mt, int ntile, int tid,
;                                                 f32x16 (&acc)[2][2], unsigned char* smem) {
;     ...
;     acc_foreach(tid, acc, [&](int row, int col, float v) {
;       int t = m0 + row;
;       float o = v;
;       if (mode == 1) o = (t >= NPADR) ? v : 0.f;
;       if (mode == 2) o = sigmf(v);
;       sT[row * 136 + col] = f2bf(o);
;     });
	s_and_b64 vcc, exec, s[6:7]
	ds_write_b16_d16_hi v117, v48 offset:64
	v_mul_f32_e32 v48, 0xbfb8aa3b, v56
	v_exp_f32_e32 v48, v48
	s_nop 0
	v_add_f32_e32 v48, 1.0, v48
	v_div_scale_f32 v49, s[8:9], v48, v48, 1.0
	v_rcp_f32_e32 v50, v49
	v_div_scale_f32 v51, vcc, 1.0, v48, 1.0
	v_fma_f32 v52, -v49, v50, 1.0
	v_fmac_f32_e32 v50, v52, v50
	v_mul_f32_e32 v52, v51, v50
	v_fma_f32 v53, -v49, v52, v51
	v_fmac_f32_e32 v52, v53, v50
	v_fma_f32 v49, -v49, v52, v51
	v_div_fmas_f32 v49, v49, v50, v52
	v_div_fixup_f32 v48, v49, v48, 1.0
	v_bfe_u32 v49, v48, 16, 1
	v_add3_u32 v48, v48, v49, s83
	s_and_b64 vcc, exec, s[6:7]
	ds_write_b16_d16_hi v118, v48 offset:64
	v_mul_f32_e32 v48, 0xbfb8aa3b, v57
	v_exp_f32_e32 v48, v48
	s_nop 0
	v_add_f32_e32 v48, 1.0, v48
	v_div_scale_f32 v49, s[8:9], v48, v48, 1.0
	v_rcp_f32_e32 v50, v49
	v_div_scale_f32 v51, vcc, 1.0, v48, 1.0
	v_fma_f32 v52, -v49, v50, 1.0
	v_fmac_f32_e32 v50, v52, v50
	v_mul_f32_e32 v52, v51, v50
	v_fma_f32 v53, -v49, v52, v51
	v_fmac_f32_e32 v52, v53, v50
	v_fma_f32 v49, -v49, v52, v51
	v_div_fmas_f32 v49, v49, v50, v52
	v_div_fixup_f32 v48, v49, v48, 1.0
	v_bfe_u32 v49, v48, 16, 1
	v_add3_u32 v48, v48, v49, s83
	s_and_b64 vcc, exec, s[6:7]
	ds_write_b16_d16_hi v119, v48 offset:64
	v_mul_f32_e32 v48, 0xbfb8aa3b, v58
	v_exp_f32_e32 v48, v48
	s_nop 0
	v_add_f32_e32 v48, 1.0, v48
	v_div_scale_f32 v49, s[8:9], v48, v48, 1.0
	v_rcp_f32_e32 v50, v49
	v_div_scale_f32 v51, vcc, 1.0, v48, 1.0
	v_fma_f32 v52, -v49, v50, 1.0
	v_fmac_f32_e32 v50, v52, v50
	v_mul_f32_e32 v52, v51, v50
	v_fma_f32 v53, -v49, v52, v51
	v_fmac_f32_e32 v52, v53, v50
	v_fma_f32 v49, -v49, v52, v51
	v_div_fmas_f32 v49, v49, v50, v52
	v_div_fixup_f32 v48, v49, v48, 1.0
	v_bfe_u32 v49, v48, 16, 1
	v_add3_u32 v48, v48, v49, s83
	s_and_b64 vcc, exec, s[6:7]
	ds_write_b16_d16_hi v120, v48 offset:64
	v_mul_f32_e32 v48, 0xbfb8aa3b, v59
	v_exp_f32_e32 v48, v48
	s_nop 0
	v_add_f32_e32 v48, 1.0, v48
	v_div_scale_f32 v49, s[8:9], v48, v48, 1.0
	v_rcp_f32_e32 v50, v49
	v_div_scale_f32 v51, vcc, 1.0, v48, 1.0
	v_fma_f32 v52, -v49, v50, 1.0
	v_fmac_f32_e32 v50, v52, v50
	v_mul_f32_e32 v52, v51, v50
	v_fma_f32 v53, -v49, v52, v51
	v_fmac_f32_e32 v52, v53, v50
	v_fma_f32 v49, -v49, v52, v51
	v_div_fmas_f32 v49, v49, v50, v52
	v_div_fixup_f32 v48, v49, v48, 1.0
	v_bfe_u32 v49, v48, 16, 1
	v_add3_u32 v48, v48, v49, s83
	s_and_b64 vcc, exec, s[6:7]
	ds_write_b16_d16_hi v121, v48 offset:64
	v_mul_f32_e32 v48, 0xbfb8aa3b, v60
	v_exp_f32_e32 v48, v48
	s_nop 0
	v_add_f32_e32 v48, 1.0, v48
	v_div_scale_f32 v49, s[8:9], v48, v48, 1.0
	v_rcp_f32_e32 v50, v49
	v_div_scale_f32 v51, vcc, 1.0, v48, 1.0
	v_fma_f32 v52, -v49, v50, 1.0
	v_fmac_f32_e32 v50, v52, v50
	v_mul_f32_e32 v52, v51, v50
	v_fma_f32 v53, -v49, v52, v51
	v_fmac_f32_e32 v52, v53, v50
	v_fma_f32 v49, -v49, v52, v51
	v_div_fmas_f32 v49, v49, v50, v52
	v_div_fixup_f32 v48, v49, v48, 1.0
	v_bfe_u32 v49, v48, 16, 1
	v_add3_u32 v48, v48, v49, s83
	s_and_b64 vcc, exec, s[6:7]
	ds_write_b16_d16_hi v122, v48 offset:64
	v_mul_f32_e32 v48, 0xbfb8aa3b, v61
	v_exp_f32_e32 v48, v48
	s_nop 0
	v_add_f32_e32 v48, 1.0, v48
	v_div_scale_f32 v49, s[8:9], v48, v48, 1.0
	v_rcp_f32_e32 v50, v49
	v_div_scale_f32 v51, vcc, 1.0, v48, 1.0
	v_fma_f32 v52, -v49, v50, 1.0
	v_fmac_f32_e32 v50, v52, v50
	v_mul_f32_e32 v52, v51, v50
	v_fma_f32 v53, -v49, v52, v51
	v_fmac_f32_e32 v52, v53, v50
	v_fma_f32 v49, -v49, v52, v51
	v_div_fmas_f32 v49, v49, v50, v52
	v_div_fixup_f32 v48, v49, v48, 1.0
	v_bfe_u32 v49, v48, 16, 1
	v_add3_u32 v48, v48, v49, s83
	s_and_b64 vcc, exec, s[6:7]
	ds_write_b16_d16_hi v123, v48 offset:64
	v_mul_f32_e32 v48, 0xbfb8aa3b, v62
	v_exp_f32_e32 v48, v48
	s_nop 0
	v_add_f32_e32 v48, 1.0, v48
	v_div_scale_f32 v49, s[8:9], v48, v48, 1.0
	v_rcp_f32_e32 v50, v49
	v_div_scale_f32 v51, vcc, 1.0, v48, 1.0
	v_fma_f32 v52, -v49, v50, 1.0
	v_fmac_f32_e32 v50, v52, v50
	v_mul_f32_e32 v52, v51, v50
	v_fma_f32 v53, -v49, v52, v51
	v_fmac_f32_e32 v52, v53, v50
	v_fma_f32 v49, -v49, v52, v51
	v_div_fmas_f32 v49, v49, v50, v52
	v_div_fixup_f32 v48, v49, v48, 1.0
	v_bfe_u32 v49, v48, 16, 1
	v_add3_u32 v48, v48, v49, s83
	s_and_b64 vcc, exec, s[6:7]
	ds_write_b16_d16_hi v116, v48 offset:64
	v_mul_f32_e32 v48, 0xbfb8aa3b, v63
	v_exp_f32_e32 v48, v48
	s_nop 0
	v_add_f32_e32 v48, 1.0, v48
	v_div_scale_f32 v49, s[8:9], v48, v48, 1.0
	v_rcp_f32_e32 v50, v49
	v_div_scale_f32 v51, vcc, 1.0, v48, 1.0
	v_fma_f32 v52, -v49, v50, 1.0
	v_fmac_f32_e32 v50, v52, v50
	v_mul_f32_e32 v52, v51, v50
	v_fma_f32 v53, -v49, v52, v51
	v_fmac_f32_e32 v52, v53, v50
	v_fma_f32 v49, -v49, v52, v51
	v_div_fmas_f32 v49, v49, v50, v52
	v_div_fixup_f32 v48, v49, v48, 1.0
	v_bfe_u32 v50, v48, 16, 1
	v_add_u32_e32 v49, 0x110, v116
	v_add3_u32 v48, v48, v50, s83
	ds_write_b16_d16_hi v49, v48 offset:64
	v_or_b32_e32 v48, 32, v96
	v_add_u32_e32 v49, s74, v48
	s_and_b64 vcc, exec, s[6:7]
	v_cmp_lt_i32_e64 s[8:9], s81, v49
	v_mul_f32_e32 v49, 0xbfb8aa3b, v0
	v_exp_f32_e32 v49, v49
	s_nop 0
	v_add_f32_e32 v49, 1.0, v49
	v_div_scale_f32 v50, s[10:11], v49, v49, 1.0
	v_rcp_f32_e32 v51, v50
	v_div_scale_f32 v52, vcc, 1.0, v49, 1.0
	v_fma_f32 v53, -v50, v51, 1.0
	v_fmac_f32_e32 v51, v53, v51
	v_mul_f32_e32 v53, v52, v51
	v_fma_f32 v54, -v50, v53, v52
	v_fmac_f32_e32 v53, v54, v51
	v_fma_f32 v50, -v50, v53, v52
	v_div_fmas_f32 v50, v50, v51, v53
	v_div_fixup_f32 v49, v50, v49, 1.0
	v_bfe_u32 v50, v49, 16, 1
	v_add3_u32 v50, v49, v50, s83
	v_mul_lo_u32 v49, v48, s86
	v_lshl_add_u32 v48, v106, 1, v49
	ds_write_b16_d16_hi v48, v50
	v_add3_u32 v50, s74, v96, 33
	s_and_b64 vcc, exec, s[6:7]
	v_cmp_lt_i32_e64 s[10:11], s81, v50
	v_mul_f32_e32 v50, 0xbfb8aa3b, v1
; __device__ __forceinline__ bf16r f2bf(float f) {
;   unsigned u = __float_as_uint(f);
;   u += 0x7fffu + ((u >> 16) & 1u);
;   return (bf16r)(u >> 16);
; }
; __device__ __forceinline__ unsigned pack2(float a, float b) { return (unsigned)f2bf(a) | ((unsigned)f2bf(b) << 16); }
; __device__ __forceinline__ float lo16(unsigned v) { return __uint_as_float(v << 16); }
; __device__ __forceinline__ float hi16(unsigned v) { return __uint_as_float(v & 0xffff0000u); }
; __device__ __forceinline__ float siluf(float x) { return x / (1.f + __expf(-x)); }
; __device__ __forceinline__ float sigmf(float x) { return 1.f / (1.f + __expf(-x)); }
; __device__ __forceinline__ void inproj_epilogue(const Params& p, int layer, int mt, int ntile, int tid,
;                                                 f32x16 (&acc)[2][2], unsigned char* smem) {
;     ...
;     acc_foreach(tid, acc, [&](int row, int col, float v) {
;       int t = m0 + row;
;       float o = v;
;       if (mode == 1) o = (t >= NPADR) ? v : 0.f;
;       if (mode == 2) o = sigmf(v);
;       sT[row * 136 + col] = f2bf(o);
;     });
	v_exp_f32_e32 v50, v50
	s_nop 0
	v_add_f32_e32 v50, 1.0, v50
	v_div_scale_f32 v51, s[12:13], v50, v50, 1.0
	v_rcp_f32_e32 v52, v51
	v_div_scale_f32 v53, vcc, 1.0, v50, 1.0
	v_fma_f32 v54, -v51, v52, 1.0
	v_fmac_f32_e32 v52, v54, v52
	v_mul_f32_e32 v54, v53, v52
	v_fma_f32 v55, -v51, v54, v53
	v_fmac_f32_e32 v54, v55, v52
	v_fma_f32 v51, -v51, v54, v53
	v_div_fmas_f32 v51, v51, v52, v54
	v_div_fixup_f32 v50, v51, v50, 1.0
	v_bfe_u32 v51, v50, 16, 1
	v_add3_u32 v51, v50, v51, s83
	v_add_u32_e32 v50, 0x110, v49
	v_lshl_add_u32 v49, v106, 1, v50
	ds_write_b16_d16_hi v49, v51
	v_add3_u32 v51, s74, v96, 34
	s_and_b64 vcc, exec, s[6:7]
	v_cmp_lt_i32_e64 s[12:13], s81, v51
	v_mul_f32_e32 v51, 0xbfb8aa3b, v2
	v_exp_f32_e32 v51, v51
	s_nop 0
	v_add_f32_e32 v51, 1.0, v51
	v_div_scale_f32 v52, s[14:15], v51, v51, 1.0
	v_rcp_f32_e32 v53, v52
	v_div_scale_f32 v54, vcc, 1.0, v51, 1.0
	v_fma_f32 v55, -v52, v53, 1.0
	v_fmac_f32_e32 v53, v55, v53
	v_mul_f32_e32 v55, v54, v53
	v_fma_f32 v56, -v52, v55, v54
	v_fmac_f32_e32 v55, v56, v53
	v_fma_f32 v52, -v52, v55, v54
	v_div_fmas_f32 v52, v52, v53, v55
	v_div_fixup_f32 v51, v52, v51, 1.0
	v_bfe_u32 v52, v51, 16, 1
	v_add3_u32 v52, v51, v52, s83
	v_add_u32_e32 v51, 0x110, v50
	v_lshl_add_u32 v50, v106, 1, v51
	ds_write_b16_d16_hi v50, v52
	v_add3_u32 v52, s74, v96, 35
	s_and_b64 vcc, exec, s[6:7]
	v_cmp_lt_i32_e64 s[14:15], s81, v52
	v_mul_f32_e32 v52, 0xbfb8aa3b, v3
	v_exp_f32_e32 v52, v52
	s_nop 0
	v_add_f32_e32 v52, 1.0, v52
	v_div_scale_f32 v53, s[16:17], v52, v52, 1.0
	v_rcp_f32_e32 v54, v53
	v_div_scale_f32 v55, vcc, 1.0, v52, 1.0
	v_fma_f32 v56, -v53, v54, 1.0
	v_fmac_f32_e32 v54, v56, v54
	v_mul_f32_e32 v56, v55, v54
	v_fma_f32 v57, -v53, v56, v55
	v_fmac_f32_e32 v56, v57, v54
	v_fma_f32 v53, -v53, v56, v55
	v_div_fmas_f32 v53, v53, v54, v56
	v_div_fixup_f32 v52, v53, v52, 1.0
	v_bfe_u32 v53, v52, 16, 1
	v_add3_u32 v53, v52, v53, s83
	v_add_u32_e32 v52, 0x110, v51
	v_lshl_add_u32 v51, v106, 1, v52
	ds_write_b16_d16_hi v51, v53
	v_add3_u32 v53, s74, v96, 40
	s_and_b64 vcc, exec, s[6:7]
	v_cmp_lt_i32_e64 s[16:17], s81, v53
	v_mul_f32_e32 v53, 0xbfb8aa3b, v4
	v_exp_f32_e32 v53, v53
	s_nop 0
	v_add_f32_e32 v53, 1.0, v53
	v_div_scale_f32 v54, s[18:19], v53, v53, 1.0
	v_rcp_f32_e32 v55, v54
	v_div_scale_f32 v56, vcc, 1.0, v53, 1.0
	v_fma_f32 v57, -v54, v55, 1.0
	v_fmac_f32_e32 v55, v57, v55
	v_mul_f32_e32 v57, v56, v55
	v_fma_f32 v58, -v54, v57, v56
	v_fmac_f32_e32 v57, v58, v55
	v_fma_f32 v54, -v54, v57, v56
	v_div_fmas_f32 v54, v54, v55, v57
	v_div_fixup_f32 v53, v54, v53, 1.0
	v_bfe_u32 v54, v53, 16, 1
	v_add3_u32 v54, v53, v54, s83
	v_add_u32_e32 v53, 0x550, v52
	v_lshl_add_u32 v52, v106, 1, v53
	ds_write_b16_d16_hi v52, v54
	v_add3_u32 v54, s74, v96, 41
	s_and_b64 vcc, exec, s[6:7]
	v_cmp_lt_i32_e64 s[18:19], s81, v54
	v_mul_f32_e32 v54, 0xbfb8aa3b, v5
	v_exp_f32_e32 v54, v54
	s_nop 0
	v_add_f32_e32 v54, 1.0, v54
	v_div_scale_f32 v55, s[20:21], v54, v54, 1.0
	v_rcp_f32_e32 v56, v55
	v_div_scale_f32 v57, vcc, 1.0, v54, 1.0
	v_fma_f32 v58, -v55, v56, 1.0
	v_fmac_f32_e32 v56, v58, v56
	v_mul_f32_e32 v58, v57, v56
	v_fma_f32 v59, -v55, v58, v57
	v_fmac_f32_e32 v58, v59, v56
	v_fma_f32 v55, -v55, v58, v57
	v_div_fmas_f32 v55, v55, v56, v58
	v_div_fixup_f32 v54, v55, v54, 1.0
	v_bfe_u32 v55, v54, 16, 1
	v_add3_u32 v55, v54, v55, s83
	v_add_u32_e32 v54, 0x110, v53
	v_lshl_add_u32 v53, v106, 1, v54
	ds_write_b16_d16_hi v53, v55
	v_add3_u32 v55, s74, v96, 42
	s_and_b64 vcc, exec, s[6:7]
	v_cmp_lt_i32_e64 s[20:21], s81, v55
	v_mul_f32_e32 v55, 0xbfb8aa3b, v6
	v_exp_f32_e32 v55, v55
	s_nop 0
	v_add_f32_e32 v55, 1.0, v55
	v_div_scale_f32 v56, s[22:23], v55, v55, 1.0
	v_rcp_f32_e32 v57, v56
	v_div_scale_f32 v58, vcc, 1.0, v55, 1.0
	v_fma_f32 v59, -v56, v57, 1.0
	v_fmac_f32_e32 v57, v59, v57
	v_mul_f32_e32 v59, v58, v57
	v_fma_f32 v60, -v56, v59, v58
	v_fmac_f32_e32 v59, v60, v57
	v_fma_f32 v56, -v56, v59, v58
	v_div_fmas_f32 v56, v56, v57, v59
	v_div_fixup_f32 v55, v56, v55, 1.0
	v_bfe_u32 v56, v55, 16, 1
	v_add3_u32 v56, v55, v56, s83
	v_add_u32_e32 v55, 0x110, v54
	v_lshl_add_u32 v54, v106, 1, v55
	ds_write_b16_d16_hi v54, v56
	v_add3_u32 v56, s74, v96, 43
	s_and_b64 vcc, exec, s[6:7]
	v_cmp_lt_i32_e64 s[22:23], s81, v56
	v_mul_f32_e32 v56, 0xbfb8aa3b, v7
	v_exp_f32_e32 v56, v56
	s_nop 0
	v_add_f32_e32 v56, 1.0, v56
	v_div_scale_f32 v57, s[24:25], v56, v56, 1.0
	v_rcp_f32_e32 v58, v57
	v_div_scale_f32 v59, vcc, 1.0, v56, 1.0
	v_fma_f32 v60, -v57, v58, 1.0
	v_fmac_f32_e32 v58, v60, v58
	v_mul_f32_e32 v60, v59, v58
	v_fma_f32 v61, -v57, v60, v59
	v_fmac_f32_e32 v60, v61, v58
	v_fma_f32 v57, -v57, v60, v59
	v_div_fmas_f32 v57, v57, v58, v60
	v_div_fixup_f32 v56, v57, v56, 1.0
	v_bfe_u32 v57, v56, 16, 1
	v_add_u32_e32 v55, 0x110, v55
	v_add3_u32 v57, v56, v57, s83
	v_lshl_add_u32 v56, v106, 1, v55
	ds_write_b16_d16_hi v56, v57
	v_add3_u32 v57, s74, v96, 48
	s_and_b64 vcc, exec, s[6:7]
	v_cmp_lt_i32_e64 s[24:25], s81, v57
	v_mul_f32_e32 v57, 0xbfb8aa3b, v8
	v_exp_f32_e32 v57, v57
	s_nop 0
	v_add_f32_e32 v57, 1.0, v57
	v_div_scale_f32 v58, s[26:27], v57, v57, 1.0
	v_rcp_f32_e32 v59, v58
	v_div_scale_f32 v60, vcc, 1.0, v57, 1.0
	v_fma_f32 v61, -v58, v59, 1.0
	v_fmac_f32_e32 v59, v61, v59
	v_mul_f32_e32 v61, v60, v59
	v_fma_f32 v62, -v58, v61, v60
	v_fmac_f32_e32 v61, v62, v59
	v_fma_f32 v58, -v58, v61, v60
	v_div_fmas_f32 v58, v58, v59, v61
	v_div_fixup_f32 v57, v58, v57, 1.0
	v_bfe_u32 v58, v57, 16, 1
	v_add_u32_e32 v55, 0x550, v55
	v_add3_u32 v58, v57, v58, s83
	v_lshl_add_u32 v57, v106, 1, v55
	ds_write_b16_d16_hi v57, v58
	v_add3_u32 v58, s74, v96, 49
	s_and_b64 vcc, exec, s[6:7]
	v_cmp_lt_i32_e64 s[26:27], s81, v58
; __device__ __forceinline__ bf16r f2bf(float f) {
;   unsigned u = __float_as_uint(f);
;   u += 0x7fffu + ((u >> 16) & 1u);
;   return (bf16r)(u >> 16);
; }
; __device__ __forceinline__ unsigned pack2(float a, float b) { return (unsigned)f2bf(a) | ((unsigned)f2bf(b) << 16); }
; __device__ __forceinline__ float lo16(unsigned v) { return __uint_as_float(v << 16); }
; __device__ __forceinline__ float hi16(unsigned v) { return __uint_as_float(v & 0xffff0000u); }
; __device__ __forceinline__ float siluf(float x) { return x / (1.f + __expf(-x)); }
; __device__ __forceinline__ float sigmf(float x) { return 1.f / (1.f + __expf(-x)); }
; __device__ __forceinline__ void inproj_epilogue(const Params& p, int layer, int mt, int ntile, int tid,
;                                                 f32x16 (&acc)[2][2], unsigned char* smem) {
;     ...
;     acc_foreach(tid, acc, [&](int row, int col, float v) {
;       int t = m0 + row;
;       float o = v;
;       if (mode == 1) o = (t >= NPADR) ? v : 0.f;
;       if (mode == 2) o = sigmf(v);
;       sT[row * 136 + col] = f2bf(o);
;     });
	v_mul_f32_e32 v58, 0xbfb8aa3b, v9
	v_exp_f32_e32 v58, v58
	s_nop 0
	v_add_f32_e32 v58, 1.0, v58
	v_div_scale_f32 v59, s[28:29], v58, v58, 1.0
	v_rcp_f32_e32 v60, v59
	v_div_scale_f32 v61, vcc, 1.0, v58, 1.0
	v_fma_f32 v62, -v59, v60, 1.0
	v_fmac_f32_e32 v60, v62, v60
	v_mul_f32_e32 v62, v61, v60
	v_fma_f32 v63, -v59, v62, v61
	v_fmac_f32_e32 v62, v63, v60
	v_fma_f32 v59, -v59, v62, v61
	v_div_fmas_f32 v59, v59, v60, v62
	v_div_fixup_f32 v58, v59, v58, 1.0
	v_bfe_u32 v59, v58, 16, 1
	v_add_u32_e32 v55, 0x110, v55
	v_add3_u32 v59, v58, v59, s83
	v_lshl_add_u32 v58, v106, 1, v55
	ds_write_b16_d16_hi v58, v59
	v_add3_u32 v59, s74, v96, 50
	s_and_b64 vcc, exec, s[6:7]
	v_cmp_lt_i32_e64 s[28:29], s81, v59
	v_mul_f32_e32 v59, 0xbfb8aa3b, v10
	v_exp_f32_e32 v59, v59
	s_nop 0
	v_add_f32_e32 v59, 1.0, v59
	v_div_scale_f32 v60, s[30:31], v59, v59, 1.0
	v_rcp_f32_e32 v61, v60
	v_div_scale_f32 v62, vcc, 1.0, v59, 1.0
	v_fma_f32 v63, -v60, v61, 1.0
	v_fmac_f32_e32 v61, v63, v61
	v_mul_f32_e32 v63, v62, v61
	v_fma_f32 v107, -v60, v63, v62
	v_fmac_f32_e32 v63, v107, v61
	v_fma_f32 v60, -v60, v63, v62
	v_div_fmas_f32 v60, v60, v61, v63
	v_div_fixup_f32 v59, v60, v59, 1.0
	v_bfe_u32 v60, v59, 16, 1
	v_add_u32_e32 v55, 0x110, v55
	v_add3_u32 v60, v59, v60, s83
	v_lshl_add_u32 v59, v106, 1, v55
	ds_write_b16_d16_hi v59, v60
	v_add3_u32 v60, s74, v96, 51
	s_and_b64 vcc, exec, s[6:7]
	v_cmp_lt_i32_e64 s[30:31], s81, v60
	v_mul_f32_e32 v60, 0xbfb8aa3b, v11
	v_exp_f32_e32 v60, v60
	s_nop 0
	v_add_f32_e32 v60, 1.0, v60
	v_div_scale_f32 v61, s[34:35], v60, v60, 1.0
	v_rcp_f32_e32 v62, v61
	v_div_scale_f32 v63, vcc, 1.0, v60, 1.0
	v_fma_f32 v107, -v61, v62, 1.0
	v_fmac_f32_e32 v62, v107, v62
	v_mul_f32_e32 v107, v63, v62
	v_fma_f32 v110, -v61, v107, v63
	v_fmac_f32_e32 v107, v110, v62
	v_fma_f32 v61, -v61, v107, v63
	v_div_fmas_f32 v61, v61, v62, v107
	v_div_fixup_f32 v60, v61, v60, 1.0
	v_bfe_u32 v61, v60, 16, 1
	v_add_u32_e32 v55, 0x110, v55
	v_add3_u32 v61, v60, v61, s83
	v_lshl_add_u32 v60, v106, 1, v55
	ds_write_b16_d16_hi v60, v61
	v_add3_u32 v61, s74, v96, 56
	s_and_b64 vcc, exec, s[6:7]
	v_cmp_lt_i32_e64 s[34:35], s81, v61
	v_mul_f32_e32 v61, 0xbfb8aa3b, v12
	v_exp_f32_e32 v61, v61
	s_nop 0
	v_add_f32_e32 v61, 1.0, v61
	v_div_scale_f32 v62, s[36:37], v61, v61, 1.0
	v_rcp_f32_e32 v63, v62
	v_div_scale_f32 v107, vcc, 1.0, v61, 1.0
	v_fma_f32 v110, -v62, v63, 1.0
	v_fmac_f32_e32 v63, v110, v63
	v_mul_f32_e32 v110, v107, v63
	v_fma_f32 v111, -v62, v110, v107
	v_fmac_f32_e32 v110, v111, v63
	v_fma_f32 v62, -v62, v110, v107
	v_div_fmas_f32 v62, v62, v63, v110
	v_div_fixup_f32 v61, v62, v61, 1.0
	v_bfe_u32 v62, v61, 16, 1
	v_add_u32_e32 v55, 0x550, v55
	v_add3_u32 v62, v61, v62, s83
	v_lshl_add_u32 v61, v106, 1, v55
	ds_write_b16_d16_hi v61, v62
	v_add3_u32 v62, s74, v96, 57
	s_and_b64 vcc, exec, s[6:7]
	v_cmp_lt_i32_e64 s[36:37], s81, v62
	v_mul_f32_e32 v62, 0xbfb8aa3b, v13
	v_exp_f32_e32 v62, v62
	s_nop 0
	v_add_f32_e32 v62, 1.0, v62
	v_div_scale_f32 v63, s[38:39], v62, v62, 1.0
	v_rcp_f32_e32 v107, v63
	v_div_scale_f32 v110, vcc, 1.0, v62, 1.0
	v_fma_f32 v111, -v63, v107, 1.0
	v_fmac_f32_e32 v107, v111, v107
	v_mul_f32_e32 v111, v110, v107
	v_fma_f32 v112, -v63, v111, v110
	v_fmac_f32_e32 v111, v112, v107
	v_fma_f32 v63, -v63, v111, v110
	v_div_fmas_f32 v63, v63, v107, v111
	v_div_fixup_f32 v62, v63, v62, 1.0
	v_bfe_u32 v63, v62, 16, 1
	v_add_u32_e32 v55, 0x110, v55
	v_add3_u32 v63, v62, v63, s83
	v_lshl_add_u32 v62, v106, 1, v55
	ds_write_b16_d16_hi v62, v63
	v_add3_u32 v63, s74, v96, 58
	s_and_b64 vcc, exec, s[6:7]
	v_cmp_lt_i32_e64 s[38:39], s81, v63
	v_mul_f32_e32 v63, 0xbfb8aa3b, v14
	v_exp_f32_e32 v63, v63
	s_nop 0
	v_add_f32_e32 v63, 1.0, v63
	v_div_scale_f32 v107, s[40:41], v63, v63, 1.0
	v_rcp_f32_e32 v110, v107
	v_div_scale_f32 v111, vcc, 1.0, v63, 1.0
	v_fma_f32 v112, -v107, v110, 1.0
	v_fmac_f32_e32 v110, v112, v110
	v_mul_f32_e32 v112, v111, v110
	v_fma_f32 v113, -v107, v112, v111
	v_fmac_f32_e32 v112, v113, v110
	v_fma_f32 v107, -v107, v112, v111
	v_div_fmas_f32 v107, v107, v110, v112
	v_div_fixup_f32 v63, v107, v63, 1.0
	v_bfe_u32 v107, v63, 16, 1
	v_add_u32_e32 v55, 0x110, v55
	v_add3_u32 v63, v63, v107, s83
	v_lshl_add_u32 v55, v106, 1, v55
	ds_write_b16_d16_hi v55, v63
	v_add3_u32 v63, s74, v96, 59
	s_and_b64 vcc, exec, s[6:7]
	v_cmp_lt_i32_e64 s[40:41], s81, v63
	v_mul_f32_e32 v63, 0xbfb8aa3b, v15
	v_exp_f32_e32 v63, v63
	s_nop 0
	v_add_f32_e32 v63, 1.0, v63
	v_div_scale_f32 v96, s[92:93], v63, v63, 1.0
	v_rcp_f32_e32 v106, v96
	v_div_scale_f32 v107, vcc, 1.0, v63, 1.0
	v_fma_f32 v110, -v96, v106, 1.0
	v_fmac_f32_e32 v106, v110, v106
	v_mul_f32_e32 v110, v107, v106
	v_fma_f32 v111, -v96, v110, v107
	v_fmac_f32_e32 v110, v111, v106
	v_fma_f32 v96, -v96, v110, v107
	v_div_fmas_f32 v96, v96, v106, v110
	v_div_fixup_f32 v63, v96, v63, 1.0
	v_bfe_u32 v96, v63, 16, 1
	v_add3_u32 v63, v63, v96, s83
	ds_write_b16_d16_hi v55, v63 offset:272
	s_and_b64 vcc, exec, s[6:7]
	v_mul_f32_e32 v32, 0xbfb8aa3b, v32
	v_exp_f32_e32 v32, v32
	s_nop 0
	v_add_f32_e32 v32, 1.0, v32
	v_div_scale_f32 v63, s[8:9], v32, v32, 1.0
	v_rcp_f32_e32 v96, v63
	v_div_scale_f32 v106, vcc, 1.0, v32, 1.0
	v_fma_f32 v107, -v63, v96, 1.0
	v_fmac_f32_e32 v96, v107, v96
	v_mul_f32_e32 v107, v106, v96
	v_fma_f32 v110, -v63, v107, v106
	v_fmac_f32_e32 v107, v110, v96
	v_fma_f32 v63, -v63, v107, v106
	v_div_fmas_f32 v63, v63, v96, v107
	v_div_fixup_f32 v32, v63, v32, 1.0
	v_bfe_u32 v63, v32, 16, 1
	v_add3_u32 v32, v32, v63, s83
	s_and_b64 vcc, exec, s[6:7]
	ds_write_b16_d16_hi v48, v32 offset:64
	v_mul_f32_e32 v32, 0xbfb8aa3b, v33
	v_exp_f32_e32 v32, v32
	s_nop 0
	v_add_f32_e32 v32, 1.0, v32
; __device__ __forceinline__ bf16r f2bf(float f) {
;   unsigned u = __float_as_uint(f);
;   u += 0x7fffu + ((u >> 16) & 1u);
;   return (bf16r)(u >> 16);
; }
; __device__ __forceinline__ unsigned pack2(float a, float b) { return (unsigned)f2bf(a) | ((unsigned)f2bf(b) << 16); }
; __device__ __forceinline__ float lo16(unsigned v) { return __uint_as_float(v << 16); }
; __device__ __forceinline__ float hi16(unsigned v) { return __uint_as_float(v & 0xffff0000u); }
; __device__ __forceinline__ float siluf(float x) { return x / (1.f + __expf(-x)); }
; __device__ __forceinline__ float sigmf(float x) { return 1.f / (1.f + __expf(-x)); }
; __device__ __forceinline__ void inproj_epilogue(const Params& p, int layer, int mt, int ntile, int tid,
;                                                 f32x16 (&acc)[2][2], unsigned char* smem) {
;     ...
;     acc_foreach(tid, acc, [&](int row, int col, float v) {
;       int t = m0 + row;
;       float o = v;
;       if (mode == 1) o = (t >= NPADR) ? v : 0.f;
;       if (mode == 2) o = sigmf(v);
;       sT[row * 136 + col] = f2bf(o);
;     });
	v_div_scale_f32 v33, s[8:9], v32, v32, 1.0
	v_rcp_f32_e32 v48, v33
	v_div_scale_f32 v63, vcc, 1.0, v32, 1.0
	v_fma_f32 v96, -v33, v48, 1.0
	v_fmac_f32_e32 v48, v96, v48
	v_mul_f32_e32 v96, v63, v48
	v_fma_f32 v106, -v33, v96, v63
	v_fmac_f32_e32 v96, v106, v48
	v_fma_f32 v33, -v33, v96, v63
	v_div_fmas_f32 v33, v33, v48, v96
	v_div_fixup_f32 v32, v33, v32, 1.0
	v_bfe_u32 v33, v32, 16, 1
	v_add3_u32 v32, v32, v33, s83
	s_and_b64 vcc, exec, s[6:7]
	ds_write_b16_d16_hi v49, v32 offset:64
	v_mul_f32_e32 v32, 0xbfb8aa3b, v34
	v_exp_f32_e32 v32, v32
	s_nop 0
	v_add_f32_e32 v32, 1.0, v32
	v_div_scale_f32 v33, s[8:9], v32, v32, 1.0
	v_rcp_f32_e32 v34, v33
	v_div_scale_f32 v48, vcc, 1.0, v32, 1.0
	v_fma_f32 v49, -v33, v34, 1.0
	v_fmac_f32_e32 v34, v49, v34
	v_mul_f32_e32 v49, v48, v34
	v_fma_f32 v63, -v33, v49, v48
	v_fmac_f32_e32 v49, v63, v34
	v_fma_f32 v33, -v33, v49, v48
	v_div_fmas_f32 v33, v33, v34, v49
	v_div_fixup_f32 v32, v33, v32, 1.0
	v_bfe_u32 v33, v32, 16, 1
	v_add3_u32 v32, v32, v33, s83
	s_and_b64 vcc, exec, s[6:7]
	ds_write_b16_d16_hi v50, v32 offset:64
	v_mul_f32_e32 v32, 0xbfb8aa3b, v35
	v_exp_f32_e32 v32, v32
	s_nop 0
	v_add_f32_e32 v32, 1.0, v32
	v_div_scale_f32 v33, s[8:9], v32, v32, 1.0
	v_rcp_f32_e32 v34, v33
	v_div_scale_f32 v35, vcc, 1.0, v32, 1.0
	v_fma_f32 v48, -v33, v34, 1.0
	v_fmac_f32_e32 v34, v48, v34
	v_mul_f32_e32 v48, v35, v34
	v_fma_f32 v49, -v33, v48, v35
	v_fmac_f32_e32 v48, v49, v34
	v_fma_f32 v33, -v33, v48, v35
	v_div_fmas_f32 v33, v33, v34, v48
	v_div_fixup_f32 v32, v33, v32, 1.0
	v_bfe_u32 v33, v32, 16, 1
	v_add3_u32 v32, v32, v33, s83
	s_and_b64 vcc, exec, s[6:7]
	ds_write_b16_d16_hi v51, v32 offset:64
	v_mul_f32_e32 v32, 0xbfb8aa3b, v36
	v_exp_f32_e32 v32, v32
	s_nop 0
	v_add_f32_e32 v32, 1.0, v32
	v_div_scale_f32 v33, s[8:9], v32, v32, 1.0
	v_rcp_f32_e32 v34, v33
	v_div_scale_f32 v35, vcc, 1.0, v32, 1.0
	v_fma_f32 v36, -v33, v34, 1.0
	v_fmac_f32_e32 v34, v36, v34
	v_mul_f32_e32 v36, v35, v34
	v_fma_f32 v48, -v33, v36, v35
	v_fmac_f32_e32 v36, v48, v34
	v_fma_f32 v33, -v33, v36, v35
	v_div_fmas_f32 v33, v33, v34, v36
	v_div_fixup_f32 v32, v33, v32, 1.0
	v_bfe_u32 v33, v32, 16, 1
	v_add3_u32 v32, v32, v33, s83
	s_and_b64 vcc, exec, s[6:7]
	ds_write_b16_d16_hi v52, v32 offset:64
	v_mul_f32_e32 v32, 0xbfb8aa3b, v37
	v_exp_f32_e32 v32, v32
	s_nop 0
	v_add_f32_e32 v32, 1.0, v32
	v_div_scale_f32 v33, s[8:9], v32, v32, 1.0
	v_rcp_f32_e32 v34, v33
	v_div_scale_f32 v35, vcc, 1.0, v32, 1.0
	v_fma_f32 v36, -v33, v34, 1.0
	v_fmac_f32_e32 v34, v36, v34
	v_mul_f32_e32 v36, v35, v34
	v_fma_f32 v37, -v33, v36, v35
	v_fmac_f32_e32 v36, v37, v34
	v_fma_f32 v33, -v33, v36, v35
	v_div_fmas_f32 v33, v33, v34, v36
	v_div_fixup_f32 v32, v33, v32, 1.0
	v_bfe_u32 v33, v32, 16, 1
	v_add3_u32 v32, v32, v33, s83
	s_and_b64 vcc, exec, s[6:7]
	ds_write_b16_d16_hi v53, v32 offset:64
	v_mul_f32_e32 v32, 0xbfb8aa3b, v38
	v_exp_f32_e32 v32, v32
	s_nop 0
	v_add_f32_e32 v32, 1.0, v32
	v_div_scale_f32 v33, s[8:9], v32, v32, 1.0
	v_rcp_f32_e32 v34, v33
	v_div_scale_f32 v35, vcc, 1.0, v32, 1.0
	v_fma_f32 v36, -v33, v34, 1.0
	v_fmac_f32_e32 v34, v36, v34
	v_mul_f32_e32 v36, v35, v34
	v_fma_f32 v37, -v33, v36, v35
	v_fmac_f32_e32 v36, v37, v34
	v_fma_f32 v33, -v33, v36, v35
	v_div_fmas_f32 v33, v33, v34, v36
	v_div_fixup_f32 v32, v33, v32, 1.0
	v_bfe_u32 v33, v32, 16, 1
	v_add3_u32 v32, v32, v33, s83
	s_and_b64 vcc, exec, s[6:7]
	ds_write_b16_d16_hi v54, v32 offset:64
	v_mul_f32_e32 v32, 0xbfb8aa3b, v39
	v_exp_f32_e32 v32, v32
	s_nop 0
	v_add_f32_e32 v32, 1.0, v32
	v_div_scale_f32 v33, s[8:9], v32, v32, 1.0
	v_rcp_f32_e32 v34, v33
	v_div_scale_f32 v35, vcc, 1.0, v32, 1.0
	v_fma_f32 v36, -v33, v34, 1.0
	v_fmac_f32_e32 v34, v36, v34
	v_mul_f32_e32 v36, v35, v34
	v_fma_f32 v37, -v33, v36, v35
	v_fmac_f32_e32 v36, v37, v34
	v_fma_f32 v33, -v33, v36, v35
	v_div_fmas_f32 v33, v33, v34, v36
	v_div_fixup_f32 v32, v33, v32, 1.0
	v_bfe_u32 v33, v32, 16, 1
	v_add3_u32 v32, v32, v33, s83
	s_and_b64 vcc, exec, s[6:7]
	ds_write_b16_d16_hi v56, v32 offset:64
	v_mul_f32_e32 v32, 0xbfb8aa3b, v40
	v_exp_f32_e32 v32, v32
	s_nop 0
	v_add_f32_e32 v32, 1.0, v32
	v_div_scale_f32 v33, s[8:9], v32, v32, 1.0
	v_rcp_f32_e32 v34, v33
	v_div_scale_f32 v35, vcc, 1.0, v32, 1.0
	v_fma_f32 v36, -v33, v34, 1.0
	v_fmac_f32_e32 v34, v36, v34
	v_mul_f32_e32 v36, v35, v34
; __device__ __forceinline__ bf16r f2bf(float f) {
;   unsigned u = __float_as_uint(f);
;   u += 0x7fffu + ((u >> 16) & 1u);
;   return (bf16r)(u >> 16);
; }
; __device__ __forceinline__ unsigned pack2(float a, float b) { return (unsigned)f2bf(a) | ((unsigned)f2bf(b) << 16); }
; __device__ __forceinline__ float lo16(unsigned v) { return __uint_as_float(v << 16); }
; __device__ __forceinline__ float hi16(unsigned v) { return __uint_as_float(v & 0xffff0000u); }
; __device__ __forceinline__ float siluf(float x) { return x / (1.f + __expf(-x)); }
; __device__ __forceinline__ float sigmf(float x) { return 1.f / (1.f + __expf(-x)); }
; __device__ __forceinline__ void inproj_epilogue(const Params& p, int layer, int mt, int ntile, int tid,
;                                                 f32x16 (&acc)[2][2], unsigned char* smem) {
;     ...
;     acc_foreach(tid, acc, [&](int row, int col, float v) {
;       int t = m0 + row;
;       float o = v;
;       if (mode == 1) o = (t >= NPADR) ? v : 0.f;
;       if (mode == 2) o = sigmf(v);
;       sT[row * 136 + col] = f2bf(o);
;     });
	v_fma_f32 v37, -v33, v36, v35
	v_fmac_f32_e32 v36, v37, v34
	v_fma_f32 v33, -v33, v36, v35
	v_div_fmas_f32 v33, v33, v34, v36
	v_div_fixup_f32 v32, v33, v32, 1.0
	v_bfe_u32 v33, v32, 16, 1
	v_add3_u32 v32, v32, v33, s83
	s_and_b64 vcc, exec, s[6:7]
	ds_write_b16_d16_hi v57, v32 offset:64
	v_mul_f32_e32 v32, 0xbfb8aa3b, v41
	v_exp_f32_e32 v32, v32
	s_nop 0
	v_add_f32_e32 v32, 1.0, v32
	v_div_scale_f32 v33, s[8:9], v32, v32, 1.0
	v_rcp_f32_e32 v34, v33
	v_div_scale_f32 v35, vcc, 1.0, v32, 1.0
	v_fma_f32 v36, -v33, v34, 1.0
	v_fmac_f32_e32 v34, v36, v34
	v_mul_f32_e32 v36, v35, v34
	v_fma_f32 v37, -v33, v36, v35
	v_fmac_f32_e32 v36, v37, v34
	v_fma_f32 v33, -v33, v36, v35
	v_div_fmas_f32 v33, v33, v34, v36
	v_div_fixup_f32 v32, v33, v32, 1.0
	v_bfe_u32 v33, v32, 16, 1
	v_add3_u32 v32, v32, v33, s83
	s_and_b64 vcc, exec, s[6:7]
	ds_write_b16_d16_hi v58, v32 offset:64
	v_mul_f32_e32 v32, 0xbfb8aa3b, v42
	v_exp_f32_e32 v32, v32
	s_nop 0
	v_add_f32_e32 v32, 1.0, v32
	v_div_scale_f32 v33, s[8:9], v32, v32, 1.0
	v_rcp_f32_e32 v34, v33
	v_div_scale_f32 v35, vcc, 1.0, v32, 1.0
	v_fma_f32 v36, -v33, v34, 1.0
	v_fmac_f32_e32 v34, v36, v34
	v_mul_f32_e32 v36, v35, v34
	v_fma_f32 v37, -v33, v36, v35
	v_fmac_f32_e32 v36, v37, v34
	v_fma_f32 v33, -v33, v36, v35
	v_div_fmas_f32 v33, v33, v34, v36
	v_div_fixup_f32 v32, v33, v32, 1.0
	v_bfe_u32 v33, v32, 16, 1
	v_add3_u32 v32, v32, v33, s83
	s_and_b64 vcc, exec, s[6:7]
	ds_write_b16_d16_hi v59, v32 offset:64
	v_mul_f32_e32 v32, 0xbfb8aa3b, v43
	v_exp_f32_e32 v32, v32
	s_nop 0
	v_add_f32_e32 v32, 1.0, v32
	v_div_scale_f32 v33, s[8:9], v32, v32, 1.0
	v_rcp_f32_e32 v34, v33
	v_div_scale_f32 v35, vcc, 1.0, v32, 1.0
	v_fma_f32 v36, -v33, v34, 1.0
	v_fmac_f32_e32 v34, v36, v34
	v_mul_f32_e32 v36, v35, v34
	v_fma_f32 v37, -v33, v36, v35
	v_fmac_f32_e32 v36, v37, v34
	v_fma_f32 v33, -v33, v36, v35
	v_div_fmas_f32 v33, v33, v34, v36
	v_div_fixup_f32 v32, v33, v32, 1.0
	v_bfe_u32 v33, v32, 16, 1
	v_add3_u32 v32, v32, v33, s83
	s_and_b64 vcc, exec, s[6:7]
	ds_write_b16_d16_hi v60, v32 offset:64
	v_mul_f32_e32 v32, 0xbfb8aa3b, v44
	v_exp_f32_e32 v32, v32
	s_nop 0
	v_add_f32_e32 v32, 1.0, v32
	v_div_scale_f32 v33, s[8:9], v32, v32, 1.0
	v_rcp_f32_e32 v34, v33
	v_div_scale_f32 v35, vcc, 1.0, v32, 1.0
	v_fma_f32 v36, -v33, v34, 1.0
	v_fmac_f32_e32 v34, v36, v34
	v_mul_f32_e32 v36, v35, v34
	v_fma_f32 v37, -v33, v36, v35
	v_fmac_f32_e32 v36, v37, v34
	v_fma_f32 v33, -v33, v36, v35
	v_div_fmas_f32 v33, v33, v34, v36
	v_div_fixup_f32 v32, v33, v32, 1.0
	v_bfe_u32 v33, v32, 16, 1
	v_add3_u32 v32, v32, v33, s83
	s_and_b64 vcc, exec, s[6:7]
	ds_write_b16_d16_hi v61, v32 offset:64
	v_mul_f32_e32 v32, 0xbfb8aa3b, v45
	v_exp_f32_e32 v32, v32
	s_nop 0
	v_add_f32_e32 v32, 1.0, v32
	v_div_scale_f32 v33, s[8:9], v32, v32, 1.0
	v_rcp_f32_e32 v34, v33
	v_div_scale_f32 v35, vcc, 1.0, v32, 1.0
	v_fma_f32 v36, -v33, v34, 1.0
	v_fmac_f32_e32 v34, v36, v34
	v_mul_f32_e32 v36, v35, v34
	v_fma_f32 v37, -v33, v36, v35
	v_fmac_f32_e32 v36, v37, v34
	v_fma_f32 v33, -v33, v36, v35
	v_div_fmas_f32 v33, v33, v34, v36
	v_div_fixup_f32 v32, v33, v32, 1.0
	v_bfe_u32 v33, v32, 16, 1
	v_add3_u32 v32, v32, v33, s83
	s_and_b64 vcc, exec, s[6:7]
	ds_write_b16_d16_hi v62, v32 offset:64
	v_mul_f32_e32 v32, 0xbfb8aa3b, v46
	v_exp_f32_e32 v32, v32
	s_nop 0
	v_add_f32_e32 v32, 1.0, v32
	v_div_scale_f32 v33, s[8:9], v32, v32, 1.0
	v_rcp_f32_e32 v34, v33
	v_div_scale_f32 v35, vcc, 1.0, v32, 1.0
	v_fma_f32 v36, -v33, v34, 1.0
	v_fmac_f32_e32 v34, v36, v34
	v_mul_f32_e32 v36, v35, v34
	v_fma_f32 v37, -v33, v36, v35
	v_fmac_f32_e32 v36, v37, v34
	v_fma_f32 v33, -v33, v36, v35
	v_div_fmas_f32 v33, v33, v34, v36
	v_div_fixup_f32 v32, v33, v32, 1.0
	v_bfe_u32 v33, v32, 16, 1
	v_add3_u32 v32, v32, v33, s83
	s_and_b64 vcc, exec, s[6:7]
	ds_write_b16_d16_hi v55, v32 offset:64
	v_mul_f32_e32 v32, 0xbfb8aa3b, v47
	v_exp_f32_e32 v32, v32
	s_nop 0
	v_add_f32_e32 v32, 1.0, v32
	v_div_scale_f32 v33, s[4:5], v32, v32, 1.0
	v_rcp_f32_e32 v34, v33
	v_div_scale_f32 v35, vcc, 1.0, v32, 1.0
	v_fma_f32 v36, -v33, v34, 1.0
	v_fmac_f32_e32 v34, v36, v34
	v_mul_f32_e32 v36, v35, v34
	v_fma_f32 v37, -v33, v36, v35
	v_fmac_f32_e32 v36, v37, v34
	v_fma_f32 v33, -v33, v36, v35
	v_div_fmas_f32 v33, v33, v34, v36
	v_div_fixup_f32 v32, v33, v32, 1.0
	s_branch .LBB0_4734
